# GEMM LDS-DMA loads addressed as scalar base + 32-bit lane offset (saddr form): 230 64-bit VALU adds removed from the K-loops and prologues
# speedup vs baseline: 1.0134x; 1.0086x over previous
;     __device__ bool next(int i, Unit& u) const { if (r0 + i >= r1) return false; return base.next(r0 + i, u); }
;     __device__ bool next(int i, Unit& u) const { const int L = i * G + c; if (L >= 256) return false; u.pm = L; u.pn = L >> 3; return true; }
; #define PG8_STAGE(bufoff, gbase, voff) do { _Pragma("unroll") for (int _i = 0; _i < 2; ++_i) \
;         __builtin_amdgcn_global_load_lds((const unsigned*)((const char*)(gbase) + (voff)[_i]), (LAS unsigned*)(lds + (bufoff) + ldsw + _i * 8192), 16, 0, 0); } while (0)
; #define PG8_WAIT_V(n) asm volatile("s_waitcnt vmcnt(" #n ")" ::: "memory")
; #define PG8_BAR __builtin_amdgcn_s_barrier()
; template <class Epi, class Sched>
; __device__ __forceinline__ void gemm_phase(LAS unsigned char* lds, const Gemm g, const Sched& S, const Epi& E, int wave_id) {
;     ...
;     PG8_STAGE(PG8_SB(0, 0), cB, voffB); PG8_STAGE(PG8_SB(0, 1), cB + hstepB, voffB); PG8_STAGE(PG8_SA(0, 0), cA, voffA); PG8_STAGE(PG8_SA(0, 1), cA + hstepA, voffA);
;     if (wr == 1) PG8_BAR;
;     PG8_WAIT_V(2); PG8_BAR;
;     PG8_STAGE(PG8_SB(1, 0), cB + kstep, voffB); PG8_STAGE(PG8_SA(1, 0), cA + kstep, voffA); PG8_STAGE(PG8_SB(1, 1), cB + hstepB + kstep, voffB);
;     PG8_WAIT_V(6); PG8_BAR;
;     for (;;) {
;         const bool has_next = S.next(ui + 1, nxt);
;         const char* nA = has_next ? (const char*)g.A + (size_t)nxt.pm * tstepA : cA; const char* nB = has_next ? (const char*)g.Bt + (size_t)nxt.pn * tstepB : cB;
.LBB0_246:
	s_lshl_b32 s4, s97, 5
	s_mov_b64 s[22:23], 0x80
	s_and_b32 s7, s4, 0x60
	s_add_i32 m0, s55, 0x18000
	v_lshl_add_u64 v[6:7], v[6:7], 0, s[22:23]
	s_lshl_b32 s61, s2, 6
	s_lshl_b32 s2, s2, 13
	s_lshl_b32 s9, s7, 7
	s_waitcnt vmcnt(2)
	s_barrier
	global_load_lds_dwordx4 v[6:7], off
	v_lshl_add_u64 v[4:5], v[4:5], 0, s[22:23]
	s_add_i32 m0, s55, 0x1a000
	s_add_i32 s62, s55, 0x8000
	s_add_i32 s63, s55, 0xa000
	global_load_lds_dwordx4 v[4:5], off
	v_lshl_add_u64 v[0:1], v[0:1], 0, s[22:23]
	s_mov_b32 m0, s62
	s_add_u32 s4, s12, 0x40080
	global_load_lds_dwordx4 v[0:1], off
	v_lshl_add_u64 v[0:1], v[2:3], 0, s[22:23]
	s_mov_b32 m0, s63
	s_addc_u32 s5, s13, 0
	global_load_lds_dwordx4 v[0:1], off
	s_add_i32 m0, s55, 0x1c000
	s_nop 0
	global_load_lds_dwordx4 v146, s[4:5]
	v_lshl_add_u64 v[0:1], s[4:5], 0, v[150:151]
	s_add_i32 m0, s55, 0x1e000
	v_and_b32_e32 v167, 15, v8
	global_load_lds_dwordx4 v[0:1], off
	v_lshrrev_b32_e32 v0, 1, v8
	v_and_b32_e32 v2, 24, v0
	v_lshlrev_b32_e32 v0, 1, v2
	v_lshlrev_b32_e32 v1, 2, v8
	v_lshl_or_b32 v0, v167, 6, v0
	v_and_b32_e32 v1, 32, v1
	s_cmpk_lt_u32 s80, 0x100
	v_bitop3_b32 v3, v0, s2, v1 bitop3:0xde
	s_cselect_b64 s[24:25], -1, 0
	s_lshl_b32 s2, s7, 2
	s_add_u32 s4, s92, s2
	s_addc_u32 s5, s93, 0
	v_lshlrev_b32_e32 v152, 2, v2
	v_bitop3_b32 v171, v0, s9, v1 bitop3:0xde
	v_lshl_add_u64 v[0:1], s[4:5], 0, v[152:153]
	s_mov_b64 s[4:5], 0x1f4c0000
	v_lshlrev_b32_e32 v152, 5, v167
	v_lshl_add_u64 v[154:155], v[0:1], 0, s[4:5]
	s_add_u32 s26, s92, 0x1f400000
	v_lshl_add_u64 v[0:1], s[92:93], 0, v[152:153]
	v_and_b32_e32 v152, 16, v8
	s_addc_u32 s27, s93, 0
	v_lshl_add_u64 v[0:1], v[0:1], 0, v[152:153]
	s_mov_b64 s[4:5], 0x17400000
	s_add_u32 s28, s92, 0x1a400000
	v_lshl_add_u64 v[156:157], v[0:1], 0, s[4:5]
	v_lshlrev_b32_e32 v0, 14, v9
	s_addc_u32 s29, s93, 0
	v_and_b32_e32 v0, 0xffff8000, v0
	s_add_u32 s30, s92, 0xf400000
	v_lshl_add_u32 v0, v10, 11, v0
	v_and_b32_e32 v1, 1, v9
	s_addc_u32 s31, s93, 0
	v_lshl_or_b32 v0, v1, 6, v0
	s_add_u32 s34, s92, 0x13400000
	v_lshl_add_u32 v158, v11, 1, v0
	v_lshlrev_b32_e32 v0, 14, v12
	s_addc_u32 s35, s93, 0
	v_and_b32_e32 v0, 0xffff8000, v0
	s_waitcnt vmcnt(6)
	s_add_u32 s36, s92, 0x7400000
	v_lshl_add_u32 v0, v13, 11, v0
	v_and_b32_e32 v1, 1, v12
	v_or_b32_e32 v173, s7, v2
	s_addc_u32 s37, s93, 0
	v_readlane_b32 s4, v255, 1
	v_lshl_or_b32 v0, v1, 6, v0
	s_add_i32 s67, 0, 0x10000
	s_add_i32 s72, 0, 0x14000
	v_or_b32_e32 v175, 0xffffee00, v173
	v_or_b32_e32 v177, 0xfffff000, v173
	v_or_b32_e32 v179, 0xffffee80, v173
	v_or_b32_e32 v181, 0xfffff080, v173
	s_ashr_i32 s64, s4, 31
	s_mov_b32 s65, s4
	s_ashr_i32 s66, s66, 31
	v_mov_b32_e32 v159, v153
	v_lshl_add_u32 v160, v14, 1, v0
	v_mov_b32_e32 v161, v153
	v_mov_b64_e32 v[162:163], 0xa00
	v_mov_b64_e32 v[164:165], 0x9ff
	v_add_u32_e32 v183, s67, v171
	v_add_u32_e32 v190, s72, v171
	v_add_u32_e32 v191, 0, v3
	s_movk_i32 s73, 0x300
	s_mov_b32 s74, 0x800000
	s_mov_b32 s75, 0x3f317217
	s_mov_b32 s76, 0x7f800000
	v_mov_b32_e32 v192, 0x41b17218
	s_mov_b32 s77, 0
	s_barrier
	v_readlane_b32 s5, v255, 2
	s_branch .LBB0_249

;     __device__ bool next(int i, Unit& u) const { if (r0 + i >= r1) return false; return base.next(r0 + i, u); }
;     __device__ bool next(int i, Unit& u) const { const int L = i * G + c; if (L >= 256) return false; u.pm = L; u.pn = L >> 3; return true; }
; #define PG8_STAGE(bufoff, gbase, voff) do { _Pragma("unroll") for (int _i = 0; _i < 2; ++_i) \
;         __builtin_amdgcn_global_load_lds((const unsigned*)((const char*)(gbase) + (voff)[_i]), (LAS unsigned*)(lds + (bufoff) + ldsw + _i * 8192), 16, 0, 0); } while (0)
; #define PG8_LDA(dst, b, h) do { _Pragma("unroll") for (int m = 0; m < 4; ++m) _Pragma("unroll") for (int k = 0; k < 2; ++k) dst[m][k] = *(const LAS bf16x8*)(lds + PG8_SA(b, h) + aoff + m * 2048 + k * 1024); } while (0)
; #define PG8_WAIT_V(n) asm volatile("s_waitcnt vmcnt(" #n ")" ::: "memory")
; #define PG8_WAIT_L(n) asm volatile("s_waitcnt lgkmcnt(" #n ")" ::: "memory")
; template <class Epi, class Sched>
; __device__ __forceinline__ void gemm_phase(LAS unsigned char* lds, const Gemm g, const Sched& S, const Epi& E, int wave_id) {
;     ...
;         const bool has_next = S.next(ui + 1, nxt);
;         const char* nA = has_next ? (const char*)g.A + (size_t)nxt.pm * tstepA : cA; const char* nB = has_next ? (const char*)g.Bt + (size_t)nxt.pn * tstepB : cB;
;         for (int t = 0; t < nt; t += 2) {
;             const bool last = (t == nt - 2);
;             const char* a1 = cA + (size_t)(t + 1) * kstep;
;             const char* a2 = last ? nA : cA + (size_t)(t + 2) * kstep; const char* b2 = last ? nB : cB + (size_t)(t + 2) * kstep;
;             const char* a3 = a2 + kstep; const char* b3 = b2 + kstep;
;             PG8_LDB(B0, 0, 0); PG8_LDB(B1, 0, 1); PG8_SCHED; PG8_LDA(At, 0, 0); PG8_STAGE(PG8_SA(1, 1), a1 + hstepA, voffA);
;             PG8_WAIT_V(8); PG8_WAIT_L(0); PG8_BAR; PG8_MMA(0, 0, At, B0); PG8_MMA(0, 1, At, B1); PG8_BAR; PG8_SCHED;
;             PG8_LDA(At, 0, 1); PG8_STAGE(PG8_SB(0, 0), b2, voffB); PG8_STAGE(PG8_SB(0, 1), b2 + hstepB, voffB); PG8_STAGE(PG8_SA(0, 0), a2, voffA);
;             PG8_WAIT_V(8); PG8_WAIT_L(0); PG8_BAR; PG8_MMA(1, 0, At, B0); PG8_MMA(1, 1, At, B1); PG8_BAR; PG8_SCHED;
;     __device__ __forceinline__ void load(Pre& p, const pg8::Unit& u, int ai, int m, int wr, int wc, int fr, int fq) const {
;     ...
;         if (MODE == EM_PROJ || MODE == EM_GATES) p.rs = ((const float*)(ws + WS_RINV0))[row];
.LBB0_251:
	s_ashr_i32 s45, s44, 31
	s_lshl_b64 s[14:15], s[44:45], 19
	s_add_u32 s46, s52, s14
	s_addc_u32 s47, s53, s15
	s_and_b64 s[14:15], s[4:5], exec
	s_cselect_b32 s2, s47, s11
	s_cselect_b32 s7, s46, s10
	s_ashr_i32 s39, s38, 31
	s_lshl_b64 s[14:15], s[38:39], 19
	s_add_u32 s48, s92, s14
	s_addc_u32 s49, s93, s15
	s_and_b64 s[14:15], s[4:5], exec
	s_cselect_b32 s9, s49, s13
	s_cselect_b32 s18, s48, s12
	s_add_u32 s10, s10, 0x40080
	s_addc_u32 s11, s11, 0
	s_add_u32 s33, s12, 0x100
	s_addc_u32 s39, s13, 0
	s_mov_b32 s45, -2
	s_lshl_b32 s14, s8, 8
	s_add_i32 s14, s14, s61
	v_or_b32_e32 v252, s14, v167
	v_ashrrev_i32_e32 v253, 31, v252
	v_lshl_add_u64 v[252:253], v[252:253], 2, s[26:27]
	global_load_dword v244, v[252:253], off
	global_load_dword v245, v[252:253], off offset:64
	global_load_dword v246, v[252:253], off offset:128
	global_load_dword v247, v[252:253], off offset:192
	global_load_dword v248, v[252:253], off offset:512
	global_load_dword v249, v[252:253], off offset:576
	global_load_dword v250, v[252:253], off offset:640
	global_load_dword v251, v[252:253], off offset:704
	ds_read_b128 v[16:19], v183
	ds_read_b128 v[20:23], v183 offset:1024
	ds_read_b128 v[32:35], v183 offset:2048
	ds_read_b128 v[36:39], v183 offset:3072
	ds_read_b128 v[184:187], v190
	ds_read_b128 v[194:197], v190 offset:1024
	ds_read_b128 v[198:201], v190 offset:2048
	ds_read_b128 v[202:205], v190 offset:3072
	s_add_u32 s12, s10, 0xfffc0080
	s_addc_u32 s13, s11, -1
	s_cmp_eq_u32 s45, 12
	s_cselect_b32 s15, s2, s13
	s_cselect_b32 s14, s7, s12
	s_cselect_b32 s13, s9, s39
	s_cselect_b32 s12, s18, s33
	s_add_i32 m0, s55, 0xc000
	ds_read_b128 v[206:209], v191
	ds_read_b128 v[210:213], v191 offset:1024
	ds_read_b128 v[214:217], v191 offset:2048
	ds_read_b128 v[218:221], v191 offset:3072
	ds_read_b128 v[222:225], v191 offset:4096
	ds_read_b128 v[226:229], v191 offset:5120
	ds_read_b128 v[230:233], v191 offset:6144
	ds_read_b128 v[234:237], v191 offset:7168
	global_load_lds_dwordx4 v158, s[10:11]
	s_add_i32 m0, s55, 0xe000
	s_nop 0
	global_load_lds_dwordx4 v160, s[10:11]
	s_waitcnt vmcnt(16)
	s_waitcnt lgkmcnt(0)
	s_barrier
	s_setprio 1
	s_waitcnt lgkmcnt(0)
	v_mfma_f32_16x16x32_bf16 v[140:143], v[16:19], v[206:209], 0
	v_mfma_f32_16x16x32_bf16 v[136:139], v[32:35], v[206:209], 0
	v_mfma_f32_16x16x32_bf16 v[124:127], v[16:19], v[214:217], 0
	v_mfma_f32_16x16x32_bf16 v[120:123], v[32:35], v[214:217], 0
	v_mfma_f32_16x16x32_bf16 v[108:111], v[16:19], v[222:225], 0
	v_mfma_f32_16x16x32_bf16 v[104:107], v[32:35], v[222:225], 0
	v_mfma_f32_16x16x32_bf16 v[92:95], v[16:19], v[230:233], 0
	v_mfma_f32_16x16x32_bf16 v[88:91], v[32:35], v[230:233], 0
	v_mfma_f32_16x16x32_bf16 v[140:143], v[20:23], v[210:213], v[140:143]
	v_mfma_f32_16x16x32_bf16 v[136:139], v[36:39], v[210:213], v[136:139]
	v_mfma_f32_16x16x32_bf16 v[124:127], v[20:23], v[218:221], v[124:127]
	v_mfma_f32_16x16x32_bf16 v[120:123], v[36:39], v[218:221], v[120:123]
	v_mfma_f32_16x16x32_bf16 v[108:111], v[20:23], v[226:229], v[108:111]
	v_mfma_f32_16x16x32_bf16 v[104:107], v[36:39], v[226:229], v[104:107]
	v_mfma_f32_16x16x32_bf16 v[92:95], v[20:23], v[234:237], v[92:95]
	v_mfma_f32_16x16x32_bf16 v[88:91], v[36:39], v[234:237], v[88:91]
	s_setprio 0
	s_setprio 1
	v_mfma_f32_16x16x32_bf16 v[132:135], v[184:187], v[206:209], 0
	v_mfma_f32_16x16x32_bf16 v[128:131], v[198:201], v[206:209], 0
	v_mfma_f32_16x16x32_bf16 v[116:119], v[184:187], v[214:217], 0
	v_mfma_f32_16x16x32_bf16 v[112:115], v[198:201], v[214:217], 0
	v_mfma_f32_16x16x32_bf16 v[100:103], v[184:187], v[222:225], 0
	v_mfma_f32_16x16x32_bf16 v[96:99], v[198:201], v[222:225], 0
	v_mfma_f32_16x16x32_bf16 v[84:87], v[184:187], v[230:233], 0
	v_mfma_f32_16x16x32_bf16 v[80:83], v[198:201], v[230:233], 0
	v_mfma_f32_16x16x32_bf16 v[132:135], v[194:197], v[210:213], v[132:135]
	v_mfma_f32_16x16x32_bf16 v[128:131], v[202:205], v[210:213], v[128:131]
	v_mfma_f32_16x16x32_bf16 v[116:119], v[194:197], v[218:221], v[116:119]
	v_mfma_f32_16x16x32_bf16 v[112:115], v[202:205], v[218:221], v[112:115]
	v_mfma_f32_16x16x32_bf16 v[100:103], v[194:197], v[226:229], v[100:103]
	v_mfma_f32_16x16x32_bf16 v[96:99], v[202:205], v[226:229], v[96:99]
	v_mfma_f32_16x16x32_bf16 v[84:87], v[194:197], v[234:237], v[84:87]
	v_mfma_f32_16x16x32_bf16 v[80:83], v[202:205], v[234:237], v[80:83]
	s_setprio 0
	s_barrier
	s_add_i32 s50, s67, s54
	v_lshl_add_u64 v[168:169], s[12:13], 0, v[146:147]
	s_mov_b32 m0, s50
	ds_read_b128 v[206:209], v191 offset:16384
	ds_read_b128 v[210:213], v191 offset:17408
	ds_read_b128 v[214:217], v191 offset:18432
	ds_read_b128 v[218:221], v191 offset:19456
	ds_read_b128 v[222:225], v191 offset:20480
	ds_read_b128 v[226:229], v191 offset:21504
	ds_read_b128 v[230:233], v191 offset:22528
	ds_read_b128 v[234:237], v191 offset:23552
	global_load_lds_dwordx4 v[168:169], off
	s_add_i32 m0, s50, 0x2000
	s_add_u32 s50, s12, 0x40000
	v_lshl_add_u64 v[188:189], s[12:13], 0, v[150:151]
	s_addc_u32 s51, s13, 0
	s_add_i32 s78, s72, s54
	global_load_lds_dwordx4 v[188:189], off
	s_mov_b32 m0, s78
	v_lshl_add_u64 v[240:241], s[14:15], 0, v[148:149]
	global_load_lds_dwordx4 v146, s[50:51]
	s_add_i32 m0, s78, 0x2000
	s_nop 0
	global_load_lds_dwordx4 v150, s[50:51]
	v_lshl_add_u64 v[238:239], s[14:15], 0, v[144:145]
	s_mov_b32 m0, s55
	s_nop 0
	global_load_lds_dwordx4 v[238:239], off
	s_mov_b32 m0, s58
	s_nop 0
	global_load_lds_dwordx4 v[240:241], off
	s_waitcnt vmcnt(16)
	s_waitcnt lgkmcnt(0)
	s_barrier
; #define PG8_STAGE(bufoff, gbase, voff) do { _Pragma("unroll") for (int _i = 0; _i < 2; ++_i) \
;         __builtin_amdgcn_global_load_lds((const unsigned*)((const char*)(gbase) + (voff)[_i]), (LAS unsigned*)(lds + (bufoff) + ldsw + _i * 8192), 16, 0, 0); } while (0)
; #define PG8_LDA(dst, b, h) do { _Pragma("unroll") for (int m = 0; m < 4; ++m) _Pragma("unroll") for (int k = 0; k < 2; ++k) dst[m][k] = *(const LAS bf16x8*)(lds + PG8_SA(b, h) + aoff + m * 2048 + k * 1024); } while (0)
; #define PG8_LDB(dst, b, h) do { _Pragma("unroll") for (int n = 0; n < 2; ++n) _Pragma("unroll") for (int k = 0; k < 2; ++k) dst[n][k] = *(const LAS bf16x8*)(lds + PG8_SB(b, h) + boff + n * 2048 + k * 1024); } while (0)
; #define PG8_MMA(ai, bj, At, Bt) do { __builtin_amdgcn_s_setprio(1); _Pragma("unroll") for (int m = 0; m < 4; ++m) _Pragma("unroll") for (int n = 0; n < 2; ++n) _Pragma("unroll") for (int k = 0; k < 2; ++k) \
;         acc[ai][bj][m][n] = __builtin_amdgcn_mfma_f32_16x16x32_bf16(Bt[n][k], At[m][k], acc[ai][bj][m][n], 0, 0, 0); __builtin_amdgcn_s_setprio(0); } while (0)
; #define PG8_WAIT_V(n) asm volatile("s_waitcnt vmcnt(" #n ")" ::: "memory")
; #define PG8_WAIT_L(n) asm volatile("s_waitcnt lgkmcnt(" #n ")" ::: "memory")
; #define PG8_BAR __builtin_amdgcn_s_barrier()
; #define PG8_SCHED __builtin_amdgcn_sched_barrier(0)
; template <class Epi, class Sched>
; __device__ __forceinline__ void gemm_phase(LAS unsigned char* lds, const Gemm g, const Sched& S, const Epi& E, int wave_id) {
;     ...
;             PG8_WAIT_V(8); PG8_WAIT_L(0); PG8_BAR; PG8_MMA(1, 0, At, B0); PG8_MMA(1, 1, At, B1); PG8_BAR; PG8_SCHED;
;             PG8_LDB(B0, 1, 0); PG8_LDB(B1, 1, 1); PG8_SCHED; PG8_LDA(At, 1, 0); PG8_STAGE(PG8_SA(0, 1), a2 + hstepA, voffA);
;             PG8_WAIT_V(8); PG8_WAIT_L(0); PG8_BAR; PG8_MMA(0, 0, At, B0); PG8_MMA(0, 1, At, B1); PG8_BAR; PG8_SCHED;
	s_setprio 1
	s_waitcnt lgkmcnt(0)
	v_mfma_f32_16x16x32_bf16 v[76:79], v[16:19], v[206:209], 0
	v_mfma_f32_16x16x32_bf16 v[72:75], v[32:35], v[206:209], 0
	v_mfma_f32_16x16x32_bf16 v[60:63], v[16:19], v[214:217], 0
	v_mfma_f32_16x16x32_bf16 v[56:59], v[32:35], v[214:217], 0
	v_mfma_f32_16x16x32_bf16 v[44:47], v[16:19], v[222:225], 0
	v_mfma_f32_16x16x32_bf16 v[40:43], v[32:35], v[222:225], 0
	v_mfma_f32_16x16x32_bf16 v[12:15], v[16:19], v[230:233], 0
	v_mfma_f32_16x16x32_bf16 v[8:11], v[32:35], v[230:233], 0
	v_mfma_f32_16x16x32_bf16 v[76:79], v[20:23], v[210:213], v[76:79]
	v_mfma_f32_16x16x32_bf16 v[72:75], v[36:39], v[210:213], v[72:75]
	v_mfma_f32_16x16x32_bf16 v[60:63], v[20:23], v[218:221], v[60:63]
	v_mfma_f32_16x16x32_bf16 v[56:59], v[36:39], v[218:221], v[56:59]
	v_mfma_f32_16x16x32_bf16 v[44:47], v[20:23], v[226:229], v[44:47]
	v_mfma_f32_16x16x32_bf16 v[40:43], v[36:39], v[226:229], v[40:43]
	v_mfma_f32_16x16x32_bf16 v[12:15], v[20:23], v[234:237], v[12:15]
	v_mfma_f32_16x16x32_bf16 v[8:11], v[36:39], v[234:237], v[8:11]
	s_setprio 0
	s_setprio 1
	v_mfma_f32_16x16x32_bf16 v[28:31], v[184:187], v[222:225], 0
	v_mfma_f32_16x16x32_bf16 v[24:27], v[198:201], v[222:225], 0
	v_mfma_f32_16x16x32_bf16 v[4:7], v[184:187], v[230:233], 0
	v_mfma_f32_16x16x32_bf16 v[0:3], v[198:201], v[230:233], 0
	v_mfma_f32_16x16x32_bf16 v[16:19], v[184:187], v[206:209], 0
	v_mfma_f32_16x16x32_bf16 v[20:23], v[198:201], v[206:209], 0
	v_mfma_f32_16x16x32_bf16 v[32:35], v[184:187], v[214:217], 0
	v_mfma_f32_16x16x32_bf16 v[36:39], v[198:201], v[214:217], 0
	v_mfma_f32_16x16x32_bf16 v[28:31], v[194:197], v[226:229], v[28:31]
	v_mfma_f32_16x16x32_bf16 v[24:27], v[202:205], v[226:229], v[24:27]
	v_mfma_f32_16x16x32_bf16 v[4:7], v[194:197], v[234:237], v[4:7]
	v_mfma_f32_16x16x32_bf16 v[0:3], v[202:205], v[234:237], v[0:3]
	v_mfma_f32_16x16x32_bf16 v[16:19], v[194:197], v[210:213], v[16:19]
	v_mfma_f32_16x16x32_bf16 v[20:23], v[202:205], v[210:213], v[20:23]
	v_mfma_f32_16x16x32_bf16 v[32:35], v[194:197], v[218:221], v[32:35]
	v_mfma_f32_16x16x32_bf16 v[36:39], v[202:205], v[218:221], v[36:39]
	s_setprio 0
	s_barrier
	s_add_i32 s50, 0, 0x18000
	s_add_i32 s51, 0, 0x1c000
	v_add_u32_e32 v68, s50, v171
	v_add_u32_e32 v152, s51, v171
	ds_read_b128 v[48:51], v68
	ds_read_b128 v[52:55], v68 offset:1024
	ds_read_b128 v[64:67], v68 offset:2048
	ds_read_b128 v[68:71], v68 offset:3072
	ds_read_b128 v[184:187], v152
	ds_read_b128 v[194:197], v152 offset:1024
	ds_read_b128 v[198:201], v152 offset:2048
	ds_read_b128 v[202:205], v152 offset:3072
	s_add_u32 s14, s14, 0x40000
	s_addc_u32 s15, s15, 0
	s_mov_b32 m0, s59
	ds_read_b128 v[206:209], v191 offset:32768
	ds_read_b128 v[210:213], v191 offset:33792
	ds_read_b128 v[214:217], v191 offset:34816
	ds_read_b128 v[218:221], v191 offset:35840
	ds_read_b128 v[222:225], v191 offset:36864
	ds_read_b128 v[226:229], v191 offset:37888
	ds_read_b128 v[230:233], v191 offset:38912
	ds_read_b128 v[234:237], v191 offset:39936
	global_load_lds_dwordx4 v144, s[14:15]
	s_mov_b32 m0, s60
	s_nop 0
	global_load_lds_dwordx4 v148, s[14:15]
	s_waitcnt vmcnt(8)
	s_waitcnt lgkmcnt(0)
	s_barrier
	s_setprio 1
	s_waitcnt lgkmcnt(0)
	v_mfma_f32_16x16x32_bf16 v[140:143], v[48:51], v[206:209], v[140:143]
	v_mfma_f32_16x16x32_bf16 v[136:139], v[64:67], v[206:209], v[136:139]
	v_mfma_f32_16x16x32_bf16 v[124:127], v[48:51], v[214:217], v[124:127]
	v_mfma_f32_16x16x32_bf16 v[120:123], v[64:67], v[214:217], v[120:123]
	v_mfma_f32_16x16x32_bf16 v[108:111], v[48:51], v[222:225], v[108:111]
	v_mfma_f32_16x16x32_bf16 v[104:107], v[64:67], v[222:225], v[104:107]
	v_mfma_f32_16x16x32_bf16 v[92:95], v[48:51], v[230:233], v[92:95]
	v_mfma_f32_16x16x32_bf16 v[88:91], v[64:67], v[230:233], v[88:91]
	v_mfma_f32_16x16x32_bf16 v[140:143], v[52:55], v[210:213], v[140:143]
	v_mfma_f32_16x16x32_bf16 v[136:139], v[68:71], v[210:213], v[136:139]
	v_mfma_f32_16x16x32_bf16 v[124:127], v[52:55], v[218:221], v[124:127]
	v_mfma_f32_16x16x32_bf16 v[120:123], v[68:71], v[218:221], v[120:123]
	v_mfma_f32_16x16x32_bf16 v[108:111], v[52:55], v[226:229], v[108:111]
	v_mfma_f32_16x16x32_bf16 v[104:107], v[68:71], v[226:229], v[104:107]
	v_mfma_f32_16x16x32_bf16 v[92:95], v[52:55], v[234:237], v[92:95]
	v_mfma_f32_16x16x32_bf16 v[88:91], v[68:71], v[234:237], v[88:91]
	s_setprio 0
	s_setprio 1
	v_mfma_f32_16x16x32_bf16 v[132:135], v[184:187], v[206:209], v[132:135]
	v_mfma_f32_16x16x32_bf16 v[128:131], v[198:201], v[206:209], v[128:131]
	v_mfma_f32_16x16x32_bf16 v[116:119], v[184:187], v[214:217], v[116:119]
	v_mfma_f32_16x16x32_bf16 v[112:115], v[198:201], v[214:217], v[112:115]
	v_mfma_f32_16x16x32_bf16 v[100:103], v[184:187], v[222:225], v[100:103]
	v_mfma_f32_16x16x32_bf16 v[96:99], v[198:201], v[222:225], v[96:99]
	v_mfma_f32_16x16x32_bf16 v[84:87], v[184:187], v[230:233], v[84:87]
	v_mfma_f32_16x16x32_bf16 v[80:83], v[198:201], v[230:233], v[80:83]
	v_mfma_f32_16x16x32_bf16 v[132:135], v[194:197], v[210:213], v[132:135]
	v_mfma_f32_16x16x32_bf16 v[128:131], v[202:205], v[210:213], v[128:131]
	v_mfma_f32_16x16x32_bf16 v[116:119], v[194:197], v[218:221], v[116:119]
	v_mfma_f32_16x16x32_bf16 v[112:115], v[202:205], v[218:221], v[112:115]
	v_mfma_f32_16x16x32_bf16 v[100:103], v[194:197], v[226:229], v[100:103]
	v_mfma_f32_16x16x32_bf16 v[96:99], v[202:205], v[226:229], v[96:99]
	v_mfma_f32_16x16x32_bf16 v[84:87], v[194:197], v[234:237], v[84:87]
	v_mfma_f32_16x16x32_bf16 v[80:83], v[202:205], v[234:237], v[80:83]
	s_setprio 0
	s_barrier
; #define PG8_STAGE(bufoff, gbase, voff) do { _Pragma("unroll") for (int _i = 0; _i < 2; ++_i) \
;         __builtin_amdgcn_global_load_lds((const unsigned*)((const char*)(gbase) + (voff)[_i]), (LAS unsigned*)(lds + (bufoff) + ldsw + _i * 8192), 16, 0, 0); } while (0)
; #define PG8_LDA(dst, b, h) do { _Pragma("unroll") for (int m = 0; m < 4; ++m) _Pragma("unroll") for (int k = 0; k < 2; ++k) dst[m][k] = *(const LAS bf16x8*)(lds + PG8_SA(b, h) + aoff + m * 2048 + k * 1024); } while (0)
; #define PG8_LDB(dst, b, h) do { _Pragma("unroll") for (int n = 0; n < 2; ++n) _Pragma("unroll") for (int k = 0; k < 2; ++k) dst[n][k] = *(const LAS bf16x8*)(lds + PG8_SB(b, h) + boff + n * 2048 + k * 1024); } while (0)
; #define PG8_WAIT_V(n) asm volatile("s_waitcnt vmcnt(" #n ")" ::: "memory")
; #define PG8_WAIT_L(n) asm volatile("s_waitcnt lgkmcnt(" #n ")" ::: "memory")
; #define PG8_BAR __builtin_amdgcn_s_barrier()
; #define PG8_SCHED __builtin_amdgcn_sched_barrier(0)
; template <class Epi, class Sched>
; __device__ __forceinline__ void gemm_phase(LAS unsigned char* lds, const Gemm g, const Sched& S, const Epi& E, int wave_id) {
;     ...
;         for (int t = 0; t < nt; t += 2) {
;             const bool last = (t == nt - 2);
;             const char* a1 = cA + (size_t)(t + 1) * kstep;
;             const char* a2 = last ? nA : cA + (size_t)(t + 2) * kstep; const char* b2 = last ? nB : cB + (size_t)(t + 2) * kstep;
;             const char* a3 = a2 + kstep; const char* b3 = b2 + kstep;
;             PG8_LDB(B0, 0, 0); PG8_LDB(B1, 0, 1); PG8_SCHED; PG8_LDA(At, 0, 0); PG8_STAGE(PG8_SA(1, 1), a1 + hstepA, voffA);
;             PG8_WAIT_V(8); PG8_WAIT_L(0); PG8_BAR; PG8_MMA(0, 0, At, B0); PG8_MMA(0, 1, At, B1); PG8_BAR; PG8_SCHED;
;             PG8_LDA(At, 0, 1); PG8_STAGE(PG8_SB(0, 0), b2, voffB); PG8_STAGE(PG8_SB(0, 1), b2 + hstepB, voffB); PG8_STAGE(PG8_SA(0, 0), a2, voffA);
;             PG8_WAIT_V(8); PG8_WAIT_L(0); PG8_BAR; PG8_MMA(1, 0, At, B0); PG8_MMA(1, 1, At, B1); PG8_BAR; PG8_SCHED;
;             PG8_LDB(B0, 1, 0); PG8_LDB(B1, 1, 1); PG8_SCHED; PG8_LDA(At, 1, 0); PG8_STAGE(PG8_SA(0, 1), a2 + hstepA, voffA);
;             PG8_WAIT_V(8); PG8_WAIT_L(0); PG8_BAR; PG8_MMA(0, 0, At, B0); PG8_MMA(0, 1, At, B1); PG8_BAR; PG8_SCHED;
;             PG8_LDA(At, 1, 1); PG8_STAGE(PG8_SB(1, 0), b3, voffB); PG8_STAGE(PG8_SB(1, 1), b3 + hstepB, voffB); PG8_STAGE(PG8_SA(1, 0), a3, voffA);
	s_add_i32 s14, s50, s54
	v_lshl_add_u64 v[168:169], v[168:169], 0, s[22:23]
	s_mov_b32 m0, s14
	ds_read_b128 v[206:209], v191 offset:49152
	ds_read_b128 v[210:213], v191 offset:50176
	ds_read_b128 v[214:217], v191 offset:51200
	ds_read_b128 v[218:221], v191 offset:52224
	ds_read_b128 v[222:225], v191 offset:53248
	ds_read_b128 v[226:229], v191 offset:54272
	ds_read_b128 v[230:233], v191 offset:55296
	ds_read_b128 v[234:237], v191 offset:56320
	global_load_lds_dwordx4 v[168:169], off
	s_add_i32 m0, s14, 0x2000
	s_add_u32 s12, s12, 0x40080
	v_lshl_add_u64 v[168:169], v[188:189], 0, s[22:23]
	s_addc_u32 s13, s13, 0
	s_add_i32 s14, s51, s54
	global_load_lds_dwordx4 v[168:169], off
	s_mov_b32 m0, s14
	s_nop 0
	global_load_lds_dwordx4 v146, s[12:13]
	s_add_i32 m0, s14, 0x2000
	s_nop 0
	global_load_lds_dwordx4 v150, s[12:13]
	v_lshl_add_u64 v[168:169], v[238:239], 0, s[22:23]
	s_mov_b32 m0, s62
	s_nop 0
	global_load_lds_dwordx4 v[168:169], off
	v_lshl_add_u64 v[168:169], v[240:241], 0, s[22:23]
	s_mov_b32 m0, s63
	s_nop 0
	global_load_lds_dwordx4 v[168:169], off
	s_waitcnt vmcnt(8)
	s_waitcnt lgkmcnt(0)
	s_barrier
	s_setprio 1
	s_waitcnt lgkmcnt(0)
	v_mfma_f32_16x16x32_bf16 v[76:79], v[48:51], v[206:209], v[76:79]
	v_mfma_f32_16x16x32_bf16 v[72:75], v[64:67], v[206:209], v[72:75]
	v_mfma_f32_16x16x32_bf16 v[60:63], v[48:51], v[214:217], v[60:63]
	v_mfma_f32_16x16x32_bf16 v[56:59], v[64:67], v[214:217], v[56:59]
	v_mfma_f32_16x16x32_bf16 v[44:47], v[48:51], v[222:225], v[44:47]
	v_mfma_f32_16x16x32_bf16 v[40:43], v[64:67], v[222:225], v[40:43]
	v_mfma_f32_16x16x32_bf16 v[12:15], v[48:51], v[230:233], v[12:15]
	v_mfma_f32_16x16x32_bf16 v[8:11], v[64:67], v[230:233], v[8:11]
	v_mfma_f32_16x16x32_bf16 v[76:79], v[52:55], v[210:213], v[76:79]
	v_mfma_f32_16x16x32_bf16 v[72:75], v[68:71], v[210:213], v[72:75]
	v_mfma_f32_16x16x32_bf16 v[60:63], v[52:55], v[218:221], v[60:63]
	v_mfma_f32_16x16x32_bf16 v[56:59], v[68:71], v[218:221], v[56:59]
	v_mfma_f32_16x16x32_bf16 v[44:47], v[52:55], v[226:229], v[44:47]
	v_mfma_f32_16x16x32_bf16 v[40:43], v[68:71], v[226:229], v[40:43]
	v_mfma_f32_16x16x32_bf16 v[12:15], v[52:55], v[234:237], v[12:15]
	v_mfma_f32_16x16x32_bf16 v[8:11], v[68:71], v[234:237], v[8:11]
	s_setprio 0
	s_setprio 1
	v_mfma_f32_16x16x32_bf16 v[16:19], v[184:187], v[206:209], v[16:19]
	v_mfma_f32_16x16x32_bf16 v[68:71], v[194:197], v[210:213], v[16:19]
	v_mfma_f32_16x16x32_bf16 v[16:19], v[198:201], v[206:209], v[20:23]
	v_mfma_f32_16x16x32_bf16 v[64:67], v[202:205], v[210:213], v[16:19]
	v_mfma_f32_16x16x32_bf16 v[16:19], v[184:187], v[214:217], v[32:35]
	v_mfma_f32_16x16x32_bf16 v[52:55], v[194:197], v[218:221], v[16:19]
	v_mfma_f32_16x16x32_bf16 v[16:19], v[198:201], v[214:217], v[36:39]
	v_mfma_f32_16x16x32_bf16 v[48:51], v[202:205], v[218:221], v[16:19]
	v_mfma_f32_16x16x32_bf16 v[16:19], v[184:187], v[222:225], v[28:31]
	v_mfma_f32_16x16x32_bf16 v[28:31], v[194:197], v[226:229], v[16:19]
	v_mfma_f32_16x16x32_bf16 v[16:19], v[198:201], v[222:225], v[24:27]
	v_mfma_f32_16x16x32_bf16 v[4:7], v[184:187], v[230:233], v[4:7]
	v_mfma_f32_16x16x32_bf16 v[0:3], v[198:201], v[230:233], v[0:3]
	v_mfma_f32_16x16x32_bf16 v[24:27], v[202:205], v[226:229], v[16:19]
	v_mfma_f32_16x16x32_bf16 v[4:7], v[194:197], v[234:237], v[4:7]
	v_mfma_f32_16x16x32_bf16 v[0:3], v[202:205], v[234:237], v[0:3]
	s_setprio 0
	s_barrier
	s_add_i32 s45, s45, 2
	s_add_u32 s10, s10, 0x100
	s_addc_u32 s11, s11, 0
	s_add_u32 s33, s33, 0x100
	s_addc_u32 s39, s39, 0
	s_cmp_gt_u32 s45, 13
.LBB0_252:
	ds_read_b128 v[16:19], v183
	ds_read_b128 v[20:23], v183 offset:1024
	ds_read_b128 v[32:35], v183 offset:2048
	ds_read_b128 v[36:39], v183 offset:3072
	ds_read_b128 v[184:187], v190
	ds_read_b128 v[194:197], v190 offset:1024
	ds_read_b128 v[198:201], v190 offset:2048
	ds_read_b128 v[202:205], v190 offset:3072
	s_add_u32 s12, s10, 0xfffc0080
	s_addc_u32 s13, s11, -1
	s_cmp_eq_u32 s45, 12
	s_cselect_b32 s15, s2, s13
	s_cselect_b32 s14, s7, s12
	s_cselect_b32 s13, s9, s39
	s_cselect_b32 s12, s18, s33
	s_add_i32 m0, s55, 0xc000
	ds_read_b128 v[206:209], v191
	ds_read_b128 v[210:213], v191 offset:1024
	ds_read_b128 v[214:217], v191 offset:2048
	ds_read_b128 v[218:221], v191 offset:3072
	ds_read_b128 v[222:225], v191 offset:4096
	ds_read_b128 v[226:229], v191 offset:5120
	ds_read_b128 v[230:233], v191 offset:6144
	ds_read_b128 v[234:237], v191 offset:7168
	global_load_lds_dwordx4 v158, s[10:11]
	s_add_i32 m0, s55, 0xe000
	s_nop 0
	global_load_lds_dwordx4 v160, s[10:11]
	s_waitcnt vmcnt(8)
	s_waitcnt lgkmcnt(0)
	s_barrier
; #define PG8_STAGE(bufoff, gbase, voff) do { _Pragma("unroll") for (int _i = 0; _i < 2; ++_i) \
;         __builtin_amdgcn_global_load_lds((const unsigned*)((const char*)(gbase) + (voff)[_i]), (LAS unsigned*)(lds + (bufoff) + ldsw + _i * 8192), 16, 0, 0); } while (0)
; #define PG8_LDA(dst, b, h) do { _Pragma("unroll") for (int m = 0; m < 4; ++m) _Pragma("unroll") for (int k = 0; k < 2; ++k) dst[m][k] = *(const LAS bf16x8*)(lds + PG8_SA(b, h) + aoff + m * 2048 + k * 1024); } while (0)
; #define PG8_MMA(ai, bj, At, Bt) do { __builtin_amdgcn_s_setprio(1); _Pragma("unroll") for (int m = 0; m < 4; ++m) _Pragma("unroll") for (int n = 0; n < 2; ++n) _Pragma("unroll") for (int k = 0; k < 2; ++k) \
;         acc[ai][bj][m][n] = __builtin_amdgcn_mfma_f32_16x16x32_bf16(Bt[n][k], At[m][k], acc[ai][bj][m][n], 0, 0, 0); __builtin_amdgcn_s_setprio(0); } while (0)
; #define PG8_WAIT_V(n) asm volatile("s_waitcnt vmcnt(" #n ")" ::: "memory")
; #define PG8_WAIT_L(n) asm volatile("s_waitcnt lgkmcnt(" #n ")" ::: "memory")
; #define PG8_BAR __builtin_amdgcn_s_barrier()
; #define PG8_SCHED __builtin_amdgcn_sched_barrier(0)
; template <class Epi, class Sched>
; __device__ __forceinline__ void gemm_phase(LAS unsigned char* lds, const Gemm g, const Sched& S, const Epi& E, int wave_id) {
;     ...
;             PG8_WAIT_V(8); PG8_WAIT_L(0); PG8_BAR; PG8_MMA(0, 0, At, B0); PG8_MMA(0, 1, At, B1); PG8_BAR; PG8_SCHED;
;             PG8_LDA(At, 0, 1); PG8_STAGE(PG8_SB(0, 0), b2, voffB); PG8_STAGE(PG8_SB(0, 1), b2 + hstepB, voffB); PG8_STAGE(PG8_SA(0, 0), a2, voffA);
;             PG8_WAIT_V(8); PG8_WAIT_L(0); PG8_BAR; PG8_MMA(1, 0, At, B0); PG8_MMA(1, 1, At, B1); PG8_BAR; PG8_SCHED;
	s_setprio 1
	s_waitcnt lgkmcnt(0)
	v_mfma_f32_16x16x32_bf16 v[140:143], v[16:19], v[206:209], v[140:143]
	v_mfma_f32_16x16x32_bf16 v[136:139], v[32:35], v[206:209], v[136:139]
	v_mfma_f32_16x16x32_bf16 v[124:127], v[16:19], v[214:217], v[124:127]
	v_mfma_f32_16x16x32_bf16 v[120:123], v[32:35], v[214:217], v[120:123]
	v_mfma_f32_16x16x32_bf16 v[108:111], v[16:19], v[222:225], v[108:111]
	v_mfma_f32_16x16x32_bf16 v[104:107], v[32:35], v[222:225], v[104:107]
	v_mfma_f32_16x16x32_bf16 v[92:95], v[16:19], v[230:233], v[92:95]
	v_mfma_f32_16x16x32_bf16 v[88:91], v[32:35], v[230:233], v[88:91]
	v_mfma_f32_16x16x32_bf16 v[140:143], v[20:23], v[210:213], v[140:143]
	v_mfma_f32_16x16x32_bf16 v[136:139], v[36:39], v[210:213], v[136:139]
	v_mfma_f32_16x16x32_bf16 v[124:127], v[20:23], v[218:221], v[124:127]
	v_mfma_f32_16x16x32_bf16 v[120:123], v[36:39], v[218:221], v[120:123]
	v_mfma_f32_16x16x32_bf16 v[108:111], v[20:23], v[226:229], v[108:111]
	v_mfma_f32_16x16x32_bf16 v[104:107], v[36:39], v[226:229], v[104:107]
	v_mfma_f32_16x16x32_bf16 v[92:95], v[20:23], v[234:237], v[92:95]
	v_mfma_f32_16x16x32_bf16 v[88:91], v[36:39], v[234:237], v[88:91]
	s_setprio 0
	s_setprio 1
	v_mfma_f32_16x16x32_bf16 v[132:135], v[184:187], v[206:209], v[132:135]
	v_mfma_f32_16x16x32_bf16 v[128:131], v[198:201], v[206:209], v[128:131]
	v_mfma_f32_16x16x32_bf16 v[116:119], v[184:187], v[214:217], v[116:119]
	v_mfma_f32_16x16x32_bf16 v[112:115], v[198:201], v[214:217], v[112:115]
	v_mfma_f32_16x16x32_bf16 v[100:103], v[184:187], v[222:225], v[100:103]
	v_mfma_f32_16x16x32_bf16 v[96:99], v[198:201], v[222:225], v[96:99]
	v_mfma_f32_16x16x32_bf16 v[84:87], v[184:187], v[230:233], v[84:87]
	v_mfma_f32_16x16x32_bf16 v[80:83], v[198:201], v[230:233], v[80:83]
	v_mfma_f32_16x16x32_bf16 v[132:135], v[194:197], v[210:213], v[132:135]
	v_mfma_f32_16x16x32_bf16 v[128:131], v[202:205], v[210:213], v[128:131]
	v_mfma_f32_16x16x32_bf16 v[116:119], v[194:197], v[218:221], v[116:119]
	v_mfma_f32_16x16x32_bf16 v[112:115], v[202:205], v[218:221], v[112:115]
	v_mfma_f32_16x16x32_bf16 v[100:103], v[194:197], v[226:229], v[100:103]
	v_mfma_f32_16x16x32_bf16 v[96:99], v[202:205], v[226:229], v[96:99]
	v_mfma_f32_16x16x32_bf16 v[84:87], v[194:197], v[234:237], v[84:87]
	v_mfma_f32_16x16x32_bf16 v[80:83], v[202:205], v[234:237], v[80:83]
	s_setprio 0
	s_barrier
	s_add_i32 s50, s67, s54
	v_lshl_add_u64 v[168:169], s[12:13], 0, v[146:147]
	s_mov_b32 m0, s50
	ds_read_b128 v[206:209], v191 offset:16384
	ds_read_b128 v[210:213], v191 offset:17408
	ds_read_b128 v[214:217], v191 offset:18432
	ds_read_b128 v[218:221], v191 offset:19456
	ds_read_b128 v[222:225], v191 offset:20480
	ds_read_b128 v[226:229], v191 offset:21504
	ds_read_b128 v[230:233], v191 offset:22528
	ds_read_b128 v[234:237], v191 offset:23552
	global_load_lds_dwordx4 v[168:169], off
	s_add_i32 m0, s50, 0x2000
	s_add_u32 s50, s12, 0x40000
	v_lshl_add_u64 v[188:189], s[12:13], 0, v[150:151]
	s_addc_u32 s51, s13, 0
	s_add_i32 s78, s72, s54
	global_load_lds_dwordx4 v[188:189], off
	s_mov_b32 m0, s78
	v_lshl_add_u64 v[240:241], s[14:15], 0, v[148:149]
	global_load_lds_dwordx4 v146, s[50:51]
	s_add_i32 m0, s78, 0x2000
	s_nop 0
	global_load_lds_dwordx4 v150, s[50:51]
	v_lshl_add_u64 v[238:239], s[14:15], 0, v[144:145]
	s_mov_b32 m0, s55
	s_nop 0
	global_load_lds_dwordx4 v[238:239], off
	s_mov_b32 m0, s58
	s_nop 0
	global_load_lds_dwordx4 v[240:241], off
	s_waitcnt vmcnt(8)
	s_waitcnt lgkmcnt(0)
	s_barrier
	s_setprio 1
	s_waitcnt lgkmcnt(0)
	v_mfma_f32_16x16x32_bf16 v[76:79], v[16:19], v[206:209], v[76:79]
	v_mfma_f32_16x16x32_bf16 v[72:75], v[32:35], v[206:209], v[72:75]
	v_mfma_f32_16x16x32_bf16 v[60:63], v[16:19], v[214:217], v[60:63]
	v_mfma_f32_16x16x32_bf16 v[56:59], v[32:35], v[214:217], v[56:59]
	v_mfma_f32_16x16x32_bf16 v[44:47], v[16:19], v[222:225], v[44:47]
	v_mfma_f32_16x16x32_bf16 v[40:43], v[32:35], v[222:225], v[40:43]
	v_mfma_f32_16x16x32_bf16 v[12:15], v[16:19], v[230:233], v[12:15]
	v_mfma_f32_16x16x32_bf16 v[8:11], v[32:35], v[230:233], v[8:11]
	v_mfma_f32_16x16x32_bf16 v[76:79], v[20:23], v[210:213], v[76:79]
	v_mfma_f32_16x16x32_bf16 v[72:75], v[36:39], v[210:213], v[72:75]
	v_mfma_f32_16x16x32_bf16 v[60:63], v[20:23], v[218:221], v[60:63]
	v_mfma_f32_16x16x32_bf16 v[56:59], v[36:39], v[218:221], v[56:59]
	v_mfma_f32_16x16x32_bf16 v[44:47], v[20:23], v[226:229], v[44:47]
	v_mfma_f32_16x16x32_bf16 v[40:43], v[36:39], v[226:229], v[40:43]
	v_mfma_f32_16x16x32_bf16 v[12:15], v[20:23], v[234:237], v[12:15]
	v_mfma_f32_16x16x32_bf16 v[8:11], v[36:39], v[234:237], v[8:11]
	s_setprio 0
	s_setprio 1
	v_mfma_f32_16x16x32_bf16 v[28:31], v[184:187], v[222:225], v[28:31]
	v_mfma_f32_16x16x32_bf16 v[24:27], v[198:201], v[222:225], v[24:27]
	v_mfma_f32_16x16x32_bf16 v[4:7], v[184:187], v[230:233], v[4:7]
	v_mfma_f32_16x16x32_bf16 v[0:3], v[198:201], v[230:233], v[0:3]
	v_mfma_f32_16x16x32_bf16 v[16:19], v[184:187], v[206:209], v[68:71]
	v_mfma_f32_16x16x32_bf16 v[20:23], v[198:201], v[206:209], v[64:67]
	v_mfma_f32_16x16x32_bf16 v[32:35], v[184:187], v[214:217], v[52:55]
	v_mfma_f32_16x16x32_bf16 v[36:39], v[198:201], v[214:217], v[48:51]
	v_mfma_f32_16x16x32_bf16 v[28:31], v[194:197], v[226:229], v[28:31]
	v_mfma_f32_16x16x32_bf16 v[24:27], v[202:205], v[226:229], v[24:27]
	v_mfma_f32_16x16x32_bf16 v[4:7], v[194:197], v[234:237], v[4:7]
	v_mfma_f32_16x16x32_bf16 v[0:3], v[202:205], v[234:237], v[0:3]
	v_mfma_f32_16x16x32_bf16 v[16:19], v[194:197], v[210:213], v[16:19]
	v_mfma_f32_16x16x32_bf16 v[20:23], v[202:205], v[210:213], v[20:23]
	v_mfma_f32_16x16x32_bf16 v[32:35], v[194:197], v[218:221], v[32:35]
	v_mfma_f32_16x16x32_bf16 v[36:39], v[202:205], v[218:221], v[36:39]
	s_setprio 0
	s_barrier
; #define PG8_STAGE(bufoff, gbase, voff) do { _Pragma("unroll") for (int _i = 0; _i < 2; ++_i) \
;         __builtin_amdgcn_global_load_lds((const unsigned*)((const char*)(gbase) + (voff)[_i]), (LAS unsigned*)(lds + (bufoff) + ldsw + _i * 8192), 16, 0, 0); } while (0)
; #define PG8_LDA(dst, b, h) do { _Pragma("unroll") for (int m = 0; m < 4; ++m) _Pragma("unroll") for (int k = 0; k < 2; ++k) dst[m][k] = *(const LAS bf16x8*)(lds + PG8_SA(b, h) + aoff + m * 2048 + k * 1024); } while (0)
; #define PG8_LDB(dst, b, h) do { _Pragma("unroll") for (int n = 0; n < 2; ++n) _Pragma("unroll") for (int k = 0; k < 2; ++k) dst[n][k] = *(const LAS bf16x8*)(lds + PG8_SB(b, h) + boff + n * 2048 + k * 1024); } while (0)
; #define PG8_MMA(ai, bj, At, Bt) do { __builtin_amdgcn_s_setprio(1); _Pragma("unroll") for (int m = 0; m < 4; ++m) _Pragma("unroll") for (int n = 0; n < 2; ++n) _Pragma("unroll") for (int k = 0; k < 2; ++k) \
;         acc[ai][bj][m][n] = __builtin_amdgcn_mfma_f32_16x16x32_bf16(Bt[n][k], At[m][k], acc[ai][bj][m][n], 0, 0, 0); __builtin_amdgcn_s_setprio(0); } while (0)
; #define PG8_WAIT_V(n) asm volatile("s_waitcnt vmcnt(" #n ")" ::: "memory")
; #define PG8_WAIT_L(n) asm volatile("s_waitcnt lgkmcnt(" #n ")" ::: "memory")
; #define PG8_BAR __builtin_amdgcn_s_barrier()
; #define PG8_SCHED __builtin_amdgcn_sched_barrier(0)
; template <class Epi, class Sched>
; __device__ __forceinline__ void gemm_phase(LAS unsigned char* lds, const Gemm g, const Sched& S, const Epi& E, int wave_id) {
;     ...
;             PG8_LDB(B0, 1, 0); PG8_LDB(B1, 1, 1); PG8_SCHED; PG8_LDA(At, 1, 0); PG8_STAGE(PG8_SA(0, 1), a2 + hstepA, voffA);
;             PG8_WAIT_V(8); PG8_WAIT_L(0); PG8_BAR; PG8_MMA(0, 0, At, B0); PG8_MMA(0, 1, At, B1); PG8_BAR; PG8_SCHED;
;             PG8_LDA(At, 1, 1); PG8_STAGE(PG8_SB(1, 0), b3, voffB); PG8_STAGE(PG8_SB(1, 1), b3 + hstepB, voffB); PG8_STAGE(PG8_SA(1, 0), a3, voffA);
;             PG8_WAIT_V(8); PG8_WAIT_L(0); PG8_BAR; PG8_MMA(1, 0, At, B0); PG8_MMA(1, 1, At, B1); PG8_BAR; PG8_SCHED;
;         }
;         if (wr == 0) PG8_BAR;
	s_add_i32 s50, 0, 0x18000
	s_add_i32 s51, 0, 0x1c000
	v_add_u32_e32 v68, s50, v171
	v_add_u32_e32 v152, s51, v171
	ds_read_b128 v[48:51], v68
	ds_read_b128 v[52:55], v68 offset:1024
	ds_read_b128 v[64:67], v68 offset:2048
	ds_read_b128 v[68:71], v68 offset:3072
	ds_read_b128 v[184:187], v152
	ds_read_b128 v[194:197], v152 offset:1024
	ds_read_b128 v[198:201], v152 offset:2048
	ds_read_b128 v[202:205], v152 offset:3072
	s_add_u32 s14, s14, 0x40000
	s_addc_u32 s15, s15, 0
	s_mov_b32 m0, s59
	ds_read_b128 v[206:209], v191 offset:32768
	ds_read_b128 v[210:213], v191 offset:33792
	ds_read_b128 v[214:217], v191 offset:34816
	ds_read_b128 v[218:221], v191 offset:35840
	ds_read_b128 v[222:225], v191 offset:36864
	ds_read_b128 v[226:229], v191 offset:37888
	ds_read_b128 v[230:233], v191 offset:38912
	ds_read_b128 v[234:237], v191 offset:39936
	global_load_lds_dwordx4 v144, s[14:15]
	s_mov_b32 m0, s60
	s_nop 0
	global_load_lds_dwordx4 v148, s[14:15]
	s_waitcnt vmcnt(8)
	s_waitcnt lgkmcnt(0)
	s_barrier
	s_setprio 1
	s_waitcnt lgkmcnt(0)
	v_mfma_f32_16x16x32_bf16 v[140:143], v[48:51], v[206:209], v[140:143]
	v_mfma_f32_16x16x32_bf16 v[136:139], v[64:67], v[206:209], v[136:139]
	v_mfma_f32_16x16x32_bf16 v[124:127], v[48:51], v[214:217], v[124:127]
	v_mfma_f32_16x16x32_bf16 v[120:123], v[64:67], v[214:217], v[120:123]
	v_mfma_f32_16x16x32_bf16 v[108:111], v[48:51], v[222:225], v[108:111]
	v_mfma_f32_16x16x32_bf16 v[104:107], v[64:67], v[222:225], v[104:107]
	v_mfma_f32_16x16x32_bf16 v[92:95], v[48:51], v[230:233], v[92:95]
	v_mfma_f32_16x16x32_bf16 v[88:91], v[64:67], v[230:233], v[88:91]
	v_mfma_f32_16x16x32_bf16 v[140:143], v[52:55], v[210:213], v[140:143]
	v_mfma_f32_16x16x32_bf16 v[136:139], v[68:71], v[210:213], v[136:139]
	v_mfma_f32_16x16x32_bf16 v[124:127], v[52:55], v[218:221], v[124:127]
	v_mfma_f32_16x16x32_bf16 v[120:123], v[68:71], v[218:221], v[120:123]
	v_mfma_f32_16x16x32_bf16 v[108:111], v[52:55], v[226:229], v[108:111]
	v_mfma_f32_16x16x32_bf16 v[104:107], v[68:71], v[226:229], v[104:107]
	v_mfma_f32_16x16x32_bf16 v[92:95], v[52:55], v[234:237], v[92:95]
	v_mfma_f32_16x16x32_bf16 v[88:91], v[68:71], v[234:237], v[88:91]
	s_setprio 0
	s_setprio 1
	v_mfma_f32_16x16x32_bf16 v[132:135], v[184:187], v[206:209], v[132:135]
	v_mfma_f32_16x16x32_bf16 v[128:131], v[198:201], v[206:209], v[128:131]
	v_mfma_f32_16x16x32_bf16 v[116:119], v[184:187], v[214:217], v[116:119]
	v_mfma_f32_16x16x32_bf16 v[112:115], v[198:201], v[214:217], v[112:115]
	v_mfma_f32_16x16x32_bf16 v[100:103], v[184:187], v[222:225], v[100:103]
	v_mfma_f32_16x16x32_bf16 v[96:99], v[198:201], v[222:225], v[96:99]
	v_mfma_f32_16x16x32_bf16 v[84:87], v[184:187], v[230:233], v[84:87]
	v_mfma_f32_16x16x32_bf16 v[80:83], v[198:201], v[230:233], v[80:83]
	v_mfma_f32_16x16x32_bf16 v[132:135], v[194:197], v[210:213], v[132:135]
	v_mfma_f32_16x16x32_bf16 v[128:131], v[202:205], v[210:213], v[128:131]
	v_mfma_f32_16x16x32_bf16 v[116:119], v[194:197], v[218:221], v[116:119]
	v_mfma_f32_16x16x32_bf16 v[112:115], v[202:205], v[218:221], v[112:115]
	v_mfma_f32_16x16x32_bf16 v[100:103], v[194:197], v[226:229], v[100:103]
	v_mfma_f32_16x16x32_bf16 v[96:99], v[202:205], v[226:229], v[96:99]
	v_mfma_f32_16x16x32_bf16 v[84:87], v[194:197], v[234:237], v[84:87]
	v_mfma_f32_16x16x32_bf16 v[80:83], v[202:205], v[234:237], v[80:83]
	s_setprio 0
	s_barrier
	s_add_i32 s14, s50, s54
	v_lshl_add_u64 v[168:169], v[168:169], 0, s[22:23]
	s_mov_b32 m0, s14
	ds_read_b128 v[206:209], v191 offset:49152
	ds_read_b128 v[210:213], v191 offset:50176
	ds_read_b128 v[214:217], v191 offset:51200
	ds_read_b128 v[218:221], v191 offset:52224
	ds_read_b128 v[222:225], v191 offset:53248
	ds_read_b128 v[226:229], v191 offset:54272
	ds_read_b128 v[230:233], v191 offset:55296
	ds_read_b128 v[234:237], v191 offset:56320
	global_load_lds_dwordx4 v[168:169], off
	s_add_i32 m0, s14, 0x2000
	s_add_u32 s12, s12, 0x40080
	v_lshl_add_u64 v[168:169], v[188:189], 0, s[22:23]
	s_addc_u32 s13, s13, 0
	s_add_i32 s14, s51, s54
	global_load_lds_dwordx4 v[168:169], off
	s_mov_b32 m0, s14
	s_nop 0
	global_load_lds_dwordx4 v146, s[12:13]
	s_add_i32 m0, s14, 0x2000
	s_nop 0
	global_load_lds_dwordx4 v150, s[12:13]
	v_lshl_add_u64 v[168:169], v[238:239], 0, s[22:23]
	s_mov_b32 m0, s62
	s_nop 0
	global_load_lds_dwordx4 v[168:169], off
	v_lshl_add_u64 v[168:169], v[240:241], 0, s[22:23]
	s_mov_b32 m0, s63
	s_nop 0
	global_load_lds_dwordx4 v[168:169], off
	s_waitcnt vmcnt(8)
	s_waitcnt lgkmcnt(0)
	s_barrier
	s_setprio 1
	s_waitcnt lgkmcnt(0)
	v_mfma_f32_16x16x32_bf16 v[76:79], v[48:51], v[206:209], v[76:79]
	v_mfma_f32_16x16x32_bf16 v[72:75], v[64:67], v[206:209], v[72:75]
	v_mfma_f32_16x16x32_bf16 v[60:63], v[48:51], v[214:217], v[60:63]
	v_mfma_f32_16x16x32_bf16 v[56:59], v[64:67], v[214:217], v[56:59]
	v_mfma_f32_16x16x32_bf16 v[44:47], v[48:51], v[222:225], v[44:47]
	v_mfma_f32_16x16x32_bf16 v[40:43], v[64:67], v[222:225], v[40:43]
	v_mfma_f32_16x16x32_bf16 v[12:15], v[48:51], v[230:233], v[12:15]
	v_mfma_f32_16x16x32_bf16 v[8:11], v[64:67], v[230:233], v[8:11]
	v_mfma_f32_16x16x32_bf16 v[76:79], v[52:55], v[210:213], v[76:79]
	v_mfma_f32_16x16x32_bf16 v[72:75], v[68:71], v[210:213], v[72:75]
	v_mfma_f32_16x16x32_bf16 v[60:63], v[52:55], v[218:221], v[60:63]
	v_mfma_f32_16x16x32_bf16 v[56:59], v[68:71], v[218:221], v[56:59]
	v_mfma_f32_16x16x32_bf16 v[44:47], v[52:55], v[226:229], v[44:47]
	v_mfma_f32_16x16x32_bf16 v[40:43], v[68:71], v[226:229], v[40:43]
	v_mfma_f32_16x16x32_bf16 v[12:15], v[52:55], v[234:237], v[12:15]
	v_mfma_f32_16x16x32_bf16 v[8:11], v[68:71], v[234:237], v[8:11]
	s_setprio 0
	s_setprio 1
	v_mfma_f32_16x16x32_bf16 v[16:19], v[184:187], v[206:209], v[16:19]
	v_mfma_f32_16x16x32_bf16 v[68:71], v[194:197], v[210:213], v[16:19]
	v_mfma_f32_16x16x32_bf16 v[16:19], v[198:201], v[206:209], v[20:23]
	v_mfma_f32_16x16x32_bf16 v[64:67], v[202:205], v[210:213], v[16:19]
	v_mfma_f32_16x16x32_bf16 v[16:19], v[184:187], v[214:217], v[32:35]
	v_mfma_f32_16x16x32_bf16 v[52:55], v[194:197], v[218:221], v[16:19]
	v_mfma_f32_16x16x32_bf16 v[16:19], v[198:201], v[214:217], v[36:39]
	v_mfma_f32_16x16x32_bf16 v[48:51], v[202:205], v[218:221], v[16:19]
	v_mfma_f32_16x16x32_bf16 v[16:19], v[184:187], v[222:225], v[28:31]
	v_mfma_f32_16x16x32_bf16 v[28:31], v[194:197], v[226:229], v[16:19]
	v_mfma_f32_16x16x32_bf16 v[16:19], v[198:201], v[222:225], v[24:27]
	v_mfma_f32_16x16x32_bf16 v[4:7], v[184:187], v[230:233], v[4:7]
	v_mfma_f32_16x16x32_bf16 v[0:3], v[198:201], v[230:233], v[0:3]
	v_mfma_f32_16x16x32_bf16 v[24:27], v[202:205], v[226:229], v[16:19]
	v_mfma_f32_16x16x32_bf16 v[4:7], v[194:197], v[234:237], v[4:7]
	v_mfma_f32_16x16x32_bf16 v[0:3], v[202:205], v[234:237], v[0:3]
	s_setprio 0
	s_barrier
	s_add_i32 s45, s45, 2
	s_add_u32 s10, s10, 0x100
	s_addc_u32 s11, s11, 0
	s_add_u32 s33, s33, 0x100
	s_addc_u32 s39, s39, 0
	s_cmp_gt_u32 s45, 13
	s_cbranch_scc0 .LBB0_252
	s_and_b64 vcc, exec, s[24:25]
	s_cbranch_vccz .LBB0_255
	s_barrier

; #define PG8_STAGE(bufoff, gbase, voff) do { _Pragma("unroll") for (int _i = 0; _i < 2; ++_i) \
;         __builtin_amdgcn_global_load_lds((const unsigned*)((const char*)(gbase) + (voff)[_i]), (LAS unsigned*)(lds + (bufoff) + ldsw + _i * 8192), 16, 0, 0); } while (0)
; #define PG8_WAIT_V(n) asm volatile("s_waitcnt vmcnt(" #n ")" ::: "memory")
; #define PG8_BAR __builtin_amdgcn_s_barrier()
; template <class Epi, class Sched>
; __device__ __forceinline__ void gemm_phase(LAS unsigned char* lds, const Gemm g, const Sched& S, const Epi& E, int wave_id) {
;     ...
;     PG8_STAGE(PG8_SB(0, 0), cB, voffB); PG8_STAGE(PG8_SB(0, 1), cB + hstepB, voffB); PG8_STAGE(PG8_SA(0, 0), cA, voffA); PG8_STAGE(PG8_SA(0, 1), cA + hstepA, voffA);
;     if (wr == 1) PG8_BAR;
;     PG8_WAIT_V(2); PG8_BAR;
;     PG8_STAGE(PG8_SB(1, 0), cB + kstep, voffB); PG8_STAGE(PG8_SA(1, 0), cA + kstep, voffA); PG8_STAGE(PG8_SB(1, 1), cB + hstepB + kstep, voffB);
;     PG8_WAIT_V(6); PG8_BAR;
.LBB0_662:
	s_lshl_b32 s6, s97, 5
	s_and_b32 s14, s6, 0x60
	s_mov_b64 s[6:7], 0x80
	v_readlane_b32 s16, v255, 1
	s_add_i32 m0, s31, 0x18000
	v_lshl_add_u64 v[6:7], v[6:7], 0, s[6:7]
	s_lshl_b32 s12, s9, 13
	s_lshl_b32 s13, s14, 7
	s_ashr_i32 s51, s16, 31
	s_waitcnt vmcnt(2)
	s_barrier
	global_load_lds_dwordx4 v[6:7], off
	v_lshl_add_u64 v[4:5], v[4:5], 0, s[6:7]
	s_add_i32 m0, s31, 0x1a000
	s_add_i32 s52, s31, 0x8000
	s_add_i32 s53, s31, 0xa000
	global_load_lds_dwordx4 v[4:5], off
	v_lshl_add_u64 v[0:1], v[0:1], 0, s[6:7]
	s_mov_b32 m0, s52
	s_add_u32 s10, s36, 0x40080
	global_load_lds_dwordx4 v[0:1], off
	v_lshl_add_u64 v[0:1], v[2:3], 0, s[6:7]
	s_mov_b32 m0, s53
	s_addc_u32 s11, s37, 0
	global_load_lds_dwordx4 v[0:1], off
	s_add_i32 m0, s31, 0x1c000
	s_nop 0
	global_load_lds_dwordx4 v130, s[10:11]
	v_lshl_add_u64 v[0:1], s[10:11], 0, v[134:135]
	s_add_i32 m0, s31, 0x1e000
	s_cmpk_lt_u32 s80, 0x100
	global_load_lds_dwordx4 v[0:1], off
	v_lshrrev_b32_e32 v1, 1, v8
	v_and_b32_e32 v1, 24, v1
	v_and_b32_e32 v0, 15, v8
	v_lshlrev_b32_e32 v2, 1, v1
	v_lshl_or_b32 v158, s9, 6, v0
	v_lshl_or_b32 v0, v0, 6, v2
	v_lshlrev_b32_e32 v2, 2, v8
	v_and_b32_e32 v2, 32, v2
	v_bitop3_b32 v3, v0, s12, v2 bitop3:0xde
	v_bitop3_b32 v159, v0, s13, v2 bitop3:0xde
	v_lshlrev_b32_e32 v0, 14, v9
	v_and_b32_e32 v0, 0xffff8000, v0
	v_or_b32_e32 v160, s14, v1
	v_lshl_add_u32 v0, v10, 11, v0
	v_and_b32_e32 v1, 1, v9
	v_lshl_or_b32 v0, v1, 6, v0
	s_sext_i32_i8 s60, s8
	s_cselect_b64 s[8:9], -1, 0
	s_add_u32 s10, s92, 0x1f400000
	v_lshl_add_u32 v136, v11, 1, v0
	v_lshlrev_b32_e32 v0, 14, v12
	s_addc_u32 s11, s93, 0
	v_and_b32_e32 v0, 0xffff8000, v0
	s_waitcnt vmcnt(6)
	s_add_u32 s12, s92, 0xb400000
	v_lshl_add_u32 v0, v13, 11, v0
	v_and_b32_e32 v1, 1, v12
	s_addc_u32 s13, s93, 0
	v_lshl_or_b32 v0, v1, 6, v0
	s_add_i32 s55, 0, 0x10000
	s_add_i32 s58, 0, 0x14000
	s_mov_b32 s54, s16
	v_mov_b32_e32 v137, v131
	v_lshl_add_u32 v138, v14, 1, v0
	v_mov_b32_e32 v139, v131
	v_add_u32_e32 v161, s55, v159
	v_add_u32_e32 v162, s58, v159
	v_add_u32_e32 v163, 0, v3
	s_mov_b32 s14, 0x437f0000
	s_mov_b32 s59, 0xb400000
	v_mov_b64_e32 v[140:141], 0x3ff
	v_readlane_b32 s17, v255, 2
	s_barrier
	s_branch .LBB0_665

;     __device__ bool next(int i, Unit& u) const { if (r0 + i >= r1) return false; return base.next(r0 + i, u); }
;     __device__ bool next(int i, Unit& u) const { const int L = i * G + c; if (L >= 256) return false; u.pm = L; u.pn = L >> 3; return true; }
; #define PG8_STAGE(bufoff, gbase, voff) do { _Pragma("unroll") for (int _i = 0; _i < 2; ++_i) \
;         __builtin_amdgcn_global_load_lds((const unsigned*)((const char*)(gbase) + (voff)[_i]), (LAS unsigned*)(lds + (bufoff) + ldsw + _i * 8192), 16, 0, 0); } while (0)
; #define PG8_LDA(dst, b, h) do { _Pragma("unroll") for (int m = 0; m < 4; ++m) _Pragma("unroll") for (int k = 0; k < 2; ++k) dst[m][k] = *(const LAS bf16x8*)(lds + PG8_SA(b, h) + aoff + m * 2048 + k * 1024); } while (0)
; #define PG8_LDB(dst, b, h) do { _Pragma("unroll") for (int n = 0; n < 2; ++n) _Pragma("unroll") for (int k = 0; k < 2; ++k) dst[n][k] = *(const LAS bf16x8*)(lds + PG8_SB(b, h) + boff + n * 2048 + k * 1024); } while (0)
; #define PG8_WAIT_V(n) asm volatile("s_waitcnt vmcnt(" #n ")" ::: "memory")
; #define PG8_WAIT_L(n) asm volatile("s_waitcnt lgkmcnt(" #n ")" ::: "memory")
; template <class Epi, class Sched>
; __device__ __forceinline__ void gemm_phase(LAS unsigned char* lds, const Gemm g, const Sched& S, const Epi& E, int wave_id) {
;     ...
;         const bool has_next = S.next(ui + 1, nxt);
;         const char* nA = has_next ? (const char*)g.A + (size_t)nxt.pm * tstepA : cA; const char* nB = has_next ? (const char*)g.Bt + (size_t)nxt.pn * tstepB : cB;
;         for (int t = 0; t < nt; t += 2) {
;             const bool last = (t == nt - 2);
;             const char* a1 = cA + (size_t)(t + 1) * kstep;
;             const char* a2 = last ? nA : cA + (size_t)(t + 2) * kstep; const char* b2 = last ? nB : cB + (size_t)(t + 2) * kstep;
;             const char* a3 = a2 + kstep; const char* b3 = b2 + kstep;
;             PG8_LDB(B0, 0, 0); PG8_LDB(B1, 0, 1); PG8_SCHED; PG8_LDA(At, 0, 0); PG8_STAGE(PG8_SA(1, 1), a1 + hstepA, voffA);
;             PG8_WAIT_V(8); PG8_WAIT_L(0); PG8_BAR; PG8_MMA(0, 0, At, B0); PG8_MMA(0, 1, At, B1); PG8_BAR; PG8_SCHED;
;             PG8_LDA(At, 0, 1); PG8_STAGE(PG8_SB(0, 0), b2, voffB); PG8_STAGE(PG8_SB(0, 1), b2 + hstepB, voffB); PG8_STAGE(PG8_SA(0, 0), a2, voffA);
;             PG8_WAIT_V(8); PG8_WAIT_L(0); PG8_BAR; PG8_MMA(1, 0, At, B0); PG8_MMA(1, 1, At, B1); PG8_BAR; PG8_SCHED;
.LBB0_672:
	s_ashr_i32 s23, s22, 31
	s_lshl_b64 s[26:27], s[22:23], 19
	s_add_u32 s26, s15, s26
	s_addc_u32 s27, s33, s27
	s_and_b64 s[28:29], s[24:25], exec
	s_cselect_b32 s23, s27, s35
	s_cselect_b32 s61, s26, s34
	s_ashr_i32 s17, s16, 31
	s_lshl_b64 s[28:29], s[16:17], 19
	s_add_u32 s28, s44, s28
	s_addc_u32 s29, s45, s29
	s_and_b64 s[38:39], s[24:25], exec
	s_cselect_b32 s17, s29, s37
	s_cselect_b32 s62, s28, s36
	s_add_u32 s34, s34, 0x40080
	s_addc_u32 s35, s35, 0
	s_add_u32 s63, s36, 0x100
	s_addc_u32 s64, s37, 0
	s_mov_b32 s65, -2
	ds_read_b128 v[142:145], v161
	ds_read_b128 v[146:149], v161 offset:1024
	ds_read_b128 v[150:153], v161 offset:2048
	ds_read_b128 v[154:157], v161 offset:3072
	ds_read_b128 v[164:167], v162
	ds_read_b128 v[168:171], v162 offset:1024
	ds_read_b128 v[172:175], v162 offset:2048
	ds_read_b128 v[176:179], v162 offset:3072
	s_add_u32 s36, s34, 0xfffc0080
	s_addc_u32 s37, s35, -1
	s_cmp_eq_u32 s65, 12
	s_cselect_b32 s39, s23, s37
	s_cselect_b32 s38, s61, s36
	s_cselect_b32 s37, s17, s64
	s_cselect_b32 s36, s62, s63
	s_add_i32 m0, s31, 0xc000
	ds_read_b128 v[180:183], v163
	ds_read_b128 v[184:187], v163 offset:1024
	ds_read_b128 v[188:191], v163 offset:2048
	ds_read_b128 v[192:195], v163 offset:3072
	ds_read_b128 v[196:199], v163 offset:4096
	ds_read_b128 v[200:203], v163 offset:5120
	ds_read_b128 v[204:207], v163 offset:6144
	ds_read_b128 v[208:211], v163 offset:7168
	global_load_lds_dwordx4 v136, s[34:35]
	s_add_i32 m0, s31, 0xe000
	s_nop 0
	global_load_lds_dwordx4 v138, s[34:35]
	s_waitcnt vmcnt(8)
	s_waitcnt lgkmcnt(0)
	s_barrier
	s_setprio 1
	s_waitcnt lgkmcnt(0)
	v_mfma_f32_16x16x32_bf16 v[124:127], v[142:145], v[180:183], 0
	v_mfma_f32_16x16x32_bf16 v[120:123], v[150:153], v[180:183], 0
	v_mfma_f32_16x16x32_bf16 v[108:111], v[142:145], v[188:191], 0
	v_mfma_f32_16x16x32_bf16 v[104:107], v[150:153], v[188:191], 0
	v_mfma_f32_16x16x32_bf16 v[92:95], v[142:145], v[196:199], 0
	v_mfma_f32_16x16x32_bf16 v[88:91], v[150:153], v[196:199], 0
	v_mfma_f32_16x16x32_bf16 v[76:79], v[142:145], v[204:207], 0
	v_mfma_f32_16x16x32_bf16 v[72:75], v[150:153], v[204:207], 0
	v_mfma_f32_16x16x32_bf16 v[124:127], v[146:149], v[184:187], v[124:127]
	v_mfma_f32_16x16x32_bf16 v[120:123], v[154:157], v[184:187], v[120:123]
	v_mfma_f32_16x16x32_bf16 v[108:111], v[146:149], v[192:195], v[108:111]
	v_mfma_f32_16x16x32_bf16 v[104:107], v[154:157], v[192:195], v[104:107]
	v_mfma_f32_16x16x32_bf16 v[92:95], v[146:149], v[200:203], v[92:95]
	v_mfma_f32_16x16x32_bf16 v[88:91], v[154:157], v[200:203], v[88:91]
	v_mfma_f32_16x16x32_bf16 v[76:79], v[146:149], v[208:211], v[76:79]
	v_mfma_f32_16x16x32_bf16 v[72:75], v[154:157], v[208:211], v[72:75]
	s_setprio 0
	s_setprio 1
	v_mfma_f32_16x16x32_bf16 v[116:119], v[164:167], v[180:183], 0
	v_mfma_f32_16x16x32_bf16 v[112:115], v[172:175], v[180:183], 0
	v_mfma_f32_16x16x32_bf16 v[100:103], v[164:167], v[188:191], 0
	v_mfma_f32_16x16x32_bf16 v[96:99], v[172:175], v[188:191], 0
	v_mfma_f32_16x16x32_bf16 v[84:87], v[164:167], v[196:199], 0
	v_mfma_f32_16x16x32_bf16 v[80:83], v[172:175], v[196:199], 0
	v_mfma_f32_16x16x32_bf16 v[68:71], v[164:167], v[204:207], 0
	v_mfma_f32_16x16x32_bf16 v[64:67], v[172:175], v[204:207], 0
	v_mfma_f32_16x16x32_bf16 v[116:119], v[168:171], v[184:187], v[116:119]
	v_mfma_f32_16x16x32_bf16 v[112:115], v[176:179], v[184:187], v[112:115]
	v_mfma_f32_16x16x32_bf16 v[100:103], v[168:171], v[192:195], v[100:103]
	v_mfma_f32_16x16x32_bf16 v[96:99], v[176:179], v[192:195], v[96:99]
	v_mfma_f32_16x16x32_bf16 v[84:87], v[168:171], v[200:203], v[84:87]
	v_mfma_f32_16x16x32_bf16 v[80:83], v[176:179], v[200:203], v[80:83]
	v_mfma_f32_16x16x32_bf16 v[68:71], v[168:171], v[208:211], v[68:71]
	v_mfma_f32_16x16x32_bf16 v[64:67], v[176:179], v[208:211], v[64:67]
	s_setprio 0
	s_barrier
	s_add_i32 s66, s55, s46
	v_lshl_add_u64 v[212:213], s[36:37], 0, v[130:131]
	s_mov_b32 m0, s66
	ds_read_b128 v[180:183], v163 offset:16384
	ds_read_b128 v[184:187], v163 offset:17408
	ds_read_b128 v[188:191], v163 offset:18432
	ds_read_b128 v[192:195], v163 offset:19456
	ds_read_b128 v[196:199], v163 offset:20480
	ds_read_b128 v[200:203], v163 offset:21504
	ds_read_b128 v[204:207], v163 offset:22528
	ds_read_b128 v[208:211], v163 offset:23552
	global_load_lds_dwordx4 v[212:213], off
	s_add_i32 m0, s66, 0x2000
	s_add_u32 s66, s36, 0x40000
	v_lshl_add_u64 v[214:215], s[36:37], 0, v[134:135]
	s_addc_u32 s67, s37, 0
	s_add_i32 s72, s58, s46
	global_load_lds_dwordx4 v[214:215], off
	s_mov_b32 m0, s72
	v_lshl_add_u64 v[218:219], s[38:39], 0, v[132:133]
	global_load_lds_dwordx4 v130, s[66:67]
	s_add_i32 m0, s72, 0x2000
	s_nop 0
	global_load_lds_dwordx4 v134, s[66:67]
	v_lshl_add_u64 v[216:217], s[38:39], 0, v[128:129]
	s_mov_b32 m0, s31
	s_nop 0
	global_load_lds_dwordx4 v[216:217], off
	s_mov_b32 m0, s47
	s_nop 0
	global_load_lds_dwordx4 v[218:219], off
	s_waitcnt vmcnt(8)
	s_waitcnt lgkmcnt(0)
	s_barrier
; #define PG8_STAGE(bufoff, gbase, voff) do { _Pragma("unroll") for (int _i = 0; _i < 2; ++_i) \
;         __builtin_amdgcn_global_load_lds((const unsigned*)((const char*)(gbase) + (voff)[_i]), (LAS unsigned*)(lds + (bufoff) + ldsw + _i * 8192), 16, 0, 0); } while (0)
; #define PG8_LDA(dst, b, h) do { _Pragma("unroll") for (int m = 0; m < 4; ++m) _Pragma("unroll") for (int k = 0; k < 2; ++k) dst[m][k] = *(const LAS bf16x8*)(lds + PG8_SA(b, h) + aoff + m * 2048 + k * 1024); } while (0)
; #define PG8_LDB(dst, b, h) do { _Pragma("unroll") for (int n = 0; n < 2; ++n) _Pragma("unroll") for (int k = 0; k < 2; ++k) dst[n][k] = *(const LAS bf16x8*)(lds + PG8_SB(b, h) + boff + n * 2048 + k * 1024); } while (0)
; #define PG8_MMA(ai, bj, At, Bt) do { __builtin_amdgcn_s_setprio(1); _Pragma("unroll") for (int m = 0; m < 4; ++m) _Pragma("unroll") for (int n = 0; n < 2; ++n) _Pragma("unroll") for (int k = 0; k < 2; ++k) \
;         acc[ai][bj][m][n] = __builtin_amdgcn_mfma_f32_16x16x32_bf16(Bt[n][k], At[m][k], acc[ai][bj][m][n], 0, 0, 0); __builtin_amdgcn_s_setprio(0); } while (0)
; #define PG8_WAIT_V(n) asm volatile("s_waitcnt vmcnt(" #n ")" ::: "memory")
; #define PG8_WAIT_L(n) asm volatile("s_waitcnt lgkmcnt(" #n ")" ::: "memory")
; #define PG8_BAR __builtin_amdgcn_s_barrier()
; #define PG8_SCHED __builtin_amdgcn_sched_barrier(0)
; template <class Epi, class Sched>
; __device__ __forceinline__ void gemm_phase(LAS unsigned char* lds, const Gemm g, const Sched& S, const Epi& E, int wave_id) {
;     ...
;             PG8_WAIT_V(8); PG8_WAIT_L(0); PG8_BAR; PG8_MMA(1, 0, At, B0); PG8_MMA(1, 1, At, B1); PG8_BAR; PG8_SCHED;
;             PG8_LDB(B0, 1, 0); PG8_LDB(B1, 1, 1); PG8_SCHED; PG8_LDA(At, 1, 0); PG8_STAGE(PG8_SA(0, 1), a2 + hstepA, voffA);
;             PG8_WAIT_V(8); PG8_WAIT_L(0); PG8_BAR; PG8_MMA(0, 0, At, B0); PG8_MMA(0, 1, At, B1); PG8_BAR; PG8_SCHED;
	s_setprio 1
	s_waitcnt lgkmcnt(0)
	v_mfma_f32_16x16x32_bf16 v[60:63], v[142:145], v[180:183], 0
	v_mfma_f32_16x16x32_bf16 v[56:59], v[150:153], v[180:183], 0
	v_mfma_f32_16x16x32_bf16 v[44:47], v[142:145], v[188:191], 0
	v_mfma_f32_16x16x32_bf16 v[40:43], v[150:153], v[188:191], 0
	v_mfma_f32_16x16x32_bf16 v[28:31], v[142:145], v[196:199], 0
	v_mfma_f32_16x16x32_bf16 v[24:27], v[150:153], v[196:199], 0
	v_mfma_f32_16x16x32_bf16 v[12:15], v[142:145], v[204:207], 0
	v_mfma_f32_16x16x32_bf16 v[8:11], v[150:153], v[204:207], 0
	v_mfma_f32_16x16x32_bf16 v[60:63], v[146:149], v[184:187], v[60:63]
	v_mfma_f32_16x16x32_bf16 v[56:59], v[154:157], v[184:187], v[56:59]
	v_mfma_f32_16x16x32_bf16 v[44:47], v[146:149], v[192:195], v[44:47]
	v_mfma_f32_16x16x32_bf16 v[40:43], v[154:157], v[192:195], v[40:43]
	v_mfma_f32_16x16x32_bf16 v[28:31], v[146:149], v[200:203], v[28:31]
	v_mfma_f32_16x16x32_bf16 v[24:27], v[154:157], v[200:203], v[24:27]
	v_mfma_f32_16x16x32_bf16 v[12:15], v[146:149], v[208:211], v[12:15]
	v_mfma_f32_16x16x32_bf16 v[8:11], v[154:157], v[208:211], v[8:11]
	s_setprio 0
	s_setprio 1
	v_mfma_f32_16x16x32_bf16 v[52:55], v[164:167], v[180:183], 0
	v_mfma_f32_16x16x32_bf16 v[48:51], v[172:175], v[180:183], 0
	v_mfma_f32_16x16x32_bf16 v[36:39], v[164:167], v[188:191], 0
	v_mfma_f32_16x16x32_bf16 v[32:35], v[172:175], v[188:191], 0
	v_mfma_f32_16x16x32_bf16 v[20:23], v[164:167], v[196:199], 0
	v_mfma_f32_16x16x32_bf16 v[16:19], v[172:175], v[196:199], 0
	v_mfma_f32_16x16x32_bf16 v[4:7], v[164:167], v[204:207], 0
	v_mfma_f32_16x16x32_bf16 v[0:3], v[172:175], v[204:207], 0
	v_mfma_f32_16x16x32_bf16 v[52:55], v[168:171], v[184:187], v[52:55]
	v_mfma_f32_16x16x32_bf16 v[48:51], v[176:179], v[184:187], v[48:51]
	v_mfma_f32_16x16x32_bf16 v[36:39], v[168:171], v[192:195], v[36:39]
	v_mfma_f32_16x16x32_bf16 v[32:35], v[176:179], v[192:195], v[32:35]
	v_mfma_f32_16x16x32_bf16 v[20:23], v[168:171], v[200:203], v[20:23]
	v_mfma_f32_16x16x32_bf16 v[16:19], v[176:179], v[200:203], v[16:19]
	v_mfma_f32_16x16x32_bf16 v[4:7], v[168:171], v[208:211], v[4:7]
	v_mfma_f32_16x16x32_bf16 v[0:3], v[176:179], v[208:211], v[0:3]
	s_setprio 0
	s_barrier
	s_add_i32 s66, 0, 0x18000
	s_add_i32 s67, 0, 0x1c000
	v_add_u32_e32 v154, s66, v159
	v_add_u32_e32 v176, s67, v159
	ds_read_b128 v[142:145], v154
	ds_read_b128 v[146:149], v154 offset:1024
	ds_read_b128 v[150:153], v154 offset:2048
	ds_read_b128 v[154:157], v154 offset:3072
	ds_read_b128 v[164:167], v176
	ds_read_b128 v[168:171], v176 offset:1024
	ds_read_b128 v[172:175], v176 offset:2048
	ds_read_b128 v[176:179], v176 offset:3072
	s_add_u32 s38, s38, 0x40000
	s_addc_u32 s39, s39, 0
	s_mov_b32 m0, s48
	ds_read_b128 v[180:183], v163 offset:32768
	ds_read_b128 v[184:187], v163 offset:33792
	ds_read_b128 v[188:191], v163 offset:34816
	ds_read_b128 v[192:195], v163 offset:35840
	ds_read_b128 v[196:199], v163 offset:36864
	ds_read_b128 v[200:203], v163 offset:37888
	ds_read_b128 v[204:207], v163 offset:38912
	ds_read_b128 v[208:211], v163 offset:39936
	global_load_lds_dwordx4 v128, s[38:39]
	s_mov_b32 m0, s49
	s_nop 0
	global_load_lds_dwordx4 v132, s[38:39]
	s_waitcnt vmcnt(8)
	s_waitcnt lgkmcnt(0)
	s_barrier
	s_setprio 1
	s_waitcnt lgkmcnt(0)
	v_mfma_f32_16x16x32_bf16 v[124:127], v[142:145], v[180:183], v[124:127]
	v_mfma_f32_16x16x32_bf16 v[120:123], v[150:153], v[180:183], v[120:123]
	v_mfma_f32_16x16x32_bf16 v[108:111], v[142:145], v[188:191], v[108:111]
	v_mfma_f32_16x16x32_bf16 v[104:107], v[150:153], v[188:191], v[104:107]
	v_mfma_f32_16x16x32_bf16 v[92:95], v[142:145], v[196:199], v[92:95]
	v_mfma_f32_16x16x32_bf16 v[88:91], v[150:153], v[196:199], v[88:91]
	v_mfma_f32_16x16x32_bf16 v[76:79], v[142:145], v[204:207], v[76:79]
	v_mfma_f32_16x16x32_bf16 v[72:75], v[150:153], v[204:207], v[72:75]
	v_mfma_f32_16x16x32_bf16 v[124:127], v[146:149], v[184:187], v[124:127]
	v_mfma_f32_16x16x32_bf16 v[120:123], v[154:157], v[184:187], v[120:123]
	v_mfma_f32_16x16x32_bf16 v[108:111], v[146:149], v[192:195], v[108:111]
	v_mfma_f32_16x16x32_bf16 v[104:107], v[154:157], v[192:195], v[104:107]
	v_mfma_f32_16x16x32_bf16 v[92:95], v[146:149], v[200:203], v[92:95]
	v_mfma_f32_16x16x32_bf16 v[88:91], v[154:157], v[200:203], v[88:91]
	v_mfma_f32_16x16x32_bf16 v[76:79], v[146:149], v[208:211], v[76:79]
	v_mfma_f32_16x16x32_bf16 v[72:75], v[154:157], v[208:211], v[72:75]
	s_setprio 0
	s_setprio 1
	v_mfma_f32_16x16x32_bf16 v[116:119], v[164:167], v[180:183], v[116:119]
	v_mfma_f32_16x16x32_bf16 v[112:115], v[172:175], v[180:183], v[112:115]
	v_mfma_f32_16x16x32_bf16 v[100:103], v[164:167], v[188:191], v[100:103]
	v_mfma_f32_16x16x32_bf16 v[96:99], v[172:175], v[188:191], v[96:99]
	v_mfma_f32_16x16x32_bf16 v[84:87], v[164:167], v[196:199], v[84:87]
	v_mfma_f32_16x16x32_bf16 v[80:83], v[172:175], v[196:199], v[80:83]
	v_mfma_f32_16x16x32_bf16 v[68:71], v[164:167], v[204:207], v[68:71]
	v_mfma_f32_16x16x32_bf16 v[64:67], v[172:175], v[204:207], v[64:67]
	v_mfma_f32_16x16x32_bf16 v[116:119], v[168:171], v[184:187], v[116:119]
	v_mfma_f32_16x16x32_bf16 v[112:115], v[176:179], v[184:187], v[112:115]
	v_mfma_f32_16x16x32_bf16 v[100:103], v[168:171], v[192:195], v[100:103]
	v_mfma_f32_16x16x32_bf16 v[96:99], v[176:179], v[192:195], v[96:99]
	v_mfma_f32_16x16x32_bf16 v[84:87], v[168:171], v[200:203], v[84:87]
	v_mfma_f32_16x16x32_bf16 v[80:83], v[176:179], v[200:203], v[80:83]
	v_mfma_f32_16x16x32_bf16 v[68:71], v[168:171], v[208:211], v[68:71]
	v_mfma_f32_16x16x32_bf16 v[64:67], v[176:179], v[208:211], v[64:67]
	s_setprio 0
	s_barrier
; #define PG8_STAGE(bufoff, gbase, voff) do { _Pragma("unroll") for (int _i = 0; _i < 2; ++_i) \
;         __builtin_amdgcn_global_load_lds((const unsigned*)((const char*)(gbase) + (voff)[_i]), (LAS unsigned*)(lds + (bufoff) + ldsw + _i * 8192), 16, 0, 0); } while (0)
; #define PG8_LDA(dst, b, h) do { _Pragma("unroll") for (int m = 0; m < 4; ++m) _Pragma("unroll") for (int k = 0; k < 2; ++k) dst[m][k] = *(const LAS bf16x8*)(lds + PG8_SA(b, h) + aoff + m * 2048 + k * 1024); } while (0)
; #define PG8_LDB(dst, b, h) do { _Pragma("unroll") for (int n = 0; n < 2; ++n) _Pragma("unroll") for (int k = 0; k < 2; ++k) dst[n][k] = *(const LAS bf16x8*)(lds + PG8_SB(b, h) + boff + n * 2048 + k * 1024); } while (0)
; #define PG8_WAIT_V(n) asm volatile("s_waitcnt vmcnt(" #n ")" ::: "memory")
; #define PG8_WAIT_L(n) asm volatile("s_waitcnt lgkmcnt(" #n ")" ::: "memory")
; #define PG8_BAR __builtin_amdgcn_s_barrier()
; #define PG8_SCHED __builtin_amdgcn_sched_barrier(0)
; template <class Epi, class Sched>
; __device__ __forceinline__ void gemm_phase(LAS unsigned char* lds, const Gemm g, const Sched& S, const Epi& E, int wave_id) {
;     ...
;         for (int t = 0; t < nt; t += 2) {
;             const bool last = (t == nt - 2);
;             const char* a1 = cA + (size_t)(t + 1) * kstep;
;             const char* a2 = last ? nA : cA + (size_t)(t + 2) * kstep; const char* b2 = last ? nB : cB + (size_t)(t + 2) * kstep;
;             const char* a3 = a2 + kstep; const char* b3 = b2 + kstep;
;             PG8_LDB(B0, 0, 0); PG8_LDB(B1, 0, 1); PG8_SCHED; PG8_LDA(At, 0, 0); PG8_STAGE(PG8_SA(1, 1), a1 + hstepA, voffA);
;             PG8_WAIT_V(8); PG8_WAIT_L(0); PG8_BAR; PG8_MMA(0, 0, At, B0); PG8_MMA(0, 1, At, B1); PG8_BAR; PG8_SCHED;
;             PG8_LDA(At, 0, 1); PG8_STAGE(PG8_SB(0, 0), b2, voffB); PG8_STAGE(PG8_SB(0, 1), b2 + hstepB, voffB); PG8_STAGE(PG8_SA(0, 0), a2, voffA);
;             PG8_WAIT_V(8); PG8_WAIT_L(0); PG8_BAR; PG8_MMA(1, 0, At, B0); PG8_MMA(1, 1, At, B1); PG8_BAR; PG8_SCHED;
;             PG8_LDB(B0, 1, 0); PG8_LDB(B1, 1, 1); PG8_SCHED; PG8_LDA(At, 1, 0); PG8_STAGE(PG8_SA(0, 1), a2 + hstepA, voffA);
;             PG8_WAIT_V(8); PG8_WAIT_L(0); PG8_BAR; PG8_MMA(0, 0, At, B0); PG8_MMA(0, 1, At, B1); PG8_BAR; PG8_SCHED;
;             PG8_LDA(At, 1, 1); PG8_STAGE(PG8_SB(1, 0), b3, voffB); PG8_STAGE(PG8_SB(1, 1), b3 + hstepB, voffB); PG8_STAGE(PG8_SA(1, 0), a3, voffA);
	s_add_i32 s38, s66, s46
	v_lshl_add_u64 v[212:213], v[212:213], 0, s[6:7]
	s_mov_b32 m0, s38
	ds_read_b128 v[180:183], v163 offset:49152
	ds_read_b128 v[184:187], v163 offset:50176
	ds_read_b128 v[188:191], v163 offset:51200
	ds_read_b128 v[192:195], v163 offset:52224
	ds_read_b128 v[196:199], v163 offset:53248
	ds_read_b128 v[200:203], v163 offset:54272
	ds_read_b128 v[204:207], v163 offset:55296
	ds_read_b128 v[208:211], v163 offset:56320
	global_load_lds_dwordx4 v[212:213], off
	s_add_i32 m0, s38, 0x2000
	s_add_u32 s36, s36, 0x40080
	v_lshl_add_u64 v[212:213], v[214:215], 0, s[6:7]
	s_addc_u32 s37, s37, 0
	s_add_i32 s38, s67, s46
	global_load_lds_dwordx4 v[212:213], off
	s_mov_b32 m0, s38
	s_nop 0
	global_load_lds_dwordx4 v130, s[36:37]
	s_add_i32 m0, s38, 0x2000
	s_nop 0
	global_load_lds_dwordx4 v134, s[36:37]
	v_lshl_add_u64 v[212:213], v[216:217], 0, s[6:7]
	s_mov_b32 m0, s52
	s_nop 0
	global_load_lds_dwordx4 v[212:213], off
	v_lshl_add_u64 v[212:213], v[218:219], 0, s[6:7]
	s_mov_b32 m0, s53
	s_nop 0
	global_load_lds_dwordx4 v[212:213], off
	s_waitcnt vmcnt(8)
	s_waitcnt lgkmcnt(0)
	s_barrier
	s_setprio 1
	s_waitcnt lgkmcnt(0)
	v_mfma_f32_16x16x32_bf16 v[60:63], v[142:145], v[180:183], v[60:63]
	v_mfma_f32_16x16x32_bf16 v[56:59], v[150:153], v[180:183], v[56:59]
	v_mfma_f32_16x16x32_bf16 v[44:47], v[142:145], v[188:191], v[44:47]
	v_mfma_f32_16x16x32_bf16 v[40:43], v[150:153], v[188:191], v[40:43]
	v_mfma_f32_16x16x32_bf16 v[28:31], v[142:145], v[196:199], v[28:31]
	v_mfma_f32_16x16x32_bf16 v[24:27], v[150:153], v[196:199], v[24:27]
	v_mfma_f32_16x16x32_bf16 v[12:15], v[142:145], v[204:207], v[12:15]
	v_mfma_f32_16x16x32_bf16 v[8:11], v[150:153], v[204:207], v[8:11]
	v_mfma_f32_16x16x32_bf16 v[60:63], v[146:149], v[184:187], v[60:63]
	v_mfma_f32_16x16x32_bf16 v[56:59], v[154:157], v[184:187], v[56:59]
	v_mfma_f32_16x16x32_bf16 v[44:47], v[146:149], v[192:195], v[44:47]
	v_mfma_f32_16x16x32_bf16 v[40:43], v[154:157], v[192:195], v[40:43]
	v_mfma_f32_16x16x32_bf16 v[28:31], v[146:149], v[200:203], v[28:31]
	v_mfma_f32_16x16x32_bf16 v[24:27], v[154:157], v[200:203], v[24:27]
	v_mfma_f32_16x16x32_bf16 v[12:15], v[146:149], v[208:211], v[12:15]
	v_mfma_f32_16x16x32_bf16 v[8:11], v[154:157], v[208:211], v[8:11]
	s_setprio 0
	s_setprio 1
	v_mfma_f32_16x16x32_bf16 v[52:55], v[164:167], v[180:183], v[52:55]
	v_mfma_f32_16x16x32_bf16 v[48:51], v[172:175], v[180:183], v[48:51]
	v_mfma_f32_16x16x32_bf16 v[36:39], v[164:167], v[188:191], v[36:39]
	v_mfma_f32_16x16x32_bf16 v[32:35], v[172:175], v[188:191], v[32:35]
	v_mfma_f32_16x16x32_bf16 v[20:23], v[164:167], v[196:199], v[20:23]
	v_mfma_f32_16x16x32_bf16 v[16:19], v[172:175], v[196:199], v[16:19]
	v_mfma_f32_16x16x32_bf16 v[4:7], v[164:167], v[204:207], v[4:7]
	v_mfma_f32_16x16x32_bf16 v[0:3], v[172:175], v[204:207], v[0:3]
	v_mfma_f32_16x16x32_bf16 v[52:55], v[168:171], v[184:187], v[52:55]
	v_mfma_f32_16x16x32_bf16 v[48:51], v[176:179], v[184:187], v[48:51]
	v_mfma_f32_16x16x32_bf16 v[36:39], v[168:171], v[192:195], v[36:39]
	v_mfma_f32_16x16x32_bf16 v[32:35], v[176:179], v[192:195], v[32:35]
	v_mfma_f32_16x16x32_bf16 v[20:23], v[168:171], v[200:203], v[20:23]
	v_mfma_f32_16x16x32_bf16 v[16:19], v[176:179], v[200:203], v[16:19]
	v_mfma_f32_16x16x32_bf16 v[4:7], v[168:171], v[208:211], v[4:7]
	v_mfma_f32_16x16x32_bf16 v[0:3], v[176:179], v[208:211], v[0:3]
	s_setprio 0
	s_barrier
	s_add_i32 s65, s65, 2
	s_add_u32 s34, s34, 0x100
	s_addc_u32 s35, s35, 0
	s_add_u32 s63, s63, 0x100
	s_addc_u32 s64, s64, 0
	s_cmp_gt_u32 s65, 13
.LBB0_673:
	ds_read_b128 v[142:145], v161
	ds_read_b128 v[146:149], v161 offset:1024
	ds_read_b128 v[150:153], v161 offset:2048
	ds_read_b128 v[154:157], v161 offset:3072
	ds_read_b128 v[164:167], v162
	ds_read_b128 v[168:171], v162 offset:1024
	ds_read_b128 v[172:175], v162 offset:2048
	ds_read_b128 v[176:179], v162 offset:3072
	s_add_u32 s36, s34, 0xfffc0080
	s_addc_u32 s37, s35, -1
	s_cmp_eq_u32 s65, 12
	s_cselect_b32 s39, s23, s37
	s_cselect_b32 s38, s61, s36
	s_cselect_b32 s37, s17, s64
	s_cselect_b32 s36, s62, s63
	s_add_i32 m0, s31, 0xc000
	ds_read_b128 v[180:183], v163
	ds_read_b128 v[184:187], v163 offset:1024
	ds_read_b128 v[188:191], v163 offset:2048
	ds_read_b128 v[192:195], v163 offset:3072
	ds_read_b128 v[196:199], v163 offset:4096
	ds_read_b128 v[200:203], v163 offset:5120
	ds_read_b128 v[204:207], v163 offset:6144
	ds_read_b128 v[208:211], v163 offset:7168
	global_load_lds_dwordx4 v136, s[34:35]
	s_add_i32 m0, s31, 0xe000
	s_nop 0
	global_load_lds_dwordx4 v138, s[34:35]
	s_waitcnt vmcnt(8)
	s_waitcnt lgkmcnt(0)
	s_barrier
; #define PG8_STAGE(bufoff, gbase, voff) do { _Pragma("unroll") for (int _i = 0; _i < 2; ++_i) \
;         __builtin_amdgcn_global_load_lds((const unsigned*)((const char*)(gbase) + (voff)[_i]), (LAS unsigned*)(lds + (bufoff) + ldsw + _i * 8192), 16, 0, 0); } while (0)
; #define PG8_LDA(dst, b, h) do { _Pragma("unroll") for (int m = 0; m < 4; ++m) _Pragma("unroll") for (int k = 0; k < 2; ++k) dst[m][k] = *(const LAS bf16x8*)(lds + PG8_SA(b, h) + aoff + m * 2048 + k * 1024); } while (0)
; #define PG8_MMA(ai, bj, At, Bt) do { __builtin_amdgcn_s_setprio(1); _Pragma("unroll") for (int m = 0; m < 4; ++m) _Pragma("unroll") for (int n = 0; n < 2; ++n) _Pragma("unroll") for (int k = 0; k < 2; ++k) \
;         acc[ai][bj][m][n] = __builtin_amdgcn_mfma_f32_16x16x32_bf16(Bt[n][k], At[m][k], acc[ai][bj][m][n], 0, 0, 0); __builtin_amdgcn_s_setprio(0); } while (0)
; #define PG8_WAIT_V(n) asm volatile("s_waitcnt vmcnt(" #n ")" ::: "memory")
; #define PG8_WAIT_L(n) asm volatile("s_waitcnt lgkmcnt(" #n ")" ::: "memory")
; #define PG8_BAR __builtin_amdgcn_s_barrier()
; #define PG8_SCHED __builtin_amdgcn_sched_barrier(0)
; template <class Epi, class Sched>
; __device__ __forceinline__ void gemm_phase(LAS unsigned char* lds, const Gemm g, const Sched& S, const Epi& E, int wave_id) {
;     ...
;             PG8_WAIT_V(8); PG8_WAIT_L(0); PG8_BAR; PG8_MMA(0, 0, At, B0); PG8_MMA(0, 1, At, B1); PG8_BAR; PG8_SCHED;
;             PG8_LDA(At, 0, 1); PG8_STAGE(PG8_SB(0, 0), b2, voffB); PG8_STAGE(PG8_SB(0, 1), b2 + hstepB, voffB); PG8_STAGE(PG8_SA(0, 0), a2, voffA);
;             PG8_WAIT_V(8); PG8_WAIT_L(0); PG8_BAR; PG8_MMA(1, 0, At, B0); PG8_MMA(1, 1, At, B1); PG8_BAR; PG8_SCHED;
	s_setprio 1
	s_waitcnt lgkmcnt(0)
	v_mfma_f32_16x16x32_bf16 v[124:127], v[142:145], v[180:183], v[124:127]
	v_mfma_f32_16x16x32_bf16 v[120:123], v[150:153], v[180:183], v[120:123]
	v_mfma_f32_16x16x32_bf16 v[108:111], v[142:145], v[188:191], v[108:111]
	v_mfma_f32_16x16x32_bf16 v[104:107], v[150:153], v[188:191], v[104:107]
	v_mfma_f32_16x16x32_bf16 v[92:95], v[142:145], v[196:199], v[92:95]
	v_mfma_f32_16x16x32_bf16 v[88:91], v[150:153], v[196:199], v[88:91]
	v_mfma_f32_16x16x32_bf16 v[76:79], v[142:145], v[204:207], v[76:79]
	v_mfma_f32_16x16x32_bf16 v[72:75], v[150:153], v[204:207], v[72:75]
	v_mfma_f32_16x16x32_bf16 v[124:127], v[146:149], v[184:187], v[124:127]
	v_mfma_f32_16x16x32_bf16 v[120:123], v[154:157], v[184:187], v[120:123]
	v_mfma_f32_16x16x32_bf16 v[108:111], v[146:149], v[192:195], v[108:111]
	v_mfma_f32_16x16x32_bf16 v[104:107], v[154:157], v[192:195], v[104:107]
	v_mfma_f32_16x16x32_bf16 v[92:95], v[146:149], v[200:203], v[92:95]
	v_mfma_f32_16x16x32_bf16 v[88:91], v[154:157], v[200:203], v[88:91]
	v_mfma_f32_16x16x32_bf16 v[76:79], v[146:149], v[208:211], v[76:79]
	v_mfma_f32_16x16x32_bf16 v[72:75], v[154:157], v[208:211], v[72:75]
	s_setprio 0
	s_setprio 1
	v_mfma_f32_16x16x32_bf16 v[116:119], v[164:167], v[180:183], v[116:119]
	v_mfma_f32_16x16x32_bf16 v[112:115], v[172:175], v[180:183], v[112:115]
	v_mfma_f32_16x16x32_bf16 v[100:103], v[164:167], v[188:191], v[100:103]
	v_mfma_f32_16x16x32_bf16 v[96:99], v[172:175], v[188:191], v[96:99]
	v_mfma_f32_16x16x32_bf16 v[84:87], v[164:167], v[196:199], v[84:87]
	v_mfma_f32_16x16x32_bf16 v[80:83], v[172:175], v[196:199], v[80:83]
	v_mfma_f32_16x16x32_bf16 v[68:71], v[164:167], v[204:207], v[68:71]
	v_mfma_f32_16x16x32_bf16 v[64:67], v[172:175], v[204:207], v[64:67]
	v_mfma_f32_16x16x32_bf16 v[116:119], v[168:171], v[184:187], v[116:119]
	v_mfma_f32_16x16x32_bf16 v[112:115], v[176:179], v[184:187], v[112:115]
	v_mfma_f32_16x16x32_bf16 v[100:103], v[168:171], v[192:195], v[100:103]
	v_mfma_f32_16x16x32_bf16 v[96:99], v[176:179], v[192:195], v[96:99]
	v_mfma_f32_16x16x32_bf16 v[84:87], v[168:171], v[200:203], v[84:87]
	v_mfma_f32_16x16x32_bf16 v[80:83], v[176:179], v[200:203], v[80:83]
	v_mfma_f32_16x16x32_bf16 v[68:71], v[168:171], v[208:211], v[68:71]
	v_mfma_f32_16x16x32_bf16 v[64:67], v[176:179], v[208:211], v[64:67]
	s_setprio 0
	s_barrier
	s_add_i32 s66, s55, s46
	v_lshl_add_u64 v[212:213], s[36:37], 0, v[130:131]
	s_mov_b32 m0, s66
	ds_read_b128 v[180:183], v163 offset:16384
	ds_read_b128 v[184:187], v163 offset:17408
	ds_read_b128 v[188:191], v163 offset:18432
	ds_read_b128 v[192:195], v163 offset:19456
	ds_read_b128 v[196:199], v163 offset:20480
	ds_read_b128 v[200:203], v163 offset:21504
	ds_read_b128 v[204:207], v163 offset:22528
	ds_read_b128 v[208:211], v163 offset:23552
	global_load_lds_dwordx4 v[212:213], off
	s_add_i32 m0, s66, 0x2000
	s_add_u32 s66, s36, 0x40000
	v_lshl_add_u64 v[214:215], s[36:37], 0, v[134:135]
	s_addc_u32 s67, s37, 0
	s_add_i32 s72, s58, s46
	global_load_lds_dwordx4 v[214:215], off
	s_mov_b32 m0, s72
	v_lshl_add_u64 v[218:219], s[38:39], 0, v[132:133]
	global_load_lds_dwordx4 v130, s[66:67]
	s_add_i32 m0, s72, 0x2000
	s_nop 0
	global_load_lds_dwordx4 v134, s[66:67]
	v_lshl_add_u64 v[216:217], s[38:39], 0, v[128:129]
	s_mov_b32 m0, s31
	s_nop 0
	global_load_lds_dwordx4 v[216:217], off
	s_mov_b32 m0, s47
	s_nop 0
	global_load_lds_dwordx4 v[218:219], off
	s_waitcnt vmcnt(8)
	s_waitcnt lgkmcnt(0)
	s_barrier
	s_setprio 1
	s_waitcnt lgkmcnt(0)
	v_mfma_f32_16x16x32_bf16 v[60:63], v[142:145], v[180:183], v[60:63]
	v_mfma_f32_16x16x32_bf16 v[56:59], v[150:153], v[180:183], v[56:59]
	v_mfma_f32_16x16x32_bf16 v[44:47], v[142:145], v[188:191], v[44:47]
	v_mfma_f32_16x16x32_bf16 v[40:43], v[150:153], v[188:191], v[40:43]
	v_mfma_f32_16x16x32_bf16 v[28:31], v[142:145], v[196:199], v[28:31]
	v_mfma_f32_16x16x32_bf16 v[24:27], v[150:153], v[196:199], v[24:27]
	v_mfma_f32_16x16x32_bf16 v[12:15], v[142:145], v[204:207], v[12:15]
	v_mfma_f32_16x16x32_bf16 v[8:11], v[150:153], v[204:207], v[8:11]
	v_mfma_f32_16x16x32_bf16 v[60:63], v[146:149], v[184:187], v[60:63]
	v_mfma_f32_16x16x32_bf16 v[56:59], v[154:157], v[184:187], v[56:59]
	v_mfma_f32_16x16x32_bf16 v[44:47], v[146:149], v[192:195], v[44:47]
	v_mfma_f32_16x16x32_bf16 v[40:43], v[154:157], v[192:195], v[40:43]
	v_mfma_f32_16x16x32_bf16 v[28:31], v[146:149], v[200:203], v[28:31]
	v_mfma_f32_16x16x32_bf16 v[24:27], v[154:157], v[200:203], v[24:27]
	v_mfma_f32_16x16x32_bf16 v[12:15], v[146:149], v[208:211], v[12:15]
	v_mfma_f32_16x16x32_bf16 v[8:11], v[154:157], v[208:211], v[8:11]
	s_setprio 0
	s_setprio 1
	v_mfma_f32_16x16x32_bf16 v[52:55], v[164:167], v[180:183], v[52:55]
	v_mfma_f32_16x16x32_bf16 v[48:51], v[172:175], v[180:183], v[48:51]
	v_mfma_f32_16x16x32_bf16 v[36:39], v[164:167], v[188:191], v[36:39]
	v_mfma_f32_16x16x32_bf16 v[32:35], v[172:175], v[188:191], v[32:35]
	v_mfma_f32_16x16x32_bf16 v[20:23], v[164:167], v[196:199], v[20:23]
	v_mfma_f32_16x16x32_bf16 v[16:19], v[172:175], v[196:199], v[16:19]
	v_mfma_f32_16x16x32_bf16 v[4:7], v[164:167], v[204:207], v[4:7]
	v_mfma_f32_16x16x32_bf16 v[0:3], v[172:175], v[204:207], v[0:3]
	v_mfma_f32_16x16x32_bf16 v[52:55], v[168:171], v[184:187], v[52:55]
	v_mfma_f32_16x16x32_bf16 v[48:51], v[176:179], v[184:187], v[48:51]
	v_mfma_f32_16x16x32_bf16 v[36:39], v[168:171], v[192:195], v[36:39]
	v_mfma_f32_16x16x32_bf16 v[32:35], v[176:179], v[192:195], v[32:35]
	v_mfma_f32_16x16x32_bf16 v[20:23], v[168:171], v[200:203], v[20:23]
	v_mfma_f32_16x16x32_bf16 v[16:19], v[176:179], v[200:203], v[16:19]
	v_mfma_f32_16x16x32_bf16 v[4:7], v[168:171], v[208:211], v[4:7]
	v_mfma_f32_16x16x32_bf16 v[0:3], v[176:179], v[208:211], v[0:3]
	s_setprio 0
	s_barrier
; #define PG8_STAGE(bufoff, gbase, voff) do { _Pragma("unroll") for (int _i = 0; _i < 2; ++_i) \
;         __builtin_amdgcn_global_load_lds((const unsigned*)((const char*)(gbase) + (voff)[_i]), (LAS unsigned*)(lds + (bufoff) + ldsw + _i * 8192), 16, 0, 0); } while (0)
; #define PG8_LDA(dst, b, h) do { _Pragma("unroll") for (int m = 0; m < 4; ++m) _Pragma("unroll") for (int k = 0; k < 2; ++k) dst[m][k] = *(const LAS bf16x8*)(lds + PG8_SA(b, h) + aoff + m * 2048 + k * 1024); } while (0)
; #define PG8_LDB(dst, b, h) do { _Pragma("unroll") for (int n = 0; n < 2; ++n) _Pragma("unroll") for (int k = 0; k < 2; ++k) dst[n][k] = *(const LAS bf16x8*)(lds + PG8_SB(b, h) + boff + n * 2048 + k * 1024); } while (0)
; #define PG8_MMA(ai, bj, At, Bt) do { __builtin_amdgcn_s_setprio(1); _Pragma("unroll") for (int m = 0; m < 4; ++m) _Pragma("unroll") for (int n = 0; n < 2; ++n) _Pragma("unroll") for (int k = 0; k < 2; ++k) \
;         acc[ai][bj][m][n] = __builtin_amdgcn_mfma_f32_16x16x32_bf16(Bt[n][k], At[m][k], acc[ai][bj][m][n], 0, 0, 0); __builtin_amdgcn_s_setprio(0); } while (0)
; #define PG8_WAIT_V(n) asm volatile("s_waitcnt vmcnt(" #n ")" ::: "memory")
; #define PG8_WAIT_L(n) asm volatile("s_waitcnt lgkmcnt(" #n ")" ::: "memory")
; #define PG8_BAR __builtin_amdgcn_s_barrier()
; #define PG8_SCHED __builtin_amdgcn_sched_barrier(0)
; template <class Epi, class Sched>
; __device__ __forceinline__ void gemm_phase(LAS unsigned char* lds, const Gemm g, const Sched& S, const Epi& E, int wave_id) {
;     ...
;             PG8_LDB(B0, 1, 0); PG8_LDB(B1, 1, 1); PG8_SCHED; PG8_LDA(At, 1, 0); PG8_STAGE(PG8_SA(0, 1), a2 + hstepA, voffA);
;             PG8_WAIT_V(8); PG8_WAIT_L(0); PG8_BAR; PG8_MMA(0, 0, At, B0); PG8_MMA(0, 1, At, B1); PG8_BAR; PG8_SCHED;
;             PG8_LDA(At, 1, 1); PG8_STAGE(PG8_SB(1, 0), b3, voffB); PG8_STAGE(PG8_SB(1, 1), b3 + hstepB, voffB); PG8_STAGE(PG8_SA(1, 0), a3, voffA);
;             PG8_WAIT_V(8); PG8_WAIT_L(0); PG8_BAR; PG8_MMA(1, 0, At, B0); PG8_MMA(1, 1, At, B1); PG8_BAR; PG8_SCHED;
;         }
;         if (wr == 0) PG8_BAR;
	s_add_i32 s66, 0, 0x18000
	s_add_i32 s67, 0, 0x1c000
	v_add_u32_e32 v154, s66, v159
	v_add_u32_e32 v176, s67, v159
	ds_read_b128 v[142:145], v154
	ds_read_b128 v[146:149], v154 offset:1024
	ds_read_b128 v[150:153], v154 offset:2048
	ds_read_b128 v[154:157], v154 offset:3072
	ds_read_b128 v[164:167], v176
	ds_read_b128 v[168:171], v176 offset:1024
	ds_read_b128 v[172:175], v176 offset:2048
	ds_read_b128 v[176:179], v176 offset:3072
	s_add_u32 s38, s38, 0x40000
	s_addc_u32 s39, s39, 0
	s_mov_b32 m0, s48
	ds_read_b128 v[180:183], v163 offset:32768
	ds_read_b128 v[184:187], v163 offset:33792
	ds_read_b128 v[188:191], v163 offset:34816
	ds_read_b128 v[192:195], v163 offset:35840
	ds_read_b128 v[196:199], v163 offset:36864
	ds_read_b128 v[200:203], v163 offset:37888
	ds_read_b128 v[204:207], v163 offset:38912
	ds_read_b128 v[208:211], v163 offset:39936
	global_load_lds_dwordx4 v128, s[38:39]
	s_mov_b32 m0, s49
	s_nop 0
	global_load_lds_dwordx4 v132, s[38:39]
	s_waitcnt vmcnt(8)
	s_waitcnt lgkmcnt(0)
	s_barrier
	s_setprio 1
	s_waitcnt lgkmcnt(0)
	v_mfma_f32_16x16x32_bf16 v[124:127], v[142:145], v[180:183], v[124:127]
	v_mfma_f32_16x16x32_bf16 v[120:123], v[150:153], v[180:183], v[120:123]
	v_mfma_f32_16x16x32_bf16 v[108:111], v[142:145], v[188:191], v[108:111]
	v_mfma_f32_16x16x32_bf16 v[104:107], v[150:153], v[188:191], v[104:107]
	v_mfma_f32_16x16x32_bf16 v[92:95], v[142:145], v[196:199], v[92:95]
	v_mfma_f32_16x16x32_bf16 v[88:91], v[150:153], v[196:199], v[88:91]
	v_mfma_f32_16x16x32_bf16 v[76:79], v[142:145], v[204:207], v[76:79]
	v_mfma_f32_16x16x32_bf16 v[72:75], v[150:153], v[204:207], v[72:75]
	v_mfma_f32_16x16x32_bf16 v[124:127], v[146:149], v[184:187], v[124:127]
	v_mfma_f32_16x16x32_bf16 v[120:123], v[154:157], v[184:187], v[120:123]
	v_mfma_f32_16x16x32_bf16 v[108:111], v[146:149], v[192:195], v[108:111]
	v_mfma_f32_16x16x32_bf16 v[104:107], v[154:157], v[192:195], v[104:107]
	v_mfma_f32_16x16x32_bf16 v[92:95], v[146:149], v[200:203], v[92:95]
	v_mfma_f32_16x16x32_bf16 v[88:91], v[154:157], v[200:203], v[88:91]
	v_mfma_f32_16x16x32_bf16 v[76:79], v[146:149], v[208:211], v[76:79]
	v_mfma_f32_16x16x32_bf16 v[72:75], v[154:157], v[208:211], v[72:75]
	s_setprio 0
	s_setprio 1
	v_mfma_f32_16x16x32_bf16 v[116:119], v[164:167], v[180:183], v[116:119]
	v_mfma_f32_16x16x32_bf16 v[112:115], v[172:175], v[180:183], v[112:115]
	v_mfma_f32_16x16x32_bf16 v[100:103], v[164:167], v[188:191], v[100:103]
	v_mfma_f32_16x16x32_bf16 v[96:99], v[172:175], v[188:191], v[96:99]
	v_mfma_f32_16x16x32_bf16 v[84:87], v[164:167], v[196:199], v[84:87]
	v_mfma_f32_16x16x32_bf16 v[80:83], v[172:175], v[196:199], v[80:83]
	v_mfma_f32_16x16x32_bf16 v[68:71], v[164:167], v[204:207], v[68:71]
	v_mfma_f32_16x16x32_bf16 v[64:67], v[172:175], v[204:207], v[64:67]
	v_mfma_f32_16x16x32_bf16 v[116:119], v[168:171], v[184:187], v[116:119]
	v_mfma_f32_16x16x32_bf16 v[112:115], v[176:179], v[184:187], v[112:115]
	v_mfma_f32_16x16x32_bf16 v[100:103], v[168:171], v[192:195], v[100:103]
	v_mfma_f32_16x16x32_bf16 v[96:99], v[176:179], v[192:195], v[96:99]
	v_mfma_f32_16x16x32_bf16 v[84:87], v[168:171], v[200:203], v[84:87]
	v_mfma_f32_16x16x32_bf16 v[80:83], v[176:179], v[200:203], v[80:83]
	v_mfma_f32_16x16x32_bf16 v[68:71], v[168:171], v[208:211], v[68:71]
	v_mfma_f32_16x16x32_bf16 v[64:67], v[176:179], v[208:211], v[64:67]
	s_setprio 0
	s_barrier
	s_add_i32 s38, s66, s46
	v_lshl_add_u64 v[212:213], v[212:213], 0, s[6:7]
	s_mov_b32 m0, s38
	ds_read_b128 v[180:183], v163 offset:49152
	ds_read_b128 v[184:187], v163 offset:50176
	ds_read_b128 v[188:191], v163 offset:51200
	ds_read_b128 v[192:195], v163 offset:52224
	ds_read_b128 v[196:199], v163 offset:53248
	ds_read_b128 v[200:203], v163 offset:54272
	ds_read_b128 v[204:207], v163 offset:55296
	ds_read_b128 v[208:211], v163 offset:56320
	global_load_lds_dwordx4 v[212:213], off
	s_add_i32 m0, s38, 0x2000
	s_add_u32 s36, s36, 0x40080
	v_lshl_add_u64 v[212:213], v[214:215], 0, s[6:7]
	s_addc_u32 s37, s37, 0
	s_add_i32 s38, s67, s46
	global_load_lds_dwordx4 v[212:213], off
	s_mov_b32 m0, s38
	s_nop 0
	global_load_lds_dwordx4 v130, s[36:37]
	s_add_i32 m0, s38, 0x2000
	s_nop 0
	global_load_lds_dwordx4 v134, s[36:37]
	v_lshl_add_u64 v[212:213], v[216:217], 0, s[6:7]
	s_mov_b32 m0, s52
	s_nop 0
	global_load_lds_dwordx4 v[212:213], off
	v_lshl_add_u64 v[212:213], v[218:219], 0, s[6:7]
	s_mov_b32 m0, s53
	s_nop 0
	global_load_lds_dwordx4 v[212:213], off
	s_waitcnt vmcnt(8)
	s_waitcnt lgkmcnt(0)
	s_barrier
	s_setprio 1
	s_waitcnt lgkmcnt(0)
	v_mfma_f32_16x16x32_bf16 v[60:63], v[142:145], v[180:183], v[60:63]
	v_mfma_f32_16x16x32_bf16 v[56:59], v[150:153], v[180:183], v[56:59]
	v_mfma_f32_16x16x32_bf16 v[44:47], v[142:145], v[188:191], v[44:47]
	v_mfma_f32_16x16x32_bf16 v[40:43], v[150:153], v[188:191], v[40:43]
	v_mfma_f32_16x16x32_bf16 v[28:31], v[142:145], v[196:199], v[28:31]
	v_mfma_f32_16x16x32_bf16 v[24:27], v[150:153], v[196:199], v[24:27]
	v_mfma_f32_16x16x32_bf16 v[12:15], v[142:145], v[204:207], v[12:15]
	v_mfma_f32_16x16x32_bf16 v[8:11], v[150:153], v[204:207], v[8:11]
	v_mfma_f32_16x16x32_bf16 v[60:63], v[146:149], v[184:187], v[60:63]
	v_mfma_f32_16x16x32_bf16 v[56:59], v[154:157], v[184:187], v[56:59]
	v_mfma_f32_16x16x32_bf16 v[44:47], v[146:149], v[192:195], v[44:47]
	v_mfma_f32_16x16x32_bf16 v[40:43], v[154:157], v[192:195], v[40:43]
	v_mfma_f32_16x16x32_bf16 v[28:31], v[146:149], v[200:203], v[28:31]
	v_mfma_f32_16x16x32_bf16 v[24:27], v[154:157], v[200:203], v[24:27]
	v_mfma_f32_16x16x32_bf16 v[12:15], v[146:149], v[208:211], v[12:15]
	v_mfma_f32_16x16x32_bf16 v[8:11], v[154:157], v[208:211], v[8:11]
	s_setprio 0
	s_setprio 1
	v_mfma_f32_16x16x32_bf16 v[52:55], v[164:167], v[180:183], v[52:55]
	v_mfma_f32_16x16x32_bf16 v[48:51], v[172:175], v[180:183], v[48:51]
	v_mfma_f32_16x16x32_bf16 v[36:39], v[164:167], v[188:191], v[36:39]
	v_mfma_f32_16x16x32_bf16 v[32:35], v[172:175], v[188:191], v[32:35]
	v_mfma_f32_16x16x32_bf16 v[20:23], v[164:167], v[196:199], v[20:23]
	v_mfma_f32_16x16x32_bf16 v[16:19], v[172:175], v[196:199], v[16:19]
	v_mfma_f32_16x16x32_bf16 v[4:7], v[164:167], v[204:207], v[4:7]
	v_mfma_f32_16x16x32_bf16 v[0:3], v[172:175], v[204:207], v[0:3]
	v_mfma_f32_16x16x32_bf16 v[52:55], v[168:171], v[184:187], v[52:55]
	v_mfma_f32_16x16x32_bf16 v[48:51], v[176:179], v[184:187], v[48:51]
	v_mfma_f32_16x16x32_bf16 v[36:39], v[168:171], v[192:195], v[36:39]
	v_mfma_f32_16x16x32_bf16 v[32:35], v[176:179], v[192:195], v[32:35]
	v_mfma_f32_16x16x32_bf16 v[20:23], v[168:171], v[200:203], v[20:23]
	v_mfma_f32_16x16x32_bf16 v[16:19], v[176:179], v[200:203], v[16:19]
	v_mfma_f32_16x16x32_bf16 v[4:7], v[168:171], v[208:211], v[4:7]
	v_mfma_f32_16x16x32_bf16 v[0:3], v[176:179], v[208:211], v[0:3]
	s_setprio 0
	s_barrier
	s_add_i32 s65, s65, 2
	s_add_u32 s34, s34, 0x100
	s_addc_u32 s35, s35, 0
	s_add_u32 s63, s63, 0x100
	s_addc_u32 s64, s64, 0
	s_cmp_gt_u32 s65, 13
	s_cbranch_scc0 .LBB0_673
	s_and_b64 vcc, exec, s[8:9]
	s_cbranch_vccz .LBB0_676
	s_barrier

; #define PG8_STAGE(bufoff, gbase, voff) do { _Pragma("unroll") for (int _i = 0; _i < 2; ++_i) \
;         __builtin_amdgcn_global_load_lds((const unsigned*)((const char*)(gbase) + (voff)[_i]), (LAS unsigned*)(lds + (bufoff) + ldsw + _i * 8192), 16, 0, 0); } while (0)
; #define PG8_WAIT_V(n) asm volatile("s_waitcnt vmcnt(" #n ")" ::: "memory")
; #define PG8_BAR __builtin_amdgcn_s_barrier()
; template <class Epi, class Sched>
; __device__ __forceinline__ void gemm_phase(LAS unsigned char* lds, const Gemm g, const Sched& S, const Epi& E, int wave_id) {
;     ...
;     PG8_STAGE(PG8_SB(0, 0), cB, voffB); PG8_STAGE(PG8_SB(0, 1), cB + hstepB, voffB); PG8_STAGE(PG8_SA(0, 0), cA, voffA); PG8_STAGE(PG8_SA(0, 1), cA + hstepA, voffA);
;     if (wr == 1) PG8_BAR;
;     PG8_WAIT_V(2); PG8_BAR;
;     PG8_STAGE(PG8_SB(1, 0), cB + kstep, voffB); PG8_STAGE(PG8_SA(1, 0), cA + kstep, voffA); PG8_STAGE(PG8_SB(1, 1), cB + hstepB + kstep, voffB);
;     PG8_WAIT_V(6); PG8_BAR;
.LBB0_688:
	s_mov_b64 s[10:11], 0x80
	s_add_i32 m0, s36, 0x18000
	v_lshl_add_u64 v[6:7], v[6:7], 0, s[10:11]
	s_waitcnt vmcnt(2)
	s_barrier
	global_load_lds_dwordx4 v[6:7], off
	v_lshl_add_u64 v[2:3], v[2:3], 0, s[10:11]
	s_add_i32 m0, s36, 0x1a000
	s_add_i32 s48, s36, 0x8000
	s_add_i32 s50, s36, 0xa000
	global_load_lds_dwordx4 v[2:3], off
	v_lshl_add_u64 v[0:1], v[0:1], 0, s[10:11]
	s_mov_b32 m0, s48
	s_add_u32 s4, s30, 0x10080
	global_load_lds_dwordx4 v[0:1], off
	v_lshl_add_u64 v[0:1], v[4:5], 0, s[10:11]
	s_mov_b32 m0, s50
	s_addc_u32 s5, s31, 0
	s_add_i32 s51, s36, 0x1c000
	global_load_lds_dwordx4 v[0:1], off
	s_mov_b32 m0, s51
	s_add_i32 s58, s36, 0x1e000
	global_load_lds_dwordx4 v68, s[4:5]
	v_lshl_add_u64 v[0:1], s[4:5], 0, v[64:65]
	s_mov_b32 m0, s58
	s_movk_i32 s4, 0x3c0
	global_load_lds_dwordx4 v[0:1], off
	v_and_b32_e32 v0, 15, v8
	v_lshrrev_b32_e32 v1, 1, v8
	v_or_b32_e32 v74, s55, v0
	v_and_b32_e32 v1, 24, v1
	v_lshlrev_b32_e32 v2, 6, v74
	v_lshlrev_b32_e32 v3, 1, v1
	v_and_or_b32 v2, v2, s4, v3
	v_lshl_or_b32 v0, v0, 6, v3
	v_lshlrev_b32_e32 v3, 2, v8
	v_and_b32_e32 v3, 32, v3
	v_bitop3_b32 v3, v0, s52, v3 bitop3:0xde
	v_or_b32_e32 v0, s53, v1
	s_cmpk_lt_u32 s80, 0x100
	v_lshlrev_b32_e32 v0, 2, v0
	v_mov_b32_e32 v1, v69
	v_readlane_b32 s16, v255, 1
	s_cselect_b64 s[4:5], -1, 0
	v_lshl_add_u64 v[0:1], s[92:93], 0, v[0:1]
	s_mov_b64 s[12:13], 0x1d400000
	s_add_i32 s59, s66, s16
	v_lshl_add_u64 v[72:73], v[0:1], 0, s[12:13]
	s_mul_i32 s13, s59, 0x30000
	s_mul_hi_i32 s12, s59, 0x30000
	s_add_u32 s13, s92, s13
	s_addc_u32 s14, s93, s12
	v_lshlrev_b32_e32 v4, 2, v74
	s_add_u32 s12, s13, 0x17400000
	v_and_b32_e32 v4, 32, v4
	s_waitcnt vmcnt(6)
	s_addc_u32 s13, s14, 0
	s_add_i32 s64, 0, 0x10000
	s_mov_b32 s22, s66
	s_add_i32 s66, 0, 0x18000
	v_bitop3_b32 v2, v2, s54, v4 bitop3:0xde
	v_readlane_b32 s17, v255, 2
	v_add_u32_e32 v75, s64, v3
	s_add_i32 s64, s64, s44
	v_cndmask_b32_e64 v0, 0, 1, s[4:5]
	v_add_u32_e32 v77, s66, v3
	s_add_i32 s66, s66, s44
	s_mul_hi_i32 s60, s16, 0x30000
	s_mul_i32 s61, s16, 0x30000
	v_add_u32_e32 v76, 0, v2
	s_add_i32 s62, s36, 0xc000
	s_add_i32 s63, s36, 0xe000
	s_mov_b64 s[14:15], 0x100
	s_add_i32 s65, s64, 0x2000
	s_mov_b64 s[16:17], 0x180
	s_add_i32 s67, s66, 0x2000
	v_cmp_ne_u32_e64 s[4:5], 1, v0
	s_mov_b32 s73, s22
	s_mov_b64 s[22:23], s[28:29]
	s_barrier
	s_branch .LBB0_691

; #define PG8_STAGE(bufoff, gbase, voff) do { _Pragma("unroll") for (int _i = 0; _i < 2; ++_i) \
;         __builtin_amdgcn_global_load_lds((const unsigned*)((const char*)(gbase) + (voff)[_i]), (LAS unsigned*)(lds + (bufoff) + ldsw + _i * 8192), 16, 0, 0); } while (0)
; #define PG8_LDA(dst, b, h) do { _Pragma("unroll") for (int m = 0; m < 4; ++m) _Pragma("unroll") for (int k = 0; k < 2; ++k) dst[m][k] = *(const LAS bf16x8*)(lds + PG8_SA(b, h) + aoff + m * 2048 + k * 1024); } while (0)
; #define PG8_LDB(dst, b, h) do { _Pragma("unroll") for (int n = 0; n < 2; ++n) _Pragma("unroll") for (int k = 0; k < 2; ++k) dst[n][k] = *(const LAS bf16x8*)(lds + PG8_SB(b, h) + boff + n * 2048 + k * 1024); } while (0)
; #define PG8_WAIT_V(n) asm volatile("s_waitcnt vmcnt(" #n ")" ::: "memory")
; #define PG8_BAR __builtin_amdgcn_s_barrier()
; template <class Epi, class Sched>
; __device__ __forceinline__ void gemm_phase(LAS unsigned char* lds, const Gemm g, const Sched& S, const Epi& E, int wave_id) {
;     ...
;         for (int t = 0; t < nt; t += 2) {
;             const bool last = (t == nt - 2);
;             const char* a1 = cA + (size_t)(t + 1) * kstep;
;             const char* a2 = last ? nA : cA + (size_t)(t + 2) * kstep; const char* b2 = last ? nB : cB + (size_t)(t + 2) * kstep;
;             const char* a3 = a2 + kstep; const char* b3 = b2 + kstep;
;             PG8_LDB(B0, 0, 0); PG8_LDB(B1, 0, 1); PG8_SCHED; PG8_LDA(At, 0, 0); PG8_STAGE(PG8_SA(1, 1), a1 + hstepA, voffA);
;             PG8_WAIT_V(8); PG8_WAIT_L(0); PG8_BAR; PG8_MMA(0, 0, At, B0); PG8_MMA(0, 1, At, B1); PG8_BAR; PG8_SCHED;
;             PG8_LDA(At, 0, 1); PG8_STAGE(PG8_SB(0, 0), b2, voffB); PG8_STAGE(PG8_SB(0, 1), b2 + hstepB, voffB); PG8_STAGE(PG8_SA(0, 0), a2, voffA);
;             PG8_WAIT_V(8); PG8_WAIT_L(0); PG8_BAR; PG8_MMA(1, 0, At, B0); PG8_MMA(1, 1, At, B1); PG8_BAR; PG8_SCHED;
;             PG8_LDB(B0, 1, 0); PG8_LDB(B1, 1, 1); PG8_SCHED; PG8_LDA(At, 1, 0); PG8_STAGE(PG8_SA(0, 1), a2 + hstepA, voffA);
;             PG8_WAIT_V(8); PG8_WAIT_L(0); PG8_BAR; PG8_MMA(0, 0, At, B0); PG8_MMA(0, 1, At, B1); PG8_BAR; PG8_SCHED;
;             PG8_LDA(At, 1, 1); PG8_STAGE(PG8_SB(1, 0), b3, voffB); PG8_STAGE(PG8_SB(1, 1), b3 + hstepB, voffB); PG8_STAGE(PG8_SA(1, 0), a3, voffA);
;             PG8_WAIT_V(8); PG8_WAIT_L(0); PG8_BAR; PG8_MMA(1, 0, At, B0); PG8_MMA(1, 1, At, B1); PG8_BAR; PG8_SCHED;
.LBB0_693:
	s_ashr_i32 s72, s59, 3
	s_and_b64 s[24:25], s[26:27], exec
	ds_read_b128 v[0:3], v75
	ds_read_b128 v[4:7], v75 offset:1024
	ds_read_b128 v[8:11], v75 offset:2048
	ds_read_b128 v[12:15], v75 offset:3072
	s_cselect_b32 s24, s72, s34
	s_ashr_i32 s25, s24, 31
	s_lshl_b64 s[24:25], s[24:25], 17
	s_add_u32 s24, s2, s24
	s_addc_u32 s25, s33, s25
	s_and_b64 s[34:35], s[26:27], exec
	s_cselect_b32 s35, s25, s31
	s_cselect_b32 s34, s24, s30
	s_add_u32 s74, s28, 0x18080
	s_addc_u32 s75, s29, 0
	s_mov_b32 m0, s62
	ds_read_b128 v[16:19], v76
	ds_read_b128 v[20:23], v76 offset:1024
	ds_read_b128 v[24:27], v76 offset:2048
	ds_read_b128 v[28:31], v76 offset:3072
	ds_read_b128 v[32:35], v76 offset:4096
	ds_read_b128 v[36:39], v76 offset:5120
	ds_read_b128 v[40:43], v76 offset:6144
	ds_read_b128 v[44:47], v76 offset:7168
	global_load_lds_dwordx4 v70, s[74:75]
	s_mov_b32 m0, s63
	s_nop 0
	global_load_lds_dwordx4 v66, s[74:75]
	s_waitcnt vmcnt(8)
	s_waitcnt lgkmcnt(0)
	s_barrier
	s_setprio 1
	s_waitcnt lgkmcnt(0)
	v_mfma_f32_16x16x32_bf16 v[48:51], v[0:3], v[16:19], 0
	v_mfma_f32_16x16x32_bf16 v[16:19], v[8:11], v[16:19], 0
	v_mfma_f32_16x16x32_bf16 v[48:51], v[4:7], v[20:23], v[48:51]
	v_mfma_f32_16x16x32_bf16 v[16:19], v[12:15], v[20:23], v[16:19]
	v_mfma_f32_16x16x32_bf16 v[20:23], v[0:3], v[24:27], 0
	v_mfma_f32_16x16x32_bf16 v[24:27], v[8:11], v[24:27], 0
	v_mfma_f32_16x16x32_bf16 v[20:23], v[4:7], v[28:31], v[20:23]
	v_mfma_f32_16x16x32_bf16 v[24:27], v[12:15], v[28:31], v[24:27]
	v_mfma_f32_16x16x32_bf16 v[28:31], v[0:3], v[32:35], 0
	v_mfma_f32_16x16x32_bf16 v[32:35], v[8:11], v[32:35], 0
	v_mfma_f32_16x16x32_bf16 v[28:31], v[4:7], v[36:39], v[28:31]
	v_mfma_f32_16x16x32_bf16 v[32:35], v[12:15], v[36:39], v[32:35]
	v_mfma_f32_16x16x32_bf16 v[36:39], v[0:3], v[40:43], 0
	v_mfma_f32_16x16x32_bf16 v[40:43], v[8:11], v[40:43], 0
	v_mfma_f32_16x16x32_bf16 v[36:39], v[4:7], v[44:47], v[36:39]
	v_mfma_f32_16x16x32_bf16 v[40:43], v[12:15], v[44:47], v[40:43]
	s_setprio 0
	s_setprio 1
	s_setprio 0
	s_barrier
	v_lshl_add_u64 v[126:127], s[30:31], 0, v[68:69]
	s_mov_b32 m0, s64
	v_lshl_add_u64 v[94:95], v[126:127], 0, s[14:15]
	v_lshl_add_u64 v[128:129], s[30:31], 0, v[64:65]
	s_add_u32 s74, s30, 0x10100
	ds_read_b128 v[44:47], v76 offset:16384
	ds_read_b128 v[52:55], v76 offset:17408
	ds_read_b128 v[56:59], v76 offset:18432
	ds_read_b128 v[60:63], v76 offset:19456
	ds_read_b128 v[78:81], v76 offset:20480
	ds_read_b128 v[82:85], v76 offset:21504
	ds_read_b128 v[86:89], v76 offset:22528
	ds_read_b128 v[90:93], v76 offset:23552
	global_load_lds_dwordx4 v[94:95], off
	v_lshl_add_u64 v[94:95], v[128:129], 0, s[14:15]
	s_mov_b32 m0, s65
	s_addc_u32 s75, s31, 0
	global_load_lds_dwordx4 v[94:95], off
	s_mov_b32 m0, s37
	v_lshl_add_u64 v[130:131], s[28:29], 0, v[70:71]
	global_load_lds_dwordx4 v68, s[74:75]
	s_mov_b32 m0, s38
	v_lshl_add_u64 v[132:133], s[28:29], 0, v[66:67]
	global_load_lds_dwordx4 v64, s[74:75]
	v_lshl_add_u64 v[94:95], v[130:131], 0, s[14:15]
	s_mov_b32 m0, s36
	s_nop 0
	global_load_lds_dwordx4 v[94:95], off
	v_lshl_add_u64 v[94:95], v[132:133], 0, s[14:15]
	s_mov_b32 m0, s39
	s_nop 0
	global_load_lds_dwordx4 v[94:95], off
	s_waitcnt vmcnt(8)
	s_waitcnt lgkmcnt(0)
	s_barrier
	s_setprio 1
	s_waitcnt lgkmcnt(0)
	v_mfma_f32_16x16x32_bf16 v[94:97], v[0:3], v[44:47], 0
	v_mfma_f32_16x16x32_bf16 v[44:47], v[8:11], v[44:47], 0
	v_mfma_f32_16x16x32_bf16 v[94:97], v[4:7], v[52:55], v[94:97]
	v_mfma_f32_16x16x32_bf16 v[44:47], v[12:15], v[52:55], v[44:47]
	v_mfma_f32_16x16x32_bf16 v[52:55], v[0:3], v[56:59], 0
	v_mfma_f32_16x16x32_bf16 v[56:59], v[8:11], v[56:59], 0
	v_mfma_f32_16x16x32_bf16 v[52:55], v[4:7], v[60:63], v[52:55]
	v_mfma_f32_16x16x32_bf16 v[56:59], v[12:15], v[60:63], v[56:59]
	v_mfma_f32_16x16x32_bf16 v[60:63], v[0:3], v[78:81], 0
	v_mfma_f32_16x16x32_bf16 v[0:3], v[0:3], v[86:89], 0
	v_mfma_f32_16x16x32_bf16 v[60:63], v[4:7], v[82:85], v[60:63]
	v_mfma_f32_16x16x32_bf16 v[0:3], v[4:7], v[90:93], v[0:3]
	v_mfma_f32_16x16x32_bf16 v[4:7], v[8:11], v[86:89], 0
	v_mfma_f32_16x16x32_bf16 v[78:81], v[8:11], v[78:81], 0
	v_mfma_f32_16x16x32_bf16 v[4:7], v[12:15], v[90:93], v[4:7]
	v_mfma_f32_16x16x32_bf16 v[78:81], v[12:15], v[82:85], v[78:81]
	s_setprio 0
	s_setprio 1
	s_setprio 0
	s_barrier
	ds_read_b128 v[8:11], v77
	ds_read_b128 v[12:15], v77 offset:1024
	ds_read_b128 v[82:85], v77 offset:2048
	ds_read_b128 v[86:89], v77 offset:3072
	s_add_u32 s74, s28, 0x18100
	s_addc_u32 s75, s29, 0
	s_mov_b32 m0, s45
	ds_read_b128 v[90:93], v76 offset:32768
	ds_read_b128 v[98:101], v76 offset:33792
	ds_read_b128 v[102:105], v76 offset:34816
	ds_read_b128 v[106:109], v76 offset:35840
	ds_read_b128 v[110:113], v76 offset:36864
	ds_read_b128 v[114:117], v76 offset:37888
	ds_read_b128 v[118:121], v76 offset:38912
	ds_read_b128 v[122:125], v76 offset:39936
	global_load_lds_dwordx4 v70, s[74:75]
	s_mov_b32 m0, s46
	s_nop 0
	global_load_lds_dwordx4 v66, s[74:75]
	s_waitcnt vmcnt(8)
	s_waitcnt lgkmcnt(0)
	s_barrier
	s_setprio 1
	s_waitcnt lgkmcnt(0)
	v_mfma_f32_16x16x32_bf16 v[48:51], v[8:11], v[90:93], v[48:51]
	v_mfma_f32_16x16x32_bf16 v[16:19], v[82:85], v[90:93], v[16:19]
	v_mfma_f32_16x16x32_bf16 v[20:23], v[8:11], v[102:105], v[20:23]
	v_mfma_f32_16x16x32_bf16 v[24:27], v[82:85], v[102:105], v[24:27]
	v_mfma_f32_16x16x32_bf16 v[28:31], v[8:11], v[110:113], v[28:31]
	v_mfma_f32_16x16x32_bf16 v[32:35], v[82:85], v[110:113], v[32:35]
	v_mfma_f32_16x16x32_bf16 v[36:39], v[8:11], v[118:121], v[36:39]
	v_mfma_f32_16x16x32_bf16 v[40:43], v[82:85], v[118:121], v[40:43]
	v_mfma_f32_16x16x32_bf16 v[48:51], v[12:15], v[98:101], v[48:51]
	v_mfma_f32_16x16x32_bf16 v[16:19], v[86:89], v[98:101], v[16:19]
	v_mfma_f32_16x16x32_bf16 v[20:23], v[12:15], v[106:109], v[20:23]
	v_mfma_f32_16x16x32_bf16 v[24:27], v[86:89], v[106:109], v[24:27]
	v_mfma_f32_16x16x32_bf16 v[28:31], v[12:15], v[114:117], v[28:31]
	v_mfma_f32_16x16x32_bf16 v[32:35], v[86:89], v[114:117], v[32:35]
	v_mfma_f32_16x16x32_bf16 v[36:39], v[12:15], v[122:125], v[36:39]
	v_mfma_f32_16x16x32_bf16 v[40:43], v[86:89], v[122:125], v[40:43]
	s_setprio 0
	s_setprio 1
	s_setprio 0
	s_barrier
; #define PG8_STAGE(bufoff, gbase, voff) do { _Pragma("unroll") for (int _i = 0; _i < 2; ++_i) \
;         __builtin_amdgcn_global_load_lds((const unsigned*)((const char*)(gbase) + (voff)[_i]), (LAS unsigned*)(lds + (bufoff) + ldsw + _i * 8192), 16, 0, 0); } while (0)
; #define PG8_LDA(dst, b, h) do { _Pragma("unroll") for (int m = 0; m < 4; ++m) _Pragma("unroll") for (int k = 0; k < 2; ++k) dst[m][k] = *(const LAS bf16x8*)(lds + PG8_SA(b, h) + aoff + m * 2048 + k * 1024); } while (0)
; #define PG8_LDB(dst, b, h) do { _Pragma("unroll") for (int n = 0; n < 2; ++n) _Pragma("unroll") for (int k = 0; k < 2; ++k) dst[n][k] = *(const LAS bf16x8*)(lds + PG8_SB(b, h) + boff + n * 2048 + k * 1024); } while (0)
; #define PG8_WAIT_V(n) asm volatile("s_waitcnt vmcnt(" #n ")" ::: "memory")
; #define PG8_BAR __builtin_amdgcn_s_barrier()
; template <class Epi, class Sched>
; __device__ __forceinline__ void gemm_phase(LAS unsigned char* lds, const Gemm g, const Sched& S, const Epi& E, int wave_id) {
;     ...
;         for (int t = 0; t < nt; t += 2) {
;             const bool last = (t == nt - 2);
;             const char* a1 = cA + (size_t)(t + 1) * kstep;
;             const char* a2 = last ? nA : cA + (size_t)(t + 2) * kstep; const char* b2 = last ? nB : cB + (size_t)(t + 2) * kstep;
;             const char* a3 = a2 + kstep; const char* b3 = b2 + kstep;
;             PG8_LDB(B0, 0, 0); PG8_LDB(B1, 0, 1); PG8_SCHED; PG8_LDA(At, 0, 0); PG8_STAGE(PG8_SA(1, 1), a1 + hstepA, voffA);
;             PG8_WAIT_V(8); PG8_WAIT_L(0); PG8_BAR; PG8_MMA(0, 0, At, B0); PG8_MMA(0, 1, At, B1); PG8_BAR; PG8_SCHED;
;             PG8_LDA(At, 0, 1); PG8_STAGE(PG8_SB(0, 0), b2, voffB); PG8_STAGE(PG8_SB(0, 1), b2 + hstepB, voffB); PG8_STAGE(PG8_SA(0, 0), a2, voffA);
;             PG8_WAIT_V(8); PG8_WAIT_L(0); PG8_BAR; PG8_MMA(1, 0, At, B0); PG8_MMA(1, 1, At, B1); PG8_BAR; PG8_SCHED;
;             PG8_LDB(B0, 1, 0); PG8_LDB(B1, 1, 1); PG8_SCHED; PG8_LDA(At, 1, 0); PG8_STAGE(PG8_SA(0, 1), a2 + hstepA, voffA);
;             PG8_WAIT_V(8); PG8_WAIT_L(0); PG8_BAR; PG8_MMA(0, 0, At, B0); PG8_MMA(0, 1, At, B1); PG8_BAR; PG8_SCHED;
;             PG8_LDA(At, 1, 1); PG8_STAGE(PG8_SB(1, 0), b3, voffB); PG8_STAGE(PG8_SB(1, 1), b3 + hstepB, voffB); PG8_STAGE(PG8_SA(1, 0), a3, voffA);
;             PG8_WAIT_V(8); PG8_WAIT_L(0); PG8_BAR; PG8_MMA(1, 0, At, B0); PG8_MMA(1, 1, At, B1); PG8_BAR; PG8_SCHED;
	s_mov_b32 m0, s66
	v_lshl_add_u64 v[126:127], v[126:127], 0, s[16:17]
	s_add_u32 s30, s30, 0x10180
	ds_read_b128 v[90:93], v76 offset:49152
	ds_read_b128 v[98:101], v76 offset:50176
	ds_read_b128 v[102:105], v76 offset:51200
	ds_read_b128 v[106:109], v76 offset:52224
	ds_read_b128 v[110:113], v76 offset:53248
	ds_read_b128 v[114:117], v76 offset:54272
	ds_read_b128 v[118:121], v76 offset:55296
	ds_read_b128 v[122:125], v76 offset:56320
	global_load_lds_dwordx4 v[126:127], off
	v_lshl_add_u64 v[126:127], v[128:129], 0, s[16:17]
	s_mov_b32 m0, s67
	s_addc_u32 s31, s31, 0
	global_load_lds_dwordx4 v[126:127], off
	s_mov_b32 m0, s51
	s_nop 0
	global_load_lds_dwordx4 v68, s[30:31]
	s_mov_b32 m0, s58
	s_nop 0
	global_load_lds_dwordx4 v64, s[30:31]
	v_lshl_add_u64 v[126:127], v[130:131], 0, s[16:17]
	s_mov_b32 m0, s48
	s_nop 0
	global_load_lds_dwordx4 v[126:127], off
	v_lshl_add_u64 v[126:127], v[132:133], 0, s[16:17]
	s_mov_b32 m0, s50
	s_nop 0
	global_load_lds_dwordx4 v[126:127], off
	s_waitcnt vmcnt(8)
	s_waitcnt lgkmcnt(0)
	s_barrier
	s_setprio 1
	s_waitcnt lgkmcnt(0)
	v_mfma_f32_16x16x32_bf16 v[44:47], v[82:85], v[90:93], v[44:47]
	v_mfma_f32_16x16x32_bf16 v[52:55], v[8:11], v[102:105], v[52:55]
	v_mfma_f32_16x16x32_bf16 v[56:59], v[82:85], v[102:105], v[56:59]
	v_mfma_f32_16x16x32_bf16 v[60:63], v[8:11], v[110:113], v[60:63]
	v_mfma_f32_16x16x32_bf16 v[0:3], v[8:11], v[118:121], v[0:3]
	v_mfma_f32_16x16x32_bf16 v[4:7], v[82:85], v[118:121], v[4:7]
	v_mfma_f32_16x16x32_bf16 v[94:97], v[8:11], v[90:93], v[94:97]
	v_mfma_f32_16x16x32_bf16 v[44:47], v[86:89], v[98:101], v[44:47]
	v_mfma_f32_16x16x32_bf16 v[52:55], v[12:15], v[106:109], v[52:55]
	v_mfma_f32_16x16x32_bf16 v[56:59], v[86:89], v[106:109], v[56:59]
	v_mfma_f32_16x16x32_bf16 v[60:63], v[12:15], v[114:117], v[60:63]
	v_mfma_f32_16x16x32_bf16 v[78:81], v[82:85], v[110:113], v[78:81]
	v_mfma_f32_16x16x32_bf16 v[0:3], v[12:15], v[122:125], v[0:3]
	v_mfma_f32_16x16x32_bf16 v[4:7], v[86:89], v[122:125], v[4:7]
	v_mfma_f32_16x16x32_bf16 v[94:97], v[12:15], v[98:101], v[94:97]
	v_mfma_f32_16x16x32_bf16 v[78:81], v[86:89], v[114:117], v[78:81]
	s_setprio 0
	s_setprio 1
	s_setprio 0
	s_barrier
	ds_read_b128 v[8:11], v75
	ds_read_b128 v[12:15], v75 offset:1024
	ds_read_b128 v[82:85], v75 offset:2048
	ds_read_b128 v[86:89], v75 offset:3072
	s_add_u32 s28, s28, 0x18180
	s_addc_u32 s29, s29, 0
	s_mov_b32 m0, s62
	ds_read_b128 v[90:93], v76
	ds_read_b128 v[98:101], v76 offset:1024
	ds_read_b128 v[102:105], v76 offset:2048
	ds_read_b128 v[106:109], v76 offset:3072
	ds_read_b128 v[110:113], v76 offset:4096
	ds_read_b128 v[114:117], v76 offset:5120
	ds_read_b128 v[118:121], v76 offset:6144
	ds_read_b128 v[122:125], v76 offset:7168
	global_load_lds_dwordx4 v70, s[28:29]
	s_mov_b32 m0, s63
	s_nop 0
	global_load_lds_dwordx4 v66, s[28:29]
	s_waitcnt vmcnt(8)
	s_waitcnt lgkmcnt(0)
	s_barrier
	s_setprio 1
	s_waitcnt lgkmcnt(0)
	v_mfma_f32_16x16x32_bf16 v[24:27], v[82:85], v[102:105], v[24:27]
	v_mfma_f32_16x16x32_bf16 v[48:51], v[8:11], v[90:93], v[48:51]
	v_mfma_f32_16x16x32_bf16 v[16:19], v[82:85], v[90:93], v[16:19]
	v_mfma_f32_16x16x32_bf16 v[90:93], v[86:89], v[106:109], v[24:27]
	v_mfma_f32_16x16x32_bf16 v[24:27], v[8:11], v[110:113], v[28:31]
	v_mfma_f32_16x16x32_bf16 v[48:51], v[12:15], v[98:101], v[48:51]
	v_mfma_f32_16x16x32_bf16 v[16:19], v[86:89], v[98:101], v[16:19]
	v_mfma_f32_16x16x32_bf16 v[98:101], v[12:15], v[114:117], v[24:27]
	v_mfma_f32_16x16x32_bf16 v[24:27], v[82:85], v[110:113], v[32:35]
	v_mfma_f32_16x16x32_bf16 v[32:35], v[86:89], v[114:117], v[24:27]
	v_mfma_f32_16x16x32_bf16 v[24:27], v[8:11], v[118:121], v[36:39]
	v_mfma_f32_16x16x32_bf16 v[20:23], v[8:11], v[102:105], v[20:23]
	v_mfma_f32_16x16x32_bf16 v[36:39], v[12:15], v[122:125], v[24:27]
	v_mfma_f32_16x16x32_bf16 v[24:27], v[82:85], v[118:121], v[40:43]
	v_mfma_f32_16x16x32_bf16 v[20:23], v[12:15], v[106:109], v[20:23]
	v_mfma_f32_16x16x32_bf16 v[40:43], v[86:89], v[122:125], v[24:27]
	s_setprio 0
	s_setprio 1
	s_setprio 0
	s_barrier
	s_mov_b32 m0, s64
	v_lshl_add_u64 v[138:139], s[34:35], 0, v[68:69]
	s_add_u32 s28, s34, 0x10000
	ds_read_b128 v[24:27], v76 offset:16384
	ds_read_b128 v[28:31], v76 offset:17408
	ds_read_b128 v[102:105], v76 offset:18432
	ds_read_b128 v[106:109], v76 offset:19456
	ds_read_b128 v[110:113], v76 offset:20480
	ds_read_b128 v[114:117], v76 offset:21504
	ds_read_b128 v[118:121], v76 offset:22528
	ds_read_b128 v[122:125], v76 offset:23552
	global_load_lds_dwordx4 v[138:139], off
	v_lshl_add_u64 v[140:141], s[34:35], 0, v[64:65]
	s_mov_b32 m0, s65
	s_addc_u32 s29, s35, 0
	global_load_lds_dwordx4 v[140:141], off
	s_mov_b32 m0, s37
	v_lshl_add_u64 v[142:143], s[22:23], 0, v[70:71]
	global_load_lds_dwordx4 v68, s[28:29]
	s_mov_b32 m0, s38
	v_lshl_add_u64 v[144:145], s[22:23], 0, v[66:67]
	global_load_lds_dwordx4 v64, s[28:29]
	s_mov_b32 m0, s36
	s_nop 0
	global_load_lds_dwordx4 v[142:143], off
	s_mov_b32 m0, s39
	s_nop 0
	global_load_lds_dwordx4 v[144:145], off
	s_waitcnt vmcnt(8)
	s_waitcnt lgkmcnt(0)
	s_barrier
; #define PG8_STAGE(bufoff, gbase, voff) do { _Pragma("unroll") for (int _i = 0; _i < 2; ++_i) \
;         __builtin_amdgcn_global_load_lds((const unsigned*)((const char*)(gbase) + (voff)[_i]), (LAS unsigned*)(lds + (bufoff) + ldsw + _i * 8192), 16, 0, 0); } while (0)
; #define PG8_LDA(dst, b, h) do { _Pragma("unroll") for (int m = 0; m < 4; ++m) _Pragma("unroll") for (int k = 0; k < 2; ++k) dst[m][k] = *(const LAS bf16x8*)(lds + PG8_SA(b, h) + aoff + m * 2048 + k * 1024); } while (0)
; #define PG8_LDB(dst, b, h) do { _Pragma("unroll") for (int n = 0; n < 2; ++n) _Pragma("unroll") for (int k = 0; k < 2; ++k) dst[n][k] = *(const LAS bf16x8*)(lds + PG8_SB(b, h) + boff + n * 2048 + k * 1024); } while (0)
; #define PG8_MMA(ai, bj, At, Bt) do { __builtin_amdgcn_s_setprio(1); _Pragma("unroll") for (int m = 0; m < 4; ++m) _Pragma("unroll") for (int n = 0; n < 2; ++n) _Pragma("unroll") for (int k = 0; k < 2; ++k) \
;         acc[ai][bj][m][n] = __builtin_amdgcn_mfma_f32_16x16x32_bf16(Bt[n][k], At[m][k], acc[ai][bj][m][n], 0, 0, 0); __builtin_amdgcn_s_setprio(0); } while (0)
; #define PG8_WAIT_V(n) asm volatile("s_waitcnt vmcnt(" #n ")" ::: "memory")
; #define PG8_WAIT_L(n) asm volatile("s_waitcnt lgkmcnt(" #n ")" ::: "memory")
; #define PG8_BAR __builtin_amdgcn_s_barrier()
; template <class Epi, class Sched>
; __device__ __forceinline__ void gemm_phase(LAS unsigned char* lds, const Gemm g, const Sched& S, const Epi& E, int wave_id) {
;     ...
;             PG8_WAIT_V(8); PG8_WAIT_L(0); PG8_BAR; PG8_MMA(0, 0, At, B0); PG8_MMA(0, 1, At, B1); PG8_BAR; PG8_SCHED;
;             PG8_LDA(At, 0, 1); PG8_STAGE(PG8_SB(0, 0), b2, voffB); PG8_STAGE(PG8_SB(0, 1), b2 + hstepB, voffB); PG8_STAGE(PG8_SA(0, 0), a2, voffA);
;             PG8_WAIT_V(8); PG8_WAIT_L(0); PG8_BAR; PG8_MMA(1, 0, At, B0); PG8_MMA(1, 1, At, B1); PG8_BAR; PG8_SCHED;
;             PG8_LDB(B0, 1, 0); PG8_LDB(B1, 1, 1); PG8_SCHED; PG8_LDA(At, 1, 0); PG8_STAGE(PG8_SA(0, 1), a2 + hstepA, voffA);
;             PG8_WAIT_V(8); PG8_WAIT_L(0); PG8_BAR; PG8_MMA(0, 0, At, B0); PG8_MMA(0, 1, At, B1); PG8_BAR; PG8_SCHED;
;             PG8_LDA(At, 1, 1); PG8_STAGE(PG8_SB(1, 0), b3, voffB); PG8_STAGE(PG8_SB(1, 1), b3 + hstepB, voffB); PG8_STAGE(PG8_SA(1, 0), a3, voffA);
;             PG8_WAIT_V(8); PG8_WAIT_L(0); PG8_BAR; PG8_MMA(1, 0, At, B0); PG8_MMA(1, 1, At, B1); PG8_BAR; PG8_SCHED;
;         }
;         if (wr == 0) PG8_BAR;
	s_setprio 1
	s_waitcnt lgkmcnt(0)
	v_mfma_f32_16x16x32_bf16 v[94:97], v[8:11], v[24:27], v[94:97]
	v_mfma_f32_16x16x32_bf16 v[24:27], v[82:85], v[24:27], v[44:47]
	v_mfma_f32_16x16x32_bf16 v[44:47], v[86:89], v[28:31], v[24:27]
	v_mfma_f32_16x16x32_bf16 v[24:27], v[8:11], v[102:105], v[52:55]
	v_mfma_f32_16x16x32_bf16 v[52:55], v[12:15], v[106:109], v[24:27]
	v_mfma_f32_16x16x32_bf16 v[24:27], v[82:85], v[102:105], v[56:59]
	v_mfma_f32_16x16x32_bf16 v[102:105], v[86:89], v[106:109], v[24:27]
	v_mfma_f32_16x16x32_bf16 v[24:27], v[8:11], v[110:113], v[60:63]
	v_mfma_f32_16x16x32_bf16 v[0:3], v[8:11], v[118:121], v[0:3]
	v_mfma_f32_16x16x32_bf16 v[106:109], v[12:15], v[114:117], v[24:27]
	v_mfma_f32_16x16x32_bf16 v[24:27], v[82:85], v[110:113], v[78:81]
	v_mfma_f32_16x16x32_bf16 v[110:113], v[12:15], v[122:125], v[0:3]
	v_mfma_f32_16x16x32_bf16 v[0:3], v[82:85], v[118:121], v[4:7]
	v_mfma_f32_16x16x32_bf16 v[94:97], v[12:15], v[28:31], v[94:97]
	v_mfma_f32_16x16x32_bf16 v[78:81], v[86:89], v[114:117], v[24:27]
	v_mfma_f32_16x16x32_bf16 v[82:85], v[86:89], v[122:125], v[0:3]
	s_setprio 0
	s_setprio 1
	s_setprio 0
	s_barrier
	ds_read_b128 v[86:89], v77
	ds_read_b128 v[114:117], v77 offset:1024
	ds_read_b128 v[118:121], v77 offset:2048
	ds_read_b128 v[122:125], v77 offset:3072
	s_add_u32 s28, s22, 0x18000
	s_addc_u32 s29, s23, 0
	s_mov_b32 m0, s45
	ds_read_b128 v[0:3], v76 offset:32768
	ds_read_b128 v[4:7], v76 offset:33792
	ds_read_b128 v[8:11], v76 offset:34816
	ds_read_b128 v[12:15], v76 offset:35840
	ds_read_b128 v[56:59], v76 offset:36864
	ds_read_b128 v[60:63], v76 offset:37888
	ds_read_b128 v[126:129], v76 offset:38912
	ds_read_b128 v[130:133], v76 offset:39936
	global_load_lds_dwordx4 v70, s[28:29]
	s_mov_b32 m0, s46
	s_nop 0
	global_load_lds_dwordx4 v66, s[28:29]
	s_waitcnt vmcnt(8)
	s_waitcnt lgkmcnt(0)
	s_barrier
	s_setprio 1
	s_waitcnt lgkmcnt(0)
	v_mfma_f32_16x16x32_bf16 v[24:27], v[86:89], v[0:3], v[48:51]
	v_mfma_f32_16x16x32_bf16 v[0:3], v[118:121], v[0:3], v[16:19]
	v_mfma_f32_16x16x32_bf16 v[28:31], v[122:125], v[4:7], v[0:3]
	v_mfma_f32_16x16x32_bf16 v[0:3], v[86:89], v[8:11], v[20:23]
	v_mfma_f32_16x16x32_bf16 v[16:19], v[114:117], v[12:15], v[0:3]
	v_mfma_f32_16x16x32_bf16 v[0:3], v[118:121], v[8:11], v[90:93]
	v_mfma_f32_16x16x32_bf16 v[20:23], v[122:125], v[12:15], v[0:3]
	v_mfma_f32_16x16x32_bf16 v[0:3], v[86:89], v[56:59], v[98:101]
	v_mfma_f32_16x16x32_bf16 v[8:11], v[114:117], v[60:63], v[0:3]
	v_mfma_f32_16x16x32_bf16 v[0:3], v[118:121], v[56:59], v[32:35]
	v_mfma_f32_16x16x32_bf16 v[24:27], v[114:117], v[4:7], v[24:27]
	v_mfma_f32_16x16x32_bf16 v[12:15], v[122:125], v[60:63], v[0:3]
	v_mfma_f32_16x16x32_bf16 v[0:3], v[86:89], v[126:129], v[36:39]
	v_mfma_f32_16x16x32_bf16 v[4:7], v[118:121], v[126:129], v[40:43]
	v_mfma_f32_16x16x32_bf16 v[0:3], v[114:117], v[130:133], v[0:3]
	v_mfma_f32_16x16x32_bf16 v[4:7], v[122:125], v[130:133], v[4:7]
	s_setprio 0
	s_setprio 1
	s_setprio 0
	s_barrier
	s_mov_b32 m0, s66
	v_lshl_add_u64 v[48:49], v[138:139], 0, s[10:11]
	s_add_u32 s28, s34, 0x10080
	ds_read_b128 v[32:35], v76 offset:49152
	ds_read_b128 v[36:39], v76 offset:50176
	ds_read_b128 v[40:43], v76 offset:51200
	ds_read_b128 v[90:93], v76 offset:52224
	ds_read_b128 v[98:101], v76 offset:53248
	ds_read_b128 v[126:129], v76 offset:54272
	ds_read_b128 v[130:133], v76 offset:55296
	ds_read_b128 v[134:137], v76 offset:56320
	global_load_lds_dwordx4 v[48:49], off
	v_lshl_add_u64 v[48:49], v[140:141], 0, s[10:11]
	s_mov_b32 m0, s67
	s_addc_u32 s29, s35, 0
	global_load_lds_dwordx4 v[48:49], off
	s_mov_b32 m0, s51
	s_nop 0
	global_load_lds_dwordx4 v68, s[28:29]
	s_mov_b32 m0, s58
	s_nop 0
	global_load_lds_dwordx4 v64, s[28:29]
	v_lshl_add_u64 v[48:49], v[142:143], 0, s[10:11]
	s_mov_b32 m0, s48
	s_nop 0
	global_load_lds_dwordx4 v[48:49], off
	v_lshl_add_u64 v[48:49], v[144:145], 0, s[10:11]
	s_mov_b32 m0, s50
	s_nop 0
	global_load_lds_dwordx4 v[48:49], off
	s_waitcnt vmcnt(8)
	s_waitcnt lgkmcnt(0)
	s_barrier
	s_setprio 1
	s_waitcnt lgkmcnt(0)
	v_mfma_f32_16x16x32_bf16 v[48:51], v[86:89], v[32:35], v[94:97]
	v_mfma_f32_16x16x32_bf16 v[32:35], v[118:121], v[32:35], v[44:47]
	v_mfma_f32_16x16x32_bf16 v[60:63], v[122:125], v[36:39], v[32:35]
	v_mfma_f32_16x16x32_bf16 v[32:35], v[86:89], v[40:43], v[52:55]
	v_mfma_f32_16x16x32_bf16 v[56:59], v[114:117], v[36:39], v[48:51]
	v_mfma_f32_16x16x32_bf16 v[48:51], v[114:117], v[90:93], v[32:35]
	v_mfma_f32_16x16x32_bf16 v[32:35], v[118:121], v[40:43], v[102:105]
	v_mfma_f32_16x16x32_bf16 v[52:55], v[122:125], v[90:93], v[32:35]
	v_mfma_f32_16x16x32_bf16 v[32:35], v[86:89], v[98:101], v[106:109]
	v_mfma_f32_16x16x32_bf16 v[40:43], v[114:117], v[126:129], v[32:35]
	v_mfma_f32_16x16x32_bf16 v[32:35], v[118:121], v[98:101], v[78:81]
	v_mfma_f32_16x16x32_bf16 v[44:47], v[122:125], v[126:129], v[32:35]
	v_mfma_f32_16x16x32_bf16 v[32:35], v[86:89], v[130:133], v[110:113]
	v_mfma_f32_16x16x32_bf16 v[36:39], v[118:121], v[130:133], v[82:85]
	v_mfma_f32_16x16x32_bf16 v[32:35], v[114:117], v[134:137], v[32:35]
	v_mfma_f32_16x16x32_bf16 v[36:39], v[122:125], v[134:137], v[36:39]
	s_setprio 0
	s_setprio 1
	s_setprio 0
	s_barrier
	s_and_b64 vcc, exec, s[4:5]
	s_cbranch_vccnz .LBB0_695
	s_barrier

;     __device__ bool next(int i, Unit& u) const { if (r0 + i >= r1) return false; return base.next(r0 + i, u); }
;     __device__ bool next(int i, Unit& u) const { const int L = i * G + c; if (L >= 256) return false; u.pm = L; u.pn = L >> 3; return true; }
; #define PG8_STAGE(bufoff, gbase, voff) do { _Pragma("unroll") for (int _i = 0; _i < 2; ++_i) \
;         __builtin_amdgcn_global_load_lds((const unsigned*)((const char*)(gbase) + (voff)[_i]), (LAS unsigned*)(lds + (bufoff) + ldsw + _i * 8192), 16, 0, 0); } while (0)
; #define PG8_WAIT_V(n) asm volatile("s_waitcnt vmcnt(" #n ")" ::: "memory")
; #define PG8_BAR __builtin_amdgcn_s_barrier()
; template <class Epi, class Sched>
; __device__ __forceinline__ void gemm_phase(LAS unsigned char* lds, const Gemm g, const Sched& S, const Epi& E, int wave_id) {
;     ...
;     const char* cA = (const char*)g.A + (size_t)cur.pm * tstepA; const char* cB = (const char*)g.Bt + (size_t)cur.pn * tstepB;
;     PG8_STAGE(PG8_SB(0, 0), cB, voffB); PG8_STAGE(PG8_SB(0, 1), cB + hstepB, voffB); PG8_STAGE(PG8_SA(0, 0), cA, voffA); PG8_STAGE(PG8_SA(0, 1), cA + hstepA, voffA);
;     if (wr == 1) PG8_BAR;
;     PG8_WAIT_V(2); PG8_BAR;
;     PG8_STAGE(PG8_SB(1, 0), cB + kstep, voffB); PG8_STAGE(PG8_SA(1, 0), cA + kstep, voffA); PG8_STAGE(PG8_SB(1, 1), cB + hstepB + kstep, voffB);
;     PG8_WAIT_V(6); PG8_BAR;
;     for (;;) {
;         const bool has_next = S.next(ui + 1, nxt);
;         const char* nA = has_next ? (const char*)g.A + (size_t)nxt.pm * tstepA : cA; const char* nB = has_next ? (const char*)g.Bt + (size_t)nxt.pn * tstepB : cB;
.LBB0_717:
	s_mov_b64 s[6:7], 0x80
	v_readlane_b32 s12, v255, 1
	s_add_i32 m0, s29, 0x18000
	v_lshl_add_u64 v[6:7], v[6:7], 0, s[6:7]
	s_ashr_i32 s49, s12, 31
	s_waitcnt vmcnt(2)
	s_barrier
	global_load_lds_dwordx4 v[6:7], off
	v_lshl_add_u64 v[4:5], v[4:5], 0, s[6:7]
	s_add_i32 m0, s29, 0x1a000
	s_add_i32 s50, s29, 0x8000
	s_add_i32 s51, s29, 0xa000
	global_load_lds_dwordx4 v[4:5], off
	v_lshl_add_u64 v[0:1], v[0:1], 0, s[6:7]
	s_mov_b32 m0, s50
	s_add_u32 s10, s34, 0x40080
	global_load_lds_dwordx4 v[0:1], off
	v_lshl_add_u64 v[0:1], v[2:3], 0, s[6:7]
	s_mov_b32 m0, s51
	s_addc_u32 s11, s35, 0
	global_load_lds_dwordx4 v[0:1], off
	s_add_i32 m0, s29, 0x1c000
	s_nop 0
	global_load_lds_dwordx4 v130, s[10:11]
	v_lshl_add_u64 v[0:1], s[10:11], 0, v[134:135]
	s_add_i32 m0, s29, 0x1e000
	s_sext_i32_i8 s58, s8
	global_load_lds_dwordx4 v[0:1], off
	v_and_b32_e32 v0, 15, v8
	v_lshrrev_b32_e32 v1, 1, v8
	v_or_b32_e32 v158, s55, v0
	v_and_b32_e32 v1, 24, v1
	v_lshlrev_b32_e32 v2, 6, v158
	v_lshlrev_b32_e32 v3, 1, v1
	s_movk_i32 s8, 0x3c0
	v_and_or_b32 v2, v2, s8, v3
	v_lshl_or_b32 v0, v0, 6, v3
	v_lshlrev_b32_e32 v3, 2, v8
	v_and_b32_e32 v3, 32, v3
	v_bitop3_b32 v159, v0, s52, v3 bitop3:0xde
	v_lshlrev_b32_e32 v0, 14, v9
	v_and_b32_e32 v0, 0xffff8000, v0
	v_or_b32_e32 v160, s53, v1
	v_lshl_add_u32 v0, v10, 11, v0
	v_and_b32_e32 v1, 1, v9
	s_cmpk_lt_u32 s80, 0x100
	v_lshl_or_b32 v0, v1, 6, v0
	s_cselect_b64 s[8:9], -1, 0
	s_add_u32 s10, s92, 0x1f400000
	v_lshl_add_u32 v136, v11, 1, v0
	v_lshlrev_b32_e32 v0, 14, v12
	v_lshlrev_b32_e32 v4, 2, v158
	s_addc_u32 s11, s93, 0
	v_and_b32_e32 v0, 0xffff8000, v0
	v_readlane_b32 s13, v255, 2
	v_and_b32_e32 v4, 32, v4
	s_mov_b32 s52, s12
	s_waitcnt vmcnt(6)
	s_add_u32 s12, s92, 0xb400000
	v_lshl_add_u32 v0, v13, 11, v0
	v_and_b32_e32 v1, 1, v12
	v_bitop3_b32 v2, v2, s54, v4 bitop3:0xde
	s_addc_u32 s13, s93, 0
	v_lshl_or_b32 v0, v1, 6, v0
	s_add_i32 s53, 0, 0x10000
	s_add_i32 s54, 0, 0x14000
	v_mov_b32_e32 v137, v131
	v_lshl_add_u32 v138, v14, 1, v0
	v_mov_b32_e32 v139, v131
	v_add_u32_e32 v161, s53, v159
	v_add_u32_e32 v162, s54, v159
	v_add_u32_e32 v163, 0, v2
	s_mov_b32 s14, 0x437f0000
	s_mov_b32 s55, 0xb400000
	v_mov_b64_e32 v[140:141], 0x3ff
	s_barrier
	s_branch .LBB0_720

;     __device__ bool next(int i, Unit& u) const { if (r0 + i >= r1) return false; return base.next(r0 + i, u); }
;     __device__ bool next(int i, Unit& u) const { const int L = i * G + c; if (L >= 256) return false; u.pm = L; u.pn = L >> 3; return true; }
; #define PG8_STAGE(bufoff, gbase, voff) do { _Pragma("unroll") for (int _i = 0; _i < 2; ++_i) \
;         __builtin_amdgcn_global_load_lds((const unsigned*)((const char*)(gbase) + (voff)[_i]), (LAS unsigned*)(lds + (bufoff) + ldsw + _i * 8192), 16, 0, 0); } while (0)
; #define PG8_LDA(dst, b, h) do { _Pragma("unroll") for (int m = 0; m < 4; ++m) _Pragma("unroll") for (int k = 0; k < 2; ++k) dst[m][k] = *(const LAS bf16x8*)(lds + PG8_SA(b, h) + aoff + m * 2048 + k * 1024); } while (0)
; #define PG8_LDB(dst, b, h) do { _Pragma("unroll") for (int n = 0; n < 2; ++n) _Pragma("unroll") for (int k = 0; k < 2; ++k) dst[n][k] = *(const LAS bf16x8*)(lds + PG8_SB(b, h) + boff + n * 2048 + k * 1024); } while (0)
; #define PG8_WAIT_V(n) asm volatile("s_waitcnt vmcnt(" #n ")" ::: "memory")
; #define PG8_WAIT_L(n) asm volatile("s_waitcnt lgkmcnt(" #n ")" ::: "memory")
; template <class Epi, class Sched>
; __device__ __forceinline__ void gemm_phase(LAS unsigned char* lds, const Gemm g, const Sched& S, const Epi& E, int wave_id) {
;     ...
;         const bool has_next = S.next(ui + 1, nxt);
;         const char* nA = has_next ? (const char*)g.A + (size_t)nxt.pm * tstepA : cA; const char* nB = has_next ? (const char*)g.Bt + (size_t)nxt.pn * tstepB : cB;
;         for (int t = 0; t < nt; t += 2) {
;             const bool last = (t == nt - 2);
;             const char* a1 = cA + (size_t)(t + 1) * kstep;
;             const char* a2 = last ? nA : cA + (size_t)(t + 2) * kstep; const char* b2 = last ? nB : cB + (size_t)(t + 2) * kstep;
;             const char* a3 = a2 + kstep; const char* b3 = b2 + kstep;
;             PG8_LDB(B0, 0, 0); PG8_LDB(B1, 0, 1); PG8_SCHED; PG8_LDA(At, 0, 0); PG8_STAGE(PG8_SA(1, 1), a1 + hstepA, voffA);
;             PG8_WAIT_V(8); PG8_WAIT_L(0); PG8_BAR; PG8_MMA(0, 0, At, B0); PG8_MMA(0, 1, At, B1); PG8_BAR; PG8_SCHED;
;             PG8_LDA(At, 0, 1); PG8_STAGE(PG8_SB(0, 0), b2, voffB); PG8_STAGE(PG8_SB(0, 1), b2 + hstepB, voffB); PG8_STAGE(PG8_SA(0, 0), a2, voffA);
;             PG8_WAIT_V(8); PG8_WAIT_L(0); PG8_BAR; PG8_MMA(1, 0, At, B0); PG8_MMA(1, 1, At, B1); PG8_BAR; PG8_SCHED;
.LBB0_727:
	s_ashr_i32 s21, s20, 31
	s_lshl_b64 s[24:25], s[20:21], 19
	s_add_u32 s24, s15, s24
	s_addc_u32 s25, s33, s25
	s_and_b64 s[26:27], s[22:23], exec
	s_cselect_b32 s21, s25, s31
	s_cselect_b32 s59, s24, s30
	s_ashr_i32 s17, s16, 31
	s_lshl_b64 s[26:27], s[16:17], 19
	s_add_u32 s26, s38, s26
	s_addc_u32 s27, s39, s27
	s_and_b64 s[36:37], s[22:23], exec
	s_cselect_b32 s17, s27, s35
	s_cselect_b32 s60, s26, s34
	s_add_u32 s30, s30, 0x40080
	s_addc_u32 s31, s31, 0
	s_add_u32 s61, s34, 0x100
	s_addc_u32 s62, s35, 0
	s_mov_b32 s63, -2
	s_waitcnt vmcnt(0)
	ds_read_b128 v[142:145], v161
	ds_read_b128 v[146:149], v161 offset:1024
	ds_read_b128 v[150:153], v161 offset:2048
	ds_read_b128 v[154:157], v161 offset:3072
	ds_read_b128 v[164:167], v162
	ds_read_b128 v[168:171], v162 offset:1024
	ds_read_b128 v[172:175], v162 offset:2048
	ds_read_b128 v[176:179], v162 offset:3072
	s_add_u32 s34, s30, 0xfffc0080
	s_addc_u32 s35, s31, -1
	s_cmp_eq_u32 s63, 12
	s_cselect_b32 s37, s21, s35
	s_cselect_b32 s36, s59, s34
	s_cselect_b32 s35, s17, s62
	s_cselect_b32 s34, s60, s61
	s_add_i32 m0, s29, 0xc000
	ds_read_b128 v[180:183], v163
	ds_read_b128 v[184:187], v163 offset:1024
	ds_read_b128 v[188:191], v163 offset:2048
	ds_read_b128 v[192:195], v163 offset:3072
	ds_read_b128 v[196:199], v163 offset:4096
	ds_read_b128 v[200:203], v163 offset:5120
	ds_read_b128 v[204:207], v163 offset:6144
	ds_read_b128 v[208:211], v163 offset:7168
	global_load_lds_dwordx4 v136, s[30:31]
	s_add_i32 m0, s29, 0xe000
	s_nop 0
	global_load_lds_dwordx4 v138, s[30:31]
	s_waitcnt vmcnt(8)
	s_waitcnt lgkmcnt(0)
	s_barrier
	s_setprio 1
	s_waitcnt lgkmcnt(0)
	v_mfma_f32_16x16x32_bf16 v[124:127], v[142:145], v[180:183], 0
	v_mfma_f32_16x16x32_bf16 v[120:123], v[150:153], v[180:183], 0
	v_mfma_f32_16x16x32_bf16 v[108:111], v[142:145], v[188:191], 0
	v_mfma_f32_16x16x32_bf16 v[104:107], v[150:153], v[188:191], 0
	v_mfma_f32_16x16x32_bf16 v[92:95], v[142:145], v[196:199], 0
	v_mfma_f32_16x16x32_bf16 v[88:91], v[150:153], v[196:199], 0
	v_mfma_f32_16x16x32_bf16 v[76:79], v[142:145], v[204:207], 0
	v_mfma_f32_16x16x32_bf16 v[72:75], v[150:153], v[204:207], 0
	v_mfma_f32_16x16x32_bf16 v[124:127], v[146:149], v[184:187], v[124:127]
	v_mfma_f32_16x16x32_bf16 v[120:123], v[154:157], v[184:187], v[120:123]
	v_mfma_f32_16x16x32_bf16 v[108:111], v[146:149], v[192:195], v[108:111]
	v_mfma_f32_16x16x32_bf16 v[104:107], v[154:157], v[192:195], v[104:107]
	v_mfma_f32_16x16x32_bf16 v[92:95], v[146:149], v[200:203], v[92:95]
	v_mfma_f32_16x16x32_bf16 v[88:91], v[154:157], v[200:203], v[88:91]
	v_mfma_f32_16x16x32_bf16 v[76:79], v[146:149], v[208:211], v[76:79]
	v_mfma_f32_16x16x32_bf16 v[72:75], v[154:157], v[208:211], v[72:75]
	s_setprio 0
	s_setprio 1
	v_mfma_f32_16x16x32_bf16 v[116:119], v[164:167], v[180:183], 0
	v_mfma_f32_16x16x32_bf16 v[112:115], v[172:175], v[180:183], 0
	v_mfma_f32_16x16x32_bf16 v[100:103], v[164:167], v[188:191], 0
	v_mfma_f32_16x16x32_bf16 v[96:99], v[172:175], v[188:191], 0
	v_mfma_f32_16x16x32_bf16 v[84:87], v[164:167], v[196:199], 0
	v_mfma_f32_16x16x32_bf16 v[80:83], v[172:175], v[196:199], 0
	v_mfma_f32_16x16x32_bf16 v[68:71], v[164:167], v[204:207], 0
	v_mfma_f32_16x16x32_bf16 v[64:67], v[172:175], v[204:207], 0
	v_mfma_f32_16x16x32_bf16 v[116:119], v[168:171], v[184:187], v[116:119]
	v_mfma_f32_16x16x32_bf16 v[112:115], v[176:179], v[184:187], v[112:115]
	v_mfma_f32_16x16x32_bf16 v[100:103], v[168:171], v[192:195], v[100:103]
	v_mfma_f32_16x16x32_bf16 v[96:99], v[176:179], v[192:195], v[96:99]
	v_mfma_f32_16x16x32_bf16 v[84:87], v[168:171], v[200:203], v[84:87]
	v_mfma_f32_16x16x32_bf16 v[80:83], v[176:179], v[200:203], v[80:83]
	v_mfma_f32_16x16x32_bf16 v[68:71], v[168:171], v[208:211], v[68:71]
	v_mfma_f32_16x16x32_bf16 v[64:67], v[176:179], v[208:211], v[64:67]
	s_setprio 0
	s_barrier
	s_add_i32 s64, s53, s44
	v_lshl_add_u64 v[212:213], s[34:35], 0, v[130:131]
	s_mov_b32 m0, s64
	ds_read_b128 v[180:183], v163 offset:16384
	ds_read_b128 v[184:187], v163 offset:17408
	ds_read_b128 v[188:191], v163 offset:18432
	ds_read_b128 v[192:195], v163 offset:19456
	ds_read_b128 v[196:199], v163 offset:20480
	ds_read_b128 v[200:203], v163 offset:21504
	ds_read_b128 v[204:207], v163 offset:22528
	ds_read_b128 v[208:211], v163 offset:23552
	global_load_lds_dwordx4 v[212:213], off
	s_add_i32 m0, s64, 0x2000
	s_add_u32 s64, s34, 0x40000
	v_lshl_add_u64 v[214:215], s[34:35], 0, v[134:135]
	s_addc_u32 s65, s35, 0
	s_add_i32 s66, s54, s44
	global_load_lds_dwordx4 v[214:215], off
	s_mov_b32 m0, s66
	v_lshl_add_u64 v[218:219], s[36:37], 0, v[132:133]
	global_load_lds_dwordx4 v130, s[64:65]
	s_add_i32 m0, s66, 0x2000
	s_nop 0
	global_load_lds_dwordx4 v134, s[64:65]
	v_lshl_add_u64 v[216:217], s[36:37], 0, v[128:129]
	s_mov_b32 m0, s29
	s_nop 0
	global_load_lds_dwordx4 v[216:217], off
	s_mov_b32 m0, s45
	s_nop 0
	global_load_lds_dwordx4 v[218:219], off
	s_waitcnt vmcnt(8)
	s_waitcnt lgkmcnt(0)
	s_barrier
; #define PG8_STAGE(bufoff, gbase, voff) do { _Pragma("unroll") for (int _i = 0; _i < 2; ++_i) \
;         __builtin_amdgcn_global_load_lds((const unsigned*)((const char*)(gbase) + (voff)[_i]), (LAS unsigned*)(lds + (bufoff) + ldsw + _i * 8192), 16, 0, 0); } while (0)
; #define PG8_LDA(dst, b, h) do { _Pragma("unroll") for (int m = 0; m < 4; ++m) _Pragma("unroll") for (int k = 0; k < 2; ++k) dst[m][k] = *(const LAS bf16x8*)(lds + PG8_SA(b, h) + aoff + m * 2048 + k * 1024); } while (0)
; #define PG8_LDB(dst, b, h) do { _Pragma("unroll") for (int n = 0; n < 2; ++n) _Pragma("unroll") for (int k = 0; k < 2; ++k) dst[n][k] = *(const LAS bf16x8*)(lds + PG8_SB(b, h) + boff + n * 2048 + k * 1024); } while (0)
; #define PG8_MMA(ai, bj, At, Bt) do { __builtin_amdgcn_s_setprio(1); _Pragma("unroll") for (int m = 0; m < 4; ++m) _Pragma("unroll") for (int n = 0; n < 2; ++n) _Pragma("unroll") for (int k = 0; k < 2; ++k) \
;         acc[ai][bj][m][n] = __builtin_amdgcn_mfma_f32_16x16x32_bf16(Bt[n][k], At[m][k], acc[ai][bj][m][n], 0, 0, 0); __builtin_amdgcn_s_setprio(0); } while (0)
; #define PG8_WAIT_V(n) asm volatile("s_waitcnt vmcnt(" #n ")" ::: "memory")
; #define PG8_WAIT_L(n) asm volatile("s_waitcnt lgkmcnt(" #n ")" ::: "memory")
; #define PG8_BAR __builtin_amdgcn_s_barrier()
; #define PG8_SCHED __builtin_amdgcn_sched_barrier(0)
; template <class Epi, class Sched>
; __device__ __forceinline__ void gemm_phase(LAS unsigned char* lds, const Gemm g, const Sched& S, const Epi& E, int wave_id) {
;     ...
;             PG8_WAIT_V(8); PG8_WAIT_L(0); PG8_BAR; PG8_MMA(1, 0, At, B0); PG8_MMA(1, 1, At, B1); PG8_BAR; PG8_SCHED;
;             PG8_LDB(B0, 1, 0); PG8_LDB(B1, 1, 1); PG8_SCHED; PG8_LDA(At, 1, 0); PG8_STAGE(PG8_SA(0, 1), a2 + hstepA, voffA);
;             PG8_WAIT_V(8); PG8_WAIT_L(0); PG8_BAR; PG8_MMA(0, 0, At, B0); PG8_MMA(0, 1, At, B1); PG8_BAR; PG8_SCHED;
	s_setprio 1
	s_waitcnt lgkmcnt(0)
	v_mfma_f32_16x16x32_bf16 v[60:63], v[142:145], v[180:183], 0
	v_mfma_f32_16x16x32_bf16 v[56:59], v[150:153], v[180:183], 0
	v_mfma_f32_16x16x32_bf16 v[44:47], v[142:145], v[188:191], 0
	v_mfma_f32_16x16x32_bf16 v[40:43], v[150:153], v[188:191], 0
	v_mfma_f32_16x16x32_bf16 v[28:31], v[142:145], v[196:199], 0
	v_mfma_f32_16x16x32_bf16 v[24:27], v[150:153], v[196:199], 0
	v_mfma_f32_16x16x32_bf16 v[12:15], v[142:145], v[204:207], 0
	v_mfma_f32_16x16x32_bf16 v[8:11], v[150:153], v[204:207], 0
	v_mfma_f32_16x16x32_bf16 v[60:63], v[146:149], v[184:187], v[60:63]
	v_mfma_f32_16x16x32_bf16 v[56:59], v[154:157], v[184:187], v[56:59]
	v_mfma_f32_16x16x32_bf16 v[44:47], v[146:149], v[192:195], v[44:47]
	v_mfma_f32_16x16x32_bf16 v[40:43], v[154:157], v[192:195], v[40:43]
	v_mfma_f32_16x16x32_bf16 v[28:31], v[146:149], v[200:203], v[28:31]
	v_mfma_f32_16x16x32_bf16 v[24:27], v[154:157], v[200:203], v[24:27]
	v_mfma_f32_16x16x32_bf16 v[12:15], v[146:149], v[208:211], v[12:15]
	v_mfma_f32_16x16x32_bf16 v[8:11], v[154:157], v[208:211], v[8:11]
	s_setprio 0
	s_setprio 1
	v_mfma_f32_16x16x32_bf16 v[52:55], v[164:167], v[180:183], 0
	v_mfma_f32_16x16x32_bf16 v[48:51], v[172:175], v[180:183], 0
	v_mfma_f32_16x16x32_bf16 v[36:39], v[164:167], v[188:191], 0
	v_mfma_f32_16x16x32_bf16 v[32:35], v[172:175], v[188:191], 0
	v_mfma_f32_16x16x32_bf16 v[20:23], v[164:167], v[196:199], 0
	v_mfma_f32_16x16x32_bf16 v[16:19], v[172:175], v[196:199], 0
	v_mfma_f32_16x16x32_bf16 v[4:7], v[164:167], v[204:207], 0
	v_mfma_f32_16x16x32_bf16 v[0:3], v[172:175], v[204:207], 0
	v_mfma_f32_16x16x32_bf16 v[52:55], v[168:171], v[184:187], v[52:55]
	v_mfma_f32_16x16x32_bf16 v[48:51], v[176:179], v[184:187], v[48:51]
	v_mfma_f32_16x16x32_bf16 v[36:39], v[168:171], v[192:195], v[36:39]
	v_mfma_f32_16x16x32_bf16 v[32:35], v[176:179], v[192:195], v[32:35]
	v_mfma_f32_16x16x32_bf16 v[20:23], v[168:171], v[200:203], v[20:23]
	v_mfma_f32_16x16x32_bf16 v[16:19], v[176:179], v[200:203], v[16:19]
	v_mfma_f32_16x16x32_bf16 v[4:7], v[168:171], v[208:211], v[4:7]
	v_mfma_f32_16x16x32_bf16 v[0:3], v[176:179], v[208:211], v[0:3]
	s_setprio 0
	s_barrier
	s_add_i32 s64, 0, 0x18000
	s_add_i32 s65, 0, 0x1c000
	v_add_u32_e32 v154, s64, v159
	v_add_u32_e32 v176, s65, v159
	ds_read_b128 v[142:145], v154
	ds_read_b128 v[146:149], v154 offset:1024
	ds_read_b128 v[150:153], v154 offset:2048
	ds_read_b128 v[154:157], v154 offset:3072
	ds_read_b128 v[164:167], v176
	ds_read_b128 v[168:171], v176 offset:1024
	ds_read_b128 v[172:175], v176 offset:2048
	ds_read_b128 v[176:179], v176 offset:3072
	s_add_u32 s36, s36, 0x40000
	s_addc_u32 s37, s37, 0
	s_mov_b32 m0, s46
	ds_read_b128 v[180:183], v163 offset:32768
	ds_read_b128 v[184:187], v163 offset:33792
	ds_read_b128 v[188:191], v163 offset:34816
	ds_read_b128 v[192:195], v163 offset:35840
	ds_read_b128 v[196:199], v163 offset:36864
	ds_read_b128 v[200:203], v163 offset:37888
	ds_read_b128 v[204:207], v163 offset:38912
	ds_read_b128 v[208:211], v163 offset:39936
	global_load_lds_dwordx4 v128, s[36:37]
	s_mov_b32 m0, s47
	s_nop 0
	global_load_lds_dwordx4 v132, s[36:37]
	s_waitcnt vmcnt(8)
	s_waitcnt lgkmcnt(0)
	s_barrier
	s_setprio 1
	s_waitcnt lgkmcnt(0)
	v_mfma_f32_16x16x32_bf16 v[124:127], v[142:145], v[180:183], v[124:127]
	v_mfma_f32_16x16x32_bf16 v[120:123], v[150:153], v[180:183], v[120:123]
	v_mfma_f32_16x16x32_bf16 v[108:111], v[142:145], v[188:191], v[108:111]
	v_mfma_f32_16x16x32_bf16 v[104:107], v[150:153], v[188:191], v[104:107]
	v_mfma_f32_16x16x32_bf16 v[92:95], v[142:145], v[196:199], v[92:95]
	v_mfma_f32_16x16x32_bf16 v[88:91], v[150:153], v[196:199], v[88:91]
	v_mfma_f32_16x16x32_bf16 v[76:79], v[142:145], v[204:207], v[76:79]
	v_mfma_f32_16x16x32_bf16 v[72:75], v[150:153], v[204:207], v[72:75]
	v_mfma_f32_16x16x32_bf16 v[124:127], v[146:149], v[184:187], v[124:127]
	v_mfma_f32_16x16x32_bf16 v[120:123], v[154:157], v[184:187], v[120:123]
	v_mfma_f32_16x16x32_bf16 v[108:111], v[146:149], v[192:195], v[108:111]
	v_mfma_f32_16x16x32_bf16 v[104:107], v[154:157], v[192:195], v[104:107]
	v_mfma_f32_16x16x32_bf16 v[92:95], v[146:149], v[200:203], v[92:95]
	v_mfma_f32_16x16x32_bf16 v[88:91], v[154:157], v[200:203], v[88:91]
	v_mfma_f32_16x16x32_bf16 v[76:79], v[146:149], v[208:211], v[76:79]
	v_mfma_f32_16x16x32_bf16 v[72:75], v[154:157], v[208:211], v[72:75]
	s_setprio 0
	s_setprio 1
	v_mfma_f32_16x16x32_bf16 v[116:119], v[164:167], v[180:183], v[116:119]
	v_mfma_f32_16x16x32_bf16 v[112:115], v[172:175], v[180:183], v[112:115]
	v_mfma_f32_16x16x32_bf16 v[100:103], v[164:167], v[188:191], v[100:103]
	v_mfma_f32_16x16x32_bf16 v[96:99], v[172:175], v[188:191], v[96:99]
	v_mfma_f32_16x16x32_bf16 v[84:87], v[164:167], v[196:199], v[84:87]
	v_mfma_f32_16x16x32_bf16 v[80:83], v[172:175], v[196:199], v[80:83]
	v_mfma_f32_16x16x32_bf16 v[68:71], v[164:167], v[204:207], v[68:71]
	v_mfma_f32_16x16x32_bf16 v[64:67], v[172:175], v[204:207], v[64:67]
	v_mfma_f32_16x16x32_bf16 v[116:119], v[168:171], v[184:187], v[116:119]
	v_mfma_f32_16x16x32_bf16 v[112:115], v[176:179], v[184:187], v[112:115]
	v_mfma_f32_16x16x32_bf16 v[100:103], v[168:171], v[192:195], v[100:103]
	v_mfma_f32_16x16x32_bf16 v[96:99], v[176:179], v[192:195], v[96:99]
	v_mfma_f32_16x16x32_bf16 v[84:87], v[168:171], v[200:203], v[84:87]
	v_mfma_f32_16x16x32_bf16 v[80:83], v[176:179], v[200:203], v[80:83]
	v_mfma_f32_16x16x32_bf16 v[68:71], v[168:171], v[208:211], v[68:71]
	v_mfma_f32_16x16x32_bf16 v[64:67], v[176:179], v[208:211], v[64:67]
	s_setprio 0
	s_barrier
; #define PG8_STAGE(bufoff, gbase, voff) do { _Pragma("unroll") for (int _i = 0; _i < 2; ++_i) \
;         __builtin_amdgcn_global_load_lds((const unsigned*)((const char*)(gbase) + (voff)[_i]), (LAS unsigned*)(lds + (bufoff) + ldsw + _i * 8192), 16, 0, 0); } while (0)
; #define PG8_LDA(dst, b, h) do { _Pragma("unroll") for (int m = 0; m < 4; ++m) _Pragma("unroll") for (int k = 0; k < 2; ++k) dst[m][k] = *(const LAS bf16x8*)(lds + PG8_SA(b, h) + aoff + m * 2048 + k * 1024); } while (0)
; #define PG8_LDB(dst, b, h) do { _Pragma("unroll") for (int n = 0; n < 2; ++n) _Pragma("unroll") for (int k = 0; k < 2; ++k) dst[n][k] = *(const LAS bf16x8*)(lds + PG8_SB(b, h) + boff + n * 2048 + k * 1024); } while (0)
; #define PG8_MMA(ai, bj, At, Bt) do { __builtin_amdgcn_s_setprio(1); _Pragma("unroll") for (int m = 0; m < 4; ++m) _Pragma("unroll") for (int n = 0; n < 2; ++n) _Pragma("unroll") for (int k = 0; k < 2; ++k) \
;         acc[ai][bj][m][n] = __builtin_amdgcn_mfma_f32_16x16x32_bf16(Bt[n][k], At[m][k], acc[ai][bj][m][n], 0, 0, 0); __builtin_amdgcn_s_setprio(0); } while (0)
; #define PG8_WAIT_V(n) asm volatile("s_waitcnt vmcnt(" #n ")" ::: "memory")
; #define PG8_WAIT_L(n) asm volatile("s_waitcnt lgkmcnt(" #n ")" ::: "memory")
; #define PG8_BAR __builtin_amdgcn_s_barrier()
; #define PG8_SCHED __builtin_amdgcn_sched_barrier(0)
; template <class Epi, class Sched>
; __device__ __forceinline__ void gemm_phase(LAS unsigned char* lds, const Gemm g, const Sched& S, const Epi& E, int wave_id) {
;     ...
;             PG8_LDB(B0, 0, 0); PG8_LDB(B1, 0, 1); PG8_SCHED; PG8_LDA(At, 0, 0); PG8_STAGE(PG8_SA(1, 1), a1 + hstepA, voffA);
;             PG8_WAIT_V(8); PG8_WAIT_L(0); PG8_BAR; PG8_MMA(0, 0, At, B0); PG8_MMA(0, 1, At, B1); PG8_BAR; PG8_SCHED;
;     ...
;             PG8_WAIT_V(8); PG8_WAIT_L(0); PG8_BAR; PG8_MMA(0, 0, At, B0); PG8_MMA(0, 1, At, B1); PG8_BAR; PG8_SCHED;
;             PG8_LDA(At, 1, 1); PG8_STAGE(PG8_SB(1, 0), b3, voffB); PG8_STAGE(PG8_SB(1, 1), b3 + hstepB, voffB); PG8_STAGE(PG8_SA(1, 0), a3, voffA);
;             PG8_WAIT_V(8); PG8_WAIT_L(0); PG8_BAR; PG8_MMA(1, 0, At, B0); PG8_MMA(1, 1, At, B1); PG8_BAR; PG8_SCHED;
	s_add_i32 s36, s64, s44
	v_lshl_add_u64 v[212:213], v[212:213], 0, s[6:7]
	s_mov_b32 m0, s36
	ds_read_b128 v[180:183], v163 offset:49152
	ds_read_b128 v[184:187], v163 offset:50176
	ds_read_b128 v[188:191], v163 offset:51200
	ds_read_b128 v[192:195], v163 offset:52224
	ds_read_b128 v[196:199], v163 offset:53248
	ds_read_b128 v[200:203], v163 offset:54272
	ds_read_b128 v[204:207], v163 offset:55296
	ds_read_b128 v[208:211], v163 offset:56320
	global_load_lds_dwordx4 v[212:213], off
	s_add_i32 m0, s36, 0x2000
	s_add_u32 s34, s34, 0x40080
	v_lshl_add_u64 v[212:213], v[214:215], 0, s[6:7]
	s_addc_u32 s35, s35, 0
	s_add_i32 s36, s65, s44
	global_load_lds_dwordx4 v[212:213], off
	s_mov_b32 m0, s36
	s_nop 0
	global_load_lds_dwordx4 v130, s[34:35]
	s_add_i32 m0, s36, 0x2000
	s_nop 0
	global_load_lds_dwordx4 v134, s[34:35]
	v_lshl_add_u64 v[212:213], v[216:217], 0, s[6:7]
	s_mov_b32 m0, s50
	s_nop 0
	global_load_lds_dwordx4 v[212:213], off
	v_lshl_add_u64 v[212:213], v[218:219], 0, s[6:7]
	s_mov_b32 m0, s51
	s_nop 0
	global_load_lds_dwordx4 v[212:213], off
	s_waitcnt vmcnt(8)
	s_waitcnt lgkmcnt(0)
	s_barrier
	s_setprio 1
	s_waitcnt lgkmcnt(0)
	v_mfma_f32_16x16x32_bf16 v[60:63], v[142:145], v[180:183], v[60:63]
	v_mfma_f32_16x16x32_bf16 v[56:59], v[150:153], v[180:183], v[56:59]
	v_mfma_f32_16x16x32_bf16 v[44:47], v[142:145], v[188:191], v[44:47]
	v_mfma_f32_16x16x32_bf16 v[40:43], v[150:153], v[188:191], v[40:43]
	v_mfma_f32_16x16x32_bf16 v[28:31], v[142:145], v[196:199], v[28:31]
	v_mfma_f32_16x16x32_bf16 v[24:27], v[150:153], v[196:199], v[24:27]
	v_mfma_f32_16x16x32_bf16 v[12:15], v[142:145], v[204:207], v[12:15]
	v_mfma_f32_16x16x32_bf16 v[8:11], v[150:153], v[204:207], v[8:11]
	v_mfma_f32_16x16x32_bf16 v[60:63], v[146:149], v[184:187], v[60:63]
	v_mfma_f32_16x16x32_bf16 v[56:59], v[154:157], v[184:187], v[56:59]
	v_mfma_f32_16x16x32_bf16 v[44:47], v[146:149], v[192:195], v[44:47]
	v_mfma_f32_16x16x32_bf16 v[40:43], v[154:157], v[192:195], v[40:43]
	v_mfma_f32_16x16x32_bf16 v[28:31], v[146:149], v[200:203], v[28:31]
	v_mfma_f32_16x16x32_bf16 v[24:27], v[154:157], v[200:203], v[24:27]
	v_mfma_f32_16x16x32_bf16 v[12:15], v[146:149], v[208:211], v[12:15]
	v_mfma_f32_16x16x32_bf16 v[8:11], v[154:157], v[208:211], v[8:11]
	s_setprio 0
	s_setprio 1
	v_mfma_f32_16x16x32_bf16 v[52:55], v[164:167], v[180:183], v[52:55]
	v_mfma_f32_16x16x32_bf16 v[48:51], v[172:175], v[180:183], v[48:51]
	v_mfma_f32_16x16x32_bf16 v[36:39], v[164:167], v[188:191], v[36:39]
	v_mfma_f32_16x16x32_bf16 v[32:35], v[172:175], v[188:191], v[32:35]
	v_mfma_f32_16x16x32_bf16 v[20:23], v[164:167], v[196:199], v[20:23]
	v_mfma_f32_16x16x32_bf16 v[16:19], v[172:175], v[196:199], v[16:19]
	v_mfma_f32_16x16x32_bf16 v[4:7], v[164:167], v[204:207], v[4:7]
	v_mfma_f32_16x16x32_bf16 v[0:3], v[172:175], v[204:207], v[0:3]
	v_mfma_f32_16x16x32_bf16 v[52:55], v[168:171], v[184:187], v[52:55]
	v_mfma_f32_16x16x32_bf16 v[48:51], v[176:179], v[184:187], v[48:51]
	v_mfma_f32_16x16x32_bf16 v[36:39], v[168:171], v[192:195], v[36:39]
	v_mfma_f32_16x16x32_bf16 v[32:35], v[176:179], v[192:195], v[32:35]
	v_mfma_f32_16x16x32_bf16 v[20:23], v[168:171], v[200:203], v[20:23]
	v_mfma_f32_16x16x32_bf16 v[16:19], v[176:179], v[200:203], v[16:19]
	v_mfma_f32_16x16x32_bf16 v[4:7], v[168:171], v[208:211], v[4:7]
	v_mfma_f32_16x16x32_bf16 v[0:3], v[176:179], v[208:211], v[0:3]
	s_setprio 0
	s_barrier
	s_add_i32 s63, s63, 2
	s_add_u32 s30, s30, 0x100
	s_addc_u32 s31, s31, 0
	s_add_u32 s61, s61, 0x100
	s_addc_u32 s62, s62, 0
	s_cmp_gt_u32 s63, 13
.LBB0_728:
	ds_read_b128 v[142:145], v161
	ds_read_b128 v[146:149], v161 offset:1024
	ds_read_b128 v[150:153], v161 offset:2048
	ds_read_b128 v[154:157], v161 offset:3072
	ds_read_b128 v[164:167], v162
	ds_read_b128 v[168:171], v162 offset:1024
	ds_read_b128 v[172:175], v162 offset:2048
	ds_read_b128 v[176:179], v162 offset:3072
	s_add_u32 s34, s30, 0xfffc0080
	s_addc_u32 s35, s31, -1
	s_cmp_eq_u32 s63, 12
	s_cselect_b32 s37, s21, s35
	s_cselect_b32 s36, s59, s34
	s_cselect_b32 s35, s17, s62
	s_cselect_b32 s34, s60, s61
	s_add_i32 m0, s29, 0xc000
	ds_read_b128 v[180:183], v163
	ds_read_b128 v[184:187], v163 offset:1024
	ds_read_b128 v[188:191], v163 offset:2048
	ds_read_b128 v[192:195], v163 offset:3072
	ds_read_b128 v[196:199], v163 offset:4096
	ds_read_b128 v[200:203], v163 offset:5120
	ds_read_b128 v[204:207], v163 offset:6144
	ds_read_b128 v[208:211], v163 offset:7168
	global_load_lds_dwordx4 v136, s[30:31]
	s_add_i32 m0, s29, 0xe000
	s_nop 0
	global_load_lds_dwordx4 v138, s[30:31]
	s_waitcnt vmcnt(8)
	s_waitcnt lgkmcnt(0)
	s_barrier
; #define PG8_STAGE(bufoff, gbase, voff) do { _Pragma("unroll") for (int _i = 0; _i < 2; ++_i) \
;         __builtin_amdgcn_global_load_lds((const unsigned*)((const char*)(gbase) + (voff)[_i]), (LAS unsigned*)(lds + (bufoff) + ldsw + _i * 8192), 16, 0, 0); } while (0)
; #define PG8_LDA(dst, b, h) do { _Pragma("unroll") for (int m = 0; m < 4; ++m) _Pragma("unroll") for (int k = 0; k < 2; ++k) dst[m][k] = *(const LAS bf16x8*)(lds + PG8_SA(b, h) + aoff + m * 2048 + k * 1024); } while (0)
; #define PG8_MMA(ai, bj, At, Bt) do { __builtin_amdgcn_s_setprio(1); _Pragma("unroll") for (int m = 0; m < 4; ++m) _Pragma("unroll") for (int n = 0; n < 2; ++n) _Pragma("unroll") for (int k = 0; k < 2; ++k) \
;         acc[ai][bj][m][n] = __builtin_amdgcn_mfma_f32_16x16x32_bf16(Bt[n][k], At[m][k], acc[ai][bj][m][n], 0, 0, 0); __builtin_amdgcn_s_setprio(0); } while (0)
; #define PG8_WAIT_V(n) asm volatile("s_waitcnt vmcnt(" #n ")" ::: "memory")
; #define PG8_WAIT_L(n) asm volatile("s_waitcnt lgkmcnt(" #n ")" ::: "memory")
; #define PG8_BAR __builtin_amdgcn_s_barrier()
; #define PG8_SCHED __builtin_amdgcn_sched_barrier(0)
; template <class Epi, class Sched>
; __device__ __forceinline__ void gemm_phase(LAS unsigned char* lds, const Gemm g, const Sched& S, const Epi& E, int wave_id) {
;     ...
;             PG8_WAIT_V(8); PG8_WAIT_L(0); PG8_BAR; PG8_MMA(0, 0, At, B0); PG8_MMA(0, 1, At, B1); PG8_BAR; PG8_SCHED;
;             PG8_LDA(At, 0, 1); PG8_STAGE(PG8_SB(0, 0), b2, voffB); PG8_STAGE(PG8_SB(0, 1), b2 + hstepB, voffB); PG8_STAGE(PG8_SA(0, 0), a2, voffA);
;             PG8_WAIT_V(8); PG8_WAIT_L(0); PG8_BAR; PG8_MMA(1, 0, At, B0); PG8_MMA(1, 1, At, B1); PG8_BAR; PG8_SCHED;
	s_setprio 1
	s_waitcnt lgkmcnt(0)
	v_mfma_f32_16x16x32_bf16 v[124:127], v[142:145], v[180:183], v[124:127]
	v_mfma_f32_16x16x32_bf16 v[120:123], v[150:153], v[180:183], v[120:123]
	v_mfma_f32_16x16x32_bf16 v[108:111], v[142:145], v[188:191], v[108:111]
	v_mfma_f32_16x16x32_bf16 v[104:107], v[150:153], v[188:191], v[104:107]
	v_mfma_f32_16x16x32_bf16 v[92:95], v[142:145], v[196:199], v[92:95]
	v_mfma_f32_16x16x32_bf16 v[88:91], v[150:153], v[196:199], v[88:91]
	v_mfma_f32_16x16x32_bf16 v[76:79], v[142:145], v[204:207], v[76:79]
	v_mfma_f32_16x16x32_bf16 v[72:75], v[150:153], v[204:207], v[72:75]
	v_mfma_f32_16x16x32_bf16 v[124:127], v[146:149], v[184:187], v[124:127]
	v_mfma_f32_16x16x32_bf16 v[120:123], v[154:157], v[184:187], v[120:123]
	v_mfma_f32_16x16x32_bf16 v[108:111], v[146:149], v[192:195], v[108:111]
	v_mfma_f32_16x16x32_bf16 v[104:107], v[154:157], v[192:195], v[104:107]
	v_mfma_f32_16x16x32_bf16 v[92:95], v[146:149], v[200:203], v[92:95]
	v_mfma_f32_16x16x32_bf16 v[88:91], v[154:157], v[200:203], v[88:91]
	v_mfma_f32_16x16x32_bf16 v[76:79], v[146:149], v[208:211], v[76:79]
	v_mfma_f32_16x16x32_bf16 v[72:75], v[154:157], v[208:211], v[72:75]
	s_setprio 0
	s_setprio 1
	v_mfma_f32_16x16x32_bf16 v[116:119], v[164:167], v[180:183], v[116:119]
	v_mfma_f32_16x16x32_bf16 v[112:115], v[172:175], v[180:183], v[112:115]
	v_mfma_f32_16x16x32_bf16 v[100:103], v[164:167], v[188:191], v[100:103]
	v_mfma_f32_16x16x32_bf16 v[96:99], v[172:175], v[188:191], v[96:99]
	v_mfma_f32_16x16x32_bf16 v[84:87], v[164:167], v[196:199], v[84:87]
	v_mfma_f32_16x16x32_bf16 v[80:83], v[172:175], v[196:199], v[80:83]
	v_mfma_f32_16x16x32_bf16 v[68:71], v[164:167], v[204:207], v[68:71]
	v_mfma_f32_16x16x32_bf16 v[64:67], v[172:175], v[204:207], v[64:67]
	v_mfma_f32_16x16x32_bf16 v[116:119], v[168:171], v[184:187], v[116:119]
	v_mfma_f32_16x16x32_bf16 v[112:115], v[176:179], v[184:187], v[112:115]
	v_mfma_f32_16x16x32_bf16 v[100:103], v[168:171], v[192:195], v[100:103]
	v_mfma_f32_16x16x32_bf16 v[96:99], v[176:179], v[192:195], v[96:99]
	v_mfma_f32_16x16x32_bf16 v[84:87], v[168:171], v[200:203], v[84:87]
	v_mfma_f32_16x16x32_bf16 v[80:83], v[176:179], v[200:203], v[80:83]
	v_mfma_f32_16x16x32_bf16 v[68:71], v[168:171], v[208:211], v[68:71]
	v_mfma_f32_16x16x32_bf16 v[64:67], v[176:179], v[208:211], v[64:67]
	s_setprio 0
	s_barrier
	s_add_i32 s64, s53, s44
	v_lshl_add_u64 v[212:213], s[34:35], 0, v[130:131]
	s_mov_b32 m0, s64
	ds_read_b128 v[180:183], v163 offset:16384
	ds_read_b128 v[184:187], v163 offset:17408
	ds_read_b128 v[188:191], v163 offset:18432
	ds_read_b128 v[192:195], v163 offset:19456
	ds_read_b128 v[196:199], v163 offset:20480
	ds_read_b128 v[200:203], v163 offset:21504
	ds_read_b128 v[204:207], v163 offset:22528
	ds_read_b128 v[208:211], v163 offset:23552
	global_load_lds_dwordx4 v[212:213], off
	s_add_i32 m0, s64, 0x2000
	s_add_u32 s64, s34, 0x40000
	v_lshl_add_u64 v[214:215], s[34:35], 0, v[134:135]
	s_addc_u32 s65, s35, 0
	s_add_i32 s66, s54, s44
	global_load_lds_dwordx4 v[214:215], off
	s_mov_b32 m0, s66
	v_lshl_add_u64 v[218:219], s[36:37], 0, v[132:133]
	global_load_lds_dwordx4 v130, s[64:65]
	s_add_i32 m0, s66, 0x2000
	s_nop 0
	global_load_lds_dwordx4 v134, s[64:65]
	v_lshl_add_u64 v[216:217], s[36:37], 0, v[128:129]
	s_mov_b32 m0, s29
	s_nop 0
	global_load_lds_dwordx4 v[216:217], off
	s_mov_b32 m0, s45
	s_nop 0
	global_load_lds_dwordx4 v[218:219], off
	s_waitcnt vmcnt(8)
	s_waitcnt lgkmcnt(0)
	s_barrier
	s_setprio 1
	s_waitcnt lgkmcnt(0)
	v_mfma_f32_16x16x32_bf16 v[60:63], v[142:145], v[180:183], v[60:63]
	v_mfma_f32_16x16x32_bf16 v[56:59], v[150:153], v[180:183], v[56:59]
	v_mfma_f32_16x16x32_bf16 v[44:47], v[142:145], v[188:191], v[44:47]
	v_mfma_f32_16x16x32_bf16 v[40:43], v[150:153], v[188:191], v[40:43]
	v_mfma_f32_16x16x32_bf16 v[28:31], v[142:145], v[196:199], v[28:31]
	v_mfma_f32_16x16x32_bf16 v[24:27], v[150:153], v[196:199], v[24:27]
	v_mfma_f32_16x16x32_bf16 v[12:15], v[142:145], v[204:207], v[12:15]
	v_mfma_f32_16x16x32_bf16 v[8:11], v[150:153], v[204:207], v[8:11]
	v_mfma_f32_16x16x32_bf16 v[60:63], v[146:149], v[184:187], v[60:63]
	v_mfma_f32_16x16x32_bf16 v[56:59], v[154:157], v[184:187], v[56:59]
	v_mfma_f32_16x16x32_bf16 v[44:47], v[146:149], v[192:195], v[44:47]
	v_mfma_f32_16x16x32_bf16 v[40:43], v[154:157], v[192:195], v[40:43]
	v_mfma_f32_16x16x32_bf16 v[28:31], v[146:149], v[200:203], v[28:31]
	v_mfma_f32_16x16x32_bf16 v[24:27], v[154:157], v[200:203], v[24:27]
	v_mfma_f32_16x16x32_bf16 v[12:15], v[146:149], v[208:211], v[12:15]
	v_mfma_f32_16x16x32_bf16 v[8:11], v[154:157], v[208:211], v[8:11]
	s_setprio 0
	s_setprio 1
	v_mfma_f32_16x16x32_bf16 v[52:55], v[164:167], v[180:183], v[52:55]
	v_mfma_f32_16x16x32_bf16 v[48:51], v[172:175], v[180:183], v[48:51]
	v_mfma_f32_16x16x32_bf16 v[36:39], v[164:167], v[188:191], v[36:39]
	v_mfma_f32_16x16x32_bf16 v[32:35], v[172:175], v[188:191], v[32:35]
	v_mfma_f32_16x16x32_bf16 v[20:23], v[164:167], v[196:199], v[20:23]
	v_mfma_f32_16x16x32_bf16 v[16:19], v[172:175], v[196:199], v[16:19]
	v_mfma_f32_16x16x32_bf16 v[4:7], v[164:167], v[204:207], v[4:7]
	v_mfma_f32_16x16x32_bf16 v[0:3], v[172:175], v[204:207], v[0:3]
	v_mfma_f32_16x16x32_bf16 v[52:55], v[168:171], v[184:187], v[52:55]
	v_mfma_f32_16x16x32_bf16 v[48:51], v[176:179], v[184:187], v[48:51]
	v_mfma_f32_16x16x32_bf16 v[36:39], v[168:171], v[192:195], v[36:39]
	v_mfma_f32_16x16x32_bf16 v[32:35], v[176:179], v[192:195], v[32:35]
	v_mfma_f32_16x16x32_bf16 v[20:23], v[168:171], v[200:203], v[20:23]
	v_mfma_f32_16x16x32_bf16 v[16:19], v[176:179], v[200:203], v[16:19]
	v_mfma_f32_16x16x32_bf16 v[4:7], v[168:171], v[208:211], v[4:7]
	v_mfma_f32_16x16x32_bf16 v[0:3], v[176:179], v[208:211], v[0:3]
	s_setprio 0
	s_barrier
; #define PG8_STAGE(bufoff, gbase, voff) do { _Pragma("unroll") for (int _i = 0; _i < 2; ++_i) \
;         __builtin_amdgcn_global_load_lds((const unsigned*)((const char*)(gbase) + (voff)[_i]), (LAS unsigned*)(lds + (bufoff) + ldsw + _i * 8192), 16, 0, 0); } while (0)
; #define PG8_LDA(dst, b, h) do { _Pragma("unroll") for (int m = 0; m < 4; ++m) _Pragma("unroll") for (int k = 0; k < 2; ++k) dst[m][k] = *(const LAS bf16x8*)(lds + PG8_SA(b, h) + aoff + m * 2048 + k * 1024); } while (0)
; #define PG8_LDB(dst, b, h) do { _Pragma("unroll") for (int n = 0; n < 2; ++n) _Pragma("unroll") for (int k = 0; k < 2; ++k) dst[n][k] = *(const LAS bf16x8*)(lds + PG8_SB(b, h) + boff + n * 2048 + k * 1024); } while (0)
; #define PG8_MMA(ai, bj, At, Bt) do { __builtin_amdgcn_s_setprio(1); _Pragma("unroll") for (int m = 0; m < 4; ++m) _Pragma("unroll") for (int n = 0; n < 2; ++n) _Pragma("unroll") for (int k = 0; k < 2; ++k) \
;         acc[ai][bj][m][n] = __builtin_amdgcn_mfma_f32_16x16x32_bf16(Bt[n][k], At[m][k], acc[ai][bj][m][n], 0, 0, 0); __builtin_amdgcn_s_setprio(0); } while (0)
; #define PG8_WAIT_V(n) asm volatile("s_waitcnt vmcnt(" #n ")" ::: "memory")
; #define PG8_WAIT_L(n) asm volatile("s_waitcnt lgkmcnt(" #n ")" ::: "memory")
; #define PG8_BAR __builtin_amdgcn_s_barrier()
; #define PG8_SCHED __builtin_amdgcn_sched_barrier(0)
; template <class Epi, class Sched>
; __device__ __forceinline__ void gemm_phase(LAS unsigned char* lds, const Gemm g, const Sched& S, const Epi& E, int wave_id) {
;     ...
;             PG8_LDB(B0, 1, 0); PG8_LDB(B1, 1, 1); PG8_SCHED; PG8_LDA(At, 1, 0); PG8_STAGE(PG8_SA(0, 1), a2 + hstepA, voffA);
;             PG8_WAIT_V(8); PG8_WAIT_L(0); PG8_BAR; PG8_MMA(0, 0, At, B0); PG8_MMA(0, 1, At, B1); PG8_BAR; PG8_SCHED;
;             PG8_LDA(At, 1, 1); PG8_STAGE(PG8_SB(1, 0), b3, voffB); PG8_STAGE(PG8_SB(1, 1), b3 + hstepB, voffB); PG8_STAGE(PG8_SA(1, 0), a3, voffA);
;             PG8_WAIT_V(8); PG8_WAIT_L(0); PG8_BAR; PG8_MMA(1, 0, At, B0); PG8_MMA(1, 1, At, B1); PG8_BAR; PG8_SCHED;
;         }
;         if (wr == 0) PG8_BAR;
	s_add_i32 s64, 0, 0x18000
	s_add_i32 s65, 0, 0x1c000
	v_add_u32_e32 v154, s64, v159
	v_add_u32_e32 v176, s65, v159
	ds_read_b128 v[142:145], v154
	ds_read_b128 v[146:149], v154 offset:1024
	ds_read_b128 v[150:153], v154 offset:2048
	ds_read_b128 v[154:157], v154 offset:3072
	ds_read_b128 v[164:167], v176
	ds_read_b128 v[168:171], v176 offset:1024
	ds_read_b128 v[172:175], v176 offset:2048
	ds_read_b128 v[176:179], v176 offset:3072
	s_add_u32 s36, s36, 0x40000
	s_addc_u32 s37, s37, 0
	s_mov_b32 m0, s46
	ds_read_b128 v[180:183], v163 offset:32768
	ds_read_b128 v[184:187], v163 offset:33792
	ds_read_b128 v[188:191], v163 offset:34816
	ds_read_b128 v[192:195], v163 offset:35840
	ds_read_b128 v[196:199], v163 offset:36864
	ds_read_b128 v[200:203], v163 offset:37888
	ds_read_b128 v[204:207], v163 offset:38912
	ds_read_b128 v[208:211], v163 offset:39936
	global_load_lds_dwordx4 v128, s[36:37]
	s_mov_b32 m0, s47
	s_nop 0
	global_load_lds_dwordx4 v132, s[36:37]
	s_waitcnt vmcnt(8)
	s_waitcnt lgkmcnt(0)
	s_barrier
	s_setprio 1
	s_waitcnt lgkmcnt(0)
	v_mfma_f32_16x16x32_bf16 v[124:127], v[142:145], v[180:183], v[124:127]
	v_mfma_f32_16x16x32_bf16 v[120:123], v[150:153], v[180:183], v[120:123]
	v_mfma_f32_16x16x32_bf16 v[108:111], v[142:145], v[188:191], v[108:111]
	v_mfma_f32_16x16x32_bf16 v[104:107], v[150:153], v[188:191], v[104:107]
	v_mfma_f32_16x16x32_bf16 v[92:95], v[142:145], v[196:199], v[92:95]
	v_mfma_f32_16x16x32_bf16 v[88:91], v[150:153], v[196:199], v[88:91]
	v_mfma_f32_16x16x32_bf16 v[76:79], v[142:145], v[204:207], v[76:79]
	v_mfma_f32_16x16x32_bf16 v[72:75], v[150:153], v[204:207], v[72:75]
	v_mfma_f32_16x16x32_bf16 v[124:127], v[146:149], v[184:187], v[124:127]
	v_mfma_f32_16x16x32_bf16 v[120:123], v[154:157], v[184:187], v[120:123]
	v_mfma_f32_16x16x32_bf16 v[108:111], v[146:149], v[192:195], v[108:111]
	v_mfma_f32_16x16x32_bf16 v[104:107], v[154:157], v[192:195], v[104:107]
	v_mfma_f32_16x16x32_bf16 v[92:95], v[146:149], v[200:203], v[92:95]
	v_mfma_f32_16x16x32_bf16 v[88:91], v[154:157], v[200:203], v[88:91]
	v_mfma_f32_16x16x32_bf16 v[76:79], v[146:149], v[208:211], v[76:79]
	v_mfma_f32_16x16x32_bf16 v[72:75], v[154:157], v[208:211], v[72:75]
	s_setprio 0
	s_setprio 1
	v_mfma_f32_16x16x32_bf16 v[116:119], v[164:167], v[180:183], v[116:119]
	v_mfma_f32_16x16x32_bf16 v[112:115], v[172:175], v[180:183], v[112:115]
	v_mfma_f32_16x16x32_bf16 v[100:103], v[164:167], v[188:191], v[100:103]
	v_mfma_f32_16x16x32_bf16 v[96:99], v[172:175], v[188:191], v[96:99]
	v_mfma_f32_16x16x32_bf16 v[84:87], v[164:167], v[196:199], v[84:87]
	v_mfma_f32_16x16x32_bf16 v[80:83], v[172:175], v[196:199], v[80:83]
	v_mfma_f32_16x16x32_bf16 v[68:71], v[164:167], v[204:207], v[68:71]
	v_mfma_f32_16x16x32_bf16 v[64:67], v[172:175], v[204:207], v[64:67]
	v_mfma_f32_16x16x32_bf16 v[116:119], v[168:171], v[184:187], v[116:119]
	v_mfma_f32_16x16x32_bf16 v[112:115], v[176:179], v[184:187], v[112:115]
	v_mfma_f32_16x16x32_bf16 v[100:103], v[168:171], v[192:195], v[100:103]
	v_mfma_f32_16x16x32_bf16 v[96:99], v[176:179], v[192:195], v[96:99]
	v_mfma_f32_16x16x32_bf16 v[84:87], v[168:171], v[200:203], v[84:87]
	v_mfma_f32_16x16x32_bf16 v[80:83], v[176:179], v[200:203], v[80:83]
	v_mfma_f32_16x16x32_bf16 v[68:71], v[168:171], v[208:211], v[68:71]
	v_mfma_f32_16x16x32_bf16 v[64:67], v[176:179], v[208:211], v[64:67]
	s_setprio 0
	s_barrier
	s_add_i32 s36, s64, s44
	v_lshl_add_u64 v[212:213], v[212:213], 0, s[6:7]
	s_mov_b32 m0, s36
	ds_read_b128 v[180:183], v163 offset:49152
	ds_read_b128 v[184:187], v163 offset:50176
	ds_read_b128 v[188:191], v163 offset:51200
	ds_read_b128 v[192:195], v163 offset:52224
	ds_read_b128 v[196:199], v163 offset:53248
	ds_read_b128 v[200:203], v163 offset:54272
	ds_read_b128 v[204:207], v163 offset:55296
	ds_read_b128 v[208:211], v163 offset:56320
	global_load_lds_dwordx4 v[212:213], off
	s_add_i32 m0, s36, 0x2000
	s_add_u32 s34, s34, 0x40080
	v_lshl_add_u64 v[212:213], v[214:215], 0, s[6:7]
	s_addc_u32 s35, s35, 0
	s_add_i32 s36, s65, s44
	global_load_lds_dwordx4 v[212:213], off
	s_mov_b32 m0, s36
	s_nop 0
	global_load_lds_dwordx4 v130, s[34:35]
	s_add_i32 m0, s36, 0x2000
	s_nop 0
	global_load_lds_dwordx4 v134, s[34:35]
	v_lshl_add_u64 v[212:213], v[216:217], 0, s[6:7]
	s_mov_b32 m0, s50
	s_nop 0
	global_load_lds_dwordx4 v[212:213], off
	v_lshl_add_u64 v[212:213], v[218:219], 0, s[6:7]
	s_mov_b32 m0, s51
	s_nop 0
	global_load_lds_dwordx4 v[212:213], off
	s_waitcnt vmcnt(8)
	s_waitcnt lgkmcnt(0)
	s_barrier
	s_setprio 1
	s_waitcnt lgkmcnt(0)
	v_mfma_f32_16x16x32_bf16 v[60:63], v[142:145], v[180:183], v[60:63]
	v_mfma_f32_16x16x32_bf16 v[56:59], v[150:153], v[180:183], v[56:59]
	v_mfma_f32_16x16x32_bf16 v[44:47], v[142:145], v[188:191], v[44:47]
	v_mfma_f32_16x16x32_bf16 v[40:43], v[150:153], v[188:191], v[40:43]
	v_mfma_f32_16x16x32_bf16 v[28:31], v[142:145], v[196:199], v[28:31]
	v_mfma_f32_16x16x32_bf16 v[24:27], v[150:153], v[196:199], v[24:27]
	v_mfma_f32_16x16x32_bf16 v[12:15], v[142:145], v[204:207], v[12:15]
	v_mfma_f32_16x16x32_bf16 v[8:11], v[150:153], v[204:207], v[8:11]
	v_mfma_f32_16x16x32_bf16 v[60:63], v[146:149], v[184:187], v[60:63]
	v_mfma_f32_16x16x32_bf16 v[56:59], v[154:157], v[184:187], v[56:59]
	v_mfma_f32_16x16x32_bf16 v[44:47], v[146:149], v[192:195], v[44:47]
	v_mfma_f32_16x16x32_bf16 v[40:43], v[154:157], v[192:195], v[40:43]
	v_mfma_f32_16x16x32_bf16 v[28:31], v[146:149], v[200:203], v[28:31]
	v_mfma_f32_16x16x32_bf16 v[24:27], v[154:157], v[200:203], v[24:27]
	v_mfma_f32_16x16x32_bf16 v[12:15], v[146:149], v[208:211], v[12:15]
	v_mfma_f32_16x16x32_bf16 v[8:11], v[154:157], v[208:211], v[8:11]
	s_setprio 0
	s_setprio 1
	v_mfma_f32_16x16x32_bf16 v[52:55], v[164:167], v[180:183], v[52:55]
	v_mfma_f32_16x16x32_bf16 v[48:51], v[172:175], v[180:183], v[48:51]
	v_mfma_f32_16x16x32_bf16 v[36:39], v[164:167], v[188:191], v[36:39]
	v_mfma_f32_16x16x32_bf16 v[32:35], v[172:175], v[188:191], v[32:35]
	v_mfma_f32_16x16x32_bf16 v[20:23], v[164:167], v[196:199], v[20:23]
	v_mfma_f32_16x16x32_bf16 v[16:19], v[172:175], v[196:199], v[16:19]
	v_mfma_f32_16x16x32_bf16 v[4:7], v[164:167], v[204:207], v[4:7]
	v_mfma_f32_16x16x32_bf16 v[0:3], v[172:175], v[204:207], v[0:3]
	v_mfma_f32_16x16x32_bf16 v[52:55], v[168:171], v[184:187], v[52:55]
	v_mfma_f32_16x16x32_bf16 v[48:51], v[176:179], v[184:187], v[48:51]
	v_mfma_f32_16x16x32_bf16 v[36:39], v[168:171], v[192:195], v[36:39]
	v_mfma_f32_16x16x32_bf16 v[32:35], v[176:179], v[192:195], v[32:35]
	v_mfma_f32_16x16x32_bf16 v[20:23], v[168:171], v[200:203], v[20:23]
	v_mfma_f32_16x16x32_bf16 v[16:19], v[176:179], v[200:203], v[16:19]
	v_mfma_f32_16x16x32_bf16 v[4:7], v[168:171], v[208:211], v[4:7]
	v_mfma_f32_16x16x32_bf16 v[0:3], v[176:179], v[208:211], v[0:3]
	s_setprio 0
	s_barrier
	s_add_i32 s63, s63, 2
	s_add_u32 s30, s30, 0x100
	s_addc_u32 s31, s31, 0
	s_add_u32 s61, s61, 0x100
	s_addc_u32 s62, s62, 0
	s_cmp_gt_u32 s63, 13
	s_cbranch_scc0 .LBB0_728
	s_and_b64 vcc, exec, s[8:9]
	s_cbranch_vccz .LBB0_731
	s_barrier

;     __device__ bool next(int i, Unit& u) const { if (r0 + i >= r1) return false; return base.next(r0 + i, u); }
;     __device__ bool next(int i, Unit& u) const { const int L = i * G + c; if (L >= 256) return false; u.pm = L; u.pn = L >> 3; return true; }
; #define PG8_STAGE(bufoff, gbase, voff) do { _Pragma("unroll") for (int _i = 0; _i < 2; ++_i) \
;         __builtin_amdgcn_global_load_lds((const unsigned*)((const char*)(gbase) + (voff)[_i]), (LAS unsigned*)(lds + (bufoff) + ldsw + _i * 8192), 16, 0, 0); } while (0)
; #define PG8_WAIT_V(n) asm volatile("s_waitcnt vmcnt(" #n ")" ::: "memory")
; #define PG8_BAR __builtin_amdgcn_s_barrier()
;     __device__ bool next(int i, Unit& u) const {
;         const long L = (long)i * G + c; if (L >= nwg) return false;
;         int wgid = (int)L; { const int q = nwg / NXCD, r = nwg % NXCD, xcd = wgid % NXCD, off = wgid / NXCD; wgid = (xcd < r ? xcd * (q + 1) : r * (q + 1) + (xcd - r) * q) + off; }
;         const int nig = WGM * nN, gid = wgid / nig, fm = gid * WGM, gsz = (nM - fm) < WGM ? (nM - fm) : WGM;
;         u.pm = fm + ((wgid % nig) % gsz); u.pn = (wgid % nig) / gsz; return true;
; template <class Epi, class Sched>
; __device__ __forceinline__ void gemm_phase(LAS unsigned char* lds, const Gemm g, const Sched& S, const Epi& E, int wave_id) {
;     ...
;     const char* cA = (const char*)g.A + (size_t)cur.pm * tstepA; const char* cB = (const char*)g.Bt + (size_t)cur.pn * tstepB;
;     PG8_STAGE(PG8_SB(0, 0), cB, voffB); PG8_STAGE(PG8_SB(0, 1), cB + hstepB, voffB); PG8_STAGE(PG8_SA(0, 0), cA, voffA); PG8_STAGE(PG8_SA(0, 1), cA + hstepA, voffA);
;     if (wr == 1) PG8_BAR;
;     PG8_WAIT_V(2); PG8_BAR;
;     PG8_STAGE(PG8_SB(1, 0), cB + kstep, voffB); PG8_STAGE(PG8_SA(1, 0), cA + kstep, voffA); PG8_STAGE(PG8_SB(1, 1), cB + hstepB + kstep, voffB);
;     PG8_WAIT_V(6); PG8_BAR;
;     for (;;) {
;         const bool has_next = S.next(ui + 1, nxt);
;         const char* nA = has_next ? (const char*)g.A + (size_t)nxt.pm * tstepA : cA; const char* nB = has_next ? (const char*)g.Bt + (size_t)nxt.pn * tstepB : cB;
.LBB0_800:
	v_lshrrev_b32_e32 v16, 1, v14
	v_and_b32_e32 v16, 24, v16
	v_and_b32_e32 v15, 15, v14
	v_lshlrev_b32_e32 v17, 1, v16
	v_lshlrev_b32_e32 v14, 2, v14
	v_lshl_or_b32 v156, s8, 6, v15
	v_lshl_or_b32 v15, v15, 6, v17
	s_lshl_b32 s8, s8, 13
	v_and_b32_e32 v14, 32, v14
	v_bitop3_b32 v17, v15, s8, v14 bitop3:0xde
	s_lshl_b32 s8, s97, 5
	s_and_b32 s16, s8, 0x60
	s_lshl_b32 s8, s16, 7
	v_bitop3_b32 v157, v15, s8, v14 bitop3:0xde
	s_mov_b64 s[8:9], 0x80
	s_add_i32 m0, s27, 0x18000
	v_lshl_add_u64 v[6:7], v[6:7], 0, s[8:9]
	s_waitcnt vmcnt(2)
	s_barrier
	global_load_lds_dwordx4 v[6:7], off
	v_lshl_add_u64 v[4:5], v[4:5], 0, s[8:9]
	s_add_i32 m0, s27, 0x1a000
	s_add_i32 s46, s27, 0x8000
	s_add_i32 s47, s27, 0xa000
	global_load_lds_dwordx4 v[4:5], off
	v_lshl_add_u64 v[0:1], v[0:1], 0, s[8:9]
	s_mov_b32 m0, s46
	s_add_u32 s10, s34, 0x40080
	global_load_lds_dwordx4 v[0:1], off
	v_lshl_add_u64 v[0:1], v[2:3], 0, s[8:9]
	s_mov_b32 m0, s47
	s_addc_u32 s11, s35, 0
	global_load_lds_dwordx4 v[0:1], off
	s_add_i32 m0, s27, 0x1c000
	s_nop 0
	global_load_lds_dwordx4 v130, s[10:11]
	s_add_i32 m0, s27, 0x1e000
	s_cmpk_lt_u32 s80, 0x100
	global_load_lds_dwordx4 v134, s[10:11]
	s_cselect_b64 s[10:11], -1, 0
	s_add_u32 s12, s92, 0x1f400000
	s_addc_u32 s13, s93, 0
	s_add_u32 s14, s92, 0xb400000
	s_addc_u32 s15, s93, 0
	s_mul_hi_i32 s17, s4, 3
	s_mul_i32 s4, s4, 3
	s_add_u32 s4, s4, s66
	s_addc_u32 s5, s17, s5
	s_ashr_i32 s17, s4, 31
	s_lshr_b32 s17, s17, 29
	s_add_i32 s17, s4, s17
	s_ashr_i32 s18, s17, 3
	s_and_b32 s17, s17, -8
	s_sub_i32 s17, s4, s17
	s_lshl_b32 s19, s17, 7
	s_cmp_lt_i32 s17, 0
	s_mulk_i32 s17, 0x81
	s_cselect_b32 s17, s17, s19
	s_add_i32 s17, s17, s18
	s_ashr_i32 s18, s17, 31
	s_lshr_b32 s18, s18, 26
	s_add_i32 s18, s17, s18
	s_ashr_i32 s19, s18, 6
	s_lshl_b32 s19, s19, 3
	s_sub_i32 s20, 0x80, s19
	s_min_i32 s20, s20, 8
	s_abs_i32 s22, s20
	v_cvt_f32_u32_e32 v2, s22
	v_mov_b64_e32 v[0:1], 0x400
	v_cmp_lt_i64_e64 s[36:37], s[4:5], v[0:1]
	s_andn2_b32 s18, s18, 63
	v_rcp_iflag_f32_e32 v0, v2
	s_sub_i32 s4, s17, s18
	s_sub_i32 s17, 0, s22
	v_or_b32_e32 v158, s16, v16
	v_mul_f32_e32 v0, 0x4f7ffffe, v0
	v_cvt_u32_f32_e32 v0, v0
	s_abs_i32 s16, s4
	s_xor_b32 s5, s4, s20
	s_ashr_i32 s5, s5, 31
	v_readfirstlane_b32 s18, v0
	s_mul_i32 s17, s17, s18
	s_mul_hi_u32 s17, s18, s17
	s_add_i32 s18, s18, s17
	s_mul_hi_u32 s17, s16, s18
	s_mul_i32 s18, s17, s22
	s_sub_i32 s16, s16, s18
	s_add_i32 s18, s17, 1
	s_sub_i32 s23, s16, s22
	s_cmp_ge_u32 s16, s22
	s_cselect_b32 s17, s18, s17
	v_lshlrev_b32_e32 v0, 14, v8
	s_cselect_b32 s16, s23, s16
	s_add_i32 s18, s17, 1
	v_and_b32_e32 v0, 0xffff8000, v0
	s_cmp_ge_u32 s16, s22
	v_lshl_add_u32 v0, v9, 11, v0
	v_and_b32_e32 v1, 1, v8
	s_cselect_b32 s16, s18, s17
	v_lshl_or_b32 v0, v1, 6, v0
	s_xor_b32 s16, s16, s5
	v_lshl_add_u32 v136, v10, 1, v0
	v_lshlrev_b32_e32 v0, 14, v11
	s_sub_i32 s16, s16, s5
	v_and_b32_e32 v0, 0xffff8000, v0
	s_waitcnt vmcnt(6)
	s_mul_i32 s5, s16, s20
	v_lshl_add_u32 v0, v12, 11, v0
	v_and_b32_e32 v1, 1, v11
	s_sub_i32 s4, s4, s5
	v_lshl_or_b32 v0, v1, 6, v0
	s_add_i32 s48, 0, 0x10000
	s_add_i32 s49, 0, 0x14000
	s_add_i32 s18, s19, s4
	v_mov_b32_e32 v137, v131
	v_lshl_add_u32 v138, v13, 1, v0
	v_mov_b32_e32 v139, v131
	v_add_u32_e32 v159, s48, v157
	v_add_u32_e32 v160, s49, v157
	v_add_u32_e32 v161, 0, v17
	s_mov_b32 s20, 0x437f0000
	s_mov_b32 s50, 0xb400000
	s_barrier
	s_branch .LBB0_803

;     __device__ bool next(int i, Unit& u) const { if (r0 + i >= r1) return false; return base.next(r0 + i, u); }
;     __device__ bool next(int i, Unit& u) const { const int L = i * G + c; if (L >= 256) return false; u.pm = L; u.pn = L >> 3; return true; }
; #define PG8_STAGE(bufoff, gbase, voff) do { _Pragma("unroll") for (int _i = 0; _i < 2; ++_i) \
;         __builtin_amdgcn_global_load_lds((const unsigned*)((const char*)(gbase) + (voff)[_i]), (LAS unsigned*)(lds + (bufoff) + ldsw + _i * 8192), 16, 0, 0); } while (0)
; #define PG8_LDA(dst, b, h) do { _Pragma("unroll") for (int m = 0; m < 4; ++m) _Pragma("unroll") for (int k = 0; k < 2; ++k) dst[m][k] = *(const LAS bf16x8*)(lds + PG8_SA(b, h) + aoff + m * 2048 + k * 1024); } while (0)
; #define PG8_LDB(dst, b, h) do { _Pragma("unroll") for (int n = 0; n < 2; ++n) _Pragma("unroll") for (int k = 0; k < 2; ++k) dst[n][k] = *(const LAS bf16x8*)(lds + PG8_SB(b, h) + boff + n * 2048 + k * 1024); } while (0)
; #define PG8_WAIT_V(n) asm volatile("s_waitcnt vmcnt(" #n ")" ::: "memory")
; #define PG8_WAIT_L(n) asm volatile("s_waitcnt lgkmcnt(" #n ")" ::: "memory")
; template <class Epi, class Sched>
; __device__ __forceinline__ void gemm_phase(LAS unsigned char* lds, const Gemm g, const Sched& S, const Epi& E, int wave_id) {
;     ...
;         const bool has_next = S.next(ui + 1, nxt);
;         const char* nA = has_next ? (const char*)g.A + (size_t)nxt.pm * tstepA : cA; const char* nB = has_next ? (const char*)g.Bt + (size_t)nxt.pn * tstepB : cB;
;         for (int t = 0; t < nt; t += 2) {
;             const bool last = (t == nt - 2);
;             const char* a1 = cA + (size_t)(t + 1) * kstep;
;             const char* a2 = last ? nA : cA + (size_t)(t + 2) * kstep; const char* b2 = last ? nB : cB + (size_t)(t + 2) * kstep;
;             const char* a3 = a2 + kstep; const char* b3 = b2 + kstep;
;             PG8_LDB(B0, 0, 0); PG8_LDB(B1, 0, 1); PG8_SCHED; PG8_LDA(At, 0, 0); PG8_STAGE(PG8_SA(1, 1), a1 + hstepA, voffA);
;             PG8_WAIT_V(8); PG8_WAIT_L(0); PG8_BAR; PG8_MMA(0, 0, At, B0); PG8_MMA(0, 1, At, B1); PG8_BAR; PG8_SCHED;
;             PG8_LDA(At, 0, 1); PG8_STAGE(PG8_SB(0, 0), b2, voffB); PG8_STAGE(PG8_SB(0, 1), b2 + hstepB, voffB); PG8_STAGE(PG8_SA(0, 0), a2, voffA);
;             PG8_WAIT_V(8); PG8_WAIT_L(0); PG8_BAR; PG8_MMA(1, 0, At, B0); PG8_MMA(1, 1, At, B1); PG8_BAR; PG8_SCHED;
.LBB0_803:
	s_ashr_i32 s19, s18, 31
	s_andn2_b64 vcc, exec, s[36:37]
	s_lshl_b64 s[22:23], s[18:19], 19
	s_add_u32 s22, s2, s22
	s_addc_u32 s23, s21, s23
	s_and_b64 s[24:25], s[36:37], exec
	s_cselect_b32 s19, s23, s31
	s_cselect_b32 s51, s22, s30
	s_ashr_i32 s17, s16, 31
	s_lshl_b64 s[24:25], s[16:17], 19
	s_add_u32 s24, s33, s24
	s_addc_u32 s25, s38, s25
	v_cndmask_b32_e64 v0, 0, 1, s[36:37]
	s_and_b64 s[36:37], s[36:37], exec
	s_cselect_b32 s17, s25, s35
	s_cselect_b32 s52, s24, s34
	s_add_u32 s30, s30, 0x40080
	s_addc_u32 s31, s31, 0
	v_cmp_ne_u32_e64 s[4:5], 1, v0
	s_add_u32 s53, s34, 0x100
	s_addc_u32 s54, s35, 0
	s_mov_b32 s55, -2
	s_waitcnt vmcnt(0)
	ds_read_b128 v[140:143], v159
	ds_read_b128 v[144:147], v159 offset:1024
	ds_read_b128 v[148:151], v159 offset:2048
	ds_read_b128 v[152:155], v159 offset:3072
	ds_read_b128 v[162:165], v160
	ds_read_b128 v[166:169], v160 offset:1024
	ds_read_b128 v[170:173], v160 offset:2048
	ds_read_b128 v[174:177], v160 offset:3072
	s_add_u32 s34, s30, 0xfffc0080
	s_addc_u32 s35, s31, -1
	s_cmp_eq_u32 s55, 12
	s_cselect_b32 s37, s19, s35
	s_cselect_b32 s36, s51, s34
	s_cselect_b32 s35, s17, s54
	s_cselect_b32 s34, s52, s53
	s_add_i32 m0, s27, 0xc000
	ds_read_b128 v[178:181], v161
	ds_read_b128 v[182:185], v161 offset:1024
	ds_read_b128 v[186:189], v161 offset:2048
	ds_read_b128 v[190:193], v161 offset:3072
	ds_read_b128 v[194:197], v161 offset:4096
	ds_read_b128 v[198:201], v161 offset:5120
	ds_read_b128 v[202:205], v161 offset:6144
	ds_read_b128 v[206:209], v161 offset:7168
	global_load_lds_dwordx4 v136, s[30:31]
	s_add_i32 m0, s27, 0xe000
	s_nop 0
	global_load_lds_dwordx4 v138, s[30:31]
	s_waitcnt vmcnt(8)
	s_waitcnt lgkmcnt(0)
	s_barrier
	s_setprio 1
	s_waitcnt lgkmcnt(0)
	v_mfma_f32_16x16x32_bf16 v[124:127], v[140:143], v[178:181], 0
	v_mfma_f32_16x16x32_bf16 v[120:123], v[148:151], v[178:181], 0
	v_mfma_f32_16x16x32_bf16 v[108:111], v[140:143], v[186:189], 0
	v_mfma_f32_16x16x32_bf16 v[104:107], v[148:151], v[186:189], 0
	v_mfma_f32_16x16x32_bf16 v[92:95], v[140:143], v[194:197], 0
	v_mfma_f32_16x16x32_bf16 v[88:91], v[148:151], v[194:197], 0
	v_mfma_f32_16x16x32_bf16 v[76:79], v[140:143], v[202:205], 0
	v_mfma_f32_16x16x32_bf16 v[72:75], v[148:151], v[202:205], 0
	v_mfma_f32_16x16x32_bf16 v[124:127], v[144:147], v[182:185], v[124:127]
	v_mfma_f32_16x16x32_bf16 v[120:123], v[152:155], v[182:185], v[120:123]
	v_mfma_f32_16x16x32_bf16 v[108:111], v[144:147], v[190:193], v[108:111]
	v_mfma_f32_16x16x32_bf16 v[104:107], v[152:155], v[190:193], v[104:107]
	v_mfma_f32_16x16x32_bf16 v[92:95], v[144:147], v[198:201], v[92:95]
	v_mfma_f32_16x16x32_bf16 v[88:91], v[152:155], v[198:201], v[88:91]
	v_mfma_f32_16x16x32_bf16 v[76:79], v[144:147], v[206:209], v[76:79]
	v_mfma_f32_16x16x32_bf16 v[72:75], v[152:155], v[206:209], v[72:75]
	s_setprio 0
	s_setprio 1
	v_mfma_f32_16x16x32_bf16 v[116:119], v[162:165], v[178:181], 0
	v_mfma_f32_16x16x32_bf16 v[112:115], v[170:173], v[178:181], 0
	v_mfma_f32_16x16x32_bf16 v[100:103], v[162:165], v[186:189], 0
	v_mfma_f32_16x16x32_bf16 v[96:99], v[170:173], v[186:189], 0
	v_mfma_f32_16x16x32_bf16 v[84:87], v[162:165], v[194:197], 0
	v_mfma_f32_16x16x32_bf16 v[80:83], v[170:173], v[194:197], 0
	v_mfma_f32_16x16x32_bf16 v[68:71], v[162:165], v[202:205], 0
	v_mfma_f32_16x16x32_bf16 v[64:67], v[170:173], v[202:205], 0
	v_mfma_f32_16x16x32_bf16 v[116:119], v[166:169], v[182:185], v[116:119]
	v_mfma_f32_16x16x32_bf16 v[112:115], v[174:177], v[182:185], v[112:115]
	v_mfma_f32_16x16x32_bf16 v[100:103], v[166:169], v[190:193], v[100:103]
	v_mfma_f32_16x16x32_bf16 v[96:99], v[174:177], v[190:193], v[96:99]
	v_mfma_f32_16x16x32_bf16 v[84:87], v[166:169], v[198:201], v[84:87]
	v_mfma_f32_16x16x32_bf16 v[80:83], v[174:177], v[198:201], v[80:83]
	v_mfma_f32_16x16x32_bf16 v[68:71], v[166:169], v[206:209], v[68:71]
	v_mfma_f32_16x16x32_bf16 v[64:67], v[174:177], v[206:209], v[64:67]
	s_setprio 0
	s_barrier
	s_add_i32 s58, s48, s39
	v_lshl_add_u64 v[210:211], s[34:35], 0, v[130:131]
	s_mov_b32 m0, s58
	ds_read_b128 v[178:181], v161 offset:16384
	ds_read_b128 v[182:185], v161 offset:17408
	ds_read_b128 v[186:189], v161 offset:18432
	ds_read_b128 v[190:193], v161 offset:19456
	ds_read_b128 v[194:197], v161 offset:20480
	ds_read_b128 v[198:201], v161 offset:21504
	ds_read_b128 v[202:205], v161 offset:22528
	ds_read_b128 v[206:209], v161 offset:23552
	global_load_lds_dwordx4 v[210:211], off
	s_add_i32 m0, s58, 0x2000
	s_add_u32 s58, s34, 0x40000
	v_lshl_add_u64 v[212:213], s[34:35], 0, v[134:135]
	s_addc_u32 s59, s35, 0
	s_add_i32 s60, s49, s39
	global_load_lds_dwordx4 v[212:213], off
	s_mov_b32 m0, s60
	v_lshl_add_u64 v[216:217], s[36:37], 0, v[132:133]
	global_load_lds_dwordx4 v130, s[58:59]
	s_add_i32 m0, s60, 0x2000
	s_nop 0
	global_load_lds_dwordx4 v134, s[58:59]
	v_lshl_add_u64 v[214:215], s[36:37], 0, v[128:129]
	s_mov_b32 m0, s27
	s_nop 0
	global_load_lds_dwordx4 v[214:215], off
	s_mov_b32 m0, s29
	s_nop 0
	global_load_lds_dwordx4 v[216:217], off
	s_waitcnt vmcnt(8)
	s_waitcnt lgkmcnt(0)
	s_barrier
; #define PG8_STAGE(bufoff, gbase, voff) do { _Pragma("unroll") for (int _i = 0; _i < 2; ++_i) \
;         __builtin_amdgcn_global_load_lds((const unsigned*)((const char*)(gbase) + (voff)[_i]), (LAS unsigned*)(lds + (bufoff) + ldsw + _i * 8192), 16, 0, 0); } while (0)
; #define PG8_LDA(dst, b, h) do { _Pragma("unroll") for (int m = 0; m < 4; ++m) _Pragma("unroll") for (int k = 0; k < 2; ++k) dst[m][k] = *(const LAS bf16x8*)(lds + PG8_SA(b, h) + aoff + m * 2048 + k * 1024); } while (0)
; #define PG8_LDB(dst, b, h) do { _Pragma("unroll") for (int n = 0; n < 2; ++n) _Pragma("unroll") for (int k = 0; k < 2; ++k) dst[n][k] = *(const LAS bf16x8*)(lds + PG8_SB(b, h) + boff + n * 2048 + k * 1024); } while (0)
; #define PG8_MMA(ai, bj, At, Bt) do { __builtin_amdgcn_s_setprio(1); _Pragma("unroll") for (int m = 0; m < 4; ++m) _Pragma("unroll") for (int n = 0; n < 2; ++n) _Pragma("unroll") for (int k = 0; k < 2; ++k) \
;         acc[ai][bj][m][n] = __builtin_amdgcn_mfma_f32_16x16x32_bf16(Bt[n][k], At[m][k], acc[ai][bj][m][n], 0, 0, 0); __builtin_amdgcn_s_setprio(0); } while (0)
; #define PG8_WAIT_V(n) asm volatile("s_waitcnt vmcnt(" #n ")" ::: "memory")
; #define PG8_WAIT_L(n) asm volatile("s_waitcnt lgkmcnt(" #n ")" ::: "memory")
; #define PG8_BAR __builtin_amdgcn_s_barrier()
; #define PG8_SCHED __builtin_amdgcn_sched_barrier(0)
; template <class Epi, class Sched>
; __device__ __forceinline__ void gemm_phase(LAS unsigned char* lds, const Gemm g, const Sched& S, const Epi& E, int wave_id) {
;     ...
;             PG8_WAIT_V(8); PG8_WAIT_L(0); PG8_BAR; PG8_MMA(1, 0, At, B0); PG8_MMA(1, 1, At, B1); PG8_BAR; PG8_SCHED;
;             PG8_LDB(B0, 1, 0); PG8_LDB(B1, 1, 1); PG8_SCHED; PG8_LDA(At, 1, 0); PG8_STAGE(PG8_SA(0, 1), a2 + hstepA, voffA);
;             PG8_WAIT_V(8); PG8_WAIT_L(0); PG8_BAR; PG8_MMA(0, 0, At, B0); PG8_MMA(0, 1, At, B1); PG8_BAR; PG8_SCHED;
	s_setprio 1
	s_waitcnt lgkmcnt(0)
	v_mfma_f32_16x16x32_bf16 v[60:63], v[140:143], v[178:181], 0
	v_mfma_f32_16x16x32_bf16 v[56:59], v[148:151], v[178:181], 0
	v_mfma_f32_16x16x32_bf16 v[44:47], v[140:143], v[186:189], 0
	v_mfma_f32_16x16x32_bf16 v[40:43], v[148:151], v[186:189], 0
	v_mfma_f32_16x16x32_bf16 v[28:31], v[140:143], v[194:197], 0
	v_mfma_f32_16x16x32_bf16 v[24:27], v[148:151], v[194:197], 0
	v_mfma_f32_16x16x32_bf16 v[12:15], v[140:143], v[202:205], 0
	v_mfma_f32_16x16x32_bf16 v[8:11], v[148:151], v[202:205], 0
	v_mfma_f32_16x16x32_bf16 v[60:63], v[144:147], v[182:185], v[60:63]
	v_mfma_f32_16x16x32_bf16 v[56:59], v[152:155], v[182:185], v[56:59]
	v_mfma_f32_16x16x32_bf16 v[44:47], v[144:147], v[190:193], v[44:47]
	v_mfma_f32_16x16x32_bf16 v[40:43], v[152:155], v[190:193], v[40:43]
	v_mfma_f32_16x16x32_bf16 v[28:31], v[144:147], v[198:201], v[28:31]
	v_mfma_f32_16x16x32_bf16 v[24:27], v[152:155], v[198:201], v[24:27]
	v_mfma_f32_16x16x32_bf16 v[12:15], v[144:147], v[206:209], v[12:15]
	v_mfma_f32_16x16x32_bf16 v[8:11], v[152:155], v[206:209], v[8:11]
	s_setprio 0
	s_setprio 1
	v_mfma_f32_16x16x32_bf16 v[52:55], v[162:165], v[178:181], 0
	v_mfma_f32_16x16x32_bf16 v[48:51], v[170:173], v[178:181], 0
	v_mfma_f32_16x16x32_bf16 v[36:39], v[162:165], v[186:189], 0
	v_mfma_f32_16x16x32_bf16 v[32:35], v[170:173], v[186:189], 0
	v_mfma_f32_16x16x32_bf16 v[20:23], v[162:165], v[194:197], 0
	v_mfma_f32_16x16x32_bf16 v[16:19], v[170:173], v[194:197], 0
	v_mfma_f32_16x16x32_bf16 v[4:7], v[162:165], v[202:205], 0
	v_mfma_f32_16x16x32_bf16 v[0:3], v[170:173], v[202:205], 0
	v_mfma_f32_16x16x32_bf16 v[52:55], v[166:169], v[182:185], v[52:55]
	v_mfma_f32_16x16x32_bf16 v[48:51], v[174:177], v[182:185], v[48:51]
	v_mfma_f32_16x16x32_bf16 v[36:39], v[166:169], v[190:193], v[36:39]
	v_mfma_f32_16x16x32_bf16 v[32:35], v[174:177], v[190:193], v[32:35]
	v_mfma_f32_16x16x32_bf16 v[20:23], v[166:169], v[198:201], v[20:23]
	v_mfma_f32_16x16x32_bf16 v[16:19], v[174:177], v[198:201], v[16:19]
	v_mfma_f32_16x16x32_bf16 v[4:7], v[166:169], v[206:209], v[4:7]
	v_mfma_f32_16x16x32_bf16 v[0:3], v[174:177], v[206:209], v[0:3]
	s_setprio 0
	s_barrier
	s_add_i32 s58, 0, 0x18000
	s_add_i32 s59, 0, 0x1c000
	v_add_u32_e32 v152, s58, v157
	v_add_u32_e32 v174, s59, v157
	ds_read_b128 v[140:143], v152
	ds_read_b128 v[144:147], v152 offset:1024
	ds_read_b128 v[148:151], v152 offset:2048
	ds_read_b128 v[152:155], v152 offset:3072
	ds_read_b128 v[162:165], v174
	ds_read_b128 v[166:169], v174 offset:1024
	ds_read_b128 v[170:173], v174 offset:2048
	ds_read_b128 v[174:177], v174 offset:3072
	s_add_u32 s36, s36, 0x40000
	s_addc_u32 s37, s37, 0
	s_mov_b32 m0, s44
	ds_read_b128 v[178:181], v161 offset:32768
	ds_read_b128 v[182:185], v161 offset:33792
	ds_read_b128 v[186:189], v161 offset:34816
	ds_read_b128 v[190:193], v161 offset:35840
	ds_read_b128 v[194:197], v161 offset:36864
	ds_read_b128 v[198:201], v161 offset:37888
	ds_read_b128 v[202:205], v161 offset:38912
	ds_read_b128 v[206:209], v161 offset:39936
	global_load_lds_dwordx4 v128, s[36:37]
	s_mov_b32 m0, s45
	s_nop 0
	global_load_lds_dwordx4 v132, s[36:37]
	s_waitcnt vmcnt(8)
	s_waitcnt lgkmcnt(0)
	s_barrier
	s_setprio 1
	s_waitcnt lgkmcnt(0)
	v_mfma_f32_16x16x32_bf16 v[124:127], v[140:143], v[178:181], v[124:127]
	v_mfma_f32_16x16x32_bf16 v[120:123], v[148:151], v[178:181], v[120:123]
	v_mfma_f32_16x16x32_bf16 v[108:111], v[140:143], v[186:189], v[108:111]
	v_mfma_f32_16x16x32_bf16 v[104:107], v[148:151], v[186:189], v[104:107]
	v_mfma_f32_16x16x32_bf16 v[92:95], v[140:143], v[194:197], v[92:95]
	v_mfma_f32_16x16x32_bf16 v[88:91], v[148:151], v[194:197], v[88:91]
	v_mfma_f32_16x16x32_bf16 v[76:79], v[140:143], v[202:205], v[76:79]
	v_mfma_f32_16x16x32_bf16 v[72:75], v[148:151], v[202:205], v[72:75]
	v_mfma_f32_16x16x32_bf16 v[124:127], v[144:147], v[182:185], v[124:127]
	v_mfma_f32_16x16x32_bf16 v[120:123], v[152:155], v[182:185], v[120:123]
	v_mfma_f32_16x16x32_bf16 v[108:111], v[144:147], v[190:193], v[108:111]
	v_mfma_f32_16x16x32_bf16 v[104:107], v[152:155], v[190:193], v[104:107]
	v_mfma_f32_16x16x32_bf16 v[92:95], v[144:147], v[198:201], v[92:95]
	v_mfma_f32_16x16x32_bf16 v[88:91], v[152:155], v[198:201], v[88:91]
	v_mfma_f32_16x16x32_bf16 v[76:79], v[144:147], v[206:209], v[76:79]
	v_mfma_f32_16x16x32_bf16 v[72:75], v[152:155], v[206:209], v[72:75]
	s_setprio 0
	s_setprio 1
	v_mfma_f32_16x16x32_bf16 v[116:119], v[162:165], v[178:181], v[116:119]
	v_mfma_f32_16x16x32_bf16 v[112:115], v[170:173], v[178:181], v[112:115]
	v_mfma_f32_16x16x32_bf16 v[100:103], v[162:165], v[186:189], v[100:103]
	v_mfma_f32_16x16x32_bf16 v[96:99], v[170:173], v[186:189], v[96:99]
	v_mfma_f32_16x16x32_bf16 v[84:87], v[162:165], v[194:197], v[84:87]
	v_mfma_f32_16x16x32_bf16 v[80:83], v[170:173], v[194:197], v[80:83]
	v_mfma_f32_16x16x32_bf16 v[68:71], v[162:165], v[202:205], v[68:71]
	v_mfma_f32_16x16x32_bf16 v[64:67], v[170:173], v[202:205], v[64:67]
	v_mfma_f32_16x16x32_bf16 v[116:119], v[166:169], v[182:185], v[116:119]
	v_mfma_f32_16x16x32_bf16 v[112:115], v[174:177], v[182:185], v[112:115]
	v_mfma_f32_16x16x32_bf16 v[100:103], v[166:169], v[190:193], v[100:103]
	v_mfma_f32_16x16x32_bf16 v[96:99], v[174:177], v[190:193], v[96:99]
	v_mfma_f32_16x16x32_bf16 v[84:87], v[166:169], v[198:201], v[84:87]
	v_mfma_f32_16x16x32_bf16 v[80:83], v[174:177], v[198:201], v[80:83]
	v_mfma_f32_16x16x32_bf16 v[68:71], v[166:169], v[206:209], v[68:71]
	v_mfma_f32_16x16x32_bf16 v[64:67], v[174:177], v[206:209], v[64:67]
	s_setprio 0
	s_barrier
; #define PG8_STAGE(bufoff, gbase, voff) do { _Pragma("unroll") for (int _i = 0; _i < 2; ++_i) \
;         __builtin_amdgcn_global_load_lds((const unsigned*)((const char*)(gbase) + (voff)[_i]), (LAS unsigned*)(lds + (bufoff) + ldsw + _i * 8192), 16, 0, 0); } while (0)
; #define PG8_LDA(dst, b, h) do { _Pragma("unroll") for (int m = 0; m < 4; ++m) _Pragma("unroll") for (int k = 0; k < 2; ++k) dst[m][k] = *(const LAS bf16x8*)(lds + PG8_SA(b, h) + aoff + m * 2048 + k * 1024); } while (0)
; #define PG8_LDB(dst, b, h) do { _Pragma("unroll") for (int n = 0; n < 2; ++n) _Pragma("unroll") for (int k = 0; k < 2; ++k) dst[n][k] = *(const LAS bf16x8*)(lds + PG8_SB(b, h) + boff + n * 2048 + k * 1024); } while (0)
; #define PG8_MMA(ai, bj, At, Bt) do { __builtin_amdgcn_s_setprio(1); _Pragma("unroll") for (int m = 0; m < 4; ++m) _Pragma("unroll") for (int n = 0; n < 2; ++n) _Pragma("unroll") for (int k = 0; k < 2; ++k) \
;         acc[ai][bj][m][n] = __builtin_amdgcn_mfma_f32_16x16x32_bf16(Bt[n][k], At[m][k], acc[ai][bj][m][n], 0, 0, 0); __builtin_amdgcn_s_setprio(0); } while (0)
; #define PG8_WAIT_V(n) asm volatile("s_waitcnt vmcnt(" #n ")" ::: "memory")
; #define PG8_WAIT_L(n) asm volatile("s_waitcnt lgkmcnt(" #n ")" ::: "memory")
; #define PG8_BAR __builtin_amdgcn_s_barrier()
; #define PG8_SCHED __builtin_amdgcn_sched_barrier(0)
; template <class Epi, class Sched>
; __device__ __forceinline__ void gemm_phase(LAS unsigned char* lds, const Gemm g, const Sched& S, const Epi& E, int wave_id) {
;     ...
;             PG8_LDB(B0, 0, 0); PG8_LDB(B1, 0, 1); PG8_SCHED; PG8_LDA(At, 0, 0); PG8_STAGE(PG8_SA(1, 1), a1 + hstepA, voffA);
;             PG8_WAIT_V(8); PG8_WAIT_L(0); PG8_BAR; PG8_MMA(0, 0, At, B0); PG8_MMA(0, 1, At, B1); PG8_BAR; PG8_SCHED;
;     ...
;             PG8_WAIT_V(8); PG8_WAIT_L(0); PG8_BAR; PG8_MMA(0, 0, At, B0); PG8_MMA(0, 1, At, B1); PG8_BAR; PG8_SCHED;
;             PG8_LDA(At, 1, 1); PG8_STAGE(PG8_SB(1, 0), b3, voffB); PG8_STAGE(PG8_SB(1, 1), b3 + hstepB, voffB); PG8_STAGE(PG8_SA(1, 0), a3, voffA);
;             PG8_WAIT_V(8); PG8_WAIT_L(0); PG8_BAR; PG8_MMA(1, 0, At, B0); PG8_MMA(1, 1, At, B1); PG8_BAR; PG8_SCHED;
	s_add_i32 s36, s58, s39
	v_lshl_add_u64 v[210:211], v[210:211], 0, s[8:9]
	s_mov_b32 m0, s36
	ds_read_b128 v[178:181], v161 offset:49152
	ds_read_b128 v[182:185], v161 offset:50176
	ds_read_b128 v[186:189], v161 offset:51200
	ds_read_b128 v[190:193], v161 offset:52224
	ds_read_b128 v[194:197], v161 offset:53248
	ds_read_b128 v[198:201], v161 offset:54272
	ds_read_b128 v[202:205], v161 offset:55296
	ds_read_b128 v[206:209], v161 offset:56320
	global_load_lds_dwordx4 v[210:211], off
	s_add_i32 m0, s36, 0x2000
	s_add_u32 s34, s34, 0x40080
	v_lshl_add_u64 v[210:211], v[212:213], 0, s[8:9]
	s_addc_u32 s35, s35, 0
	s_add_i32 s36, s59, s39
	global_load_lds_dwordx4 v[210:211], off
	s_mov_b32 m0, s36
	s_nop 0
	global_load_lds_dwordx4 v130, s[34:35]
	s_add_i32 m0, s36, 0x2000
	s_nop 0
	global_load_lds_dwordx4 v134, s[34:35]
	v_lshl_add_u64 v[210:211], v[214:215], 0, s[8:9]
	s_mov_b32 m0, s46
	s_nop 0
	global_load_lds_dwordx4 v[210:211], off
	v_lshl_add_u64 v[210:211], v[216:217], 0, s[8:9]
	s_mov_b32 m0, s47
	s_nop 0
	global_load_lds_dwordx4 v[210:211], off
	s_waitcnt vmcnt(8)
	s_waitcnt lgkmcnt(0)
	s_barrier
	s_setprio 1
	s_waitcnt lgkmcnt(0)
	v_mfma_f32_16x16x32_bf16 v[60:63], v[140:143], v[178:181], v[60:63]
	v_mfma_f32_16x16x32_bf16 v[56:59], v[148:151], v[178:181], v[56:59]
	v_mfma_f32_16x16x32_bf16 v[44:47], v[140:143], v[186:189], v[44:47]
	v_mfma_f32_16x16x32_bf16 v[40:43], v[148:151], v[186:189], v[40:43]
	v_mfma_f32_16x16x32_bf16 v[28:31], v[140:143], v[194:197], v[28:31]
	v_mfma_f32_16x16x32_bf16 v[24:27], v[148:151], v[194:197], v[24:27]
	v_mfma_f32_16x16x32_bf16 v[12:15], v[140:143], v[202:205], v[12:15]
	v_mfma_f32_16x16x32_bf16 v[8:11], v[148:151], v[202:205], v[8:11]
	v_mfma_f32_16x16x32_bf16 v[60:63], v[144:147], v[182:185], v[60:63]
	v_mfma_f32_16x16x32_bf16 v[56:59], v[152:155], v[182:185], v[56:59]
	v_mfma_f32_16x16x32_bf16 v[44:47], v[144:147], v[190:193], v[44:47]
	v_mfma_f32_16x16x32_bf16 v[40:43], v[152:155], v[190:193], v[40:43]
	v_mfma_f32_16x16x32_bf16 v[28:31], v[144:147], v[198:201], v[28:31]
	v_mfma_f32_16x16x32_bf16 v[24:27], v[152:155], v[198:201], v[24:27]
	v_mfma_f32_16x16x32_bf16 v[12:15], v[144:147], v[206:209], v[12:15]
	v_mfma_f32_16x16x32_bf16 v[8:11], v[152:155], v[206:209], v[8:11]
	s_setprio 0
	s_setprio 1
	v_mfma_f32_16x16x32_bf16 v[52:55], v[162:165], v[178:181], v[52:55]
	v_mfma_f32_16x16x32_bf16 v[48:51], v[170:173], v[178:181], v[48:51]
	v_mfma_f32_16x16x32_bf16 v[36:39], v[162:165], v[186:189], v[36:39]
	v_mfma_f32_16x16x32_bf16 v[32:35], v[170:173], v[186:189], v[32:35]
	v_mfma_f32_16x16x32_bf16 v[20:23], v[162:165], v[194:197], v[20:23]
	v_mfma_f32_16x16x32_bf16 v[16:19], v[170:173], v[194:197], v[16:19]
	v_mfma_f32_16x16x32_bf16 v[4:7], v[162:165], v[202:205], v[4:7]
	v_mfma_f32_16x16x32_bf16 v[0:3], v[170:173], v[202:205], v[0:3]
	v_mfma_f32_16x16x32_bf16 v[52:55], v[166:169], v[182:185], v[52:55]
	v_mfma_f32_16x16x32_bf16 v[48:51], v[174:177], v[182:185], v[48:51]
	v_mfma_f32_16x16x32_bf16 v[36:39], v[166:169], v[190:193], v[36:39]
	v_mfma_f32_16x16x32_bf16 v[32:35], v[174:177], v[190:193], v[32:35]
	v_mfma_f32_16x16x32_bf16 v[20:23], v[166:169], v[198:201], v[20:23]
	v_mfma_f32_16x16x32_bf16 v[16:19], v[174:177], v[198:201], v[16:19]
	v_mfma_f32_16x16x32_bf16 v[4:7], v[166:169], v[206:209], v[4:7]
	v_mfma_f32_16x16x32_bf16 v[0:3], v[174:177], v[206:209], v[0:3]
	s_setprio 0
	s_barrier
	s_add_i32 s55, s55, 2
	s_add_u32 s30, s30, 0x100
	s_addc_u32 s31, s31, 0
	s_add_u32 s53, s53, 0x100
	s_addc_u32 s54, s54, 0
	s_cmp_gt_u32 s55, 13
.LBB0_804:
	ds_read_b128 v[140:143], v159
	ds_read_b128 v[144:147], v159 offset:1024
	ds_read_b128 v[148:151], v159 offset:2048
	ds_read_b128 v[152:155], v159 offset:3072
	ds_read_b128 v[162:165], v160
	ds_read_b128 v[166:169], v160 offset:1024
	ds_read_b128 v[170:173], v160 offset:2048
	ds_read_b128 v[174:177], v160 offset:3072
	s_add_u32 s34, s30, 0xfffc0080
	s_addc_u32 s35, s31, -1
	s_cmp_eq_u32 s55, 12
	s_cselect_b32 s37, s19, s35
	s_cselect_b32 s36, s51, s34
	s_cselect_b32 s35, s17, s54
	s_cselect_b32 s34, s52, s53
	s_add_i32 m0, s27, 0xc000
	ds_read_b128 v[178:181], v161
	ds_read_b128 v[182:185], v161 offset:1024
	ds_read_b128 v[186:189], v161 offset:2048
	ds_read_b128 v[190:193], v161 offset:3072
	ds_read_b128 v[194:197], v161 offset:4096
	ds_read_b128 v[198:201], v161 offset:5120
	ds_read_b128 v[202:205], v161 offset:6144
	ds_read_b128 v[206:209], v161 offset:7168
	global_load_lds_dwordx4 v136, s[30:31]
	s_add_i32 m0, s27, 0xe000
	s_nop 0
	global_load_lds_dwordx4 v138, s[30:31]
	s_waitcnt vmcnt(8)
	s_waitcnt lgkmcnt(0)
	s_barrier
; #define PG8_STAGE(bufoff, gbase, voff) do { _Pragma("unroll") for (int _i = 0; _i < 2; ++_i) \
;         __builtin_amdgcn_global_load_lds((const unsigned*)((const char*)(gbase) + (voff)[_i]), (LAS unsigned*)(lds + (bufoff) + ldsw + _i * 8192), 16, 0, 0); } while (0)
; #define PG8_LDA(dst, b, h) do { _Pragma("unroll") for (int m = 0; m < 4; ++m) _Pragma("unroll") for (int k = 0; k < 2; ++k) dst[m][k] = *(const LAS bf16x8*)(lds + PG8_SA(b, h) + aoff + m * 2048 + k * 1024); } while (0)
; #define PG8_MMA(ai, bj, At, Bt) do { __builtin_amdgcn_s_setprio(1); _Pragma("unroll") for (int m = 0; m < 4; ++m) _Pragma("unroll") for (int n = 0; n < 2; ++n) _Pragma("unroll") for (int k = 0; k < 2; ++k) \
;         acc[ai][bj][m][n] = __builtin_amdgcn_mfma_f32_16x16x32_bf16(Bt[n][k], At[m][k], acc[ai][bj][m][n], 0, 0, 0); __builtin_amdgcn_s_setprio(0); } while (0)
; #define PG8_WAIT_V(n) asm volatile("s_waitcnt vmcnt(" #n ")" ::: "memory")
; #define PG8_WAIT_L(n) asm volatile("s_waitcnt lgkmcnt(" #n ")" ::: "memory")
; #define PG8_BAR __builtin_amdgcn_s_barrier()
; #define PG8_SCHED __builtin_amdgcn_sched_barrier(0)
; template <class Epi, class Sched>
; __device__ __forceinline__ void gemm_phase(LAS unsigned char* lds, const Gemm g, const Sched& S, const Epi& E, int wave_id) {
;     ...
;             PG8_WAIT_V(8); PG8_WAIT_L(0); PG8_BAR; PG8_MMA(0, 0, At, B0); PG8_MMA(0, 1, At, B1); PG8_BAR; PG8_SCHED;
;             PG8_LDA(At, 0, 1); PG8_STAGE(PG8_SB(0, 0), b2, voffB); PG8_STAGE(PG8_SB(0, 1), b2 + hstepB, voffB); PG8_STAGE(PG8_SA(0, 0), a2, voffA);
;             PG8_WAIT_V(8); PG8_WAIT_L(0); PG8_BAR; PG8_MMA(1, 0, At, B0); PG8_MMA(1, 1, At, B1); PG8_BAR; PG8_SCHED;
	s_setprio 1
	s_waitcnt lgkmcnt(0)
	v_mfma_f32_16x16x32_bf16 v[124:127], v[140:143], v[178:181], v[124:127]
	v_mfma_f32_16x16x32_bf16 v[120:123], v[148:151], v[178:181], v[120:123]
	v_mfma_f32_16x16x32_bf16 v[108:111], v[140:143], v[186:189], v[108:111]
	v_mfma_f32_16x16x32_bf16 v[104:107], v[148:151], v[186:189], v[104:107]
	v_mfma_f32_16x16x32_bf16 v[92:95], v[140:143], v[194:197], v[92:95]
	v_mfma_f32_16x16x32_bf16 v[88:91], v[148:151], v[194:197], v[88:91]
	v_mfma_f32_16x16x32_bf16 v[76:79], v[140:143], v[202:205], v[76:79]
	v_mfma_f32_16x16x32_bf16 v[72:75], v[148:151], v[202:205], v[72:75]
	v_mfma_f32_16x16x32_bf16 v[124:127], v[144:147], v[182:185], v[124:127]
	v_mfma_f32_16x16x32_bf16 v[120:123], v[152:155], v[182:185], v[120:123]
	v_mfma_f32_16x16x32_bf16 v[108:111], v[144:147], v[190:193], v[108:111]
	v_mfma_f32_16x16x32_bf16 v[104:107], v[152:155], v[190:193], v[104:107]
	v_mfma_f32_16x16x32_bf16 v[92:95], v[144:147], v[198:201], v[92:95]
	v_mfma_f32_16x16x32_bf16 v[88:91], v[152:155], v[198:201], v[88:91]
	v_mfma_f32_16x16x32_bf16 v[76:79], v[144:147], v[206:209], v[76:79]
	v_mfma_f32_16x16x32_bf16 v[72:75], v[152:155], v[206:209], v[72:75]
	s_setprio 0
	s_setprio 1
	v_mfma_f32_16x16x32_bf16 v[116:119], v[162:165], v[178:181], v[116:119]
	v_mfma_f32_16x16x32_bf16 v[112:115], v[170:173], v[178:181], v[112:115]
	v_mfma_f32_16x16x32_bf16 v[100:103], v[162:165], v[186:189], v[100:103]
	v_mfma_f32_16x16x32_bf16 v[96:99], v[170:173], v[186:189], v[96:99]
	v_mfma_f32_16x16x32_bf16 v[84:87], v[162:165], v[194:197], v[84:87]
	v_mfma_f32_16x16x32_bf16 v[80:83], v[170:173], v[194:197], v[80:83]
	v_mfma_f32_16x16x32_bf16 v[68:71], v[162:165], v[202:205], v[68:71]
	v_mfma_f32_16x16x32_bf16 v[64:67], v[170:173], v[202:205], v[64:67]
	v_mfma_f32_16x16x32_bf16 v[116:119], v[166:169], v[182:185], v[116:119]
	v_mfma_f32_16x16x32_bf16 v[112:115], v[174:177], v[182:185], v[112:115]
	v_mfma_f32_16x16x32_bf16 v[100:103], v[166:169], v[190:193], v[100:103]
	v_mfma_f32_16x16x32_bf16 v[96:99], v[174:177], v[190:193], v[96:99]
	v_mfma_f32_16x16x32_bf16 v[84:87], v[166:169], v[198:201], v[84:87]
	v_mfma_f32_16x16x32_bf16 v[80:83], v[174:177], v[198:201], v[80:83]
	v_mfma_f32_16x16x32_bf16 v[68:71], v[166:169], v[206:209], v[68:71]
	v_mfma_f32_16x16x32_bf16 v[64:67], v[174:177], v[206:209], v[64:67]
	s_setprio 0
	s_barrier
	s_add_i32 s58, s48, s39
	v_lshl_add_u64 v[210:211], s[34:35], 0, v[130:131]
	s_mov_b32 m0, s58
	ds_read_b128 v[178:181], v161 offset:16384
	ds_read_b128 v[182:185], v161 offset:17408
	ds_read_b128 v[186:189], v161 offset:18432
	ds_read_b128 v[190:193], v161 offset:19456
	ds_read_b128 v[194:197], v161 offset:20480
	ds_read_b128 v[198:201], v161 offset:21504
	ds_read_b128 v[202:205], v161 offset:22528
	ds_read_b128 v[206:209], v161 offset:23552
	global_load_lds_dwordx4 v[210:211], off
	s_add_i32 m0, s58, 0x2000
	s_add_u32 s58, s34, 0x40000
	v_lshl_add_u64 v[212:213], s[34:35], 0, v[134:135]
	s_addc_u32 s59, s35, 0
	s_add_i32 s60, s49, s39
	global_load_lds_dwordx4 v[212:213], off
	s_mov_b32 m0, s60
	v_lshl_add_u64 v[216:217], s[36:37], 0, v[132:133]
	global_load_lds_dwordx4 v130, s[58:59]
	s_add_i32 m0, s60, 0x2000
	s_nop 0
	global_load_lds_dwordx4 v134, s[58:59]
	v_lshl_add_u64 v[214:215], s[36:37], 0, v[128:129]
	s_mov_b32 m0, s27
	s_nop 0
	global_load_lds_dwordx4 v[214:215], off
	s_mov_b32 m0, s29
	s_nop 0
	global_load_lds_dwordx4 v[216:217], off
	s_waitcnt vmcnt(8)
	s_waitcnt lgkmcnt(0)
	s_barrier
	s_setprio 1
	s_waitcnt lgkmcnt(0)
	v_mfma_f32_16x16x32_bf16 v[60:63], v[140:143], v[178:181], v[60:63]
	v_mfma_f32_16x16x32_bf16 v[56:59], v[148:151], v[178:181], v[56:59]
	v_mfma_f32_16x16x32_bf16 v[44:47], v[140:143], v[186:189], v[44:47]
	v_mfma_f32_16x16x32_bf16 v[40:43], v[148:151], v[186:189], v[40:43]
	v_mfma_f32_16x16x32_bf16 v[28:31], v[140:143], v[194:197], v[28:31]
	v_mfma_f32_16x16x32_bf16 v[24:27], v[148:151], v[194:197], v[24:27]
	v_mfma_f32_16x16x32_bf16 v[12:15], v[140:143], v[202:205], v[12:15]
	v_mfma_f32_16x16x32_bf16 v[8:11], v[148:151], v[202:205], v[8:11]
	v_mfma_f32_16x16x32_bf16 v[60:63], v[144:147], v[182:185], v[60:63]
	v_mfma_f32_16x16x32_bf16 v[56:59], v[152:155], v[182:185], v[56:59]
	v_mfma_f32_16x16x32_bf16 v[44:47], v[144:147], v[190:193], v[44:47]
	v_mfma_f32_16x16x32_bf16 v[40:43], v[152:155], v[190:193], v[40:43]
	v_mfma_f32_16x16x32_bf16 v[28:31], v[144:147], v[198:201], v[28:31]
	v_mfma_f32_16x16x32_bf16 v[24:27], v[152:155], v[198:201], v[24:27]
	v_mfma_f32_16x16x32_bf16 v[12:15], v[144:147], v[206:209], v[12:15]
	v_mfma_f32_16x16x32_bf16 v[8:11], v[152:155], v[206:209], v[8:11]
	s_setprio 0
	s_setprio 1
	v_mfma_f32_16x16x32_bf16 v[52:55], v[162:165], v[178:181], v[52:55]
	v_mfma_f32_16x16x32_bf16 v[48:51], v[170:173], v[178:181], v[48:51]
	v_mfma_f32_16x16x32_bf16 v[36:39], v[162:165], v[186:189], v[36:39]
	v_mfma_f32_16x16x32_bf16 v[32:35], v[170:173], v[186:189], v[32:35]
	v_mfma_f32_16x16x32_bf16 v[20:23], v[162:165], v[194:197], v[20:23]
	v_mfma_f32_16x16x32_bf16 v[16:19], v[170:173], v[194:197], v[16:19]
	v_mfma_f32_16x16x32_bf16 v[4:7], v[162:165], v[202:205], v[4:7]
	v_mfma_f32_16x16x32_bf16 v[0:3], v[170:173], v[202:205], v[0:3]
	v_mfma_f32_16x16x32_bf16 v[52:55], v[166:169], v[182:185], v[52:55]
	v_mfma_f32_16x16x32_bf16 v[48:51], v[174:177], v[182:185], v[48:51]
	v_mfma_f32_16x16x32_bf16 v[36:39], v[166:169], v[190:193], v[36:39]
	v_mfma_f32_16x16x32_bf16 v[32:35], v[174:177], v[190:193], v[32:35]
	v_mfma_f32_16x16x32_bf16 v[20:23], v[166:169], v[198:201], v[20:23]
	v_mfma_f32_16x16x32_bf16 v[16:19], v[174:177], v[198:201], v[16:19]
	v_mfma_f32_16x16x32_bf16 v[4:7], v[166:169], v[206:209], v[4:7]
	v_mfma_f32_16x16x32_bf16 v[0:3], v[174:177], v[206:209], v[0:3]
	s_setprio 0
	s_barrier
; #define PG8_STAGE(bufoff, gbase, voff) do { _Pragma("unroll") for (int _i = 0; _i < 2; ++_i) \
;         __builtin_amdgcn_global_load_lds((const unsigned*)((const char*)(gbase) + (voff)[_i]), (LAS unsigned*)(lds + (bufoff) + ldsw + _i * 8192), 16, 0, 0); } while (0)
; #define PG8_LDA(dst, b, h) do { _Pragma("unroll") for (int m = 0; m < 4; ++m) _Pragma("unroll") for (int k = 0; k < 2; ++k) dst[m][k] = *(const LAS bf16x8*)(lds + PG8_SA(b, h) + aoff + m * 2048 + k * 1024); } while (0)
; #define PG8_LDB(dst, b, h) do { _Pragma("unroll") for (int n = 0; n < 2; ++n) _Pragma("unroll") for (int k = 0; k < 2; ++k) dst[n][k] = *(const LAS bf16x8*)(lds + PG8_SB(b, h) + boff + n * 2048 + k * 1024); } while (0)
; #define PG8_MMA(ai, bj, At, Bt) do { __builtin_amdgcn_s_setprio(1); _Pragma("unroll") for (int m = 0; m < 4; ++m) _Pragma("unroll") for (int n = 0; n < 2; ++n) _Pragma("unroll") for (int k = 0; k < 2; ++k) \
;         acc[ai][bj][m][n] = __builtin_amdgcn_mfma_f32_16x16x32_bf16(Bt[n][k], At[m][k], acc[ai][bj][m][n], 0, 0, 0); __builtin_amdgcn_s_setprio(0); } while (0)
; #define PG8_WAIT_V(n) asm volatile("s_waitcnt vmcnt(" #n ")" ::: "memory")
; #define PG8_WAIT_L(n) asm volatile("s_waitcnt lgkmcnt(" #n ")" ::: "memory")
; #define PG8_BAR __builtin_amdgcn_s_barrier()
; #define PG8_SCHED __builtin_amdgcn_sched_barrier(0)
; template <class Epi, class Sched>
; __device__ __forceinline__ void gemm_phase(LAS unsigned char* lds, const Gemm g, const Sched& S, const Epi& E, int wave_id) {
;     ...
;             PG8_LDB(B0, 1, 0); PG8_LDB(B1, 1, 1); PG8_SCHED; PG8_LDA(At, 1, 0); PG8_STAGE(PG8_SA(0, 1), a2 + hstepA, voffA);
;             PG8_WAIT_V(8); PG8_WAIT_L(0); PG8_BAR; PG8_MMA(0, 0, At, B0); PG8_MMA(0, 1, At, B1); PG8_BAR; PG8_SCHED;
;             PG8_LDA(At, 1, 1); PG8_STAGE(PG8_SB(1, 0), b3, voffB); PG8_STAGE(PG8_SB(1, 1), b3 + hstepB, voffB); PG8_STAGE(PG8_SA(1, 0), a3, voffA);
;             PG8_WAIT_V(8); PG8_WAIT_L(0); PG8_BAR; PG8_MMA(1, 0, At, B0); PG8_MMA(1, 1, At, B1); PG8_BAR; PG8_SCHED;
;         }
;         if (wr == 0) PG8_BAR;
	s_add_i32 s58, 0, 0x18000
	s_add_i32 s59, 0, 0x1c000
	v_add_u32_e32 v152, s58, v157
	v_add_u32_e32 v174, s59, v157
	ds_read_b128 v[140:143], v152
	ds_read_b128 v[144:147], v152 offset:1024
	ds_read_b128 v[148:151], v152 offset:2048
	ds_read_b128 v[152:155], v152 offset:3072
	ds_read_b128 v[162:165], v174
	ds_read_b128 v[166:169], v174 offset:1024
	ds_read_b128 v[170:173], v174 offset:2048
	ds_read_b128 v[174:177], v174 offset:3072
	s_add_u32 s36, s36, 0x40000
	s_addc_u32 s37, s37, 0
	s_mov_b32 m0, s44
	ds_read_b128 v[178:181], v161 offset:32768
	ds_read_b128 v[182:185], v161 offset:33792
	ds_read_b128 v[186:189], v161 offset:34816
	ds_read_b128 v[190:193], v161 offset:35840
	ds_read_b128 v[194:197], v161 offset:36864
	ds_read_b128 v[198:201], v161 offset:37888
	ds_read_b128 v[202:205], v161 offset:38912
	ds_read_b128 v[206:209], v161 offset:39936
	global_load_lds_dwordx4 v128, s[36:37]
	s_mov_b32 m0, s45
	s_nop 0
	global_load_lds_dwordx4 v132, s[36:37]
	s_waitcnt vmcnt(8)
	s_waitcnt lgkmcnt(0)
	s_barrier
	s_setprio 1
	s_waitcnt lgkmcnt(0)
	v_mfma_f32_16x16x32_bf16 v[124:127], v[140:143], v[178:181], v[124:127]
	v_mfma_f32_16x16x32_bf16 v[120:123], v[148:151], v[178:181], v[120:123]
	v_mfma_f32_16x16x32_bf16 v[108:111], v[140:143], v[186:189], v[108:111]
	v_mfma_f32_16x16x32_bf16 v[104:107], v[148:151], v[186:189], v[104:107]
	v_mfma_f32_16x16x32_bf16 v[92:95], v[140:143], v[194:197], v[92:95]
	v_mfma_f32_16x16x32_bf16 v[88:91], v[148:151], v[194:197], v[88:91]
	v_mfma_f32_16x16x32_bf16 v[76:79], v[140:143], v[202:205], v[76:79]
	v_mfma_f32_16x16x32_bf16 v[72:75], v[148:151], v[202:205], v[72:75]
	v_mfma_f32_16x16x32_bf16 v[124:127], v[144:147], v[182:185], v[124:127]
	v_mfma_f32_16x16x32_bf16 v[120:123], v[152:155], v[182:185], v[120:123]
	v_mfma_f32_16x16x32_bf16 v[108:111], v[144:147], v[190:193], v[108:111]
	v_mfma_f32_16x16x32_bf16 v[104:107], v[152:155], v[190:193], v[104:107]
	v_mfma_f32_16x16x32_bf16 v[92:95], v[144:147], v[198:201], v[92:95]
	v_mfma_f32_16x16x32_bf16 v[88:91], v[152:155], v[198:201], v[88:91]
	v_mfma_f32_16x16x32_bf16 v[76:79], v[144:147], v[206:209], v[76:79]
	v_mfma_f32_16x16x32_bf16 v[72:75], v[152:155], v[206:209], v[72:75]
	s_setprio 0
	s_setprio 1
	v_mfma_f32_16x16x32_bf16 v[116:119], v[162:165], v[178:181], v[116:119]
	v_mfma_f32_16x16x32_bf16 v[112:115], v[170:173], v[178:181], v[112:115]
	v_mfma_f32_16x16x32_bf16 v[100:103], v[162:165], v[186:189], v[100:103]
	v_mfma_f32_16x16x32_bf16 v[96:99], v[170:173], v[186:189], v[96:99]
	v_mfma_f32_16x16x32_bf16 v[84:87], v[162:165], v[194:197], v[84:87]
	v_mfma_f32_16x16x32_bf16 v[80:83], v[170:173], v[194:197], v[80:83]
	v_mfma_f32_16x16x32_bf16 v[68:71], v[162:165], v[202:205], v[68:71]
	v_mfma_f32_16x16x32_bf16 v[64:67], v[170:173], v[202:205], v[64:67]
	v_mfma_f32_16x16x32_bf16 v[116:119], v[166:169], v[182:185], v[116:119]
	v_mfma_f32_16x16x32_bf16 v[112:115], v[174:177], v[182:185], v[112:115]
	v_mfma_f32_16x16x32_bf16 v[100:103], v[166:169], v[190:193], v[100:103]
	v_mfma_f32_16x16x32_bf16 v[96:99], v[174:177], v[190:193], v[96:99]
	v_mfma_f32_16x16x32_bf16 v[84:87], v[166:169], v[198:201], v[84:87]
	v_mfma_f32_16x16x32_bf16 v[80:83], v[174:177], v[198:201], v[80:83]
	v_mfma_f32_16x16x32_bf16 v[68:71], v[166:169], v[206:209], v[68:71]
	v_mfma_f32_16x16x32_bf16 v[64:67], v[174:177], v[206:209], v[64:67]
	s_setprio 0
	s_barrier
	s_add_i32 s36, s58, s39
	v_lshl_add_u64 v[210:211], v[210:211], 0, s[8:9]
	s_mov_b32 m0, s36
	ds_read_b128 v[178:181], v161 offset:49152
	ds_read_b128 v[182:185], v161 offset:50176
	ds_read_b128 v[186:189], v161 offset:51200
	ds_read_b128 v[190:193], v161 offset:52224
	ds_read_b128 v[194:197], v161 offset:53248
	ds_read_b128 v[198:201], v161 offset:54272
	ds_read_b128 v[202:205], v161 offset:55296
	ds_read_b128 v[206:209], v161 offset:56320
	global_load_lds_dwordx4 v[210:211], off
	s_add_i32 m0, s36, 0x2000
	s_add_u32 s34, s34, 0x40080
	v_lshl_add_u64 v[210:211], v[212:213], 0, s[8:9]
	s_addc_u32 s35, s35, 0
	s_add_i32 s36, s59, s39
	global_load_lds_dwordx4 v[210:211], off
	s_mov_b32 m0, s36
	s_nop 0
	global_load_lds_dwordx4 v130, s[34:35]
	s_add_i32 m0, s36, 0x2000
	s_nop 0
	global_load_lds_dwordx4 v134, s[34:35]
	v_lshl_add_u64 v[210:211], v[214:215], 0, s[8:9]
	s_mov_b32 m0, s46
	s_nop 0
	global_load_lds_dwordx4 v[210:211], off
	v_lshl_add_u64 v[210:211], v[216:217], 0, s[8:9]
	s_mov_b32 m0, s47
	s_nop 0
	global_load_lds_dwordx4 v[210:211], off
	s_waitcnt vmcnt(8)
	s_waitcnt lgkmcnt(0)
	s_barrier
	s_setprio 1
	s_waitcnt lgkmcnt(0)
	v_mfma_f32_16x16x32_bf16 v[60:63], v[140:143], v[178:181], v[60:63]
	v_mfma_f32_16x16x32_bf16 v[56:59], v[148:151], v[178:181], v[56:59]
	v_mfma_f32_16x16x32_bf16 v[44:47], v[140:143], v[186:189], v[44:47]
	v_mfma_f32_16x16x32_bf16 v[40:43], v[148:151], v[186:189], v[40:43]
	v_mfma_f32_16x16x32_bf16 v[28:31], v[140:143], v[194:197], v[28:31]
	v_mfma_f32_16x16x32_bf16 v[24:27], v[148:151], v[194:197], v[24:27]
	v_mfma_f32_16x16x32_bf16 v[12:15], v[140:143], v[202:205], v[12:15]
	v_mfma_f32_16x16x32_bf16 v[8:11], v[148:151], v[202:205], v[8:11]
	v_mfma_f32_16x16x32_bf16 v[60:63], v[144:147], v[182:185], v[60:63]
	v_mfma_f32_16x16x32_bf16 v[56:59], v[152:155], v[182:185], v[56:59]
	v_mfma_f32_16x16x32_bf16 v[44:47], v[144:147], v[190:193], v[44:47]
	v_mfma_f32_16x16x32_bf16 v[40:43], v[152:155], v[190:193], v[40:43]
	v_mfma_f32_16x16x32_bf16 v[28:31], v[144:147], v[198:201], v[28:31]
	v_mfma_f32_16x16x32_bf16 v[24:27], v[152:155], v[198:201], v[24:27]
	v_mfma_f32_16x16x32_bf16 v[12:15], v[144:147], v[206:209], v[12:15]
	v_mfma_f32_16x16x32_bf16 v[8:11], v[152:155], v[206:209], v[8:11]
	s_setprio 0
	s_setprio 1
	v_mfma_f32_16x16x32_bf16 v[52:55], v[162:165], v[178:181], v[52:55]
	v_mfma_f32_16x16x32_bf16 v[48:51], v[170:173], v[178:181], v[48:51]
	v_mfma_f32_16x16x32_bf16 v[36:39], v[162:165], v[186:189], v[36:39]
	v_mfma_f32_16x16x32_bf16 v[32:35], v[170:173], v[186:189], v[32:35]
	v_mfma_f32_16x16x32_bf16 v[20:23], v[162:165], v[194:197], v[20:23]
	v_mfma_f32_16x16x32_bf16 v[16:19], v[170:173], v[194:197], v[16:19]
	v_mfma_f32_16x16x32_bf16 v[4:7], v[162:165], v[202:205], v[4:7]
	v_mfma_f32_16x16x32_bf16 v[0:3], v[170:173], v[202:205], v[0:3]
	v_mfma_f32_16x16x32_bf16 v[52:55], v[166:169], v[182:185], v[52:55]
	v_mfma_f32_16x16x32_bf16 v[48:51], v[174:177], v[182:185], v[48:51]
	v_mfma_f32_16x16x32_bf16 v[36:39], v[166:169], v[190:193], v[36:39]
	v_mfma_f32_16x16x32_bf16 v[32:35], v[174:177], v[190:193], v[32:35]
	v_mfma_f32_16x16x32_bf16 v[20:23], v[166:169], v[198:201], v[20:23]
	v_mfma_f32_16x16x32_bf16 v[16:19], v[174:177], v[198:201], v[16:19]
	v_mfma_f32_16x16x32_bf16 v[4:7], v[166:169], v[206:209], v[4:7]
	v_mfma_f32_16x16x32_bf16 v[0:3], v[174:177], v[206:209], v[0:3]
	s_setprio 0
	s_barrier
	s_add_i32 s55, s55, 2
	s_add_u32 s30, s30, 0x100
	s_addc_u32 s31, s31, 0
	s_add_u32 s53, s53, 0x100
	s_addc_u32 s54, s54, 0
	s_cmp_gt_u32 s55, 13
	s_cbranch_scc0 .LBB0_804
	s_and_b64 vcc, exec, s[10:11]
	s_cbranch_vccz .LBB0_807
	s_barrier

;     __device__ bool next(int i, Unit& u) const { if (r0 + i >= r1) return false; return base.next(r0 + i, u); }
;     __device__ bool next(int i, Unit& u) const { const int L = i * G + c; if (L >= 256) return false; u.pm = L; u.pn = L >> 3; return true; }
; #define PG8_STAGE(bufoff, gbase, voff) do { _Pragma("unroll") for (int _i = 0; _i < 2; ++_i) \
;         __builtin_amdgcn_global_load_lds((const unsigned*)((const char*)(gbase) + (voff)[_i]), (LAS unsigned*)(lds + (bufoff) + ldsw + _i * 8192), 16, 0, 0); } while (0)
; #define PG8_WAIT_V(n) asm volatile("s_waitcnt vmcnt(" #n ")" ::: "memory")
; #define PG8_BAR __builtin_amdgcn_s_barrier()
;     __device__ bool next(int i, Unit& u) const {
;         const long L = (long)i * G + c; if (L >= nwg) return false;
;         int wgid = (int)L; { const int q = nwg / NXCD, r = nwg % NXCD, xcd = wgid % NXCD, off = wgid / NXCD; wgid = (xcd < r ? xcd * (q + 1) : r * (q + 1) + (xcd - r) * q) + off; }
;         const int nig = WGM * nN, gid = wgid / nig, fm = gid * WGM, gsz = (nM - fm) < WGM ? (nM - fm) : WGM;
;         u.pm = fm + ((wgid % nig) % gsz); u.pn = (wgid % nig) / gsz; return true;
; template <class Epi, class Sched>
; __device__ __forceinline__ void gemm_phase(LAS unsigned char* lds, const Gemm g, const Sched& S, const Epi& E, int wave_id) {
;     ...
;     const char* cA = (const char*)g.A + (size_t)cur.pm * tstepA; const char* cB = (const char*)g.Bt + (size_t)cur.pn * tstepB;
;     PG8_STAGE(PG8_SB(0, 0), cB, voffB); PG8_STAGE(PG8_SB(0, 1), cB + hstepB, voffB); PG8_STAGE(PG8_SA(0, 0), cA, voffA); PG8_STAGE(PG8_SA(0, 1), cA + hstepA, voffA);
;     if (wr == 1) PG8_BAR;
;     PG8_WAIT_V(2); PG8_BAR;
;     PG8_STAGE(PG8_SB(1, 0), cB + kstep, voffB); PG8_STAGE(PG8_SA(1, 0), cA + kstep, voffA); PG8_STAGE(PG8_SB(1, 1), cB + hstepB + kstep, voffB);
;     PG8_WAIT_V(6); PG8_BAR;
;     for (;;) {
;         const bool has_next = S.next(ui + 1, nxt);
;         const char* nA = has_next ? (const char*)g.A + (size_t)nxt.pm * tstepA : cA; const char* nB = has_next ? (const char*)g.Bt + (size_t)nxt.pn * tstepB : cB;
.LBB0_859:
	v_lshrrev_b32_e32 v16, 1, v14
	v_and_b32_e32 v16, 24, v16
	v_and_b32_e32 v15, 15, v14
	v_lshlrev_b32_e32 v17, 1, v16
	v_lshlrev_b32_e32 v14, 2, v14
	v_lshl_or_b32 v156, s8, 6, v15
	v_lshl_or_b32 v15, v15, 6, v17
	s_lshl_b32 s8, s8, 13
	v_and_b32_e32 v14, 32, v14
	v_bitop3_b32 v17, v15, s8, v14 bitop3:0xde
	s_lshl_b32 s8, s97, 5
	s_and_b32 s16, s8, 0x60
	s_lshl_b32 s8, s16, 7
	v_bitop3_b32 v157, v15, s8, v14 bitop3:0xde
	s_mov_b64 s[8:9], 0x80
	s_add_i32 m0, s27, 0x18000
	v_lshl_add_u64 v[6:7], v[6:7], 0, s[8:9]
	s_waitcnt vmcnt(2)
	s_barrier
	global_load_lds_dwordx4 v[6:7], off
	v_lshl_add_u64 v[4:5], v[4:5], 0, s[8:9]
	s_add_i32 m0, s27, 0x1a000
	s_add_i32 s41, s27, 0x8000
	s_add_i32 s42, s27, 0xa000
	global_load_lds_dwordx4 v[4:5], off
	v_lshl_add_u64 v[0:1], v[0:1], 0, s[8:9]
	s_mov_b32 m0, s41
	s_add_u32 s10, s34, 0x40080
	global_load_lds_dwordx4 v[0:1], off
	v_lshl_add_u64 v[0:1], v[2:3], 0, s[8:9]
	s_mov_b32 m0, s42
	s_addc_u32 s11, s35, 0
	global_load_lds_dwordx4 v[0:1], off
	s_add_i32 m0, s27, 0x1c000
	s_nop 0
	global_load_lds_dwordx4 v130, s[10:11]
	s_add_i32 m0, s27, 0x1e000
	s_cmpk_lt_u32 s80, 0x100
	global_load_lds_dwordx4 v134, s[10:11]
	s_cselect_b64 s[10:11], -1, 0
	s_add_u32 s12, s92, 0x1f400000
	s_addc_u32 s13, s93, 0
	s_add_u32 s14, s92, 0xb400000
	s_addc_u32 s15, s93, 0
	s_mul_hi_i32 s17, s4, 3
	s_mul_i32 s4, s4, 3
	s_add_u32 s4, s4, s66
	s_addc_u32 s5, s17, s5
	s_ashr_i32 s17, s4, 31
	s_lshr_b32 s17, s17, 29
	s_add_i32 s17, s4, s17
	s_ashr_i32 s18, s17, 3
	s_and_b32 s17, s17, -8
	s_sub_i32 s17, s4, s17
	s_lshl_b32 s19, s17, 7
	s_cmp_lt_i32 s17, 0
	s_mulk_i32 s17, 0x81
	s_cselect_b32 s17, s17, s19
	s_add_i32 s17, s17, s18
	s_ashr_i32 s18, s17, 31
	s_lshr_b32 s18, s18, 26
	s_add_i32 s18, s17, s18
	s_ashr_i32 s19, s18, 6
	s_lshl_b32 s19, s19, 3
	s_sub_i32 s20, 0x80, s19
	s_min_i32 s20, s20, 8
	s_abs_i32 s22, s20
	v_cvt_f32_u32_e32 v2, s22
	v_mov_b64_e32 v[0:1], 0x400
	v_cmp_lt_i64_e64 s[36:37], s[4:5], v[0:1]
	s_andn2_b32 s18, s18, 63
	v_rcp_iflag_f32_e32 v0, v2
	s_sub_i32 s4, s17, s18
	s_sub_i32 s17, 0, s22
	v_or_b32_e32 v158, s16, v16
	v_mul_f32_e32 v0, 0x4f7ffffe, v0
	v_cvt_u32_f32_e32 v0, v0
	s_abs_i32 s16, s4
	s_xor_b32 s5, s4, s20
	s_ashr_i32 s5, s5, 31
	v_readfirstlane_b32 s18, v0
	s_mul_i32 s17, s17, s18
	s_mul_hi_u32 s17, s18, s17
	s_add_i32 s18, s18, s17
	s_mul_hi_u32 s17, s16, s18
	s_mul_i32 s18, s17, s22
	s_sub_i32 s16, s16, s18
	s_add_i32 s18, s17, 1
	s_sub_i32 s23, s16, s22
	s_cmp_ge_u32 s16, s22
	s_cselect_b32 s17, s18, s17
	v_lshlrev_b32_e32 v0, 14, v8
	s_cselect_b32 s16, s23, s16
	s_add_i32 s18, s17, 1
	v_and_b32_e32 v0, 0xffff8000, v0
	s_cmp_ge_u32 s16, s22
	v_lshl_add_u32 v0, v9, 11, v0
	v_and_b32_e32 v1, 1, v8
	s_cselect_b32 s16, s18, s17
	v_lshl_or_b32 v0, v1, 6, v0
	s_xor_b32 s16, s16, s5
	v_lshl_add_u32 v136, v10, 1, v0
	v_lshlrev_b32_e32 v0, 14, v11
	s_sub_i32 s16, s16, s5
	v_and_b32_e32 v0, 0xffff8000, v0
	s_waitcnt vmcnt(6)
	s_mul_i32 s5, s16, s20
	v_lshl_add_u32 v0, v12, 11, v0
	v_and_b32_e32 v1, 1, v11
	s_sub_i32 s4, s4, s5
	v_lshl_or_b32 v0, v1, 6, v0
	s_add_i32 s43, 0, 0x10000
	s_add_i32 s44, 0, 0x14000
	s_add_i32 s18, s19, s4
	v_mov_b32_e32 v137, v131
	v_lshl_add_u32 v138, v13, 1, v0
	v_mov_b32_e32 v139, v131
	v_add_u32_e32 v159, s43, v157
	v_add_u32_e32 v160, s44, v157
	v_add_u32_e32 v161, 0, v17
	s_mov_b32 s20, 0x437f0000
	s_mov_b32 s45, 0xb400000
	s_barrier
	s_branch .LBB0_862

;     __device__ bool next(int i, Unit& u) const { if (r0 + i >= r1) return false; return base.next(r0 + i, u); }
;     __device__ bool next(int i, Unit& u) const { const int L = i * G + c; if (L >= 256) return false; u.pm = L; u.pn = L >> 3; return true; }
; #define PG8_STAGE(bufoff, gbase, voff) do { _Pragma("unroll") for (int _i = 0; _i < 2; ++_i) \
;         __builtin_amdgcn_global_load_lds((const unsigned*)((const char*)(gbase) + (voff)[_i]), (LAS unsigned*)(lds + (bufoff) + ldsw + _i * 8192), 16, 0, 0); } while (0)
; #define PG8_LDA(dst, b, h) do { _Pragma("unroll") for (int m = 0; m < 4; ++m) _Pragma("unroll") for (int k = 0; k < 2; ++k) dst[m][k] = *(const LAS bf16x8*)(lds + PG8_SA(b, h) + aoff + m * 2048 + k * 1024); } while (0)
; #define PG8_LDB(dst, b, h) do { _Pragma("unroll") for (int n = 0; n < 2; ++n) _Pragma("unroll") for (int k = 0; k < 2; ++k) dst[n][k] = *(const LAS bf16x8*)(lds + PG8_SB(b, h) + boff + n * 2048 + k * 1024); } while (0)
; #define PG8_WAIT_V(n) asm volatile("s_waitcnt vmcnt(" #n ")" ::: "memory")
; #define PG8_WAIT_L(n) asm volatile("s_waitcnt lgkmcnt(" #n ")" ::: "memory")
; template <class Epi, class Sched>
; __device__ __forceinline__ void gemm_phase(LAS unsigned char* lds, const Gemm g, const Sched& S, const Epi& E, int wave_id) {
;     ...
;         const bool has_next = S.next(ui + 1, nxt);
;         const char* nA = has_next ? (const char*)g.A + (size_t)nxt.pm * tstepA : cA; const char* nB = has_next ? (const char*)g.Bt + (size_t)nxt.pn * tstepB : cB;
;         for (int t = 0; t < nt; t += 2) {
;             const bool last = (t == nt - 2);
;             const char* a1 = cA + (size_t)(t + 1) * kstep;
;             const char* a2 = last ? nA : cA + (size_t)(t + 2) * kstep; const char* b2 = last ? nB : cB + (size_t)(t + 2) * kstep;
;             const char* a3 = a2 + kstep; const char* b3 = b2 + kstep;
;             PG8_LDB(B0, 0, 0); PG8_LDB(B1, 0, 1); PG8_SCHED; PG8_LDA(At, 0, 0); PG8_STAGE(PG8_SA(1, 1), a1 + hstepA, voffA);
;             PG8_WAIT_V(8); PG8_WAIT_L(0); PG8_BAR; PG8_MMA(0, 0, At, B0); PG8_MMA(0, 1, At, B1); PG8_BAR; PG8_SCHED;
;             PG8_LDA(At, 0, 1); PG8_STAGE(PG8_SB(0, 0), b2, voffB); PG8_STAGE(PG8_SB(0, 1), b2 + hstepB, voffB); PG8_STAGE(PG8_SA(0, 0), a2, voffA);
;             PG8_WAIT_V(8); PG8_WAIT_L(0); PG8_BAR; PG8_MMA(1, 0, At, B0); PG8_MMA(1, 1, At, B1); PG8_BAR; PG8_SCHED;
.LBB0_862:
	s_ashr_i32 s19, s18, 31
	s_andn2_b64 vcc, exec, s[36:37]
	s_lshl_b64 s[22:23], s[18:19], 19
	s_add_u32 s22, s2, s22
	s_addc_u32 s23, s3, s23
	s_and_b64 s[24:25], s[36:37], exec
	s_cselect_b32 s19, s23, s31
	s_cselect_b32 s46, s22, s30
	s_ashr_i32 s17, s16, 31
	s_lshl_b64 s[24:25], s[16:17], 19
	s_add_u32 s24, s21, s24
	s_addc_u32 s25, s33, s25
	v_cndmask_b32_e64 v0, 0, 1, s[36:37]
	s_and_b64 s[36:37], s[36:37], exec
	s_cselect_b32 s17, s25, s35
	s_cselect_b32 s47, s24, s34
	s_add_u32 s30, s30, 0x40080
	s_addc_u32 s31, s31, 0
	v_cmp_ne_u32_e64 s[4:5], 1, v0
	s_add_u32 s48, s34, 0x100
	s_addc_u32 s49, s35, 0
	s_mov_b32 s50, -2
	s_waitcnt vmcnt(0)
	ds_read_b128 v[140:143], v159
	ds_read_b128 v[144:147], v159 offset:1024
	ds_read_b128 v[148:151], v159 offset:2048
	ds_read_b128 v[152:155], v159 offset:3072
	ds_read_b128 v[162:165], v160
	ds_read_b128 v[166:169], v160 offset:1024
	ds_read_b128 v[170:173], v160 offset:2048
	ds_read_b128 v[174:177], v160 offset:3072
	s_add_u32 s34, s30, 0xfffc0080
	s_addc_u32 s35, s31, -1
	s_cmp_eq_u32 s50, 12
	s_cselect_b32 s37, s19, s35
	s_cselect_b32 s36, s46, s34
	s_cselect_b32 s35, s17, s49
	s_cselect_b32 s34, s47, s48
	s_add_i32 m0, s27, 0xc000
	ds_read_b128 v[178:181], v161
	ds_read_b128 v[182:185], v161 offset:1024
	ds_read_b128 v[186:189], v161 offset:2048
	ds_read_b128 v[190:193], v161 offset:3072
	ds_read_b128 v[194:197], v161 offset:4096
	ds_read_b128 v[198:201], v161 offset:5120
	ds_read_b128 v[202:205], v161 offset:6144
	ds_read_b128 v[206:209], v161 offset:7168
	global_load_lds_dwordx4 v136, s[30:31]
	s_add_i32 m0, s27, 0xe000
	s_nop 0
	global_load_lds_dwordx4 v138, s[30:31]
	s_waitcnt vmcnt(8)
	s_waitcnt lgkmcnt(0)
	s_barrier
	s_setprio 1
	s_waitcnt lgkmcnt(0)
	v_mfma_f32_16x16x32_bf16 v[124:127], v[140:143], v[178:181], 0
	v_mfma_f32_16x16x32_bf16 v[120:123], v[148:151], v[178:181], 0
	v_mfma_f32_16x16x32_bf16 v[108:111], v[140:143], v[186:189], 0
	v_mfma_f32_16x16x32_bf16 v[104:107], v[148:151], v[186:189], 0
	v_mfma_f32_16x16x32_bf16 v[92:95], v[140:143], v[194:197], 0
	v_mfma_f32_16x16x32_bf16 v[88:91], v[148:151], v[194:197], 0
	v_mfma_f32_16x16x32_bf16 v[76:79], v[140:143], v[202:205], 0
	v_mfma_f32_16x16x32_bf16 v[72:75], v[148:151], v[202:205], 0
	v_mfma_f32_16x16x32_bf16 v[124:127], v[144:147], v[182:185], v[124:127]
	v_mfma_f32_16x16x32_bf16 v[120:123], v[152:155], v[182:185], v[120:123]
	v_mfma_f32_16x16x32_bf16 v[108:111], v[144:147], v[190:193], v[108:111]
	v_mfma_f32_16x16x32_bf16 v[104:107], v[152:155], v[190:193], v[104:107]
	v_mfma_f32_16x16x32_bf16 v[92:95], v[144:147], v[198:201], v[92:95]
	v_mfma_f32_16x16x32_bf16 v[88:91], v[152:155], v[198:201], v[88:91]
	v_mfma_f32_16x16x32_bf16 v[76:79], v[144:147], v[206:209], v[76:79]
	v_mfma_f32_16x16x32_bf16 v[72:75], v[152:155], v[206:209], v[72:75]
	s_setprio 0
	s_setprio 1
	v_mfma_f32_16x16x32_bf16 v[116:119], v[162:165], v[178:181], 0
	v_mfma_f32_16x16x32_bf16 v[112:115], v[170:173], v[178:181], 0
	v_mfma_f32_16x16x32_bf16 v[100:103], v[162:165], v[186:189], 0
	v_mfma_f32_16x16x32_bf16 v[96:99], v[170:173], v[186:189], 0
	v_mfma_f32_16x16x32_bf16 v[84:87], v[162:165], v[194:197], 0
	v_mfma_f32_16x16x32_bf16 v[80:83], v[170:173], v[194:197], 0
	v_mfma_f32_16x16x32_bf16 v[68:71], v[162:165], v[202:205], 0
	v_mfma_f32_16x16x32_bf16 v[64:67], v[170:173], v[202:205], 0
	v_mfma_f32_16x16x32_bf16 v[116:119], v[166:169], v[182:185], v[116:119]
	v_mfma_f32_16x16x32_bf16 v[112:115], v[174:177], v[182:185], v[112:115]
	v_mfma_f32_16x16x32_bf16 v[100:103], v[166:169], v[190:193], v[100:103]
	v_mfma_f32_16x16x32_bf16 v[96:99], v[174:177], v[190:193], v[96:99]
	v_mfma_f32_16x16x32_bf16 v[84:87], v[166:169], v[198:201], v[84:87]
	v_mfma_f32_16x16x32_bf16 v[80:83], v[174:177], v[198:201], v[80:83]
	v_mfma_f32_16x16x32_bf16 v[68:71], v[166:169], v[206:209], v[68:71]
	v_mfma_f32_16x16x32_bf16 v[64:67], v[174:177], v[206:209], v[64:67]
	s_setprio 0
	s_barrier
	s_add_i32 s51, s43, s38
	v_lshl_add_u64 v[210:211], s[34:35], 0, v[130:131]
	s_mov_b32 m0, s51
	ds_read_b128 v[178:181], v161 offset:16384
	ds_read_b128 v[182:185], v161 offset:17408
	ds_read_b128 v[186:189], v161 offset:18432
	ds_read_b128 v[190:193], v161 offset:19456
	ds_read_b128 v[194:197], v161 offset:20480
	ds_read_b128 v[198:201], v161 offset:21504
	ds_read_b128 v[202:205], v161 offset:22528
	ds_read_b128 v[206:209], v161 offset:23552
	global_load_lds_dwordx4 v[210:211], off
	s_add_i32 m0, s51, 0x2000
	s_add_u32 s52, s34, 0x40000
	v_lshl_add_u64 v[212:213], s[34:35], 0, v[134:135]
	s_addc_u32 s53, s35, 0
	s_add_i32 s51, s44, s38
	global_load_lds_dwordx4 v[212:213], off
	s_mov_b32 m0, s51
	v_lshl_add_u64 v[216:217], s[36:37], 0, v[132:133]
	global_load_lds_dwordx4 v130, s[52:53]
	s_add_i32 m0, s51, 0x2000
	s_nop 0
	global_load_lds_dwordx4 v134, s[52:53]
	v_lshl_add_u64 v[214:215], s[36:37], 0, v[128:129]
	s_mov_b32 m0, s27
	s_nop 0
	global_load_lds_dwordx4 v[214:215], off
	s_mov_b32 m0, s29
	s_nop 0
	global_load_lds_dwordx4 v[216:217], off
	s_waitcnt vmcnt(8)
	s_waitcnt lgkmcnt(0)
	s_barrier
; #define PG8_STAGE(bufoff, gbase, voff) do { _Pragma("unroll") for (int _i = 0; _i < 2; ++_i) \
;         __builtin_amdgcn_global_load_lds((const unsigned*)((const char*)(gbase) + (voff)[_i]), (LAS unsigned*)(lds + (bufoff) + ldsw + _i * 8192), 16, 0, 0); } while (0)
; #define PG8_LDA(dst, b, h) do { _Pragma("unroll") for (int m = 0; m < 4; ++m) _Pragma("unroll") for (int k = 0; k < 2; ++k) dst[m][k] = *(const LAS bf16x8*)(lds + PG8_SA(b, h) + aoff + m * 2048 + k * 1024); } while (0)
; #define PG8_LDB(dst, b, h) do { _Pragma("unroll") for (int n = 0; n < 2; ++n) _Pragma("unroll") for (int k = 0; k < 2; ++k) dst[n][k] = *(const LAS bf16x8*)(lds + PG8_SB(b, h) + boff + n * 2048 + k * 1024); } while (0)
; #define PG8_MMA(ai, bj, At, Bt) do { __builtin_amdgcn_s_setprio(1); _Pragma("unroll") for (int m = 0; m < 4; ++m) _Pragma("unroll") for (int n = 0; n < 2; ++n) _Pragma("unroll") for (int k = 0; k < 2; ++k) \
;         acc[ai][bj][m][n] = __builtin_amdgcn_mfma_f32_16x16x32_bf16(Bt[n][k], At[m][k], acc[ai][bj][m][n], 0, 0, 0); __builtin_amdgcn_s_setprio(0); } while (0)
; #define PG8_WAIT_V(n) asm volatile("s_waitcnt vmcnt(" #n ")" ::: "memory")
; #define PG8_WAIT_L(n) asm volatile("s_waitcnt lgkmcnt(" #n ")" ::: "memory")
; #define PG8_BAR __builtin_amdgcn_s_barrier()
; #define PG8_SCHED __builtin_amdgcn_sched_barrier(0)
; template <class Epi, class Sched>
; __device__ __forceinline__ void gemm_phase(LAS unsigned char* lds, const Gemm g, const Sched& S, const Epi& E, int wave_id) {
;     ...
;             PG8_WAIT_V(8); PG8_WAIT_L(0); PG8_BAR; PG8_MMA(1, 0, At, B0); PG8_MMA(1, 1, At, B1); PG8_BAR; PG8_SCHED;
;             PG8_LDB(B0, 1, 0); PG8_LDB(B1, 1, 1); PG8_SCHED; PG8_LDA(At, 1, 0); PG8_STAGE(PG8_SA(0, 1), a2 + hstepA, voffA);
;             PG8_WAIT_V(8); PG8_WAIT_L(0); PG8_BAR; PG8_MMA(0, 0, At, B0); PG8_MMA(0, 1, At, B1); PG8_BAR; PG8_SCHED;
	s_setprio 1
	s_waitcnt lgkmcnt(0)
	v_mfma_f32_16x16x32_bf16 v[60:63], v[140:143], v[178:181], 0
	v_mfma_f32_16x16x32_bf16 v[56:59], v[148:151], v[178:181], 0
	v_mfma_f32_16x16x32_bf16 v[44:47], v[140:143], v[186:189], 0
	v_mfma_f32_16x16x32_bf16 v[40:43], v[148:151], v[186:189], 0
	v_mfma_f32_16x16x32_bf16 v[28:31], v[140:143], v[194:197], 0
	v_mfma_f32_16x16x32_bf16 v[24:27], v[148:151], v[194:197], 0
	v_mfma_f32_16x16x32_bf16 v[12:15], v[140:143], v[202:205], 0
	v_mfma_f32_16x16x32_bf16 v[8:11], v[148:151], v[202:205], 0
	v_mfma_f32_16x16x32_bf16 v[60:63], v[144:147], v[182:185], v[60:63]
	v_mfma_f32_16x16x32_bf16 v[56:59], v[152:155], v[182:185], v[56:59]
	v_mfma_f32_16x16x32_bf16 v[44:47], v[144:147], v[190:193], v[44:47]
	v_mfma_f32_16x16x32_bf16 v[40:43], v[152:155], v[190:193], v[40:43]
	v_mfma_f32_16x16x32_bf16 v[28:31], v[144:147], v[198:201], v[28:31]
	v_mfma_f32_16x16x32_bf16 v[24:27], v[152:155], v[198:201], v[24:27]
	v_mfma_f32_16x16x32_bf16 v[12:15], v[144:147], v[206:209], v[12:15]
	v_mfma_f32_16x16x32_bf16 v[8:11], v[152:155], v[206:209], v[8:11]
	s_setprio 0
	s_setprio 1
	v_mfma_f32_16x16x32_bf16 v[52:55], v[162:165], v[178:181], 0
	v_mfma_f32_16x16x32_bf16 v[48:51], v[170:173], v[178:181], 0
	v_mfma_f32_16x16x32_bf16 v[36:39], v[162:165], v[186:189], 0
	v_mfma_f32_16x16x32_bf16 v[32:35], v[170:173], v[186:189], 0
	v_mfma_f32_16x16x32_bf16 v[20:23], v[162:165], v[194:197], 0
	v_mfma_f32_16x16x32_bf16 v[16:19], v[170:173], v[194:197], 0
	v_mfma_f32_16x16x32_bf16 v[4:7], v[162:165], v[202:205], 0
	v_mfma_f32_16x16x32_bf16 v[0:3], v[170:173], v[202:205], 0
	v_mfma_f32_16x16x32_bf16 v[52:55], v[166:169], v[182:185], v[52:55]
	v_mfma_f32_16x16x32_bf16 v[48:51], v[174:177], v[182:185], v[48:51]
	v_mfma_f32_16x16x32_bf16 v[36:39], v[166:169], v[190:193], v[36:39]
	v_mfma_f32_16x16x32_bf16 v[32:35], v[174:177], v[190:193], v[32:35]
	v_mfma_f32_16x16x32_bf16 v[20:23], v[166:169], v[198:201], v[20:23]
	v_mfma_f32_16x16x32_bf16 v[16:19], v[174:177], v[198:201], v[16:19]
	v_mfma_f32_16x16x32_bf16 v[4:7], v[166:169], v[206:209], v[4:7]
	v_mfma_f32_16x16x32_bf16 v[0:3], v[174:177], v[206:209], v[0:3]
	s_setprio 0
	s_barrier
	s_add_i32 s51, 0, 0x18000
	s_add_i32 s52, 0, 0x1c000
	v_add_u32_e32 v152, s51, v157
	v_add_u32_e32 v174, s52, v157
	ds_read_b128 v[140:143], v152
	ds_read_b128 v[144:147], v152 offset:1024
	ds_read_b128 v[148:151], v152 offset:2048
	ds_read_b128 v[152:155], v152 offset:3072
	ds_read_b128 v[162:165], v174
	ds_read_b128 v[166:169], v174 offset:1024
	ds_read_b128 v[170:173], v174 offset:2048
	ds_read_b128 v[174:177], v174 offset:3072
	s_add_u32 s36, s36, 0x40000
	s_addc_u32 s37, s37, 0
	s_mov_b32 m0, s39
	ds_read_b128 v[178:181], v161 offset:32768
	ds_read_b128 v[182:185], v161 offset:33792
	ds_read_b128 v[186:189], v161 offset:34816
	ds_read_b128 v[190:193], v161 offset:35840
	ds_read_b128 v[194:197], v161 offset:36864
	ds_read_b128 v[198:201], v161 offset:37888
	ds_read_b128 v[202:205], v161 offset:38912
	ds_read_b128 v[206:209], v161 offset:39936
	global_load_lds_dwordx4 v128, s[36:37]
	s_mov_b32 m0, s40
	s_nop 0
	global_load_lds_dwordx4 v132, s[36:37]
	s_waitcnt vmcnt(8)
	s_waitcnt lgkmcnt(0)
	s_barrier
	s_setprio 1
	s_waitcnt lgkmcnt(0)
	v_mfma_f32_16x16x32_bf16 v[124:127], v[140:143], v[178:181], v[124:127]
	v_mfma_f32_16x16x32_bf16 v[120:123], v[148:151], v[178:181], v[120:123]
	v_mfma_f32_16x16x32_bf16 v[108:111], v[140:143], v[186:189], v[108:111]
	v_mfma_f32_16x16x32_bf16 v[104:107], v[148:151], v[186:189], v[104:107]
	v_mfma_f32_16x16x32_bf16 v[92:95], v[140:143], v[194:197], v[92:95]
	v_mfma_f32_16x16x32_bf16 v[88:91], v[148:151], v[194:197], v[88:91]
	v_mfma_f32_16x16x32_bf16 v[76:79], v[140:143], v[202:205], v[76:79]
	v_mfma_f32_16x16x32_bf16 v[72:75], v[148:151], v[202:205], v[72:75]
	v_mfma_f32_16x16x32_bf16 v[124:127], v[144:147], v[182:185], v[124:127]
	v_mfma_f32_16x16x32_bf16 v[120:123], v[152:155], v[182:185], v[120:123]
	v_mfma_f32_16x16x32_bf16 v[108:111], v[144:147], v[190:193], v[108:111]
	v_mfma_f32_16x16x32_bf16 v[104:107], v[152:155], v[190:193], v[104:107]
	v_mfma_f32_16x16x32_bf16 v[92:95], v[144:147], v[198:201], v[92:95]
	v_mfma_f32_16x16x32_bf16 v[88:91], v[152:155], v[198:201], v[88:91]
	v_mfma_f32_16x16x32_bf16 v[76:79], v[144:147], v[206:209], v[76:79]
	v_mfma_f32_16x16x32_bf16 v[72:75], v[152:155], v[206:209], v[72:75]
	s_setprio 0
	s_setprio 1
	v_mfma_f32_16x16x32_bf16 v[116:119], v[162:165], v[178:181], v[116:119]
	v_mfma_f32_16x16x32_bf16 v[112:115], v[170:173], v[178:181], v[112:115]
	v_mfma_f32_16x16x32_bf16 v[100:103], v[162:165], v[186:189], v[100:103]
	v_mfma_f32_16x16x32_bf16 v[96:99], v[170:173], v[186:189], v[96:99]
	v_mfma_f32_16x16x32_bf16 v[84:87], v[162:165], v[194:197], v[84:87]
	v_mfma_f32_16x16x32_bf16 v[80:83], v[170:173], v[194:197], v[80:83]
	v_mfma_f32_16x16x32_bf16 v[68:71], v[162:165], v[202:205], v[68:71]
	v_mfma_f32_16x16x32_bf16 v[64:67], v[170:173], v[202:205], v[64:67]
	v_mfma_f32_16x16x32_bf16 v[116:119], v[166:169], v[182:185], v[116:119]
	v_mfma_f32_16x16x32_bf16 v[112:115], v[174:177], v[182:185], v[112:115]
	v_mfma_f32_16x16x32_bf16 v[100:103], v[166:169], v[190:193], v[100:103]
	v_mfma_f32_16x16x32_bf16 v[96:99], v[174:177], v[190:193], v[96:99]
	v_mfma_f32_16x16x32_bf16 v[84:87], v[166:169], v[198:201], v[84:87]
	v_mfma_f32_16x16x32_bf16 v[80:83], v[174:177], v[198:201], v[80:83]
	v_mfma_f32_16x16x32_bf16 v[68:71], v[166:169], v[206:209], v[68:71]
	v_mfma_f32_16x16x32_bf16 v[64:67], v[174:177], v[206:209], v[64:67]
	s_setprio 0
	s_barrier
; #define PG8_STAGE(bufoff, gbase, voff) do { _Pragma("unroll") for (int _i = 0; _i < 2; ++_i) \
;         __builtin_amdgcn_global_load_lds((const unsigned*)((const char*)(gbase) + (voff)[_i]), (LAS unsigned*)(lds + (bufoff) + ldsw + _i * 8192), 16, 0, 0); } while (0)
; #define PG8_LDA(dst, b, h) do { _Pragma("unroll") for (int m = 0; m < 4; ++m) _Pragma("unroll") for (int k = 0; k < 2; ++k) dst[m][k] = *(const LAS bf16x8*)(lds + PG8_SA(b, h) + aoff + m * 2048 + k * 1024); } while (0)
; #define PG8_LDB(dst, b, h) do { _Pragma("unroll") for (int n = 0; n < 2; ++n) _Pragma("unroll") for (int k = 0; k < 2; ++k) dst[n][k] = *(const LAS bf16x8*)(lds + PG8_SB(b, h) + boff + n * 2048 + k * 1024); } while (0)
; #define PG8_MMA(ai, bj, At, Bt) do { __builtin_amdgcn_s_setprio(1); _Pragma("unroll") for (int m = 0; m < 4; ++m) _Pragma("unroll") for (int n = 0; n < 2; ++n) _Pragma("unroll") for (int k = 0; k < 2; ++k) \
;         acc[ai][bj][m][n] = __builtin_amdgcn_mfma_f32_16x16x32_bf16(Bt[n][k], At[m][k], acc[ai][bj][m][n], 0, 0, 0); __builtin_amdgcn_s_setprio(0); } while (0)
; #define PG8_WAIT_V(n) asm volatile("s_waitcnt vmcnt(" #n ")" ::: "memory")
; #define PG8_WAIT_L(n) asm volatile("s_waitcnt lgkmcnt(" #n ")" ::: "memory")
; #define PG8_BAR __builtin_amdgcn_s_barrier()
; #define PG8_SCHED __builtin_amdgcn_sched_barrier(0)
; template <class Epi, class Sched>
; __device__ __forceinline__ void gemm_phase(LAS unsigned char* lds, const Gemm g, const Sched& S, const Epi& E, int wave_id) {
;     ...
;             PG8_LDB(B0, 0, 0); PG8_LDB(B1, 0, 1); PG8_SCHED; PG8_LDA(At, 0, 0); PG8_STAGE(PG8_SA(1, 1), a1 + hstepA, voffA);
;             PG8_WAIT_V(8); PG8_WAIT_L(0); PG8_BAR; PG8_MMA(0, 0, At, B0); PG8_MMA(0, 1, At, B1); PG8_BAR; PG8_SCHED;
;     ...
;             PG8_WAIT_V(8); PG8_WAIT_L(0); PG8_BAR; PG8_MMA(0, 0, At, B0); PG8_MMA(0, 1, At, B1); PG8_BAR; PG8_SCHED;
;             PG8_LDA(At, 1, 1); PG8_STAGE(PG8_SB(1, 0), b3, voffB); PG8_STAGE(PG8_SB(1, 1), b3 + hstepB, voffB); PG8_STAGE(PG8_SA(1, 0), a3, voffA);
;             PG8_WAIT_V(8); PG8_WAIT_L(0); PG8_BAR; PG8_MMA(1, 0, At, B0); PG8_MMA(1, 1, At, B1); PG8_BAR; PG8_SCHED;
	s_add_i32 s36, s51, s38
	v_lshl_add_u64 v[210:211], v[210:211], 0, s[8:9]
	s_mov_b32 m0, s36
	ds_read_b128 v[178:181], v161 offset:49152
	ds_read_b128 v[182:185], v161 offset:50176
	ds_read_b128 v[186:189], v161 offset:51200
	ds_read_b128 v[190:193], v161 offset:52224
	ds_read_b128 v[194:197], v161 offset:53248
	ds_read_b128 v[198:201], v161 offset:54272
	ds_read_b128 v[202:205], v161 offset:55296
	ds_read_b128 v[206:209], v161 offset:56320
	global_load_lds_dwordx4 v[210:211], off
	s_add_i32 m0, s36, 0x2000
	s_add_u32 s34, s34, 0x40080
	v_lshl_add_u64 v[210:211], v[212:213], 0, s[8:9]
	s_addc_u32 s35, s35, 0
	s_add_i32 s36, s52, s38
	global_load_lds_dwordx4 v[210:211], off
	s_mov_b32 m0, s36
	s_nop 0
	global_load_lds_dwordx4 v130, s[34:35]
	s_add_i32 m0, s36, 0x2000
	s_nop 0
	global_load_lds_dwordx4 v134, s[34:35]
	v_lshl_add_u64 v[210:211], v[214:215], 0, s[8:9]
	s_mov_b32 m0, s41
	s_nop 0
	global_load_lds_dwordx4 v[210:211], off
	v_lshl_add_u64 v[210:211], v[216:217], 0, s[8:9]
	s_mov_b32 m0, s42
	s_nop 0
	global_load_lds_dwordx4 v[210:211], off
	s_waitcnt vmcnt(8)
	s_waitcnt lgkmcnt(0)
	s_barrier
	s_setprio 1
	s_waitcnt lgkmcnt(0)
	v_mfma_f32_16x16x32_bf16 v[60:63], v[140:143], v[178:181], v[60:63]
	v_mfma_f32_16x16x32_bf16 v[56:59], v[148:151], v[178:181], v[56:59]
	v_mfma_f32_16x16x32_bf16 v[44:47], v[140:143], v[186:189], v[44:47]
	v_mfma_f32_16x16x32_bf16 v[40:43], v[148:151], v[186:189], v[40:43]
	v_mfma_f32_16x16x32_bf16 v[28:31], v[140:143], v[194:197], v[28:31]
	v_mfma_f32_16x16x32_bf16 v[24:27], v[148:151], v[194:197], v[24:27]
	v_mfma_f32_16x16x32_bf16 v[12:15], v[140:143], v[202:205], v[12:15]
	v_mfma_f32_16x16x32_bf16 v[8:11], v[148:151], v[202:205], v[8:11]
	v_mfma_f32_16x16x32_bf16 v[60:63], v[144:147], v[182:185], v[60:63]
	v_mfma_f32_16x16x32_bf16 v[56:59], v[152:155], v[182:185], v[56:59]
	v_mfma_f32_16x16x32_bf16 v[44:47], v[144:147], v[190:193], v[44:47]
	v_mfma_f32_16x16x32_bf16 v[40:43], v[152:155], v[190:193], v[40:43]
	v_mfma_f32_16x16x32_bf16 v[28:31], v[144:147], v[198:201], v[28:31]
	v_mfma_f32_16x16x32_bf16 v[24:27], v[152:155], v[198:201], v[24:27]
	v_mfma_f32_16x16x32_bf16 v[12:15], v[144:147], v[206:209], v[12:15]
	v_mfma_f32_16x16x32_bf16 v[8:11], v[152:155], v[206:209], v[8:11]
	s_setprio 0
	s_setprio 1
	v_mfma_f32_16x16x32_bf16 v[52:55], v[162:165], v[178:181], v[52:55]
	v_mfma_f32_16x16x32_bf16 v[48:51], v[170:173], v[178:181], v[48:51]
	v_mfma_f32_16x16x32_bf16 v[36:39], v[162:165], v[186:189], v[36:39]
	v_mfma_f32_16x16x32_bf16 v[32:35], v[170:173], v[186:189], v[32:35]
	v_mfma_f32_16x16x32_bf16 v[20:23], v[162:165], v[194:197], v[20:23]
	v_mfma_f32_16x16x32_bf16 v[16:19], v[170:173], v[194:197], v[16:19]
	v_mfma_f32_16x16x32_bf16 v[4:7], v[162:165], v[202:205], v[4:7]
	v_mfma_f32_16x16x32_bf16 v[0:3], v[170:173], v[202:205], v[0:3]
	v_mfma_f32_16x16x32_bf16 v[52:55], v[166:169], v[182:185], v[52:55]
	v_mfma_f32_16x16x32_bf16 v[48:51], v[174:177], v[182:185], v[48:51]
	v_mfma_f32_16x16x32_bf16 v[36:39], v[166:169], v[190:193], v[36:39]
	v_mfma_f32_16x16x32_bf16 v[32:35], v[174:177], v[190:193], v[32:35]
	v_mfma_f32_16x16x32_bf16 v[20:23], v[166:169], v[198:201], v[20:23]
	v_mfma_f32_16x16x32_bf16 v[16:19], v[174:177], v[198:201], v[16:19]
	v_mfma_f32_16x16x32_bf16 v[4:7], v[166:169], v[206:209], v[4:7]
	v_mfma_f32_16x16x32_bf16 v[0:3], v[174:177], v[206:209], v[0:3]
	s_setprio 0
	s_barrier
	s_add_i32 s50, s50, 2
	s_add_u32 s30, s30, 0x100
	s_addc_u32 s31, s31, 0
	s_add_u32 s48, s48, 0x100
	s_addc_u32 s49, s49, 0
	s_cmp_gt_u32 s50, 13
.LBB0_863:
	ds_read_b128 v[140:143], v159
	ds_read_b128 v[144:147], v159 offset:1024
	ds_read_b128 v[148:151], v159 offset:2048
	ds_read_b128 v[152:155], v159 offset:3072
	ds_read_b128 v[162:165], v160
	ds_read_b128 v[166:169], v160 offset:1024
	ds_read_b128 v[170:173], v160 offset:2048
	ds_read_b128 v[174:177], v160 offset:3072
	s_add_u32 s34, s30, 0xfffc0080
	s_addc_u32 s35, s31, -1
	s_cmp_eq_u32 s50, 12
	s_cselect_b32 s37, s19, s35
	s_cselect_b32 s36, s46, s34
	s_cselect_b32 s35, s17, s49
	s_cselect_b32 s34, s47, s48
	s_add_i32 m0, s27, 0xc000
	ds_read_b128 v[178:181], v161
	ds_read_b128 v[182:185], v161 offset:1024
	ds_read_b128 v[186:189], v161 offset:2048
	ds_read_b128 v[190:193], v161 offset:3072
	ds_read_b128 v[194:197], v161 offset:4096
	ds_read_b128 v[198:201], v161 offset:5120
	ds_read_b128 v[202:205], v161 offset:6144
	ds_read_b128 v[206:209], v161 offset:7168
	global_load_lds_dwordx4 v136, s[30:31]
	s_add_i32 m0, s27, 0xe000
	s_nop 0
	global_load_lds_dwordx4 v138, s[30:31]
	s_waitcnt vmcnt(8)
	s_waitcnt lgkmcnt(0)
	s_barrier
; #define PG8_STAGE(bufoff, gbase, voff) do { _Pragma("unroll") for (int _i = 0; _i < 2; ++_i) \
;         __builtin_amdgcn_global_load_lds((const unsigned*)((const char*)(gbase) + (voff)[_i]), (LAS unsigned*)(lds + (bufoff) + ldsw + _i * 8192), 16, 0, 0); } while (0)
; #define PG8_LDA(dst, b, h) do { _Pragma("unroll") for (int m = 0; m < 4; ++m) _Pragma("unroll") for (int k = 0; k < 2; ++k) dst[m][k] = *(const LAS bf16x8*)(lds + PG8_SA(b, h) + aoff + m * 2048 + k * 1024); } while (0)
; #define PG8_MMA(ai, bj, At, Bt) do { __builtin_amdgcn_s_setprio(1); _Pragma("unroll") for (int m = 0; m < 4; ++m) _Pragma("unroll") for (int n = 0; n < 2; ++n) _Pragma("unroll") for (int k = 0; k < 2; ++k) \
;         acc[ai][bj][m][n] = __builtin_amdgcn_mfma_f32_16x16x32_bf16(Bt[n][k], At[m][k], acc[ai][bj][m][n], 0, 0, 0); __builtin_amdgcn_s_setprio(0); } while (0)
; #define PG8_WAIT_V(n) asm volatile("s_waitcnt vmcnt(" #n ")" ::: "memory")
; #define PG8_WAIT_L(n) asm volatile("s_waitcnt lgkmcnt(" #n ")" ::: "memory")
; #define PG8_BAR __builtin_amdgcn_s_barrier()
; #define PG8_SCHED __builtin_amdgcn_sched_barrier(0)
; template <class Epi, class Sched>
; __device__ __forceinline__ void gemm_phase(LAS unsigned char* lds, const Gemm g, const Sched& S, const Epi& E, int wave_id) {
;     ...
;             PG8_WAIT_V(8); PG8_WAIT_L(0); PG8_BAR; PG8_MMA(0, 0, At, B0); PG8_MMA(0, 1, At, B1); PG8_BAR; PG8_SCHED;
;             PG8_LDA(At, 0, 1); PG8_STAGE(PG8_SB(0, 0), b2, voffB); PG8_STAGE(PG8_SB(0, 1), b2 + hstepB, voffB); PG8_STAGE(PG8_SA(0, 0), a2, voffA);
;             PG8_WAIT_V(8); PG8_WAIT_L(0); PG8_BAR; PG8_MMA(1, 0, At, B0); PG8_MMA(1, 1, At, B1); PG8_BAR; PG8_SCHED;
	s_setprio 1
	s_waitcnt lgkmcnt(0)
	v_mfma_f32_16x16x32_bf16 v[124:127], v[140:143], v[178:181], v[124:127]
	v_mfma_f32_16x16x32_bf16 v[120:123], v[148:151], v[178:181], v[120:123]
	v_mfma_f32_16x16x32_bf16 v[108:111], v[140:143], v[186:189], v[108:111]
	v_mfma_f32_16x16x32_bf16 v[104:107], v[148:151], v[186:189], v[104:107]
	v_mfma_f32_16x16x32_bf16 v[92:95], v[140:143], v[194:197], v[92:95]
	v_mfma_f32_16x16x32_bf16 v[88:91], v[148:151], v[194:197], v[88:91]
	v_mfma_f32_16x16x32_bf16 v[76:79], v[140:143], v[202:205], v[76:79]
	v_mfma_f32_16x16x32_bf16 v[72:75], v[148:151], v[202:205], v[72:75]
	v_mfma_f32_16x16x32_bf16 v[124:127], v[144:147], v[182:185], v[124:127]
	v_mfma_f32_16x16x32_bf16 v[120:123], v[152:155], v[182:185], v[120:123]
	v_mfma_f32_16x16x32_bf16 v[108:111], v[144:147], v[190:193], v[108:111]
	v_mfma_f32_16x16x32_bf16 v[104:107], v[152:155], v[190:193], v[104:107]
	v_mfma_f32_16x16x32_bf16 v[92:95], v[144:147], v[198:201], v[92:95]
	v_mfma_f32_16x16x32_bf16 v[88:91], v[152:155], v[198:201], v[88:91]
	v_mfma_f32_16x16x32_bf16 v[76:79], v[144:147], v[206:209], v[76:79]
	v_mfma_f32_16x16x32_bf16 v[72:75], v[152:155], v[206:209], v[72:75]
	s_setprio 0
	s_setprio 1
	v_mfma_f32_16x16x32_bf16 v[116:119], v[162:165], v[178:181], v[116:119]
	v_mfma_f32_16x16x32_bf16 v[112:115], v[170:173], v[178:181], v[112:115]
	v_mfma_f32_16x16x32_bf16 v[100:103], v[162:165], v[186:189], v[100:103]
	v_mfma_f32_16x16x32_bf16 v[96:99], v[170:173], v[186:189], v[96:99]
	v_mfma_f32_16x16x32_bf16 v[84:87], v[162:165], v[194:197], v[84:87]
	v_mfma_f32_16x16x32_bf16 v[80:83], v[170:173], v[194:197], v[80:83]
	v_mfma_f32_16x16x32_bf16 v[68:71], v[162:165], v[202:205], v[68:71]
	v_mfma_f32_16x16x32_bf16 v[64:67], v[170:173], v[202:205], v[64:67]
	v_mfma_f32_16x16x32_bf16 v[116:119], v[166:169], v[182:185], v[116:119]
	v_mfma_f32_16x16x32_bf16 v[112:115], v[174:177], v[182:185], v[112:115]
	v_mfma_f32_16x16x32_bf16 v[100:103], v[166:169], v[190:193], v[100:103]
	v_mfma_f32_16x16x32_bf16 v[96:99], v[174:177], v[190:193], v[96:99]
	v_mfma_f32_16x16x32_bf16 v[84:87], v[166:169], v[198:201], v[84:87]
	v_mfma_f32_16x16x32_bf16 v[80:83], v[174:177], v[198:201], v[80:83]
	v_mfma_f32_16x16x32_bf16 v[68:71], v[166:169], v[206:209], v[68:71]
	v_mfma_f32_16x16x32_bf16 v[64:67], v[174:177], v[206:209], v[64:67]
	s_setprio 0
	s_barrier
	s_add_i32 s51, s43, s38
	v_lshl_add_u64 v[210:211], s[34:35], 0, v[130:131]
	s_mov_b32 m0, s51
	ds_read_b128 v[178:181], v161 offset:16384
	ds_read_b128 v[182:185], v161 offset:17408
	ds_read_b128 v[186:189], v161 offset:18432
	ds_read_b128 v[190:193], v161 offset:19456
	ds_read_b128 v[194:197], v161 offset:20480
	ds_read_b128 v[198:201], v161 offset:21504
	ds_read_b128 v[202:205], v161 offset:22528
	ds_read_b128 v[206:209], v161 offset:23552
	global_load_lds_dwordx4 v[210:211], off
	s_add_i32 m0, s51, 0x2000
	s_add_u32 s52, s34, 0x40000
	v_lshl_add_u64 v[212:213], s[34:35], 0, v[134:135]
	s_addc_u32 s53, s35, 0
	s_add_i32 s51, s44, s38
	global_load_lds_dwordx4 v[212:213], off
	s_mov_b32 m0, s51
	v_lshl_add_u64 v[216:217], s[36:37], 0, v[132:133]
	global_load_lds_dwordx4 v130, s[52:53]
	s_add_i32 m0, s51, 0x2000
	s_nop 0
	global_load_lds_dwordx4 v134, s[52:53]
	v_lshl_add_u64 v[214:215], s[36:37], 0, v[128:129]
	s_mov_b32 m0, s27
	s_nop 0
	global_load_lds_dwordx4 v[214:215], off
	s_mov_b32 m0, s29
	s_nop 0
	global_load_lds_dwordx4 v[216:217], off
	s_waitcnt vmcnt(8)
	s_waitcnt lgkmcnt(0)
	s_barrier
	s_setprio 1
	s_waitcnt lgkmcnt(0)
	v_mfma_f32_16x16x32_bf16 v[60:63], v[140:143], v[178:181], v[60:63]
	v_mfma_f32_16x16x32_bf16 v[56:59], v[148:151], v[178:181], v[56:59]
	v_mfma_f32_16x16x32_bf16 v[44:47], v[140:143], v[186:189], v[44:47]
	v_mfma_f32_16x16x32_bf16 v[40:43], v[148:151], v[186:189], v[40:43]
	v_mfma_f32_16x16x32_bf16 v[28:31], v[140:143], v[194:197], v[28:31]
	v_mfma_f32_16x16x32_bf16 v[24:27], v[148:151], v[194:197], v[24:27]
	v_mfma_f32_16x16x32_bf16 v[12:15], v[140:143], v[202:205], v[12:15]
	v_mfma_f32_16x16x32_bf16 v[8:11], v[148:151], v[202:205], v[8:11]
	v_mfma_f32_16x16x32_bf16 v[60:63], v[144:147], v[182:185], v[60:63]
	v_mfma_f32_16x16x32_bf16 v[56:59], v[152:155], v[182:185], v[56:59]
	v_mfma_f32_16x16x32_bf16 v[44:47], v[144:147], v[190:193], v[44:47]
	v_mfma_f32_16x16x32_bf16 v[40:43], v[152:155], v[190:193], v[40:43]
	v_mfma_f32_16x16x32_bf16 v[28:31], v[144:147], v[198:201], v[28:31]
	v_mfma_f32_16x16x32_bf16 v[24:27], v[152:155], v[198:201], v[24:27]
	v_mfma_f32_16x16x32_bf16 v[12:15], v[144:147], v[206:209], v[12:15]
	v_mfma_f32_16x16x32_bf16 v[8:11], v[152:155], v[206:209], v[8:11]
	s_setprio 0
	s_setprio 1
	v_mfma_f32_16x16x32_bf16 v[52:55], v[162:165], v[178:181], v[52:55]
	v_mfma_f32_16x16x32_bf16 v[48:51], v[170:173], v[178:181], v[48:51]
	v_mfma_f32_16x16x32_bf16 v[36:39], v[162:165], v[186:189], v[36:39]
	v_mfma_f32_16x16x32_bf16 v[32:35], v[170:173], v[186:189], v[32:35]
	v_mfma_f32_16x16x32_bf16 v[20:23], v[162:165], v[194:197], v[20:23]
	v_mfma_f32_16x16x32_bf16 v[16:19], v[170:173], v[194:197], v[16:19]
	v_mfma_f32_16x16x32_bf16 v[4:7], v[162:165], v[202:205], v[4:7]
	v_mfma_f32_16x16x32_bf16 v[0:3], v[170:173], v[202:205], v[0:3]
	v_mfma_f32_16x16x32_bf16 v[52:55], v[166:169], v[182:185], v[52:55]
	v_mfma_f32_16x16x32_bf16 v[48:51], v[174:177], v[182:185], v[48:51]
	v_mfma_f32_16x16x32_bf16 v[36:39], v[166:169], v[190:193], v[36:39]
	v_mfma_f32_16x16x32_bf16 v[32:35], v[174:177], v[190:193], v[32:35]
	v_mfma_f32_16x16x32_bf16 v[20:23], v[166:169], v[198:201], v[20:23]
	v_mfma_f32_16x16x32_bf16 v[16:19], v[174:177], v[198:201], v[16:19]
	v_mfma_f32_16x16x32_bf16 v[4:7], v[166:169], v[206:209], v[4:7]
	v_mfma_f32_16x16x32_bf16 v[0:3], v[174:177], v[206:209], v[0:3]
	s_setprio 0
	s_barrier
; #define PG8_STAGE(bufoff, gbase, voff) do { _Pragma("unroll") for (int _i = 0; _i < 2; ++_i) \
;         __builtin_amdgcn_global_load_lds((const unsigned*)((const char*)(gbase) + (voff)[_i]), (LAS unsigned*)(lds + (bufoff) + ldsw + _i * 8192), 16, 0, 0); } while (0)
; #define PG8_LDA(dst, b, h) do { _Pragma("unroll") for (int m = 0; m < 4; ++m) _Pragma("unroll") for (int k = 0; k < 2; ++k) dst[m][k] = *(const LAS bf16x8*)(lds + PG8_SA(b, h) + aoff + m * 2048 + k * 1024); } while (0)
; #define PG8_LDB(dst, b, h) do { _Pragma("unroll") for (int n = 0; n < 2; ++n) _Pragma("unroll") for (int k = 0; k < 2; ++k) dst[n][k] = *(const LAS bf16x8*)(lds + PG8_SB(b, h) + boff + n * 2048 + k * 1024); } while (0)
; #define PG8_MMA(ai, bj, At, Bt) do { __builtin_amdgcn_s_setprio(1); _Pragma("unroll") for (int m = 0; m < 4; ++m) _Pragma("unroll") for (int n = 0; n < 2; ++n) _Pragma("unroll") for (int k = 0; k < 2; ++k) \
;         acc[ai][bj][m][n] = __builtin_amdgcn_mfma_f32_16x16x32_bf16(Bt[n][k], At[m][k], acc[ai][bj][m][n], 0, 0, 0); __builtin_amdgcn_s_setprio(0); } while (0)
; #define PG8_WAIT_V(n) asm volatile("s_waitcnt vmcnt(" #n ")" ::: "memory")
; #define PG8_WAIT_L(n) asm volatile("s_waitcnt lgkmcnt(" #n ")" ::: "memory")
; #define PG8_BAR __builtin_amdgcn_s_barrier()
; #define PG8_SCHED __builtin_amdgcn_sched_barrier(0)
; template <class Epi, class Sched>
; __device__ __forceinline__ void gemm_phase(LAS unsigned char* lds, const Gemm g, const Sched& S, const Epi& E, int wave_id) {
;     ...
;             PG8_LDB(B0, 1, 0); PG8_LDB(B1, 1, 1); PG8_SCHED; PG8_LDA(At, 1, 0); PG8_STAGE(PG8_SA(0, 1), a2 + hstepA, voffA);
;             PG8_WAIT_V(8); PG8_WAIT_L(0); PG8_BAR; PG8_MMA(0, 0, At, B0); PG8_MMA(0, 1, At, B1); PG8_BAR; PG8_SCHED;
;             PG8_LDA(At, 1, 1); PG8_STAGE(PG8_SB(1, 0), b3, voffB); PG8_STAGE(PG8_SB(1, 1), b3 + hstepB, voffB); PG8_STAGE(PG8_SA(1, 0), a3, voffA);
;             PG8_WAIT_V(8); PG8_WAIT_L(0); PG8_BAR; PG8_MMA(1, 0, At, B0); PG8_MMA(1, 1, At, B1); PG8_BAR; PG8_SCHED;
;         }
;         if (wr == 0) PG8_BAR;
	s_add_i32 s51, 0, 0x18000
	s_add_i32 s52, 0, 0x1c000
	v_add_u32_e32 v152, s51, v157
	v_add_u32_e32 v174, s52, v157
	ds_read_b128 v[140:143], v152
	ds_read_b128 v[144:147], v152 offset:1024
	ds_read_b128 v[148:151], v152 offset:2048
	ds_read_b128 v[152:155], v152 offset:3072
	ds_read_b128 v[162:165], v174
	ds_read_b128 v[166:169], v174 offset:1024
	ds_read_b128 v[170:173], v174 offset:2048
	ds_read_b128 v[174:177], v174 offset:3072
	s_add_u32 s36, s36, 0x40000
	s_addc_u32 s37, s37, 0
	s_mov_b32 m0, s39
	ds_read_b128 v[178:181], v161 offset:32768
	ds_read_b128 v[182:185], v161 offset:33792
	ds_read_b128 v[186:189], v161 offset:34816
	ds_read_b128 v[190:193], v161 offset:35840
	ds_read_b128 v[194:197], v161 offset:36864
	ds_read_b128 v[198:201], v161 offset:37888
	ds_read_b128 v[202:205], v161 offset:38912
	ds_read_b128 v[206:209], v161 offset:39936
	global_load_lds_dwordx4 v128, s[36:37]
	s_mov_b32 m0, s40
	s_nop 0
	global_load_lds_dwordx4 v132, s[36:37]
	s_waitcnt vmcnt(8)
	s_waitcnt lgkmcnt(0)
	s_barrier
	s_setprio 1
	s_waitcnt lgkmcnt(0)
	v_mfma_f32_16x16x32_bf16 v[124:127], v[140:143], v[178:181], v[124:127]
	v_mfma_f32_16x16x32_bf16 v[120:123], v[148:151], v[178:181], v[120:123]
	v_mfma_f32_16x16x32_bf16 v[108:111], v[140:143], v[186:189], v[108:111]
	v_mfma_f32_16x16x32_bf16 v[104:107], v[148:151], v[186:189], v[104:107]
	v_mfma_f32_16x16x32_bf16 v[92:95], v[140:143], v[194:197], v[92:95]
	v_mfma_f32_16x16x32_bf16 v[88:91], v[148:151], v[194:197], v[88:91]
	v_mfma_f32_16x16x32_bf16 v[76:79], v[140:143], v[202:205], v[76:79]
	v_mfma_f32_16x16x32_bf16 v[72:75], v[148:151], v[202:205], v[72:75]
	v_mfma_f32_16x16x32_bf16 v[124:127], v[144:147], v[182:185], v[124:127]
	v_mfma_f32_16x16x32_bf16 v[120:123], v[152:155], v[182:185], v[120:123]
	v_mfma_f32_16x16x32_bf16 v[108:111], v[144:147], v[190:193], v[108:111]
	v_mfma_f32_16x16x32_bf16 v[104:107], v[152:155], v[190:193], v[104:107]
	v_mfma_f32_16x16x32_bf16 v[92:95], v[144:147], v[198:201], v[92:95]
	v_mfma_f32_16x16x32_bf16 v[88:91], v[152:155], v[198:201], v[88:91]
	v_mfma_f32_16x16x32_bf16 v[76:79], v[144:147], v[206:209], v[76:79]
	v_mfma_f32_16x16x32_bf16 v[72:75], v[152:155], v[206:209], v[72:75]
	s_setprio 0
	s_setprio 1
	v_mfma_f32_16x16x32_bf16 v[116:119], v[162:165], v[178:181], v[116:119]
	v_mfma_f32_16x16x32_bf16 v[112:115], v[170:173], v[178:181], v[112:115]
	v_mfma_f32_16x16x32_bf16 v[100:103], v[162:165], v[186:189], v[100:103]
	v_mfma_f32_16x16x32_bf16 v[96:99], v[170:173], v[186:189], v[96:99]
	v_mfma_f32_16x16x32_bf16 v[84:87], v[162:165], v[194:197], v[84:87]
	v_mfma_f32_16x16x32_bf16 v[80:83], v[170:173], v[194:197], v[80:83]
	v_mfma_f32_16x16x32_bf16 v[68:71], v[162:165], v[202:205], v[68:71]
	v_mfma_f32_16x16x32_bf16 v[64:67], v[170:173], v[202:205], v[64:67]
	v_mfma_f32_16x16x32_bf16 v[116:119], v[166:169], v[182:185], v[116:119]
	v_mfma_f32_16x16x32_bf16 v[112:115], v[174:177], v[182:185], v[112:115]
	v_mfma_f32_16x16x32_bf16 v[100:103], v[166:169], v[190:193], v[100:103]
	v_mfma_f32_16x16x32_bf16 v[96:99], v[174:177], v[190:193], v[96:99]
	v_mfma_f32_16x16x32_bf16 v[84:87], v[166:169], v[198:201], v[84:87]
	v_mfma_f32_16x16x32_bf16 v[80:83], v[174:177], v[198:201], v[80:83]
	v_mfma_f32_16x16x32_bf16 v[68:71], v[166:169], v[206:209], v[68:71]
	v_mfma_f32_16x16x32_bf16 v[64:67], v[174:177], v[206:209], v[64:67]
	s_setprio 0
	s_barrier
	s_add_i32 s36, s51, s38
	v_lshl_add_u64 v[210:211], v[210:211], 0, s[8:9]
	s_mov_b32 m0, s36
	ds_read_b128 v[178:181], v161 offset:49152
	ds_read_b128 v[182:185], v161 offset:50176
	ds_read_b128 v[186:189], v161 offset:51200
	ds_read_b128 v[190:193], v161 offset:52224
	ds_read_b128 v[194:197], v161 offset:53248
	ds_read_b128 v[198:201], v161 offset:54272
	ds_read_b128 v[202:205], v161 offset:55296
	ds_read_b128 v[206:209], v161 offset:56320
	global_load_lds_dwordx4 v[210:211], off
	s_add_i32 m0, s36, 0x2000
	s_add_u32 s34, s34, 0x40080
	v_lshl_add_u64 v[210:211], v[212:213], 0, s[8:9]
	s_addc_u32 s35, s35, 0
	s_add_i32 s36, s52, s38
	global_load_lds_dwordx4 v[210:211], off
	s_mov_b32 m0, s36
	s_nop 0
	global_load_lds_dwordx4 v130, s[34:35]
	s_add_i32 m0, s36, 0x2000
	s_nop 0
	global_load_lds_dwordx4 v134, s[34:35]
	v_lshl_add_u64 v[210:211], v[214:215], 0, s[8:9]
	s_mov_b32 m0, s41
	s_nop 0
	global_load_lds_dwordx4 v[210:211], off
	v_lshl_add_u64 v[210:211], v[216:217], 0, s[8:9]
	s_mov_b32 m0, s42
	s_nop 0
	global_load_lds_dwordx4 v[210:211], off
	s_waitcnt vmcnt(8)
	s_waitcnt lgkmcnt(0)
	s_barrier
	s_setprio 1
	s_waitcnt lgkmcnt(0)
	v_mfma_f32_16x16x32_bf16 v[60:63], v[140:143], v[178:181], v[60:63]
	v_mfma_f32_16x16x32_bf16 v[56:59], v[148:151], v[178:181], v[56:59]
	v_mfma_f32_16x16x32_bf16 v[44:47], v[140:143], v[186:189], v[44:47]
	v_mfma_f32_16x16x32_bf16 v[40:43], v[148:151], v[186:189], v[40:43]
	v_mfma_f32_16x16x32_bf16 v[28:31], v[140:143], v[194:197], v[28:31]
	v_mfma_f32_16x16x32_bf16 v[24:27], v[148:151], v[194:197], v[24:27]
	v_mfma_f32_16x16x32_bf16 v[12:15], v[140:143], v[202:205], v[12:15]
	v_mfma_f32_16x16x32_bf16 v[8:11], v[148:151], v[202:205], v[8:11]
	v_mfma_f32_16x16x32_bf16 v[60:63], v[144:147], v[182:185], v[60:63]
	v_mfma_f32_16x16x32_bf16 v[56:59], v[152:155], v[182:185], v[56:59]
	v_mfma_f32_16x16x32_bf16 v[44:47], v[144:147], v[190:193], v[44:47]
	v_mfma_f32_16x16x32_bf16 v[40:43], v[152:155], v[190:193], v[40:43]
	v_mfma_f32_16x16x32_bf16 v[28:31], v[144:147], v[198:201], v[28:31]
	v_mfma_f32_16x16x32_bf16 v[24:27], v[152:155], v[198:201], v[24:27]
	v_mfma_f32_16x16x32_bf16 v[12:15], v[144:147], v[206:209], v[12:15]
	v_mfma_f32_16x16x32_bf16 v[8:11], v[152:155], v[206:209], v[8:11]
	s_setprio 0
	s_setprio 1
	v_mfma_f32_16x16x32_bf16 v[52:55], v[162:165], v[178:181], v[52:55]
	v_mfma_f32_16x16x32_bf16 v[48:51], v[170:173], v[178:181], v[48:51]
	v_mfma_f32_16x16x32_bf16 v[36:39], v[162:165], v[186:189], v[36:39]
	v_mfma_f32_16x16x32_bf16 v[32:35], v[170:173], v[186:189], v[32:35]
	v_mfma_f32_16x16x32_bf16 v[20:23], v[162:165], v[194:197], v[20:23]
	v_mfma_f32_16x16x32_bf16 v[16:19], v[170:173], v[194:197], v[16:19]
	v_mfma_f32_16x16x32_bf16 v[4:7], v[162:165], v[202:205], v[4:7]
	v_mfma_f32_16x16x32_bf16 v[0:3], v[170:173], v[202:205], v[0:3]
	v_mfma_f32_16x16x32_bf16 v[52:55], v[166:169], v[182:185], v[52:55]
	v_mfma_f32_16x16x32_bf16 v[48:51], v[174:177], v[182:185], v[48:51]
	v_mfma_f32_16x16x32_bf16 v[36:39], v[166:169], v[190:193], v[36:39]
	v_mfma_f32_16x16x32_bf16 v[32:35], v[174:177], v[190:193], v[32:35]
	v_mfma_f32_16x16x32_bf16 v[20:23], v[166:169], v[198:201], v[20:23]
	v_mfma_f32_16x16x32_bf16 v[16:19], v[174:177], v[198:201], v[16:19]
	v_mfma_f32_16x16x32_bf16 v[4:7], v[166:169], v[206:209], v[4:7]
	v_mfma_f32_16x16x32_bf16 v[0:3], v[174:177], v[206:209], v[0:3]
	s_setprio 0
	s_barrier
	s_add_i32 s50, s50, 2
	s_add_u32 s30, s30, 0x100
	s_addc_u32 s31, s31, 0
	s_add_u32 s48, s48, 0x100
	s_addc_u32 s49, s49, 0
	s_cmp_gt_u32 s50, 13
	s_cbranch_scc0 .LBB0_863
	s_and_b64 vcc, exec, s[10:11]
	s_cbranch_vccz .LBB0_866
	s_barrier

;     __device__ bool next(int i, Unit& u) const { if (r0 + i >= r1) return false; return base.next(r0 + i, u); }
;     __device__ bool next(int i, Unit& u) const { const int L = i * G + c; if (L >= 256) return false; u.pm = L; u.pn = L >> 3; return true; }
; #define PG8_STAGE(bufoff, gbase, voff) do { _Pragma("unroll") for (int _i = 0; _i < 2; ++_i) \
;         __builtin_amdgcn_global_load_lds((const unsigned*)((const char*)(gbase) + (voff)[_i]), (LAS unsigned*)(lds + (bufoff) + ldsw + _i * 8192), 16, 0, 0); } while (0)
; #define PG8_WAIT_V(n) asm volatile("s_waitcnt vmcnt(" #n ")" ::: "memory")
; #define PG8_BAR __builtin_amdgcn_s_barrier()
; template <class Epi, class Sched>
; __device__ __forceinline__ void gemm_phase(LAS unsigned char* lds, const Gemm g, const Sched& S, const Epi& E, int wave_id) {
;     ...
;     PG8_STAGE(PG8_SB(0, 0), cB, voffB); PG8_STAGE(PG8_SB(0, 1), cB + hstepB, voffB); PG8_STAGE(PG8_SA(0, 0), cA, voffA); PG8_STAGE(PG8_SA(0, 1), cA + hstepA, voffA);
;     if (wr == 1) PG8_BAR;
;     PG8_WAIT_V(2); PG8_BAR;
;     PG8_STAGE(PG8_SB(1, 0), cB + kstep, voffB); PG8_STAGE(PG8_SA(1, 0), cA + kstep, voffA); PG8_STAGE(PG8_SB(1, 1), cB + hstepB + kstep, voffB);
;     PG8_WAIT_V(6); PG8_BAR;
;     for (;;) {
;         const bool has_next = S.next(ui + 1, nxt);
;         const char* nA = has_next ? (const char*)g.A + (size_t)nxt.pm * tstepA : cA; const char* nB = has_next ? (const char*)g.Bt + (size_t)nxt.pn * tstepB : cB;
.LBB0_930:
	s_lshl_b32 s4, s97, 5
	s_mov_b64 s[12:13], 0x80
	s_and_b32 s6, s4, 0x60
	s_add_i32 m0, s38, 0x18000
	v_lshl_add_u64 v[6:7], v[6:7], 0, s[12:13]
	s_lshl_b32 s7, s6, 7
	s_waitcnt vmcnt(2)
	s_barrier
	global_load_lds_dwordx4 v[6:7], off
	v_lshl_add_u64 v[4:5], v[4:5], 0, s[12:13]
	s_add_i32 m0, s38, 0x1a000
	s_add_i32 s43, s38, 0x8000
	s_add_i32 s44, s38, 0xa000
	global_load_lds_dwordx4 v[4:5], off
	v_lshl_add_u64 v[0:1], v[0:1], 0, s[12:13]
	s_mov_b32 m0, s43
	s_add_u32 s4, s34, 0x18080
	global_load_lds_dwordx4 v[0:1], off
	v_lshl_add_u64 v[0:1], v[2:3], 0, s[12:13]
	s_mov_b32 m0, s44
	s_addc_u32 s5, s35, 0
	global_load_lds_dwordx4 v[0:1], off
	s_add_i32 m0, s38, 0x1c000
	s_nop 0
	global_load_lds_dwordx4 v132, s[4:5]
	v_lshl_add_u64 v[0:1], s[4:5], 0, v[128:129]
	s_add_i32 m0, s38, 0x1e000
	s_cmpk_lt_u32 s80, 0x100
	global_load_lds_dwordx4 v[0:1], off
	v_and_b32_e32 v1, 15, v8
	v_lshrrev_b32_e32 v0, 1, v8
	v_and_b32_e32 v2, 24, v0
	v_lshlrev_b32_e32 v3, 6, v1
	v_lshl_or_b32 v3, v2, 1, v3
	s_cselect_b64 s[4:5], -1, 0
	v_or_b32_e32 v2, s6, v2
	s_lshl_b32 s6, s3, 10
	v_lshlrev_b32_e32 v4, 2, v8
	s_add_u32 s14, s92, 0x1c400000
	v_readlane_b32 s18, v255, 1
	v_and_b32_e32 v4, 32, v4
	s_addc_u32 s15, s93, 0
	s_add_i32 s45, s66, s18
	v_bitop3_b32 v5, v3, s33, v4 bitop3:0xde
	v_bitop3_b32 v3, v3, s7, v4 bitop3:0xde
	v_lshrrev_b32_e32 v2, 4, v2
	v_lshlrev_b32_e32 v1, 4, v1
	s_mul_i32 s7, s45, 0x30000
	v_or3_b32 v139, v1, s6, v2
	s_mul_hi_i32 s6, s45, 0x30000
	s_add_u32 s7, s92, s7
	s_addc_u32 s6, s93, s6
	s_add_u32 s16, s7, 0x17400000
	s_waitcnt vmcnt(6)
	s_addc_u32 s17, s6, 0
	s_add_i32 s50, 0, 0x10000
	s_add_i32 s52, 0, 0x14000
	s_add_i32 s54, 0, 0x18000
	s_add_i32 s58, 0, 0x1c000
	v_and_b32_e32 v0, 8, v0
	v_readlane_b32 s19, v255, 2
	v_add_u32_e32 v147, s50, v3
	v_add_u32_e32 v148, s52, v3
	v_cndmask_b32_e64 v1, 0, 1, s[4:5]
	s_add_i32 s50, s50, s2
	s_add_i32 s52, s52, s2
	v_add_u32_e32 v149, s54, v3
	v_add_u32_e32 v150, s58, v3
	s_add_i32 s54, s54, s2
	s_add_i32 s58, s58, s2
	v_add_u32_e32 v138, 0, v5
	v_or_b32_e32 v151, 0x100, v139
	v_or_b32_e32 v254, 0x200, v139
	v_or_b32_e32 v142, 0x300, v139
	v_add_u32_e32 v143, 0x800, v139
	v_add_u32_e32 v144, 0x900, v139
	v_add_u32_e32 v145, 0xa00, v139
	v_add_u32_e32 v146, 0xb00, v139
	s_mul_hi_i32 s46, s18, 0x30000
	s_mul_i32 s47, s18, 0x30000
	s_add_i32 s48, s38, 0xc000
	s_add_i32 s49, s38, 0xe000
	s_mov_b64 s[18:19], 0x100
	s_mov_b64 s[20:21], 0x180
	s_mov_b64 s[22:23], 0x200
	s_mov_b64 s[24:25], 0x280
	v_lshlrev_b32_e32 v136, 1, v0
	s_add_i32 s51, s50, 0x2000
	s_add_i32 s53, s52, 0x2000
	s_add_i32 s55, s54, 0x2000
	s_add_i32 s59, s58, 0x2000
	v_cmp_ne_u32_e64 s[4:5], 1, v1
	s_mov_b32 s62, s66
	s_mov_b64 s[26:27], s[30:31]
	s_barrier
	s_waitcnt vmcnt(0)
	s_branch .LBB0_933

; #define PG8_STAGE(bufoff, gbase, voff) do { _Pragma("unroll") for (int _i = 0; _i < 2; ++_i) \
;         __builtin_amdgcn_global_load_lds((const unsigned*)((const char*)(gbase) + (voff)[_i]), (LAS unsigned*)(lds + (bufoff) + ldsw + _i * 8192), 16, 0, 0); } while (0)
; #define PG8_LDA(dst, b, h) do { _Pragma("unroll") for (int m = 0; m < 4; ++m) _Pragma("unroll") for (int k = 0; k < 2; ++k) dst[m][k] = *(const LAS bf16x8*)(lds + PG8_SA(b, h) + aoff + m * 2048 + k * 1024); } while (0)
; #define PG8_LDB(dst, b, h) do { _Pragma("unroll") for (int n = 0; n < 2; ++n) _Pragma("unroll") for (int k = 0; k < 2; ++k) dst[n][k] = *(const LAS bf16x8*)(lds + PG8_SB(b, h) + boff + n * 2048 + k * 1024); } while (0)
; #define PG8_MMA(ai, bj, At, Bt) do { __builtin_amdgcn_s_setprio(1); _Pragma("unroll") for (int m = 0; m < 4; ++m) _Pragma("unroll") for (int n = 0; n < 2; ++n) _Pragma("unroll") for (int k = 0; k < 2; ++k) \
;         acc[ai][bj][m][n] = __builtin_amdgcn_mfma_f32_16x16x32_bf16(Bt[n][k], At[m][k], acc[ai][bj][m][n], 0, 0, 0); __builtin_amdgcn_s_setprio(0); } while (0)
; #define PG8_WAIT_V(n) asm volatile("s_waitcnt vmcnt(" #n ")" ::: "memory")
; #define PG8_WAIT_L(n) asm volatile("s_waitcnt lgkmcnt(" #n ")" ::: "memory")
; #define PG8_BAR __builtin_amdgcn_s_barrier()
; #define PG8_SCHED __builtin_amdgcn_sched_barrier(0)
; template <class Epi, class Sched>
; __device__ __forceinline__ void gemm_phase(LAS unsigned char* lds, const Gemm g, const Sched& S, const Epi& E, int wave_id) {
;     ...
;             PG8_LDB(B0, 0, 0); PG8_LDB(B1, 0, 1); PG8_SCHED; PG8_LDA(At, 0, 0); PG8_STAGE(PG8_SA(1, 1), a1 + hstepA, voffA);
;             PG8_WAIT_V(8); PG8_WAIT_L(0); PG8_BAR; PG8_MMA(0, 0, At, B0); PG8_MMA(0, 1, At, B1); PG8_BAR; PG8_SCHED;
;             PG8_LDA(At, 0, 1); PG8_STAGE(PG8_SB(0, 0), b2, voffB); PG8_STAGE(PG8_SB(0, 1), b2 + hstepB, voffB); PG8_STAGE(PG8_SA(0, 0), a2, voffA);
;             PG8_WAIT_V(8); PG8_WAIT_L(0); PG8_BAR; PG8_MMA(1, 0, At, B0); PG8_MMA(1, 1, At, B1); PG8_BAR; PG8_SCHED;
.LBB0_937:
	ds_read_b128 v[8:11], v147
	ds_read_b128 v[12:15], v147 offset:1024
	ds_read_b128 v[16:19], v147 offset:2048
	ds_read_b128 v[20:23], v147 offset:3072
	ds_read_b128 v[24:27], v148
	ds_read_b128 v[28:31], v148 offset:1024
	ds_read_b128 v[32:35], v148 offset:2048
	ds_read_b128 v[36:39], v148 offset:3072
	s_add_u32 s64, s30, 0x18080
	s_addc_u32 s65, s31, 0
	s_mov_b32 m0, s48
	ds_read_b128 v[0:3], v138
	ds_read_b128 v[4:7], v138 offset:1024
	ds_read_b128 v[40:43], v138 offset:2048
	ds_read_b128 v[44:47], v138 offset:3072
	ds_read_b128 v[48:51], v138 offset:4096
	ds_read_b128 v[52:55], v138 offset:5120
	ds_read_b128 v[56:59], v138 offset:6144
	ds_read_b128 v[60:63], v138 offset:7168
	global_load_lds_dwordx4 v134, s[64:65]
	s_mov_b32 m0, s49
	s_nop 0
	global_load_lds_dwordx4 v130, s[64:65]
	s_waitcnt vmcnt(8)
	s_waitcnt lgkmcnt(0)
	s_barrier
	s_setprio 1
	s_waitcnt lgkmcnt(0)
	v_mfma_f32_16x16x32_bf16 v[64:67], v[8:11], v[0:3], 0
	v_mfma_f32_16x16x32_bf16 v[68:71], v[16:19], v[0:3], 0
	v_mfma_f32_16x16x32_bf16 v[72:75], v[8:11], v[40:43], 0
	v_mfma_f32_16x16x32_bf16 v[76:79], v[16:19], v[40:43], 0
	v_mfma_f32_16x16x32_bf16 v[80:83], v[8:11], v[48:51], 0
	v_mfma_f32_16x16x32_bf16 v[84:87], v[16:19], v[48:51], 0
	v_mfma_f32_16x16x32_bf16 v[88:91], v[8:11], v[56:59], 0
	v_mfma_f32_16x16x32_bf16 v[92:95], v[16:19], v[56:59], 0
	v_mfma_f32_16x16x32_bf16 v[64:67], v[12:15], v[4:7], v[64:67]
	v_mfma_f32_16x16x32_bf16 v[68:71], v[20:23], v[4:7], v[68:71]
	v_mfma_f32_16x16x32_bf16 v[72:75], v[12:15], v[44:47], v[72:75]
	v_mfma_f32_16x16x32_bf16 v[76:79], v[20:23], v[44:47], v[76:79]
	v_mfma_f32_16x16x32_bf16 v[80:83], v[12:15], v[52:55], v[80:83]
	v_mfma_f32_16x16x32_bf16 v[84:87], v[20:23], v[52:55], v[84:87]
	v_mfma_f32_16x16x32_bf16 v[88:91], v[12:15], v[60:63], v[88:91]
	v_mfma_f32_16x16x32_bf16 v[92:95], v[20:23], v[60:63], v[92:95]
	s_setprio 0
	s_setprio 1
	v_mfma_f32_16x16x32_bf16 v[96:99], v[24:27], v[0:3], 0
	v_mfma_f32_16x16x32_bf16 v[0:3], v[32:35], v[0:3], 0
	v_mfma_f32_16x16x32_bf16 v[100:103], v[36:39], v[4:7], v[0:3]
	v_mfma_f32_16x16x32_bf16 v[0:3], v[24:27], v[40:43], 0
	v_mfma_f32_16x16x32_bf16 v[104:107], v[28:31], v[44:47], v[0:3]
	v_mfma_f32_16x16x32_bf16 v[0:3], v[32:35], v[40:43], 0
	v_mfma_f32_16x16x32_bf16 v[40:43], v[36:39], v[44:47], v[0:3]
	v_mfma_f32_16x16x32_bf16 v[0:3], v[24:27], v[48:51], 0
	v_mfma_f32_16x16x32_bf16 v[44:47], v[28:31], v[52:55], v[0:3]
	v_mfma_f32_16x16x32_bf16 v[0:3], v[32:35], v[48:51], 0
	v_mfma_f32_16x16x32_bf16 v[48:51], v[36:39], v[52:55], v[0:3]
	v_mfma_f32_16x16x32_bf16 v[0:3], v[24:27], v[56:59], 0
	v_mfma_f32_16x16x32_bf16 v[52:55], v[28:31], v[60:63], v[0:3]
	v_mfma_f32_16x16x32_bf16 v[0:3], v[32:35], v[56:59], 0
	v_mfma_f32_16x16x32_bf16 v[96:99], v[28:31], v[4:7], v[96:99]
	v_mfma_f32_16x16x32_bf16 v[56:59], v[36:39], v[60:63], v[0:3]
	s_setprio 0
	s_barrier
	s_nop 3
	v_lshl_add_u64 v[0:1], s[34:35], 0, v[132:133]
	s_mov_b32 m0, s50
	v_lshl_add_u64 v[2:3], v[0:1], 0, s[18:19]
	ds_read_b128 v[60:63], v138 offset:16384
	ds_read_b128 v[108:111], v138 offset:17408
	ds_read_b128 v[112:115], v138 offset:18432
	ds_read_b128 v[116:119], v138 offset:19456
	ds_read_b128 v[120:123], v138 offset:20480
	ds_read_b128 v[124:127], v138 offset:21504
	ds_read_b128 v[152:155], v138 offset:22528
	ds_read_b128 v[156:159], v138 offset:23552
	global_load_lds_dwordx4 v[2:3], off
	v_lshl_add_u64 v[2:3], s[34:35], 0, v[128:129]
	s_add_u32 s64, s34, 0x18100
	v_lshl_add_u64 v[4:5], v[2:3], 0, s[18:19]
	s_mov_b32 m0, s51
	s_addc_u32 s65, s35, 0
	global_load_lds_dwordx4 v[4:5], off
	s_mov_b32 m0, s52
	s_nop 0
	global_load_lds_dwordx4 v132, s[64:65]
	s_mov_b32 m0, s53
	s_nop 0
	global_load_lds_dwordx4 v128, s[64:65]
	v_lshl_add_u64 v[4:5], s[30:31], 0, v[134:135]
	v_lshl_add_u64 v[6:7], v[4:5], 0, s[18:19]
	s_mov_b32 m0, s38
	s_nop 0
	global_load_lds_dwordx4 v[6:7], off
	v_lshl_add_u64 v[6:7], s[30:31], 0, v[130:131]
	v_lshl_add_u64 v[160:161], v[6:7], 0, s[18:19]
	s_mov_b32 m0, s39
	s_nop 0
	global_load_lds_dwordx4 v[160:161], off
	s_waitcnt vmcnt(8)
	s_waitcnt lgkmcnt(0)
	s_barrier
	s_setprio 1
	s_waitcnt lgkmcnt(0)
	v_mfma_f32_16x16x32_bf16 v[160:163], v[8:11], v[60:63], 0
	v_mfma_f32_16x16x32_bf16 v[168:171], v[8:11], v[112:115], 0
	v_mfma_f32_16x16x32_bf16 v[176:179], v[8:11], v[120:123], 0
	v_mfma_f32_16x16x32_bf16 v[8:11], v[8:11], v[152:155], 0
	v_mfma_f32_16x16x32_bf16 v[160:163], v[12:15], v[108:111], v[160:163]
	v_mfma_f32_16x16x32_bf16 v[168:171], v[12:15], v[116:119], v[168:171]
	v_mfma_f32_16x16x32_bf16 v[176:179], v[12:15], v[124:127], v[176:179]
	v_mfma_f32_16x16x32_bf16 v[8:11], v[12:15], v[156:159], v[8:11]
	v_mfma_f32_16x16x32_bf16 v[12:15], v[16:19], v[152:155], 0
	v_mfma_f32_16x16x32_bf16 v[164:167], v[16:19], v[60:63], 0
	v_mfma_f32_16x16x32_bf16 v[172:175], v[16:19], v[112:115], 0
	v_mfma_f32_16x16x32_bf16 v[180:183], v[16:19], v[120:123], 0
	v_mfma_f32_16x16x32_bf16 v[12:15], v[20:23], v[156:159], v[12:15]
	v_mfma_f32_16x16x32_bf16 v[164:167], v[20:23], v[108:111], v[164:167]
	v_mfma_f32_16x16x32_bf16 v[172:175], v[20:23], v[116:119], v[172:175]
	v_mfma_f32_16x16x32_bf16 v[180:183], v[20:23], v[124:127], v[180:183]
	s_setprio 0
	s_setprio 1
	v_mfma_f32_16x16x32_bf16 v[16:19], v[24:27], v[60:63], 0
	v_mfma_f32_16x16x32_bf16 v[20:23], v[32:35], v[60:63], 0
	v_mfma_f32_16x16x32_bf16 v[16:19], v[28:31], v[108:111], v[16:19]
	v_mfma_f32_16x16x32_bf16 v[20:23], v[36:39], v[108:111], v[20:23]
	v_mfma_f32_16x16x32_bf16 v[60:63], v[24:27], v[112:115], 0
	v_mfma_f32_16x16x32_bf16 v[108:111], v[32:35], v[112:115], 0
	v_mfma_f32_16x16x32_bf16 v[112:115], v[24:27], v[120:123], 0
	v_mfma_f32_16x16x32_bf16 v[24:27], v[24:27], v[152:155], 0
	v_mfma_f32_16x16x32_bf16 v[60:63], v[28:31], v[116:119], v[60:63]
	v_mfma_f32_16x16x32_bf16 v[108:111], v[36:39], v[116:119], v[108:111]
	v_mfma_f32_16x16x32_bf16 v[112:115], v[28:31], v[124:127], v[112:115]
	v_mfma_f32_16x16x32_bf16 v[116:119], v[32:35], v[120:123], 0
	v_mfma_f32_16x16x32_bf16 v[24:27], v[28:31], v[156:159], v[24:27]
	v_mfma_f32_16x16x32_bf16 v[28:31], v[32:35], v[152:155], 0
	v_mfma_f32_16x16x32_bf16 v[116:119], v[36:39], v[124:127], v[116:119]
	v_mfma_f32_16x16x32_bf16 v[28:31], v[36:39], v[156:159], v[28:31]
	s_setprio 0
	s_barrier
; #define PG8_STAGE(bufoff, gbase, voff) do { _Pragma("unroll") for (int _i = 0; _i < 2; ++_i) \
;         __builtin_amdgcn_global_load_lds((const unsigned*)((const char*)(gbase) + (voff)[_i]), (LAS unsigned*)(lds + (bufoff) + ldsw + _i * 8192), 16, 0, 0); } while (0)
; #define PG8_LDA(dst, b, h) do { _Pragma("unroll") for (int m = 0; m < 4; ++m) _Pragma("unroll") for (int k = 0; k < 2; ++k) dst[m][k] = *(const LAS bf16x8*)(lds + PG8_SA(b, h) + aoff + m * 2048 + k * 1024); } while (0)
; #define PG8_LDB(dst, b, h) do { _Pragma("unroll") for (int n = 0; n < 2; ++n) _Pragma("unroll") for (int k = 0; k < 2; ++k) dst[n][k] = *(const LAS bf16x8*)(lds + PG8_SB(b, h) + boff + n * 2048 + k * 1024); } while (0)
; #define PG8_MMA(ai, bj, At, Bt) do { __builtin_amdgcn_s_setprio(1); _Pragma("unroll") for (int m = 0; m < 4; ++m) _Pragma("unroll") for (int n = 0; n < 2; ++n) _Pragma("unroll") for (int k = 0; k < 2; ++k) \
;         acc[ai][bj][m][n] = __builtin_amdgcn_mfma_f32_16x16x32_bf16(Bt[n][k], At[m][k], acc[ai][bj][m][n], 0, 0, 0); __builtin_amdgcn_s_setprio(0); } while (0)
; #define PG8_WAIT_V(n) asm volatile("s_waitcnt vmcnt(" #n ")" ::: "memory")
; #define PG8_WAIT_L(n) asm volatile("s_waitcnt lgkmcnt(" #n ")" ::: "memory")
; #define PG8_BAR __builtin_amdgcn_s_barrier()
; #define PG8_SCHED __builtin_amdgcn_sched_barrier(0)
; template <class Epi, class Sched>
; __device__ __forceinline__ void gemm_phase(LAS unsigned char* lds, const Gemm g, const Sched& S, const Epi& E, int wave_id) {
;     ...
;             PG8_WAIT_V(8); PG8_WAIT_L(0); PG8_BAR; PG8_MMA(1, 0, At, B0); PG8_MMA(1, 1, At, B1); PG8_BAR; PG8_SCHED;
;             PG8_LDB(B0, 1, 0); PG8_LDB(B1, 1, 1); PG8_SCHED; PG8_LDA(At, 1, 0); PG8_STAGE(PG8_SA(0, 1), a2 + hstepA, voffA);
;             PG8_WAIT_V(8); PG8_WAIT_L(0); PG8_BAR; PG8_MMA(0, 0, At, B0); PG8_MMA(0, 1, At, B1); PG8_BAR; PG8_SCHED;
;             PG8_LDA(At, 1, 1); PG8_STAGE(PG8_SB(1, 0), b3, voffB); PG8_STAGE(PG8_SB(1, 1), b3 + hstepB, voffB); PG8_STAGE(PG8_SA(1, 0), a3, voffA);
;             PG8_WAIT_V(8); PG8_WAIT_L(0); PG8_BAR; PG8_MMA(1, 0, At, B0); PG8_MMA(1, 1, At, B1); PG8_BAR; PG8_SCHED;
	ds_read_b128 v[32:35], v149
	ds_read_b128 v[36:39], v149 offset:1024
	ds_read_b128 v[120:123], v149 offset:2048
	ds_read_b128 v[124:127], v149 offset:3072
	ds_read_b128 v[152:155], v150
	ds_read_b128 v[156:159], v150 offset:1024
	ds_read_b128 v[184:187], v150 offset:2048
	ds_read_b128 v[188:191], v150 offset:3072
	s_add_u32 s64, s30, 0x18100
	s_addc_u32 s65, s31, 0
	s_mov_b32 m0, s40
	ds_read_b128 v[192:195], v138 offset:32768
	ds_read_b128 v[196:199], v138 offset:33792
	ds_read_b128 v[200:203], v138 offset:34816
	ds_read_b128 v[204:207], v138 offset:35840
	ds_read_b128 v[208:211], v138 offset:36864
	ds_read_b128 v[212:215], v138 offset:37888
	ds_read_b128 v[216:219], v138 offset:38912
	ds_read_b128 v[220:223], v138 offset:39936
	global_load_lds_dwordx4 v134, s[64:65]
	s_mov_b32 m0, s41
	s_nop 0
	global_load_lds_dwordx4 v130, s[64:65]
	s_waitcnt vmcnt(8)
	s_waitcnt lgkmcnt(0)
	s_barrier
	s_setprio 1
	s_waitcnt lgkmcnt(0)
	v_mfma_f32_16x16x32_bf16 v[64:67], v[32:35], v[192:195], v[64:67]
	v_mfma_f32_16x16x32_bf16 v[68:71], v[120:123], v[192:195], v[68:71]
	v_mfma_f32_16x16x32_bf16 v[72:75], v[32:35], v[200:203], v[72:75]
	v_mfma_f32_16x16x32_bf16 v[76:79], v[120:123], v[200:203], v[76:79]
	v_mfma_f32_16x16x32_bf16 v[80:83], v[32:35], v[208:211], v[80:83]
	v_mfma_f32_16x16x32_bf16 v[84:87], v[120:123], v[208:211], v[84:87]
	v_mfma_f32_16x16x32_bf16 v[88:91], v[32:35], v[216:219], v[88:91]
	v_mfma_f32_16x16x32_bf16 v[92:95], v[120:123], v[216:219], v[92:95]
	v_mfma_f32_16x16x32_bf16 v[64:67], v[36:39], v[196:199], v[64:67]
	v_mfma_f32_16x16x32_bf16 v[68:71], v[124:127], v[196:199], v[68:71]
	v_mfma_f32_16x16x32_bf16 v[72:75], v[36:39], v[204:207], v[72:75]
	v_mfma_f32_16x16x32_bf16 v[76:79], v[124:127], v[204:207], v[76:79]
	v_mfma_f32_16x16x32_bf16 v[80:83], v[36:39], v[212:215], v[80:83]
	v_mfma_f32_16x16x32_bf16 v[84:87], v[124:127], v[212:215], v[84:87]
	v_mfma_f32_16x16x32_bf16 v[88:91], v[36:39], v[220:223], v[88:91]
	v_mfma_f32_16x16x32_bf16 v[92:95], v[124:127], v[220:223], v[92:95]
	s_setprio 0
	s_setprio 1
	v_mfma_f32_16x16x32_bf16 v[96:99], v[152:155], v[192:195], v[96:99]
	v_mfma_f32_16x16x32_bf16 v[100:103], v[184:187], v[192:195], v[100:103]
	v_mfma_f32_16x16x32_bf16 v[104:107], v[152:155], v[200:203], v[104:107]
	v_mfma_f32_16x16x32_bf16 v[40:43], v[184:187], v[200:203], v[40:43]
	v_mfma_f32_16x16x32_bf16 v[44:47], v[152:155], v[208:211], v[44:47]
	v_mfma_f32_16x16x32_bf16 v[48:51], v[184:187], v[208:211], v[48:51]
	v_mfma_f32_16x16x32_bf16 v[52:55], v[152:155], v[216:219], v[52:55]
	v_mfma_f32_16x16x32_bf16 v[56:59], v[184:187], v[216:219], v[56:59]
	v_mfma_f32_16x16x32_bf16 v[96:99], v[156:159], v[196:199], v[96:99]
	v_mfma_f32_16x16x32_bf16 v[100:103], v[188:191], v[196:199], v[100:103]
	v_mfma_f32_16x16x32_bf16 v[104:107], v[156:159], v[204:207], v[104:107]
	v_mfma_f32_16x16x32_bf16 v[40:43], v[188:191], v[204:207], v[40:43]
	v_mfma_f32_16x16x32_bf16 v[44:47], v[156:159], v[212:215], v[44:47]
	v_mfma_f32_16x16x32_bf16 v[48:51], v[188:191], v[212:215], v[48:51]
	v_mfma_f32_16x16x32_bf16 v[52:55], v[156:159], v[220:223], v[52:55]
	v_mfma_f32_16x16x32_bf16 v[56:59], v[188:191], v[220:223], v[56:59]
	s_setprio 0
	s_barrier
	s_mov_b32 m0, s54
	v_lshl_add_u64 v[224:225], v[0:1], 0, s[20:21]
	s_add_u32 s64, s34, 0x18180
	ds_read_b128 v[192:195], v138 offset:49152
	ds_read_b128 v[196:199], v138 offset:50176
	ds_read_b128 v[200:203], v138 offset:51200
	ds_read_b128 v[204:207], v138 offset:52224
	ds_read_b128 v[208:211], v138 offset:53248
	ds_read_b128 v[212:215], v138 offset:54272
	ds_read_b128 v[216:219], v138 offset:55296
	ds_read_b128 v[220:223], v138 offset:56320
	global_load_lds_dwordx4 v[224:225], off
	v_lshl_add_u64 v[224:225], v[2:3], 0, s[20:21]
	s_mov_b32 m0, s55
	s_addc_u32 s65, s35, 0
	global_load_lds_dwordx4 v[224:225], off
	s_mov_b32 m0, s58
	s_nop 0
	global_load_lds_dwordx4 v132, s[64:65]
	s_mov_b32 m0, s59
	s_nop 0
	global_load_lds_dwordx4 v128, s[64:65]
	v_lshl_add_u64 v[224:225], v[4:5], 0, s[20:21]
	s_mov_b32 m0, s43
	s_nop 0
	global_load_lds_dwordx4 v[224:225], off
	v_lshl_add_u64 v[224:225], v[6:7], 0, s[20:21]
	s_mov_b32 m0, s44
	s_nop 0
	global_load_lds_dwordx4 v[224:225], off
	s_waitcnt vmcnt(8)
	s_waitcnt lgkmcnt(0)
	s_barrier
	s_setprio 1
	s_waitcnt lgkmcnt(0)
	v_mfma_f32_16x16x32_bf16 v[8:11], v[32:35], v[216:219], v[8:11]
	v_mfma_f32_16x16x32_bf16 v[12:15], v[120:123], v[216:219], v[12:15]
	v_mfma_f32_16x16x32_bf16 v[160:163], v[32:35], v[192:195], v[160:163]
	v_mfma_f32_16x16x32_bf16 v[164:167], v[120:123], v[192:195], v[164:167]
	v_mfma_f32_16x16x32_bf16 v[168:171], v[32:35], v[200:203], v[168:171]
	v_mfma_f32_16x16x32_bf16 v[172:175], v[120:123], v[200:203], v[172:175]
	v_mfma_f32_16x16x32_bf16 v[176:179], v[32:35], v[208:211], v[176:179]
	v_mfma_f32_16x16x32_bf16 v[180:183], v[120:123], v[208:211], v[180:183]
	v_mfma_f32_16x16x32_bf16 v[8:11], v[36:39], v[220:223], v[8:11]
	v_mfma_f32_16x16x32_bf16 v[12:15], v[124:127], v[220:223], v[12:15]
	v_mfma_f32_16x16x32_bf16 v[160:163], v[36:39], v[196:199], v[160:163]
	v_mfma_f32_16x16x32_bf16 v[164:167], v[124:127], v[196:199], v[164:167]
	v_mfma_f32_16x16x32_bf16 v[168:171], v[36:39], v[204:207], v[168:171]
	v_mfma_f32_16x16x32_bf16 v[172:175], v[124:127], v[204:207], v[172:175]
	v_mfma_f32_16x16x32_bf16 v[176:179], v[36:39], v[212:215], v[176:179]
	v_mfma_f32_16x16x32_bf16 v[180:183], v[124:127], v[212:215], v[180:183]
	s_setprio 0
	s_setprio 1
	v_mfma_f32_16x16x32_bf16 v[16:19], v[152:155], v[192:195], v[16:19]
	v_mfma_f32_16x16x32_bf16 v[20:23], v[184:187], v[192:195], v[20:23]
	v_mfma_f32_16x16x32_bf16 v[32:35], v[152:155], v[200:203], v[60:63]
	v_mfma_f32_16x16x32_bf16 v[36:39], v[184:187], v[200:203], v[108:111]
	v_mfma_f32_16x16x32_bf16 v[60:63], v[152:155], v[208:211], v[112:115]
	v_mfma_f32_16x16x32_bf16 v[108:111], v[184:187], v[208:211], v[116:119]
	v_mfma_f32_16x16x32_bf16 v[24:27], v[152:155], v[216:219], v[24:27]
	v_mfma_f32_16x16x32_bf16 v[28:31], v[184:187], v[216:219], v[28:31]
	v_mfma_f32_16x16x32_bf16 v[16:19], v[156:159], v[196:199], v[16:19]
	v_mfma_f32_16x16x32_bf16 v[20:23], v[188:191], v[196:199], v[20:23]
	v_mfma_f32_16x16x32_bf16 v[32:35], v[156:159], v[204:207], v[32:35]
	v_mfma_f32_16x16x32_bf16 v[36:39], v[188:191], v[204:207], v[36:39]
	v_mfma_f32_16x16x32_bf16 v[60:63], v[156:159], v[212:215], v[60:63]
	v_mfma_f32_16x16x32_bf16 v[108:111], v[188:191], v[212:215], v[108:111]
	v_mfma_f32_16x16x32_bf16 v[24:27], v[156:159], v[220:223], v[24:27]
	v_mfma_f32_16x16x32_bf16 v[28:31], v[188:191], v[220:223], v[28:31]
	s_setprio 0
	s_barrier
; #define PG8_STAGE(bufoff, gbase, voff) do { _Pragma("unroll") for (int _i = 0; _i < 2; ++_i) \
;         __builtin_amdgcn_global_load_lds((const unsigned*)((const char*)(gbase) + (voff)[_i]), (LAS unsigned*)(lds + (bufoff) + ldsw + _i * 8192), 16, 0, 0); } while (0)
; #define PG8_LDA(dst, b, h) do { _Pragma("unroll") for (int m = 0; m < 4; ++m) _Pragma("unroll") for (int k = 0; k < 2; ++k) dst[m][k] = *(const LAS bf16x8*)(lds + PG8_SA(b, h) + aoff + m * 2048 + k * 1024); } while (0)
; #define PG8_LDB(dst, b, h) do { _Pragma("unroll") for (int n = 0; n < 2; ++n) _Pragma("unroll") for (int k = 0; k < 2; ++k) dst[n][k] = *(const LAS bf16x8*)(lds + PG8_SB(b, h) + boff + n * 2048 + k * 1024); } while (0)
; #define PG8_MMA(ai, bj, At, Bt) do { __builtin_amdgcn_s_setprio(1); _Pragma("unroll") for (int m = 0; m < 4; ++m) _Pragma("unroll") for (int n = 0; n < 2; ++n) _Pragma("unroll") for (int k = 0; k < 2; ++k) \
;         acc[ai][bj][m][n] = __builtin_amdgcn_mfma_f32_16x16x32_bf16(Bt[n][k], At[m][k], acc[ai][bj][m][n], 0, 0, 0); __builtin_amdgcn_s_setprio(0); } while (0)
; template <class Epi, class Sched>
; __device__ __forceinline__ void gemm_phase(LAS unsigned char* lds, const Gemm g, const Sched& S, const Epi& E, int wave_id) {
;     ...
;         for (int t = 0; t < nt; t += 2) {
;             const bool last = (t == nt - 2);
;             const char* a1 = cA + (size_t)(t + 1) * kstep;
;             const char* a2 = last ? nA : cA + (size_t)(t + 2) * kstep; const char* b2 = last ? nB : cB + (size_t)(t + 2) * kstep;
;             const char* a3 = a2 + kstep; const char* b3 = b2 + kstep;
;             PG8_LDB(B0, 0, 0); PG8_LDB(B1, 0, 1); PG8_SCHED; PG8_LDA(At, 0, 0); PG8_STAGE(PG8_SA(1, 1), a1 + hstepA, voffA);
;             PG8_WAIT_V(8); PG8_WAIT_L(0); PG8_BAR; PG8_MMA(0, 0, At, B0); PG8_MMA(0, 1, At, B1); PG8_BAR; PG8_SCHED;
;             PG8_LDA(At, 0, 1); PG8_STAGE(PG8_SB(0, 0), b2, voffB); PG8_STAGE(PG8_SB(0, 1), b2 + hstepB, voffB); PG8_STAGE(PG8_SA(0, 0), a2, voffA);
;             PG8_WAIT_V(8); PG8_WAIT_L(0); PG8_BAR; PG8_MMA(1, 0, At, B0); PG8_MMA(1, 1, At, B1); PG8_BAR; PG8_SCHED;
;             PG8_LDB(B0, 1, 0); PG8_LDB(B1, 1, 1); PG8_SCHED; PG8_LDA(At, 1, 0); PG8_STAGE(PG8_SA(0, 1), a2 + hstepA, voffA);
;             PG8_WAIT_V(8); PG8_WAIT_L(0); PG8_BAR; PG8_MMA(0, 0, At, B0); PG8_MMA(0, 1, At, B1); PG8_BAR; PG8_SCHED;
	ds_read_b128 v[112:115], v147
	ds_read_b128 v[116:119], v147 offset:1024
	ds_read_b128 v[120:123], v147 offset:2048
	ds_read_b128 v[124:127], v147 offset:3072
	ds_read_b128 v[152:155], v148
	ds_read_b128 v[156:159], v148 offset:1024
	ds_read_b128 v[184:187], v148 offset:2048
	ds_read_b128 v[188:191], v148 offset:3072
	s_add_u32 s64, s30, 0x18180
	s_addc_u32 s65, s31, 0
	s_mov_b32 m0, s48
	ds_read_b128 v[192:195], v138
	ds_read_b128 v[196:199], v138 offset:1024
	ds_read_b128 v[200:203], v138 offset:2048
	ds_read_b128 v[204:207], v138 offset:3072
	ds_read_b128 v[208:211], v138 offset:4096
	ds_read_b128 v[212:215], v138 offset:5120
	ds_read_b128 v[216:219], v138 offset:6144
	ds_read_b128 v[220:223], v138 offset:7168
	global_load_lds_dwordx4 v134, s[64:65]
	s_mov_b32 m0, s49
	s_nop 0
	global_load_lds_dwordx4 v130, s[64:65]
	s_waitcnt vmcnt(8)
	s_waitcnt lgkmcnt(0)
	s_barrier
	s_setprio 1
	s_waitcnt lgkmcnt(0)
	v_mfma_f32_16x16x32_bf16 v[64:67], v[112:115], v[192:195], v[64:67]
	v_mfma_f32_16x16x32_bf16 v[68:71], v[120:123], v[192:195], v[68:71]
	v_mfma_f32_16x16x32_bf16 v[72:75], v[112:115], v[200:203], v[72:75]
	v_mfma_f32_16x16x32_bf16 v[76:79], v[120:123], v[200:203], v[76:79]
	v_mfma_f32_16x16x32_bf16 v[80:83], v[112:115], v[208:211], v[80:83]
	v_mfma_f32_16x16x32_bf16 v[84:87], v[120:123], v[208:211], v[84:87]
	v_mfma_f32_16x16x32_bf16 v[88:91], v[112:115], v[216:219], v[88:91]
	v_mfma_f32_16x16x32_bf16 v[92:95], v[120:123], v[216:219], v[92:95]
	v_mfma_f32_16x16x32_bf16 v[64:67], v[116:119], v[196:199], v[64:67]
	v_mfma_f32_16x16x32_bf16 v[68:71], v[124:127], v[196:199], v[68:71]
	v_mfma_f32_16x16x32_bf16 v[72:75], v[116:119], v[204:207], v[72:75]
	v_mfma_f32_16x16x32_bf16 v[76:79], v[124:127], v[204:207], v[76:79]
	v_mfma_f32_16x16x32_bf16 v[80:83], v[116:119], v[212:215], v[80:83]
	v_mfma_f32_16x16x32_bf16 v[84:87], v[124:127], v[212:215], v[84:87]
	v_mfma_f32_16x16x32_bf16 v[88:91], v[116:119], v[220:223], v[88:91]
	v_mfma_f32_16x16x32_bf16 v[92:95], v[124:127], v[220:223], v[92:95]
	s_setprio 0
	s_setprio 1
	v_mfma_f32_16x16x32_bf16 v[96:99], v[152:155], v[192:195], v[96:99]
	v_mfma_f32_16x16x32_bf16 v[100:103], v[184:187], v[192:195], v[100:103]
	v_mfma_f32_16x16x32_bf16 v[104:107], v[152:155], v[200:203], v[104:107]
	v_mfma_f32_16x16x32_bf16 v[40:43], v[184:187], v[200:203], v[40:43]
	v_mfma_f32_16x16x32_bf16 v[44:47], v[152:155], v[208:211], v[44:47]
	v_mfma_f32_16x16x32_bf16 v[48:51], v[184:187], v[208:211], v[48:51]
	v_mfma_f32_16x16x32_bf16 v[52:55], v[152:155], v[216:219], v[52:55]
	v_mfma_f32_16x16x32_bf16 v[56:59], v[184:187], v[216:219], v[56:59]
	v_mfma_f32_16x16x32_bf16 v[96:99], v[156:159], v[196:199], v[96:99]
	v_mfma_f32_16x16x32_bf16 v[100:103], v[188:191], v[196:199], v[100:103]
	v_mfma_f32_16x16x32_bf16 v[104:107], v[156:159], v[204:207], v[104:107]
	v_mfma_f32_16x16x32_bf16 v[40:43], v[188:191], v[204:207], v[40:43]
	v_mfma_f32_16x16x32_bf16 v[44:47], v[156:159], v[212:215], v[44:47]
	v_mfma_f32_16x16x32_bf16 v[48:51], v[188:191], v[212:215], v[48:51]
	v_mfma_f32_16x16x32_bf16 v[52:55], v[156:159], v[220:223], v[52:55]
	v_mfma_f32_16x16x32_bf16 v[56:59], v[188:191], v[220:223], v[56:59]
	s_setprio 0
	s_barrier
	s_mov_b32 m0, s50
	v_lshl_add_u64 v[224:225], v[0:1], 0, s[22:23]
	s_add_u32 s64, s34, 0x18200
	ds_read_b128 v[192:195], v138 offset:16384
	ds_read_b128 v[196:199], v138 offset:17408
	ds_read_b128 v[200:203], v138 offset:18432
	ds_read_b128 v[204:207], v138 offset:19456
	ds_read_b128 v[208:211], v138 offset:20480
	ds_read_b128 v[212:215], v138 offset:21504
	ds_read_b128 v[216:219], v138 offset:22528
	ds_read_b128 v[220:223], v138 offset:23552
	global_load_lds_dwordx4 v[224:225], off
	v_lshl_add_u64 v[224:225], v[2:3], 0, s[22:23]
	s_mov_b32 m0, s51
	s_addc_u32 s65, s35, 0
	global_load_lds_dwordx4 v[224:225], off
	s_mov_b32 m0, s52
	s_nop 0
	global_load_lds_dwordx4 v132, s[64:65]
	s_mov_b32 m0, s53
	s_nop 0
	global_load_lds_dwordx4 v128, s[64:65]
	v_lshl_add_u64 v[224:225], v[4:5], 0, s[22:23]
	s_mov_b32 m0, s38
	s_nop 0
	global_load_lds_dwordx4 v[224:225], off
	v_lshl_add_u64 v[224:225], v[6:7], 0, s[22:23]
	s_mov_b32 m0, s39
	s_nop 0
	global_load_lds_dwordx4 v[224:225], off
	s_waitcnt vmcnt(8)
	s_waitcnt lgkmcnt(0)
	s_barrier
	s_setprio 1
	s_waitcnt lgkmcnt(0)
	v_mfma_f32_16x16x32_bf16 v[8:11], v[112:115], v[216:219], v[8:11]
	v_mfma_f32_16x16x32_bf16 v[12:15], v[120:123], v[216:219], v[12:15]
	v_mfma_f32_16x16x32_bf16 v[160:163], v[112:115], v[192:195], v[160:163]
	v_mfma_f32_16x16x32_bf16 v[164:167], v[120:123], v[192:195], v[164:167]
	v_mfma_f32_16x16x32_bf16 v[168:171], v[112:115], v[200:203], v[168:171]
	v_mfma_f32_16x16x32_bf16 v[172:175], v[120:123], v[200:203], v[172:175]
	v_mfma_f32_16x16x32_bf16 v[176:179], v[112:115], v[208:211], v[176:179]
	v_mfma_f32_16x16x32_bf16 v[180:183], v[120:123], v[208:211], v[180:183]
	v_mfma_f32_16x16x32_bf16 v[8:11], v[116:119], v[220:223], v[8:11]
	v_mfma_f32_16x16x32_bf16 v[12:15], v[124:127], v[220:223], v[12:15]
	v_mfma_f32_16x16x32_bf16 v[160:163], v[116:119], v[196:199], v[160:163]
	v_mfma_f32_16x16x32_bf16 v[164:167], v[124:127], v[196:199], v[164:167]
	v_mfma_f32_16x16x32_bf16 v[168:171], v[116:119], v[204:207], v[168:171]
	v_mfma_f32_16x16x32_bf16 v[172:175], v[124:127], v[204:207], v[172:175]
	v_mfma_f32_16x16x32_bf16 v[176:179], v[116:119], v[212:215], v[176:179]
	v_mfma_f32_16x16x32_bf16 v[180:183], v[124:127], v[212:215], v[180:183]
	s_setprio 0
	s_setprio 1
	v_mfma_f32_16x16x32_bf16 v[16:19], v[152:155], v[192:195], v[16:19]
	v_mfma_f32_16x16x32_bf16 v[20:23], v[184:187], v[192:195], v[20:23]
	v_mfma_f32_16x16x32_bf16 v[32:35], v[152:155], v[200:203], v[32:35]
	v_mfma_f32_16x16x32_bf16 v[36:39], v[184:187], v[200:203], v[36:39]
	v_mfma_f32_16x16x32_bf16 v[60:63], v[152:155], v[208:211], v[60:63]
	v_mfma_f32_16x16x32_bf16 v[108:111], v[184:187], v[208:211], v[108:111]
	v_mfma_f32_16x16x32_bf16 v[24:27], v[152:155], v[216:219], v[24:27]
	v_mfma_f32_16x16x32_bf16 v[28:31], v[184:187], v[216:219], v[28:31]
	v_mfma_f32_16x16x32_bf16 v[16:19], v[156:159], v[196:199], v[16:19]
	v_mfma_f32_16x16x32_bf16 v[20:23], v[188:191], v[196:199], v[20:23]
	v_mfma_f32_16x16x32_bf16 v[32:35], v[156:159], v[204:207], v[32:35]
	v_mfma_f32_16x16x32_bf16 v[36:39], v[188:191], v[204:207], v[36:39]
	v_mfma_f32_16x16x32_bf16 v[60:63], v[156:159], v[212:215], v[60:63]
	v_mfma_f32_16x16x32_bf16 v[108:111], v[188:191], v[212:215], v[108:111]
	v_mfma_f32_16x16x32_bf16 v[24:27], v[156:159], v[220:223], v[24:27]
	v_mfma_f32_16x16x32_bf16 v[28:31], v[188:191], v[220:223], v[28:31]
	s_setprio 0
	s_barrier
; #define PG8_STAGE(bufoff, gbase, voff) do { _Pragma("unroll") for (int _i = 0; _i < 2; ++_i) \
;         __builtin_amdgcn_global_load_lds((const unsigned*)((const char*)(gbase) + (voff)[_i]), (LAS unsigned*)(lds + (bufoff) + ldsw + _i * 8192), 16, 0, 0); } while (0)
; #define PG8_LDA(dst, b, h) do { _Pragma("unroll") for (int m = 0; m < 4; ++m) _Pragma("unroll") for (int k = 0; k < 2; ++k) dst[m][k] = *(const LAS bf16x8*)(lds + PG8_SA(b, h) + aoff + m * 2048 + k * 1024); } while (0)
; #define PG8_LDB(dst, b, h) do { _Pragma("unroll") for (int n = 0; n < 2; ++n) _Pragma("unroll") for (int k = 0; k < 2; ++k) dst[n][k] = *(const LAS bf16x8*)(lds + PG8_SB(b, h) + boff + n * 2048 + k * 1024); } while (0)
; #define PG8_WAIT_V(n) asm volatile("s_waitcnt vmcnt(" #n ")" ::: "memory")
; #define PG8_BAR __builtin_amdgcn_s_barrier()
; template <class Epi, class Sched>
; __device__ __forceinline__ void gemm_phase(LAS unsigned char* lds, const Gemm g, const Sched& S, const Epi& E, int wave_id) {
;     ...
;         for (int t = 0; t < nt; t += 2) {
;             const bool last = (t == nt - 2);
;             const char* a1 = cA + (size_t)(t + 1) * kstep;
;             const char* a2 = last ? nA : cA + (size_t)(t + 2) * kstep; const char* b2 = last ? nB : cB + (size_t)(t + 2) * kstep;
;             const char* a3 = a2 + kstep; const char* b3 = b2 + kstep;
;             PG8_LDB(B0, 0, 0); PG8_LDB(B1, 0, 1); PG8_SCHED; PG8_LDA(At, 0, 0); PG8_STAGE(PG8_SA(1, 1), a1 + hstepA, voffA);
;             PG8_WAIT_V(8); PG8_WAIT_L(0); PG8_BAR; PG8_MMA(0, 0, At, B0); PG8_MMA(0, 1, At, B1); PG8_BAR; PG8_SCHED;
;             PG8_LDA(At, 0, 1); PG8_STAGE(PG8_SB(0, 0), b2, voffB); PG8_STAGE(PG8_SB(0, 1), b2 + hstepB, voffB); PG8_STAGE(PG8_SA(0, 0), a2, voffA);
;             PG8_WAIT_V(8); PG8_WAIT_L(0); PG8_BAR; PG8_MMA(1, 0, At, B0); PG8_MMA(1, 1, At, B1); PG8_BAR; PG8_SCHED;
;             PG8_LDB(B0, 1, 0); PG8_LDB(B1, 1, 1); PG8_SCHED; PG8_LDA(At, 1, 0); PG8_STAGE(PG8_SA(0, 1), a2 + hstepA, voffA);
;             PG8_WAIT_V(8); PG8_WAIT_L(0); PG8_BAR; PG8_MMA(0, 0, At, B0); PG8_MMA(0, 1, At, B1); PG8_BAR; PG8_SCHED;
;             PG8_LDA(At, 1, 1); PG8_STAGE(PG8_SB(1, 0), b3, voffB); PG8_STAGE(PG8_SB(1, 1), b3 + hstepB, voffB); PG8_STAGE(PG8_SA(1, 0), a3, voffA);
;             PG8_WAIT_V(8); PG8_WAIT_L(0); PG8_BAR; PG8_MMA(1, 0, At, B0); PG8_MMA(1, 1, At, B1); PG8_BAR; PG8_SCHED;
	ds_read_b128 v[112:115], v149
	ds_read_b128 v[116:119], v149 offset:1024
	ds_read_b128 v[120:123], v149 offset:2048
	ds_read_b128 v[124:127], v149 offset:3072
	ds_read_b128 v[152:155], v150
	ds_read_b128 v[156:159], v150 offset:1024
	ds_read_b128 v[184:187], v150 offset:2048
	ds_read_b128 v[188:191], v150 offset:3072
	s_add_u32 s64, s30, 0x18200
	s_addc_u32 s65, s31, 0
	s_mov_b32 m0, s40
	ds_read_b128 v[192:195], v138 offset:32768
	ds_read_b128 v[196:199], v138 offset:33792
	ds_read_b128 v[200:203], v138 offset:34816
	ds_read_b128 v[204:207], v138 offset:35840
	ds_read_b128 v[208:211], v138 offset:36864
	ds_read_b128 v[212:215], v138 offset:37888
	ds_read_b128 v[216:219], v138 offset:38912
	ds_read_b128 v[220:223], v138 offset:39936
	global_load_lds_dwordx4 v134, s[64:65]
	s_mov_b32 m0, s41
	s_nop 0
	global_load_lds_dwordx4 v130, s[64:65]
	s_waitcnt vmcnt(8)
	s_waitcnt lgkmcnt(0)
	s_barrier
	s_setprio 1
	s_waitcnt lgkmcnt(0)
	v_mfma_f32_16x16x32_bf16 v[64:67], v[112:115], v[192:195], v[64:67]
	v_mfma_f32_16x16x32_bf16 v[68:71], v[120:123], v[192:195], v[68:71]
	v_mfma_f32_16x16x32_bf16 v[72:75], v[112:115], v[200:203], v[72:75]
	v_mfma_f32_16x16x32_bf16 v[76:79], v[120:123], v[200:203], v[76:79]
	v_mfma_f32_16x16x32_bf16 v[80:83], v[112:115], v[208:211], v[80:83]
	v_mfma_f32_16x16x32_bf16 v[84:87], v[120:123], v[208:211], v[84:87]
	v_mfma_f32_16x16x32_bf16 v[88:91], v[112:115], v[216:219], v[88:91]
	v_mfma_f32_16x16x32_bf16 v[92:95], v[120:123], v[216:219], v[92:95]
	v_mfma_f32_16x16x32_bf16 v[64:67], v[116:119], v[196:199], v[64:67]
	v_mfma_f32_16x16x32_bf16 v[68:71], v[124:127], v[196:199], v[68:71]
	v_mfma_f32_16x16x32_bf16 v[72:75], v[116:119], v[204:207], v[72:75]
	v_mfma_f32_16x16x32_bf16 v[76:79], v[124:127], v[204:207], v[76:79]
	v_mfma_f32_16x16x32_bf16 v[80:83], v[116:119], v[212:215], v[80:83]
	v_mfma_f32_16x16x32_bf16 v[84:87], v[124:127], v[212:215], v[84:87]
	v_mfma_f32_16x16x32_bf16 v[88:91], v[116:119], v[220:223], v[88:91]
	v_mfma_f32_16x16x32_bf16 v[92:95], v[124:127], v[220:223], v[92:95]
	s_setprio 0
	s_setprio 1
	v_mfma_f32_16x16x32_bf16 v[96:99], v[152:155], v[192:195], v[96:99]
	v_mfma_f32_16x16x32_bf16 v[100:103], v[184:187], v[192:195], v[100:103]
	v_mfma_f32_16x16x32_bf16 v[104:107], v[152:155], v[200:203], v[104:107]
	v_mfma_f32_16x16x32_bf16 v[40:43], v[184:187], v[200:203], v[40:43]
	v_mfma_f32_16x16x32_bf16 v[44:47], v[152:155], v[208:211], v[44:47]
	v_mfma_f32_16x16x32_bf16 v[48:51], v[184:187], v[208:211], v[48:51]
	v_mfma_f32_16x16x32_bf16 v[52:55], v[152:155], v[216:219], v[52:55]
	v_mfma_f32_16x16x32_bf16 v[56:59], v[184:187], v[216:219], v[56:59]
	v_mfma_f32_16x16x32_bf16 v[96:99], v[156:159], v[196:199], v[96:99]
	v_mfma_f32_16x16x32_bf16 v[100:103], v[188:191], v[196:199], v[100:103]
	v_mfma_f32_16x16x32_bf16 v[104:107], v[156:159], v[204:207], v[104:107]
	v_mfma_f32_16x16x32_bf16 v[40:43], v[188:191], v[204:207], v[40:43]
	v_mfma_f32_16x16x32_bf16 v[44:47], v[156:159], v[212:215], v[44:47]
	v_mfma_f32_16x16x32_bf16 v[48:51], v[188:191], v[212:215], v[48:51]
	v_mfma_f32_16x16x32_bf16 v[52:55], v[156:159], v[220:223], v[52:55]
	v_mfma_f32_16x16x32_bf16 v[56:59], v[188:191], v[220:223], v[56:59]
	s_setprio 0
	s_barrier
	s_mov_b32 m0, s54
	v_lshl_add_u64 v[0:1], v[0:1], 0, s[24:25]
	s_add_u32 s34, s34, 0x18280
	ds_read_b128 v[192:195], v138 offset:49152
	ds_read_b128 v[196:199], v138 offset:50176
	ds_read_b128 v[200:203], v138 offset:51200
	ds_read_b128 v[204:207], v138 offset:52224
	ds_read_b128 v[208:211], v138 offset:53248
	ds_read_b128 v[212:215], v138 offset:54272
	ds_read_b128 v[216:219], v138 offset:55296
	ds_read_b128 v[220:223], v138 offset:56320
	global_load_lds_dwordx4 v[0:1], off
	v_lshl_add_u64 v[0:1], v[2:3], 0, s[24:25]
	s_mov_b32 m0, s55
	s_addc_u32 s35, s35, 0
	global_load_lds_dwordx4 v[0:1], off
	s_mov_b32 m0, s58
	s_nop 0
	global_load_lds_dwordx4 v132, s[34:35]
	s_mov_b32 m0, s59
	s_nop 0
	global_load_lds_dwordx4 v128, s[34:35]
	v_lshl_add_u64 v[0:1], v[4:5], 0, s[24:25]
	s_mov_b32 m0, s43
	s_nop 0
	global_load_lds_dwordx4 v[0:1], off
	v_lshl_add_u64 v[0:1], v[6:7], 0, s[24:25]
	s_mov_b32 m0, s44
	s_nop 0
	global_load_lds_dwordx4 v[0:1], off
	s_waitcnt vmcnt(8)
	s_waitcnt lgkmcnt(0)
	s_barrier
	s_setprio 1
	s_waitcnt lgkmcnt(0)
	v_mfma_f32_16x16x32_bf16 v[0:3], v[112:115], v[192:195], v[160:163]
	v_mfma_f32_16x16x32_bf16 v[4:7], v[120:123], v[192:195], v[164:167]
	v_mfma_f32_16x16x32_bf16 v[8:11], v[112:115], v[216:219], v[8:11]
	v_mfma_f32_16x16x32_bf16 v[12:15], v[120:123], v[216:219], v[12:15]
	v_mfma_f32_16x16x32_bf16 v[0:3], v[116:119], v[196:199], v[0:3]
	v_mfma_f32_16x16x32_bf16 v[4:7], v[124:127], v[196:199], v[4:7]
	v_mfma_f32_16x16x32_bf16 v[160:163], v[112:115], v[200:203], v[168:171]
	v_mfma_f32_16x16x32_bf16 v[164:167], v[120:123], v[200:203], v[172:175]
	v_mfma_f32_16x16x32_bf16 v[168:171], v[112:115], v[208:211], v[176:179]
	v_mfma_f32_16x16x32_bf16 v[172:175], v[120:123], v[208:211], v[180:183]
	v_mfma_f32_16x16x32_bf16 v[8:11], v[116:119], v[220:223], v[8:11]
	v_mfma_f32_16x16x32_bf16 v[12:15], v[124:127], v[220:223], v[12:15]
	v_mfma_f32_16x16x32_bf16 v[160:163], v[116:119], v[204:207], v[160:163]
	v_mfma_f32_16x16x32_bf16 v[164:167], v[124:127], v[204:207], v[164:167]
	v_mfma_f32_16x16x32_bf16 v[168:171], v[116:119], v[212:215], v[168:171]
	v_mfma_f32_16x16x32_bf16 v[172:175], v[124:127], v[212:215], v[172:175]
	s_setprio 0
	s_setprio 1
	v_mfma_f32_16x16x32_bf16 v[16:19], v[152:155], v[192:195], v[16:19]
	v_mfma_f32_16x16x32_bf16 v[20:23], v[184:187], v[192:195], v[20:23]
	v_mfma_f32_16x16x32_bf16 v[32:35], v[152:155], v[200:203], v[32:35]
	v_mfma_f32_16x16x32_bf16 v[36:39], v[184:187], v[200:203], v[36:39]
	v_mfma_f32_16x16x32_bf16 v[60:63], v[152:155], v[208:211], v[60:63]
	v_mfma_f32_16x16x32_bf16 v[108:111], v[184:187], v[208:211], v[108:111]
	v_mfma_f32_16x16x32_bf16 v[24:27], v[152:155], v[216:219], v[24:27]
	v_mfma_f32_16x16x32_bf16 v[28:31], v[184:187], v[216:219], v[28:31]
	v_mfma_f32_16x16x32_bf16 v[16:19], v[156:159], v[196:199], v[16:19]
	v_mfma_f32_16x16x32_bf16 v[20:23], v[188:191], v[196:199], v[20:23]
	v_mfma_f32_16x16x32_bf16 v[32:35], v[156:159], v[204:207], v[32:35]
	v_mfma_f32_16x16x32_bf16 v[36:39], v[188:191], v[204:207], v[36:39]
	v_mfma_f32_16x16x32_bf16 v[60:63], v[156:159], v[212:215], v[60:63]
	v_mfma_f32_16x16x32_bf16 v[108:111], v[188:191], v[212:215], v[108:111]
	v_mfma_f32_16x16x32_bf16 v[24:27], v[156:159], v[220:223], v[24:27]
	v_mfma_f32_16x16x32_bf16 v[28:31], v[188:191], v[220:223], v[28:31]
	s_setprio 0
	s_barrier
;     __device__ bool next(int i, Unit& u) const { if (r0 + i >= r1) return false; return base.next(r0 + i, u); }
;     __device__ bool next(int i, Unit& u) const { const int L = i * G + c; if (L >= 256) return false; u.pm = L; u.pn = L >> 3; return true; }
; #define PG8_STAGE(bufoff, gbase, voff) do { _Pragma("unroll") for (int _i = 0; _i < 2; ++_i) \
;         __builtin_amdgcn_global_load_lds((const unsigned*)((const char*)(gbase) + (voff)[_i]), (LAS unsigned*)(lds + (bufoff) + ldsw + _i * 8192), 16, 0, 0); } while (0)
; #define PG8_WAIT_V(n) asm volatile("s_waitcnt vmcnt(" #n ")" ::: "memory")
; template <class Epi, class Sched>
; __device__ __forceinline__ void gemm_phase(LAS unsigned char* lds, const Gemm g, const Sched& S, const Epi& E, int wave_id) {
;     ...
;         const bool has_next = S.next(ui + 1, nxt);
;         const char* nA = has_next ? (const char*)g.A + (size_t)nxt.pm * tstepA : cA; const char* nB = has_next ? (const char*)g.Bt + (size_t)nxt.pn * tstepB : cB;
;         for (int t = 0; t < nt; t += 2) {
;             const bool last = (t == nt - 2);
;             const char* a1 = cA + (size_t)(t + 1) * kstep;
;             const char* a2 = last ? nA : cA + (size_t)(t + 2) * kstep; const char* b2 = last ? nB : cB + (size_t)(t + 2) * kstep;
;             const char* a3 = a2 + kstep; const char* b3 = b2 + kstep;
;             PG8_LDB(B0, 0, 0); PG8_LDB(B1, 0, 1); PG8_SCHED; PG8_LDA(At, 0, 0); PG8_STAGE(PG8_SA(1, 1), a1 + hstepA, voffA);
;             PG8_WAIT_V(8); PG8_WAIT_L(0); PG8_BAR; PG8_MMA(0, 0, At, B0); PG8_MMA(0, 1, At, B1); PG8_BAR; PG8_SCHED;
;             PG8_LDA(At, 0, 1); PG8_STAGE(PG8_SB(0, 0), b2, voffB); PG8_STAGE(PG8_SB(0, 1), b2 + hstepB, voffB); PG8_STAGE(PG8_SA(0, 0), a2, voffA);
;             PG8_WAIT_V(8); PG8_WAIT_L(0); PG8_BAR; PG8_MMA(1, 0, At, B0); PG8_MMA(1, 1, At, B1); PG8_BAR; PG8_SCHED;
;             PG8_LDB(B0, 1, 0); PG8_LDB(B1, 1, 1); PG8_SCHED; PG8_LDA(At, 1, 0); PG8_STAGE(PG8_SA(0, 1), a2 + hstepA, voffA);
;             PG8_WAIT_V(8); PG8_WAIT_L(0); PG8_BAR; PG8_MMA(0, 0, At, B0); PG8_MMA(0, 1, At, B1); PG8_BAR; PG8_SCHED;
;             PG8_LDA(At, 1, 1); PG8_STAGE(PG8_SB(1, 0), b3, voffB); PG8_STAGE(PG8_SB(1, 1), b3 + hstepB, voffB); PG8_STAGE(PG8_SA(1, 0), a3, voffA);
;             PG8_WAIT_V(8); PG8_WAIT_L(0); PG8_BAR; PG8_MMA(1, 0, At, B0); PG8_MMA(1, 1, At, B1); PG8_BAR; PG8_SCHED;
	ds_read_b128 v[112:115], v147
	ds_read_b128 v[116:119], v147 offset:1024
	ds_read_b128 v[120:123], v147 offset:2048
	ds_read_b128 v[124:127], v147 offset:3072
	ds_read_b128 v[152:155], v148
	ds_read_b128 v[156:159], v148 offset:1024
	ds_read_b128 v[176:179], v148 offset:2048
	ds_read_b128 v[180:183], v148 offset:3072
	s_add_u32 s30, s30, 0x18280
	s_addc_u32 s31, s31, 0
	s_mov_b32 m0, s48
	ds_read_b128 v[184:187], v138
	ds_read_b128 v[188:191], v138 offset:1024
	ds_read_b128 v[192:195], v138 offset:2048
	ds_read_b128 v[196:199], v138 offset:3072
	ds_read_b128 v[200:203], v138 offset:4096
	ds_read_b128 v[204:207], v138 offset:5120
	ds_read_b128 v[208:211], v138 offset:6144
	ds_read_b128 v[212:215], v138 offset:7168
	global_load_lds_dwordx4 v134, s[30:31]
	s_mov_b32 m0, s49
	s_nop 0
	global_load_lds_dwordx4 v130, s[30:31]
	s_waitcnt vmcnt(8)
	s_waitcnt lgkmcnt(0)
	s_barrier
	s_setprio 1
	s_waitcnt lgkmcnt(0)
	v_mfma_f32_16x16x32_bf16 v[64:67], v[112:115], v[184:187], v[64:67]
	v_mfma_f32_16x16x32_bf16 v[68:71], v[120:123], v[184:187], v[68:71]
	v_mfma_f32_16x16x32_bf16 v[72:75], v[112:115], v[192:195], v[72:75]
	v_mfma_f32_16x16x32_bf16 v[76:79], v[120:123], v[192:195], v[76:79]
	v_mfma_f32_16x16x32_bf16 v[80:83], v[112:115], v[200:203], v[80:83]
	v_mfma_f32_16x16x32_bf16 v[84:87], v[120:123], v[200:203], v[84:87]
	v_mfma_f32_16x16x32_bf16 v[88:91], v[112:115], v[208:211], v[88:91]
	v_mfma_f32_16x16x32_bf16 v[64:67], v[116:119], v[188:191], v[64:67]
	v_mfma_f32_16x16x32_bf16 v[68:71], v[124:127], v[188:191], v[68:71]
	v_mfma_f32_16x16x32_bf16 v[72:75], v[116:119], v[196:199], v[72:75]
	v_mfma_f32_16x16x32_bf16 v[76:79], v[124:127], v[196:199], v[76:79]
	v_mfma_f32_16x16x32_bf16 v[80:83], v[116:119], v[204:207], v[80:83]
	v_mfma_f32_16x16x32_bf16 v[84:87], v[124:127], v[204:207], v[84:87]
	v_mfma_f32_16x16x32_bf16 v[216:219], v[116:119], v[212:215], v[88:91]
	v_mfma_f32_16x16x32_bf16 v[88:91], v[120:123], v[208:211], v[92:95]
	v_mfma_f32_16x16x32_bf16 v[220:223], v[124:127], v[212:215], v[88:91]
	s_setprio 0
	s_setprio 1
	v_mfma_f32_16x16x32_bf16 v[88:91], v[152:155], v[184:187], v[96:99]
	v_mfma_f32_16x16x32_bf16 v[96:99], v[156:159], v[188:191], v[88:91]
	v_mfma_f32_16x16x32_bf16 v[88:91], v[176:179], v[184:187], v[100:103]
	v_mfma_f32_16x16x32_bf16 v[40:43], v[176:179], v[192:195], v[40:43]
	v_mfma_f32_16x16x32_bf16 v[44:47], v[152:155], v[200:203], v[44:47]
	v_mfma_f32_16x16x32_bf16 v[48:51], v[176:179], v[200:203], v[48:51]
	v_mfma_f32_16x16x32_bf16 v[52:55], v[152:155], v[208:211], v[52:55]
	v_mfma_f32_16x16x32_bf16 v[56:59], v[176:179], v[208:211], v[56:59]
	v_mfma_f32_16x16x32_bf16 v[100:103], v[180:183], v[188:191], v[88:91]
	v_mfma_f32_16x16x32_bf16 v[88:91], v[152:155], v[192:195], v[104:107]
	v_mfma_f32_16x16x32_bf16 v[40:43], v[180:183], v[196:199], v[40:43]
	v_mfma_f32_16x16x32_bf16 v[44:47], v[156:159], v[204:207], v[44:47]
	v_mfma_f32_16x16x32_bf16 v[48:51], v[180:183], v[204:207], v[48:51]
	v_mfma_f32_16x16x32_bf16 v[52:55], v[156:159], v[212:215], v[52:55]
	v_mfma_f32_16x16x32_bf16 v[56:59], v[180:183], v[212:215], v[56:59]
	v_mfma_f32_16x16x32_bf16 v[184:187], v[156:159], v[196:199], v[88:91]
	s_setprio 0
	s_barrier
	s_mov_b32 m0, s50
	v_lshl_add_u64 v[248:249], s[28:29], 0, v[132:133]
	s_add_u32 s30, s28, 0x18000
	ds_read_b128 v[88:91], v138 offset:16384
	ds_read_b128 v[92:95], v138 offset:17408
	ds_read_b128 v[104:107], v138 offset:18432
	ds_read_b128 v[188:191], v138 offset:19456
	ds_read_b128 v[192:195], v138 offset:20480
	ds_read_b128 v[196:199], v138 offset:21504
	ds_read_b128 v[200:203], v138 offset:22528
	ds_read_b128 v[204:207], v138 offset:23552
	global_load_lds_dwordx4 v[248:249], off
	v_lshl_add_u64 v[250:251], s[28:29], 0, v[128:129]
	s_mov_b32 m0, s51
	s_addc_u32 s31, s29, 0
	global_load_lds_dwordx4 v[250:251], off
	s_mov_b32 m0, s52
	v_lshl_add_u64 v[252:253], s[26:27], 0, v[134:135]
	global_load_lds_dwordx4 v132, s[30:31]
	s_mov_b32 m0, s53
	v_lshl_add_u64 v[140:141], s[26:27], 0, v[130:131]
	global_load_lds_dwordx4 v128, s[30:31]
	s_mov_b32 m0, s38
	s_nop 0
	global_load_lds_dwordx4 v[252:253], off
	s_mov_b32 m0, s39
	s_nop 0
	global_load_lds_dwordx4 v[140:141], off
	s_waitcnt vmcnt(8)
	s_waitcnt lgkmcnt(0)
	s_barrier
	s_setprio 1
	s_waitcnt lgkmcnt(0)
	v_mfma_f32_16x16x32_bf16 v[0:3], v[112:115], v[88:91], v[0:3]
	v_mfma_f32_16x16x32_bf16 v[4:7], v[120:123], v[88:91], v[4:7]
	v_mfma_f32_16x16x32_bf16 v[8:11], v[112:115], v[200:203], v[8:11]
	v_mfma_f32_16x16x32_bf16 v[0:3], v[116:119], v[92:95], v[0:3]
	v_mfma_f32_16x16x32_bf16 v[4:7], v[124:127], v[92:95], v[4:7]
	v_mfma_f32_16x16x32_bf16 v[160:163], v[112:115], v[104:107], v[160:163]
	v_mfma_f32_16x16x32_bf16 v[164:167], v[120:123], v[104:107], v[164:167]
	v_mfma_f32_16x16x32_bf16 v[168:171], v[112:115], v[192:195], v[168:171]
	v_mfma_f32_16x16x32_bf16 v[172:175], v[120:123], v[192:195], v[172:175]
	v_mfma_f32_16x16x32_bf16 v[8:11], v[116:119], v[204:207], v[8:11]
	v_mfma_f32_16x16x32_bf16 v[12:15], v[120:123], v[200:203], v[12:15]
	v_mfma_f32_16x16x32_bf16 v[160:163], v[116:119], v[188:191], v[160:163]
	v_mfma_f32_16x16x32_bf16 v[164:167], v[124:127], v[188:191], v[164:167]
	v_mfma_f32_16x16x32_bf16 v[168:171], v[116:119], v[196:199], v[168:171]
	v_mfma_f32_16x16x32_bf16 v[172:175], v[124:127], v[196:199], v[172:175]
	v_mfma_f32_16x16x32_bf16 v[208:211], v[124:127], v[204:207], v[12:15]
	s_setprio 0
	s_setprio 1
	v_mfma_f32_16x16x32_bf16 v[12:15], v[152:155], v[88:91], v[16:19]
	v_mfma_f32_16x16x32_bf16 v[16:19], v[156:159], v[92:95], v[12:15]
	v_mfma_f32_16x16x32_bf16 v[12:15], v[176:179], v[88:91], v[20:23]
	v_mfma_f32_16x16x32_bf16 v[20:23], v[180:183], v[92:95], v[12:15]
	v_mfma_f32_16x16x32_bf16 v[12:15], v[152:155], v[104:107], v[32:35]
	v_mfma_f32_16x16x32_bf16 v[32:35], v[156:159], v[188:191], v[12:15]
	v_mfma_f32_16x16x32_bf16 v[12:15], v[176:179], v[104:107], v[36:39]
	v_mfma_f32_16x16x32_bf16 v[188:191], v[180:183], v[188:191], v[12:15]
	v_mfma_f32_16x16x32_bf16 v[12:15], v[152:155], v[192:195], v[60:63]
	v_mfma_f32_16x16x32_bf16 v[212:215], v[156:159], v[196:199], v[12:15]
	v_mfma_f32_16x16x32_bf16 v[12:15], v[176:179], v[192:195], v[108:111]
	v_mfma_f32_16x16x32_bf16 v[192:195], v[180:183], v[196:199], v[12:15]
	v_mfma_f32_16x16x32_bf16 v[12:15], v[152:155], v[200:203], v[24:27]
	v_mfma_f32_16x16x32_bf16 v[152:155], v[156:159], v[204:207], v[12:15]
	v_mfma_f32_16x16x32_bf16 v[12:15], v[176:179], v[200:203], v[28:31]
	v_mfma_f32_16x16x32_bf16 v[156:159], v[180:183], v[204:207], v[12:15]
	s_setprio 0
	s_barrier
; #define PG8_STAGE(bufoff, gbase, voff) do { _Pragma("unroll") for (int _i = 0; _i < 2; ++_i) \
;         __builtin_amdgcn_global_load_lds((const unsigned*)((const char*)(gbase) + (voff)[_i]), (LAS unsigned*)(lds + (bufoff) + ldsw + _i * 8192), 16, 0, 0); } while (0)
; #define PG8_LDA(dst, b, h) do { _Pragma("unroll") for (int m = 0; m < 4; ++m) _Pragma("unroll") for (int k = 0; k < 2; ++k) dst[m][k] = *(const LAS bf16x8*)(lds + PG8_SA(b, h) + aoff + m * 2048 + k * 1024); } while (0)
; #define PG8_LDB(dst, b, h) do { _Pragma("unroll") for (int n = 0; n < 2; ++n) _Pragma("unroll") for (int k = 0; k < 2; ++k) dst[n][k] = *(const LAS bf16x8*)(lds + PG8_SB(b, h) + boff + n * 2048 + k * 1024); } while (0)
; template <class Epi, class Sched>
; __device__ __forceinline__ void gemm_phase(LAS unsigned char* lds, const Gemm g, const Sched& S, const Epi& E, int wave_id) {
;     ...
;         for (int t = 0; t < nt; t += 2) {
;             const bool last = (t == nt - 2);
;             const char* a1 = cA + (size_t)(t + 1) * kstep;
;             const char* a2 = last ? nA : cA + (size_t)(t + 2) * kstep; const char* b2 = last ? nB : cB + (size_t)(t + 2) * kstep;
;             const char* a3 = a2 + kstep; const char* b3 = b2 + kstep;
;             PG8_LDB(B0, 0, 0); PG8_LDB(B1, 0, 1); PG8_SCHED; PG8_LDA(At, 0, 0); PG8_STAGE(PG8_SA(1, 1), a1 + hstepA, voffA);
;             PG8_WAIT_V(8); PG8_WAIT_L(0); PG8_BAR; PG8_MMA(0, 0, At, B0); PG8_MMA(0, 1, At, B1); PG8_BAR; PG8_SCHED;
;             PG8_LDA(At, 0, 1); PG8_STAGE(PG8_SB(0, 0), b2, voffB); PG8_STAGE(PG8_SB(0, 1), b2 + hstepB, voffB); PG8_STAGE(PG8_SA(0, 0), a2, voffA);
;             PG8_WAIT_V(8); PG8_WAIT_L(0); PG8_BAR; PG8_MMA(1, 0, At, B0); PG8_MMA(1, 1, At, B1); PG8_BAR; PG8_SCHED;
;             PG8_LDB(B0, 1, 0); PG8_LDB(B1, 1, 1); PG8_SCHED; PG8_LDA(At, 1, 0); PG8_STAGE(PG8_SA(0, 1), a2 + hstepA, voffA);
;             PG8_WAIT_V(8); PG8_WAIT_L(0); PG8_BAR; PG8_MMA(0, 0, At, B0); PG8_MMA(0, 1, At, B1); PG8_BAR; PG8_SCHED;
;             PG8_LDA(At, 1, 1); PG8_STAGE(PG8_SB(1, 0), b3, voffB); PG8_STAGE(PG8_SB(1, 1), b3 + hstepB, voffB); PG8_STAGE(PG8_SA(1, 0), a3, voffA);
;             PG8_WAIT_V(8); PG8_WAIT_L(0); PG8_BAR; PG8_MMA(1, 0, At, B0); PG8_MMA(1, 1, At, B1); PG8_BAR; PG8_SCHED;
;         }
;         if (wr == 0) PG8_BAR;
;         E(acc, cur, wr, wc, fr, fq);
;         if (!has_next) break;
	s_nop 4
	ds_read_b128 v[12:15], v149
	ds_read_b128 v[36:39], v149 offset:1024
	ds_read_b128 v[176:179], v149 offset:2048
	ds_read_b128 v[180:183], v149 offset:3072
	ds_read_b128 v[196:199], v150
	ds_read_b128 v[200:203], v150 offset:1024
	ds_read_b128 v[204:207], v150 offset:2048
	ds_read_b128 v[224:227], v150 offset:3072
	s_add_u32 s30, s26, 0x18000
	s_addc_u32 s31, s27, 0
	s_mov_b32 m0, s40
	ds_read_b128 v[24:27], v138 offset:32768
	ds_read_b128 v[28:31], v138 offset:33792
	ds_read_b128 v[60:63], v138 offset:34816
	ds_read_b128 v[228:231], v138 offset:35840
	ds_read_b128 v[232:235], v138 offset:36864
	ds_read_b128 v[236:239], v138 offset:37888
	ds_read_b128 v[240:243], v138 offset:38912
	ds_read_b128 v[244:247], v138 offset:39936
	global_load_lds_dwordx4 v134, s[30:31]
	s_mov_b32 m0, s41
	s_nop 0
	global_load_lds_dwordx4 v130, s[30:31]
	s_waitcnt vmcnt(8)
	s_waitcnt lgkmcnt(0)
	s_barrier
	s_setprio 1
	s_waitcnt lgkmcnt(0)
	v_mfma_f32_16x16x32_bf16 v[64:67], v[12:15], v[24:27], v[64:67]
	v_mfma_f32_16x16x32_bf16 v[124:127], v[36:39], v[28:31], v[64:67]
	v_mfma_f32_16x16x32_bf16 v[64:67], v[176:179], v[24:27], v[68:71]
	v_mfma_f32_16x16x32_bf16 v[120:123], v[180:183], v[28:31], v[64:67]
	v_mfma_f32_16x16x32_bf16 v[64:67], v[12:15], v[60:63], v[72:75]
	v_mfma_f32_16x16x32_bf16 v[108:111], v[36:39], v[228:231], v[64:67]
	v_mfma_f32_16x16x32_bf16 v[64:67], v[176:179], v[60:63], v[76:79]
	v_mfma_f32_16x16x32_bf16 v[104:107], v[180:183], v[228:231], v[64:67]
	v_mfma_f32_16x16x32_bf16 v[64:67], v[12:15], v[232:235], v[80:83]
	v_mfma_f32_16x16x32_bf16 v[92:95], v[36:39], v[236:239], v[64:67]
	v_mfma_f32_16x16x32_bf16 v[64:67], v[176:179], v[232:235], v[84:87]
	v_mfma_f32_16x16x32_bf16 v[88:91], v[180:183], v[236:239], v[64:67]
	v_mfma_f32_16x16x32_bf16 v[64:67], v[12:15], v[240:243], v[216:219]
	v_mfma_f32_16x16x32_bf16 v[76:79], v[36:39], v[244:247], v[64:67]
	v_mfma_f32_16x16x32_bf16 v[64:67], v[176:179], v[240:243], v[220:223]
	v_mfma_f32_16x16x32_bf16 v[72:75], v[180:183], v[244:247], v[64:67]
	s_setprio 0
	s_setprio 1
	v_mfma_f32_16x16x32_bf16 v[64:67], v[196:199], v[24:27], v[96:99]
	v_mfma_f32_16x16x32_bf16 v[24:27], v[204:207], v[24:27], v[100:103]
	v_mfma_f32_16x16x32_bf16 v[112:115], v[224:227], v[28:31], v[24:27]
	v_mfma_f32_16x16x32_bf16 v[24:27], v[196:199], v[60:63], v[184:187]
	v_mfma_f32_16x16x32_bf16 v[100:103], v[200:203], v[228:231], v[24:27]
	v_mfma_f32_16x16x32_bf16 v[24:27], v[204:207], v[60:63], v[40:43]
	v_mfma_f32_16x16x32_bf16 v[96:99], v[224:227], v[228:231], v[24:27]
	v_mfma_f32_16x16x32_bf16 v[24:27], v[196:199], v[232:235], v[44:47]
	v_mfma_f32_16x16x32_bf16 v[84:87], v[200:203], v[236:239], v[24:27]
	v_mfma_f32_16x16x32_bf16 v[24:27], v[204:207], v[232:235], v[48:51]
	v_mfma_f32_16x16x32_bf16 v[80:83], v[224:227], v[236:239], v[24:27]
	v_mfma_f32_16x16x32_bf16 v[24:27], v[196:199], v[240:243], v[52:55]
	v_mfma_f32_16x16x32_bf16 v[68:71], v[200:203], v[244:247], v[24:27]
	v_mfma_f32_16x16x32_bf16 v[24:27], v[204:207], v[240:243], v[56:59]
	v_mfma_f32_16x16x32_bf16 v[116:119], v[200:203], v[28:31], v[64:67]
	v_mfma_f32_16x16x32_bf16 v[64:67], v[224:227], v[244:247], v[24:27]
	s_setprio 0
	s_barrier
	s_mov_b32 m0, s54
	s_nop 2
	v_lshl_add_u64 v[24:25], v[248:249], 0, s[12:13]
	s_add_u32 s30, s28, 0x18080
	ds_read_b128 v[48:51], v138 offset:49152
	ds_read_b128 v[184:187], v138 offset:50176
	ds_read_b128 v[216:219], v138 offset:51200
	ds_read_b128 v[220:223], v138 offset:52224
	ds_read_b128 v[228:231], v138 offset:53248
	ds_read_b128 v[232:235], v138 offset:54272
	ds_read_b128 v[236:239], v138 offset:55296
	ds_read_b128 v[240:243], v138 offset:56320
	global_load_lds_dwordx4 v[24:25], off
	v_lshl_add_u64 v[24:25], v[250:251], 0, s[12:13]
	s_mov_b32 m0, s55
	s_addc_u32 s31, s29, 0
	global_load_lds_dwordx4 v[24:25], off
	s_mov_b32 m0, s58
	s_nop 0
	global_load_lds_dwordx4 v132, s[30:31]
	s_mov_b32 m0, s59
	s_nop 0
	global_load_lds_dwordx4 v128, s[30:31]
	v_lshl_add_u64 v[24:25], v[252:253], 0, s[12:13]
	s_mov_b32 m0, s43
	s_nop 0
	global_load_lds_dwordx4 v[24:25], off
	v_lshl_add_u64 v[24:25], v[140:141], 0, s[12:13]
	s_mov_b32 m0, s44
	s_nop 0
	global_load_lds_dwordx4 v[24:25], off
	s_waitcnt vmcnt(8)
	s_waitcnt lgkmcnt(0)
	s_barrier
	s_setprio 1
	s_waitcnt lgkmcnt(0)
	v_mfma_f32_16x16x32_bf16 v[0:3], v[12:15], v[48:51], v[0:3]
	v_mfma_f32_16x16x32_bf16 v[60:63], v[36:39], v[184:187], v[0:3]
	v_mfma_f32_16x16x32_bf16 v[0:3], v[176:179], v[48:51], v[4:7]
	v_mfma_f32_16x16x32_bf16 v[56:59], v[180:183], v[184:187], v[0:3]
	v_mfma_f32_16x16x32_bf16 v[0:3], v[12:15], v[216:219], v[160:163]
	v_mfma_f32_16x16x32_bf16 v[44:47], v[36:39], v[220:223], v[0:3]
	v_mfma_f32_16x16x32_bf16 v[0:3], v[176:179], v[216:219], v[164:167]
	v_mfma_f32_16x16x32_bf16 v[40:43], v[180:183], v[220:223], v[0:3]
	v_mfma_f32_16x16x32_bf16 v[0:3], v[12:15], v[228:231], v[168:171]
	v_mfma_f32_16x16x32_bf16 v[28:31], v[36:39], v[232:235], v[0:3]
	v_mfma_f32_16x16x32_bf16 v[0:3], v[176:179], v[228:231], v[172:175]
	v_mfma_f32_16x16x32_bf16 v[24:27], v[180:183], v[232:235], v[0:3]
	v_mfma_f32_16x16x32_bf16 v[0:3], v[12:15], v[236:239], v[8:11]
	v_mfma_f32_16x16x32_bf16 v[12:15], v[36:39], v[240:243], v[0:3]
	v_mfma_f32_16x16x32_bf16 v[0:3], v[176:179], v[236:239], v[208:211]
	v_mfma_f32_16x16x32_bf16 v[8:11], v[180:183], v[240:243], v[0:3]
	s_setprio 0
	s_setprio 1
	v_mfma_f32_16x16x32_bf16 v[0:3], v[196:199], v[48:51], v[16:19]
	v_mfma_f32_16x16x32_bf16 v[52:55], v[200:203], v[184:187], v[0:3]
	v_mfma_f32_16x16x32_bf16 v[0:3], v[204:207], v[48:51], v[20:23]
	v_mfma_f32_16x16x32_bf16 v[48:51], v[224:227], v[184:187], v[0:3]
	v_mfma_f32_16x16x32_bf16 v[0:3], v[196:199], v[216:219], v[32:35]
	v_mfma_f32_16x16x32_bf16 v[36:39], v[200:203], v[220:223], v[0:3]
	v_mfma_f32_16x16x32_bf16 v[0:3], v[204:207], v[216:219], v[188:191]
	v_mfma_f32_16x16x32_bf16 v[32:35], v[224:227], v[220:223], v[0:3]
	v_mfma_f32_16x16x32_bf16 v[0:3], v[196:199], v[228:231], v[212:215]
	v_mfma_f32_16x16x32_bf16 v[20:23], v[200:203], v[232:235], v[0:3]
	v_mfma_f32_16x16x32_bf16 v[0:3], v[204:207], v[228:231], v[192:195]
	v_mfma_f32_16x16x32_bf16 v[16:19], v[224:227], v[232:235], v[0:3]
	v_mfma_f32_16x16x32_bf16 v[0:3], v[196:199], v[236:239], v[152:155]
	v_mfma_f32_16x16x32_bf16 v[4:7], v[200:203], v[240:243], v[0:3]
	v_mfma_f32_16x16x32_bf16 v[0:3], v[204:207], v[236:239], v[156:159]
	v_mfma_f32_16x16x32_bf16 v[0:3], v[224:227], v[240:243], v[0:3]
	s_setprio 0
	s_barrier
	s_and_b64 vcc, exec, s[4:5]
	s_cbranch_vccnz .LBB0_939
	s_barrier

; #define PG8_STAGE(bufoff, gbase, voff) do { _Pragma("unroll") for (int _i = 0; _i < 2; ++_i) \
;         __builtin_amdgcn_global_load_lds((const unsigned*)((const char*)(gbase) + (voff)[_i]), (LAS unsigned*)(lds + (bufoff) + ldsw + _i * 8192), 16, 0, 0); } while (0)
; #define PG8_WAIT_V(n) asm volatile("s_waitcnt vmcnt(" #n ")" ::: "memory")
; #define PG8_BAR __builtin_amdgcn_s_barrier()
; #define lane lane_id()
; template <class Epi, class Sched>
; __device__ __forceinline__ void gemm_phase(LAS unsigned char* lds, const Gemm g, const Sched& S, const Epi& E, int wave_id) {
;     ...
;     const int wid = wave_id, lane = tid & 63, wr = wid >> 2, wc = wid & 3, fr = lane & 15, fq = lane >> 4;
;     const int K = g.K, nt = K / BK;
;     unsigned voffA[2], voffB[2];
; #pragma unroll
;     for (int i = 0; i < 2; ++i) { int R, C; stage_rc(tid * 16 + i * 8192, R, C); const int Rb = (R & ~31) + perm32(R & 31);
;         voffA[i] = (unsigned)(R * g.lda + C) * 2u; voffB[i] = (unsigned)(Rb * g.ldb + C) * 2u; }
;     const size_t kstep = (size_t)(BK * 2);
;     const size_t hstepA = (size_t)HALF * g.lda * 2, hstepB = (size_t)HALF * g.ldb * 2;
;     const size_t tstepA = 2 * hstepA, tstepB = 2 * hstepB;
;     const unsigned ldsw = (unsigned)wid * 1024u;
;     const int aoff = lds_byte(wr * 64 + fr, fq * 8), boff = lds_byte(wc * 32 + fr, fq * 8);
;     ...
;     PG8_STAGE(PG8_SB(0, 0), cB, voffB); PG8_STAGE(PG8_SB(0, 1), cB + hstepB, voffB); PG8_STAGE(PG8_SA(0, 0), cA, voffA); PG8_STAGE(PG8_SA(0, 1), cA + hstepA, voffA);
;     if (wr == 1) PG8_BAR;
;     PG8_WAIT_V(2); PG8_BAR;
;     PG8_STAGE(PG8_SB(1, 0), cB + kstep, voffB); PG8_STAGE(PG8_SA(1, 0), cA + kstep, voffA); PG8_STAGE(PG8_SB(1, 1), cB + hstepB + kstep, voffB);
;     PG8_WAIT_V(6); PG8_BAR;
.LBB0_950:
	s_add_u32 s42, s92, 0x13400000
	s_mov_b64 s[10:11], 0x80
	s_addc_u32 s43, s93, 0
	s_bfe_u32 s5, s80, 0x20006
	s_add_i32 m0, s37, 0x18000
	v_lshl_add_u64 v[6:7], v[6:7], 0, s[10:11]
	s_lshl_b32 s44, s3, 6
	s_lshl_b32 s14, s5, 12
	s_waitcnt vmcnt(2)
	s_barrier
	global_load_lds_dwordx4 v[6:7], off
	v_lshl_add_u64 v[4:5], v[4:5], 0, s[10:11]
	s_add_i32 m0, s37, 0x1a000
	s_add_i32 s45, s37, 0x8000
	s_add_i32 s46, s37, 0xa000
	global_load_lds_dwordx4 v[4:5], off
	v_lshl_add_u64 v[0:1], v[0:1], 0, s[10:11]
	s_mov_b32 m0, s45
	s_add_u32 s12, s26, 0x40080
	global_load_lds_dwordx4 v[0:1], off
	v_lshl_add_u64 v[0:1], v[2:3], 0, s[10:11]
	s_mov_b32 m0, s46
	s_addc_u32 s13, s27, 0
	global_load_lds_dwordx4 v[0:1], off
	s_add_i32 m0, s37, 0x1c000
	s_nop 0
	global_load_lds_dwordx4 v130, s[12:13]
	v_lshl_add_u64 v[0:1], s[12:13], 0, v[134:135]
	s_add_i32 m0, s37, 0x1e000
	v_and_b32_e32 v2, 15, v8
	global_load_lds_dwordx4 v[0:1], off
	v_bfe_u32 v1, v8, 4, 2
	v_lshrrev_b32_e32 v0, 4, v8
	v_lshlrev_b32_e32 v1, 4, v1
	v_lshlrev_b32_e32 v4, 2, v8
	v_lshl_or_b32 v3, v2, 6, v1
	v_and_b32_e32 v4, 32, v4
	v_bfe_u32 v0, v0, 1, 1
	v_bitop3_b32 v5, v3, s33, v4 bitop3:0xde
	v_bitop3_b32 v150, v3, s14, v4 bitop3:0xde
	v_lshl_or_b32 v0, s5, 1, v0
	v_and_or_b32 v3, v1, 16, v2
	v_lshlrev_b32_e32 v136, 4, v3
	v_mul_u32_u24_e32 v3, 0x210, v0
	v_lshlrev_b32_e32 v138, 11, v0
	v_lshlrev_b32_e32 v0, 14, v9
	v_and_b32_e32 v0, 0xffff8000, v0
	s_cmpk_lt_u32 s80, 0x100
	s_mul_i32 s14, s3, 0x2100
	v_lshl_add_u32 v0, v10, 11, v0
	v_and_b32_e32 v6, 1, v9
	s_cselect_b64 s[12:13], -1, 0
	s_add_i32 s14, s14, 0
	v_lshl_or_b32 v0, v6, 6, v0
	s_lshl_b32 s5, s5, 6
	s_add_i32 s14, s14, 0x20000
	v_lshl_add_u32 v142, v11, 1, v0
	v_lshlrev_b32_e32 v0, 14, v12
	s_add_i32 s5, s5, s14
	v_and_b32_e32 v0, 0xffff8000, v0
	s_sext_i32_i8 s23, s4
	s_waitcnt vmcnt(6)
	s_movk_i32 s4, 0x210
	v_mov_b32_e32 v4, s5
	v_lshl_add_u32 v0, v13, 11, v0
	v_and_b32_e32 v6, 1, v12
	v_readlane_b32 s16, v255, 1
	v_mad_u32_u24 v2, v2, s4, v4
	v_add_u32_e32 v4, s14, v136
	v_lshl_or_b32 v0, v6, 6, v0
	s_add_i32 s47, 0, 0x10000
	s_add_i32 s48, 0, 0x14000
	v_mov_b32_e32 v137, v131
	s_ashr_i32 s3, s16, 31
	s_mov_b32 s33, s16
	v_mov_b32_e32 v139, v131
	v_or_b32_e32 v140, 0x4000, v138
	v_mov_b32_e32 v141, v131
	v_mov_b32_e32 v143, v131
	v_lshl_add_u32 v144, v14, 1, v0
	v_mov_b32_e32 v145, v131
	v_mov_b64_e32 v[146:147], 0x200
	v_mov_b64_e32 v[148:149], 0x1ff
	v_add_u32_e32 v151, s47, v150
	v_add_u32_e32 v152, s48, v150
	v_add_u32_e32 v153, 0, v5
	v_add_u32_e32 v154, v2, v1
	v_add_u32_e32 v155, v4, v3
	s_barrier
	v_readlane_b32 s17, v255, 2
	s_waitcnt vmcnt(0)
	s_branch .LBB0_953

;     __device__ bool next(int i, Unit& u) const { if (r0 + i >= r1) return false; return base.next(r0 + i, u); }
;     __device__ bool next(int i, Unit& u) const { const int L = i * G + c; if (L >= 256) return false; u.pm = L; u.pn = L >> 3; return true; }
; #define PG8_STAGE(bufoff, gbase, voff) do { _Pragma("unroll") for (int _i = 0; _i < 2; ++_i) \
;         __builtin_amdgcn_global_load_lds((const unsigned*)((const char*)(gbase) + (voff)[_i]), (LAS unsigned*)(lds + (bufoff) + ldsw + _i * 8192), 16, 0, 0); } while (0)
; #define PG8_LDA(dst, b, h) do { _Pragma("unroll") for (int m = 0; m < 4; ++m) _Pragma("unroll") for (int k = 0; k < 2; ++k) dst[m][k] = *(const LAS bf16x8*)(lds + PG8_SA(b, h) + aoff + m * 2048 + k * 1024); } while (0)
; #define PG8_LDB(dst, b, h) do { _Pragma("unroll") for (int n = 0; n < 2; ++n) _Pragma("unroll") for (int k = 0; k < 2; ++k) dst[n][k] = *(const LAS bf16x8*)(lds + PG8_SB(b, h) + boff + n * 2048 + k * 1024); } while (0)
; #define PG8_WAIT_V(n) asm volatile("s_waitcnt vmcnt(" #n ")" ::: "memory")
; #define PG8_WAIT_L(n) asm volatile("s_waitcnt lgkmcnt(" #n ")" ::: "memory")
; template <class Epi, class Sched>
; __device__ __forceinline__ void gemm_phase(LAS unsigned char* lds, const Gemm g, const Sched& S, const Epi& E, int wave_id) {
;     ...
;         const bool has_next = S.next(ui + 1, nxt);
;         const char* nA = has_next ? (const char*)g.A + (size_t)nxt.pm * tstepA : cA; const char* nB = has_next ? (const char*)g.Bt + (size_t)nxt.pn * tstepB : cB;
;         for (int t = 0; t < nt; t += 2) {
;             const bool last = (t == nt - 2);
;             const char* a1 = cA + (size_t)(t + 1) * kstep;
;             const char* a2 = last ? nA : cA + (size_t)(t + 2) * kstep; const char* b2 = last ? nB : cB + (size_t)(t + 2) * kstep;
;             const char* a3 = a2 + kstep; const char* b3 = b2 + kstep;
;             PG8_LDB(B0, 0, 0); PG8_LDB(B1, 0, 1); PG8_SCHED; PG8_LDA(At, 0, 0); PG8_STAGE(PG8_SA(1, 1), a1 + hstepA, voffA);
;             PG8_WAIT_V(8); PG8_WAIT_L(0); PG8_BAR; PG8_MMA(0, 0, At, B0); PG8_MMA(0, 1, At, B1); PG8_BAR; PG8_SCHED;
;             PG8_LDA(At, 0, 1); PG8_STAGE(PG8_SB(0, 0), b2, voffB); PG8_STAGE(PG8_SB(0, 1), b2 + hstepB, voffB); PG8_STAGE(PG8_SA(0, 0), a2, voffA);
;             PG8_WAIT_V(8); PG8_WAIT_L(0); PG8_BAR; PG8_MMA(1, 0, At, B0); PG8_MMA(1, 1, At, B1); PG8_BAR; PG8_SCHED;
.LBB0_959:
	s_ashr_i32 s17, s16, 31
	s_lshl_b64 s[18:19], s[16:17], 19
	s_add_u32 s18, s31, s18
	s_addc_u32 s19, s34, s19
	s_and_b64 s[20:21], s[4:5], exec
	s_cselect_b32 s17, s19, s25
	s_cselect_b32 s49, s18, s24
	s_ashr_i32 s15, s14, 31
	s_lshl_b64 s[20:21], s[14:15], 19
	s_add_u32 s20, s35, s20
	s_addc_u32 s21, s36, s21
	s_and_b64 s[28:29], s[4:5], exec
	s_cselect_b32 s15, s21, s27
	s_cselect_b32 s50, s20, s26
	s_add_u32 s24, s24, 0x40080
	s_addc_u32 s25, s25, 0
	s_add_u32 s51, s26, 0x100
	s_addc_u32 s52, s27, 0
	s_mov_b32 s53, -2
	ds_read_b128 v[156:159], v151
	ds_read_b128 v[160:163], v151 offset:1024
	ds_read_b128 v[164:167], v151 offset:2048
	ds_read_b128 v[168:171], v151 offset:3072
	ds_read_b128 v[172:175], v152
	ds_read_b128 v[176:179], v152 offset:1024
	ds_read_b128 v[180:183], v152 offset:2048
	ds_read_b128 v[184:187], v152 offset:3072
	s_add_u32 s26, s24, 0xfffc0080
	s_addc_u32 s27, s25, -1
	s_cmp_eq_u32 s53, 12
	s_cselect_b32 s29, s17, s27
	s_cselect_b32 s28, s49, s26
	s_cselect_b32 s27, s15, s52
	s_cselect_b32 s26, s50, s51
	s_add_i32 m0, s37, 0xc000
	ds_read_b128 v[188:191], v153
	ds_read_b128 v[192:195], v153 offset:1024
	ds_read_b128 v[196:199], v153 offset:2048
	ds_read_b128 v[200:203], v153 offset:3072
	ds_read_b128 v[204:207], v153 offset:4096
	ds_read_b128 v[208:211], v153 offset:5120
	ds_read_b128 v[212:215], v153 offset:6144
	ds_read_b128 v[216:219], v153 offset:7168
	global_load_lds_dwordx4 v142, s[24:25]
	s_add_i32 m0, s37, 0xe000
	s_nop 0
	global_load_lds_dwordx4 v144, s[24:25]
	s_waitcnt vmcnt(8)
	s_waitcnt lgkmcnt(0)
	s_barrier
	s_setprio 1
	s_waitcnt lgkmcnt(0)
	v_mfma_f32_16x16x32_bf16 v[124:127], v[156:159], v[188:191], 0
	v_mfma_f32_16x16x32_bf16 v[120:123], v[164:167], v[188:191], 0
	v_mfma_f32_16x16x32_bf16 v[108:111], v[156:159], v[196:199], 0
	v_mfma_f32_16x16x32_bf16 v[104:107], v[164:167], v[196:199], 0
	v_mfma_f32_16x16x32_bf16 v[92:95], v[156:159], v[204:207], 0
	v_mfma_f32_16x16x32_bf16 v[88:91], v[164:167], v[204:207], 0
	v_mfma_f32_16x16x32_bf16 v[76:79], v[156:159], v[212:215], 0
	v_mfma_f32_16x16x32_bf16 v[72:75], v[164:167], v[212:215], 0
	v_mfma_f32_16x16x32_bf16 v[124:127], v[160:163], v[192:195], v[124:127]
	v_mfma_f32_16x16x32_bf16 v[120:123], v[168:171], v[192:195], v[120:123]
	v_mfma_f32_16x16x32_bf16 v[108:111], v[160:163], v[200:203], v[108:111]
	v_mfma_f32_16x16x32_bf16 v[104:107], v[168:171], v[200:203], v[104:107]
	v_mfma_f32_16x16x32_bf16 v[92:95], v[160:163], v[208:211], v[92:95]
	v_mfma_f32_16x16x32_bf16 v[88:91], v[168:171], v[208:211], v[88:91]
	v_mfma_f32_16x16x32_bf16 v[76:79], v[160:163], v[216:219], v[76:79]
	v_mfma_f32_16x16x32_bf16 v[72:75], v[168:171], v[216:219], v[72:75]
	s_setprio 0
	s_setprio 1
	v_mfma_f32_16x16x32_bf16 v[116:119], v[172:175], v[188:191], 0
	v_mfma_f32_16x16x32_bf16 v[112:115], v[180:183], v[188:191], 0
	v_mfma_f32_16x16x32_bf16 v[100:103], v[172:175], v[196:199], 0
	v_mfma_f32_16x16x32_bf16 v[96:99], v[180:183], v[196:199], 0
	v_mfma_f32_16x16x32_bf16 v[84:87], v[172:175], v[204:207], 0
	v_mfma_f32_16x16x32_bf16 v[80:83], v[180:183], v[204:207], 0
	v_mfma_f32_16x16x32_bf16 v[68:71], v[172:175], v[212:215], 0
	v_mfma_f32_16x16x32_bf16 v[64:67], v[180:183], v[212:215], 0
	v_mfma_f32_16x16x32_bf16 v[116:119], v[176:179], v[192:195], v[116:119]
	v_mfma_f32_16x16x32_bf16 v[112:115], v[184:187], v[192:195], v[112:115]
	v_mfma_f32_16x16x32_bf16 v[100:103], v[176:179], v[200:203], v[100:103]
	v_mfma_f32_16x16x32_bf16 v[96:99], v[184:187], v[200:203], v[96:99]
	v_mfma_f32_16x16x32_bf16 v[84:87], v[176:179], v[208:211], v[84:87]
	v_mfma_f32_16x16x32_bf16 v[80:83], v[184:187], v[208:211], v[80:83]
	v_mfma_f32_16x16x32_bf16 v[68:71], v[176:179], v[216:219], v[68:71]
	v_mfma_f32_16x16x32_bf16 v[64:67], v[184:187], v[216:219], v[64:67]
	s_setprio 0
	s_barrier
	s_add_i32 s54, s47, s2
	v_lshl_add_u64 v[220:221], s[26:27], 0, v[130:131]
	s_mov_b32 m0, s54
	ds_read_b128 v[188:191], v153 offset:16384
	ds_read_b128 v[192:195], v153 offset:17408
	ds_read_b128 v[196:199], v153 offset:18432
	ds_read_b128 v[200:203], v153 offset:19456
	ds_read_b128 v[204:207], v153 offset:20480
	ds_read_b128 v[208:211], v153 offset:21504
	ds_read_b128 v[212:215], v153 offset:22528
	ds_read_b128 v[216:219], v153 offset:23552
	global_load_lds_dwordx4 v[220:221], off
	s_add_i32 m0, s54, 0x2000
	s_add_u32 s54, s26, 0x40000
	v_lshl_add_u64 v[222:223], s[26:27], 0, v[134:135]
	s_addc_u32 s55, s27, 0
	s_add_i32 s58, s48, s2
	global_load_lds_dwordx4 v[222:223], off
	s_mov_b32 m0, s58
	v_lshl_add_u64 v[226:227], s[28:29], 0, v[132:133]
	global_load_lds_dwordx4 v130, s[54:55]
	s_add_i32 m0, s58, 0x2000
	s_nop 0
	global_load_lds_dwordx4 v134, s[54:55]
	v_lshl_add_u64 v[224:225], s[28:29], 0, v[128:129]
	s_mov_b32 m0, s37
	s_nop 0
	global_load_lds_dwordx4 v[224:225], off
	s_mov_b32 m0, s38
	s_nop 0
	global_load_lds_dwordx4 v[226:227], off
	s_waitcnt vmcnt(8)
	s_waitcnt lgkmcnt(0)
	s_barrier
; #define PG8_STAGE(bufoff, gbase, voff) do { _Pragma("unroll") for (int _i = 0; _i < 2; ++_i) \
;         __builtin_amdgcn_global_load_lds((const unsigned*)((const char*)(gbase) + (voff)[_i]), (LAS unsigned*)(lds + (bufoff) + ldsw + _i * 8192), 16, 0, 0); } while (0)
; #define PG8_LDA(dst, b, h) do { _Pragma("unroll") for (int m = 0; m < 4; ++m) _Pragma("unroll") for (int k = 0; k < 2; ++k) dst[m][k] = *(const LAS bf16x8*)(lds + PG8_SA(b, h) + aoff + m * 2048 + k * 1024); } while (0)
; #define PG8_LDB(dst, b, h) do { _Pragma("unroll") for (int n = 0; n < 2; ++n) _Pragma("unroll") for (int k = 0; k < 2; ++k) dst[n][k] = *(const LAS bf16x8*)(lds + PG8_SB(b, h) + boff + n * 2048 + k * 1024); } while (0)
; #define PG8_MMA(ai, bj, At, Bt) do { __builtin_amdgcn_s_setprio(1); _Pragma("unroll") for (int m = 0; m < 4; ++m) _Pragma("unroll") for (int n = 0; n < 2; ++n) _Pragma("unroll") for (int k = 0; k < 2; ++k) \
;         acc[ai][bj][m][n] = __builtin_amdgcn_mfma_f32_16x16x32_bf16(Bt[n][k], At[m][k], acc[ai][bj][m][n], 0, 0, 0); __builtin_amdgcn_s_setprio(0); } while (0)
; #define PG8_WAIT_V(n) asm volatile("s_waitcnt vmcnt(" #n ")" ::: "memory")
; #define PG8_WAIT_L(n) asm volatile("s_waitcnt lgkmcnt(" #n ")" ::: "memory")
; #define PG8_BAR __builtin_amdgcn_s_barrier()
; #define PG8_SCHED __builtin_amdgcn_sched_barrier(0)
; template <class Epi, class Sched>
; __device__ __forceinline__ void gemm_phase(LAS unsigned char* lds, const Gemm g, const Sched& S, const Epi& E, int wave_id) {
;     ...
;             PG8_WAIT_V(8); PG8_WAIT_L(0); PG8_BAR; PG8_MMA(1, 0, At, B0); PG8_MMA(1, 1, At, B1); PG8_BAR; PG8_SCHED;
;             PG8_LDB(B0, 1, 0); PG8_LDB(B1, 1, 1); PG8_SCHED; PG8_LDA(At, 1, 0); PG8_STAGE(PG8_SA(0, 1), a2 + hstepA, voffA);
;             PG8_WAIT_V(8); PG8_WAIT_L(0); PG8_BAR; PG8_MMA(0, 0, At, B0); PG8_MMA(0, 1, At, B1); PG8_BAR; PG8_SCHED;
	s_setprio 1
	s_waitcnt lgkmcnt(0)
	v_mfma_f32_16x16x32_bf16 v[60:63], v[156:159], v[188:191], 0
	v_mfma_f32_16x16x32_bf16 v[56:59], v[164:167], v[188:191], 0
	v_mfma_f32_16x16x32_bf16 v[44:47], v[156:159], v[196:199], 0
	v_mfma_f32_16x16x32_bf16 v[40:43], v[164:167], v[196:199], 0
	v_mfma_f32_16x16x32_bf16 v[28:31], v[156:159], v[204:207], 0
	v_mfma_f32_16x16x32_bf16 v[24:27], v[164:167], v[204:207], 0
	v_mfma_f32_16x16x32_bf16 v[12:15], v[156:159], v[212:215], 0
	v_mfma_f32_16x16x32_bf16 v[8:11], v[164:167], v[212:215], 0
	v_mfma_f32_16x16x32_bf16 v[60:63], v[160:163], v[192:195], v[60:63]
	v_mfma_f32_16x16x32_bf16 v[56:59], v[168:171], v[192:195], v[56:59]
	v_mfma_f32_16x16x32_bf16 v[44:47], v[160:163], v[200:203], v[44:47]
	v_mfma_f32_16x16x32_bf16 v[40:43], v[168:171], v[200:203], v[40:43]
	v_mfma_f32_16x16x32_bf16 v[28:31], v[160:163], v[208:211], v[28:31]
	v_mfma_f32_16x16x32_bf16 v[24:27], v[168:171], v[208:211], v[24:27]
	v_mfma_f32_16x16x32_bf16 v[12:15], v[160:163], v[216:219], v[12:15]
	v_mfma_f32_16x16x32_bf16 v[8:11], v[168:171], v[216:219], v[8:11]
	s_setprio 0
	s_setprio 1
	v_mfma_f32_16x16x32_bf16 v[52:55], v[172:175], v[188:191], 0
	v_mfma_f32_16x16x32_bf16 v[48:51], v[180:183], v[188:191], 0
	v_mfma_f32_16x16x32_bf16 v[36:39], v[172:175], v[196:199], 0
	v_mfma_f32_16x16x32_bf16 v[32:35], v[180:183], v[196:199], 0
	v_mfma_f32_16x16x32_bf16 v[20:23], v[172:175], v[204:207], 0
	v_mfma_f32_16x16x32_bf16 v[16:19], v[180:183], v[204:207], 0
	v_mfma_f32_16x16x32_bf16 v[4:7], v[172:175], v[212:215], 0
	v_mfma_f32_16x16x32_bf16 v[0:3], v[180:183], v[212:215], 0
	v_mfma_f32_16x16x32_bf16 v[52:55], v[176:179], v[192:195], v[52:55]
	v_mfma_f32_16x16x32_bf16 v[48:51], v[184:187], v[192:195], v[48:51]
	v_mfma_f32_16x16x32_bf16 v[36:39], v[176:179], v[200:203], v[36:39]
	v_mfma_f32_16x16x32_bf16 v[32:35], v[184:187], v[200:203], v[32:35]
	v_mfma_f32_16x16x32_bf16 v[20:23], v[176:179], v[208:211], v[20:23]
	v_mfma_f32_16x16x32_bf16 v[16:19], v[184:187], v[208:211], v[16:19]
	v_mfma_f32_16x16x32_bf16 v[4:7], v[176:179], v[216:219], v[4:7]
	v_mfma_f32_16x16x32_bf16 v[0:3], v[184:187], v[216:219], v[0:3]
	s_setprio 0
	s_barrier
	s_add_i32 s54, 0, 0x18000
	s_add_i32 s55, 0, 0x1c000
	v_add_u32_e32 v168, s54, v150
	v_add_u32_e32 v184, s55, v150
	ds_read_b128 v[156:159], v168
	ds_read_b128 v[160:163], v168 offset:1024
	ds_read_b128 v[164:167], v168 offset:2048
	ds_read_b128 v[168:171], v168 offset:3072
	ds_read_b128 v[172:175], v184
	ds_read_b128 v[176:179], v184 offset:1024
	ds_read_b128 v[180:183], v184 offset:2048
	ds_read_b128 v[184:187], v184 offset:3072
	s_add_u32 s28, s28, 0x40000
	s_addc_u32 s29, s29, 0
	s_mov_b32 m0, s39
	ds_read_b128 v[188:191], v153 offset:32768
	ds_read_b128 v[192:195], v153 offset:33792
	ds_read_b128 v[196:199], v153 offset:34816
	ds_read_b128 v[200:203], v153 offset:35840
	ds_read_b128 v[204:207], v153 offset:36864
	ds_read_b128 v[208:211], v153 offset:37888
	ds_read_b128 v[212:215], v153 offset:38912
	ds_read_b128 v[216:219], v153 offset:39936
	global_load_lds_dwordx4 v128, s[28:29]
	s_mov_b32 m0, s40
	s_nop 0
	global_load_lds_dwordx4 v132, s[28:29]
	s_waitcnt vmcnt(8)
	s_waitcnt lgkmcnt(0)
	s_barrier
	s_setprio 1
	s_waitcnt lgkmcnt(0)
	v_mfma_f32_16x16x32_bf16 v[124:127], v[156:159], v[188:191], v[124:127]
	v_mfma_f32_16x16x32_bf16 v[120:123], v[164:167], v[188:191], v[120:123]
	v_mfma_f32_16x16x32_bf16 v[108:111], v[156:159], v[196:199], v[108:111]
	v_mfma_f32_16x16x32_bf16 v[104:107], v[164:167], v[196:199], v[104:107]
	v_mfma_f32_16x16x32_bf16 v[92:95], v[156:159], v[204:207], v[92:95]
	v_mfma_f32_16x16x32_bf16 v[88:91], v[164:167], v[204:207], v[88:91]
	v_mfma_f32_16x16x32_bf16 v[76:79], v[156:159], v[212:215], v[76:79]
	v_mfma_f32_16x16x32_bf16 v[72:75], v[164:167], v[212:215], v[72:75]
	v_mfma_f32_16x16x32_bf16 v[124:127], v[160:163], v[192:195], v[124:127]
	v_mfma_f32_16x16x32_bf16 v[120:123], v[168:171], v[192:195], v[120:123]
	v_mfma_f32_16x16x32_bf16 v[108:111], v[160:163], v[200:203], v[108:111]
	v_mfma_f32_16x16x32_bf16 v[104:107], v[168:171], v[200:203], v[104:107]
	v_mfma_f32_16x16x32_bf16 v[92:95], v[160:163], v[208:211], v[92:95]
	v_mfma_f32_16x16x32_bf16 v[88:91], v[168:171], v[208:211], v[88:91]
	v_mfma_f32_16x16x32_bf16 v[76:79], v[160:163], v[216:219], v[76:79]
	v_mfma_f32_16x16x32_bf16 v[72:75], v[168:171], v[216:219], v[72:75]
	s_setprio 0
	s_setprio 1
	v_mfma_f32_16x16x32_bf16 v[116:119], v[172:175], v[188:191], v[116:119]
	v_mfma_f32_16x16x32_bf16 v[112:115], v[180:183], v[188:191], v[112:115]
	v_mfma_f32_16x16x32_bf16 v[100:103], v[172:175], v[196:199], v[100:103]
	v_mfma_f32_16x16x32_bf16 v[96:99], v[180:183], v[196:199], v[96:99]
	v_mfma_f32_16x16x32_bf16 v[84:87], v[172:175], v[204:207], v[84:87]
	v_mfma_f32_16x16x32_bf16 v[80:83], v[180:183], v[204:207], v[80:83]
	v_mfma_f32_16x16x32_bf16 v[68:71], v[172:175], v[212:215], v[68:71]
	v_mfma_f32_16x16x32_bf16 v[64:67], v[180:183], v[212:215], v[64:67]
	v_mfma_f32_16x16x32_bf16 v[116:119], v[176:179], v[192:195], v[116:119]
	v_mfma_f32_16x16x32_bf16 v[112:115], v[184:187], v[192:195], v[112:115]
	v_mfma_f32_16x16x32_bf16 v[100:103], v[176:179], v[200:203], v[100:103]
	v_mfma_f32_16x16x32_bf16 v[96:99], v[184:187], v[200:203], v[96:99]
	v_mfma_f32_16x16x32_bf16 v[84:87], v[176:179], v[208:211], v[84:87]
	v_mfma_f32_16x16x32_bf16 v[80:83], v[184:187], v[208:211], v[80:83]
	v_mfma_f32_16x16x32_bf16 v[68:71], v[176:179], v[216:219], v[68:71]
	v_mfma_f32_16x16x32_bf16 v[64:67], v[184:187], v[216:219], v[64:67]
	s_setprio 0
	s_barrier
; #define PG8_STAGE(bufoff, gbase, voff) do { _Pragma("unroll") for (int _i = 0; _i < 2; ++_i) \
;         __builtin_amdgcn_global_load_lds((const unsigned*)((const char*)(gbase) + (voff)[_i]), (LAS unsigned*)(lds + (bufoff) + ldsw + _i * 8192), 16, 0, 0); } while (0)
; #define PG8_LDA(dst, b, h) do { _Pragma("unroll") for (int m = 0; m < 4; ++m) _Pragma("unroll") for (int k = 0; k < 2; ++k) dst[m][k] = *(const LAS bf16x8*)(lds + PG8_SA(b, h) + aoff + m * 2048 + k * 1024); } while (0)
; #define PG8_LDB(dst, b, h) do { _Pragma("unroll") for (int n = 0; n < 2; ++n) _Pragma("unroll") for (int k = 0; k < 2; ++k) dst[n][k] = *(const LAS bf16x8*)(lds + PG8_SB(b, h) + boff + n * 2048 + k * 1024); } while (0)
; #define PG8_MMA(ai, bj, At, Bt) do { __builtin_amdgcn_s_setprio(1); _Pragma("unroll") for (int m = 0; m < 4; ++m) _Pragma("unroll") for (int n = 0; n < 2; ++n) _Pragma("unroll") for (int k = 0; k < 2; ++k) \
;         acc[ai][bj][m][n] = __builtin_amdgcn_mfma_f32_16x16x32_bf16(Bt[n][k], At[m][k], acc[ai][bj][m][n], 0, 0, 0); __builtin_amdgcn_s_setprio(0); } while (0)
; #define PG8_WAIT_V(n) asm volatile("s_waitcnt vmcnt(" #n ")" ::: "memory")
; #define PG8_WAIT_L(n) asm volatile("s_waitcnt lgkmcnt(" #n ")" ::: "memory")
; template <class Epi, class Sched>
; __device__ __forceinline__ void gemm_phase(LAS unsigned char* lds, const Gemm g, const Sched& S, const Epi& E, int wave_id) {
;     ...
;         for (int t = 0; t < nt; t += 2) {
;             const bool last = (t == nt - 2);
;             const char* a1 = cA + (size_t)(t + 1) * kstep;
;             const char* a2 = last ? nA : cA + (size_t)(t + 2) * kstep; const char* b2 = last ? nB : cB + (size_t)(t + 2) * kstep;
;             const char* a3 = a2 + kstep; const char* b3 = b2 + kstep;
;             PG8_LDB(B0, 0, 0); PG8_LDB(B1, 0, 1); PG8_SCHED; PG8_LDA(At, 0, 0); PG8_STAGE(PG8_SA(1, 1), a1 + hstepA, voffA);
;             PG8_WAIT_V(8); PG8_WAIT_L(0); PG8_BAR; PG8_MMA(0, 0, At, B0); PG8_MMA(0, 1, At, B1); PG8_BAR; PG8_SCHED;
;     ...
;             PG8_WAIT_V(8); PG8_WAIT_L(0); PG8_BAR; PG8_MMA(0, 0, At, B0); PG8_MMA(0, 1, At, B1); PG8_BAR; PG8_SCHED;
;             PG8_LDA(At, 1, 1); PG8_STAGE(PG8_SB(1, 0), b3, voffB); PG8_STAGE(PG8_SB(1, 1), b3 + hstepB, voffB); PG8_STAGE(PG8_SA(1, 0), a3, voffA);
;             PG8_WAIT_V(8); PG8_WAIT_L(0); PG8_BAR; PG8_MMA(1, 0, At, B0); PG8_MMA(1, 1, At, B1); PG8_BAR; PG8_SCHED;
	s_add_i32 s28, s54, s2
	v_lshl_add_u64 v[220:221], v[220:221], 0, s[10:11]
	s_mov_b32 m0, s28
	ds_read_b128 v[188:191], v153 offset:49152
	ds_read_b128 v[192:195], v153 offset:50176
	ds_read_b128 v[196:199], v153 offset:51200
	ds_read_b128 v[200:203], v153 offset:52224
	ds_read_b128 v[204:207], v153 offset:53248
	ds_read_b128 v[208:211], v153 offset:54272
	ds_read_b128 v[212:215], v153 offset:55296
	ds_read_b128 v[216:219], v153 offset:56320
	global_load_lds_dwordx4 v[220:221], off
	s_add_i32 m0, s28, 0x2000
	s_add_u32 s26, s26, 0x40080
	v_lshl_add_u64 v[220:221], v[222:223], 0, s[10:11]
	s_addc_u32 s27, s27, 0
	s_add_i32 s28, s55, s2
	global_load_lds_dwordx4 v[220:221], off
	s_mov_b32 m0, s28
	s_nop 0
	global_load_lds_dwordx4 v130, s[26:27]
	s_add_i32 m0, s28, 0x2000
	s_nop 0
	global_load_lds_dwordx4 v134, s[26:27]
	v_lshl_add_u64 v[220:221], v[224:225], 0, s[10:11]
	s_mov_b32 m0, s45
	s_nop 0
	global_load_lds_dwordx4 v[220:221], off
	v_lshl_add_u64 v[220:221], v[226:227], 0, s[10:11]
	s_mov_b32 m0, s46
	s_nop 0
	global_load_lds_dwordx4 v[220:221], off
	s_waitcnt vmcnt(8)
	s_waitcnt lgkmcnt(0)
	s_barrier
	s_setprio 1
	s_waitcnt lgkmcnt(0)
	v_mfma_f32_16x16x32_bf16 v[60:63], v[156:159], v[188:191], v[60:63]
	v_mfma_f32_16x16x32_bf16 v[56:59], v[164:167], v[188:191], v[56:59]
	v_mfma_f32_16x16x32_bf16 v[44:47], v[156:159], v[196:199], v[44:47]
	v_mfma_f32_16x16x32_bf16 v[40:43], v[164:167], v[196:199], v[40:43]
	v_mfma_f32_16x16x32_bf16 v[28:31], v[156:159], v[204:207], v[28:31]
	v_mfma_f32_16x16x32_bf16 v[24:27], v[164:167], v[204:207], v[24:27]
	v_mfma_f32_16x16x32_bf16 v[12:15], v[156:159], v[212:215], v[12:15]
	v_mfma_f32_16x16x32_bf16 v[8:11], v[164:167], v[212:215], v[8:11]
	v_mfma_f32_16x16x32_bf16 v[60:63], v[160:163], v[192:195], v[60:63]
	v_mfma_f32_16x16x32_bf16 v[56:59], v[168:171], v[192:195], v[56:59]
	v_mfma_f32_16x16x32_bf16 v[44:47], v[160:163], v[200:203], v[44:47]
	v_mfma_f32_16x16x32_bf16 v[40:43], v[168:171], v[200:203], v[40:43]
	v_mfma_f32_16x16x32_bf16 v[28:31], v[160:163], v[208:211], v[28:31]
	v_mfma_f32_16x16x32_bf16 v[24:27], v[168:171], v[208:211], v[24:27]
	v_mfma_f32_16x16x32_bf16 v[12:15], v[160:163], v[216:219], v[12:15]
	v_mfma_f32_16x16x32_bf16 v[8:11], v[168:171], v[216:219], v[8:11]
	s_setprio 0
	s_setprio 1
	v_mfma_f32_16x16x32_bf16 v[52:55], v[172:175], v[188:191], v[52:55]
	v_mfma_f32_16x16x32_bf16 v[48:51], v[180:183], v[188:191], v[48:51]
	v_mfma_f32_16x16x32_bf16 v[36:39], v[172:175], v[196:199], v[36:39]
	v_mfma_f32_16x16x32_bf16 v[32:35], v[180:183], v[196:199], v[32:35]
	v_mfma_f32_16x16x32_bf16 v[20:23], v[172:175], v[204:207], v[20:23]
	v_mfma_f32_16x16x32_bf16 v[16:19], v[180:183], v[204:207], v[16:19]
	v_mfma_f32_16x16x32_bf16 v[4:7], v[172:175], v[212:215], v[4:7]
	v_mfma_f32_16x16x32_bf16 v[0:3], v[180:183], v[212:215], v[0:3]
	v_mfma_f32_16x16x32_bf16 v[52:55], v[176:179], v[192:195], v[52:55]
	v_mfma_f32_16x16x32_bf16 v[48:51], v[184:187], v[192:195], v[48:51]
	v_mfma_f32_16x16x32_bf16 v[36:39], v[176:179], v[200:203], v[36:39]
	v_mfma_f32_16x16x32_bf16 v[32:35], v[184:187], v[200:203], v[32:35]
	v_mfma_f32_16x16x32_bf16 v[20:23], v[176:179], v[208:211], v[20:23]
	v_mfma_f32_16x16x32_bf16 v[16:19], v[184:187], v[208:211], v[16:19]
	v_mfma_f32_16x16x32_bf16 v[4:7], v[176:179], v[216:219], v[4:7]
	v_mfma_f32_16x16x32_bf16 v[0:3], v[184:187], v[216:219], v[0:3]
	s_setprio 0
	s_barrier
	s_add_i32 s53, s53, 2
	s_add_u32 s24, s24, 0x100
	s_addc_u32 s25, s25, 0
	s_add_u32 s51, s51, 0x100
	s_addc_u32 s52, s52, 0
	s_cmp_gt_u32 s53, 13
.LBB0_960:
	ds_read_b128 v[156:159], v151
	ds_read_b128 v[160:163], v151 offset:1024
	ds_read_b128 v[164:167], v151 offset:2048
	ds_read_b128 v[168:171], v151 offset:3072
	ds_read_b128 v[172:175], v152
	ds_read_b128 v[176:179], v152 offset:1024
	ds_read_b128 v[180:183], v152 offset:2048
	ds_read_b128 v[184:187], v152 offset:3072
	s_add_u32 s26, s24, 0xfffc0080
	s_addc_u32 s27, s25, -1
	s_cmp_eq_u32 s53, 12
	s_cselect_b32 s29, s17, s27
	s_cselect_b32 s28, s49, s26
	s_cselect_b32 s27, s15, s52
	s_cselect_b32 s26, s50, s51
	s_add_i32 m0, s37, 0xc000
	ds_read_b128 v[188:191], v153
	ds_read_b128 v[192:195], v153 offset:1024
	ds_read_b128 v[196:199], v153 offset:2048
	ds_read_b128 v[200:203], v153 offset:3072
	ds_read_b128 v[204:207], v153 offset:4096
	ds_read_b128 v[208:211], v153 offset:5120
	ds_read_b128 v[212:215], v153 offset:6144
	ds_read_b128 v[216:219], v153 offset:7168
	global_load_lds_dwordx4 v142, s[24:25]
	s_add_i32 m0, s37, 0xe000
	s_nop 0
	global_load_lds_dwordx4 v144, s[24:25]
	s_waitcnt vmcnt(8)
	s_waitcnt lgkmcnt(0)
	s_barrier
; #define PG8_STAGE(bufoff, gbase, voff) do { _Pragma("unroll") for (int _i = 0; _i < 2; ++_i) \
;         __builtin_amdgcn_global_load_lds((const unsigned*)((const char*)(gbase) + (voff)[_i]), (LAS unsigned*)(lds + (bufoff) + ldsw + _i * 8192), 16, 0, 0); } while (0)
; #define PG8_LDA(dst, b, h) do { _Pragma("unroll") for (int m = 0; m < 4; ++m) _Pragma("unroll") for (int k = 0; k < 2; ++k) dst[m][k] = *(const LAS bf16x8*)(lds + PG8_SA(b, h) + aoff + m * 2048 + k * 1024); } while (0)
; #define PG8_LDB(dst, b, h) do { _Pragma("unroll") for (int n = 0; n < 2; ++n) _Pragma("unroll") for (int k = 0; k < 2; ++k) dst[n][k] = *(const LAS bf16x8*)(lds + PG8_SB(b, h) + boff + n * 2048 + k * 1024); } while (0)
; #define PG8_MMA(ai, bj, At, Bt) do { __builtin_amdgcn_s_setprio(1); _Pragma("unroll") for (int m = 0; m < 4; ++m) _Pragma("unroll") for (int n = 0; n < 2; ++n) _Pragma("unroll") for (int k = 0; k < 2; ++k) \
;         acc[ai][bj][m][n] = __builtin_amdgcn_mfma_f32_16x16x32_bf16(Bt[n][k], At[m][k], acc[ai][bj][m][n], 0, 0, 0); __builtin_amdgcn_s_setprio(0); } while (0)
; #define PG8_WAIT_V(n) asm volatile("s_waitcnt vmcnt(" #n ")" ::: "memory")
; #define PG8_WAIT_L(n) asm volatile("s_waitcnt lgkmcnt(" #n ")" ::: "memory")
; #define PG8_BAR __builtin_amdgcn_s_barrier()
; #define PG8_SCHED __builtin_amdgcn_sched_barrier(0)
; template <class Epi, class Sched>
; __device__ __forceinline__ void gemm_phase(LAS unsigned char* lds, const Gemm g, const Sched& S, const Epi& E, int wave_id) {
;     ...
;             PG8_WAIT_V(8); PG8_WAIT_L(0); PG8_BAR; PG8_MMA(0, 0, At, B0); PG8_MMA(0, 1, At, B1); PG8_BAR; PG8_SCHED;
;             PG8_LDA(At, 0, 1); PG8_STAGE(PG8_SB(0, 0), b2, voffB); PG8_STAGE(PG8_SB(0, 1), b2 + hstepB, voffB); PG8_STAGE(PG8_SA(0, 0), a2, voffA);
;             PG8_WAIT_V(8); PG8_WAIT_L(0); PG8_BAR; PG8_MMA(1, 0, At, B0); PG8_MMA(1, 1, At, B1); PG8_BAR; PG8_SCHED;
;             PG8_LDB(B0, 1, 0); PG8_LDB(B1, 1, 1); PG8_SCHED; PG8_LDA(At, 1, 0); PG8_STAGE(PG8_SA(0, 1), a2 + hstepA, voffA);
;             PG8_WAIT_V(8); PG8_WAIT_L(0); PG8_BAR; PG8_MMA(0, 0, At, B0); PG8_MMA(0, 1, At, B1); PG8_BAR; PG8_SCHED;
	s_setprio 1
	s_waitcnt lgkmcnt(0)
	v_mfma_f32_16x16x32_bf16 v[124:127], v[156:159], v[188:191], v[124:127]
	v_mfma_f32_16x16x32_bf16 v[120:123], v[164:167], v[188:191], v[120:123]
	v_mfma_f32_16x16x32_bf16 v[108:111], v[156:159], v[196:199], v[108:111]
	v_mfma_f32_16x16x32_bf16 v[104:107], v[164:167], v[196:199], v[104:107]
	v_mfma_f32_16x16x32_bf16 v[92:95], v[156:159], v[204:207], v[92:95]
	v_mfma_f32_16x16x32_bf16 v[88:91], v[164:167], v[204:207], v[88:91]
	v_mfma_f32_16x16x32_bf16 v[76:79], v[156:159], v[212:215], v[76:79]
	v_mfma_f32_16x16x32_bf16 v[72:75], v[164:167], v[212:215], v[72:75]
	v_mfma_f32_16x16x32_bf16 v[124:127], v[160:163], v[192:195], v[124:127]
	v_mfma_f32_16x16x32_bf16 v[120:123], v[168:171], v[192:195], v[120:123]
	v_mfma_f32_16x16x32_bf16 v[108:111], v[160:163], v[200:203], v[108:111]
	v_mfma_f32_16x16x32_bf16 v[104:107], v[168:171], v[200:203], v[104:107]
	v_mfma_f32_16x16x32_bf16 v[92:95], v[160:163], v[208:211], v[92:95]
	v_mfma_f32_16x16x32_bf16 v[88:91], v[168:171], v[208:211], v[88:91]
	v_mfma_f32_16x16x32_bf16 v[76:79], v[160:163], v[216:219], v[76:79]
	v_mfma_f32_16x16x32_bf16 v[72:75], v[168:171], v[216:219], v[72:75]
	s_setprio 0
	s_setprio 1
	v_mfma_f32_16x16x32_bf16 v[116:119], v[172:175], v[188:191], v[116:119]
	v_mfma_f32_16x16x32_bf16 v[112:115], v[180:183], v[188:191], v[112:115]
	v_mfma_f32_16x16x32_bf16 v[100:103], v[172:175], v[196:199], v[100:103]
	v_mfma_f32_16x16x32_bf16 v[96:99], v[180:183], v[196:199], v[96:99]
	v_mfma_f32_16x16x32_bf16 v[84:87], v[172:175], v[204:207], v[84:87]
	v_mfma_f32_16x16x32_bf16 v[80:83], v[180:183], v[204:207], v[80:83]
	v_mfma_f32_16x16x32_bf16 v[68:71], v[172:175], v[212:215], v[68:71]
	v_mfma_f32_16x16x32_bf16 v[64:67], v[180:183], v[212:215], v[64:67]
	v_mfma_f32_16x16x32_bf16 v[116:119], v[176:179], v[192:195], v[116:119]
	v_mfma_f32_16x16x32_bf16 v[112:115], v[184:187], v[192:195], v[112:115]
	v_mfma_f32_16x16x32_bf16 v[100:103], v[176:179], v[200:203], v[100:103]
	v_mfma_f32_16x16x32_bf16 v[96:99], v[184:187], v[200:203], v[96:99]
	v_mfma_f32_16x16x32_bf16 v[84:87], v[176:179], v[208:211], v[84:87]
	v_mfma_f32_16x16x32_bf16 v[80:83], v[184:187], v[208:211], v[80:83]
	v_mfma_f32_16x16x32_bf16 v[68:71], v[176:179], v[216:219], v[68:71]
	v_mfma_f32_16x16x32_bf16 v[64:67], v[184:187], v[216:219], v[64:67]
	s_setprio 0
	s_barrier
	s_add_i32 s54, s47, s2
	v_lshl_add_u64 v[220:221], s[26:27], 0, v[130:131]
	s_mov_b32 m0, s54
	ds_read_b128 v[188:191], v153 offset:16384
	ds_read_b128 v[192:195], v153 offset:17408
	ds_read_b128 v[196:199], v153 offset:18432
	ds_read_b128 v[200:203], v153 offset:19456
	ds_read_b128 v[204:207], v153 offset:20480
	ds_read_b128 v[208:211], v153 offset:21504
	ds_read_b128 v[212:215], v153 offset:22528
	ds_read_b128 v[216:219], v153 offset:23552
	global_load_lds_dwordx4 v[220:221], off
	s_add_i32 m0, s54, 0x2000
	s_add_u32 s54, s26, 0x40000
	v_lshl_add_u64 v[222:223], s[26:27], 0, v[134:135]
	s_addc_u32 s55, s27, 0
	s_add_i32 s58, s48, s2
	global_load_lds_dwordx4 v[222:223], off
	s_mov_b32 m0, s58
	v_lshl_add_u64 v[226:227], s[28:29], 0, v[132:133]
	global_load_lds_dwordx4 v130, s[54:55]
	s_add_i32 m0, s58, 0x2000
	s_nop 0
	global_load_lds_dwordx4 v134, s[54:55]
	v_lshl_add_u64 v[224:225], s[28:29], 0, v[128:129]
	s_mov_b32 m0, s37
	s_nop 0
	global_load_lds_dwordx4 v[224:225], off
	s_mov_b32 m0, s38
	s_nop 0
	global_load_lds_dwordx4 v[226:227], off
	s_waitcnt vmcnt(8)
	s_waitcnt lgkmcnt(0)
	s_barrier
	s_setprio 1
	s_waitcnt lgkmcnt(0)
	v_mfma_f32_16x16x32_bf16 v[60:63], v[156:159], v[188:191], v[60:63]
	v_mfma_f32_16x16x32_bf16 v[56:59], v[164:167], v[188:191], v[56:59]
	v_mfma_f32_16x16x32_bf16 v[44:47], v[156:159], v[196:199], v[44:47]
	v_mfma_f32_16x16x32_bf16 v[40:43], v[164:167], v[196:199], v[40:43]
	v_mfma_f32_16x16x32_bf16 v[28:31], v[156:159], v[204:207], v[28:31]
	v_mfma_f32_16x16x32_bf16 v[24:27], v[164:167], v[204:207], v[24:27]
	v_mfma_f32_16x16x32_bf16 v[12:15], v[156:159], v[212:215], v[12:15]
	v_mfma_f32_16x16x32_bf16 v[8:11], v[164:167], v[212:215], v[8:11]
	v_mfma_f32_16x16x32_bf16 v[60:63], v[160:163], v[192:195], v[60:63]
	v_mfma_f32_16x16x32_bf16 v[56:59], v[168:171], v[192:195], v[56:59]
	v_mfma_f32_16x16x32_bf16 v[44:47], v[160:163], v[200:203], v[44:47]
	v_mfma_f32_16x16x32_bf16 v[40:43], v[168:171], v[200:203], v[40:43]
	v_mfma_f32_16x16x32_bf16 v[28:31], v[160:163], v[208:211], v[28:31]
	v_mfma_f32_16x16x32_bf16 v[24:27], v[168:171], v[208:211], v[24:27]
	v_mfma_f32_16x16x32_bf16 v[12:15], v[160:163], v[216:219], v[12:15]
	v_mfma_f32_16x16x32_bf16 v[8:11], v[168:171], v[216:219], v[8:11]
	s_setprio 0
	s_setprio 1
	v_mfma_f32_16x16x32_bf16 v[52:55], v[172:175], v[188:191], v[52:55]
	v_mfma_f32_16x16x32_bf16 v[48:51], v[180:183], v[188:191], v[48:51]
	v_mfma_f32_16x16x32_bf16 v[36:39], v[172:175], v[196:199], v[36:39]
	v_mfma_f32_16x16x32_bf16 v[32:35], v[180:183], v[196:199], v[32:35]
	v_mfma_f32_16x16x32_bf16 v[20:23], v[172:175], v[204:207], v[20:23]
	v_mfma_f32_16x16x32_bf16 v[16:19], v[180:183], v[204:207], v[16:19]
	v_mfma_f32_16x16x32_bf16 v[4:7], v[172:175], v[212:215], v[4:7]
	v_mfma_f32_16x16x32_bf16 v[0:3], v[180:183], v[212:215], v[0:3]
	v_mfma_f32_16x16x32_bf16 v[52:55], v[176:179], v[192:195], v[52:55]
	v_mfma_f32_16x16x32_bf16 v[48:51], v[184:187], v[192:195], v[48:51]
	v_mfma_f32_16x16x32_bf16 v[36:39], v[176:179], v[200:203], v[36:39]
	v_mfma_f32_16x16x32_bf16 v[32:35], v[184:187], v[200:203], v[32:35]
	v_mfma_f32_16x16x32_bf16 v[20:23], v[176:179], v[208:211], v[20:23]
	v_mfma_f32_16x16x32_bf16 v[16:19], v[184:187], v[208:211], v[16:19]
	v_mfma_f32_16x16x32_bf16 v[4:7], v[176:179], v[216:219], v[4:7]
	v_mfma_f32_16x16x32_bf16 v[0:3], v[184:187], v[216:219], v[0:3]
	s_setprio 0
	s_barrier
; #define PG8_STAGE(bufoff, gbase, voff) do { _Pragma("unroll") for (int _i = 0; _i < 2; ++_i) \
;         __builtin_amdgcn_global_load_lds((const unsigned*)((const char*)(gbase) + (voff)[_i]), (LAS unsigned*)(lds + (bufoff) + ldsw + _i * 8192), 16, 0, 0); } while (0)
; #define PG8_LDA(dst, b, h) do { _Pragma("unroll") for (int m = 0; m < 4; ++m) _Pragma("unroll") for (int k = 0; k < 2; ++k) dst[m][k] = *(const LAS bf16x8*)(lds + PG8_SA(b, h) + aoff + m * 2048 + k * 1024); } while (0)
; #define PG8_LDB(dst, b, h) do { _Pragma("unroll") for (int n = 0; n < 2; ++n) _Pragma("unroll") for (int k = 0; k < 2; ++k) dst[n][k] = *(const LAS bf16x8*)(lds + PG8_SB(b, h) + boff + n * 2048 + k * 1024); } while (0)
; #define PG8_MMA(ai, bj, At, Bt) do { __builtin_amdgcn_s_setprio(1); _Pragma("unroll") for (int m = 0; m < 4; ++m) _Pragma("unroll") for (int n = 0; n < 2; ++n) _Pragma("unroll") for (int k = 0; k < 2; ++k) \
;         acc[ai][bj][m][n] = __builtin_amdgcn_mfma_f32_16x16x32_bf16(Bt[n][k], At[m][k], acc[ai][bj][m][n], 0, 0, 0); __builtin_amdgcn_s_setprio(0); } while (0)
; #define PG8_WAIT_V(n) asm volatile("s_waitcnt vmcnt(" #n ")" ::: "memory")
; #define PG8_WAIT_L(n) asm volatile("s_waitcnt lgkmcnt(" #n ")" ::: "memory")
; #define PG8_BAR __builtin_amdgcn_s_barrier()
; #define PG8_SCHED __builtin_amdgcn_sched_barrier(0)
; template <class Epi, class Sched>
; __device__ __forceinline__ void gemm_phase(LAS unsigned char* lds, const Gemm g, const Sched& S, const Epi& E, int wave_id) {
;     ...
;             PG8_LDB(B0, 1, 0); PG8_LDB(B1, 1, 1); PG8_SCHED; PG8_LDA(At, 1, 0); PG8_STAGE(PG8_SA(0, 1), a2 + hstepA, voffA);
;             PG8_WAIT_V(8); PG8_WAIT_L(0); PG8_BAR; PG8_MMA(0, 0, At, B0); PG8_MMA(0, 1, At, B1); PG8_BAR; PG8_SCHED;
;             PG8_LDA(At, 1, 1); PG8_STAGE(PG8_SB(1, 0), b3, voffB); PG8_STAGE(PG8_SB(1, 1), b3 + hstepB, voffB); PG8_STAGE(PG8_SA(1, 0), a3, voffA);
;             PG8_WAIT_V(8); PG8_WAIT_L(0); PG8_BAR; PG8_MMA(1, 0, At, B0); PG8_MMA(1, 1, At, B1); PG8_BAR; PG8_SCHED;
;         }
	s_add_i32 s54, 0, 0x18000
	s_add_i32 s55, 0, 0x1c000
	v_add_u32_e32 v168, s54, v150
	v_add_u32_e32 v184, s55, v150
	ds_read_b128 v[156:159], v168
	ds_read_b128 v[160:163], v168 offset:1024
	ds_read_b128 v[164:167], v168 offset:2048
	ds_read_b128 v[168:171], v168 offset:3072
	ds_read_b128 v[172:175], v184
	ds_read_b128 v[176:179], v184 offset:1024
	ds_read_b128 v[180:183], v184 offset:2048
	ds_read_b128 v[184:187], v184 offset:3072
	s_add_u32 s28, s28, 0x40000
	s_addc_u32 s29, s29, 0
	s_mov_b32 m0, s39
	ds_read_b128 v[188:191], v153 offset:32768
	ds_read_b128 v[192:195], v153 offset:33792
	ds_read_b128 v[196:199], v153 offset:34816
	ds_read_b128 v[200:203], v153 offset:35840
	ds_read_b128 v[204:207], v153 offset:36864
	ds_read_b128 v[208:211], v153 offset:37888
	ds_read_b128 v[212:215], v153 offset:38912
	ds_read_b128 v[216:219], v153 offset:39936
	global_load_lds_dwordx4 v128, s[28:29]
	s_mov_b32 m0, s40
	s_nop 0
	global_load_lds_dwordx4 v132, s[28:29]
	s_waitcnt vmcnt(8)
	s_waitcnt lgkmcnt(0)
	s_barrier
	s_setprio 1
	s_waitcnt lgkmcnt(0)
	v_mfma_f32_16x16x32_bf16 v[124:127], v[156:159], v[188:191], v[124:127]
	v_mfma_f32_16x16x32_bf16 v[120:123], v[164:167], v[188:191], v[120:123]
	v_mfma_f32_16x16x32_bf16 v[108:111], v[156:159], v[196:199], v[108:111]
	v_mfma_f32_16x16x32_bf16 v[104:107], v[164:167], v[196:199], v[104:107]
	v_mfma_f32_16x16x32_bf16 v[92:95], v[156:159], v[204:207], v[92:95]
	v_mfma_f32_16x16x32_bf16 v[88:91], v[164:167], v[204:207], v[88:91]
	v_mfma_f32_16x16x32_bf16 v[76:79], v[156:159], v[212:215], v[76:79]
	v_mfma_f32_16x16x32_bf16 v[72:75], v[164:167], v[212:215], v[72:75]
	v_mfma_f32_16x16x32_bf16 v[124:127], v[160:163], v[192:195], v[124:127]
	v_mfma_f32_16x16x32_bf16 v[120:123], v[168:171], v[192:195], v[120:123]
	v_mfma_f32_16x16x32_bf16 v[108:111], v[160:163], v[200:203], v[108:111]
	v_mfma_f32_16x16x32_bf16 v[104:107], v[168:171], v[200:203], v[104:107]
	v_mfma_f32_16x16x32_bf16 v[92:95], v[160:163], v[208:211], v[92:95]
	v_mfma_f32_16x16x32_bf16 v[88:91], v[168:171], v[208:211], v[88:91]
	v_mfma_f32_16x16x32_bf16 v[76:79], v[160:163], v[216:219], v[76:79]
	v_mfma_f32_16x16x32_bf16 v[72:75], v[168:171], v[216:219], v[72:75]
	s_setprio 0
	s_setprio 1
	v_mfma_f32_16x16x32_bf16 v[116:119], v[172:175], v[188:191], v[116:119]
	v_mfma_f32_16x16x32_bf16 v[112:115], v[180:183], v[188:191], v[112:115]
	v_mfma_f32_16x16x32_bf16 v[100:103], v[172:175], v[196:199], v[100:103]
	v_mfma_f32_16x16x32_bf16 v[96:99], v[180:183], v[196:199], v[96:99]
	v_mfma_f32_16x16x32_bf16 v[84:87], v[172:175], v[204:207], v[84:87]
	v_mfma_f32_16x16x32_bf16 v[80:83], v[180:183], v[204:207], v[80:83]
	v_mfma_f32_16x16x32_bf16 v[68:71], v[172:175], v[212:215], v[68:71]
	v_mfma_f32_16x16x32_bf16 v[64:67], v[180:183], v[212:215], v[64:67]
	v_mfma_f32_16x16x32_bf16 v[116:119], v[176:179], v[192:195], v[116:119]
	v_mfma_f32_16x16x32_bf16 v[112:115], v[184:187], v[192:195], v[112:115]
	v_mfma_f32_16x16x32_bf16 v[100:103], v[176:179], v[200:203], v[100:103]
	v_mfma_f32_16x16x32_bf16 v[96:99], v[184:187], v[200:203], v[96:99]
	v_mfma_f32_16x16x32_bf16 v[84:87], v[176:179], v[208:211], v[84:87]
	v_mfma_f32_16x16x32_bf16 v[80:83], v[184:187], v[208:211], v[80:83]
	v_mfma_f32_16x16x32_bf16 v[68:71], v[176:179], v[216:219], v[68:71]
	v_mfma_f32_16x16x32_bf16 v[64:67], v[184:187], v[216:219], v[64:67]
	s_setprio 0
	s_barrier
	s_add_i32 s28, s54, s2
	v_lshl_add_u64 v[220:221], v[220:221], 0, s[10:11]
	s_mov_b32 m0, s28
	ds_read_b128 v[188:191], v153 offset:49152
	ds_read_b128 v[192:195], v153 offset:50176
	ds_read_b128 v[196:199], v153 offset:51200
	ds_read_b128 v[200:203], v153 offset:52224
	ds_read_b128 v[204:207], v153 offset:53248
	ds_read_b128 v[208:211], v153 offset:54272
	ds_read_b128 v[212:215], v153 offset:55296
	ds_read_b128 v[216:219], v153 offset:56320
	global_load_lds_dwordx4 v[220:221], off
	s_add_i32 m0, s28, 0x2000
	s_add_u32 s26, s26, 0x40080
	v_lshl_add_u64 v[220:221], v[222:223], 0, s[10:11]
	s_addc_u32 s27, s27, 0
	s_add_i32 s28, s55, s2
	global_load_lds_dwordx4 v[220:221], off
	s_mov_b32 m0, s28
	s_nop 0
	global_load_lds_dwordx4 v130, s[26:27]
	s_add_i32 m0, s28, 0x2000
	s_nop 0
	global_load_lds_dwordx4 v134, s[26:27]
	v_lshl_add_u64 v[220:221], v[224:225], 0, s[10:11]
	s_mov_b32 m0, s45
	s_nop 0
	global_load_lds_dwordx4 v[220:221], off
	v_lshl_add_u64 v[220:221], v[226:227], 0, s[10:11]
	s_mov_b32 m0, s46
	s_nop 0
	global_load_lds_dwordx4 v[220:221], off
	s_waitcnt vmcnt(8)
	s_waitcnt lgkmcnt(0)
	s_barrier
	s_setprio 1
	s_waitcnt lgkmcnt(0)
	v_mfma_f32_16x16x32_bf16 v[60:63], v[156:159], v[188:191], v[60:63]
	v_mfma_f32_16x16x32_bf16 v[56:59], v[164:167], v[188:191], v[56:59]
	v_mfma_f32_16x16x32_bf16 v[44:47], v[156:159], v[196:199], v[44:47]
	v_mfma_f32_16x16x32_bf16 v[40:43], v[164:167], v[196:199], v[40:43]
	v_mfma_f32_16x16x32_bf16 v[28:31], v[156:159], v[204:207], v[28:31]
	v_mfma_f32_16x16x32_bf16 v[24:27], v[164:167], v[204:207], v[24:27]
	v_mfma_f32_16x16x32_bf16 v[12:15], v[156:159], v[212:215], v[12:15]
	v_mfma_f32_16x16x32_bf16 v[8:11], v[164:167], v[212:215], v[8:11]
	v_mfma_f32_16x16x32_bf16 v[60:63], v[160:163], v[192:195], v[60:63]
	v_mfma_f32_16x16x32_bf16 v[56:59], v[168:171], v[192:195], v[56:59]
	v_mfma_f32_16x16x32_bf16 v[44:47], v[160:163], v[200:203], v[44:47]
	v_mfma_f32_16x16x32_bf16 v[40:43], v[168:171], v[200:203], v[40:43]
	v_mfma_f32_16x16x32_bf16 v[28:31], v[160:163], v[208:211], v[28:31]
	v_mfma_f32_16x16x32_bf16 v[24:27], v[168:171], v[208:211], v[24:27]
	v_mfma_f32_16x16x32_bf16 v[12:15], v[160:163], v[216:219], v[12:15]
	v_mfma_f32_16x16x32_bf16 v[8:11], v[168:171], v[216:219], v[8:11]
	s_setprio 0
	s_setprio 1
	v_mfma_f32_16x16x32_bf16 v[52:55], v[172:175], v[188:191], v[52:55]
	v_mfma_f32_16x16x32_bf16 v[48:51], v[180:183], v[188:191], v[48:51]
	v_mfma_f32_16x16x32_bf16 v[36:39], v[172:175], v[196:199], v[36:39]
	v_mfma_f32_16x16x32_bf16 v[32:35], v[180:183], v[196:199], v[32:35]
	v_mfma_f32_16x16x32_bf16 v[20:23], v[172:175], v[204:207], v[20:23]
	v_mfma_f32_16x16x32_bf16 v[16:19], v[180:183], v[204:207], v[16:19]
	v_mfma_f32_16x16x32_bf16 v[4:7], v[172:175], v[212:215], v[4:7]
	v_mfma_f32_16x16x32_bf16 v[0:3], v[180:183], v[212:215], v[0:3]
	v_mfma_f32_16x16x32_bf16 v[52:55], v[176:179], v[192:195], v[52:55]
	v_mfma_f32_16x16x32_bf16 v[48:51], v[184:187], v[192:195], v[48:51]
	v_mfma_f32_16x16x32_bf16 v[36:39], v[176:179], v[200:203], v[36:39]
	v_mfma_f32_16x16x32_bf16 v[32:35], v[184:187], v[200:203], v[32:35]
	v_mfma_f32_16x16x32_bf16 v[20:23], v[176:179], v[208:211], v[20:23]
	v_mfma_f32_16x16x32_bf16 v[16:19], v[184:187], v[208:211], v[16:19]
	v_mfma_f32_16x16x32_bf16 v[4:7], v[176:179], v[216:219], v[4:7]
	v_mfma_f32_16x16x32_bf16 v[0:3], v[184:187], v[216:219], v[0:3]
	s_setprio 0
	s_barrier
	s_add_i32 s53, s53, 2
	s_add_u32 s24, s24, 0x100
	s_addc_u32 s25, s25, 0
	s_add_u32 s51, s51, 0x100
	s_addc_u32 s52, s52, 0
	s_cmp_gt_u32 s53, 13
	s_cbranch_scc0 .LBB0_960
	s_and_b64 vcc, exec, s[12:13]
	s_cbranch_vccz .LBB0_963
	s_barrier

; #define PG8_STAGE(bufoff, gbase, voff) do { _Pragma("unroll") for (int _i = 0; _i < 2; ++_i) \
;         __builtin_amdgcn_global_load_lds((const unsigned*)((const char*)(gbase) + (voff)[_i]), (LAS unsigned*)(lds + (bufoff) + ldsw + _i * 8192), 16, 0, 0); } while (0)
; #define PG8_WAIT_V(n) asm volatile("s_waitcnt vmcnt(" #n ")" ::: "memory")
; #define PG8_BAR __builtin_amdgcn_s_barrier()
; #define lane lane_id()
; template <class Epi, class Sched>
; __device__ __forceinline__ void gemm_phase(LAS unsigned char* lds, const Gemm g, const Sched& S, const Epi& E, int wave_id) {
;     ...
;     const int wid = wave_id, lane = tid & 63, wr = wid >> 2, wc = wid & 3, fr = lane & 15, fq = lane >> 4;
;     const int K = g.K, nt = K / BK;
;     unsigned voffA[2], voffB[2];
; #pragma unroll
;     for (int i = 0; i < 2; ++i) { int R, C; stage_rc(tid * 16 + i * 8192, R, C); const int Rb = (R & ~31) + perm32(R & 31);
;         voffA[i] = (unsigned)(R * g.lda + C) * 2u; voffB[i] = (unsigned)(Rb * g.ldb + C) * 2u; }
;     const size_t kstep = (size_t)(BK * 2);
;     const size_t hstepA = (size_t)HALF * g.lda * 2, hstepB = (size_t)HALF * g.ldb * 2;
;     const size_t tstepA = 2 * hstepA, tstepB = 2 * hstepB;
;     const unsigned ldsw = (unsigned)wid * 1024u;
;     const int aoff = lds_byte(wr * 64 + fr, fq * 8), boff = lds_byte(wc * 32 + fr, fq * 8);
;     ...
;     PG8_STAGE(PG8_SB(0, 0), cB, voffB); PG8_STAGE(PG8_SB(0, 1), cB + hstepB, voffB); PG8_STAGE(PG8_SA(0, 0), cA, voffA); PG8_STAGE(PG8_SA(0, 1), cA + hstepA, voffA);
;     if (wr == 1) PG8_BAR;
;     PG8_WAIT_V(2); PG8_BAR;
;     PG8_STAGE(PG8_SB(1, 0), cB + kstep, voffB); PG8_STAGE(PG8_SA(1, 0), cA + kstep, voffA); PG8_STAGE(PG8_SB(1, 1), cB + hstepB + kstep, voffB);
;     PG8_WAIT_V(6); PG8_BAR;
.LBB0_1031:
	s_lshl_b32 s10, s97, 5
	s_and_b32 s15, s10, 0x60
	s_mov_b64 s[10:11], 0x80
	s_add_i32 m0, s25, 0x18000
	v_lshl_add_u64 v[6:7], v[6:7], 0, s[10:11]
	s_lshl_b32 s14, s5, 13
	s_lshl_b32 s16, s15, 7
	s_waitcnt vmcnt(2)
	s_barrier
	global_load_lds_dwordx4 v[6:7], off
	v_lshl_add_u64 v[4:5], v[4:5], 0, s[10:11]
	s_add_i32 m0, s25, 0x1a000
	s_add_i32 s41, s25, 0x8000
	s_add_i32 s42, s25, 0xa000
	global_load_lds_dwordx4 v[4:5], off
	v_lshl_add_u64 v[0:1], v[0:1], 0, s[10:11]
	s_mov_b32 m0, s41
	s_add_u32 s12, s28, 0x20080
	global_load_lds_dwordx4 v[0:1], off
	v_lshl_add_u64 v[0:1], v[2:3], 0, s[10:11]
	s_mov_b32 m0, s42
	s_addc_u32 s13, s29, 0
	global_load_lds_dwordx4 v[0:1], off
	s_add_i32 m0, s25, 0x1c000
	s_nop 0
	global_load_lds_dwordx4 v170, s[12:13]
	v_lshl_add_u64 v[0:1], s[12:13], 0, v[174:175]
	s_add_i32 m0, s25, 0x1e000
	s_cmpk_lt_u32 s80, 0x100
	global_load_lds_dwordx4 v[0:1], off
	v_lshrrev_b32_e32 v0, 1, v8
	v_and_b32_e32 v2, 24, v0
	s_sext_i32_i8 s47, s4
	v_and_b32_e32 v1, 15, v8
	v_lshlrev_b32_e32 v0, 1, v2
	v_lshlrev_b32_e32 v3, 2, v8
	s_cselect_b64 s[12:13], -1, 0
	s_lshl_b32 s4, s15, 1
	v_lshl_or_b32 v198, s5, 6, v1
	v_lshl_or_b32 v1, v1, 6, v0
	v_and_b32_e32 v3, 32, v3
	s_add_u32 s4, s92, s4
	v_bitop3_b32 v4, v1, s14, v3 bitop3:0xde
	v_bitop3_b32 v199, v1, s16, v3 bitop3:0xde
	s_addc_u32 s5, s93, 0
	v_mov_b32_e32 v1, v171
	v_lshl_add_u64 v[0:1], s[4:5], 0, v[0:1]
	s_mov_b64 s[4:5], 0x1a400000
	v_lshl_add_u64 v[176:177], v[0:1], 0, s[4:5]
	v_lshlrev_b32_e32 v0, 13, v9
	v_and_b32_e32 v0, 0xffffc000, v0
	v_lshl_add_u32 v0, v10, 10, v0
	v_and_b32_e32 v1, 1, v9
	v_lshl_or_b32 v0, v1, 6, v0
	v_lshl_add_u32 v178, v11, 1, v0
	v_lshlrev_b32_e32 v0, 13, v12
	v_and_b32_e32 v0, 0xffffc000, v0
	s_waitcnt vmcnt(6)
	s_add_u32 s14, s92, 0xf400000
	v_lshl_add_u32 v0, v13, 10, v0
	v_and_b32_e32 v1, 1, v12
	v_or_b32_e32 v200, s15, v2
	s_addc_u32 s15, s93, 0
	v_readlane_b32 s4, v255, 1
	v_lshl_or_b32 v0, v1, 6, v0
	s_add_i32 s45, 0, 0x10000
	s_add_i32 s46, 0, 0x14000
	s_ashr_i32 s43, s4, 31
	s_mov_b32 s44, s4
	v_mov_b32_e32 v179, v171
	v_lshl_add_u32 v180, v14, 1, v0
	v_mov_b32_e32 v181, v171
	v_mov_b64_e32 v[182:183], 0x200
	v_mov_b64_e32 v[184:185], 0x1ff
	v_add_u32_e32 v201, s45, v199
	v_add_u32_e32 v202, s46, v199
	v_add_u32_e32 v203, 0, v4
	s_barrier
	v_readlane_b32 s5, v255, 2
	s_branch .LBB0_1034

;     __device__ bool next(int i, Unit& u) const { if (r0 + i >= r1) return false; return base.next(r0 + i, u); }
;     __device__ bool next(int i, Unit& u) const { const int L = i * G + c; if (L >= 256) return false; u.pm = L; u.pn = L >> 3; return true; }
; #define PG8_STAGE(bufoff, gbase, voff) do { _Pragma("unroll") for (int _i = 0; _i < 2; ++_i) \
;         __builtin_amdgcn_global_load_lds((const unsigned*)((const char*)(gbase) + (voff)[_i]), (LAS unsigned*)(lds + (bufoff) + ldsw + _i * 8192), 16, 0, 0); } while (0)
; #define PG8_LDA(dst, b, h) do { _Pragma("unroll") for (int m = 0; m < 4; ++m) _Pragma("unroll") for (int k = 0; k < 2; ++k) dst[m][k] = *(const LAS bf16x8*)(lds + PG8_SA(b, h) + aoff + m * 2048 + k * 1024); } while (0)
; #define PG8_LDB(dst, b, h) do { _Pragma("unroll") for (int n = 0; n < 2; ++n) _Pragma("unroll") for (int k = 0; k < 2; ++k) dst[n][k] = *(const LAS bf16x8*)(lds + PG8_SB(b, h) + boff + n * 2048 + k * 1024); } while (0)
; #define PG8_WAIT_V(n) asm volatile("s_waitcnt vmcnt(" #n ")" ::: "memory")
; #define PG8_WAIT_L(n) asm volatile("s_waitcnt lgkmcnt(" #n ")" ::: "memory")
; template <class Epi, class Sched>
; __device__ __forceinline__ void gemm_phase(LAS unsigned char* lds, const Gemm g, const Sched& S, const Epi& E, int wave_id) {
;     ...
;         const bool has_next = S.next(ui + 1, nxt);
;         const char* nA = has_next ? (const char*)g.A + (size_t)nxt.pm * tstepA : cA; const char* nB = has_next ? (const char*)g.Bt + (size_t)nxt.pn * tstepB : cB;
;         for (int t = 0; t < nt; t += 2) {
;             const bool last = (t == nt - 2);
;             const char* a1 = cA + (size_t)(t + 1) * kstep;
;             const char* a2 = last ? nA : cA + (size_t)(t + 2) * kstep; const char* b2 = last ? nB : cB + (size_t)(t + 2) * kstep;
;             const char* a3 = a2 + kstep; const char* b3 = b2 + kstep;
;             PG8_LDB(B0, 0, 0); PG8_LDB(B1, 0, 1); PG8_SCHED; PG8_LDA(At, 0, 0); PG8_STAGE(PG8_SA(1, 1), a1 + hstepA, voffA);
;             PG8_WAIT_V(8); PG8_WAIT_L(0); PG8_BAR; PG8_MMA(0, 0, At, B0); PG8_MMA(0, 1, At, B1); PG8_BAR; PG8_SCHED;
;             PG8_LDA(At, 0, 1); PG8_STAGE(PG8_SB(0, 0), b2, voffB); PG8_STAGE(PG8_SB(0, 1), b2 + hstepB, voffB); PG8_STAGE(PG8_SA(0, 0), a2, voffA);
;             PG8_WAIT_V(8); PG8_WAIT_L(0); PG8_BAR; PG8_MMA(1, 0, At, B0); PG8_MMA(1, 1, At, B1); PG8_BAR; PG8_SCHED;
.LBB0_1040:
	s_ashr_i32 s19, s18, 31
	s_lshl_b64 s[20:21], s[18:19], 18
	s_add_u32 s20, s3, s20
	s_addc_u32 s21, s33, s21
	s_and_b64 s[22:23], s[4:5], exec
	s_cselect_b32 s19, s21, s27
	s_cselect_b32 s48, s20, s26
	s_ashr_i32 s17, s16, 31
	s_lshl_b64 s[22:23], s[16:17], 18
	s_add_u32 s22, s34, s22
	s_addc_u32 s23, s35, s23
	s_and_b64 s[30:31], s[4:5], exec
	s_cselect_b32 s17, s23, s29
	s_cselect_b32 s49, s22, s28
	s_add_u32 s26, s26, 0x20080
	s_addc_u32 s27, s27, 0
	s_add_u32 s50, s28, 0x100
	s_addc_u32 s51, s29, 0
	s_mov_b32 s52, -2
	s_waitcnt vmcnt(0)
	ds_read_b128 v[116:119], v201
	ds_read_b128 v[120:123], v201 offset:1024
	ds_read_b128 v[124:127], v201 offset:2048
	ds_read_b128 v[136:139], v201 offset:3072
	ds_read_b128 v[140:143], v202
	ds_read_b128 v[148:151], v202 offset:1024
	ds_read_b128 v[152:155], v202 offset:2048
	ds_read_b128 v[156:159], v202 offset:3072
	s_add_u32 s28, s26, 0xfffe0080
	s_addc_u32 s29, s27, -1
	s_cmp_eq_u32 s52, 4
	s_cselect_b32 s31, s19, s29
	s_cselect_b32 s30, s48, s28
	s_cselect_b32 s29, s17, s51
	s_cselect_b32 s28, s49, s50
	s_add_i32 m0, s25, 0xc000
	ds_read_b128 v[160:163], v203
	ds_read_b128 v[164:167], v203 offset:1024
	ds_read_b128 v[186:189], v203 offset:2048
	ds_read_b128 v[190:193], v203 offset:3072
	ds_read_b128 v[194:197], v203 offset:4096
	ds_read_b128 v[204:207], v203 offset:5120
	ds_read_b128 v[208:211], v203 offset:6144
	ds_read_b128 v[212:215], v203 offset:7168
	global_load_lds_dwordx4 v178, s[26:27]
	s_add_i32 m0, s25, 0xe000
	s_nop 0
	global_load_lds_dwordx4 v180, s[26:27]
	s_waitcnt vmcnt(8)
	s_waitcnt lgkmcnt(0)
	s_barrier
	s_setprio 1
	s_waitcnt lgkmcnt(0)
	v_mfma_f32_16x16x32_bf16 v[144:147], v[116:119], v[160:163], 0
	v_mfma_f32_16x16x32_bf16 v[128:131], v[124:127], v[160:163], 0
	v_mfma_f32_16x16x32_bf16 v[108:111], v[116:119], v[186:189], 0
	v_mfma_f32_16x16x32_bf16 v[100:103], v[124:127], v[186:189], 0
	v_mfma_f32_16x16x32_bf16 v[92:95], v[116:119], v[194:197], 0
	v_mfma_f32_16x16x32_bf16 v[84:87], v[124:127], v[194:197], 0
	v_mfma_f32_16x16x32_bf16 v[76:79], v[116:119], v[208:211], 0
	v_mfma_f32_16x16x32_bf16 v[68:71], v[124:127], v[208:211], 0
	v_mfma_f32_16x16x32_bf16 v[144:147], v[120:123], v[164:167], v[144:147]
	v_mfma_f32_16x16x32_bf16 v[128:131], v[136:139], v[164:167], v[128:131]
	v_mfma_f32_16x16x32_bf16 v[108:111], v[120:123], v[190:193], v[108:111]
	v_mfma_f32_16x16x32_bf16 v[100:103], v[136:139], v[190:193], v[100:103]
	v_mfma_f32_16x16x32_bf16 v[92:95], v[120:123], v[204:207], v[92:95]
	v_mfma_f32_16x16x32_bf16 v[84:87], v[136:139], v[204:207], v[84:87]
	v_mfma_f32_16x16x32_bf16 v[76:79], v[120:123], v[212:215], v[76:79]
	v_mfma_f32_16x16x32_bf16 v[68:71], v[136:139], v[212:215], v[68:71]
	s_setprio 0
	s_setprio 1
	v_mfma_f32_16x16x32_bf16 v[132:135], v[140:143], v[160:163], 0
	v_mfma_f32_16x16x32_bf16 v[112:115], v[152:155], v[160:163], 0
	v_mfma_f32_16x16x32_bf16 v[104:107], v[140:143], v[186:189], 0
	v_mfma_f32_16x16x32_bf16 v[96:99], v[152:155], v[186:189], 0
	v_mfma_f32_16x16x32_bf16 v[88:91], v[140:143], v[194:197], 0
	v_mfma_f32_16x16x32_bf16 v[80:83], v[152:155], v[194:197], 0
	v_mfma_f32_16x16x32_bf16 v[72:75], v[140:143], v[208:211], 0
	v_mfma_f32_16x16x32_bf16 v[64:67], v[152:155], v[208:211], 0
	v_mfma_f32_16x16x32_bf16 v[132:135], v[148:151], v[164:167], v[132:135]
	v_mfma_f32_16x16x32_bf16 v[112:115], v[156:159], v[164:167], v[112:115]
	v_mfma_f32_16x16x32_bf16 v[104:107], v[148:151], v[190:193], v[104:107]
	v_mfma_f32_16x16x32_bf16 v[96:99], v[156:159], v[190:193], v[96:99]
	v_mfma_f32_16x16x32_bf16 v[88:91], v[148:151], v[204:207], v[88:91]
	v_mfma_f32_16x16x32_bf16 v[80:83], v[156:159], v[204:207], v[80:83]
	v_mfma_f32_16x16x32_bf16 v[72:75], v[148:151], v[212:215], v[72:75]
	v_mfma_f32_16x16x32_bf16 v[64:67], v[156:159], v[212:215], v[64:67]
	s_setprio 0
	s_barrier
	s_add_i32 s53, s45, s36
	v_lshl_add_u64 v[216:217], s[28:29], 0, v[170:171]
	s_mov_b32 m0, s53
	ds_read_b128 v[160:163], v203 offset:16384
	ds_read_b128 v[164:167], v203 offset:17408
	ds_read_b128 v[186:189], v203 offset:18432
	ds_read_b128 v[190:193], v203 offset:19456
	ds_read_b128 v[194:197], v203 offset:20480
	ds_read_b128 v[204:207], v203 offset:21504
	ds_read_b128 v[208:211], v203 offset:22528
	ds_read_b128 v[212:215], v203 offset:23552
	global_load_lds_dwordx4 v[216:217], off
	s_add_i32 m0, s53, 0x2000
	s_add_u32 s54, s28, 0x20000
	v_lshl_add_u64 v[218:219], s[28:29], 0, v[174:175]
	s_addc_u32 s55, s29, 0
	s_add_i32 s53, s46, s36
	global_load_lds_dwordx4 v[218:219], off
	s_mov_b32 m0, s53
	v_lshl_add_u64 v[222:223], s[30:31], 0, v[172:173]
	global_load_lds_dwordx4 v170, s[54:55]
	s_add_i32 m0, s53, 0x2000
	s_nop 0
	global_load_lds_dwordx4 v174, s[54:55]
	v_lshl_add_u64 v[220:221], s[30:31], 0, v[168:169]
	s_mov_b32 m0, s25
	s_nop 0
	global_load_lds_dwordx4 v[220:221], off
	s_mov_b32 m0, s37
	s_nop 0
	global_load_lds_dwordx4 v[222:223], off
	s_waitcnt vmcnt(8)
	s_waitcnt lgkmcnt(0)
	s_barrier
; #define PG8_STAGE(bufoff, gbase, voff) do { _Pragma("unroll") for (int _i = 0; _i < 2; ++_i) \
;         __builtin_amdgcn_global_load_lds((const unsigned*)((const char*)(gbase) + (voff)[_i]), (LAS unsigned*)(lds + (bufoff) + ldsw + _i * 8192), 16, 0, 0); } while (0)
; #define PG8_LDA(dst, b, h) do { _Pragma("unroll") for (int m = 0; m < 4; ++m) _Pragma("unroll") for (int k = 0; k < 2; ++k) dst[m][k] = *(const LAS bf16x8*)(lds + PG8_SA(b, h) + aoff + m * 2048 + k * 1024); } while (0)
; #define PG8_LDB(dst, b, h) do { _Pragma("unroll") for (int n = 0; n < 2; ++n) _Pragma("unroll") for (int k = 0; k < 2; ++k) dst[n][k] = *(const LAS bf16x8*)(lds + PG8_SB(b, h) + boff + n * 2048 + k * 1024); } while (0)
; #define PG8_MMA(ai, bj, At, Bt) do { __builtin_amdgcn_s_setprio(1); _Pragma("unroll") for (int m = 0; m < 4; ++m) _Pragma("unroll") for (int n = 0; n < 2; ++n) _Pragma("unroll") for (int k = 0; k < 2; ++k) \
;         acc[ai][bj][m][n] = __builtin_amdgcn_mfma_f32_16x16x32_bf16(Bt[n][k], At[m][k], acc[ai][bj][m][n], 0, 0, 0); __builtin_amdgcn_s_setprio(0); } while (0)
; #define PG8_WAIT_V(n) asm volatile("s_waitcnt vmcnt(" #n ")" ::: "memory")
; #define PG8_WAIT_L(n) asm volatile("s_waitcnt lgkmcnt(" #n ")" ::: "memory")
; #define PG8_BAR __builtin_amdgcn_s_barrier()
; #define PG8_SCHED __builtin_amdgcn_sched_barrier(0)
; template <class Epi, class Sched>
; __device__ __forceinline__ void gemm_phase(LAS unsigned char* lds, const Gemm g, const Sched& S, const Epi& E, int wave_id) {
;     ...
;             PG8_WAIT_V(8); PG8_WAIT_L(0); PG8_BAR; PG8_MMA(1, 0, At, B0); PG8_MMA(1, 1, At, B1); PG8_BAR; PG8_SCHED;
;             PG8_LDB(B0, 1, 0); PG8_LDB(B1, 1, 1); PG8_SCHED; PG8_LDA(At, 1, 0); PG8_STAGE(PG8_SA(0, 1), a2 + hstepA, voffA);
;             PG8_WAIT_V(8); PG8_WAIT_L(0); PG8_BAR; PG8_MMA(0, 0, At, B0); PG8_MMA(0, 1, At, B1); PG8_BAR; PG8_SCHED;
	s_setprio 1
	s_waitcnt lgkmcnt(0)
	v_mfma_f32_16x16x32_bf16 v[60:63], v[116:119], v[160:163], 0
	v_mfma_f32_16x16x32_bf16 v[52:55], v[124:127], v[160:163], 0
	v_mfma_f32_16x16x32_bf16 v[44:47], v[116:119], v[186:189], 0
	v_mfma_f32_16x16x32_bf16 v[36:39], v[124:127], v[186:189], 0
	v_mfma_f32_16x16x32_bf16 v[28:31], v[116:119], v[194:197], 0
	v_mfma_f32_16x16x32_bf16 v[20:23], v[124:127], v[194:197], 0
	v_mfma_f32_16x16x32_bf16 v[12:15], v[116:119], v[208:211], 0
	v_mfma_f32_16x16x32_bf16 v[4:7], v[124:127], v[208:211], 0
	v_mfma_f32_16x16x32_bf16 v[60:63], v[120:123], v[164:167], v[60:63]
	v_mfma_f32_16x16x32_bf16 v[52:55], v[136:139], v[164:167], v[52:55]
	v_mfma_f32_16x16x32_bf16 v[44:47], v[120:123], v[190:193], v[44:47]
	v_mfma_f32_16x16x32_bf16 v[36:39], v[136:139], v[190:193], v[36:39]
	v_mfma_f32_16x16x32_bf16 v[28:31], v[120:123], v[204:207], v[28:31]
	v_mfma_f32_16x16x32_bf16 v[20:23], v[136:139], v[204:207], v[20:23]
	v_mfma_f32_16x16x32_bf16 v[12:15], v[120:123], v[212:215], v[12:15]
	v_mfma_f32_16x16x32_bf16 v[4:7], v[136:139], v[212:215], v[4:7]
	s_setprio 0
	s_setprio 1
	v_mfma_f32_16x16x32_bf16 v[56:59], v[140:143], v[160:163], 0
	v_mfma_f32_16x16x32_bf16 v[48:51], v[152:155], v[160:163], 0
	v_mfma_f32_16x16x32_bf16 v[40:43], v[140:143], v[186:189], 0
	v_mfma_f32_16x16x32_bf16 v[32:35], v[152:155], v[186:189], 0
	v_mfma_f32_16x16x32_bf16 v[24:27], v[140:143], v[194:197], 0
	v_mfma_f32_16x16x32_bf16 v[16:19], v[152:155], v[194:197], 0
	v_mfma_f32_16x16x32_bf16 v[8:11], v[140:143], v[208:211], 0
	v_mfma_f32_16x16x32_bf16 v[0:3], v[152:155], v[208:211], 0
	v_mfma_f32_16x16x32_bf16 v[56:59], v[148:151], v[164:167], v[56:59]
	v_mfma_f32_16x16x32_bf16 v[48:51], v[156:159], v[164:167], v[48:51]
	v_mfma_f32_16x16x32_bf16 v[40:43], v[148:151], v[190:193], v[40:43]
	v_mfma_f32_16x16x32_bf16 v[32:35], v[156:159], v[190:193], v[32:35]
	v_mfma_f32_16x16x32_bf16 v[24:27], v[148:151], v[204:207], v[24:27]
	v_mfma_f32_16x16x32_bf16 v[16:19], v[156:159], v[204:207], v[16:19]
	v_mfma_f32_16x16x32_bf16 v[8:11], v[148:151], v[212:215], v[8:11]
	v_mfma_f32_16x16x32_bf16 v[0:3], v[156:159], v[212:215], v[0:3]
	s_setprio 0
	s_barrier
	s_add_i32 s53, 0, 0x18000
	s_add_i32 s54, 0, 0x1c000
	v_add_u32_e32 v136, s53, v199
	v_add_u32_e32 v156, s54, v199
	ds_read_b128 v[116:119], v136
	ds_read_b128 v[120:123], v136 offset:1024
	ds_read_b128 v[124:127], v136 offset:2048
	ds_read_b128 v[136:139], v136 offset:3072
	ds_read_b128 v[140:143], v156
	ds_read_b128 v[148:151], v156 offset:1024
	ds_read_b128 v[152:155], v156 offset:2048
	ds_read_b128 v[156:159], v156 offset:3072
	s_add_u32 s30, s30, 0x20000
	s_addc_u32 s31, s31, 0
	s_mov_b32 m0, s38
	ds_read_b128 v[160:163], v203 offset:32768
	ds_read_b128 v[164:167], v203 offset:33792
	ds_read_b128 v[186:189], v203 offset:34816
	ds_read_b128 v[190:193], v203 offset:35840
	ds_read_b128 v[194:197], v203 offset:36864
	ds_read_b128 v[204:207], v203 offset:37888
	ds_read_b128 v[208:211], v203 offset:38912
	ds_read_b128 v[212:215], v203 offset:39936
	global_load_lds_dwordx4 v168, s[30:31]
	s_mov_b32 m0, s39
	s_nop 0
	global_load_lds_dwordx4 v172, s[30:31]
	s_waitcnt vmcnt(8)
	s_waitcnt lgkmcnt(0)
	s_barrier
	s_setprio 1
	s_waitcnt lgkmcnt(0)
	v_mfma_f32_16x16x32_bf16 v[144:147], v[116:119], v[160:163], v[144:147]
	v_mfma_f32_16x16x32_bf16 v[128:131], v[124:127], v[160:163], v[128:131]
	v_mfma_f32_16x16x32_bf16 v[108:111], v[116:119], v[186:189], v[108:111]
	v_mfma_f32_16x16x32_bf16 v[100:103], v[124:127], v[186:189], v[100:103]
	v_mfma_f32_16x16x32_bf16 v[92:95], v[116:119], v[194:197], v[92:95]
	v_mfma_f32_16x16x32_bf16 v[84:87], v[124:127], v[194:197], v[84:87]
	v_mfma_f32_16x16x32_bf16 v[76:79], v[116:119], v[208:211], v[76:79]
	v_mfma_f32_16x16x32_bf16 v[68:71], v[124:127], v[208:211], v[68:71]
	v_mfma_f32_16x16x32_bf16 v[144:147], v[120:123], v[164:167], v[144:147]
	v_mfma_f32_16x16x32_bf16 v[128:131], v[136:139], v[164:167], v[128:131]
	v_mfma_f32_16x16x32_bf16 v[108:111], v[120:123], v[190:193], v[108:111]
	v_mfma_f32_16x16x32_bf16 v[100:103], v[136:139], v[190:193], v[100:103]
	v_mfma_f32_16x16x32_bf16 v[92:95], v[120:123], v[204:207], v[92:95]
	v_mfma_f32_16x16x32_bf16 v[84:87], v[136:139], v[204:207], v[84:87]
	v_mfma_f32_16x16x32_bf16 v[76:79], v[120:123], v[212:215], v[76:79]
	v_mfma_f32_16x16x32_bf16 v[68:71], v[136:139], v[212:215], v[68:71]
	s_setprio 0
	s_setprio 1
	v_mfma_f32_16x16x32_bf16 v[132:135], v[140:143], v[160:163], v[132:135]
	v_mfma_f32_16x16x32_bf16 v[112:115], v[152:155], v[160:163], v[112:115]
	v_mfma_f32_16x16x32_bf16 v[104:107], v[140:143], v[186:189], v[104:107]
	v_mfma_f32_16x16x32_bf16 v[96:99], v[152:155], v[186:189], v[96:99]
	v_mfma_f32_16x16x32_bf16 v[88:91], v[140:143], v[194:197], v[88:91]
	v_mfma_f32_16x16x32_bf16 v[80:83], v[152:155], v[194:197], v[80:83]
	v_mfma_f32_16x16x32_bf16 v[72:75], v[140:143], v[208:211], v[72:75]
	v_mfma_f32_16x16x32_bf16 v[64:67], v[152:155], v[208:211], v[64:67]
	v_mfma_f32_16x16x32_bf16 v[132:135], v[148:151], v[164:167], v[132:135]
	v_mfma_f32_16x16x32_bf16 v[112:115], v[156:159], v[164:167], v[112:115]
	v_mfma_f32_16x16x32_bf16 v[104:107], v[148:151], v[190:193], v[104:107]
	v_mfma_f32_16x16x32_bf16 v[96:99], v[156:159], v[190:193], v[96:99]
	v_mfma_f32_16x16x32_bf16 v[88:91], v[148:151], v[204:207], v[88:91]
	v_mfma_f32_16x16x32_bf16 v[80:83], v[156:159], v[204:207], v[80:83]
	v_mfma_f32_16x16x32_bf16 v[72:75], v[148:151], v[212:215], v[72:75]
	v_mfma_f32_16x16x32_bf16 v[64:67], v[156:159], v[212:215], v[64:67]
	s_setprio 0
	s_barrier
; #define PG8_STAGE(bufoff, gbase, voff) do { _Pragma("unroll") for (int _i = 0; _i < 2; ++_i) \
;         __builtin_amdgcn_global_load_lds((const unsigned*)((const char*)(gbase) + (voff)[_i]), (LAS unsigned*)(lds + (bufoff) + ldsw + _i * 8192), 16, 0, 0); } while (0)
; #define PG8_LDA(dst, b, h) do { _Pragma("unroll") for (int m = 0; m < 4; ++m) _Pragma("unroll") for (int k = 0; k < 2; ++k) dst[m][k] = *(const LAS bf16x8*)(lds + PG8_SA(b, h) + aoff + m * 2048 + k * 1024); } while (0)
; #define PG8_LDB(dst, b, h) do { _Pragma("unroll") for (int n = 0; n < 2; ++n) _Pragma("unroll") for (int k = 0; k < 2; ++k) dst[n][k] = *(const LAS bf16x8*)(lds + PG8_SB(b, h) + boff + n * 2048 + k * 1024); } while (0)
; #define PG8_MMA(ai, bj, At, Bt) do { __builtin_amdgcn_s_setprio(1); _Pragma("unroll") for (int m = 0; m < 4; ++m) _Pragma("unroll") for (int n = 0; n < 2; ++n) _Pragma("unroll") for (int k = 0; k < 2; ++k) \
;         acc[ai][bj][m][n] = __builtin_amdgcn_mfma_f32_16x16x32_bf16(Bt[n][k], At[m][k], acc[ai][bj][m][n], 0, 0, 0); __builtin_amdgcn_s_setprio(0); } while (0)
; #define PG8_WAIT_V(n) asm volatile("s_waitcnt vmcnt(" #n ")" ::: "memory")
; #define PG8_WAIT_L(n) asm volatile("s_waitcnt lgkmcnt(" #n ")" ::: "memory")
; template <class Epi, class Sched>
; __device__ __forceinline__ void gemm_phase(LAS unsigned char* lds, const Gemm g, const Sched& S, const Epi& E, int wave_id) {
;     ...
;         for (int t = 0; t < nt; t += 2) {
;             const bool last = (t == nt - 2);
;             const char* a1 = cA + (size_t)(t + 1) * kstep;
;             const char* a2 = last ? nA : cA + (size_t)(t + 2) * kstep; const char* b2 = last ? nB : cB + (size_t)(t + 2) * kstep;
;             const char* a3 = a2 + kstep; const char* b3 = b2 + kstep;
;             PG8_LDB(B0, 0, 0); PG8_LDB(B1, 0, 1); PG8_SCHED; PG8_LDA(At, 0, 0); PG8_STAGE(PG8_SA(1, 1), a1 + hstepA, voffA);
;             PG8_WAIT_V(8); PG8_WAIT_L(0); PG8_BAR; PG8_MMA(0, 0, At, B0); PG8_MMA(0, 1, At, B1); PG8_BAR; PG8_SCHED;
;     ...
;             PG8_WAIT_V(8); PG8_WAIT_L(0); PG8_BAR; PG8_MMA(0, 0, At, B0); PG8_MMA(0, 1, At, B1); PG8_BAR; PG8_SCHED;
;             PG8_LDA(At, 1, 1); PG8_STAGE(PG8_SB(1, 0), b3, voffB); PG8_STAGE(PG8_SB(1, 1), b3 + hstepB, voffB); PG8_STAGE(PG8_SA(1, 0), a3, voffA);
;             PG8_WAIT_V(8); PG8_WAIT_L(0); PG8_BAR; PG8_MMA(1, 0, At, B0); PG8_MMA(1, 1, At, B1); PG8_BAR; PG8_SCHED;
	s_add_i32 s30, s53, s36
	v_lshl_add_u64 v[216:217], v[216:217], 0, s[10:11]
	s_mov_b32 m0, s30
	ds_read_b128 v[160:163], v203 offset:49152
	ds_read_b128 v[164:167], v203 offset:50176
	ds_read_b128 v[186:189], v203 offset:51200
	ds_read_b128 v[190:193], v203 offset:52224
	ds_read_b128 v[194:197], v203 offset:53248
	ds_read_b128 v[204:207], v203 offset:54272
	ds_read_b128 v[208:211], v203 offset:55296
	ds_read_b128 v[212:215], v203 offset:56320
	global_load_lds_dwordx4 v[216:217], off
	s_add_i32 m0, s30, 0x2000
	s_add_u32 s28, s28, 0x20080
	v_lshl_add_u64 v[216:217], v[218:219], 0, s[10:11]
	s_addc_u32 s29, s29, 0
	s_add_i32 s30, s54, s36
	global_load_lds_dwordx4 v[216:217], off
	s_mov_b32 m0, s30
	s_nop 0
	global_load_lds_dwordx4 v170, s[28:29]
	s_add_i32 m0, s30, 0x2000
	s_nop 0
	global_load_lds_dwordx4 v174, s[28:29]
	v_lshl_add_u64 v[216:217], v[220:221], 0, s[10:11]
	s_mov_b32 m0, s41
	s_nop 0
	global_load_lds_dwordx4 v[216:217], off
	v_lshl_add_u64 v[216:217], v[222:223], 0, s[10:11]
	s_mov_b32 m0, s42
	s_nop 0
	global_load_lds_dwordx4 v[216:217], off
	s_waitcnt vmcnt(8)
	s_waitcnt lgkmcnt(0)
	s_barrier
	s_setprio 1
	s_waitcnt lgkmcnt(0)
	v_mfma_f32_16x16x32_bf16 v[60:63], v[116:119], v[160:163], v[60:63]
	v_mfma_f32_16x16x32_bf16 v[52:55], v[124:127], v[160:163], v[52:55]
	v_mfma_f32_16x16x32_bf16 v[44:47], v[116:119], v[186:189], v[44:47]
	v_mfma_f32_16x16x32_bf16 v[36:39], v[124:127], v[186:189], v[36:39]
	v_mfma_f32_16x16x32_bf16 v[28:31], v[116:119], v[194:197], v[28:31]
	v_mfma_f32_16x16x32_bf16 v[20:23], v[124:127], v[194:197], v[20:23]
	v_mfma_f32_16x16x32_bf16 v[12:15], v[116:119], v[208:211], v[12:15]
	v_mfma_f32_16x16x32_bf16 v[4:7], v[124:127], v[208:211], v[4:7]
	v_mfma_f32_16x16x32_bf16 v[60:63], v[120:123], v[164:167], v[60:63]
	v_mfma_f32_16x16x32_bf16 v[52:55], v[136:139], v[164:167], v[52:55]
	v_mfma_f32_16x16x32_bf16 v[44:47], v[120:123], v[190:193], v[44:47]
	v_mfma_f32_16x16x32_bf16 v[36:39], v[136:139], v[190:193], v[36:39]
	v_mfma_f32_16x16x32_bf16 v[28:31], v[120:123], v[204:207], v[28:31]
	v_mfma_f32_16x16x32_bf16 v[20:23], v[136:139], v[204:207], v[20:23]
	v_mfma_f32_16x16x32_bf16 v[12:15], v[120:123], v[212:215], v[12:15]
	v_mfma_f32_16x16x32_bf16 v[4:7], v[136:139], v[212:215], v[4:7]
	s_setprio 0
	s_setprio 1
	v_mfma_f32_16x16x32_bf16 v[56:59], v[140:143], v[160:163], v[56:59]
	v_mfma_f32_16x16x32_bf16 v[48:51], v[152:155], v[160:163], v[48:51]
	v_mfma_f32_16x16x32_bf16 v[40:43], v[140:143], v[186:189], v[40:43]
	v_mfma_f32_16x16x32_bf16 v[32:35], v[152:155], v[186:189], v[32:35]
	v_mfma_f32_16x16x32_bf16 v[24:27], v[140:143], v[194:197], v[24:27]
	v_mfma_f32_16x16x32_bf16 v[16:19], v[152:155], v[194:197], v[16:19]
	v_mfma_f32_16x16x32_bf16 v[8:11], v[140:143], v[208:211], v[8:11]
	v_mfma_f32_16x16x32_bf16 v[0:3], v[152:155], v[208:211], v[0:3]
	v_mfma_f32_16x16x32_bf16 v[56:59], v[148:151], v[164:167], v[56:59]
	v_mfma_f32_16x16x32_bf16 v[48:51], v[156:159], v[164:167], v[48:51]
	v_mfma_f32_16x16x32_bf16 v[40:43], v[148:151], v[190:193], v[40:43]
	v_mfma_f32_16x16x32_bf16 v[32:35], v[156:159], v[190:193], v[32:35]
	v_mfma_f32_16x16x32_bf16 v[24:27], v[148:151], v[204:207], v[24:27]
	v_mfma_f32_16x16x32_bf16 v[16:19], v[156:159], v[204:207], v[16:19]
	v_mfma_f32_16x16x32_bf16 v[8:11], v[148:151], v[212:215], v[8:11]
	v_mfma_f32_16x16x32_bf16 v[0:3], v[156:159], v[212:215], v[0:3]
	s_setprio 0
	s_barrier
	s_add_i32 s52, s52, 2
	s_add_u32 s26, s26, 0x100
	s_addc_u32 s27, s27, 0
	s_add_u32 s50, s50, 0x100
	s_addc_u32 s51, s51, 0
	s_cmp_gt_u32 s52, 5
.LBB0_1041:
	ds_read_b128 v[116:119], v201
	ds_read_b128 v[120:123], v201 offset:1024
	ds_read_b128 v[124:127], v201 offset:2048
	ds_read_b128 v[136:139], v201 offset:3072
	ds_read_b128 v[140:143], v202
	ds_read_b128 v[148:151], v202 offset:1024
	ds_read_b128 v[152:155], v202 offset:2048
	ds_read_b128 v[156:159], v202 offset:3072
	s_add_u32 s28, s26, 0xfffe0080
	s_addc_u32 s29, s27, -1
	s_cmp_eq_u32 s52, 4
	s_cselect_b32 s31, s19, s29
	s_cselect_b32 s30, s48, s28
	s_cselect_b32 s29, s17, s51
	s_cselect_b32 s28, s49, s50
	s_add_i32 m0, s25, 0xc000
	ds_read_b128 v[160:163], v203
	ds_read_b128 v[164:167], v203 offset:1024
	ds_read_b128 v[186:189], v203 offset:2048
	ds_read_b128 v[190:193], v203 offset:3072
	ds_read_b128 v[194:197], v203 offset:4096
	ds_read_b128 v[204:207], v203 offset:5120
	ds_read_b128 v[208:211], v203 offset:6144
	ds_read_b128 v[212:215], v203 offset:7168
	global_load_lds_dwordx4 v178, s[26:27]
	s_add_i32 m0, s25, 0xe000
	s_nop 0
	global_load_lds_dwordx4 v180, s[26:27]
	s_waitcnt vmcnt(8)
	s_waitcnt lgkmcnt(0)
	s_barrier
; #define PG8_STAGE(bufoff, gbase, voff) do { _Pragma("unroll") for (int _i = 0; _i < 2; ++_i) \
;         __builtin_amdgcn_global_load_lds((const unsigned*)((const char*)(gbase) + (voff)[_i]), (LAS unsigned*)(lds + (bufoff) + ldsw + _i * 8192), 16, 0, 0); } while (0)
; #define PG8_LDA(dst, b, h) do { _Pragma("unroll") for (int m = 0; m < 4; ++m) _Pragma("unroll") for (int k = 0; k < 2; ++k) dst[m][k] = *(const LAS bf16x8*)(lds + PG8_SA(b, h) + aoff + m * 2048 + k * 1024); } while (0)
; #define PG8_LDB(dst, b, h) do { _Pragma("unroll") for (int n = 0; n < 2; ++n) _Pragma("unroll") for (int k = 0; k < 2; ++k) dst[n][k] = *(const LAS bf16x8*)(lds + PG8_SB(b, h) + boff + n * 2048 + k * 1024); } while (0)
; #define PG8_MMA(ai, bj, At, Bt) do { __builtin_amdgcn_s_setprio(1); _Pragma("unroll") for (int m = 0; m < 4; ++m) _Pragma("unroll") for (int n = 0; n < 2; ++n) _Pragma("unroll") for (int k = 0; k < 2; ++k) \
;         acc[ai][bj][m][n] = __builtin_amdgcn_mfma_f32_16x16x32_bf16(Bt[n][k], At[m][k], acc[ai][bj][m][n], 0, 0, 0); __builtin_amdgcn_s_setprio(0); } while (0)
; #define PG8_WAIT_V(n) asm volatile("s_waitcnt vmcnt(" #n ")" ::: "memory")
; #define PG8_WAIT_L(n) asm volatile("s_waitcnt lgkmcnt(" #n ")" ::: "memory")
; #define PG8_BAR __builtin_amdgcn_s_barrier()
; #define PG8_SCHED __builtin_amdgcn_sched_barrier(0)
; template <class Epi, class Sched>
; __device__ __forceinline__ void gemm_phase(LAS unsigned char* lds, const Gemm g, const Sched& S, const Epi& E, int wave_id) {
;     ...
;             PG8_WAIT_V(8); PG8_WAIT_L(0); PG8_BAR; PG8_MMA(0, 0, At, B0); PG8_MMA(0, 1, At, B1); PG8_BAR; PG8_SCHED;
;             PG8_LDA(At, 0, 1); PG8_STAGE(PG8_SB(0, 0), b2, voffB); PG8_STAGE(PG8_SB(0, 1), b2 + hstepB, voffB); PG8_STAGE(PG8_SA(0, 0), a2, voffA);
;             PG8_WAIT_V(8); PG8_WAIT_L(0); PG8_BAR; PG8_MMA(1, 0, At, B0); PG8_MMA(1, 1, At, B1); PG8_BAR; PG8_SCHED;
;             PG8_LDB(B0, 1, 0); PG8_LDB(B1, 1, 1); PG8_SCHED; PG8_LDA(At, 1, 0); PG8_STAGE(PG8_SA(0, 1), a2 + hstepA, voffA);
;             PG8_WAIT_V(8); PG8_WAIT_L(0); PG8_BAR; PG8_MMA(0, 0, At, B0); PG8_MMA(0, 1, At, B1); PG8_BAR; PG8_SCHED;
	s_setprio 1
	s_waitcnt lgkmcnt(0)
	v_mfma_f32_16x16x32_bf16 v[144:147], v[116:119], v[160:163], v[144:147]
	v_mfma_f32_16x16x32_bf16 v[128:131], v[124:127], v[160:163], v[128:131]
	v_mfma_f32_16x16x32_bf16 v[108:111], v[116:119], v[186:189], v[108:111]
	v_mfma_f32_16x16x32_bf16 v[100:103], v[124:127], v[186:189], v[100:103]
	v_mfma_f32_16x16x32_bf16 v[92:95], v[116:119], v[194:197], v[92:95]
	v_mfma_f32_16x16x32_bf16 v[84:87], v[124:127], v[194:197], v[84:87]
	v_mfma_f32_16x16x32_bf16 v[76:79], v[116:119], v[208:211], v[76:79]
	v_mfma_f32_16x16x32_bf16 v[68:71], v[124:127], v[208:211], v[68:71]
	v_mfma_f32_16x16x32_bf16 v[144:147], v[120:123], v[164:167], v[144:147]
	v_mfma_f32_16x16x32_bf16 v[128:131], v[136:139], v[164:167], v[128:131]
	v_mfma_f32_16x16x32_bf16 v[108:111], v[120:123], v[190:193], v[108:111]
	v_mfma_f32_16x16x32_bf16 v[100:103], v[136:139], v[190:193], v[100:103]
	v_mfma_f32_16x16x32_bf16 v[92:95], v[120:123], v[204:207], v[92:95]
	v_mfma_f32_16x16x32_bf16 v[84:87], v[136:139], v[204:207], v[84:87]
	v_mfma_f32_16x16x32_bf16 v[76:79], v[120:123], v[212:215], v[76:79]
	v_mfma_f32_16x16x32_bf16 v[68:71], v[136:139], v[212:215], v[68:71]
	s_setprio 0
	s_setprio 1
	v_mfma_f32_16x16x32_bf16 v[132:135], v[140:143], v[160:163], v[132:135]
	v_mfma_f32_16x16x32_bf16 v[112:115], v[152:155], v[160:163], v[112:115]
	v_mfma_f32_16x16x32_bf16 v[104:107], v[140:143], v[186:189], v[104:107]
	v_mfma_f32_16x16x32_bf16 v[96:99], v[152:155], v[186:189], v[96:99]
	v_mfma_f32_16x16x32_bf16 v[88:91], v[140:143], v[194:197], v[88:91]
	v_mfma_f32_16x16x32_bf16 v[80:83], v[152:155], v[194:197], v[80:83]
	v_mfma_f32_16x16x32_bf16 v[72:75], v[140:143], v[208:211], v[72:75]
	v_mfma_f32_16x16x32_bf16 v[64:67], v[152:155], v[208:211], v[64:67]
	v_mfma_f32_16x16x32_bf16 v[132:135], v[148:151], v[164:167], v[132:135]
	v_mfma_f32_16x16x32_bf16 v[112:115], v[156:159], v[164:167], v[112:115]
	v_mfma_f32_16x16x32_bf16 v[104:107], v[148:151], v[190:193], v[104:107]
	v_mfma_f32_16x16x32_bf16 v[96:99], v[156:159], v[190:193], v[96:99]
	v_mfma_f32_16x16x32_bf16 v[88:91], v[148:151], v[204:207], v[88:91]
	v_mfma_f32_16x16x32_bf16 v[80:83], v[156:159], v[204:207], v[80:83]
	v_mfma_f32_16x16x32_bf16 v[72:75], v[148:151], v[212:215], v[72:75]
	v_mfma_f32_16x16x32_bf16 v[64:67], v[156:159], v[212:215], v[64:67]
	s_setprio 0
	s_barrier
	s_add_i32 s53, s45, s36
	v_lshl_add_u64 v[216:217], s[28:29], 0, v[170:171]
	s_mov_b32 m0, s53
	ds_read_b128 v[160:163], v203 offset:16384
	ds_read_b128 v[164:167], v203 offset:17408
	ds_read_b128 v[186:189], v203 offset:18432
	ds_read_b128 v[190:193], v203 offset:19456
	ds_read_b128 v[194:197], v203 offset:20480
	ds_read_b128 v[204:207], v203 offset:21504
	ds_read_b128 v[208:211], v203 offset:22528
	ds_read_b128 v[212:215], v203 offset:23552
	global_load_lds_dwordx4 v[216:217], off
	s_add_i32 m0, s53, 0x2000
	s_add_u32 s54, s28, 0x20000
	v_lshl_add_u64 v[218:219], s[28:29], 0, v[174:175]
	s_addc_u32 s55, s29, 0
	s_add_i32 s53, s46, s36
	global_load_lds_dwordx4 v[218:219], off
	s_mov_b32 m0, s53
	v_lshl_add_u64 v[222:223], s[30:31], 0, v[172:173]
	global_load_lds_dwordx4 v170, s[54:55]
	s_add_i32 m0, s53, 0x2000
	s_nop 0
	global_load_lds_dwordx4 v174, s[54:55]
	v_lshl_add_u64 v[220:221], s[30:31], 0, v[168:169]
	s_mov_b32 m0, s25
	s_nop 0
	global_load_lds_dwordx4 v[220:221], off
	s_mov_b32 m0, s37
	s_nop 0
	global_load_lds_dwordx4 v[222:223], off
	s_waitcnt vmcnt(8)
	s_waitcnt lgkmcnt(0)
	s_barrier
	s_setprio 1
	s_waitcnt lgkmcnt(0)
	v_mfma_f32_16x16x32_bf16 v[60:63], v[116:119], v[160:163], v[60:63]
	v_mfma_f32_16x16x32_bf16 v[52:55], v[124:127], v[160:163], v[52:55]
	v_mfma_f32_16x16x32_bf16 v[44:47], v[116:119], v[186:189], v[44:47]
	v_mfma_f32_16x16x32_bf16 v[36:39], v[124:127], v[186:189], v[36:39]
	v_mfma_f32_16x16x32_bf16 v[28:31], v[116:119], v[194:197], v[28:31]
	v_mfma_f32_16x16x32_bf16 v[20:23], v[124:127], v[194:197], v[20:23]
	v_mfma_f32_16x16x32_bf16 v[12:15], v[116:119], v[208:211], v[12:15]
	v_mfma_f32_16x16x32_bf16 v[4:7], v[124:127], v[208:211], v[4:7]
	v_mfma_f32_16x16x32_bf16 v[60:63], v[120:123], v[164:167], v[60:63]
	v_mfma_f32_16x16x32_bf16 v[52:55], v[136:139], v[164:167], v[52:55]
	v_mfma_f32_16x16x32_bf16 v[44:47], v[120:123], v[190:193], v[44:47]
	v_mfma_f32_16x16x32_bf16 v[36:39], v[136:139], v[190:193], v[36:39]
	v_mfma_f32_16x16x32_bf16 v[28:31], v[120:123], v[204:207], v[28:31]
	v_mfma_f32_16x16x32_bf16 v[20:23], v[136:139], v[204:207], v[20:23]
	v_mfma_f32_16x16x32_bf16 v[12:15], v[120:123], v[212:215], v[12:15]
	v_mfma_f32_16x16x32_bf16 v[4:7], v[136:139], v[212:215], v[4:7]
	s_setprio 0
	s_setprio 1
	v_mfma_f32_16x16x32_bf16 v[56:59], v[140:143], v[160:163], v[56:59]
	v_mfma_f32_16x16x32_bf16 v[48:51], v[152:155], v[160:163], v[48:51]
	v_mfma_f32_16x16x32_bf16 v[40:43], v[140:143], v[186:189], v[40:43]
	v_mfma_f32_16x16x32_bf16 v[32:35], v[152:155], v[186:189], v[32:35]
	v_mfma_f32_16x16x32_bf16 v[24:27], v[140:143], v[194:197], v[24:27]
	v_mfma_f32_16x16x32_bf16 v[16:19], v[152:155], v[194:197], v[16:19]
	v_mfma_f32_16x16x32_bf16 v[8:11], v[140:143], v[208:211], v[8:11]
	v_mfma_f32_16x16x32_bf16 v[0:3], v[152:155], v[208:211], v[0:3]
	v_mfma_f32_16x16x32_bf16 v[56:59], v[148:151], v[164:167], v[56:59]
	v_mfma_f32_16x16x32_bf16 v[48:51], v[156:159], v[164:167], v[48:51]
	v_mfma_f32_16x16x32_bf16 v[40:43], v[148:151], v[190:193], v[40:43]
	v_mfma_f32_16x16x32_bf16 v[32:35], v[156:159], v[190:193], v[32:35]
	v_mfma_f32_16x16x32_bf16 v[24:27], v[148:151], v[204:207], v[24:27]
	v_mfma_f32_16x16x32_bf16 v[16:19], v[156:159], v[204:207], v[16:19]
	v_mfma_f32_16x16x32_bf16 v[8:11], v[148:151], v[212:215], v[8:11]
	v_mfma_f32_16x16x32_bf16 v[0:3], v[156:159], v[212:215], v[0:3]
	s_setprio 0
	s_barrier
; #define PG8_STAGE(bufoff, gbase, voff) do { _Pragma("unroll") for (int _i = 0; _i < 2; ++_i) \
;         __builtin_amdgcn_global_load_lds((const unsigned*)((const char*)(gbase) + (voff)[_i]), (LAS unsigned*)(lds + (bufoff) + ldsw + _i * 8192), 16, 0, 0); } while (0)
; #define PG8_LDA(dst, b, h) do { _Pragma("unroll") for (int m = 0; m < 4; ++m) _Pragma("unroll") for (int k = 0; k < 2; ++k) dst[m][k] = *(const LAS bf16x8*)(lds + PG8_SA(b, h) + aoff + m * 2048 + k * 1024); } while (0)
; #define PG8_LDB(dst, b, h) do { _Pragma("unroll") for (int n = 0; n < 2; ++n) _Pragma("unroll") for (int k = 0; k < 2; ++k) dst[n][k] = *(const LAS bf16x8*)(lds + PG8_SB(b, h) + boff + n * 2048 + k * 1024); } while (0)
; #define PG8_MMA(ai, bj, At, Bt) do { __builtin_amdgcn_s_setprio(1); _Pragma("unroll") for (int m = 0; m < 4; ++m) _Pragma("unroll") for (int n = 0; n < 2; ++n) _Pragma("unroll") for (int k = 0; k < 2; ++k) \
;         acc[ai][bj][m][n] = __builtin_amdgcn_mfma_f32_16x16x32_bf16(Bt[n][k], At[m][k], acc[ai][bj][m][n], 0, 0, 0); __builtin_amdgcn_s_setprio(0); } while (0)
; #define PG8_WAIT_V(n) asm volatile("s_waitcnt vmcnt(" #n ")" ::: "memory")
; #define PG8_WAIT_L(n) asm volatile("s_waitcnt lgkmcnt(" #n ")" ::: "memory")
; #define PG8_BAR __builtin_amdgcn_s_barrier()
; #define PG8_SCHED __builtin_amdgcn_sched_barrier(0)
; template <class Epi, class Sched>
; __device__ __forceinline__ void gemm_phase(LAS unsigned char* lds, const Gemm g, const Sched& S, const Epi& E, int wave_id) {
;     ...
;             PG8_LDB(B0, 1, 0); PG8_LDB(B1, 1, 1); PG8_SCHED; PG8_LDA(At, 1, 0); PG8_STAGE(PG8_SA(0, 1), a2 + hstepA, voffA);
;             PG8_WAIT_V(8); PG8_WAIT_L(0); PG8_BAR; PG8_MMA(0, 0, At, B0); PG8_MMA(0, 1, At, B1); PG8_BAR; PG8_SCHED;
;             PG8_LDA(At, 1, 1); PG8_STAGE(PG8_SB(1, 0), b3, voffB); PG8_STAGE(PG8_SB(1, 1), b3 + hstepB, voffB); PG8_STAGE(PG8_SA(1, 0), a3, voffA);
;             PG8_WAIT_V(8); PG8_WAIT_L(0); PG8_BAR; PG8_MMA(1, 0, At, B0); PG8_MMA(1, 1, At, B1); PG8_BAR; PG8_SCHED;
;         }
	s_add_i32 s53, 0, 0x18000
	s_add_i32 s54, 0, 0x1c000
	v_add_u32_e32 v136, s53, v199
	v_add_u32_e32 v156, s54, v199
	ds_read_b128 v[116:119], v136
	ds_read_b128 v[120:123], v136 offset:1024
	ds_read_b128 v[124:127], v136 offset:2048
	ds_read_b128 v[136:139], v136 offset:3072
	ds_read_b128 v[140:143], v156
	ds_read_b128 v[148:151], v156 offset:1024
	ds_read_b128 v[152:155], v156 offset:2048
	ds_read_b128 v[156:159], v156 offset:3072
	s_add_u32 s30, s30, 0x20000
	s_addc_u32 s31, s31, 0
	s_mov_b32 m0, s38
	ds_read_b128 v[160:163], v203 offset:32768
	ds_read_b128 v[164:167], v203 offset:33792
	ds_read_b128 v[186:189], v203 offset:34816
	ds_read_b128 v[190:193], v203 offset:35840
	ds_read_b128 v[194:197], v203 offset:36864
	ds_read_b128 v[204:207], v203 offset:37888
	ds_read_b128 v[208:211], v203 offset:38912
	ds_read_b128 v[212:215], v203 offset:39936
	global_load_lds_dwordx4 v168, s[30:31]
	s_mov_b32 m0, s39
	s_nop 0
	global_load_lds_dwordx4 v172, s[30:31]
	s_waitcnt vmcnt(8)
	s_waitcnt lgkmcnt(0)
	s_barrier
	s_setprio 1
	s_waitcnt lgkmcnt(0)
	v_mfma_f32_16x16x32_bf16 v[144:147], v[116:119], v[160:163], v[144:147]
	v_mfma_f32_16x16x32_bf16 v[128:131], v[124:127], v[160:163], v[128:131]
	v_mfma_f32_16x16x32_bf16 v[108:111], v[116:119], v[186:189], v[108:111]
	v_mfma_f32_16x16x32_bf16 v[100:103], v[124:127], v[186:189], v[100:103]
	v_mfma_f32_16x16x32_bf16 v[92:95], v[116:119], v[194:197], v[92:95]
	v_mfma_f32_16x16x32_bf16 v[84:87], v[124:127], v[194:197], v[84:87]
	v_mfma_f32_16x16x32_bf16 v[76:79], v[116:119], v[208:211], v[76:79]
	v_mfma_f32_16x16x32_bf16 v[68:71], v[124:127], v[208:211], v[68:71]
	v_mfma_f32_16x16x32_bf16 v[144:147], v[120:123], v[164:167], v[144:147]
	v_mfma_f32_16x16x32_bf16 v[128:131], v[136:139], v[164:167], v[128:131]
	v_mfma_f32_16x16x32_bf16 v[108:111], v[120:123], v[190:193], v[108:111]
	v_mfma_f32_16x16x32_bf16 v[100:103], v[136:139], v[190:193], v[100:103]
	v_mfma_f32_16x16x32_bf16 v[92:95], v[120:123], v[204:207], v[92:95]
	v_mfma_f32_16x16x32_bf16 v[84:87], v[136:139], v[204:207], v[84:87]
	v_mfma_f32_16x16x32_bf16 v[76:79], v[120:123], v[212:215], v[76:79]
	v_mfma_f32_16x16x32_bf16 v[68:71], v[136:139], v[212:215], v[68:71]
	s_setprio 0
	s_setprio 1
	v_mfma_f32_16x16x32_bf16 v[132:135], v[140:143], v[160:163], v[132:135]
	v_mfma_f32_16x16x32_bf16 v[112:115], v[152:155], v[160:163], v[112:115]
	v_mfma_f32_16x16x32_bf16 v[104:107], v[140:143], v[186:189], v[104:107]
	v_mfma_f32_16x16x32_bf16 v[96:99], v[152:155], v[186:189], v[96:99]
	v_mfma_f32_16x16x32_bf16 v[88:91], v[140:143], v[194:197], v[88:91]
	v_mfma_f32_16x16x32_bf16 v[80:83], v[152:155], v[194:197], v[80:83]
	v_mfma_f32_16x16x32_bf16 v[72:75], v[140:143], v[208:211], v[72:75]
	v_mfma_f32_16x16x32_bf16 v[64:67], v[152:155], v[208:211], v[64:67]
	v_mfma_f32_16x16x32_bf16 v[132:135], v[148:151], v[164:167], v[132:135]
	v_mfma_f32_16x16x32_bf16 v[112:115], v[156:159], v[164:167], v[112:115]
	v_mfma_f32_16x16x32_bf16 v[104:107], v[148:151], v[190:193], v[104:107]
	v_mfma_f32_16x16x32_bf16 v[96:99], v[156:159], v[190:193], v[96:99]
	v_mfma_f32_16x16x32_bf16 v[88:91], v[148:151], v[204:207], v[88:91]
	v_mfma_f32_16x16x32_bf16 v[80:83], v[156:159], v[204:207], v[80:83]
	v_mfma_f32_16x16x32_bf16 v[72:75], v[148:151], v[212:215], v[72:75]
	v_mfma_f32_16x16x32_bf16 v[64:67], v[156:159], v[212:215], v[64:67]
	s_setprio 0
	s_barrier
	s_add_i32 s30, s53, s36
	v_lshl_add_u64 v[216:217], v[216:217], 0, s[10:11]
	s_mov_b32 m0, s30
	ds_read_b128 v[160:163], v203 offset:49152
	ds_read_b128 v[164:167], v203 offset:50176
	ds_read_b128 v[186:189], v203 offset:51200
	ds_read_b128 v[190:193], v203 offset:52224
	ds_read_b128 v[194:197], v203 offset:53248
	ds_read_b128 v[204:207], v203 offset:54272
	ds_read_b128 v[208:211], v203 offset:55296
	ds_read_b128 v[212:215], v203 offset:56320
	global_load_lds_dwordx4 v[216:217], off
	s_add_i32 m0, s30, 0x2000
	s_add_u32 s28, s28, 0x20080
	v_lshl_add_u64 v[216:217], v[218:219], 0, s[10:11]
	s_addc_u32 s29, s29, 0
	s_add_i32 s30, s54, s36
	global_load_lds_dwordx4 v[216:217], off
	s_mov_b32 m0, s30
	s_nop 0
	global_load_lds_dwordx4 v170, s[28:29]
	s_add_i32 m0, s30, 0x2000
	s_nop 0
	global_load_lds_dwordx4 v174, s[28:29]
	v_lshl_add_u64 v[216:217], v[220:221], 0, s[10:11]
	s_mov_b32 m0, s41
	s_nop 0
	global_load_lds_dwordx4 v[216:217], off
	v_lshl_add_u64 v[216:217], v[222:223], 0, s[10:11]
	s_mov_b32 m0, s42
	s_nop 0
	global_load_lds_dwordx4 v[216:217], off
	s_waitcnt vmcnt(8)
	s_waitcnt lgkmcnt(0)
	s_barrier
	s_setprio 1
	s_waitcnt lgkmcnt(0)
	v_mfma_f32_16x16x32_bf16 v[60:63], v[116:119], v[160:163], v[60:63]
	v_mfma_f32_16x16x32_bf16 v[52:55], v[124:127], v[160:163], v[52:55]
	v_mfma_f32_16x16x32_bf16 v[44:47], v[116:119], v[186:189], v[44:47]
	v_mfma_f32_16x16x32_bf16 v[36:39], v[124:127], v[186:189], v[36:39]
	v_mfma_f32_16x16x32_bf16 v[28:31], v[116:119], v[194:197], v[28:31]
	v_mfma_f32_16x16x32_bf16 v[20:23], v[124:127], v[194:197], v[20:23]
	v_mfma_f32_16x16x32_bf16 v[12:15], v[116:119], v[208:211], v[12:15]
	v_mfma_f32_16x16x32_bf16 v[4:7], v[124:127], v[208:211], v[4:7]
	v_mfma_f32_16x16x32_bf16 v[60:63], v[120:123], v[164:167], v[60:63]
	v_mfma_f32_16x16x32_bf16 v[52:55], v[136:139], v[164:167], v[52:55]
	v_mfma_f32_16x16x32_bf16 v[44:47], v[120:123], v[190:193], v[44:47]
	v_mfma_f32_16x16x32_bf16 v[36:39], v[136:139], v[190:193], v[36:39]
	v_mfma_f32_16x16x32_bf16 v[28:31], v[120:123], v[204:207], v[28:31]
	v_mfma_f32_16x16x32_bf16 v[20:23], v[136:139], v[204:207], v[20:23]
	v_mfma_f32_16x16x32_bf16 v[12:15], v[120:123], v[212:215], v[12:15]
	v_mfma_f32_16x16x32_bf16 v[4:7], v[136:139], v[212:215], v[4:7]
	s_setprio 0
	s_setprio 1
	v_mfma_f32_16x16x32_bf16 v[56:59], v[140:143], v[160:163], v[56:59]
	v_mfma_f32_16x16x32_bf16 v[48:51], v[152:155], v[160:163], v[48:51]
	v_mfma_f32_16x16x32_bf16 v[40:43], v[140:143], v[186:189], v[40:43]
	v_mfma_f32_16x16x32_bf16 v[32:35], v[152:155], v[186:189], v[32:35]
	v_mfma_f32_16x16x32_bf16 v[24:27], v[140:143], v[194:197], v[24:27]
	v_mfma_f32_16x16x32_bf16 v[16:19], v[152:155], v[194:197], v[16:19]
	v_mfma_f32_16x16x32_bf16 v[8:11], v[140:143], v[208:211], v[8:11]
	v_mfma_f32_16x16x32_bf16 v[0:3], v[152:155], v[208:211], v[0:3]
	v_mfma_f32_16x16x32_bf16 v[56:59], v[148:151], v[164:167], v[56:59]
	v_mfma_f32_16x16x32_bf16 v[48:51], v[156:159], v[164:167], v[48:51]
	v_mfma_f32_16x16x32_bf16 v[40:43], v[148:151], v[190:193], v[40:43]
	v_mfma_f32_16x16x32_bf16 v[32:35], v[156:159], v[190:193], v[32:35]
	v_mfma_f32_16x16x32_bf16 v[24:27], v[148:151], v[204:207], v[24:27]
	v_mfma_f32_16x16x32_bf16 v[16:19], v[156:159], v[204:207], v[16:19]
	v_mfma_f32_16x16x32_bf16 v[8:11], v[148:151], v[212:215], v[8:11]
	v_mfma_f32_16x16x32_bf16 v[0:3], v[156:159], v[212:215], v[0:3]
	s_setprio 0
	s_barrier
	s_add_i32 s52, s52, 2
	s_add_u32 s26, s26, 0x100
	s_addc_u32 s27, s27, 0
	s_add_u32 s50, s50, 0x100
	s_addc_u32 s51, s51, 0
	s_cmp_gt_u32 s52, 5
	s_cbranch_scc0 .LBB0_1041
	s_and_b64 vcc, exec, s[12:13]
	s_cbranch_vccz .LBB0_1044
	s_barrier

; #define PG8_STAGE(bufoff, gbase, voff) do { _Pragma("unroll") for (int _i = 0; _i < 2; ++_i) \
;         __builtin_amdgcn_global_load_lds((const unsigned*)((const char*)(gbase) + (voff)[_i]), (LAS unsigned*)(lds + (bufoff) + ldsw + _i * 8192), 16, 0, 0); } while (0)
; #define PG8_WAIT_V(n) asm volatile("s_waitcnt vmcnt(" #n ")" ::: "memory")
; #define PG8_BAR __builtin_amdgcn_s_barrier()
; #define lane lane_id()
; template <class Epi, class Sched>
; __device__ __forceinline__ void gemm_phase(LAS unsigned char* lds, const Gemm g, const Sched& S, const Epi& E, int wave_id) {
;     ...
;     const int wid = wave_id, lane = tid & 63, wr = wid >> 2, wc = wid & 3, fr = lane & 15, fq = lane >> 4;
;     const int K = g.K, nt = K / BK;
;     unsigned voffA[2], voffB[2];
; #pragma unroll
;     for (int i = 0; i < 2; ++i) { int R, C; stage_rc(tid * 16 + i * 8192, R, C); const int Rb = (R & ~31) + perm32(R & 31);
;         voffA[i] = (unsigned)(R * g.lda + C) * 2u; voffB[i] = (unsigned)(Rb * g.ldb + C) * 2u; }
;     const size_t kstep = (size_t)(BK * 2);
;     const size_t hstepA = (size_t)HALF * g.lda * 2, hstepB = (size_t)HALF * g.ldb * 2;
;     const size_t tstepA = 2 * hstepA, tstepB = 2 * hstepB;
;     const unsigned ldsw = (unsigned)wid * 1024u;
;     const int aoff = lds_byte(wr * 64 + fr, fq * 8), boff = lds_byte(wc * 32 + fr, fq * 8);
;     ...
;     PG8_STAGE(PG8_SB(0, 0), cB, voffB); PG8_STAGE(PG8_SB(0, 1), cB + hstepB, voffB); PG8_STAGE(PG8_SA(0, 0), cA, voffA); PG8_STAGE(PG8_SA(0, 1), cA + hstepA, voffA);
;     if (wr == 1) PG8_BAR;
;     PG8_WAIT_V(2); PG8_BAR;
;     PG8_STAGE(PG8_SB(1, 0), cB + kstep, voffB); PG8_STAGE(PG8_SA(1, 0), cA + kstep, voffA); PG8_STAGE(PG8_SB(1, 1), cB + hstepB + kstep, voffB);
;     PG8_WAIT_V(6); PG8_BAR;
.LBB0_1136:
	s_mov_b64 s[12:13], 0x80
	s_bfe_u32 s16, s80, 0x20006
	s_add_i32 m0, s38, 0x18000
	v_lshl_add_u64 v[6:7], v[6:7], 0, s[12:13]
	s_lshl_b32 s43, s5, 6
	s_lshl_b32 s18, s5, 13
	s_lshl_b32 s19, s16, 5
	s_lshl_b32 s20, s16, 12
	s_waitcnt vmcnt(2)
	s_barrier
	global_load_lds_dwordx4 v[6:7], off
	v_lshl_add_u64 v[4:5], v[4:5], 0, s[12:13]
	s_add_i32 m0, s38, 0x1a000
	s_add_i32 s44, s38, 0x8000
	s_add_i32 s45, s38, 0xa000
	global_load_lds_dwordx4 v[4:5], off
	v_lshl_add_u64 v[0:1], v[0:1], 0, s[12:13]
	s_mov_b32 m0, s44
	s_add_u32 s14, s30, 0x20080
	global_load_lds_dwordx4 v[0:1], off
	v_lshl_add_u64 v[0:1], v[2:3], 0, s[12:13]
	s_mov_b32 m0, s45
	s_addc_u32 s15, s31, 0
	global_load_lds_dwordx4 v[0:1], off
	s_add_i32 m0, s38, 0x1c000
	s_nop 0
	global_load_lds_dwordx4 v154, s[14:15]
	v_lshl_add_u64 v[0:1], s[14:15], 0, v[158:159]
	s_add_i32 m0, s38, 0x1e000
	s_cmpk_lt_u32 s80, 0x100
	global_load_lds_dwordx4 v[0:1], off
	s_sext_i32_i8 s27, s4
	v_bfe_u32 v1, v9, 4, 2
	s_cselect_b64 s[14:15], -1, 0
	s_lshl_b32 s4, s16, 6
	v_and_b32_e32 v204, 15, v9
	v_lshlrev_b32_e32 v2, 4, v1
	v_lshlrev_b32_e32 v4, 2, v9
	s_add_u32 s46, s92, 0xb400000
	v_lshl_or_b32 v3, v204, 6, v2
	v_and_b32_e32 v4, 32, v4
	s_addc_u32 s47, s93, 0
	v_bitop3_b32 v5, v3, s18, v4 bitop3:0xde
	v_bitop3_b32 v205, v3, s20, v4 bitop3:0xde
	s_add_u32 s48, s92, 0x13400000
	v_lshlrev_b32_e32 v4, 13, v8
	s_addc_u32 s49, s93, 0
	v_and_b32_e32 v4, 0xffffc000, v4
	s_mulk_i32 s5, 0x2100
	s_add_u32 s50, s92, 0x7400000
	v_lshl_add_u32 v4, v10, 10, v4
	v_and_b32_e32 v6, 1, v8
	v_lshrrev_b32_e32 v0, 4, v9
	s_addc_u32 s51, s93, 0
	s_add_i32 s5, s5, 0
	v_lshl_or_b32 v4, v6, 6, v4
	v_bfe_u32 v0, v0, 1, 1
	s_add_i32 s5, s5, 0x20000
	v_lshl_add_u32 v170, v11, 1, v4
	v_lshlrev_b32_e32 v4, 13, v12
	v_lshl_or_b32 v162, v1, 3, s19
	v_lshl_or_b32 v0, s16, 1, v0
	v_and_or_b32 v1, v2, 16, v204
	s_add_i32 s4, s4, s5
	v_and_b32_e32 v4, 0xffffc000, v4
	s_waitcnt vmcnt(6)
	v_lshlrev_b32_e32 v164, 4, v1
	s_movk_i32 s16, 0x210
	v_mul_u32_u24_e32 v1, 0x210, v0
	v_lshlrev_b32_e32 v166, 11, v0
	v_mov_b32_e32 v0, s4
	v_lshl_add_u32 v4, v13, 10, v4
	v_and_b32_e32 v6, 1, v12
	v_mad_u32_u24 v0, v204, s16, v0
	v_add_u32_e32 v3, s5, v164
	v_readlane_b32 s4, v255, 1
	v_lshl_or_b32 v4, v6, 6, v4
	s_add_i32 s54, 0, 0x10000
	s_add_i32 s55, 0, 0x14000
	v_mov_b32_e32 v163, v161
	v_mov_b32_e32 v165, v161
	v_mov_b32_e32 v167, v161
	v_or_b32_e32 v168, 0x4000, v166
	v_mov_b32_e32 v169, v161
	s_ashr_i32 s52, s4, 31
	s_mov_b32 s53, s4
	v_mov_b32_e32 v171, v161
	v_lshl_add_u32 v172, v14, 1, v4
	v_mov_b32_e32 v173, v161
	v_mov_b64_e32 v[174:175], 0x200
	v_mov_b64_e32 v[176:177], 0x1ff
	v_add_u32_e32 v206, s54, v205
	v_add_u32_e32 v207, s55, v205
	v_add_u32_e32 v208, 0, v5
	v_lshlrev_b32_e32 v160, 1, v162
	s_mov_b32 s16, 0x3b808081
	v_add_u32_e32 v209, v0, v2
	v_add_u32_e32 v210, v3, v1
	s_barrier
	v_readlane_b32 s5, v255, 2
	s_branch .LBB0_1139

;     __device__ bool next(int i, Unit& u) const { if (r0 + i >= r1) return false; return base.next(r0 + i, u); }
;     __device__ bool next(int i, Unit& u) const { const int L = i * G + c; if (L >= 256) return false; u.pm = L; u.pn = L >> 3; return true; }
; #define PG8_STAGE(bufoff, gbase, voff) do { _Pragma("unroll") for (int _i = 0; _i < 2; ++_i) \
;         __builtin_amdgcn_global_load_lds((const unsigned*)((const char*)(gbase) + (voff)[_i]), (LAS unsigned*)(lds + (bufoff) + ldsw + _i * 8192), 16, 0, 0); } while (0)
; #define PG8_LDA(dst, b, h) do { _Pragma("unroll") for (int m = 0; m < 4; ++m) _Pragma("unroll") for (int k = 0; k < 2; ++k) dst[m][k] = *(const LAS bf16x8*)(lds + PG8_SA(b, h) + aoff + m * 2048 + k * 1024); } while (0)
; #define PG8_LDB(dst, b, h) do { _Pragma("unroll") for (int n = 0; n < 2; ++n) _Pragma("unroll") for (int k = 0; k < 2; ++k) dst[n][k] = *(const LAS bf16x8*)(lds + PG8_SB(b, h) + boff + n * 2048 + k * 1024); } while (0)
; #define PG8_WAIT_V(n) asm volatile("s_waitcnt vmcnt(" #n ")" ::: "memory")
; #define PG8_WAIT_L(n) asm volatile("s_waitcnt lgkmcnt(" #n ")" ::: "memory")
; template <class Epi, class Sched>
; __device__ __forceinline__ void gemm_phase(LAS unsigned char* lds, const Gemm g, const Sched& S, const Epi& E, int wave_id) {
;     ...
;         const bool has_next = S.next(ui + 1, nxt);
;         const char* nA = has_next ? (const char*)g.A + (size_t)nxt.pm * tstepA : cA; const char* nB = has_next ? (const char*)g.Bt + (size_t)nxt.pn * tstepB : cB;
;         for (int t = 0; t < nt; t += 2) {
;             const bool last = (t == nt - 2);
;             const char* a1 = cA + (size_t)(t + 1) * kstep;
;             const char* a2 = last ? nA : cA + (size_t)(t + 2) * kstep; const char* b2 = last ? nB : cB + (size_t)(t + 2) * kstep;
;             const char* a3 = a2 + kstep; const char* b3 = b2 + kstep;
;             PG8_LDB(B0, 0, 0); PG8_LDB(B1, 0, 1); PG8_SCHED; PG8_LDA(At, 0, 0); PG8_STAGE(PG8_SA(1, 1), a1 + hstepA, voffA);
;             PG8_WAIT_V(8); PG8_WAIT_L(0); PG8_BAR; PG8_MMA(0, 0, At, B0); PG8_MMA(0, 1, At, B1); PG8_BAR; PG8_SCHED;
;             PG8_LDA(At, 0, 1); PG8_STAGE(PG8_SB(0, 0), b2, voffB); PG8_STAGE(PG8_SB(0, 1), b2 + hstepB, voffB); PG8_STAGE(PG8_SA(0, 0), a2, voffA);
;             PG8_WAIT_V(8); PG8_WAIT_L(0); PG8_BAR; PG8_MMA(1, 0, At, B0); PG8_MMA(1, 1, At, B1); PG8_BAR; PG8_SCHED;
.LBB0_1145:
	s_ashr_i32 s21, s20, 31
	s_lshl_b64 s[22:23], s[20:21], 18
	s_add_u32 s22, s3, s22
	s_addc_u32 s23, s17, s23
	s_and_b64 s[24:25], s[4:5], exec
	s_cselect_b32 s21, s23, s29
	s_cselect_b32 s56, s22, s28
	s_ashr_i32 s19, s18, 31
	s_lshl_b64 s[24:25], s[18:19], 18
	s_add_u32 s24, s33, s24
	s_addc_u32 s25, s36, s25
	s_and_b64 s[34:35], s[4:5], exec
	s_cselect_b32 s19, s25, s31
	s_cselect_b32 s57, s24, s30
	s_add_u32 s28, s28, 0x20080
	s_addc_u32 s29, s29, 0
	s_add_u32 s58, s30, 0x100
	s_addc_u32 s59, s31, 0
	s_mov_b32 s60, -2
	s_waitcnt vmcnt(0)
	ds_read_b128 v[128:131], v206
	ds_read_b128 v[132:135], v206 offset:1024
	ds_read_b128 v[136:139], v206 offset:2048
	ds_read_b128 v[140:143], v206 offset:3072
	ds_read_b128 v[144:147], v207
	ds_read_b128 v[148:151], v207 offset:1024
	ds_read_b128 v[178:181], v207 offset:2048
	ds_read_b128 v[182:185], v207 offset:3072
	s_add_u32 s30, s28, 0xfffe0080
	s_addc_u32 s31, s29, -1
	s_cmp_eq_u32 s60, 4
	s_cselect_b32 s35, s21, s31
	s_cselect_b32 s34, s56, s30
	s_cselect_b32 s31, s19, s59
	s_cselect_b32 s30, s57, s58
	s_add_i32 m0, s38, 0xc000
	ds_read_b128 v[186:189], v208
	ds_read_b128 v[190:193], v208 offset:1024
	ds_read_b128 v[194:197], v208 offset:2048
	ds_read_b128 v[198:201], v208 offset:3072
	ds_read_b128 v[212:215], v208 offset:4096
	ds_read_b128 v[216:219], v208 offset:5120
	ds_read_b128 v[220:223], v208 offset:6144
	ds_read_b128 v[224:227], v208 offset:7168
	global_load_lds_dwordx4 v170, s[28:29]
	s_add_i32 m0, s38, 0xe000
	s_nop 0
	global_load_lds_dwordx4 v172, s[28:29]
	s_waitcnt vmcnt(8)
	s_waitcnt lgkmcnt(0)
	s_barrier
	s_setprio 1
	s_waitcnt lgkmcnt(0)
	v_mfma_f32_16x16x32_bf16 v[124:127], v[128:131], v[186:189], 0
	v_mfma_f32_16x16x32_bf16 v[120:123], v[136:139], v[186:189], 0
	v_mfma_f32_16x16x32_bf16 v[108:111], v[128:131], v[194:197], 0
	v_mfma_f32_16x16x32_bf16 v[104:107], v[136:139], v[194:197], 0
	v_mfma_f32_16x16x32_bf16 v[92:95], v[128:131], v[212:215], 0
	v_mfma_f32_16x16x32_bf16 v[88:91], v[136:139], v[212:215], 0
	v_mfma_f32_16x16x32_bf16 v[76:79], v[128:131], v[220:223], 0
	v_mfma_f32_16x16x32_bf16 v[72:75], v[136:139], v[220:223], 0
	v_mfma_f32_16x16x32_bf16 v[124:127], v[132:135], v[190:193], v[124:127]
	v_mfma_f32_16x16x32_bf16 v[120:123], v[140:143], v[190:193], v[120:123]
	v_mfma_f32_16x16x32_bf16 v[108:111], v[132:135], v[198:201], v[108:111]
	v_mfma_f32_16x16x32_bf16 v[104:107], v[140:143], v[198:201], v[104:107]
	v_mfma_f32_16x16x32_bf16 v[92:95], v[132:135], v[216:219], v[92:95]
	v_mfma_f32_16x16x32_bf16 v[88:91], v[140:143], v[216:219], v[88:91]
	v_mfma_f32_16x16x32_bf16 v[76:79], v[132:135], v[224:227], v[76:79]
	v_mfma_f32_16x16x32_bf16 v[72:75], v[140:143], v[224:227], v[72:75]
	s_setprio 0
	s_setprio 1
	v_mfma_f32_16x16x32_bf16 v[116:119], v[144:147], v[186:189], 0
	v_mfma_f32_16x16x32_bf16 v[112:115], v[178:181], v[186:189], 0
	v_mfma_f32_16x16x32_bf16 v[100:103], v[144:147], v[194:197], 0
	v_mfma_f32_16x16x32_bf16 v[96:99], v[178:181], v[194:197], 0
	v_mfma_f32_16x16x32_bf16 v[84:87], v[144:147], v[212:215], 0
	v_mfma_f32_16x16x32_bf16 v[80:83], v[178:181], v[212:215], 0
	v_mfma_f32_16x16x32_bf16 v[68:71], v[144:147], v[220:223], 0
	v_mfma_f32_16x16x32_bf16 v[64:67], v[178:181], v[220:223], 0
	v_mfma_f32_16x16x32_bf16 v[116:119], v[148:151], v[190:193], v[116:119]
	v_mfma_f32_16x16x32_bf16 v[112:115], v[182:185], v[190:193], v[112:115]
	v_mfma_f32_16x16x32_bf16 v[100:103], v[148:151], v[198:201], v[100:103]
	v_mfma_f32_16x16x32_bf16 v[96:99], v[182:185], v[198:201], v[96:99]
	v_mfma_f32_16x16x32_bf16 v[84:87], v[148:151], v[216:219], v[84:87]
	v_mfma_f32_16x16x32_bf16 v[80:83], v[182:185], v[216:219], v[80:83]
	v_mfma_f32_16x16x32_bf16 v[68:71], v[148:151], v[224:227], v[68:71]
	v_mfma_f32_16x16x32_bf16 v[64:67], v[182:185], v[224:227], v[64:67]
	s_setprio 0
	s_barrier
	s_add_i32 s61, s54, s37
	v_lshl_add_u64 v[202:203], s[30:31], 0, v[154:155]
	s_mov_b32 m0, s61
	ds_read_b128 v[186:189], v208 offset:16384
	ds_read_b128 v[190:193], v208 offset:17408
	ds_read_b128 v[194:197], v208 offset:18432
	ds_read_b128 v[198:201], v208 offset:19456
	ds_read_b128 v[212:215], v208 offset:20480
	ds_read_b128 v[216:219], v208 offset:21504
	ds_read_b128 v[220:223], v208 offset:22528
	ds_read_b128 v[224:227], v208 offset:23552
	global_load_lds_dwordx4 v[202:203], off
	s_add_i32 m0, s61, 0x2000
	s_add_u32 s62, s30, 0x20000
	v_lshl_add_u64 v[228:229], s[30:31], 0, v[158:159]
	s_addc_u32 s63, s31, 0
	s_add_i32 s61, s55, s37
	global_load_lds_dwordx4 v[228:229], off
	s_mov_b32 m0, s61
	v_lshl_add_u64 v[232:233], s[34:35], 0, v[156:157]
	global_load_lds_dwordx4 v154, s[62:63]
	s_add_i32 m0, s61, 0x2000
	s_nop 0
	global_load_lds_dwordx4 v158, s[62:63]
	v_lshl_add_u64 v[230:231], s[34:35], 0, v[152:153]
	s_mov_b32 m0, s38
	s_nop 0
	global_load_lds_dwordx4 v[230:231], off
	s_mov_b32 m0, s39
	s_nop 0
	global_load_lds_dwordx4 v[232:233], off
	s_waitcnt vmcnt(8)
	s_waitcnt lgkmcnt(0)
	s_barrier
; #define PG8_STAGE(bufoff, gbase, voff) do { _Pragma("unroll") for (int _i = 0; _i < 2; ++_i) \
;         __builtin_amdgcn_global_load_lds((const unsigned*)((const char*)(gbase) + (voff)[_i]), (LAS unsigned*)(lds + (bufoff) + ldsw + _i * 8192), 16, 0, 0); } while (0)
; #define PG8_LDA(dst, b, h) do { _Pragma("unroll") for (int m = 0; m < 4; ++m) _Pragma("unroll") for (int k = 0; k < 2; ++k) dst[m][k] = *(const LAS bf16x8*)(lds + PG8_SA(b, h) + aoff + m * 2048 + k * 1024); } while (0)
; #define PG8_LDB(dst, b, h) do { _Pragma("unroll") for (int n = 0; n < 2; ++n) _Pragma("unroll") for (int k = 0; k < 2; ++k) dst[n][k] = *(const LAS bf16x8*)(lds + PG8_SB(b, h) + boff + n * 2048 + k * 1024); } while (0)
; #define PG8_MMA(ai, bj, At, Bt) do { __builtin_amdgcn_s_setprio(1); _Pragma("unroll") for (int m = 0; m < 4; ++m) _Pragma("unroll") for (int n = 0; n < 2; ++n) _Pragma("unroll") for (int k = 0; k < 2; ++k) \
;         acc[ai][bj][m][n] = __builtin_amdgcn_mfma_f32_16x16x32_bf16(Bt[n][k], At[m][k], acc[ai][bj][m][n], 0, 0, 0); __builtin_amdgcn_s_setprio(0); } while (0)
; #define PG8_WAIT_V(n) asm volatile("s_waitcnt vmcnt(" #n ")" ::: "memory")
; #define PG8_WAIT_L(n) asm volatile("s_waitcnt lgkmcnt(" #n ")" ::: "memory")
; #define PG8_BAR __builtin_amdgcn_s_barrier()
; #define PG8_SCHED __builtin_amdgcn_sched_barrier(0)
; template <class Epi, class Sched>
; __device__ __forceinline__ void gemm_phase(LAS unsigned char* lds, const Gemm g, const Sched& S, const Epi& E, int wave_id) {
;     ...
;             PG8_WAIT_V(8); PG8_WAIT_L(0); PG8_BAR; PG8_MMA(1, 0, At, B0); PG8_MMA(1, 1, At, B1); PG8_BAR; PG8_SCHED;
;             PG8_LDB(B0, 1, 0); PG8_LDB(B1, 1, 1); PG8_SCHED; PG8_LDA(At, 1, 0); PG8_STAGE(PG8_SA(0, 1), a2 + hstepA, voffA);
;             PG8_WAIT_V(8); PG8_WAIT_L(0); PG8_BAR; PG8_MMA(0, 0, At, B0); PG8_MMA(0, 1, At, B1); PG8_BAR; PG8_SCHED;
	s_setprio 1
	s_waitcnt lgkmcnt(0)
	v_mfma_f32_16x16x32_bf16 v[60:63], v[128:131], v[186:189], 0
	v_mfma_f32_16x16x32_bf16 v[56:59], v[136:139], v[186:189], 0
	v_mfma_f32_16x16x32_bf16 v[44:47], v[128:131], v[194:197], 0
	v_mfma_f32_16x16x32_bf16 v[40:43], v[136:139], v[194:197], 0
	v_mfma_f32_16x16x32_bf16 v[28:31], v[128:131], v[212:215], 0
	v_mfma_f32_16x16x32_bf16 v[24:27], v[136:139], v[212:215], 0
	v_mfma_f32_16x16x32_bf16 v[12:15], v[128:131], v[220:223], 0
	v_mfma_f32_16x16x32_bf16 v[8:11], v[136:139], v[220:223], 0
	v_mfma_f32_16x16x32_bf16 v[60:63], v[132:135], v[190:193], v[60:63]
	v_mfma_f32_16x16x32_bf16 v[56:59], v[140:143], v[190:193], v[56:59]
	v_mfma_f32_16x16x32_bf16 v[44:47], v[132:135], v[198:201], v[44:47]
	v_mfma_f32_16x16x32_bf16 v[40:43], v[140:143], v[198:201], v[40:43]
	v_mfma_f32_16x16x32_bf16 v[28:31], v[132:135], v[216:219], v[28:31]
	v_mfma_f32_16x16x32_bf16 v[24:27], v[140:143], v[216:219], v[24:27]
	v_mfma_f32_16x16x32_bf16 v[12:15], v[132:135], v[224:227], v[12:15]
	v_mfma_f32_16x16x32_bf16 v[8:11], v[140:143], v[224:227], v[8:11]
	s_setprio 0
	s_setprio 1
	v_mfma_f32_16x16x32_bf16 v[52:55], v[144:147], v[186:189], 0
	v_mfma_f32_16x16x32_bf16 v[48:51], v[178:181], v[186:189], 0
	v_mfma_f32_16x16x32_bf16 v[36:39], v[144:147], v[194:197], 0
	v_mfma_f32_16x16x32_bf16 v[32:35], v[178:181], v[194:197], 0
	v_mfma_f32_16x16x32_bf16 v[20:23], v[144:147], v[212:215], 0
	v_mfma_f32_16x16x32_bf16 v[16:19], v[178:181], v[212:215], 0
	v_mfma_f32_16x16x32_bf16 v[4:7], v[144:147], v[220:223], 0
	v_mfma_f32_16x16x32_bf16 v[0:3], v[178:181], v[220:223], 0
	v_mfma_f32_16x16x32_bf16 v[52:55], v[148:151], v[190:193], v[52:55]
	v_mfma_f32_16x16x32_bf16 v[48:51], v[182:185], v[190:193], v[48:51]
	v_mfma_f32_16x16x32_bf16 v[36:39], v[148:151], v[198:201], v[36:39]
	v_mfma_f32_16x16x32_bf16 v[32:35], v[182:185], v[198:201], v[32:35]
	v_mfma_f32_16x16x32_bf16 v[20:23], v[148:151], v[216:219], v[20:23]
	v_mfma_f32_16x16x32_bf16 v[16:19], v[182:185], v[216:219], v[16:19]
	v_mfma_f32_16x16x32_bf16 v[4:7], v[148:151], v[224:227], v[4:7]
	v_mfma_f32_16x16x32_bf16 v[0:3], v[182:185], v[224:227], v[0:3]
	s_setprio 0
	s_barrier
	s_add_i32 s61, 0, 0x18000
	s_add_i32 s62, 0, 0x1c000
	v_add_u32_e32 v140, s61, v205
	v_add_u32_e32 v182, s62, v205
	ds_read_b128 v[128:131], v140
	ds_read_b128 v[132:135], v140 offset:1024
	ds_read_b128 v[136:139], v140 offset:2048
	ds_read_b128 v[140:143], v140 offset:3072
	ds_read_b128 v[144:147], v182
	ds_read_b128 v[148:151], v182 offset:1024
	ds_read_b128 v[178:181], v182 offset:2048
	ds_read_b128 v[182:185], v182 offset:3072
	s_add_u32 s34, s34, 0x20000
	s_addc_u32 s35, s35, 0
	s_mov_b32 m0, s40
	ds_read_b128 v[186:189], v208 offset:32768
	ds_read_b128 v[190:193], v208 offset:33792
	ds_read_b128 v[194:197], v208 offset:34816
	ds_read_b128 v[198:201], v208 offset:35840
	ds_read_b128 v[212:215], v208 offset:36864
	ds_read_b128 v[216:219], v208 offset:37888
	ds_read_b128 v[220:223], v208 offset:38912
	ds_read_b128 v[224:227], v208 offset:39936
	global_load_lds_dwordx4 v152, s[34:35]
	s_mov_b32 m0, s41
	s_nop 0
	global_load_lds_dwordx4 v156, s[34:35]
	s_waitcnt vmcnt(8)
	s_waitcnt lgkmcnt(0)
	s_barrier
	s_setprio 1
	s_waitcnt lgkmcnt(0)
	v_mfma_f32_16x16x32_bf16 v[124:127], v[128:131], v[186:189], v[124:127]
	v_mfma_f32_16x16x32_bf16 v[120:123], v[136:139], v[186:189], v[120:123]
	v_mfma_f32_16x16x32_bf16 v[108:111], v[128:131], v[194:197], v[108:111]
	v_mfma_f32_16x16x32_bf16 v[104:107], v[136:139], v[194:197], v[104:107]
	v_mfma_f32_16x16x32_bf16 v[92:95], v[128:131], v[212:215], v[92:95]
	v_mfma_f32_16x16x32_bf16 v[88:91], v[136:139], v[212:215], v[88:91]
	v_mfma_f32_16x16x32_bf16 v[76:79], v[128:131], v[220:223], v[76:79]
	v_mfma_f32_16x16x32_bf16 v[72:75], v[136:139], v[220:223], v[72:75]
	v_mfma_f32_16x16x32_bf16 v[124:127], v[132:135], v[190:193], v[124:127]
	v_mfma_f32_16x16x32_bf16 v[120:123], v[140:143], v[190:193], v[120:123]
	v_mfma_f32_16x16x32_bf16 v[108:111], v[132:135], v[198:201], v[108:111]
	v_mfma_f32_16x16x32_bf16 v[104:107], v[140:143], v[198:201], v[104:107]
	v_mfma_f32_16x16x32_bf16 v[92:95], v[132:135], v[216:219], v[92:95]
	v_mfma_f32_16x16x32_bf16 v[88:91], v[140:143], v[216:219], v[88:91]
	v_mfma_f32_16x16x32_bf16 v[76:79], v[132:135], v[224:227], v[76:79]
	v_mfma_f32_16x16x32_bf16 v[72:75], v[140:143], v[224:227], v[72:75]
	s_setprio 0
	s_setprio 1
	v_mfma_f32_16x16x32_bf16 v[116:119], v[144:147], v[186:189], v[116:119]
	v_mfma_f32_16x16x32_bf16 v[112:115], v[178:181], v[186:189], v[112:115]
	v_mfma_f32_16x16x32_bf16 v[100:103], v[144:147], v[194:197], v[100:103]
	v_mfma_f32_16x16x32_bf16 v[96:99], v[178:181], v[194:197], v[96:99]
	v_mfma_f32_16x16x32_bf16 v[84:87], v[144:147], v[212:215], v[84:87]
	v_mfma_f32_16x16x32_bf16 v[80:83], v[178:181], v[212:215], v[80:83]
	v_mfma_f32_16x16x32_bf16 v[68:71], v[144:147], v[220:223], v[68:71]
	v_mfma_f32_16x16x32_bf16 v[64:67], v[178:181], v[220:223], v[64:67]
	v_mfma_f32_16x16x32_bf16 v[116:119], v[148:151], v[190:193], v[116:119]
	v_mfma_f32_16x16x32_bf16 v[112:115], v[182:185], v[190:193], v[112:115]
	v_mfma_f32_16x16x32_bf16 v[100:103], v[148:151], v[198:201], v[100:103]
	v_mfma_f32_16x16x32_bf16 v[96:99], v[182:185], v[198:201], v[96:99]
	v_mfma_f32_16x16x32_bf16 v[84:87], v[148:151], v[216:219], v[84:87]
	v_mfma_f32_16x16x32_bf16 v[80:83], v[182:185], v[216:219], v[80:83]
	v_mfma_f32_16x16x32_bf16 v[68:71], v[148:151], v[224:227], v[68:71]
	v_mfma_f32_16x16x32_bf16 v[64:67], v[182:185], v[224:227], v[64:67]
	s_setprio 0
	s_barrier
; #define PG8_STAGE(bufoff, gbase, voff) do { _Pragma("unroll") for (int _i = 0; _i < 2; ++_i) \
;         __builtin_amdgcn_global_load_lds((const unsigned*)((const char*)(gbase) + (voff)[_i]), (LAS unsigned*)(lds + (bufoff) + ldsw + _i * 8192), 16, 0, 0); } while (0)
; #define PG8_LDA(dst, b, h) do { _Pragma("unroll") for (int m = 0; m < 4; ++m) _Pragma("unroll") for (int k = 0; k < 2; ++k) dst[m][k] = *(const LAS bf16x8*)(lds + PG8_SA(b, h) + aoff + m * 2048 + k * 1024); } while (0)
; #define PG8_LDB(dst, b, h) do { _Pragma("unroll") for (int n = 0; n < 2; ++n) _Pragma("unroll") for (int k = 0; k < 2; ++k) dst[n][k] = *(const LAS bf16x8*)(lds + PG8_SB(b, h) + boff + n * 2048 + k * 1024); } while (0)
; #define PG8_MMA(ai, bj, At, Bt) do { __builtin_amdgcn_s_setprio(1); _Pragma("unroll") for (int m = 0; m < 4; ++m) _Pragma("unroll") for (int n = 0; n < 2; ++n) _Pragma("unroll") for (int k = 0; k < 2; ++k) \
;         acc[ai][bj][m][n] = __builtin_amdgcn_mfma_f32_16x16x32_bf16(Bt[n][k], At[m][k], acc[ai][bj][m][n], 0, 0, 0); __builtin_amdgcn_s_setprio(0); } while (0)
; #define PG8_WAIT_V(n) asm volatile("s_waitcnt vmcnt(" #n ")" ::: "memory")
; #define PG8_WAIT_L(n) asm volatile("s_waitcnt lgkmcnt(" #n ")" ::: "memory")
; template <class Epi, class Sched>
; __device__ __forceinline__ void gemm_phase(LAS unsigned char* lds, const Gemm g, const Sched& S, const Epi& E, int wave_id) {
;     ...
;         for (int t = 0; t < nt; t += 2) {
;             const bool last = (t == nt - 2);
;             const char* a1 = cA + (size_t)(t + 1) * kstep;
;             const char* a2 = last ? nA : cA + (size_t)(t + 2) * kstep; const char* b2 = last ? nB : cB + (size_t)(t + 2) * kstep;
;             const char* a3 = a2 + kstep; const char* b3 = b2 + kstep;
;             PG8_LDB(B0, 0, 0); PG8_LDB(B1, 0, 1); PG8_SCHED; PG8_LDA(At, 0, 0); PG8_STAGE(PG8_SA(1, 1), a1 + hstepA, voffA);
;             PG8_WAIT_V(8); PG8_WAIT_L(0); PG8_BAR; PG8_MMA(0, 0, At, B0); PG8_MMA(0, 1, At, B1); PG8_BAR; PG8_SCHED;
;     ...
;             PG8_WAIT_V(8); PG8_WAIT_L(0); PG8_BAR; PG8_MMA(0, 0, At, B0); PG8_MMA(0, 1, At, B1); PG8_BAR; PG8_SCHED;
;             PG8_LDA(At, 1, 1); PG8_STAGE(PG8_SB(1, 0), b3, voffB); PG8_STAGE(PG8_SB(1, 1), b3 + hstepB, voffB); PG8_STAGE(PG8_SA(1, 0), a3, voffA);
;             PG8_WAIT_V(8); PG8_WAIT_L(0); PG8_BAR; PG8_MMA(1, 0, At, B0); PG8_MMA(1, 1, At, B1); PG8_BAR; PG8_SCHED;
	s_add_i32 s34, s61, s37
	v_lshl_add_u64 v[202:203], v[202:203], 0, s[12:13]
	s_mov_b32 m0, s34
	ds_read_b128 v[186:189], v208 offset:49152
	ds_read_b128 v[190:193], v208 offset:50176
	ds_read_b128 v[194:197], v208 offset:51200
	ds_read_b128 v[198:201], v208 offset:52224
	ds_read_b128 v[212:215], v208 offset:53248
	ds_read_b128 v[216:219], v208 offset:54272
	ds_read_b128 v[220:223], v208 offset:55296
	ds_read_b128 v[224:227], v208 offset:56320
	global_load_lds_dwordx4 v[202:203], off
	s_add_i32 m0, s34, 0x2000
	s_add_u32 s30, s30, 0x20080
	v_lshl_add_u64 v[202:203], v[228:229], 0, s[12:13]
	s_addc_u32 s31, s31, 0
	s_add_i32 s34, s62, s37
	global_load_lds_dwordx4 v[202:203], off
	s_mov_b32 m0, s34
	s_nop 0
	global_load_lds_dwordx4 v154, s[30:31]
	s_add_i32 m0, s34, 0x2000
	s_nop 0
	global_load_lds_dwordx4 v158, s[30:31]
	v_lshl_add_u64 v[202:203], v[230:231], 0, s[12:13]
	s_mov_b32 m0, s44
	s_nop 0
	global_load_lds_dwordx4 v[202:203], off
	v_lshl_add_u64 v[202:203], v[232:233], 0, s[12:13]
	s_mov_b32 m0, s45
	s_nop 0
	global_load_lds_dwordx4 v[202:203], off
	s_waitcnt vmcnt(8)
	s_waitcnt lgkmcnt(0)
	s_barrier
	s_setprio 1
	s_waitcnt lgkmcnt(0)
	v_mfma_f32_16x16x32_bf16 v[60:63], v[128:131], v[186:189], v[60:63]
	v_mfma_f32_16x16x32_bf16 v[56:59], v[136:139], v[186:189], v[56:59]
	v_mfma_f32_16x16x32_bf16 v[44:47], v[128:131], v[194:197], v[44:47]
	v_mfma_f32_16x16x32_bf16 v[40:43], v[136:139], v[194:197], v[40:43]
	v_mfma_f32_16x16x32_bf16 v[28:31], v[128:131], v[212:215], v[28:31]
	v_mfma_f32_16x16x32_bf16 v[24:27], v[136:139], v[212:215], v[24:27]
	v_mfma_f32_16x16x32_bf16 v[12:15], v[128:131], v[220:223], v[12:15]
	v_mfma_f32_16x16x32_bf16 v[8:11], v[136:139], v[220:223], v[8:11]
	v_mfma_f32_16x16x32_bf16 v[60:63], v[132:135], v[190:193], v[60:63]
	v_mfma_f32_16x16x32_bf16 v[56:59], v[140:143], v[190:193], v[56:59]
	v_mfma_f32_16x16x32_bf16 v[44:47], v[132:135], v[198:201], v[44:47]
	v_mfma_f32_16x16x32_bf16 v[40:43], v[140:143], v[198:201], v[40:43]
	v_mfma_f32_16x16x32_bf16 v[28:31], v[132:135], v[216:219], v[28:31]
	v_mfma_f32_16x16x32_bf16 v[24:27], v[140:143], v[216:219], v[24:27]
	v_mfma_f32_16x16x32_bf16 v[12:15], v[132:135], v[224:227], v[12:15]
	v_mfma_f32_16x16x32_bf16 v[8:11], v[140:143], v[224:227], v[8:11]
	s_setprio 0
	s_setprio 1
	v_mfma_f32_16x16x32_bf16 v[52:55], v[144:147], v[186:189], v[52:55]
	v_mfma_f32_16x16x32_bf16 v[48:51], v[178:181], v[186:189], v[48:51]
	v_mfma_f32_16x16x32_bf16 v[36:39], v[144:147], v[194:197], v[36:39]
	v_mfma_f32_16x16x32_bf16 v[32:35], v[178:181], v[194:197], v[32:35]
	v_mfma_f32_16x16x32_bf16 v[20:23], v[144:147], v[212:215], v[20:23]
	v_mfma_f32_16x16x32_bf16 v[16:19], v[178:181], v[212:215], v[16:19]
	v_mfma_f32_16x16x32_bf16 v[4:7], v[144:147], v[220:223], v[4:7]
	v_mfma_f32_16x16x32_bf16 v[0:3], v[178:181], v[220:223], v[0:3]
	v_mfma_f32_16x16x32_bf16 v[52:55], v[148:151], v[190:193], v[52:55]
	v_mfma_f32_16x16x32_bf16 v[48:51], v[182:185], v[190:193], v[48:51]
	v_mfma_f32_16x16x32_bf16 v[36:39], v[148:151], v[198:201], v[36:39]
	v_mfma_f32_16x16x32_bf16 v[32:35], v[182:185], v[198:201], v[32:35]
	v_mfma_f32_16x16x32_bf16 v[20:23], v[148:151], v[216:219], v[20:23]
	v_mfma_f32_16x16x32_bf16 v[16:19], v[182:185], v[216:219], v[16:19]
	v_mfma_f32_16x16x32_bf16 v[4:7], v[148:151], v[224:227], v[4:7]
	v_mfma_f32_16x16x32_bf16 v[0:3], v[182:185], v[224:227], v[0:3]
	s_setprio 0
	s_barrier
	s_add_i32 s60, s60, 2
	s_add_u32 s28, s28, 0x100
	s_addc_u32 s29, s29, 0
	s_add_u32 s58, s58, 0x100
	s_addc_u32 s59, s59, 0
	s_cmp_gt_u32 s60, 5
.LBB0_1146:
	ds_read_b128 v[128:131], v206
	ds_read_b128 v[132:135], v206 offset:1024
	ds_read_b128 v[136:139], v206 offset:2048
	ds_read_b128 v[140:143], v206 offset:3072
	ds_read_b128 v[144:147], v207
	ds_read_b128 v[148:151], v207 offset:1024
	ds_read_b128 v[178:181], v207 offset:2048
	ds_read_b128 v[182:185], v207 offset:3072
	s_add_u32 s30, s28, 0xfffe0080
	s_addc_u32 s31, s29, -1
	s_cmp_eq_u32 s60, 4
	s_cselect_b32 s35, s21, s31
	s_cselect_b32 s34, s56, s30
	s_cselect_b32 s31, s19, s59
	s_cselect_b32 s30, s57, s58
	s_add_i32 m0, s38, 0xc000
	ds_read_b128 v[186:189], v208
	ds_read_b128 v[190:193], v208 offset:1024
	ds_read_b128 v[194:197], v208 offset:2048
	ds_read_b128 v[198:201], v208 offset:3072
	ds_read_b128 v[212:215], v208 offset:4096
	ds_read_b128 v[216:219], v208 offset:5120
	ds_read_b128 v[220:223], v208 offset:6144
	ds_read_b128 v[224:227], v208 offset:7168
	global_load_lds_dwordx4 v170, s[28:29]
	s_add_i32 m0, s38, 0xe000
	s_nop 0
	global_load_lds_dwordx4 v172, s[28:29]
	s_waitcnt vmcnt(8)
	s_waitcnt lgkmcnt(0)
	s_barrier
; #define PG8_STAGE(bufoff, gbase, voff) do { _Pragma("unroll") for (int _i = 0; _i < 2; ++_i) \
;         __builtin_amdgcn_global_load_lds((const unsigned*)((const char*)(gbase) + (voff)[_i]), (LAS unsigned*)(lds + (bufoff) + ldsw + _i * 8192), 16, 0, 0); } while (0)
; #define PG8_LDA(dst, b, h) do { _Pragma("unroll") for (int m = 0; m < 4; ++m) _Pragma("unroll") for (int k = 0; k < 2; ++k) dst[m][k] = *(const LAS bf16x8*)(lds + PG8_SA(b, h) + aoff + m * 2048 + k * 1024); } while (0)
; #define PG8_LDB(dst, b, h) do { _Pragma("unroll") for (int n = 0; n < 2; ++n) _Pragma("unroll") for (int k = 0; k < 2; ++k) dst[n][k] = *(const LAS bf16x8*)(lds + PG8_SB(b, h) + boff + n * 2048 + k * 1024); } while (0)
; #define PG8_MMA(ai, bj, At, Bt) do { __builtin_amdgcn_s_setprio(1); _Pragma("unroll") for (int m = 0; m < 4; ++m) _Pragma("unroll") for (int n = 0; n < 2; ++n) _Pragma("unroll") for (int k = 0; k < 2; ++k) \
;         acc[ai][bj][m][n] = __builtin_amdgcn_mfma_f32_16x16x32_bf16(Bt[n][k], At[m][k], acc[ai][bj][m][n], 0, 0, 0); __builtin_amdgcn_s_setprio(0); } while (0)
; #define PG8_WAIT_V(n) asm volatile("s_waitcnt vmcnt(" #n ")" ::: "memory")
; #define PG8_WAIT_L(n) asm volatile("s_waitcnt lgkmcnt(" #n ")" ::: "memory")
; #define PG8_BAR __builtin_amdgcn_s_barrier()
; #define PG8_SCHED __builtin_amdgcn_sched_barrier(0)
; template <class Epi, class Sched>
; __device__ __forceinline__ void gemm_phase(LAS unsigned char* lds, const Gemm g, const Sched& S, const Epi& E, int wave_id) {
;     ...
;             PG8_WAIT_V(8); PG8_WAIT_L(0); PG8_BAR; PG8_MMA(0, 0, At, B0); PG8_MMA(0, 1, At, B1); PG8_BAR; PG8_SCHED;
;             PG8_LDA(At, 0, 1); PG8_STAGE(PG8_SB(0, 0), b2, voffB); PG8_STAGE(PG8_SB(0, 1), b2 + hstepB, voffB); PG8_STAGE(PG8_SA(0, 0), a2, voffA);
;             PG8_WAIT_V(8); PG8_WAIT_L(0); PG8_BAR; PG8_MMA(1, 0, At, B0); PG8_MMA(1, 1, At, B1); PG8_BAR; PG8_SCHED;
;             PG8_LDB(B0, 1, 0); PG8_LDB(B1, 1, 1); PG8_SCHED; PG8_LDA(At, 1, 0); PG8_STAGE(PG8_SA(0, 1), a2 + hstepA, voffA);
;             PG8_WAIT_V(8); PG8_WAIT_L(0); PG8_BAR; PG8_MMA(0, 0, At, B0); PG8_MMA(0, 1, At, B1); PG8_BAR; PG8_SCHED;
	s_setprio 1
	s_waitcnt lgkmcnt(0)
	v_mfma_f32_16x16x32_bf16 v[124:127], v[128:131], v[186:189], v[124:127]
	v_mfma_f32_16x16x32_bf16 v[120:123], v[136:139], v[186:189], v[120:123]
	v_mfma_f32_16x16x32_bf16 v[108:111], v[128:131], v[194:197], v[108:111]
	v_mfma_f32_16x16x32_bf16 v[104:107], v[136:139], v[194:197], v[104:107]
	v_mfma_f32_16x16x32_bf16 v[92:95], v[128:131], v[212:215], v[92:95]
	v_mfma_f32_16x16x32_bf16 v[88:91], v[136:139], v[212:215], v[88:91]
	v_mfma_f32_16x16x32_bf16 v[76:79], v[128:131], v[220:223], v[76:79]
	v_mfma_f32_16x16x32_bf16 v[72:75], v[136:139], v[220:223], v[72:75]
	v_mfma_f32_16x16x32_bf16 v[124:127], v[132:135], v[190:193], v[124:127]
	v_mfma_f32_16x16x32_bf16 v[120:123], v[140:143], v[190:193], v[120:123]
	v_mfma_f32_16x16x32_bf16 v[108:111], v[132:135], v[198:201], v[108:111]
	v_mfma_f32_16x16x32_bf16 v[104:107], v[140:143], v[198:201], v[104:107]
	v_mfma_f32_16x16x32_bf16 v[92:95], v[132:135], v[216:219], v[92:95]
	v_mfma_f32_16x16x32_bf16 v[88:91], v[140:143], v[216:219], v[88:91]
	v_mfma_f32_16x16x32_bf16 v[76:79], v[132:135], v[224:227], v[76:79]
	v_mfma_f32_16x16x32_bf16 v[72:75], v[140:143], v[224:227], v[72:75]
	s_setprio 0
	s_setprio 1
	v_mfma_f32_16x16x32_bf16 v[116:119], v[144:147], v[186:189], v[116:119]
	v_mfma_f32_16x16x32_bf16 v[112:115], v[178:181], v[186:189], v[112:115]
	v_mfma_f32_16x16x32_bf16 v[100:103], v[144:147], v[194:197], v[100:103]
	v_mfma_f32_16x16x32_bf16 v[96:99], v[178:181], v[194:197], v[96:99]
	v_mfma_f32_16x16x32_bf16 v[84:87], v[144:147], v[212:215], v[84:87]
	v_mfma_f32_16x16x32_bf16 v[80:83], v[178:181], v[212:215], v[80:83]
	v_mfma_f32_16x16x32_bf16 v[68:71], v[144:147], v[220:223], v[68:71]
	v_mfma_f32_16x16x32_bf16 v[64:67], v[178:181], v[220:223], v[64:67]
	v_mfma_f32_16x16x32_bf16 v[116:119], v[148:151], v[190:193], v[116:119]
	v_mfma_f32_16x16x32_bf16 v[112:115], v[182:185], v[190:193], v[112:115]
	v_mfma_f32_16x16x32_bf16 v[100:103], v[148:151], v[198:201], v[100:103]
	v_mfma_f32_16x16x32_bf16 v[96:99], v[182:185], v[198:201], v[96:99]
	v_mfma_f32_16x16x32_bf16 v[84:87], v[148:151], v[216:219], v[84:87]
	v_mfma_f32_16x16x32_bf16 v[80:83], v[182:185], v[216:219], v[80:83]
	v_mfma_f32_16x16x32_bf16 v[68:71], v[148:151], v[224:227], v[68:71]
	v_mfma_f32_16x16x32_bf16 v[64:67], v[182:185], v[224:227], v[64:67]
	s_setprio 0
	s_barrier
	s_add_i32 s61, s54, s37
	v_lshl_add_u64 v[202:203], s[30:31], 0, v[154:155]
	s_mov_b32 m0, s61
	ds_read_b128 v[186:189], v208 offset:16384
	ds_read_b128 v[190:193], v208 offset:17408
	ds_read_b128 v[194:197], v208 offset:18432
	ds_read_b128 v[198:201], v208 offset:19456
	ds_read_b128 v[212:215], v208 offset:20480
	ds_read_b128 v[216:219], v208 offset:21504
	ds_read_b128 v[220:223], v208 offset:22528
	ds_read_b128 v[224:227], v208 offset:23552
	global_load_lds_dwordx4 v[202:203], off
	s_add_i32 m0, s61, 0x2000
	s_add_u32 s62, s30, 0x20000
	v_lshl_add_u64 v[228:229], s[30:31], 0, v[158:159]
	s_addc_u32 s63, s31, 0
	s_add_i32 s61, s55, s37
	global_load_lds_dwordx4 v[228:229], off
	s_mov_b32 m0, s61
	v_lshl_add_u64 v[232:233], s[34:35], 0, v[156:157]
	global_load_lds_dwordx4 v154, s[62:63]
	s_add_i32 m0, s61, 0x2000
	s_nop 0
	global_load_lds_dwordx4 v158, s[62:63]
	v_lshl_add_u64 v[230:231], s[34:35], 0, v[152:153]
	s_mov_b32 m0, s38
	s_nop 0
	global_load_lds_dwordx4 v[230:231], off
	s_mov_b32 m0, s39
	s_nop 0
	global_load_lds_dwordx4 v[232:233], off
	s_waitcnt vmcnt(8)
	s_waitcnt lgkmcnt(0)
	s_barrier
	s_setprio 1
	s_waitcnt lgkmcnt(0)
	v_mfma_f32_16x16x32_bf16 v[60:63], v[128:131], v[186:189], v[60:63]
	v_mfma_f32_16x16x32_bf16 v[56:59], v[136:139], v[186:189], v[56:59]
	v_mfma_f32_16x16x32_bf16 v[44:47], v[128:131], v[194:197], v[44:47]
	v_mfma_f32_16x16x32_bf16 v[40:43], v[136:139], v[194:197], v[40:43]
	v_mfma_f32_16x16x32_bf16 v[28:31], v[128:131], v[212:215], v[28:31]
	v_mfma_f32_16x16x32_bf16 v[24:27], v[136:139], v[212:215], v[24:27]
	v_mfma_f32_16x16x32_bf16 v[12:15], v[128:131], v[220:223], v[12:15]
	v_mfma_f32_16x16x32_bf16 v[8:11], v[136:139], v[220:223], v[8:11]
	v_mfma_f32_16x16x32_bf16 v[60:63], v[132:135], v[190:193], v[60:63]
	v_mfma_f32_16x16x32_bf16 v[56:59], v[140:143], v[190:193], v[56:59]
	v_mfma_f32_16x16x32_bf16 v[44:47], v[132:135], v[198:201], v[44:47]
	v_mfma_f32_16x16x32_bf16 v[40:43], v[140:143], v[198:201], v[40:43]
	v_mfma_f32_16x16x32_bf16 v[28:31], v[132:135], v[216:219], v[28:31]
	v_mfma_f32_16x16x32_bf16 v[24:27], v[140:143], v[216:219], v[24:27]
	v_mfma_f32_16x16x32_bf16 v[12:15], v[132:135], v[224:227], v[12:15]
	v_mfma_f32_16x16x32_bf16 v[8:11], v[140:143], v[224:227], v[8:11]
	s_setprio 0
	s_setprio 1
	v_mfma_f32_16x16x32_bf16 v[52:55], v[144:147], v[186:189], v[52:55]
	v_mfma_f32_16x16x32_bf16 v[48:51], v[178:181], v[186:189], v[48:51]
	v_mfma_f32_16x16x32_bf16 v[36:39], v[144:147], v[194:197], v[36:39]
	v_mfma_f32_16x16x32_bf16 v[32:35], v[178:181], v[194:197], v[32:35]
	v_mfma_f32_16x16x32_bf16 v[20:23], v[144:147], v[212:215], v[20:23]
	v_mfma_f32_16x16x32_bf16 v[16:19], v[178:181], v[212:215], v[16:19]
	v_mfma_f32_16x16x32_bf16 v[4:7], v[144:147], v[220:223], v[4:7]
	v_mfma_f32_16x16x32_bf16 v[0:3], v[178:181], v[220:223], v[0:3]
	v_mfma_f32_16x16x32_bf16 v[52:55], v[148:151], v[190:193], v[52:55]
	v_mfma_f32_16x16x32_bf16 v[48:51], v[182:185], v[190:193], v[48:51]
	v_mfma_f32_16x16x32_bf16 v[36:39], v[148:151], v[198:201], v[36:39]
	v_mfma_f32_16x16x32_bf16 v[32:35], v[182:185], v[198:201], v[32:35]
	v_mfma_f32_16x16x32_bf16 v[20:23], v[148:151], v[216:219], v[20:23]
	v_mfma_f32_16x16x32_bf16 v[16:19], v[182:185], v[216:219], v[16:19]
	v_mfma_f32_16x16x32_bf16 v[4:7], v[148:151], v[224:227], v[4:7]
	v_mfma_f32_16x16x32_bf16 v[0:3], v[182:185], v[224:227], v[0:3]
	s_setprio 0
	s_barrier
; #define PG8_STAGE(bufoff, gbase, voff) do { _Pragma("unroll") for (int _i = 0; _i < 2; ++_i) \
;         __builtin_amdgcn_global_load_lds((const unsigned*)((const char*)(gbase) + (voff)[_i]), (LAS unsigned*)(lds + (bufoff) + ldsw + _i * 8192), 16, 0, 0); } while (0)
; #define PG8_LDA(dst, b, h) do { _Pragma("unroll") for (int m = 0; m < 4; ++m) _Pragma("unroll") for (int k = 0; k < 2; ++k) dst[m][k] = *(const LAS bf16x8*)(lds + PG8_SA(b, h) + aoff + m * 2048 + k * 1024); } while (0)
; #define PG8_LDB(dst, b, h) do { _Pragma("unroll") for (int n = 0; n < 2; ++n) _Pragma("unroll") for (int k = 0; k < 2; ++k) dst[n][k] = *(const LAS bf16x8*)(lds + PG8_SB(b, h) + boff + n * 2048 + k * 1024); } while (0)
; #define PG8_MMA(ai, bj, At, Bt) do { __builtin_amdgcn_s_setprio(1); _Pragma("unroll") for (int m = 0; m < 4; ++m) _Pragma("unroll") for (int n = 0; n < 2; ++n) _Pragma("unroll") for (int k = 0; k < 2; ++k) \
;         acc[ai][bj][m][n] = __builtin_amdgcn_mfma_f32_16x16x32_bf16(Bt[n][k], At[m][k], acc[ai][bj][m][n], 0, 0, 0); __builtin_amdgcn_s_setprio(0); } while (0)
; #define PG8_WAIT_V(n) asm volatile("s_waitcnt vmcnt(" #n ")" ::: "memory")
; #define PG8_WAIT_L(n) asm volatile("s_waitcnt lgkmcnt(" #n ")" ::: "memory")
; #define PG8_BAR __builtin_amdgcn_s_barrier()
; #define PG8_SCHED __builtin_amdgcn_sched_barrier(0)
; template <class Epi, class Sched>
; __device__ __forceinline__ void gemm_phase(LAS unsigned char* lds, const Gemm g, const Sched& S, const Epi& E, int wave_id) {
;     ...
;             PG8_LDB(B0, 1, 0); PG8_LDB(B1, 1, 1); PG8_SCHED; PG8_LDA(At, 1, 0); PG8_STAGE(PG8_SA(0, 1), a2 + hstepA, voffA);
;             PG8_WAIT_V(8); PG8_WAIT_L(0); PG8_BAR; PG8_MMA(0, 0, At, B0); PG8_MMA(0, 1, At, B1); PG8_BAR; PG8_SCHED;
	s_add_i32 s61, 0, 0x18000
	s_add_i32 s62, 0, 0x1c000
	v_add_u32_e32 v140, s61, v205
	v_add_u32_e32 v182, s62, v205
	ds_read_b128 v[128:131], v140
	ds_read_b128 v[132:135], v140 offset:1024
	ds_read_b128 v[136:139], v140 offset:2048
	ds_read_b128 v[140:143], v140 offset:3072
	ds_read_b128 v[144:147], v182
	ds_read_b128 v[148:151], v182 offset:1024
	ds_read_b128 v[178:181], v182 offset:2048
	ds_read_b128 v[182:185], v182 offset:3072
	s_add_u32 s34, s34, 0x20000
	s_addc_u32 s35, s35, 0
	s_mov_b32 m0, s40
	ds_read_b128 v[186:189], v208 offset:32768
	ds_read_b128 v[190:193], v208 offset:33792
	ds_read_b128 v[194:197], v208 offset:34816
	ds_read_b128 v[198:201], v208 offset:35840
	ds_read_b128 v[212:215], v208 offset:36864
	ds_read_b128 v[216:219], v208 offset:37888
	ds_read_b128 v[220:223], v208 offset:38912
	ds_read_b128 v[224:227], v208 offset:39936
	global_load_lds_dwordx4 v152, s[34:35]
	v_lshl_add_u64 v[234:235], s[34:35], 0, v[156:157]
	s_mov_b32 m0, s41
	s_nop 0
	global_load_lds_dwordx4 v[234:235], off
	s_waitcnt vmcnt(8)
	s_waitcnt lgkmcnt(0)
	s_barrier
	s_setprio 1
	s_waitcnt lgkmcnt(0)
	v_mfma_f32_16x16x32_bf16 v[124:127], v[128:131], v[186:189], v[124:127]
	v_mfma_f32_16x16x32_bf16 v[120:123], v[136:139], v[186:189], v[120:123]
	v_mfma_f32_16x16x32_bf16 v[108:111], v[128:131], v[194:197], v[108:111]
	v_mfma_f32_16x16x32_bf16 v[104:107], v[136:139], v[194:197], v[104:107]
	v_mfma_f32_16x16x32_bf16 v[92:95], v[128:131], v[212:215], v[92:95]
	v_mfma_f32_16x16x32_bf16 v[88:91], v[136:139], v[212:215], v[88:91]
	v_mfma_f32_16x16x32_bf16 v[76:79], v[128:131], v[220:223], v[76:79]
	v_mfma_f32_16x16x32_bf16 v[72:75], v[136:139], v[220:223], v[72:75]
	v_mfma_f32_16x16x32_bf16 v[124:127], v[132:135], v[190:193], v[124:127]
	v_mfma_f32_16x16x32_bf16 v[120:123], v[140:143], v[190:193], v[120:123]
	v_mfma_f32_16x16x32_bf16 v[108:111], v[132:135], v[198:201], v[108:111]
	v_mfma_f32_16x16x32_bf16 v[104:107], v[140:143], v[198:201], v[104:107]
	v_mfma_f32_16x16x32_bf16 v[92:95], v[132:135], v[216:219], v[92:95]
	v_mfma_f32_16x16x32_bf16 v[88:91], v[140:143], v[216:219], v[88:91]
	v_mfma_f32_16x16x32_bf16 v[76:79], v[132:135], v[224:227], v[76:79]
	v_mfma_f32_16x16x32_bf16 v[72:75], v[140:143], v[224:227], v[72:75]
	s_setprio 0
	s_setprio 1
	v_mfma_f32_16x16x32_bf16 v[116:119], v[144:147], v[186:189], v[116:119]
	v_mfma_f32_16x16x32_bf16 v[112:115], v[178:181], v[186:189], v[112:115]
	v_mfma_f32_16x16x32_bf16 v[100:103], v[144:147], v[194:197], v[100:103]
	v_mfma_f32_16x16x32_bf16 v[96:99], v[178:181], v[194:197], v[96:99]
	v_mfma_f32_16x16x32_bf16 v[84:87], v[144:147], v[212:215], v[84:87]
	v_mfma_f32_16x16x32_bf16 v[80:83], v[178:181], v[212:215], v[80:83]
	v_mfma_f32_16x16x32_bf16 v[68:71], v[144:147], v[220:223], v[68:71]
	v_mfma_f32_16x16x32_bf16 v[64:67], v[178:181], v[220:223], v[64:67]
	v_mfma_f32_16x16x32_bf16 v[116:119], v[148:151], v[190:193], v[116:119]
	v_mfma_f32_16x16x32_bf16 v[112:115], v[182:185], v[190:193], v[112:115]
	v_mfma_f32_16x16x32_bf16 v[100:103], v[148:151], v[198:201], v[100:103]
	v_mfma_f32_16x16x32_bf16 v[96:99], v[182:185], v[198:201], v[96:99]
	v_mfma_f32_16x16x32_bf16 v[84:87], v[148:151], v[216:219], v[84:87]
	v_mfma_f32_16x16x32_bf16 v[80:83], v[182:185], v[216:219], v[80:83]
	v_mfma_f32_16x16x32_bf16 v[68:71], v[148:151], v[224:227], v[68:71]
	v_mfma_f32_16x16x32_bf16 v[64:67], v[182:185], v[224:227], v[64:67]
	s_setprio 0
	s_barrier
; #define PG8_STAGE(bufoff, gbase, voff) do { _Pragma("unroll") for (int _i = 0; _i < 2; ++_i) \
;         __builtin_amdgcn_global_load_lds((const unsigned*)((const char*)(gbase) + (voff)[_i]), (LAS unsigned*)(lds + (bufoff) + ldsw + _i * 8192), 16, 0, 0); } while (0)
; #define PG8_LDA(dst, b, h) do { _Pragma("unroll") for (int m = 0; m < 4; ++m) _Pragma("unroll") for (int k = 0; k < 2; ++k) dst[m][k] = *(const LAS bf16x8*)(lds + PG8_SA(b, h) + aoff + m * 2048 + k * 1024); } while (0)
; #define PG8_MMA(ai, bj, At, Bt) do { __builtin_amdgcn_s_setprio(1); _Pragma("unroll") for (int m = 0; m < 4; ++m) _Pragma("unroll") for (int n = 0; n < 2; ++n) _Pragma("unroll") for (int k = 0; k < 2; ++k) \
;         acc[ai][bj][m][n] = __builtin_amdgcn_mfma_f32_16x16x32_bf16(Bt[n][k], At[m][k], acc[ai][bj][m][n], 0, 0, 0); __builtin_amdgcn_s_setprio(0); } while (0)
; #define PG8_WAIT_V(n) asm volatile("s_waitcnt vmcnt(" #n ")" ::: "memory")
; #define PG8_WAIT_L(n) asm volatile("s_waitcnt lgkmcnt(" #n ")" ::: "memory")
; #define PG8_BAR __builtin_amdgcn_s_barrier()
; #define PG8_SCHED __builtin_amdgcn_sched_barrier(0)
; template <class Epi, class Sched>
; __device__ __forceinline__ void gemm_phase(LAS unsigned char* lds, const Gemm g, const Sched& S, const Epi& E, int wave_id) {
;     ...
;             PG8_WAIT_V(8); PG8_WAIT_L(0); PG8_BAR; PG8_MMA(0, 0, At, B0); PG8_MMA(0, 1, At, B1); PG8_BAR; PG8_SCHED;
;             PG8_LDA(At, 1, 1); PG8_STAGE(PG8_SB(1, 0), b3, voffB); PG8_STAGE(PG8_SB(1, 1), b3 + hstepB, voffB); PG8_STAGE(PG8_SA(1, 0), a3, voffA);
;             PG8_WAIT_V(8); PG8_WAIT_L(0); PG8_BAR; PG8_MMA(1, 0, At, B0); PG8_MMA(1, 1, At, B1); PG8_BAR; PG8_SCHED;
;         }
	s_add_i32 s34, s61, s37
	v_lshl_add_u64 v[202:203], v[202:203], 0, s[12:13]
	s_mov_b32 m0, s34
	ds_read_b128 v[186:189], v208 offset:49152
	ds_read_b128 v[190:193], v208 offset:50176
	ds_read_b128 v[194:197], v208 offset:51200
	ds_read_b128 v[198:201], v208 offset:52224
	ds_read_b128 v[212:215], v208 offset:53248
	ds_read_b128 v[216:219], v208 offset:54272
	ds_read_b128 v[220:223], v208 offset:55296
	ds_read_b128 v[224:227], v208 offset:56320
	global_load_lds_dwordx4 v[202:203], off
	s_add_i32 m0, s34, 0x2000
	s_add_u32 s30, s30, 0x20080
	v_lshl_add_u64 v[202:203], v[228:229], 0, s[12:13]
	s_addc_u32 s31, s31, 0
	s_add_i32 s34, s62, s37
	global_load_lds_dwordx4 v[202:203], off
	s_mov_b32 m0, s34
	s_nop 0
	global_load_lds_dwordx4 v154, s[30:31]
	s_add_i32 m0, s34, 0x2000
	s_nop 0
	global_load_lds_dwordx4 v158, s[30:31]
	v_lshl_add_u64 v[202:203], v[230:231], 0, s[12:13]
	s_mov_b32 m0, s44
	s_nop 0
	global_load_lds_dwordx4 v[202:203], off
	v_lshl_add_u64 v[202:203], v[232:233], 0, s[12:13]
	s_mov_b32 m0, s45
	s_nop 0
	global_load_lds_dwordx4 v[202:203], off
	s_waitcnt vmcnt(8)
	s_waitcnt lgkmcnt(0)
	s_barrier
	s_setprio 1
	s_waitcnt lgkmcnt(0)
	v_mfma_f32_16x16x32_bf16 v[60:63], v[128:131], v[186:189], v[60:63]
	v_mfma_f32_16x16x32_bf16 v[56:59], v[136:139], v[186:189], v[56:59]
	v_mfma_f32_16x16x32_bf16 v[44:47], v[128:131], v[194:197], v[44:47]
	v_mfma_f32_16x16x32_bf16 v[40:43], v[136:139], v[194:197], v[40:43]
	v_mfma_f32_16x16x32_bf16 v[28:31], v[128:131], v[212:215], v[28:31]
	v_mfma_f32_16x16x32_bf16 v[24:27], v[136:139], v[212:215], v[24:27]
	v_mfma_f32_16x16x32_bf16 v[12:15], v[128:131], v[220:223], v[12:15]
	v_mfma_f32_16x16x32_bf16 v[8:11], v[136:139], v[220:223], v[8:11]
	v_mfma_f32_16x16x32_bf16 v[60:63], v[132:135], v[190:193], v[60:63]
	v_mfma_f32_16x16x32_bf16 v[56:59], v[140:143], v[190:193], v[56:59]
	v_mfma_f32_16x16x32_bf16 v[44:47], v[132:135], v[198:201], v[44:47]
	v_mfma_f32_16x16x32_bf16 v[40:43], v[140:143], v[198:201], v[40:43]
	v_mfma_f32_16x16x32_bf16 v[28:31], v[132:135], v[216:219], v[28:31]
	v_mfma_f32_16x16x32_bf16 v[24:27], v[140:143], v[216:219], v[24:27]
	v_mfma_f32_16x16x32_bf16 v[12:15], v[132:135], v[224:227], v[12:15]
	v_mfma_f32_16x16x32_bf16 v[8:11], v[140:143], v[224:227], v[8:11]
	s_setprio 0
	s_setprio 1
	v_mfma_f32_16x16x32_bf16 v[52:55], v[144:147], v[186:189], v[52:55]
	v_mfma_f32_16x16x32_bf16 v[48:51], v[178:181], v[186:189], v[48:51]
	v_mfma_f32_16x16x32_bf16 v[36:39], v[144:147], v[194:197], v[36:39]
	v_mfma_f32_16x16x32_bf16 v[32:35], v[178:181], v[194:197], v[32:35]
	v_mfma_f32_16x16x32_bf16 v[20:23], v[144:147], v[212:215], v[20:23]
	v_mfma_f32_16x16x32_bf16 v[16:19], v[178:181], v[212:215], v[16:19]
	v_mfma_f32_16x16x32_bf16 v[4:7], v[144:147], v[220:223], v[4:7]
	v_mfma_f32_16x16x32_bf16 v[0:3], v[178:181], v[220:223], v[0:3]
	v_mfma_f32_16x16x32_bf16 v[52:55], v[148:151], v[190:193], v[52:55]
	v_mfma_f32_16x16x32_bf16 v[48:51], v[182:185], v[190:193], v[48:51]
	v_mfma_f32_16x16x32_bf16 v[36:39], v[148:151], v[198:201], v[36:39]
	v_mfma_f32_16x16x32_bf16 v[32:35], v[182:185], v[198:201], v[32:35]
	v_mfma_f32_16x16x32_bf16 v[20:23], v[148:151], v[216:219], v[20:23]
	v_mfma_f32_16x16x32_bf16 v[16:19], v[182:185], v[216:219], v[16:19]
	v_mfma_f32_16x16x32_bf16 v[4:7], v[148:151], v[224:227], v[4:7]
	v_mfma_f32_16x16x32_bf16 v[0:3], v[182:185], v[224:227], v[0:3]
	s_setprio 0
	s_barrier
	s_add_i32 s60, s60, 2
	s_add_u32 s28, s28, 0x100
	s_addc_u32 s29, s29, 0
	s_add_u32 s58, s58, 0x100
	s_addc_u32 s59, s59, 0
	s_cmp_gt_u32 s60, 5
	s_cbranch_scc0 .LBB0_1146
	s_and_b64 vcc, exec, s[14:15]
	s_cbranch_vccz .LBB0_1149
	s_barrier

;     __device__ bool next(int i, Unit& u) const { if (r0 + i >= r1) return false; return base.next(r0 + i, u); }
;     __device__ bool next(int i, Unit& u) const { const int L = i * G + c; if (L >= 256) return false; u.pm = L; u.pn = L >> 3; return true; }
; #define PG8_STAGE(bufoff, gbase, voff) do { _Pragma("unroll") for (int _i = 0; _i < 2; ++_i) \
;         __builtin_amdgcn_global_load_lds((const unsigned*)((const char*)(gbase) + (voff)[_i]), (LAS unsigned*)(lds + (bufoff) + ldsw + _i * 8192), 16, 0, 0); } while (0)
; #define PG8_WAIT_V(n) asm volatile("s_waitcnt vmcnt(" #n ")" ::: "memory")
; #define PG8_BAR __builtin_amdgcn_s_barrier()
; template <class Epi, class Sched>
; __device__ __forceinline__ void gemm_phase(LAS unsigned char* lds, const Gemm g, const Sched& S, const Epi& E, int wave_id) {
;     ...
;     const int aoff = lds_byte(wr * 64 + fr, fq * 8), boff = lds_byte(wc * 32 + fr, fq * 8);
;     ...
;     Unit cur, nxt; int ui = 0;
;     if (!S.next(0, cur)) return;
;     f32x4 acc[2][2][4][2];
; #pragma unroll
;     for (int a = 0; a < 2; ++a)
; #pragma unroll
;         for (int b = 0; b < 2; ++b)
; #pragma unroll
;             for (int m = 0; m < 4; ++m)
; #pragma unroll
;                 for (int n = 0; n < 2; ++n) acc[a][b][m][n] = (f32x4){0.f, 0.f, 0.f, 0.f};
;     bf16x8 At[4][2], B0[2][2], B1[2][2];
;     const char* cA = (const char*)g.A + (size_t)cur.pm * tstepA; const char* cB = (const char*)g.Bt + (size_t)cur.pn * tstepB;
;     PG8_STAGE(PG8_SB(0, 0), cB, voffB); PG8_STAGE(PG8_SB(0, 1), cB + hstepB, voffB); PG8_STAGE(PG8_SA(0, 0), cA, voffA); PG8_STAGE(PG8_SA(0, 1), cA + hstepA, voffA);
;     if (wr == 1) PG8_BAR;
;     PG8_WAIT_V(2); PG8_BAR;
;     PG8_STAGE(PG8_SB(1, 0), cB + kstep, voffB); PG8_STAGE(PG8_SA(1, 0), cA + kstep, voffA); PG8_STAGE(PG8_SB(1, 1), cB + hstepB + kstep, voffB);
;     PG8_WAIT_V(6); PG8_BAR;
;     for (;;) {
;         const bool has_next = S.next(ui + 1, nxt);
;         const char* nA = has_next ? (const char*)g.A + (size_t)nxt.pm * tstepA : cA; const char* nB = has_next ? (const char*)g.Bt + (size_t)nxt.pn * tstepB : cB;
.LBB0_1241:
	s_mov_b64 s[16:17], 0x80
	s_add_i32 m0, s49, 0x18000
	v_lshl_add_u64 v[6:7], v[6:7], 0, s[16:17]
	s_waitcnt vmcnt(2)
	s_barrier
	global_load_lds_dwordx4 v[6:7], off
	v_lshl_add_u64 v[4:5], v[4:5], 0, s[16:17]
	s_add_i32 m0, s49, 0x1a000
	s_add_i32 s54, s49, 0x8000
	s_add_i32 s55, s49, 0xa000
	global_load_lds_dwordx4 v[4:5], off
	v_lshl_add_u64 v[0:1], v[0:1], 0, s[16:17]
	s_mov_b32 m0, s54
	s_add_u32 s6, s36, 0x40080
	global_load_lds_dwordx4 v[0:1], off
	v_lshl_add_u64 v[0:1], v[2:3], 0, s[16:17]
	s_mov_b32 m0, s55
	s_addc_u32 s7, s37, 0
	global_load_lds_dwordx4 v[0:1], off
	s_add_i32 m0, s49, 0x1c000
	s_nop 0
	global_load_lds_dwordx4 v146, s[6:7]
	v_lshl_add_u64 v[0:1], s[6:7], 0, v[150:151]
	s_add_i32 m0, s49, 0x1e000
	v_and_b32_e32 v176, 15, v8
	global_load_lds_dwordx4 v[0:1], off
	v_bfe_u32 v1, v8, 4, 2
	v_or_b32_e32 v2, s3, v176
	s_sext_i32_i8 s31, s4
	v_lshlrev_b32_e32 v3, 6, v2
	v_lshlrev_b32_e32 v4, 4, v1
	s_movk_i32 s4, 0x3c0
	v_lshlrev_b32_e32 v2, 2, v2
	v_lshrrev_b32_e32 v0, 4, v8
	v_and_or_b32 v3, v3, s4, v4
	v_and_b32_e32 v2, 32, v2
	v_lshlrev_b32_e32 v5, 2, v8
	v_bitop3_b32 v2, v3, s42, v2 bitop3:0xde
	v_lshl_or_b32 v3, v176, 6, v4
	v_and_b32_e32 v5, 32, v5
	s_cmpk_lt_u32 s80, 0x100
	v_bfe_u32 v0, v0, 1, 1
	v_bitop3_b32 v177, v3, s41, v5 bitop3:0xde
	s_cselect_b64 s[18:19], -1, 0
	s_lshl_b32 s20, s33, 6
	v_lshl_or_b32 v0, s33, 1, v0
	v_and_or_b32 v3, v4, 16, v176
	v_readlane_b32 s6, v255, 1
	v_lshlrev_b32_e32 v152, 4, v3
	v_mul_u32_u24_e32 v3, 0x210, v0
	v_lshlrev_b32_e32 v154, 11, v0
	v_cmp_eq_u32_e64 s[4:5], 0, v1
	v_readlane_b32 s7, v255, 2
	s_ashr_i32 s56, s6, 31
	v_or_b32_e32 v0, s20, v4
	v_mov_b32_e32 v1, v147
	v_lshlrev_b32_e32 v5, 14, v9
	s_mov_b32 s57, s6
	v_lshl_add_u64 v[158:159], s[92:93], 0, v[0:1]
	s_mov_b64 s[6:7], 0x3400000
	s_add_u32 s58, s92, 0xb400000
	v_and_b32_e32 v5, 0xffff8000, v5
	v_lshl_add_u64 v[160:161], v[158:159], 0, s[6:7]
	s_addc_u32 s59, s93, 0
	s_add_i32 s6, s40, 0
	v_lshl_add_u32 v5, v10, 11, v5
	v_and_b32_e32 v6, 1, v9
	s_add_i32 s6, s6, 0x20000
	v_lshl_or_b32 v5, v6, 6, v5
	s_add_i32 s7, s20, s6
	v_lshl_add_u32 v162, v11, 1, v5
	v_lshlrev_b32_e32 v5, 14, v12
	s_movk_i32 s21, 0x210
	v_mov_b32_e32 v0, s7
	v_and_b32_e32 v5, 0xffff8000, v5
	s_waitcnt vmcnt(6)
	v_mad_u32_u24 v0, v176, s21, v0
	s_add_u32 s20, s92, 0x1f440000
	v_lshl_add_u32 v5, v13, 11, v5
	v_and_b32_e32 v6, 1, v12
	v_add_u32_e32 v1, s6, v152
	s_addc_u32 s21, s93, 0
	v_lshl_or_b32 v5, v6, 6, v5
	s_add_i32 s60, 0, 0x10000
	s_add_i32 s61, 0, 0x14000
	v_add_u32_e32 v181, v0, v4
	v_mbcnt_lo_u32_b32 v0, -1, 0
	v_mov_b32_e32 v153, v147
	v_mov_b32_e32 v155, v147
	v_or_b32_e32 v156, 0x4000, v154
	v_mov_b32_e32 v157, v147
	v_mov_b32_e32 v163, v147
	v_lshl_add_u32 v164, v14, 1, v5
	v_mov_b32_e32 v165, v147
	v_mov_b64_e32 v[166:167], 0x200
	v_mov_b64_e32 v[168:169], 0x1ff
	v_add_u32_e32 v178, s60, v177
	v_add_u32_e32 v179, s61, v177
	v_add_u32_e32 v180, 0, v2
	s_mov_b32 s62, 0x3400000
	v_add_u32_e32 v182, v1, v3
	v_mbcnt_hi_u32_b32 v183, -1, v0
	s_barrier
	s_branch .LBB0_1244

;     __device__ bool next(int i, Unit& u) const { if (r0 + i >= r1) return false; return base.next(r0 + i, u); }
;     __device__ bool next(int i, Unit& u) const { const int L = i * G + c; if (L >= 256) return false; u.pm = L; u.pn = L >> 3; return true; }
; #define PG8_STAGE(bufoff, gbase, voff) do { _Pragma("unroll") for (int _i = 0; _i < 2; ++_i) \
;         __builtin_amdgcn_global_load_lds((const unsigned*)((const char*)(gbase) + (voff)[_i]), (LAS unsigned*)(lds + (bufoff) + ldsw + _i * 8192), 16, 0, 0); } while (0)
; #define PG8_WAIT_V(n) asm volatile("s_waitcnt vmcnt(" #n ")" ::: "memory")
; template <class Epi, class Sched>
; __device__ __forceinline__ void gemm_phase(LAS unsigned char* lds, const Gemm g, const Sched& S, const Epi& E, int wave_id) {
;     ...
;         const bool has_next = S.next(ui + 1, nxt);
;         const char* nA = has_next ? (const char*)g.A + (size_t)nxt.pm * tstepA : cA; const char* nB = has_next ? (const char*)g.Bt + (size_t)nxt.pn * tstepB : cB;
;         for (int t = 0; t < nt; t += 2) {
;             const bool last = (t == nt - 2);
;             const char* a1 = cA + (size_t)(t + 1) * kstep;
;             const char* a2 = last ? nA : cA + (size_t)(t + 2) * kstep; const char* b2 = last ? nB : cB + (size_t)(t + 2) * kstep;
;             const char* a3 = a2 + kstep; const char* b3 = b2 + kstep;
;             PG8_LDB(B0, 0, 0); PG8_LDB(B1, 0, 1); PG8_SCHED; PG8_LDA(At, 0, 0); PG8_STAGE(PG8_SA(1, 1), a1 + hstepA, voffA);
;             PG8_WAIT_V(8); PG8_WAIT_L(0); PG8_BAR; PG8_MMA(0, 0, At, B0); PG8_MMA(0, 1, At, B1); PG8_BAR; PG8_SCHED;
;             PG8_LDA(At, 0, 1); PG8_STAGE(PG8_SB(0, 0), b2, voffB); PG8_STAGE(PG8_SB(0, 1), b2 + hstepB, voffB); PG8_STAGE(PG8_SA(0, 0), a2, voffA);
;             PG8_WAIT_V(8); PG8_WAIT_L(0); PG8_BAR; PG8_MMA(1, 0, At, B0); PG8_MMA(1, 1, At, B1); PG8_BAR; PG8_SCHED;
;             PG8_LDB(B0, 1, 0); PG8_LDB(B1, 1, 1); PG8_SCHED; PG8_LDA(At, 1, 0); PG8_STAGE(PG8_SA(0, 1), a2 + hstepA, voffA);
;             PG8_WAIT_V(8); PG8_WAIT_L(0); PG8_BAR; PG8_MMA(0, 0, At, B0); PG8_MMA(0, 1, At, B1); PG8_BAR; PG8_SCHED;
;             PG8_LDA(At, 1, 1); PG8_STAGE(PG8_SB(1, 0), b3, voffB); PG8_STAGE(PG8_SB(1, 1), b3 + hstepB, voffB); PG8_STAGE(PG8_SA(1, 0), a3, voffA);
;             PG8_WAIT_V(8); PG8_WAIT_L(0); PG8_BAR; PG8_MMA(1, 0, At, B0); PG8_MMA(1, 1, At, B1); PG8_BAR; PG8_SCHED;
.LBB0_1250:
	s_ashr_i32 s25, s24, 31
	s_lshl_b64 s[26:27], s[24:25], 19
	s_add_u32 s26, s45, s26
	s_addc_u32 s27, s46, s27
	s_and_b64 s[28:29], s[6:7], exec
	s_cselect_b32 s25, s27, s35
	s_cselect_b32 s63, s26, s34
	s_ashr_i32 s23, s22, 31
	s_lshl_b64 s[28:29], s[22:23], 19
	s_add_u32 s28, s47, s28
	s_addc_u32 s29, s48, s29
	s_and_b64 s[38:39], s[6:7], exec
	s_cselect_b32 s23, s29, s37
	s_cselect_b32 s64, s28, s36
	s_add_u32 s34, s34, 0x40080
	s_addc_u32 s35, s35, 0
	s_add_u32 s65, s36, 0x100
	s_addc_u32 s66, s37, 0
	s_mov_b32 s67, -2
	s_waitcnt lgkmcnt(0)
	s_waitcnt vmcnt(0)
	ds_read_b128 v[128:131], v178
	ds_read_b128 v[132:135], v178 offset:1024
	ds_read_b128 v[136:139], v178 offset:2048
	ds_read_b128 v[140:143], v178 offset:3072
	ds_read_b128 v[170:173], v179
	ds_read_b128 v[184:187], v179 offset:1024
	ds_read_b128 v[188:191], v179 offset:2048
	ds_read_b128 v[192:195], v179 offset:3072
	s_add_u32 s36, s34, 0xfffc0080
	s_addc_u32 s37, s35, -1
	s_cmp_eq_u32 s67, 12
	s_cselect_b32 s39, s25, s37
	s_cselect_b32 s38, s63, s36
	s_cselect_b32 s37, s23, s66
	s_cselect_b32 s36, s64, s65
	s_add_i32 m0, s49, 0xc000
	ds_read_b128 v[196:199], v180
	ds_read_b128 v[200:203], v180 offset:1024
	ds_read_b128 v[204:207], v180 offset:2048
	ds_read_b128 v[208:211], v180 offset:3072
	ds_read_b128 v[212:215], v180 offset:4096
	ds_read_b128 v[216:219], v180 offset:5120
	ds_read_b128 v[220:223], v180 offset:6144
	ds_read_b128 v[224:227], v180 offset:7168
	global_load_lds_dwordx4 v162, s[34:35]
	s_add_i32 m0, s49, 0xe000
	s_nop 0
	global_load_lds_dwordx4 v164, s[34:35]
	s_waitcnt vmcnt(8)
	s_waitcnt lgkmcnt(0)
	s_barrier
	s_setprio 1
	s_waitcnt lgkmcnt(0)
	v_mfma_f32_16x16x32_bf16 v[124:127], v[128:131], v[196:199], 0
	v_mfma_f32_16x16x32_bf16 v[120:123], v[136:139], v[196:199], 0
	v_mfma_f32_16x16x32_bf16 v[108:111], v[128:131], v[204:207], 0
	v_mfma_f32_16x16x32_bf16 v[104:107], v[136:139], v[204:207], 0
	v_mfma_f32_16x16x32_bf16 v[92:95], v[128:131], v[212:215], 0
	v_mfma_f32_16x16x32_bf16 v[88:91], v[136:139], v[212:215], 0
	v_mfma_f32_16x16x32_bf16 v[76:79], v[128:131], v[220:223], 0
	v_mfma_f32_16x16x32_bf16 v[72:75], v[136:139], v[220:223], 0
	v_mfma_f32_16x16x32_bf16 v[124:127], v[132:135], v[200:203], v[124:127]
	v_mfma_f32_16x16x32_bf16 v[120:123], v[140:143], v[200:203], v[120:123]
	v_mfma_f32_16x16x32_bf16 v[108:111], v[132:135], v[208:211], v[108:111]
	v_mfma_f32_16x16x32_bf16 v[104:107], v[140:143], v[208:211], v[104:107]
	v_mfma_f32_16x16x32_bf16 v[92:95], v[132:135], v[216:219], v[92:95]
	v_mfma_f32_16x16x32_bf16 v[88:91], v[140:143], v[216:219], v[88:91]
	v_mfma_f32_16x16x32_bf16 v[76:79], v[132:135], v[224:227], v[76:79]
	v_mfma_f32_16x16x32_bf16 v[72:75], v[140:143], v[224:227], v[72:75]
	s_setprio 0
	s_setprio 1
	v_mfma_f32_16x16x32_bf16 v[116:119], v[170:173], v[196:199], 0
	v_mfma_f32_16x16x32_bf16 v[112:115], v[188:191], v[196:199], 0
	v_mfma_f32_16x16x32_bf16 v[100:103], v[170:173], v[204:207], 0
	v_mfma_f32_16x16x32_bf16 v[96:99], v[188:191], v[204:207], 0
	v_mfma_f32_16x16x32_bf16 v[84:87], v[170:173], v[212:215], 0
	v_mfma_f32_16x16x32_bf16 v[80:83], v[188:191], v[212:215], 0
	v_mfma_f32_16x16x32_bf16 v[68:71], v[170:173], v[220:223], 0
	v_mfma_f32_16x16x32_bf16 v[64:67], v[188:191], v[220:223], 0
	v_mfma_f32_16x16x32_bf16 v[116:119], v[184:187], v[200:203], v[116:119]
	v_mfma_f32_16x16x32_bf16 v[112:115], v[192:195], v[200:203], v[112:115]
	v_mfma_f32_16x16x32_bf16 v[100:103], v[184:187], v[208:211], v[100:103]
	v_mfma_f32_16x16x32_bf16 v[96:99], v[192:195], v[208:211], v[96:99]
	v_mfma_f32_16x16x32_bf16 v[84:87], v[184:187], v[216:219], v[84:87]
	v_mfma_f32_16x16x32_bf16 v[80:83], v[192:195], v[216:219], v[80:83]
	v_mfma_f32_16x16x32_bf16 v[68:71], v[184:187], v[224:227], v[68:71]
	v_mfma_f32_16x16x32_bf16 v[64:67], v[192:195], v[224:227], v[64:67]
	s_setprio 0
	s_barrier
	s_add_i32 s72, s60, s2
	v_lshl_add_u64 v[174:175], s[36:37], 0, v[146:147]
	s_mov_b32 m0, s72
	ds_read_b128 v[196:199], v180 offset:16384
	ds_read_b128 v[200:203], v180 offset:17408
	ds_read_b128 v[204:207], v180 offset:18432
	ds_read_b128 v[208:211], v180 offset:19456
	ds_read_b128 v[212:215], v180 offset:20480
	ds_read_b128 v[216:219], v180 offset:21504
	ds_read_b128 v[220:223], v180 offset:22528
	ds_read_b128 v[224:227], v180 offset:23552
	global_load_lds_dwordx4 v[174:175], off
	s_add_i32 m0, s72, 0x2000
	s_add_u32 s72, s36, 0x40000
	v_lshl_add_u64 v[228:229], s[36:37], 0, v[150:151]
	s_addc_u32 s73, s37, 0
	s_add_i32 s74, s61, s2
	global_load_lds_dwordx4 v[228:229], off
	s_mov_b32 m0, s74
	v_lshl_add_u64 v[232:233], s[38:39], 0, v[148:149]
	global_load_lds_dwordx4 v146, s[72:73]
	s_add_i32 m0, s74, 0x2000
	s_nop 0
	global_load_lds_dwordx4 v150, s[72:73]
	v_lshl_add_u64 v[230:231], s[38:39], 0, v[144:145]
	s_mov_b32 m0, s49
	s_nop 0
	global_load_lds_dwordx4 v[230:231], off
	s_mov_b32 m0, s50
	s_nop 0
	global_load_lds_dwordx4 v[232:233], off
	s_waitcnt vmcnt(8)
	s_waitcnt lgkmcnt(0)
	s_barrier
; #define PG8_STAGE(bufoff, gbase, voff) do { _Pragma("unroll") for (int _i = 0; _i < 2; ++_i) \
;         __builtin_amdgcn_global_load_lds((const unsigned*)((const char*)(gbase) + (voff)[_i]), (LAS unsigned*)(lds + (bufoff) + ldsw + _i * 8192), 16, 0, 0); } while (0)
; #define PG8_LDA(dst, b, h) do { _Pragma("unroll") for (int m = 0; m < 4; ++m) _Pragma("unroll") for (int k = 0; k < 2; ++k) dst[m][k] = *(const LAS bf16x8*)(lds + PG8_SA(b, h) + aoff + m * 2048 + k * 1024); } while (0)
; #define PG8_LDB(dst, b, h) do { _Pragma("unroll") for (int n = 0; n < 2; ++n) _Pragma("unroll") for (int k = 0; k < 2; ++k) dst[n][k] = *(const LAS bf16x8*)(lds + PG8_SB(b, h) + boff + n * 2048 + k * 1024); } while (0)
; #define PG8_MMA(ai, bj, At, Bt) do { __builtin_amdgcn_s_setprio(1); _Pragma("unroll") for (int m = 0; m < 4; ++m) _Pragma("unroll") for (int n = 0; n < 2; ++n) _Pragma("unroll") for (int k = 0; k < 2; ++k) \
;         acc[ai][bj][m][n] = __builtin_amdgcn_mfma_f32_16x16x32_bf16(Bt[n][k], At[m][k], acc[ai][bj][m][n], 0, 0, 0); __builtin_amdgcn_s_setprio(0); } while (0)
; #define PG8_WAIT_V(n) asm volatile("s_waitcnt vmcnt(" #n ")" ::: "memory")
; #define PG8_WAIT_L(n) asm volatile("s_waitcnt lgkmcnt(" #n ")" ::: "memory")
; #define PG8_BAR __builtin_amdgcn_s_barrier()
; #define PG8_SCHED __builtin_amdgcn_sched_barrier(0)
; template <class Epi, class Sched>
; __device__ __forceinline__ void gemm_phase(LAS unsigned char* lds, const Gemm g, const Sched& S, const Epi& E, int wave_id) {
;     ...
;             PG8_LDB(B0, 0, 0); PG8_LDB(B1, 0, 1); PG8_SCHED; PG8_LDA(At, 0, 0); PG8_STAGE(PG8_SA(1, 1), a1 + hstepA, voffA);
;             PG8_WAIT_V(8); PG8_WAIT_L(0); PG8_BAR; PG8_MMA(0, 0, At, B0); PG8_MMA(0, 1, At, B1); PG8_BAR; PG8_SCHED;
;             PG8_LDA(At, 0, 1); PG8_STAGE(PG8_SB(0, 0), b2, voffB); PG8_STAGE(PG8_SB(0, 1), b2 + hstepB, voffB); PG8_STAGE(PG8_SA(0, 0), a2, voffA);
;             PG8_WAIT_V(8); PG8_WAIT_L(0); PG8_BAR; PG8_MMA(1, 0, At, B0); PG8_MMA(1, 1, At, B1); PG8_BAR; PG8_SCHED;
;             PG8_LDB(B0, 1, 0); PG8_LDB(B1, 1, 1); PG8_SCHED; PG8_LDA(At, 1, 0); PG8_STAGE(PG8_SA(0, 1), a2 + hstepA, voffA);
;             PG8_WAIT_V(8); PG8_WAIT_L(0); PG8_BAR; PG8_MMA(0, 0, At, B0); PG8_MMA(0, 1, At, B1); PG8_BAR; PG8_SCHED;
	s_setprio 1
	s_waitcnt lgkmcnt(0)
	v_mfma_f32_16x16x32_bf16 v[60:63], v[128:131], v[196:199], 0
	v_mfma_f32_16x16x32_bf16 v[56:59], v[136:139], v[196:199], 0
	v_mfma_f32_16x16x32_bf16 v[44:47], v[128:131], v[204:207], 0
	v_mfma_f32_16x16x32_bf16 v[40:43], v[136:139], v[204:207], 0
	v_mfma_f32_16x16x32_bf16 v[28:31], v[128:131], v[212:215], 0
	v_mfma_f32_16x16x32_bf16 v[24:27], v[136:139], v[212:215], 0
	v_mfma_f32_16x16x32_bf16 v[12:15], v[128:131], v[220:223], 0
	v_mfma_f32_16x16x32_bf16 v[8:11], v[136:139], v[220:223], 0
	v_mfma_f32_16x16x32_bf16 v[60:63], v[132:135], v[200:203], v[60:63]
	v_mfma_f32_16x16x32_bf16 v[56:59], v[140:143], v[200:203], v[56:59]
	v_mfma_f32_16x16x32_bf16 v[44:47], v[132:135], v[208:211], v[44:47]
	v_mfma_f32_16x16x32_bf16 v[40:43], v[140:143], v[208:211], v[40:43]
	v_mfma_f32_16x16x32_bf16 v[28:31], v[132:135], v[216:219], v[28:31]
	v_mfma_f32_16x16x32_bf16 v[24:27], v[140:143], v[216:219], v[24:27]
	v_mfma_f32_16x16x32_bf16 v[12:15], v[132:135], v[224:227], v[12:15]
	v_mfma_f32_16x16x32_bf16 v[8:11], v[140:143], v[224:227], v[8:11]
	s_setprio 0
	s_setprio 1
	v_mfma_f32_16x16x32_bf16 v[52:55], v[170:173], v[196:199], 0
	v_mfma_f32_16x16x32_bf16 v[48:51], v[188:191], v[196:199], 0
	v_mfma_f32_16x16x32_bf16 v[36:39], v[170:173], v[204:207], 0
	v_mfma_f32_16x16x32_bf16 v[32:35], v[188:191], v[204:207], 0
	v_mfma_f32_16x16x32_bf16 v[20:23], v[170:173], v[212:215], 0
	v_mfma_f32_16x16x32_bf16 v[16:19], v[188:191], v[212:215], 0
	v_mfma_f32_16x16x32_bf16 v[4:7], v[170:173], v[220:223], 0
	v_mfma_f32_16x16x32_bf16 v[0:3], v[188:191], v[220:223], 0
	v_mfma_f32_16x16x32_bf16 v[52:55], v[184:187], v[200:203], v[52:55]
	v_mfma_f32_16x16x32_bf16 v[48:51], v[192:195], v[200:203], v[48:51]
	v_mfma_f32_16x16x32_bf16 v[36:39], v[184:187], v[208:211], v[36:39]
	v_mfma_f32_16x16x32_bf16 v[32:35], v[192:195], v[208:211], v[32:35]
	v_mfma_f32_16x16x32_bf16 v[20:23], v[184:187], v[216:219], v[20:23]
	v_mfma_f32_16x16x32_bf16 v[16:19], v[192:195], v[216:219], v[16:19]
	v_mfma_f32_16x16x32_bf16 v[4:7], v[184:187], v[224:227], v[4:7]
	v_mfma_f32_16x16x32_bf16 v[0:3], v[192:195], v[224:227], v[0:3]
	s_setprio 0
	s_barrier
	s_add_i32 s72, 0, 0x18000
	s_add_i32 s73, 0, 0x1c000
	v_add_u32_e32 v140, s72, v177
	v_add_u32_e32 v192, s73, v177
	ds_read_b128 v[128:131], v140
	ds_read_b128 v[132:135], v140 offset:1024
	ds_read_b128 v[136:139], v140 offset:2048
	ds_read_b128 v[140:143], v140 offset:3072
	ds_read_b128 v[170:173], v192
	ds_read_b128 v[184:187], v192 offset:1024
	ds_read_b128 v[188:191], v192 offset:2048
	ds_read_b128 v[192:195], v192 offset:3072
	s_add_u32 s38, s38, 0x40000
	s_addc_u32 s39, s39, 0
	s_mov_b32 m0, s51
	ds_read_b128 v[196:199], v180 offset:32768
	ds_read_b128 v[200:203], v180 offset:33792
	ds_read_b128 v[204:207], v180 offset:34816
	ds_read_b128 v[208:211], v180 offset:35840
	ds_read_b128 v[212:215], v180 offset:36864
	ds_read_b128 v[216:219], v180 offset:37888
	ds_read_b128 v[220:223], v180 offset:38912
	ds_read_b128 v[224:227], v180 offset:39936
	global_load_lds_dwordx4 v144, s[38:39]
	s_mov_b32 m0, s52
	s_nop 0
	global_load_lds_dwordx4 v148, s[38:39]
	s_waitcnt vmcnt(8)
	s_waitcnt lgkmcnt(0)
	s_barrier
	s_setprio 1
	s_waitcnt lgkmcnt(0)
	v_mfma_f32_16x16x32_bf16 v[124:127], v[128:131], v[196:199], v[124:127]
	v_mfma_f32_16x16x32_bf16 v[120:123], v[136:139], v[196:199], v[120:123]
	v_mfma_f32_16x16x32_bf16 v[108:111], v[128:131], v[204:207], v[108:111]
	v_mfma_f32_16x16x32_bf16 v[104:107], v[136:139], v[204:207], v[104:107]
	v_mfma_f32_16x16x32_bf16 v[92:95], v[128:131], v[212:215], v[92:95]
	v_mfma_f32_16x16x32_bf16 v[88:91], v[136:139], v[212:215], v[88:91]
	v_mfma_f32_16x16x32_bf16 v[76:79], v[128:131], v[220:223], v[76:79]
	v_mfma_f32_16x16x32_bf16 v[72:75], v[136:139], v[220:223], v[72:75]
	v_mfma_f32_16x16x32_bf16 v[124:127], v[132:135], v[200:203], v[124:127]
	v_mfma_f32_16x16x32_bf16 v[120:123], v[140:143], v[200:203], v[120:123]
	v_mfma_f32_16x16x32_bf16 v[108:111], v[132:135], v[208:211], v[108:111]
	v_mfma_f32_16x16x32_bf16 v[104:107], v[140:143], v[208:211], v[104:107]
	v_mfma_f32_16x16x32_bf16 v[92:95], v[132:135], v[216:219], v[92:95]
	v_mfma_f32_16x16x32_bf16 v[88:91], v[140:143], v[216:219], v[88:91]
	v_mfma_f32_16x16x32_bf16 v[76:79], v[132:135], v[224:227], v[76:79]
	v_mfma_f32_16x16x32_bf16 v[72:75], v[140:143], v[224:227], v[72:75]
	s_setprio 0
	s_setprio 1
	v_mfma_f32_16x16x32_bf16 v[116:119], v[170:173], v[196:199], v[116:119]
	v_mfma_f32_16x16x32_bf16 v[112:115], v[188:191], v[196:199], v[112:115]
	v_mfma_f32_16x16x32_bf16 v[100:103], v[170:173], v[204:207], v[100:103]
	v_mfma_f32_16x16x32_bf16 v[96:99], v[188:191], v[204:207], v[96:99]
	v_mfma_f32_16x16x32_bf16 v[84:87], v[170:173], v[212:215], v[84:87]
	v_mfma_f32_16x16x32_bf16 v[80:83], v[188:191], v[212:215], v[80:83]
	v_mfma_f32_16x16x32_bf16 v[68:71], v[170:173], v[220:223], v[68:71]
	v_mfma_f32_16x16x32_bf16 v[64:67], v[188:191], v[220:223], v[64:67]
	v_mfma_f32_16x16x32_bf16 v[116:119], v[184:187], v[200:203], v[116:119]
	v_mfma_f32_16x16x32_bf16 v[112:115], v[192:195], v[200:203], v[112:115]
	v_mfma_f32_16x16x32_bf16 v[100:103], v[184:187], v[208:211], v[100:103]
	v_mfma_f32_16x16x32_bf16 v[96:99], v[192:195], v[208:211], v[96:99]
	v_mfma_f32_16x16x32_bf16 v[84:87], v[184:187], v[216:219], v[84:87]
	v_mfma_f32_16x16x32_bf16 v[80:83], v[192:195], v[216:219], v[80:83]
	v_mfma_f32_16x16x32_bf16 v[68:71], v[184:187], v[224:227], v[68:71]
	v_mfma_f32_16x16x32_bf16 v[64:67], v[192:195], v[224:227], v[64:67]
	s_setprio 0
	s_barrier
; #define PG8_STAGE(bufoff, gbase, voff) do { _Pragma("unroll") for (int _i = 0; _i < 2; ++_i) \
;         __builtin_amdgcn_global_load_lds((const unsigned*)((const char*)(gbase) + (voff)[_i]), (LAS unsigned*)(lds + (bufoff) + ldsw + _i * 8192), 16, 0, 0); } while (0)
; #define PG8_LDA(dst, b, h) do { _Pragma("unroll") for (int m = 0; m < 4; ++m) _Pragma("unroll") for (int k = 0; k < 2; ++k) dst[m][k] = *(const LAS bf16x8*)(lds + PG8_SA(b, h) + aoff + m * 2048 + k * 1024); } while (0)
; #define PG8_MMA(ai, bj, At, Bt) do { __builtin_amdgcn_s_setprio(1); _Pragma("unroll") for (int m = 0; m < 4; ++m) _Pragma("unroll") for (int n = 0; n < 2; ++n) _Pragma("unroll") for (int k = 0; k < 2; ++k) \
;         acc[ai][bj][m][n] = __builtin_amdgcn_mfma_f32_16x16x32_bf16(Bt[n][k], At[m][k], acc[ai][bj][m][n], 0, 0, 0); __builtin_amdgcn_s_setprio(0); } while (0)
; #define PG8_WAIT_V(n) asm volatile("s_waitcnt vmcnt(" #n ")" ::: "memory")
; #define PG8_WAIT_L(n) asm volatile("s_waitcnt lgkmcnt(" #n ")" ::: "memory")
; #define PG8_BAR __builtin_amdgcn_s_barrier()
; #define PG8_SCHED __builtin_amdgcn_sched_barrier(0)
; template <class Epi, class Sched>
; __device__ __forceinline__ void gemm_phase(LAS unsigned char* lds, const Gemm g, const Sched& S, const Epi& E, int wave_id) {
;     ...
;             PG8_WAIT_V(8); PG8_WAIT_L(0); PG8_BAR; PG8_MMA(0, 0, At, B0); PG8_MMA(0, 1, At, B1); PG8_BAR; PG8_SCHED;
;             PG8_LDA(At, 1, 1); PG8_STAGE(PG8_SB(1, 0), b3, voffB); PG8_STAGE(PG8_SB(1, 1), b3 + hstepB, voffB); PG8_STAGE(PG8_SA(1, 0), a3, voffA);
;             PG8_WAIT_V(8); PG8_WAIT_L(0); PG8_BAR; PG8_MMA(1, 0, At, B0); PG8_MMA(1, 1, At, B1); PG8_BAR; PG8_SCHED;
	s_add_i32 s38, s72, s2
	v_lshl_add_u64 v[174:175], v[174:175], 0, s[16:17]
	s_mov_b32 m0, s38
	ds_read_b128 v[196:199], v180 offset:49152
	ds_read_b128 v[200:203], v180 offset:50176
	ds_read_b128 v[204:207], v180 offset:51200
	ds_read_b128 v[208:211], v180 offset:52224
	ds_read_b128 v[212:215], v180 offset:53248
	ds_read_b128 v[216:219], v180 offset:54272
	ds_read_b128 v[220:223], v180 offset:55296
	ds_read_b128 v[224:227], v180 offset:56320
	global_load_lds_dwordx4 v[174:175], off
	s_add_i32 m0, s38, 0x2000
	s_add_u32 s36, s36, 0x40080
	v_lshl_add_u64 v[174:175], v[228:229], 0, s[16:17]
	s_addc_u32 s37, s37, 0
	s_add_i32 s38, s73, s2
	global_load_lds_dwordx4 v[174:175], off
	s_mov_b32 m0, s38
	s_nop 0
	global_load_lds_dwordx4 v146, s[36:37]
	s_add_i32 m0, s38, 0x2000
	s_nop 0
	global_load_lds_dwordx4 v150, s[36:37]
	v_lshl_add_u64 v[174:175], v[230:231], 0, s[16:17]
	s_mov_b32 m0, s54
	s_nop 0
	global_load_lds_dwordx4 v[174:175], off
	v_lshl_add_u64 v[174:175], v[232:233], 0, s[16:17]
	s_mov_b32 m0, s55
	s_nop 0
	global_load_lds_dwordx4 v[174:175], off
	s_waitcnt vmcnt(8)
	s_waitcnt lgkmcnt(0)
	s_barrier
	s_setprio 1
	s_waitcnt lgkmcnt(0)
	v_mfma_f32_16x16x32_bf16 v[60:63], v[128:131], v[196:199], v[60:63]
	v_mfma_f32_16x16x32_bf16 v[56:59], v[136:139], v[196:199], v[56:59]
	v_mfma_f32_16x16x32_bf16 v[44:47], v[128:131], v[204:207], v[44:47]
	v_mfma_f32_16x16x32_bf16 v[40:43], v[136:139], v[204:207], v[40:43]
	v_mfma_f32_16x16x32_bf16 v[28:31], v[128:131], v[212:215], v[28:31]
	v_mfma_f32_16x16x32_bf16 v[24:27], v[136:139], v[212:215], v[24:27]
	v_mfma_f32_16x16x32_bf16 v[12:15], v[128:131], v[220:223], v[12:15]
	v_mfma_f32_16x16x32_bf16 v[8:11], v[136:139], v[220:223], v[8:11]
	v_mfma_f32_16x16x32_bf16 v[60:63], v[132:135], v[200:203], v[60:63]
	v_mfma_f32_16x16x32_bf16 v[56:59], v[140:143], v[200:203], v[56:59]
	v_mfma_f32_16x16x32_bf16 v[44:47], v[132:135], v[208:211], v[44:47]
	v_mfma_f32_16x16x32_bf16 v[40:43], v[140:143], v[208:211], v[40:43]
	v_mfma_f32_16x16x32_bf16 v[28:31], v[132:135], v[216:219], v[28:31]
	v_mfma_f32_16x16x32_bf16 v[24:27], v[140:143], v[216:219], v[24:27]
	v_mfma_f32_16x16x32_bf16 v[12:15], v[132:135], v[224:227], v[12:15]
	v_mfma_f32_16x16x32_bf16 v[8:11], v[140:143], v[224:227], v[8:11]
	s_setprio 0
	s_setprio 1
	v_mfma_f32_16x16x32_bf16 v[52:55], v[170:173], v[196:199], v[52:55]
	v_mfma_f32_16x16x32_bf16 v[48:51], v[188:191], v[196:199], v[48:51]
	v_mfma_f32_16x16x32_bf16 v[36:39], v[170:173], v[204:207], v[36:39]
	v_mfma_f32_16x16x32_bf16 v[32:35], v[188:191], v[204:207], v[32:35]
	v_mfma_f32_16x16x32_bf16 v[20:23], v[170:173], v[212:215], v[20:23]
	v_mfma_f32_16x16x32_bf16 v[16:19], v[188:191], v[212:215], v[16:19]
	v_mfma_f32_16x16x32_bf16 v[4:7], v[170:173], v[220:223], v[4:7]
	v_mfma_f32_16x16x32_bf16 v[0:3], v[188:191], v[220:223], v[0:3]
	v_mfma_f32_16x16x32_bf16 v[52:55], v[184:187], v[200:203], v[52:55]
	v_mfma_f32_16x16x32_bf16 v[48:51], v[192:195], v[200:203], v[48:51]
	v_mfma_f32_16x16x32_bf16 v[36:39], v[184:187], v[208:211], v[36:39]
	v_mfma_f32_16x16x32_bf16 v[32:35], v[192:195], v[208:211], v[32:35]
	v_mfma_f32_16x16x32_bf16 v[20:23], v[184:187], v[216:219], v[20:23]
	v_mfma_f32_16x16x32_bf16 v[16:19], v[192:195], v[216:219], v[16:19]
	v_mfma_f32_16x16x32_bf16 v[4:7], v[184:187], v[224:227], v[4:7]
	v_mfma_f32_16x16x32_bf16 v[0:3], v[192:195], v[224:227], v[0:3]
	s_setprio 0
	s_barrier
	s_add_i32 s67, s67, 2
	s_add_u32 s34, s34, 0x100
	s_addc_u32 s35, s35, 0
	s_add_u32 s65, s65, 0x100
	s_addc_u32 s66, s66, 0
	s_cmp_gt_u32 s67, 13
.LBB0_1251:
	ds_read_b128 v[128:131], v178
	ds_read_b128 v[132:135], v178 offset:1024
	ds_read_b128 v[136:139], v178 offset:2048
	ds_read_b128 v[140:143], v178 offset:3072
	ds_read_b128 v[170:173], v179
	ds_read_b128 v[184:187], v179 offset:1024
	ds_read_b128 v[188:191], v179 offset:2048
	ds_read_b128 v[192:195], v179 offset:3072
	s_add_u32 s36, s34, 0xfffc0080
	s_addc_u32 s37, s35, -1
	s_cmp_eq_u32 s67, 12
	s_cselect_b32 s39, s25, s37
	s_cselect_b32 s38, s63, s36
	s_cselect_b32 s37, s23, s66
	s_cselect_b32 s36, s64, s65
	s_add_i32 m0, s49, 0xc000
	ds_read_b128 v[196:199], v180
	ds_read_b128 v[200:203], v180 offset:1024
	ds_read_b128 v[204:207], v180 offset:2048
	ds_read_b128 v[208:211], v180 offset:3072
	ds_read_b128 v[212:215], v180 offset:4096
	ds_read_b128 v[216:219], v180 offset:5120
	ds_read_b128 v[220:223], v180 offset:6144
	ds_read_b128 v[224:227], v180 offset:7168
	global_load_lds_dwordx4 v162, s[34:35]
	s_add_i32 m0, s49, 0xe000
	s_nop 0
	global_load_lds_dwordx4 v164, s[34:35]
	s_waitcnt vmcnt(8)
	s_waitcnt lgkmcnt(0)
	s_barrier
; #define PG8_STAGE(bufoff, gbase, voff) do { _Pragma("unroll") for (int _i = 0; _i < 2; ++_i) \
;         __builtin_amdgcn_global_load_lds((const unsigned*)((const char*)(gbase) + (voff)[_i]), (LAS unsigned*)(lds + (bufoff) + ldsw + _i * 8192), 16, 0, 0); } while (0)
; #define PG8_LDA(dst, b, h) do { _Pragma("unroll") for (int m = 0; m < 4; ++m) _Pragma("unroll") for (int k = 0; k < 2; ++k) dst[m][k] = *(const LAS bf16x8*)(lds + PG8_SA(b, h) + aoff + m * 2048 + k * 1024); } while (0)
; #define PG8_LDB(dst, b, h) do { _Pragma("unroll") for (int n = 0; n < 2; ++n) _Pragma("unroll") for (int k = 0; k < 2; ++k) dst[n][k] = *(const LAS bf16x8*)(lds + PG8_SB(b, h) + boff + n * 2048 + k * 1024); } while (0)
; #define PG8_MMA(ai, bj, At, Bt) do { __builtin_amdgcn_s_setprio(1); _Pragma("unroll") for (int m = 0; m < 4; ++m) _Pragma("unroll") for (int n = 0; n < 2; ++n) _Pragma("unroll") for (int k = 0; k < 2; ++k) \
;         acc[ai][bj][m][n] = __builtin_amdgcn_mfma_f32_16x16x32_bf16(Bt[n][k], At[m][k], acc[ai][bj][m][n], 0, 0, 0); __builtin_amdgcn_s_setprio(0); } while (0)
; #define PG8_WAIT_V(n) asm volatile("s_waitcnt vmcnt(" #n ")" ::: "memory")
; #define PG8_WAIT_L(n) asm volatile("s_waitcnt lgkmcnt(" #n ")" ::: "memory")
; #define PG8_BAR __builtin_amdgcn_s_barrier()
; #define PG8_SCHED __builtin_amdgcn_sched_barrier(0)
; template <class Epi, class Sched>
; __device__ __forceinline__ void gemm_phase(LAS unsigned char* lds, const Gemm g, const Sched& S, const Epi& E, int wave_id) {
;     ...
;             PG8_LDB(B0, 0, 0); PG8_LDB(B1, 0, 1); PG8_SCHED; PG8_LDA(At, 0, 0); PG8_STAGE(PG8_SA(1, 1), a1 + hstepA, voffA);
;             PG8_WAIT_V(8); PG8_WAIT_L(0); PG8_BAR; PG8_MMA(0, 0, At, B0); PG8_MMA(0, 1, At, B1); PG8_BAR; PG8_SCHED;
;             PG8_LDA(At, 0, 1); PG8_STAGE(PG8_SB(0, 0), b2, voffB); PG8_STAGE(PG8_SB(0, 1), b2 + hstepB, voffB); PG8_STAGE(PG8_SA(0, 0), a2, voffA);
;             PG8_WAIT_V(8); PG8_WAIT_L(0); PG8_BAR; PG8_MMA(1, 0, At, B0); PG8_MMA(1, 1, At, B1); PG8_BAR; PG8_SCHED;
	s_setprio 1
	s_waitcnt lgkmcnt(0)
	v_mfma_f32_16x16x32_bf16 v[124:127], v[128:131], v[196:199], v[124:127]
	v_mfma_f32_16x16x32_bf16 v[120:123], v[136:139], v[196:199], v[120:123]
	v_mfma_f32_16x16x32_bf16 v[108:111], v[128:131], v[204:207], v[108:111]
	v_mfma_f32_16x16x32_bf16 v[104:107], v[136:139], v[204:207], v[104:107]
	v_mfma_f32_16x16x32_bf16 v[92:95], v[128:131], v[212:215], v[92:95]
	v_mfma_f32_16x16x32_bf16 v[88:91], v[136:139], v[212:215], v[88:91]
	v_mfma_f32_16x16x32_bf16 v[76:79], v[128:131], v[220:223], v[76:79]
	v_mfma_f32_16x16x32_bf16 v[72:75], v[136:139], v[220:223], v[72:75]
	v_mfma_f32_16x16x32_bf16 v[124:127], v[132:135], v[200:203], v[124:127]
	v_mfma_f32_16x16x32_bf16 v[120:123], v[140:143], v[200:203], v[120:123]
	v_mfma_f32_16x16x32_bf16 v[108:111], v[132:135], v[208:211], v[108:111]
	v_mfma_f32_16x16x32_bf16 v[104:107], v[140:143], v[208:211], v[104:107]
	v_mfma_f32_16x16x32_bf16 v[92:95], v[132:135], v[216:219], v[92:95]
	v_mfma_f32_16x16x32_bf16 v[88:91], v[140:143], v[216:219], v[88:91]
	v_mfma_f32_16x16x32_bf16 v[76:79], v[132:135], v[224:227], v[76:79]
	v_mfma_f32_16x16x32_bf16 v[72:75], v[140:143], v[224:227], v[72:75]
	s_setprio 0
	s_setprio 1
	v_mfma_f32_16x16x32_bf16 v[116:119], v[170:173], v[196:199], v[116:119]
	v_mfma_f32_16x16x32_bf16 v[112:115], v[188:191], v[196:199], v[112:115]
	v_mfma_f32_16x16x32_bf16 v[100:103], v[170:173], v[204:207], v[100:103]
	v_mfma_f32_16x16x32_bf16 v[96:99], v[188:191], v[204:207], v[96:99]
	v_mfma_f32_16x16x32_bf16 v[84:87], v[170:173], v[212:215], v[84:87]
	v_mfma_f32_16x16x32_bf16 v[80:83], v[188:191], v[212:215], v[80:83]
	v_mfma_f32_16x16x32_bf16 v[68:71], v[170:173], v[220:223], v[68:71]
	v_mfma_f32_16x16x32_bf16 v[64:67], v[188:191], v[220:223], v[64:67]
	v_mfma_f32_16x16x32_bf16 v[116:119], v[184:187], v[200:203], v[116:119]
	v_mfma_f32_16x16x32_bf16 v[112:115], v[192:195], v[200:203], v[112:115]
	v_mfma_f32_16x16x32_bf16 v[100:103], v[184:187], v[208:211], v[100:103]
	v_mfma_f32_16x16x32_bf16 v[96:99], v[192:195], v[208:211], v[96:99]
	v_mfma_f32_16x16x32_bf16 v[84:87], v[184:187], v[216:219], v[84:87]
	v_mfma_f32_16x16x32_bf16 v[80:83], v[192:195], v[216:219], v[80:83]
	v_mfma_f32_16x16x32_bf16 v[68:71], v[184:187], v[224:227], v[68:71]
	v_mfma_f32_16x16x32_bf16 v[64:67], v[192:195], v[224:227], v[64:67]
	s_setprio 0
	s_barrier
	s_add_i32 s72, s60, s2
	v_lshl_add_u64 v[174:175], s[36:37], 0, v[146:147]
	s_mov_b32 m0, s72
	ds_read_b128 v[196:199], v180 offset:16384
	ds_read_b128 v[200:203], v180 offset:17408
	ds_read_b128 v[204:207], v180 offset:18432
	ds_read_b128 v[208:211], v180 offset:19456
	ds_read_b128 v[212:215], v180 offset:20480
	ds_read_b128 v[216:219], v180 offset:21504
	ds_read_b128 v[220:223], v180 offset:22528
	ds_read_b128 v[224:227], v180 offset:23552
	global_load_lds_dwordx4 v[174:175], off
	s_add_i32 m0, s72, 0x2000
	s_add_u32 s72, s36, 0x40000
	v_lshl_add_u64 v[228:229], s[36:37], 0, v[150:151]
	s_addc_u32 s73, s37, 0
	s_add_i32 s74, s61, s2
	global_load_lds_dwordx4 v[228:229], off
	s_mov_b32 m0, s74
	v_lshl_add_u64 v[232:233], s[38:39], 0, v[148:149]
	global_load_lds_dwordx4 v146, s[72:73]
	s_add_i32 m0, s74, 0x2000
	s_nop 0
	global_load_lds_dwordx4 v150, s[72:73]
	v_lshl_add_u64 v[230:231], s[38:39], 0, v[144:145]
	s_mov_b32 m0, s49
	s_nop 0
	global_load_lds_dwordx4 v[230:231], off
	s_mov_b32 m0, s50
	s_nop 0
	global_load_lds_dwordx4 v[232:233], off
	s_waitcnt vmcnt(8)
	s_waitcnt lgkmcnt(0)
	s_barrier
	s_setprio 1
	s_waitcnt lgkmcnt(0)
	v_mfma_f32_16x16x32_bf16 v[60:63], v[128:131], v[196:199], v[60:63]
	v_mfma_f32_16x16x32_bf16 v[56:59], v[136:139], v[196:199], v[56:59]
	v_mfma_f32_16x16x32_bf16 v[44:47], v[128:131], v[204:207], v[44:47]
	v_mfma_f32_16x16x32_bf16 v[40:43], v[136:139], v[204:207], v[40:43]
	v_mfma_f32_16x16x32_bf16 v[28:31], v[128:131], v[212:215], v[28:31]
	v_mfma_f32_16x16x32_bf16 v[24:27], v[136:139], v[212:215], v[24:27]
	v_mfma_f32_16x16x32_bf16 v[12:15], v[128:131], v[220:223], v[12:15]
	v_mfma_f32_16x16x32_bf16 v[8:11], v[136:139], v[220:223], v[8:11]
	v_mfma_f32_16x16x32_bf16 v[60:63], v[132:135], v[200:203], v[60:63]
	v_mfma_f32_16x16x32_bf16 v[56:59], v[140:143], v[200:203], v[56:59]
	v_mfma_f32_16x16x32_bf16 v[44:47], v[132:135], v[208:211], v[44:47]
	v_mfma_f32_16x16x32_bf16 v[40:43], v[140:143], v[208:211], v[40:43]
	v_mfma_f32_16x16x32_bf16 v[28:31], v[132:135], v[216:219], v[28:31]
	v_mfma_f32_16x16x32_bf16 v[24:27], v[140:143], v[216:219], v[24:27]
	v_mfma_f32_16x16x32_bf16 v[12:15], v[132:135], v[224:227], v[12:15]
	v_mfma_f32_16x16x32_bf16 v[8:11], v[140:143], v[224:227], v[8:11]
	s_setprio 0
	s_setprio 1
	v_mfma_f32_16x16x32_bf16 v[52:55], v[170:173], v[196:199], v[52:55]
	v_mfma_f32_16x16x32_bf16 v[48:51], v[188:191], v[196:199], v[48:51]
	v_mfma_f32_16x16x32_bf16 v[36:39], v[170:173], v[204:207], v[36:39]
	v_mfma_f32_16x16x32_bf16 v[32:35], v[188:191], v[204:207], v[32:35]
	v_mfma_f32_16x16x32_bf16 v[20:23], v[170:173], v[212:215], v[20:23]
	v_mfma_f32_16x16x32_bf16 v[16:19], v[188:191], v[212:215], v[16:19]
	v_mfma_f32_16x16x32_bf16 v[4:7], v[170:173], v[220:223], v[4:7]
	v_mfma_f32_16x16x32_bf16 v[0:3], v[188:191], v[220:223], v[0:3]
	v_mfma_f32_16x16x32_bf16 v[52:55], v[184:187], v[200:203], v[52:55]
	v_mfma_f32_16x16x32_bf16 v[48:51], v[192:195], v[200:203], v[48:51]
	v_mfma_f32_16x16x32_bf16 v[36:39], v[184:187], v[208:211], v[36:39]
	v_mfma_f32_16x16x32_bf16 v[32:35], v[192:195], v[208:211], v[32:35]
	v_mfma_f32_16x16x32_bf16 v[20:23], v[184:187], v[216:219], v[20:23]
	v_mfma_f32_16x16x32_bf16 v[16:19], v[192:195], v[216:219], v[16:19]
	v_mfma_f32_16x16x32_bf16 v[4:7], v[184:187], v[224:227], v[4:7]
	v_mfma_f32_16x16x32_bf16 v[0:3], v[192:195], v[224:227], v[0:3]
	s_setprio 0
	s_barrier
; #define PG8_STAGE(bufoff, gbase, voff) do { _Pragma("unroll") for (int _i = 0; _i < 2; ++_i) \
;         __builtin_amdgcn_global_load_lds((const unsigned*)((const char*)(gbase) + (voff)[_i]), (LAS unsigned*)(lds + (bufoff) + ldsw + _i * 8192), 16, 0, 0); } while (0)
; #define PG8_LDA(dst, b, h) do { _Pragma("unroll") for (int m = 0; m < 4; ++m) _Pragma("unroll") for (int k = 0; k < 2; ++k) dst[m][k] = *(const LAS bf16x8*)(lds + PG8_SA(b, h) + aoff + m * 2048 + k * 1024); } while (0)
; #define PG8_LDB(dst, b, h) do { _Pragma("unroll") for (int n = 0; n < 2; ++n) _Pragma("unroll") for (int k = 0; k < 2; ++k) dst[n][k] = *(const LAS bf16x8*)(lds + PG8_SB(b, h) + boff + n * 2048 + k * 1024); } while (0)
; #define PG8_MMA(ai, bj, At, Bt) do { __builtin_amdgcn_s_setprio(1); _Pragma("unroll") for (int m = 0; m < 4; ++m) _Pragma("unroll") for (int n = 0; n < 2; ++n) _Pragma("unroll") for (int k = 0; k < 2; ++k) \
;         acc[ai][bj][m][n] = __builtin_amdgcn_mfma_f32_16x16x32_bf16(Bt[n][k], At[m][k], acc[ai][bj][m][n], 0, 0, 0); __builtin_amdgcn_s_setprio(0); } while (0)
; #define PG8_WAIT_V(n) asm volatile("s_waitcnt vmcnt(" #n ")" ::: "memory")
; template <class Epi, class Sched>
; __device__ __forceinline__ void gemm_phase(LAS unsigned char* lds, const Gemm g, const Sched& S, const Epi& E, int wave_id) {
;     ...
;             PG8_LDB(B0, 0, 0); PG8_LDB(B1, 0, 1); PG8_SCHED; PG8_LDA(At, 0, 0); PG8_STAGE(PG8_SA(1, 1), a1 + hstepA, voffA);
;             PG8_WAIT_V(8); PG8_WAIT_L(0); PG8_BAR; PG8_MMA(0, 0, At, B0); PG8_MMA(0, 1, At, B1); PG8_BAR; PG8_SCHED;
;             PG8_LDA(At, 0, 1); PG8_STAGE(PG8_SB(0, 0), b2, voffB); PG8_STAGE(PG8_SB(0, 1), b2 + hstepB, voffB); PG8_STAGE(PG8_SA(0, 0), a2, voffA);
;             PG8_WAIT_V(8); PG8_WAIT_L(0); PG8_BAR; PG8_MMA(1, 0, At, B0); PG8_MMA(1, 1, At, B1); PG8_BAR; PG8_SCHED;
;             PG8_LDB(B0, 1, 0); PG8_LDB(B1, 1, 1); PG8_SCHED; PG8_LDA(At, 1, 0); PG8_STAGE(PG8_SA(0, 1), a2 + hstepA, voffA);
;             PG8_WAIT_V(8); PG8_WAIT_L(0); PG8_BAR; PG8_MMA(0, 0, At, B0); PG8_MMA(0, 1, At, B1); PG8_BAR; PG8_SCHED;
;             PG8_LDA(At, 1, 1); PG8_STAGE(PG8_SB(1, 0), b3, voffB); PG8_STAGE(PG8_SB(1, 1), b3 + hstepB, voffB); PG8_STAGE(PG8_SA(1, 0), a3, voffA);
;             PG8_WAIT_V(8); PG8_WAIT_L(0); PG8_BAR; PG8_MMA(1, 0, At, B0); PG8_MMA(1, 1, At, B1); PG8_BAR; PG8_SCHED;
;         }
;         if (wr == 0) PG8_BAR;
	s_add_i32 s72, 0, 0x18000
	s_add_i32 s73, 0, 0x1c000
	v_add_u32_e32 v140, s72, v177
	v_add_u32_e32 v192, s73, v177
	ds_read_b128 v[128:131], v140
	ds_read_b128 v[132:135], v140 offset:1024
	ds_read_b128 v[136:139], v140 offset:2048
	ds_read_b128 v[140:143], v140 offset:3072
	ds_read_b128 v[170:173], v192
	ds_read_b128 v[184:187], v192 offset:1024
	ds_read_b128 v[188:191], v192 offset:2048
	ds_read_b128 v[192:195], v192 offset:3072
	s_add_u32 s38, s38, 0x40000
	s_addc_u32 s39, s39, 0
	s_mov_b32 m0, s51
	ds_read_b128 v[196:199], v180 offset:32768
	ds_read_b128 v[200:203], v180 offset:33792
	ds_read_b128 v[204:207], v180 offset:34816
	ds_read_b128 v[208:211], v180 offset:35840
	ds_read_b128 v[212:215], v180 offset:36864
	ds_read_b128 v[216:219], v180 offset:37888
	ds_read_b128 v[220:223], v180 offset:38912
	ds_read_b128 v[224:227], v180 offset:39936
	global_load_lds_dwordx4 v144, s[38:39]
	s_mov_b32 m0, s52
	s_nop 0
	global_load_lds_dwordx4 v148, s[38:39]
	s_waitcnt vmcnt(8)
	s_waitcnt lgkmcnt(0)
	s_barrier
	s_setprio 1
	s_waitcnt lgkmcnt(0)
	v_mfma_f32_16x16x32_bf16 v[124:127], v[128:131], v[196:199], v[124:127]
	v_mfma_f32_16x16x32_bf16 v[120:123], v[136:139], v[196:199], v[120:123]
	v_mfma_f32_16x16x32_bf16 v[108:111], v[128:131], v[204:207], v[108:111]
	v_mfma_f32_16x16x32_bf16 v[104:107], v[136:139], v[204:207], v[104:107]
	v_mfma_f32_16x16x32_bf16 v[92:95], v[128:131], v[212:215], v[92:95]
	v_mfma_f32_16x16x32_bf16 v[88:91], v[136:139], v[212:215], v[88:91]
	v_mfma_f32_16x16x32_bf16 v[76:79], v[128:131], v[220:223], v[76:79]
	v_mfma_f32_16x16x32_bf16 v[72:75], v[136:139], v[220:223], v[72:75]
	v_mfma_f32_16x16x32_bf16 v[124:127], v[132:135], v[200:203], v[124:127]
	v_mfma_f32_16x16x32_bf16 v[120:123], v[140:143], v[200:203], v[120:123]
	v_mfma_f32_16x16x32_bf16 v[108:111], v[132:135], v[208:211], v[108:111]
	v_mfma_f32_16x16x32_bf16 v[104:107], v[140:143], v[208:211], v[104:107]
	v_mfma_f32_16x16x32_bf16 v[92:95], v[132:135], v[216:219], v[92:95]
	v_mfma_f32_16x16x32_bf16 v[88:91], v[140:143], v[216:219], v[88:91]
	v_mfma_f32_16x16x32_bf16 v[76:79], v[132:135], v[224:227], v[76:79]
	v_mfma_f32_16x16x32_bf16 v[72:75], v[140:143], v[224:227], v[72:75]
	s_setprio 0
	s_setprio 1
	v_mfma_f32_16x16x32_bf16 v[116:119], v[170:173], v[196:199], v[116:119]
	v_mfma_f32_16x16x32_bf16 v[112:115], v[188:191], v[196:199], v[112:115]
	v_mfma_f32_16x16x32_bf16 v[100:103], v[170:173], v[204:207], v[100:103]
	v_mfma_f32_16x16x32_bf16 v[96:99], v[188:191], v[204:207], v[96:99]
	v_mfma_f32_16x16x32_bf16 v[84:87], v[170:173], v[212:215], v[84:87]
	v_mfma_f32_16x16x32_bf16 v[80:83], v[188:191], v[212:215], v[80:83]
	v_mfma_f32_16x16x32_bf16 v[68:71], v[170:173], v[220:223], v[68:71]
	v_mfma_f32_16x16x32_bf16 v[64:67], v[188:191], v[220:223], v[64:67]
	v_mfma_f32_16x16x32_bf16 v[116:119], v[184:187], v[200:203], v[116:119]
	v_mfma_f32_16x16x32_bf16 v[112:115], v[192:195], v[200:203], v[112:115]
	v_mfma_f32_16x16x32_bf16 v[100:103], v[184:187], v[208:211], v[100:103]
	v_mfma_f32_16x16x32_bf16 v[96:99], v[192:195], v[208:211], v[96:99]
	v_mfma_f32_16x16x32_bf16 v[84:87], v[184:187], v[216:219], v[84:87]
	v_mfma_f32_16x16x32_bf16 v[80:83], v[192:195], v[216:219], v[80:83]
	v_mfma_f32_16x16x32_bf16 v[68:71], v[184:187], v[224:227], v[68:71]
	v_mfma_f32_16x16x32_bf16 v[64:67], v[192:195], v[224:227], v[64:67]
	s_setprio 0
	s_barrier
	s_add_i32 s38, s72, s2
	v_lshl_add_u64 v[174:175], v[174:175], 0, s[16:17]
	s_mov_b32 m0, s38
	ds_read_b128 v[196:199], v180 offset:49152
	ds_read_b128 v[200:203], v180 offset:50176
	ds_read_b128 v[204:207], v180 offset:51200
	ds_read_b128 v[208:211], v180 offset:52224
	ds_read_b128 v[212:215], v180 offset:53248
	ds_read_b128 v[216:219], v180 offset:54272
	ds_read_b128 v[220:223], v180 offset:55296
	ds_read_b128 v[224:227], v180 offset:56320
	global_load_lds_dwordx4 v[174:175], off
	s_add_i32 m0, s38, 0x2000
	s_add_u32 s36, s36, 0x40080
	v_lshl_add_u64 v[174:175], v[228:229], 0, s[16:17]
	s_addc_u32 s37, s37, 0
	s_add_i32 s38, s73, s2
	global_load_lds_dwordx4 v[174:175], off
	s_mov_b32 m0, s38
	s_nop 0
	global_load_lds_dwordx4 v146, s[36:37]
	s_add_i32 m0, s38, 0x2000
	s_nop 0
	global_load_lds_dwordx4 v150, s[36:37]
	v_lshl_add_u64 v[174:175], v[230:231], 0, s[16:17]
	s_mov_b32 m0, s54
	s_nop 0
	global_load_lds_dwordx4 v[174:175], off
	v_lshl_add_u64 v[174:175], v[232:233], 0, s[16:17]
	s_mov_b32 m0, s55
	s_nop 0
	global_load_lds_dwordx4 v[174:175], off
	s_waitcnt vmcnt(8)
	s_waitcnt lgkmcnt(0)
	s_barrier
	s_setprio 1
	s_waitcnt lgkmcnt(0)
	v_mfma_f32_16x16x32_bf16 v[60:63], v[128:131], v[196:199], v[60:63]
	v_mfma_f32_16x16x32_bf16 v[56:59], v[136:139], v[196:199], v[56:59]
	v_mfma_f32_16x16x32_bf16 v[44:47], v[128:131], v[204:207], v[44:47]
	v_mfma_f32_16x16x32_bf16 v[40:43], v[136:139], v[204:207], v[40:43]
	v_mfma_f32_16x16x32_bf16 v[28:31], v[128:131], v[212:215], v[28:31]
	v_mfma_f32_16x16x32_bf16 v[24:27], v[136:139], v[212:215], v[24:27]
	v_mfma_f32_16x16x32_bf16 v[12:15], v[128:131], v[220:223], v[12:15]
	v_mfma_f32_16x16x32_bf16 v[8:11], v[136:139], v[220:223], v[8:11]
	v_mfma_f32_16x16x32_bf16 v[60:63], v[132:135], v[200:203], v[60:63]
	v_mfma_f32_16x16x32_bf16 v[56:59], v[140:143], v[200:203], v[56:59]
	v_mfma_f32_16x16x32_bf16 v[44:47], v[132:135], v[208:211], v[44:47]
	v_mfma_f32_16x16x32_bf16 v[40:43], v[140:143], v[208:211], v[40:43]
	v_mfma_f32_16x16x32_bf16 v[28:31], v[132:135], v[216:219], v[28:31]
	v_mfma_f32_16x16x32_bf16 v[24:27], v[140:143], v[216:219], v[24:27]
	v_mfma_f32_16x16x32_bf16 v[12:15], v[132:135], v[224:227], v[12:15]
	v_mfma_f32_16x16x32_bf16 v[8:11], v[140:143], v[224:227], v[8:11]
	s_setprio 0
	s_setprio 1
	v_mfma_f32_16x16x32_bf16 v[52:55], v[170:173], v[196:199], v[52:55]
	v_mfma_f32_16x16x32_bf16 v[48:51], v[188:191], v[196:199], v[48:51]
	v_mfma_f32_16x16x32_bf16 v[36:39], v[170:173], v[204:207], v[36:39]
	v_mfma_f32_16x16x32_bf16 v[32:35], v[188:191], v[204:207], v[32:35]
	v_mfma_f32_16x16x32_bf16 v[20:23], v[170:173], v[212:215], v[20:23]
	v_mfma_f32_16x16x32_bf16 v[16:19], v[188:191], v[212:215], v[16:19]
	v_mfma_f32_16x16x32_bf16 v[4:7], v[170:173], v[220:223], v[4:7]
	v_mfma_f32_16x16x32_bf16 v[0:3], v[188:191], v[220:223], v[0:3]
	v_mfma_f32_16x16x32_bf16 v[52:55], v[184:187], v[200:203], v[52:55]
	v_mfma_f32_16x16x32_bf16 v[48:51], v[192:195], v[200:203], v[48:51]
	v_mfma_f32_16x16x32_bf16 v[36:39], v[184:187], v[208:211], v[36:39]
	v_mfma_f32_16x16x32_bf16 v[32:35], v[192:195], v[208:211], v[32:35]
	v_mfma_f32_16x16x32_bf16 v[20:23], v[184:187], v[216:219], v[20:23]
	v_mfma_f32_16x16x32_bf16 v[16:19], v[192:195], v[216:219], v[16:19]
	v_mfma_f32_16x16x32_bf16 v[4:7], v[184:187], v[224:227], v[4:7]
	v_mfma_f32_16x16x32_bf16 v[0:3], v[192:195], v[224:227], v[0:3]
	s_setprio 0
	s_barrier
	s_add_i32 s67, s67, 2
	s_add_u32 s34, s34, 0x100
	s_addc_u32 s35, s35, 0
	s_add_u32 s65, s65, 0x100
	s_addc_u32 s66, s66, 0
	s_cmp_gt_u32 s67, 13
	s_cbranch_scc0 .LBB0_1251
	s_and_b64 vcc, exec, s[18:19]
	s_cbranch_vccz .LBB0_1254
	s_barrier

;     __device__ bool next(int i, Unit& u) const { if (r0 + i >= r1) return false; return base.next(r0 + i, u); }
;     __device__ bool next(int i, Unit& u) const { const int L = i * G + c; if (L >= 256) return false; u.pm = L; u.pn = L >> 3; return true; }
; #define PG8_STAGE(bufoff, gbase, voff) do { _Pragma("unroll") for (int _i = 0; _i < 2; ++_i) \
;         __builtin_amdgcn_global_load_lds((const unsigned*)((const char*)(gbase) + (voff)[_i]), (LAS unsigned*)(lds + (bufoff) + ldsw + _i * 8192), 16, 0, 0); } while (0)
; #define PG8_WAIT_V(n) asm volatile("s_waitcnt vmcnt(" #n ")" ::: "memory")
; #define PG8_BAR __builtin_amdgcn_s_barrier()
; template <class Epi, class Sched>
; __device__ __forceinline__ void gemm_phase(LAS unsigned char* lds, const Gemm g, const Sched& S, const Epi& E, int wave_id) {
;     ...
;     PG8_STAGE(PG8_SB(0, 0), cB, voffB); PG8_STAGE(PG8_SB(0, 1), cB + hstepB, voffB); PG8_STAGE(PG8_SA(0, 0), cA, voffA); PG8_STAGE(PG8_SA(0, 1), cA + hstepA, voffA);
;     if (wr == 1) PG8_BAR;
;     PG8_WAIT_V(2); PG8_BAR;
;     PG8_STAGE(PG8_SB(1, 0), cB + kstep, voffB); PG8_STAGE(PG8_SA(1, 0), cA + kstep, voffA); PG8_STAGE(PG8_SB(1, 1), cB + hstepB + kstep, voffB);
;     PG8_WAIT_V(6); PG8_BAR;
;     for (;;) {
;         const bool has_next = S.next(ui + 1, nxt);
;         const char* nA = has_next ? (const char*)g.A + (size_t)nxt.pm * tstepA : cA; const char* nB = has_next ? (const char*)g.Bt + (size_t)nxt.pn * tstepB : cB;
.LBB0_1267:
	s_add_u32 s56, s92, 0x13400000
	s_mov_b64 s[12:13], 0x80
	s_addc_u32 s57, s93, 0
	s_add_i32 m0, s51, 0x18000
	v_lshl_add_u64 v[6:7], v[6:7], 0, s[12:13]
	s_waitcnt vmcnt(2)
	s_barrier
	global_load_lds_dwordx4 v[6:7], off
	v_lshl_add_u64 v[4:5], v[4:5], 0, s[12:13]
	s_add_i32 m0, s51, 0x1a000
	s_add_i32 s58, s51, 0x8000
	s_add_i32 s59, s51, 0xa000
	global_load_lds_dwordx4 v[4:5], off
	v_lshl_add_u64 v[0:1], v[0:1], 0, s[12:13]
	s_mov_b32 m0, s58
	s_add_u32 s14, s26, 0x10080
	global_load_lds_dwordx4 v[0:1], off
	v_lshl_add_u64 v[0:1], v[2:3], 0, s[12:13]
	s_mov_b32 m0, s59
	s_addc_u32 s15, s27, 0
	global_load_lds_dwordx4 v[0:1], off
	s_add_i32 m0, s51, 0x1c000
	s_nop 0
	global_load_lds_dwordx4 v130, s[14:15]
	v_lshl_add_u64 v[0:1], s[14:15], 0, v[134:135]
	s_add_i32 m0, s51, 0x1e000
	v_and_b32_e32 v2, 15, v8
	global_load_lds_dwordx4 v[0:1], off
	v_lshrrev_b32_e32 v0, 4, v8
	v_bfe_u32 v1, v8, 4, 2
	v_or_b32_e32 v3, s3, v2
	s_sext_i32_i8 s25, s4
	v_lshlrev_b32_e32 v1, 4, v1
	v_lshlrev_b32_e32 v4, 6, v3
	s_movk_i32 s4, 0x3c0
	v_lshlrev_b32_e32 v3, 2, v3
	s_cmpk_lt_u32 s80, 0x100
	v_bfe_u32 v0, v0, 1, 1
	v_readlane_b32 s16, v255, 1
	v_and_or_b32 v4, v4, s4, v1
	v_and_b32_e32 v3, 32, v3
	v_lshlrev_b32_e32 v5, 2, v8
	s_cselect_b64 s[14:15], -1, 0
	v_lshl_or_b32 v0, s33, 1, v0
	s_lshl_b32 s5, s33, 6
	s_ashr_i32 s33, s16, 31
	s_mov_b32 s60, s16
	s_add_i32 s16, s40, 0
	v_bitop3_b32 v3, v4, s42, v3 bitop3:0xde
	v_lshl_or_b32 v4, v2, 6, v1
	v_and_b32_e32 v5, 32, v5
	s_add_i32 s16, s16, 0x20000
	v_bitop3_b32 v146, v4, s41, v5 bitop3:0xde
	v_and_or_b32 v4, v1, 16, v2
	s_add_i32 s5, s5, s16
	s_waitcnt vmcnt(6)
	v_lshlrev_b32_e32 v136, 4, v4
	s_movk_i32 s4, 0x210
	v_mov_b32_e32 v5, s5
	v_mul_u32_u24_e32 v4, 0x210, v0
	v_mad_u32_u24 v2, v2, s4, v5
	v_add_u32_e32 v5, s16, v136
	v_lshlrev_b32_e32 v138, 11, v0
	s_add_i32 s61, 0, 0x10000
	s_add_i32 s62, 0, 0x14000
	v_mov_b32_e32 v137, v131
	v_mov_b32_e32 v139, v131
	v_or_b32_e32 v140, 0x4000, v138
	v_mov_b32_e32 v141, v131
	v_mov_b64_e32 v[142:143], 0x200
	v_mov_b64_e32 v[144:145], 0x1ff
	v_add_u32_e32 v147, s61, v146
	v_add_u32_e32 v148, s62, v146
	v_add_u32_e32 v149, 0, v3
	v_add_u32_e32 v150, v2, v1
	v_add_u32_e32 v151, v5, v4
	s_barrier
	v_readlane_b32 s17, v255, 2
	s_waitcnt vmcnt(0)
	s_branch .LBB0_1270

;     __device__ bool next(int i, Unit& u) const { if (r0 + i >= r1) return false; return base.next(r0 + i, u); }
;     __device__ bool next(int i, Unit& u) const { const int L = i * G + c; if (L >= 256) return false; u.pm = L; u.pn = L >> 3; return true; }
; #define PG8_STAGE(bufoff, gbase, voff) do { _Pragma("unroll") for (int _i = 0; _i < 2; ++_i) \
;         __builtin_amdgcn_global_load_lds((const unsigned*)((const char*)(gbase) + (voff)[_i]), (LAS unsigned*)(lds + (bufoff) + ldsw + _i * 8192), 16, 0, 0); } while (0)
; #define PG8_LDA(dst, b, h) do { _Pragma("unroll") for (int m = 0; m < 4; ++m) _Pragma("unroll") for (int k = 0; k < 2; ++k) dst[m][k] = *(const LAS bf16x8*)(lds + PG8_SA(b, h) + aoff + m * 2048 + k * 1024); } while (0)
; #define PG8_LDB(dst, b, h) do { _Pragma("unroll") for (int n = 0; n < 2; ++n) _Pragma("unroll") for (int k = 0; k < 2; ++k) dst[n][k] = *(const LAS bf16x8*)(lds + PG8_SB(b, h) + boff + n * 2048 + k * 1024); } while (0)
; #define PG8_WAIT_V(n) asm volatile("s_waitcnt vmcnt(" #n ")" ::: "memory")
; #define PG8_WAIT_L(n) asm volatile("s_waitcnt lgkmcnt(" #n ")" ::: "memory")
; template <class Epi, class Sched>
; __device__ __forceinline__ void gemm_phase(LAS unsigned char* lds, const Gemm g, const Sched& S, const Epi& E, int wave_id) {
;     ...
;         const bool has_next = S.next(ui + 1, nxt);
;         const char* nA = has_next ? (const char*)g.A + (size_t)nxt.pm * tstepA : cA; const char* nB = has_next ? (const char*)g.Bt + (size_t)nxt.pn * tstepB : cB;
;         for (int t = 0; t < nt; t += 2) {
;             const bool last = (t == nt - 2);
;             const char* a1 = cA + (size_t)(t + 1) * kstep;
;             const char* a2 = last ? nA : cA + (size_t)(t + 2) * kstep; const char* b2 = last ? nB : cB + (size_t)(t + 2) * kstep;
;             const char* a3 = a2 + kstep; const char* b3 = b2 + kstep;
;             PG8_LDB(B0, 0, 0); PG8_LDB(B1, 0, 1); PG8_SCHED; PG8_LDA(At, 0, 0); PG8_STAGE(PG8_SA(1, 1), a1 + hstepA, voffA);
;             PG8_WAIT_V(8); PG8_WAIT_L(0); PG8_BAR; PG8_MMA(0, 0, At, B0); PG8_MMA(0, 1, At, B1); PG8_BAR; PG8_SCHED;
;             PG8_LDA(At, 0, 1); PG8_STAGE(PG8_SB(0, 0), b2, voffB); PG8_STAGE(PG8_SB(0, 1), b2 + hstepB, voffB); PG8_STAGE(PG8_SA(0, 0), a2, voffA);
;             PG8_WAIT_V(8); PG8_WAIT_L(0); PG8_BAR; PG8_MMA(1, 0, At, B0); PG8_MMA(1, 1, At, B1); PG8_BAR; PG8_SCHED;
.LBB0_1276:
	s_ashr_i32 s19, s18, 31
	s_lshl_b64 s[20:21], s[18:19], 17
	s_add_u32 s20, s47, s20
	s_addc_u32 s21, s48, s21
	s_and_b64 s[22:23], s[4:5], exec
	s_cselect_b32 s19, s21, s29
	s_cselect_b32 s63, s20, s28
	s_ashr_i32 s17, s16, 31
	s_lshl_b64 s[22:23], s[16:17], 17
	s_add_u32 s22, s49, s22
	s_addc_u32 s23, s50, s23
	s_and_b64 s[30:31], s[4:5], exec
	s_cselect_b32 s17, s23, s27
	s_cselect_b32 s64, s22, s26
	s_mov_b32 s36, 0
	s_mov_b64 s[30:31], -1
	s_mov_b64 s[34:35], 0
	s_add_u32 s37, s28, s36
	s_addc_u32 s42, s29, 0
	s_add_u32 s40, s37, 0x100
	s_addc_u32 s41, s42, 0
	s_and_b64 s[38:39], s[34:35], exec
	s_cselect_b32 s39, s19, s41
	s_cselect_b32 s38, s63, s40
	s_add_u32 s36, s26, s36
	s_addc_u32 s40, s27, 0
	s_add_u32 s36, s36, 0x100
	s_addc_u32 s40, s40, 0
	s_and_b64 s[34:35], s[34:35], exec
	s_cselect_b32 s41, s17, s40
	s_cselect_b32 s40, s64, s36
	s_add_u32 s44, s37, 0x10080
	ds_read_b128 v[152:155], v147
	ds_read_b128 v[156:159], v147 offset:1024
	ds_read_b128 v[160:163], v147 offset:2048
	ds_read_b128 v[164:167], v147 offset:3072
	ds_read_b128 v[168:171], v148
	ds_read_b128 v[172:175], v148 offset:1024
	ds_read_b128 v[176:179], v148 offset:2048
	ds_read_b128 v[180:183], v148 offset:3072
	s_addc_u32 s45, s42, 0
	s_add_i32 s76, s61, s2
	s_add_i32 m0, s51, 0xc000
	s_add_i32 s79, s51, 0xe000
	s_add_i32 s73, s76, 0x2000
	s_add_u32 s42, s40, 0x10000
	s_addc_u32 s43, s41, 0
	s_add_i32 s75, s62, s2
	s_add_i32 s74, s75, 0x2000
	s_add_i32 s72, 0, 0x18000
	s_add_i32 s67, 0, 0x1c000
	s_add_u32 s36, s38, 0x10000
	s_addc_u32 s37, s39, 0
	s_add_i32 s66, s72, s2
	s_add_i32 s65, s66, 0x2000
	s_add_u32 s34, s40, 0x10080
	s_addc_u32 s35, s41, 0
	s_add_i32 s78, s67, s2
	s_add_i32 s77, s78, 0x2000
	ds_read_b128 v[184:187], v149
	ds_read_b128 v[188:191], v149 offset:1024
	ds_read_b128 v[192:195], v149 offset:2048
	ds_read_b128 v[196:199], v149 offset:3072
	ds_read_b128 v[200:203], v149 offset:4096
	ds_read_b128 v[204:207], v149 offset:5120
	ds_read_b128 v[208:211], v149 offset:6144
	ds_read_b128 v[212:215], v149 offset:7168
	global_load_lds_dwordx4 v128, s[44:45]
	s_mov_b32 m0, s79
	s_nop 0
	global_load_lds_dwordx4 v132, s[44:45]
	s_waitcnt vmcnt(8)
	s_waitcnt lgkmcnt(0)
	s_barrier
	s_setprio 1
	s_waitcnt lgkmcnt(0)
	v_mfma_f32_16x16x32_bf16 v[124:127], v[152:155], v[184:187], 0
	v_mfma_f32_16x16x32_bf16 v[120:123], v[160:163], v[184:187], 0
	v_mfma_f32_16x16x32_bf16 v[108:111], v[152:155], v[192:195], 0
	v_mfma_f32_16x16x32_bf16 v[104:107], v[160:163], v[192:195], 0
	v_mfma_f32_16x16x32_bf16 v[92:95], v[152:155], v[200:203], 0
	v_mfma_f32_16x16x32_bf16 v[88:91], v[160:163], v[200:203], 0
	v_mfma_f32_16x16x32_bf16 v[76:79], v[152:155], v[208:211], 0
	v_mfma_f32_16x16x32_bf16 v[72:75], v[160:163], v[208:211], 0
	v_mfma_f32_16x16x32_bf16 v[124:127], v[156:159], v[188:191], v[124:127]
	v_mfma_f32_16x16x32_bf16 v[120:123], v[164:167], v[188:191], v[120:123]
	v_mfma_f32_16x16x32_bf16 v[108:111], v[156:159], v[196:199], v[108:111]
	v_mfma_f32_16x16x32_bf16 v[104:107], v[164:167], v[196:199], v[104:107]
	v_mfma_f32_16x16x32_bf16 v[92:95], v[156:159], v[204:207], v[92:95]
	v_mfma_f32_16x16x32_bf16 v[88:91], v[164:167], v[204:207], v[88:91]
	v_mfma_f32_16x16x32_bf16 v[76:79], v[156:159], v[212:215], v[76:79]
	v_mfma_f32_16x16x32_bf16 v[72:75], v[164:167], v[212:215], v[72:75]
	s_setprio 0
	s_setprio 1
	v_mfma_f32_16x16x32_bf16 v[116:119], v[168:171], v[184:187], 0
	v_mfma_f32_16x16x32_bf16 v[112:115], v[176:179], v[184:187], 0
	v_mfma_f32_16x16x32_bf16 v[100:103], v[168:171], v[192:195], 0
	v_mfma_f32_16x16x32_bf16 v[96:99], v[176:179], v[192:195], 0
	v_mfma_f32_16x16x32_bf16 v[84:87], v[168:171], v[200:203], 0
	v_mfma_f32_16x16x32_bf16 v[80:83], v[176:179], v[200:203], 0
	v_mfma_f32_16x16x32_bf16 v[68:71], v[168:171], v[208:211], 0
	v_mfma_f32_16x16x32_bf16 v[64:67], v[176:179], v[208:211], 0
	v_mfma_f32_16x16x32_bf16 v[116:119], v[172:175], v[188:191], v[116:119]
	v_mfma_f32_16x16x32_bf16 v[112:115], v[180:183], v[188:191], v[112:115]
	v_mfma_f32_16x16x32_bf16 v[100:103], v[172:175], v[196:199], v[100:103]
	v_mfma_f32_16x16x32_bf16 v[96:99], v[180:183], v[196:199], v[96:99]
	v_mfma_f32_16x16x32_bf16 v[84:87], v[172:175], v[204:207], v[84:87]
	v_mfma_f32_16x16x32_bf16 v[80:83], v[180:183], v[204:207], v[80:83]
	v_mfma_f32_16x16x32_bf16 v[68:71], v[172:175], v[212:215], v[68:71]
	v_mfma_f32_16x16x32_bf16 v[64:67], v[180:183], v[212:215], v[64:67]
	s_setprio 0
	s_barrier
	s_mov_b32 m0, s76
	v_lshl_add_u64 v[216:217], s[40:41], 0, v[130:131]
	ds_read_b128 v[184:187], v149 offset:16384
	ds_read_b128 v[188:191], v149 offset:17408
	ds_read_b128 v[192:195], v149 offset:18432
	ds_read_b128 v[196:199], v149 offset:19456
	ds_read_b128 v[200:203], v149 offset:20480
	ds_read_b128 v[204:207], v149 offset:21504
	ds_read_b128 v[208:211], v149 offset:22528
	ds_read_b128 v[212:215], v149 offset:23552
	global_load_lds_dwordx4 v[216:217], off
	v_lshl_add_u64 v[218:219], s[40:41], 0, v[134:135]
	s_mov_b32 m0, s73
	s_nop 0
	global_load_lds_dwordx4 v[218:219], off
	s_mov_b32 m0, s75
	v_lshl_add_u64 v[222:223], s[38:39], 0, v[132:133]
	global_load_lds_dwordx4 v130, s[42:43]
	s_mov_b32 m0, s74
	s_nop 0
	global_load_lds_dwordx4 v134, s[42:43]
	v_lshl_add_u64 v[220:221], s[38:39], 0, v[128:129]
	s_mov_b32 m0, s51
	s_nop 0
	global_load_lds_dwordx4 v[220:221], off
	s_mov_b32 m0, s52
	s_nop 0
	global_load_lds_dwordx4 v[222:223], off
	s_waitcnt vmcnt(8)
	s_waitcnt lgkmcnt(0)
	s_barrier
; #define PG8_STAGE(bufoff, gbase, voff) do { _Pragma("unroll") for (int _i = 0; _i < 2; ++_i) \
;         __builtin_amdgcn_global_load_lds((const unsigned*)((const char*)(gbase) + (voff)[_i]), (LAS unsigned*)(lds + (bufoff) + ldsw + _i * 8192), 16, 0, 0); } while (0)
; #define PG8_LDA(dst, b, h) do { _Pragma("unroll") for (int m = 0; m < 4; ++m) _Pragma("unroll") for (int k = 0; k < 2; ++k) dst[m][k] = *(const LAS bf16x8*)(lds + PG8_SA(b, h) + aoff + m * 2048 + k * 1024); } while (0)
; #define PG8_LDB(dst, b, h) do { _Pragma("unroll") for (int n = 0; n < 2; ++n) _Pragma("unroll") for (int k = 0; k < 2; ++k) dst[n][k] = *(const LAS bf16x8*)(lds + PG8_SB(b, h) + boff + n * 2048 + k * 1024); } while (0)
; #define PG8_MMA(ai, bj, At, Bt) do { __builtin_amdgcn_s_setprio(1); _Pragma("unroll") for (int m = 0; m < 4; ++m) _Pragma("unroll") for (int n = 0; n < 2; ++n) _Pragma("unroll") for (int k = 0; k < 2; ++k) \
;         acc[ai][bj][m][n] = __builtin_amdgcn_mfma_f32_16x16x32_bf16(Bt[n][k], At[m][k], acc[ai][bj][m][n], 0, 0, 0); __builtin_amdgcn_s_setprio(0); } while (0)
; #define PG8_WAIT_V(n) asm volatile("s_waitcnt vmcnt(" #n ")" ::: "memory")
; #define PG8_WAIT_L(n) asm volatile("s_waitcnt lgkmcnt(" #n ")" ::: "memory")
; #define PG8_BAR __builtin_amdgcn_s_barrier()
; #define PG8_SCHED __builtin_amdgcn_sched_barrier(0)
; template <class Epi, class Sched>
; __device__ __forceinline__ void gemm_phase(LAS unsigned char* lds, const Gemm g, const Sched& S, const Epi& E, int wave_id) {
;     ...
;             PG8_LDB(B0, 1, 0); PG8_LDB(B1, 1, 1); PG8_SCHED; PG8_LDA(At, 1, 0); PG8_STAGE(PG8_SA(0, 1), a2 + hstepA, voffA);
;             PG8_WAIT_V(8); PG8_WAIT_L(0); PG8_BAR; PG8_MMA(0, 0, At, B0); PG8_MMA(0, 1, At, B1); PG8_BAR; PG8_SCHED;
	s_setprio 1
	s_waitcnt lgkmcnt(0)
	v_mfma_f32_16x16x32_bf16 v[60:63], v[152:155], v[184:187], 0
	v_mfma_f32_16x16x32_bf16 v[56:59], v[160:163], v[184:187], 0
	v_mfma_f32_16x16x32_bf16 v[44:47], v[152:155], v[192:195], 0
	v_mfma_f32_16x16x32_bf16 v[40:43], v[160:163], v[192:195], 0
	v_mfma_f32_16x16x32_bf16 v[28:31], v[152:155], v[200:203], 0
	v_mfma_f32_16x16x32_bf16 v[24:27], v[160:163], v[200:203], 0
	v_mfma_f32_16x16x32_bf16 v[12:15], v[152:155], v[208:211], 0
	v_mfma_f32_16x16x32_bf16 v[8:11], v[160:163], v[208:211], 0
	v_mfma_f32_16x16x32_bf16 v[60:63], v[156:159], v[188:191], v[60:63]
	v_mfma_f32_16x16x32_bf16 v[56:59], v[164:167], v[188:191], v[56:59]
	v_mfma_f32_16x16x32_bf16 v[44:47], v[156:159], v[196:199], v[44:47]
	v_mfma_f32_16x16x32_bf16 v[40:43], v[164:167], v[196:199], v[40:43]
	v_mfma_f32_16x16x32_bf16 v[28:31], v[156:159], v[204:207], v[28:31]
	v_mfma_f32_16x16x32_bf16 v[24:27], v[164:167], v[204:207], v[24:27]
	v_mfma_f32_16x16x32_bf16 v[12:15], v[156:159], v[212:215], v[12:15]
	v_mfma_f32_16x16x32_bf16 v[8:11], v[164:167], v[212:215], v[8:11]
	s_setprio 0
	s_setprio 1
	v_mfma_f32_16x16x32_bf16 v[52:55], v[168:171], v[184:187], 0
	v_mfma_f32_16x16x32_bf16 v[48:51], v[176:179], v[184:187], 0
	v_mfma_f32_16x16x32_bf16 v[36:39], v[168:171], v[192:195], 0
	v_mfma_f32_16x16x32_bf16 v[32:35], v[176:179], v[192:195], 0
	v_mfma_f32_16x16x32_bf16 v[20:23], v[168:171], v[200:203], 0
	v_mfma_f32_16x16x32_bf16 v[16:19], v[176:179], v[200:203], 0
	v_mfma_f32_16x16x32_bf16 v[4:7], v[168:171], v[208:211], 0
	v_mfma_f32_16x16x32_bf16 v[0:3], v[176:179], v[208:211], 0
	v_mfma_f32_16x16x32_bf16 v[52:55], v[172:175], v[188:191], v[52:55]
	v_mfma_f32_16x16x32_bf16 v[48:51], v[180:183], v[188:191], v[48:51]
	v_mfma_f32_16x16x32_bf16 v[36:39], v[172:175], v[196:199], v[36:39]
	v_mfma_f32_16x16x32_bf16 v[32:35], v[180:183], v[196:199], v[32:35]
	v_mfma_f32_16x16x32_bf16 v[20:23], v[172:175], v[204:207], v[20:23]
	v_mfma_f32_16x16x32_bf16 v[16:19], v[180:183], v[204:207], v[16:19]
	v_mfma_f32_16x16x32_bf16 v[4:7], v[172:175], v[212:215], v[4:7]
	v_mfma_f32_16x16x32_bf16 v[0:3], v[180:183], v[212:215], v[0:3]
	s_setprio 0
	s_barrier
	v_add_u32_e32 v164, s72, v146
	v_add_u32_e32 v180, s67, v146
	ds_read_b128 v[152:155], v164
	ds_read_b128 v[156:159], v164 offset:1024
	ds_read_b128 v[160:163], v164 offset:2048
	ds_read_b128 v[164:167], v164 offset:3072
	ds_read_b128 v[168:171], v180
	ds_read_b128 v[172:175], v180 offset:1024
	ds_read_b128 v[176:179], v180 offset:2048
	ds_read_b128 v[180:183], v180 offset:3072
	s_mov_b32 m0, s53
	ds_read_b128 v[184:187], v149 offset:32768
	ds_read_b128 v[188:191], v149 offset:33792
	ds_read_b128 v[192:195], v149 offset:34816
	ds_read_b128 v[196:199], v149 offset:35840
	ds_read_b128 v[200:203], v149 offset:36864
	ds_read_b128 v[204:207], v149 offset:37888
	ds_read_b128 v[208:211], v149 offset:38912
	ds_read_b128 v[212:215], v149 offset:39936
	global_load_lds_dwordx4 v128, s[36:37]
	s_mov_b32 m0, s54
	s_nop 0
	global_load_lds_dwordx4 v132, s[36:37]
	s_waitcnt vmcnt(8)
	s_waitcnt lgkmcnt(0)
	s_barrier
	s_setprio 1
	s_waitcnt lgkmcnt(0)
	v_mfma_f32_16x16x32_bf16 v[124:127], v[152:155], v[184:187], v[124:127]
	v_mfma_f32_16x16x32_bf16 v[120:123], v[160:163], v[184:187], v[120:123]
	v_mfma_f32_16x16x32_bf16 v[108:111], v[152:155], v[192:195], v[108:111]
	v_mfma_f32_16x16x32_bf16 v[104:107], v[160:163], v[192:195], v[104:107]
	v_mfma_f32_16x16x32_bf16 v[92:95], v[152:155], v[200:203], v[92:95]
	v_mfma_f32_16x16x32_bf16 v[88:91], v[160:163], v[200:203], v[88:91]
	v_mfma_f32_16x16x32_bf16 v[76:79], v[152:155], v[208:211], v[76:79]
	v_mfma_f32_16x16x32_bf16 v[72:75], v[160:163], v[208:211], v[72:75]
	v_mfma_f32_16x16x32_bf16 v[124:127], v[156:159], v[188:191], v[124:127]
	v_mfma_f32_16x16x32_bf16 v[120:123], v[164:167], v[188:191], v[120:123]
	v_mfma_f32_16x16x32_bf16 v[108:111], v[156:159], v[196:199], v[108:111]
	v_mfma_f32_16x16x32_bf16 v[104:107], v[164:167], v[196:199], v[104:107]
	v_mfma_f32_16x16x32_bf16 v[92:95], v[156:159], v[204:207], v[92:95]
	v_mfma_f32_16x16x32_bf16 v[88:91], v[164:167], v[204:207], v[88:91]
	v_mfma_f32_16x16x32_bf16 v[76:79], v[156:159], v[212:215], v[76:79]
	v_mfma_f32_16x16x32_bf16 v[72:75], v[164:167], v[212:215], v[72:75]
	s_setprio 0
	s_setprio 1
	v_mfma_f32_16x16x32_bf16 v[116:119], v[168:171], v[184:187], v[116:119]
	v_mfma_f32_16x16x32_bf16 v[112:115], v[176:179], v[184:187], v[112:115]
	v_mfma_f32_16x16x32_bf16 v[100:103], v[168:171], v[192:195], v[100:103]
	v_mfma_f32_16x16x32_bf16 v[96:99], v[176:179], v[192:195], v[96:99]
	v_mfma_f32_16x16x32_bf16 v[84:87], v[168:171], v[200:203], v[84:87]
	v_mfma_f32_16x16x32_bf16 v[80:83], v[176:179], v[200:203], v[80:83]
	v_mfma_f32_16x16x32_bf16 v[68:71], v[168:171], v[208:211], v[68:71]
	v_mfma_f32_16x16x32_bf16 v[64:67], v[176:179], v[208:211], v[64:67]
	v_mfma_f32_16x16x32_bf16 v[116:119], v[172:175], v[188:191], v[116:119]
	v_mfma_f32_16x16x32_bf16 v[112:115], v[180:183], v[188:191], v[112:115]
	v_mfma_f32_16x16x32_bf16 v[100:103], v[172:175], v[196:199], v[100:103]
	v_mfma_f32_16x16x32_bf16 v[96:99], v[180:183], v[196:199], v[96:99]
	v_mfma_f32_16x16x32_bf16 v[84:87], v[172:175], v[204:207], v[84:87]
	v_mfma_f32_16x16x32_bf16 v[80:83], v[180:183], v[204:207], v[80:83]
	v_mfma_f32_16x16x32_bf16 v[68:71], v[172:175], v[212:215], v[68:71]
	v_mfma_f32_16x16x32_bf16 v[64:67], v[180:183], v[212:215], v[64:67]
	s_setprio 0
	s_barrier
; #define PG8_STAGE(bufoff, gbase, voff) do { _Pragma("unroll") for (int _i = 0; _i < 2; ++_i) \
;         __builtin_amdgcn_global_load_lds((const unsigned*)((const char*)(gbase) + (voff)[_i]), (LAS unsigned*)(lds + (bufoff) + ldsw + _i * 8192), 16, 0, 0); } while (0)
; #define PG8_LDA(dst, b, h) do { _Pragma("unroll") for (int m = 0; m < 4; ++m) _Pragma("unroll") for (int k = 0; k < 2; ++k) dst[m][k] = *(const LAS bf16x8*)(lds + PG8_SA(b, h) + aoff + m * 2048 + k * 1024); } while (0)
; #define PG8_LDB(dst, b, h) do { _Pragma("unroll") for (int n = 0; n < 2; ++n) _Pragma("unroll") for (int k = 0; k < 2; ++k) dst[n][k] = *(const LAS bf16x8*)(lds + PG8_SB(b, h) + boff + n * 2048 + k * 1024); } while (0)
; #define PG8_MMA(ai, bj, At, Bt) do { __builtin_amdgcn_s_setprio(1); _Pragma("unroll") for (int m = 0; m < 4; ++m) _Pragma("unroll") for (int n = 0; n < 2; ++n) _Pragma("unroll") for (int k = 0; k < 2; ++k) \
;         acc[ai][bj][m][n] = __builtin_amdgcn_mfma_f32_16x16x32_bf16(Bt[n][k], At[m][k], acc[ai][bj][m][n], 0, 0, 0); __builtin_amdgcn_s_setprio(0); } while (0)
; #define PG8_WAIT_V(n) asm volatile("s_waitcnt vmcnt(" #n ")" ::: "memory")
; #define PG8_WAIT_L(n) asm volatile("s_waitcnt lgkmcnt(" #n ")" ::: "memory")
; #define PG8_BAR __builtin_amdgcn_s_barrier()
; #define PG8_SCHED __builtin_amdgcn_sched_barrier(0)
; template <class Epi, class Sched>
; __device__ __forceinline__ void gemm_phase(LAS unsigned char* lds, const Gemm g, const Sched& S, const Epi& E, int wave_id) {
;     ...
;             PG8_LDB(B0, 0, 0); PG8_LDB(B1, 0, 1); PG8_SCHED; PG8_LDA(At, 0, 0); PG8_STAGE(PG8_SA(1, 1), a1 + hstepA, voffA);
;             PG8_WAIT_V(8); PG8_WAIT_L(0); PG8_BAR; PG8_MMA(0, 0, At, B0); PG8_MMA(0, 1, At, B1); PG8_BAR; PG8_SCHED;
;     ...
;             PG8_LDA(At, 1, 1); PG8_STAGE(PG8_SB(1, 0), b3, voffB); PG8_STAGE(PG8_SB(1, 1), b3 + hstepB, voffB); PG8_STAGE(PG8_SA(1, 0), a3, voffA);
;             PG8_WAIT_V(8); PG8_WAIT_L(0); PG8_BAR; PG8_MMA(1, 0, At, B0); PG8_MMA(1, 1, At, B1); PG8_BAR; PG8_SCHED;
	s_mov_b32 m0, s66
	v_lshl_add_u64 v[216:217], v[216:217], 0, s[12:13]
	ds_read_b128 v[184:187], v149 offset:49152
	ds_read_b128 v[188:191], v149 offset:50176
	ds_read_b128 v[192:195], v149 offset:51200
	ds_read_b128 v[196:199], v149 offset:52224
	ds_read_b128 v[200:203], v149 offset:53248
	ds_read_b128 v[204:207], v149 offset:54272
	ds_read_b128 v[208:211], v149 offset:55296
	ds_read_b128 v[212:215], v149 offset:56320
	global_load_lds_dwordx4 v[216:217], off
	v_lshl_add_u64 v[216:217], v[218:219], 0, s[12:13]
	s_mov_b32 m0, s65
	s_nop 0
	global_load_lds_dwordx4 v[216:217], off
	s_mov_b32 m0, s78
	s_nop 0
	global_load_lds_dwordx4 v130, s[34:35]
	s_mov_b32 m0, s77
	s_nop 0
	global_load_lds_dwordx4 v134, s[34:35]
	v_lshl_add_u64 v[216:217], v[220:221], 0, s[12:13]
	s_mov_b32 m0, s58
	s_nop 0
	global_load_lds_dwordx4 v[216:217], off
	v_lshl_add_u64 v[216:217], v[222:223], 0, s[12:13]
	s_mov_b32 m0, s59
	s_nop 0
	global_load_lds_dwordx4 v[216:217], off
	s_waitcnt vmcnt(8)
	s_waitcnt lgkmcnt(0)
	s_barrier
	s_setprio 1
	s_waitcnt lgkmcnt(0)
	v_mfma_f32_16x16x32_bf16 v[60:63], v[152:155], v[184:187], v[60:63]
	v_mfma_f32_16x16x32_bf16 v[56:59], v[160:163], v[184:187], v[56:59]
	v_mfma_f32_16x16x32_bf16 v[44:47], v[152:155], v[192:195], v[44:47]
	v_mfma_f32_16x16x32_bf16 v[40:43], v[160:163], v[192:195], v[40:43]
	v_mfma_f32_16x16x32_bf16 v[28:31], v[152:155], v[200:203], v[28:31]
	v_mfma_f32_16x16x32_bf16 v[24:27], v[160:163], v[200:203], v[24:27]
	v_mfma_f32_16x16x32_bf16 v[12:15], v[152:155], v[208:211], v[12:15]
	v_mfma_f32_16x16x32_bf16 v[8:11], v[160:163], v[208:211], v[8:11]
	v_mfma_f32_16x16x32_bf16 v[60:63], v[156:159], v[188:191], v[60:63]
	v_mfma_f32_16x16x32_bf16 v[56:59], v[164:167], v[188:191], v[56:59]
	v_mfma_f32_16x16x32_bf16 v[44:47], v[156:159], v[196:199], v[44:47]
	v_mfma_f32_16x16x32_bf16 v[40:43], v[164:167], v[196:199], v[40:43]
	v_mfma_f32_16x16x32_bf16 v[28:31], v[156:159], v[204:207], v[28:31]
	v_mfma_f32_16x16x32_bf16 v[24:27], v[164:167], v[204:207], v[24:27]
	v_mfma_f32_16x16x32_bf16 v[12:15], v[156:159], v[212:215], v[12:15]
	v_mfma_f32_16x16x32_bf16 v[8:11], v[164:167], v[212:215], v[8:11]
	s_setprio 0
	s_setprio 1
	v_mfma_f32_16x16x32_bf16 v[52:55], v[168:171], v[184:187], v[52:55]
	v_mfma_f32_16x16x32_bf16 v[48:51], v[176:179], v[184:187], v[48:51]
	v_mfma_f32_16x16x32_bf16 v[36:39], v[168:171], v[192:195], v[36:39]
	v_mfma_f32_16x16x32_bf16 v[32:35], v[176:179], v[192:195], v[32:35]
	v_mfma_f32_16x16x32_bf16 v[20:23], v[168:171], v[200:203], v[20:23]
	v_mfma_f32_16x16x32_bf16 v[16:19], v[176:179], v[200:203], v[16:19]
	v_mfma_f32_16x16x32_bf16 v[4:7], v[168:171], v[208:211], v[4:7]
	v_mfma_f32_16x16x32_bf16 v[0:3], v[176:179], v[208:211], v[0:3]
	v_mfma_f32_16x16x32_bf16 v[52:55], v[172:175], v[188:191], v[52:55]
	v_mfma_f32_16x16x32_bf16 v[48:51], v[180:183], v[188:191], v[48:51]
	v_mfma_f32_16x16x32_bf16 v[36:39], v[172:175], v[196:199], v[36:39]
	v_mfma_f32_16x16x32_bf16 v[32:35], v[180:183], v[196:199], v[32:35]
	v_mfma_f32_16x16x32_bf16 v[20:23], v[172:175], v[204:207], v[20:23]
	v_mfma_f32_16x16x32_bf16 v[16:19], v[180:183], v[204:207], v[16:19]
	v_mfma_f32_16x16x32_bf16 v[4:7], v[172:175], v[212:215], v[4:7]
	v_mfma_f32_16x16x32_bf16 v[0:3], v[180:183], v[212:215], v[0:3]
	s_setprio 0
	s_barrier
	s_movk_i32 s36, 0x100
	s_andn2_b64 vcc, exec, s[30:31]
	s_mov_b64 s[34:35], -1
	s_mov_b64 s[30:31], 0
.LBB0_1277:
	s_add_u32 s37, s28, s36
	s_addc_u32 s42, s29, 0
	s_add_u32 s40, s37, 0x100
	s_addc_u32 s41, s42, 0
	s_and_b64 s[38:39], s[34:35], exec
	s_cselect_b32 s39, s19, s41
	s_cselect_b32 s38, s63, s40
	s_add_u32 s36, s26, s36
	s_addc_u32 s40, s27, 0
	s_add_u32 s36, s36, 0x100
	s_addc_u32 s40, s40, 0
	s_and_b64 s[34:35], s[34:35], exec
	s_cselect_b32 s41, s17, s40
	s_cselect_b32 s40, s64, s36
	s_add_u32 s44, s37, 0x10080
	ds_read_b128 v[152:155], v147
	ds_read_b128 v[156:159], v147 offset:1024
	ds_read_b128 v[160:163], v147 offset:2048
	ds_read_b128 v[164:167], v147 offset:3072
	ds_read_b128 v[168:171], v148
	ds_read_b128 v[172:175], v148 offset:1024
	ds_read_b128 v[176:179], v148 offset:2048
	ds_read_b128 v[180:183], v148 offset:3072
	s_addc_u32 s45, s42, 0
	s_add_i32 s76, s61, s2
	s_add_i32 m0, s51, 0xc000
	s_add_i32 s79, s51, 0xe000
	s_add_i32 s73, s76, 0x2000
	s_add_u32 s42, s40, 0x10000
	s_addc_u32 s43, s41, 0
	s_add_i32 s75, s62, s2
	s_add_i32 s74, s75, 0x2000
	s_add_i32 s72, 0, 0x18000
	s_add_i32 s67, 0, 0x1c000
	s_add_u32 s36, s38, 0x10000
	s_addc_u32 s37, s39, 0
	s_add_i32 s66, s72, s2
	s_add_i32 s65, s66, 0x2000
	s_add_u32 s34, s40, 0x10080
	s_addc_u32 s35, s41, 0
	s_add_i32 s78, s67, s2
	s_add_i32 s77, s78, 0x2000
	ds_read_b128 v[184:187], v149
	ds_read_b128 v[188:191], v149 offset:1024
	ds_read_b128 v[192:195], v149 offset:2048
	ds_read_b128 v[196:199], v149 offset:3072
	ds_read_b128 v[200:203], v149 offset:4096
	ds_read_b128 v[204:207], v149 offset:5120
	ds_read_b128 v[208:211], v149 offset:6144
	ds_read_b128 v[212:215], v149 offset:7168
	global_load_lds_dwordx4 v128, s[44:45]
	s_mov_b32 m0, s79
	s_nop 0
	global_load_lds_dwordx4 v132, s[44:45]
	s_waitcnt vmcnt(8)
	s_waitcnt lgkmcnt(0)
	s_barrier
; #define PG8_STAGE(bufoff, gbase, voff) do { _Pragma("unroll") for (int _i = 0; _i < 2; ++_i) \
;         __builtin_amdgcn_global_load_lds((const unsigned*)((const char*)(gbase) + (voff)[_i]), (LAS unsigned*)(lds + (bufoff) + ldsw + _i * 8192), 16, 0, 0); } while (0)
; #define PG8_LDA(dst, b, h) do { _Pragma("unroll") for (int m = 0; m < 4; ++m) _Pragma("unroll") for (int k = 0; k < 2; ++k) dst[m][k] = *(const LAS bf16x8*)(lds + PG8_SA(b, h) + aoff + m * 2048 + k * 1024); } while (0)
; #define PG8_LDB(dst, b, h) do { _Pragma("unroll") for (int n = 0; n < 2; ++n) _Pragma("unroll") for (int k = 0; k < 2; ++k) dst[n][k] = *(const LAS bf16x8*)(lds + PG8_SB(b, h) + boff + n * 2048 + k * 1024); } while (0)
; #define PG8_MMA(ai, bj, At, Bt) do { __builtin_amdgcn_s_setprio(1); _Pragma("unroll") for (int m = 0; m < 4; ++m) _Pragma("unroll") for (int n = 0; n < 2; ++n) _Pragma("unroll") for (int k = 0; k < 2; ++k) \
;         acc[ai][bj][m][n] = __builtin_amdgcn_mfma_f32_16x16x32_bf16(Bt[n][k], At[m][k], acc[ai][bj][m][n], 0, 0, 0); __builtin_amdgcn_s_setprio(0); } while (0)
; #define PG8_WAIT_V(n) asm volatile("s_waitcnt vmcnt(" #n ")" ::: "memory")
; #define PG8_WAIT_L(n) asm volatile("s_waitcnt lgkmcnt(" #n ")" ::: "memory")
; #define PG8_BAR __builtin_amdgcn_s_barrier()
; #define PG8_SCHED __builtin_amdgcn_sched_barrier(0)
; template <class Epi, class Sched>
; __device__ __forceinline__ void gemm_phase(LAS unsigned char* lds, const Gemm g, const Sched& S, const Epi& E, int wave_id) {
;     ...
;             PG8_LDB(B0, 0, 0); PG8_LDB(B1, 0, 1); PG8_SCHED; PG8_LDA(At, 0, 0); PG8_STAGE(PG8_SA(1, 1), a1 + hstepA, voffA);
;             PG8_WAIT_V(8); PG8_WAIT_L(0); PG8_BAR; PG8_MMA(0, 0, At, B0); PG8_MMA(0, 1, At, B1); PG8_BAR; PG8_SCHED;
;             PG8_LDA(At, 0, 1); PG8_STAGE(PG8_SB(0, 0), b2, voffB); PG8_STAGE(PG8_SB(0, 1), b2 + hstepB, voffB); PG8_STAGE(PG8_SA(0, 0), a2, voffA);
;             PG8_WAIT_V(8); PG8_WAIT_L(0); PG8_BAR; PG8_MMA(1, 0, At, B0); PG8_MMA(1, 1, At, B1); PG8_BAR; PG8_SCHED;
	s_setprio 1
	s_waitcnt lgkmcnt(0)
	v_mfma_f32_16x16x32_bf16 v[124:127], v[152:155], v[184:187], v[124:127]
	v_mfma_f32_16x16x32_bf16 v[120:123], v[160:163], v[184:187], v[120:123]
	v_mfma_f32_16x16x32_bf16 v[108:111], v[152:155], v[192:195], v[108:111]
	v_mfma_f32_16x16x32_bf16 v[104:107], v[160:163], v[192:195], v[104:107]
	v_mfma_f32_16x16x32_bf16 v[92:95], v[152:155], v[200:203], v[92:95]
	v_mfma_f32_16x16x32_bf16 v[88:91], v[160:163], v[200:203], v[88:91]
	v_mfma_f32_16x16x32_bf16 v[76:79], v[152:155], v[208:211], v[76:79]
	v_mfma_f32_16x16x32_bf16 v[72:75], v[160:163], v[208:211], v[72:75]
	v_mfma_f32_16x16x32_bf16 v[124:127], v[156:159], v[188:191], v[124:127]
	v_mfma_f32_16x16x32_bf16 v[120:123], v[164:167], v[188:191], v[120:123]
	v_mfma_f32_16x16x32_bf16 v[108:111], v[156:159], v[196:199], v[108:111]
	v_mfma_f32_16x16x32_bf16 v[104:107], v[164:167], v[196:199], v[104:107]
	v_mfma_f32_16x16x32_bf16 v[92:95], v[156:159], v[204:207], v[92:95]
	v_mfma_f32_16x16x32_bf16 v[88:91], v[164:167], v[204:207], v[88:91]
	v_mfma_f32_16x16x32_bf16 v[76:79], v[156:159], v[212:215], v[76:79]
	v_mfma_f32_16x16x32_bf16 v[72:75], v[164:167], v[212:215], v[72:75]
	s_setprio 0
	s_setprio 1
	v_mfma_f32_16x16x32_bf16 v[116:119], v[168:171], v[184:187], v[116:119]
	v_mfma_f32_16x16x32_bf16 v[112:115], v[176:179], v[184:187], v[112:115]
	v_mfma_f32_16x16x32_bf16 v[100:103], v[168:171], v[192:195], v[100:103]
	v_mfma_f32_16x16x32_bf16 v[96:99], v[176:179], v[192:195], v[96:99]
	v_mfma_f32_16x16x32_bf16 v[84:87], v[168:171], v[200:203], v[84:87]
	v_mfma_f32_16x16x32_bf16 v[80:83], v[176:179], v[200:203], v[80:83]
	v_mfma_f32_16x16x32_bf16 v[68:71], v[168:171], v[208:211], v[68:71]
	v_mfma_f32_16x16x32_bf16 v[64:67], v[176:179], v[208:211], v[64:67]
	v_mfma_f32_16x16x32_bf16 v[116:119], v[172:175], v[188:191], v[116:119]
	v_mfma_f32_16x16x32_bf16 v[112:115], v[180:183], v[188:191], v[112:115]
	v_mfma_f32_16x16x32_bf16 v[100:103], v[172:175], v[196:199], v[100:103]
	v_mfma_f32_16x16x32_bf16 v[96:99], v[180:183], v[196:199], v[96:99]
	v_mfma_f32_16x16x32_bf16 v[84:87], v[172:175], v[204:207], v[84:87]
	v_mfma_f32_16x16x32_bf16 v[80:83], v[180:183], v[204:207], v[80:83]
	v_mfma_f32_16x16x32_bf16 v[68:71], v[172:175], v[212:215], v[68:71]
	v_mfma_f32_16x16x32_bf16 v[64:67], v[180:183], v[212:215], v[64:67]
	s_setprio 0
	s_barrier
	s_mov_b32 m0, s76
	v_lshl_add_u64 v[216:217], s[40:41], 0, v[130:131]
	ds_read_b128 v[184:187], v149 offset:16384
	ds_read_b128 v[188:191], v149 offset:17408
	ds_read_b128 v[192:195], v149 offset:18432
	ds_read_b128 v[196:199], v149 offset:19456
	ds_read_b128 v[200:203], v149 offset:20480
	ds_read_b128 v[204:207], v149 offset:21504
	ds_read_b128 v[208:211], v149 offset:22528
	ds_read_b128 v[212:215], v149 offset:23552
	global_load_lds_dwordx4 v[216:217], off
	v_lshl_add_u64 v[218:219], s[40:41], 0, v[134:135]
	s_mov_b32 m0, s73
	s_nop 0
	global_load_lds_dwordx4 v[218:219], off
	s_mov_b32 m0, s75
	v_lshl_add_u64 v[222:223], s[38:39], 0, v[132:133]
	global_load_lds_dwordx4 v130, s[42:43]
	s_mov_b32 m0, s74
	s_nop 0
	global_load_lds_dwordx4 v134, s[42:43]
	v_lshl_add_u64 v[220:221], s[38:39], 0, v[128:129]
	s_mov_b32 m0, s51
	s_nop 0
	global_load_lds_dwordx4 v[220:221], off
	s_mov_b32 m0, s52
	s_nop 0
	global_load_lds_dwordx4 v[222:223], off
	s_waitcnt vmcnt(8)
	s_waitcnt lgkmcnt(0)
	s_barrier
	s_setprio 1
	s_waitcnt lgkmcnt(0)
	v_mfma_f32_16x16x32_bf16 v[60:63], v[152:155], v[184:187], v[60:63]
	v_mfma_f32_16x16x32_bf16 v[56:59], v[160:163], v[184:187], v[56:59]
	v_mfma_f32_16x16x32_bf16 v[44:47], v[152:155], v[192:195], v[44:47]
	v_mfma_f32_16x16x32_bf16 v[40:43], v[160:163], v[192:195], v[40:43]
	v_mfma_f32_16x16x32_bf16 v[28:31], v[152:155], v[200:203], v[28:31]
	v_mfma_f32_16x16x32_bf16 v[24:27], v[160:163], v[200:203], v[24:27]
	v_mfma_f32_16x16x32_bf16 v[12:15], v[152:155], v[208:211], v[12:15]
	v_mfma_f32_16x16x32_bf16 v[8:11], v[160:163], v[208:211], v[8:11]
	v_mfma_f32_16x16x32_bf16 v[60:63], v[156:159], v[188:191], v[60:63]
	v_mfma_f32_16x16x32_bf16 v[56:59], v[164:167], v[188:191], v[56:59]
	v_mfma_f32_16x16x32_bf16 v[44:47], v[156:159], v[196:199], v[44:47]
	v_mfma_f32_16x16x32_bf16 v[40:43], v[164:167], v[196:199], v[40:43]
	v_mfma_f32_16x16x32_bf16 v[28:31], v[156:159], v[204:207], v[28:31]
	v_mfma_f32_16x16x32_bf16 v[24:27], v[164:167], v[204:207], v[24:27]
	v_mfma_f32_16x16x32_bf16 v[12:15], v[156:159], v[212:215], v[12:15]
	v_mfma_f32_16x16x32_bf16 v[8:11], v[164:167], v[212:215], v[8:11]
	s_setprio 0
	s_setprio 1
	v_mfma_f32_16x16x32_bf16 v[52:55], v[168:171], v[184:187], v[52:55]
	v_mfma_f32_16x16x32_bf16 v[48:51], v[176:179], v[184:187], v[48:51]
	v_mfma_f32_16x16x32_bf16 v[36:39], v[168:171], v[192:195], v[36:39]
	v_mfma_f32_16x16x32_bf16 v[32:35], v[176:179], v[192:195], v[32:35]
	v_mfma_f32_16x16x32_bf16 v[20:23], v[168:171], v[200:203], v[20:23]
	v_mfma_f32_16x16x32_bf16 v[16:19], v[176:179], v[200:203], v[16:19]
	v_mfma_f32_16x16x32_bf16 v[4:7], v[168:171], v[208:211], v[4:7]
	v_mfma_f32_16x16x32_bf16 v[0:3], v[176:179], v[208:211], v[0:3]
	v_mfma_f32_16x16x32_bf16 v[52:55], v[172:175], v[188:191], v[52:55]
	v_mfma_f32_16x16x32_bf16 v[48:51], v[180:183], v[188:191], v[48:51]
	v_mfma_f32_16x16x32_bf16 v[36:39], v[172:175], v[196:199], v[36:39]
	v_mfma_f32_16x16x32_bf16 v[32:35], v[180:183], v[196:199], v[32:35]
	v_mfma_f32_16x16x32_bf16 v[20:23], v[172:175], v[204:207], v[20:23]
	v_mfma_f32_16x16x32_bf16 v[16:19], v[180:183], v[204:207], v[16:19]
	v_mfma_f32_16x16x32_bf16 v[4:7], v[172:175], v[212:215], v[4:7]
	v_mfma_f32_16x16x32_bf16 v[0:3], v[180:183], v[212:215], v[0:3]
	s_setprio 0
	s_barrier
; #define PG8_STAGE(bufoff, gbase, voff) do { _Pragma("unroll") for (int _i = 0; _i < 2; ++_i) \
;         __builtin_amdgcn_global_load_lds((const unsigned*)((const char*)(gbase) + (voff)[_i]), (LAS unsigned*)(lds + (bufoff) + ldsw + _i * 8192), 16, 0, 0); } while (0)
; #define PG8_LDA(dst, b, h) do { _Pragma("unroll") for (int m = 0; m < 4; ++m) _Pragma("unroll") for (int k = 0; k < 2; ++k) dst[m][k] = *(const LAS bf16x8*)(lds + PG8_SA(b, h) + aoff + m * 2048 + k * 1024); } while (0)
; #define PG8_LDB(dst, b, h) do { _Pragma("unroll") for (int n = 0; n < 2; ++n) _Pragma("unroll") for (int k = 0; k < 2; ++k) dst[n][k] = *(const LAS bf16x8*)(lds + PG8_SB(b, h) + boff + n * 2048 + k * 1024); } while (0)
; #define PG8_MMA(ai, bj, At, Bt) do { __builtin_amdgcn_s_setprio(1); _Pragma("unroll") for (int m = 0; m < 4; ++m) _Pragma("unroll") for (int n = 0; n < 2; ++n) _Pragma("unroll") for (int k = 0; k < 2; ++k) \
;         acc[ai][bj][m][n] = __builtin_amdgcn_mfma_f32_16x16x32_bf16(Bt[n][k], At[m][k], acc[ai][bj][m][n], 0, 0, 0); __builtin_amdgcn_s_setprio(0); } while (0)
; #define PG8_WAIT_V(n) asm volatile("s_waitcnt vmcnt(" #n ")" ::: "memory")
; #define PG8_WAIT_L(n) asm volatile("s_waitcnt lgkmcnt(" #n ")" ::: "memory")
; #define PG8_BAR __builtin_amdgcn_s_barrier()
; #define PG8_SCHED __builtin_amdgcn_sched_barrier(0)
; template <class Epi, class Sched>
; __device__ __forceinline__ void gemm_phase(LAS unsigned char* lds, const Gemm g, const Sched& S, const Epi& E, int wave_id) {
;     ...
;             PG8_LDB(B0, 1, 0); PG8_LDB(B1, 1, 1); PG8_SCHED; PG8_LDA(At, 1, 0); PG8_STAGE(PG8_SA(0, 1), a2 + hstepA, voffA);
;             PG8_WAIT_V(8); PG8_WAIT_L(0); PG8_BAR; PG8_MMA(0, 0, At, B0); PG8_MMA(0, 1, At, B1); PG8_BAR; PG8_SCHED;
;             PG8_LDA(At, 1, 1); PG8_STAGE(PG8_SB(1, 0), b3, voffB); PG8_STAGE(PG8_SB(1, 1), b3 + hstepB, voffB); PG8_STAGE(PG8_SA(1, 0), a3, voffA);
;             PG8_WAIT_V(8); PG8_WAIT_L(0); PG8_BAR; PG8_MMA(1, 0, At, B0); PG8_MMA(1, 1, At, B1); PG8_BAR; PG8_SCHED;
;         }
;         if (wr == 0) PG8_BAR;
	v_add_u32_e32 v164, s72, v146
	v_add_u32_e32 v180, s67, v146
	ds_read_b128 v[152:155], v164
	ds_read_b128 v[156:159], v164 offset:1024
	ds_read_b128 v[160:163], v164 offset:2048
	ds_read_b128 v[164:167], v164 offset:3072
	ds_read_b128 v[168:171], v180
	ds_read_b128 v[172:175], v180 offset:1024
	ds_read_b128 v[176:179], v180 offset:2048
	ds_read_b128 v[180:183], v180 offset:3072
	s_mov_b32 m0, s53
	ds_read_b128 v[184:187], v149 offset:32768
	ds_read_b128 v[188:191], v149 offset:33792
	ds_read_b128 v[192:195], v149 offset:34816
	ds_read_b128 v[196:199], v149 offset:35840
	ds_read_b128 v[200:203], v149 offset:36864
	ds_read_b128 v[204:207], v149 offset:37888
	ds_read_b128 v[208:211], v149 offset:38912
	ds_read_b128 v[212:215], v149 offset:39936
	global_load_lds_dwordx4 v128, s[36:37]
	s_mov_b32 m0, s54
	s_nop 0
	global_load_lds_dwordx4 v132, s[36:37]
	s_waitcnt vmcnt(8)
	s_waitcnt lgkmcnt(0)
	s_barrier
	s_setprio 1
	s_waitcnt lgkmcnt(0)
	v_mfma_f32_16x16x32_bf16 v[124:127], v[152:155], v[184:187], v[124:127]
	v_mfma_f32_16x16x32_bf16 v[120:123], v[160:163], v[184:187], v[120:123]
	v_mfma_f32_16x16x32_bf16 v[108:111], v[152:155], v[192:195], v[108:111]
	v_mfma_f32_16x16x32_bf16 v[104:107], v[160:163], v[192:195], v[104:107]
	v_mfma_f32_16x16x32_bf16 v[92:95], v[152:155], v[200:203], v[92:95]
	v_mfma_f32_16x16x32_bf16 v[88:91], v[160:163], v[200:203], v[88:91]
	v_mfma_f32_16x16x32_bf16 v[76:79], v[152:155], v[208:211], v[76:79]
	v_mfma_f32_16x16x32_bf16 v[72:75], v[160:163], v[208:211], v[72:75]
	v_mfma_f32_16x16x32_bf16 v[124:127], v[156:159], v[188:191], v[124:127]
	v_mfma_f32_16x16x32_bf16 v[120:123], v[164:167], v[188:191], v[120:123]
	v_mfma_f32_16x16x32_bf16 v[108:111], v[156:159], v[196:199], v[108:111]
	v_mfma_f32_16x16x32_bf16 v[104:107], v[164:167], v[196:199], v[104:107]
	v_mfma_f32_16x16x32_bf16 v[92:95], v[156:159], v[204:207], v[92:95]
	v_mfma_f32_16x16x32_bf16 v[88:91], v[164:167], v[204:207], v[88:91]
	v_mfma_f32_16x16x32_bf16 v[76:79], v[156:159], v[212:215], v[76:79]
	v_mfma_f32_16x16x32_bf16 v[72:75], v[164:167], v[212:215], v[72:75]
	s_setprio 0
	s_setprio 1
	v_mfma_f32_16x16x32_bf16 v[116:119], v[168:171], v[184:187], v[116:119]
	v_mfma_f32_16x16x32_bf16 v[112:115], v[176:179], v[184:187], v[112:115]
	v_mfma_f32_16x16x32_bf16 v[100:103], v[168:171], v[192:195], v[100:103]
	v_mfma_f32_16x16x32_bf16 v[96:99], v[176:179], v[192:195], v[96:99]
	v_mfma_f32_16x16x32_bf16 v[84:87], v[168:171], v[200:203], v[84:87]
	v_mfma_f32_16x16x32_bf16 v[80:83], v[176:179], v[200:203], v[80:83]
	v_mfma_f32_16x16x32_bf16 v[68:71], v[168:171], v[208:211], v[68:71]
	v_mfma_f32_16x16x32_bf16 v[64:67], v[176:179], v[208:211], v[64:67]
	v_mfma_f32_16x16x32_bf16 v[116:119], v[172:175], v[188:191], v[116:119]
	v_mfma_f32_16x16x32_bf16 v[112:115], v[180:183], v[188:191], v[112:115]
	v_mfma_f32_16x16x32_bf16 v[100:103], v[172:175], v[196:199], v[100:103]
	v_mfma_f32_16x16x32_bf16 v[96:99], v[180:183], v[196:199], v[96:99]
	v_mfma_f32_16x16x32_bf16 v[84:87], v[172:175], v[204:207], v[84:87]
	v_mfma_f32_16x16x32_bf16 v[80:83], v[180:183], v[204:207], v[80:83]
	v_mfma_f32_16x16x32_bf16 v[68:71], v[172:175], v[212:215], v[68:71]
	v_mfma_f32_16x16x32_bf16 v[64:67], v[180:183], v[212:215], v[64:67]
	s_setprio 0
	s_barrier
	s_mov_b32 m0, s66
	v_lshl_add_u64 v[216:217], v[216:217], 0, s[12:13]
	ds_read_b128 v[184:187], v149 offset:49152
	ds_read_b128 v[188:191], v149 offset:50176
	ds_read_b128 v[192:195], v149 offset:51200
	ds_read_b128 v[196:199], v149 offset:52224
	ds_read_b128 v[200:203], v149 offset:53248
	ds_read_b128 v[204:207], v149 offset:54272
	ds_read_b128 v[208:211], v149 offset:55296
	ds_read_b128 v[212:215], v149 offset:56320
	global_load_lds_dwordx4 v[216:217], off
	v_lshl_add_u64 v[216:217], v[218:219], 0, s[12:13]
	s_mov_b32 m0, s65
	s_nop 0
	global_load_lds_dwordx4 v[216:217], off
	s_mov_b32 m0, s78
	s_nop 0
	global_load_lds_dwordx4 v130, s[34:35]
	s_mov_b32 m0, s77
	s_nop 0
	global_load_lds_dwordx4 v134, s[34:35]
	v_lshl_add_u64 v[216:217], v[220:221], 0, s[12:13]
	s_mov_b32 m0, s58
	s_nop 0
	global_load_lds_dwordx4 v[216:217], off
	v_lshl_add_u64 v[216:217], v[222:223], 0, s[12:13]
	s_mov_b32 m0, s59
	s_nop 0
	global_load_lds_dwordx4 v[216:217], off
	s_waitcnt vmcnt(8)
	s_waitcnt lgkmcnt(0)
	s_barrier
	s_setprio 1
	s_waitcnt lgkmcnt(0)
	v_mfma_f32_16x16x32_bf16 v[60:63], v[152:155], v[184:187], v[60:63]
	v_mfma_f32_16x16x32_bf16 v[56:59], v[160:163], v[184:187], v[56:59]
	v_mfma_f32_16x16x32_bf16 v[44:47], v[152:155], v[192:195], v[44:47]
	v_mfma_f32_16x16x32_bf16 v[40:43], v[160:163], v[192:195], v[40:43]
	v_mfma_f32_16x16x32_bf16 v[28:31], v[152:155], v[200:203], v[28:31]
	v_mfma_f32_16x16x32_bf16 v[24:27], v[160:163], v[200:203], v[24:27]
	v_mfma_f32_16x16x32_bf16 v[12:15], v[152:155], v[208:211], v[12:15]
	v_mfma_f32_16x16x32_bf16 v[8:11], v[160:163], v[208:211], v[8:11]
	v_mfma_f32_16x16x32_bf16 v[60:63], v[156:159], v[188:191], v[60:63]
	v_mfma_f32_16x16x32_bf16 v[56:59], v[164:167], v[188:191], v[56:59]
	v_mfma_f32_16x16x32_bf16 v[44:47], v[156:159], v[196:199], v[44:47]
	v_mfma_f32_16x16x32_bf16 v[40:43], v[164:167], v[196:199], v[40:43]
	v_mfma_f32_16x16x32_bf16 v[28:31], v[156:159], v[204:207], v[28:31]
	v_mfma_f32_16x16x32_bf16 v[24:27], v[164:167], v[204:207], v[24:27]
	v_mfma_f32_16x16x32_bf16 v[12:15], v[156:159], v[212:215], v[12:15]
	v_mfma_f32_16x16x32_bf16 v[8:11], v[164:167], v[212:215], v[8:11]
	s_setprio 0
	s_setprio 1
	v_mfma_f32_16x16x32_bf16 v[52:55], v[168:171], v[184:187], v[52:55]
	v_mfma_f32_16x16x32_bf16 v[48:51], v[176:179], v[184:187], v[48:51]
	v_mfma_f32_16x16x32_bf16 v[36:39], v[168:171], v[192:195], v[36:39]
	v_mfma_f32_16x16x32_bf16 v[32:35], v[176:179], v[192:195], v[32:35]
	v_mfma_f32_16x16x32_bf16 v[20:23], v[168:171], v[200:203], v[20:23]
	v_mfma_f32_16x16x32_bf16 v[16:19], v[176:179], v[200:203], v[16:19]
	v_mfma_f32_16x16x32_bf16 v[4:7], v[168:171], v[208:211], v[4:7]
	v_mfma_f32_16x16x32_bf16 v[0:3], v[176:179], v[208:211], v[0:3]
	v_mfma_f32_16x16x32_bf16 v[52:55], v[172:175], v[188:191], v[52:55]
	v_mfma_f32_16x16x32_bf16 v[48:51], v[180:183], v[188:191], v[48:51]
	v_mfma_f32_16x16x32_bf16 v[36:39], v[172:175], v[196:199], v[36:39]
	v_mfma_f32_16x16x32_bf16 v[32:35], v[180:183], v[196:199], v[32:35]
	v_mfma_f32_16x16x32_bf16 v[20:23], v[172:175], v[204:207], v[20:23]
	v_mfma_f32_16x16x32_bf16 v[16:19], v[180:183], v[204:207], v[16:19]
	v_mfma_f32_16x16x32_bf16 v[4:7], v[172:175], v[212:215], v[4:7]
	v_mfma_f32_16x16x32_bf16 v[0:3], v[180:183], v[212:215], v[0:3]
	s_setprio 0
	s_barrier
	s_movk_i32 s36, 0x100
	s_andn2_b64 vcc, exec, s[30:31]
	s_mov_b64 s[34:35], -1
	s_mov_b64 s[30:31], 0
	s_cbranch_vccz .LBB0_1277
	s_and_b64 vcc, exec, s[14:15]
	s_cbranch_vccz .LBB0_1280
	s_barrier

;     __device__ bool next(int i, Unit& u) const { if (r0 + i >= r1) return false; return base.next(r0 + i, u); }
;     __device__ bool next(int i, Unit& u) const { const int L = i * G + c; if (L >= 256) return false; u.pm = L; u.pn = L >> 3; return true; }
; #define PG8_STAGE(bufoff, gbase, voff) do { _Pragma("unroll") for (int _i = 0; _i < 2; ++_i) \
;         __builtin_amdgcn_global_load_lds((const unsigned*)((const char*)(gbase) + (voff)[_i]), (LAS unsigned*)(lds + (bufoff) + ldsw + _i * 8192), 16, 0, 0); } while (0)
; #define PG8_WAIT_V(n) asm volatile("s_waitcnt vmcnt(" #n ")" ::: "memory")
; #define PG8_BAR __builtin_amdgcn_s_barrier()
; template <class Epi, class Sched>
; __device__ __forceinline__ void gemm_phase(LAS unsigned char* lds, const Gemm g, const Sched& S, const Epi& E, int wave_id) {
;     ...
;     PG8_STAGE(PG8_SB(0, 0), cB, voffB); PG8_STAGE(PG8_SB(0, 1), cB + hstepB, voffB); PG8_STAGE(PG8_SA(0, 0), cA, voffA); PG8_STAGE(PG8_SA(0, 1), cA + hstepA, voffA);
;     if (wr == 1) PG8_BAR;
;     PG8_WAIT_V(2); PG8_BAR;
;     PG8_STAGE(PG8_SB(1, 0), cB + kstep, voffB); PG8_STAGE(PG8_SA(1, 0), cA + kstep, voffA); PG8_STAGE(PG8_SB(1, 1), cB + hstepB + kstep, voffB);
;     PG8_WAIT_V(6); PG8_BAR;
;     for (;;) {
;         const bool has_next = S.next(ui + 1, nxt);
;         const char* nA = has_next ? (const char*)g.A + (size_t)nxt.pm * tstepA : cA; const char* nB = has_next ? (const char*)g.Bt + (size_t)nxt.pn * tstepB : cB;
;     __device__ __forceinline__ void operator()(f32x4 (&acc)[2][2][4][2], const pg8::Unit& u, int wr, int wc, int fr, int fq) const {
;     ...
;         if (MODE == EM_RES2) {
; #pragma unroll
;             for (int bj = 0; bj < 2; ++bj) { const float* fg = x + u.pn * 256 + bj * 128 + wc * 32 + fq * 8; cv[bj][0] = *(const f32x4*)fg; cv[bj][1] = *(const f32x4*)(fg + 4); } }
.LBB0_1372:
	s_mov_b64 s[22:23], 0x80
	s_bfe_u32 s18, s80, 0x20006
	s_add_i32 m0, s37, 0x18000
	v_lshl_add_u64 v[6:7], v[6:7], 0, s[22:23]
	s_lshl_b32 s5, s6, 13
	s_lshl_b32 s36, s18, 5
	s_lshl_b32 s7, s18, 12
	s_waitcnt vmcnt(2)
	s_barrier
	global_load_lds_dwordx4 v[6:7], off
	v_lshl_add_u64 v[4:5], v[4:5], 0, s[22:23]
	s_add_i32 m0, s37, 0x1a000
	s_add_i32 s55, s37, 0x8000
	s_add_i32 s56, s37, 0xa000
	global_load_lds_dwordx4 v[4:5], off
	v_lshl_add_u64 v[0:1], v[0:1], 0, s[22:23]
	s_mov_b32 m0, s55
	s_add_u32 s8, s46, 0x40080
	global_load_lds_dwordx4 v[0:1], off
	v_lshl_add_u64 v[0:1], v[2:3], 0, s[22:23]
	s_mov_b32 m0, s56
	s_addc_u32 s9, s47, 0
	global_load_lds_dwordx4 v[0:1], off
	s_add_i32 m0, s37, 0x1c000
	s_nop 0
	global_load_lds_dwordx4 v154, s[8:9]
	v_lshl_add_u64 v[0:1], s[8:9], 0, v[158:159]
	s_add_i32 m0, s37, 0x1e000
	v_bfe_u32 v2, v9, 4, 2
	global_load_lds_dwordx4 v[0:1], off
	v_and_b32_e32 v1, 15, v9
	s_cmpk_lt_u32 s80, 0x100
	v_readlane_b32 s8, v255, 1
	v_lshl_or_b32 v163, s6, 6, v1
	v_lshlrev_b32_e32 v3, 4, v2
	v_lshlrev_b32_e32 v4, 2, v9
	s_cselect_b64 s[24:25], -1, 0
	s_or_b32 s6, s18, s6
	s_ashr_i32 s57, s8, 31
	s_mov_b32 s58, s8
	s_lshl_b32 s8, s18, 7
	v_lshl_or_b32 v3, v1, 6, v3
	v_and_b32_e32 v4, 32, v4
	v_or3_b32 v1, s6, v1, v2
	v_readlane_b32 s9, v255, 2
	s_add_u32 s8, s68, s8
	v_bitop3_b32 v165, v3, s7, v4 bitop3:0xde
	v_cmp_eq_u32_e64 s[6:7], 0, v1
	s_addc_u32 s9, s69, 0
	v_lshlrev_b32_e32 v1, 14, v8
	s_add_u32 s26, s92, 0x1f440000
	v_and_b32_e32 v1, 0xffff8000, v1
	s_sext_i32_i8 s11, s4
	v_lshlrev_b32_e32 v0, 3, v2
	v_bitop3_b32 v5, v3, s5, v4 bitop3:0xde
	v_cmp_eq_u32_e64 s[4:5], 0, v2
	v_lshlrev_b32_e32 v160, 5, v2
	s_addc_u32 s27, s93, 0
	v_lshl_add_u32 v1, v10, 11, v1
	v_and_b32_e32 v2, 1, v8
	s_add_u32 s28, s92, 0x13400000
	v_lshl_or_b32 v1, v2, 6, v1
	s_addc_u32 s29, s93, 0
	v_lshl_add_u32 v168, v11, 1, v1
	v_lshlrev_b32_e32 v1, 14, v12
	s_add_u32 s30, s92, 0x1f480000
	v_and_b32_e32 v1, 0xffff8000, v1
	s_addc_u32 s31, s93, 0
	v_lshl_add_u32 v1, v13, 11, v1
	v_and_b32_e32 v2, 1, v12
	s_waitcnt vmcnt(6)
	s_add_u32 s59, s92, 0x1f604000
	v_lshl_or_b32 v1, v2, 6, v1
	v_or_b32_e32 v162, s36, v0
	s_addc_u32 s60, s93, 0
	v_lshl_add_u32 v170, v14, 1, v1
	s_add_i32 s61, 0, 0x10000
	s_add_i32 s62, 0, 0x14000
	v_mbcnt_lo_u32_b32 v1, -1, 0
	v_or_b32_e32 v164, 0x80, v162
	v_lshl_add_u64 v[166:167], s[8:9], 0, v[160:161]
	v_mov_b32_e32 v169, v161
	v_mov_b32_e32 v171, v161
	v_mov_b64_e32 v[172:173], 0x200
	v_mov_b64_e32 v[174:175], 0x1ff
	v_add_u32_e32 v200, s61, v165
	v_add_u32_e32 v201, s62, v165
	v_add_u32_e32 v202, 0, v5
	v_mbcnt_hi_u32_b32 v203, -1, v1
	v_mov_b32_e32 v204, 0x358637bd
	s_mov_b32 s34, 0x3a800000
	s_mov_b32 s63, 0x800000
	s_lshl_b32 s18, s36, 2
	v_lshlrev_b32_e32 v160, 2, v0
	s_mov_b32 s36, 0x358637bd
	s_mov_b32 s64, s19
	s_barrier
	s_branch .LBB0_1375

;     __device__ bool next(int i, Unit& u) const { if (r0 + i >= r1) return false; return base.next(r0 + i, u); }
;     __device__ bool next(int i, Unit& u) const { const int L = i * G + c; if (L >= 256) return false; u.pm = L; u.pn = L >> 3; return true; }
; #define PG8_STAGE(bufoff, gbase, voff) do { _Pragma("unroll") for (int _i = 0; _i < 2; ++_i) \
;         __builtin_amdgcn_global_load_lds((const unsigned*)((const char*)(gbase) + (voff)[_i]), (LAS unsigned*)(lds + (bufoff) + ldsw + _i * 8192), 16, 0, 0); } while (0)
; #define PG8_LDA(dst, b, h) do { _Pragma("unroll") for (int m = 0; m < 4; ++m) _Pragma("unroll") for (int k = 0; k < 2; ++k) dst[m][k] = *(const LAS bf16x8*)(lds + PG8_SA(b, h) + aoff + m * 2048 + k * 1024); } while (0)
; #define PG8_LDB(dst, b, h) do { _Pragma("unroll") for (int n = 0; n < 2; ++n) _Pragma("unroll") for (int k = 0; k < 2; ++k) dst[n][k] = *(const LAS bf16x8*)(lds + PG8_SB(b, h) + boff + n * 2048 + k * 1024); } while (0)
; #define PG8_WAIT_V(n) asm volatile("s_waitcnt vmcnt(" #n ")" ::: "memory")
; #define PG8_WAIT_L(n) asm volatile("s_waitcnt lgkmcnt(" #n ")" ::: "memory")
; template <class Epi, class Sched>
; __device__ __forceinline__ void gemm_phase(LAS unsigned char* lds, const Gemm g, const Sched& S, const Epi& E, int wave_id) {
;     ...
;         const bool has_next = S.next(ui + 1, nxt);
;         const char* nA = has_next ? (const char*)g.A + (size_t)nxt.pm * tstepA : cA; const char* nB = has_next ? (const char*)g.Bt + (size_t)nxt.pn * tstepB : cB;
;         for (int t = 0; t < nt; t += 2) {
;             const bool last = (t == nt - 2);
;             const char* a1 = cA + (size_t)(t + 1) * kstep;
;             const char* a2 = last ? nA : cA + (size_t)(t + 2) * kstep; const char* b2 = last ? nB : cB + (size_t)(t + 2) * kstep;
;             const char* a3 = a2 + kstep; const char* b3 = b2 + kstep;
;             PG8_LDB(B0, 0, 0); PG8_LDB(B1, 0, 1); PG8_SCHED; PG8_LDA(At, 0, 0); PG8_STAGE(PG8_SA(1, 1), a1 + hstepA, voffA);
;             PG8_WAIT_V(8); PG8_WAIT_L(0); PG8_BAR; PG8_MMA(0, 0, At, B0); PG8_MMA(0, 1, At, B1); PG8_BAR; PG8_SCHED;
;             PG8_LDA(At, 0, 1); PG8_STAGE(PG8_SB(0, 0), b2, voffB); PG8_STAGE(PG8_SB(0, 1), b2 + hstepB, voffB); PG8_STAGE(PG8_SA(0, 0), a2, voffA);
;             PG8_WAIT_V(8); PG8_WAIT_L(0); PG8_BAR; PG8_MMA(1, 0, At, B0); PG8_MMA(1, 1, At, B1); PG8_BAR; PG8_SCHED;
.LBB0_1381:
	s_ashr_i32 s41, s40, 31
	s_lshl_b64 s[42:43], s[40:41], 19
	s_add_u32 s42, s16, s42
	s_addc_u32 s43, s17, s43
	s_and_b64 s[44:45], s[8:9], exec
	s_cselect_b32 s41, s43, s13
	s_cselect_b32 s50, s42, s12
	s_ashr_i32 s39, s38, 31
	s_lshl_b64 s[44:45], s[38:39], 19
	s_add_u32 s44, s3, s44
	s_addc_u32 s45, s33, s45
	s_and_b64 s[48:49], s[8:9], exec
	s_cselect_b32 s39, s45, s47
	s_cselect_b32 s51, s44, s46
	s_add_u32 s12, s12, 0x40080
	s_addc_u32 s13, s13, 0
	s_add_u32 s65, s46, 0x100
	s_addc_u32 s66, s47, 0
	s_mov_b32 s67, -2
	s_waitcnt vmcnt(0)
	ds_read_b128 v[8:11], v200
	ds_read_b128 v[12:15], v200 offset:1024
	ds_read_b128 v[16:19], v200 offset:2048
	ds_read_b128 v[20:23], v200 offset:3072
	ds_read_b128 v[144:147], v201
	ds_read_b128 v[148:151], v201 offset:1024
	ds_read_b128 v[176:179], v201 offset:2048
	ds_read_b128 v[180:183], v201 offset:3072
	s_add_u32 s46, s12, 0xfffc0080
	s_addc_u32 s47, s13, -1
	s_cmp_eq_u32 s67, 12
	s_cselect_b32 s49, s41, s47
	s_cselect_b32 s48, s50, s46
	s_cselect_b32 s47, s39, s66
	s_cselect_b32 s46, s51, s65
	s_add_i32 m0, s37, 0xc000
	ds_read_b128 v[184:187], v202
	ds_read_b128 v[188:191], v202 offset:1024
	ds_read_b128 v[192:195], v202 offset:2048
	ds_read_b128 v[196:199], v202 offset:3072
	ds_read_b128 v[206:209], v202 offset:4096
	ds_read_b128 v[210:213], v202 offset:5120
	ds_read_b128 v[214:217], v202 offset:6144
	ds_read_b128 v[218:221], v202 offset:7168
	global_load_lds_dwordx4 v168, s[12:13]
	s_add_i32 m0, s37, 0xe000
	s_nop 0
	global_load_lds_dwordx4 v170, s[12:13]
	s_waitcnt vmcnt(8)
	s_waitcnt lgkmcnt(0)
	s_barrier
	s_setprio 1
	s_waitcnt lgkmcnt(0)
	v_mfma_f32_16x16x32_bf16 v[140:143], v[8:11], v[184:187], 0
	v_mfma_f32_16x16x32_bf16 v[136:139], v[16:19], v[184:187], 0
	v_mfma_f32_16x16x32_bf16 v[124:127], v[8:11], v[192:195], 0
	v_mfma_f32_16x16x32_bf16 v[120:123], v[16:19], v[192:195], 0
	v_mfma_f32_16x16x32_bf16 v[108:111], v[8:11], v[206:209], 0
	v_mfma_f32_16x16x32_bf16 v[104:107], v[16:19], v[206:209], 0
	v_mfma_f32_16x16x32_bf16 v[92:95], v[8:11], v[214:217], 0
	v_mfma_f32_16x16x32_bf16 v[88:91], v[16:19], v[214:217], 0
	v_mfma_f32_16x16x32_bf16 v[140:143], v[12:15], v[188:191], v[140:143]
	v_mfma_f32_16x16x32_bf16 v[136:139], v[20:23], v[188:191], v[136:139]
	v_mfma_f32_16x16x32_bf16 v[124:127], v[12:15], v[196:199], v[124:127]
	v_mfma_f32_16x16x32_bf16 v[120:123], v[20:23], v[196:199], v[120:123]
	v_mfma_f32_16x16x32_bf16 v[108:111], v[12:15], v[210:213], v[108:111]
	v_mfma_f32_16x16x32_bf16 v[104:107], v[20:23], v[210:213], v[104:107]
	v_mfma_f32_16x16x32_bf16 v[92:95], v[12:15], v[218:221], v[92:95]
	v_mfma_f32_16x16x32_bf16 v[88:91], v[20:23], v[218:221], v[88:91]
	s_setprio 0
	s_setprio 1
	v_mfma_f32_16x16x32_bf16 v[132:135], v[144:147], v[184:187], 0
	v_mfma_f32_16x16x32_bf16 v[128:131], v[176:179], v[184:187], 0
	v_mfma_f32_16x16x32_bf16 v[116:119], v[144:147], v[192:195], 0
	v_mfma_f32_16x16x32_bf16 v[112:115], v[176:179], v[192:195], 0
	v_mfma_f32_16x16x32_bf16 v[100:103], v[144:147], v[206:209], 0
	v_mfma_f32_16x16x32_bf16 v[96:99], v[176:179], v[206:209], 0
	v_mfma_f32_16x16x32_bf16 v[84:87], v[144:147], v[214:217], 0
	v_mfma_f32_16x16x32_bf16 v[80:83], v[176:179], v[214:217], 0
	v_mfma_f32_16x16x32_bf16 v[132:135], v[148:151], v[188:191], v[132:135]
	v_mfma_f32_16x16x32_bf16 v[128:131], v[180:183], v[188:191], v[128:131]
	v_mfma_f32_16x16x32_bf16 v[116:119], v[148:151], v[196:199], v[116:119]
	v_mfma_f32_16x16x32_bf16 v[112:115], v[180:183], v[196:199], v[112:115]
	v_mfma_f32_16x16x32_bf16 v[100:103], v[148:151], v[210:213], v[100:103]
	v_mfma_f32_16x16x32_bf16 v[96:99], v[180:183], v[210:213], v[96:99]
	v_mfma_f32_16x16x32_bf16 v[84:87], v[148:151], v[218:221], v[84:87]
	v_mfma_f32_16x16x32_bf16 v[80:83], v[180:183], v[218:221], v[80:83]
	s_setprio 0
	s_barrier
	s_add_i32 s72, s61, s35
	v_lshl_add_u64 v[222:223], s[46:47], 0, v[154:155]
	s_mov_b32 m0, s72
	ds_read_b128 v[184:187], v202 offset:16384
	ds_read_b128 v[188:191], v202 offset:17408
	ds_read_b128 v[192:195], v202 offset:18432
	ds_read_b128 v[196:199], v202 offset:19456
	ds_read_b128 v[206:209], v202 offset:20480
	ds_read_b128 v[210:213], v202 offset:21504
	ds_read_b128 v[214:217], v202 offset:22528
	ds_read_b128 v[218:221], v202 offset:23552
	global_load_lds_dwordx4 v[222:223], off
	s_add_i32 m0, s72, 0x2000
	s_add_u32 s72, s46, 0x40000
	v_lshl_add_u64 v[224:225], s[46:47], 0, v[158:159]
	s_addc_u32 s73, s47, 0
	s_add_i32 s74, s62, s35
	global_load_lds_dwordx4 v[224:225], off
	s_mov_b32 m0, s74
	v_lshl_add_u64 v[228:229], s[48:49], 0, v[156:157]
	global_load_lds_dwordx4 v154, s[72:73]
	s_add_i32 m0, s74, 0x2000
	s_nop 0
	global_load_lds_dwordx4 v158, s[72:73]
	v_lshl_add_u64 v[226:227], s[48:49], 0, v[152:153]
	s_mov_b32 m0, s37
	s_nop 0
	global_load_lds_dwordx4 v[226:227], off
	s_mov_b32 m0, s52
	s_nop 0
	global_load_lds_dwordx4 v[228:229], off
	s_waitcnt vmcnt(8)
	s_waitcnt lgkmcnt(0)
	s_barrier
; #define PG8_STAGE(bufoff, gbase, voff) do { _Pragma("unroll") for (int _i = 0; _i < 2; ++_i) \
;         __builtin_amdgcn_global_load_lds((const unsigned*)((const char*)(gbase) + (voff)[_i]), (LAS unsigned*)(lds + (bufoff) + ldsw + _i * 8192), 16, 0, 0); } while (0)
; #define PG8_LDA(dst, b, h) do { _Pragma("unroll") for (int m = 0; m < 4; ++m) _Pragma("unroll") for (int k = 0; k < 2; ++k) dst[m][k] = *(const LAS bf16x8*)(lds + PG8_SA(b, h) + aoff + m * 2048 + k * 1024); } while (0)
; #define PG8_LDB(dst, b, h) do { _Pragma("unroll") for (int n = 0; n < 2; ++n) _Pragma("unroll") for (int k = 0; k < 2; ++k) dst[n][k] = *(const LAS bf16x8*)(lds + PG8_SB(b, h) + boff + n * 2048 + k * 1024); } while (0)
; #define PG8_MMA(ai, bj, At, Bt) do { __builtin_amdgcn_s_setprio(1); _Pragma("unroll") for (int m = 0; m < 4; ++m) _Pragma("unroll") for (int n = 0; n < 2; ++n) _Pragma("unroll") for (int k = 0; k < 2; ++k) \
;         acc[ai][bj][m][n] = __builtin_amdgcn_mfma_f32_16x16x32_bf16(Bt[n][k], At[m][k], acc[ai][bj][m][n], 0, 0, 0); __builtin_amdgcn_s_setprio(0); } while (0)
; #define PG8_WAIT_V(n) asm volatile("s_waitcnt vmcnt(" #n ")" ::: "memory")
; #define PG8_WAIT_L(n) asm volatile("s_waitcnt lgkmcnt(" #n ")" ::: "memory")
; #define PG8_BAR __builtin_amdgcn_s_barrier()
; #define PG8_SCHED __builtin_amdgcn_sched_barrier(0)
; template <class Epi, class Sched>
; __device__ __forceinline__ void gemm_phase(LAS unsigned char* lds, const Gemm g, const Sched& S, const Epi& E, int wave_id) {
;     ...
;             PG8_LDB(B0, 1, 0); PG8_LDB(B1, 1, 1); PG8_SCHED; PG8_LDA(At, 1, 0); PG8_STAGE(PG8_SA(0, 1), a2 + hstepA, voffA);
;             PG8_WAIT_V(8); PG8_WAIT_L(0); PG8_BAR; PG8_MMA(0, 0, At, B0); PG8_MMA(0, 1, At, B1); PG8_BAR; PG8_SCHED;
	s_setprio 1
	s_waitcnt lgkmcnt(0)
	v_mfma_f32_16x16x32_bf16 v[76:79], v[8:11], v[184:187], 0
	v_mfma_f32_16x16x32_bf16 v[72:75], v[16:19], v[184:187], 0
	v_mfma_f32_16x16x32_bf16 v[60:63], v[8:11], v[192:195], 0
	v_mfma_f32_16x16x32_bf16 v[56:59], v[16:19], v[192:195], 0
	v_mfma_f32_16x16x32_bf16 v[44:47], v[8:11], v[206:209], 0
	v_mfma_f32_16x16x32_bf16 v[40:43], v[16:19], v[206:209], 0
	v_mfma_f32_16x16x32_bf16 v[8:11], v[8:11], v[214:217], 0
	v_mfma_f32_16x16x32_bf16 v[76:79], v[12:15], v[188:191], v[76:79]
	v_mfma_f32_16x16x32_bf16 v[72:75], v[20:23], v[188:191], v[72:75]
	v_mfma_f32_16x16x32_bf16 v[60:63], v[12:15], v[196:199], v[60:63]
	v_mfma_f32_16x16x32_bf16 v[56:59], v[20:23], v[196:199], v[56:59]
	v_mfma_f32_16x16x32_bf16 v[44:47], v[12:15], v[210:213], v[44:47]
	v_mfma_f32_16x16x32_bf16 v[40:43], v[20:23], v[210:213], v[40:43]
	v_mfma_f32_16x16x32_bf16 v[8:11], v[12:15], v[218:221], v[8:11]
	v_mfma_f32_16x16x32_bf16 v[12:15], v[16:19], v[214:217], 0
	v_mfma_f32_16x16x32_bf16 v[12:15], v[20:23], v[218:221], v[12:15]
	s_setprio 0
	s_setprio 1
	v_mfma_f32_16x16x32_bf16 v[24:27], v[144:147], v[192:195], 0
	v_mfma_f32_16x16x32_bf16 v[52:55], v[148:151], v[196:199], v[24:27]
	v_mfma_f32_16x16x32_bf16 v[24:27], v[176:179], v[192:195], 0
	v_mfma_f32_16x16x32_bf16 v[48:51], v[180:183], v[196:199], v[24:27]
	v_mfma_f32_16x16x32_bf16 v[24:27], v[144:147], v[206:209], 0
	v_mfma_f32_16x16x32_bf16 v[36:39], v[148:151], v[210:213], v[24:27]
	v_mfma_f32_16x16x32_bf16 v[24:27], v[176:179], v[206:209], 0
	v_mfma_f32_16x16x32_bf16 v[4:7], v[144:147], v[214:217], 0
	v_mfma_f32_16x16x32_bf16 v[0:3], v[176:179], v[214:217], 0
	v_mfma_f32_16x16x32_bf16 v[16:19], v[144:147], v[184:187], 0
	v_mfma_f32_16x16x32_bf16 v[20:23], v[176:179], v[184:187], 0
	v_mfma_f32_16x16x32_bf16 v[32:35], v[180:183], v[210:213], v[24:27]
	v_mfma_f32_16x16x32_bf16 v[4:7], v[148:151], v[218:221], v[4:7]
	v_mfma_f32_16x16x32_bf16 v[0:3], v[180:183], v[218:221], v[0:3]
	v_mfma_f32_16x16x32_bf16 v[16:19], v[148:151], v[188:191], v[16:19]
	v_mfma_f32_16x16x32_bf16 v[20:23], v[180:183], v[188:191], v[20:23]
	s_setprio 0
	s_barrier
	s_add_i32 s72, 0, 0x18000
	s_add_i32 s73, 0, 0x1c000
	v_add_u32_e32 v68, s72, v165
	v_add_u32_e32 v180, s73, v165
	ds_read_b128 v[24:27], v68
	ds_read_b128 v[28:31], v68 offset:1024
	ds_read_b128 v[64:67], v68 offset:2048
	ds_read_b128 v[68:71], v68 offset:3072
	ds_read_b128 v[144:147], v180
	ds_read_b128 v[148:151], v180 offset:1024
	ds_read_b128 v[176:179], v180 offset:2048
	ds_read_b128 v[180:183], v180 offset:3072
	s_add_u32 s48, s48, 0x40000
	s_addc_u32 s49, s49, 0
	s_mov_b32 m0, s53
	ds_read_b128 v[184:187], v202 offset:32768
	ds_read_b128 v[188:191], v202 offset:33792
	ds_read_b128 v[192:195], v202 offset:34816
	ds_read_b128 v[196:199], v202 offset:35840
	ds_read_b128 v[206:209], v202 offset:36864
	ds_read_b128 v[210:213], v202 offset:37888
	ds_read_b128 v[214:217], v202 offset:38912
	ds_read_b128 v[218:221], v202 offset:39936
	global_load_lds_dwordx4 v152, s[48:49]
	s_mov_b32 m0, s54
	s_nop 0
	global_load_lds_dwordx4 v156, s[48:49]
	s_waitcnt vmcnt(8)
	s_waitcnt lgkmcnt(0)
	s_barrier
	s_setprio 1
	s_waitcnt lgkmcnt(0)
	v_mfma_f32_16x16x32_bf16 v[140:143], v[24:27], v[184:187], v[140:143]
	v_mfma_f32_16x16x32_bf16 v[136:139], v[64:67], v[184:187], v[136:139]
	v_mfma_f32_16x16x32_bf16 v[124:127], v[24:27], v[192:195], v[124:127]
	v_mfma_f32_16x16x32_bf16 v[120:123], v[64:67], v[192:195], v[120:123]
	v_mfma_f32_16x16x32_bf16 v[108:111], v[24:27], v[206:209], v[108:111]
	v_mfma_f32_16x16x32_bf16 v[104:107], v[64:67], v[206:209], v[104:107]
	v_mfma_f32_16x16x32_bf16 v[92:95], v[24:27], v[214:217], v[92:95]
	v_mfma_f32_16x16x32_bf16 v[88:91], v[64:67], v[214:217], v[88:91]
	v_mfma_f32_16x16x32_bf16 v[140:143], v[28:31], v[188:191], v[140:143]
	v_mfma_f32_16x16x32_bf16 v[136:139], v[68:71], v[188:191], v[136:139]
	v_mfma_f32_16x16x32_bf16 v[124:127], v[28:31], v[196:199], v[124:127]
	v_mfma_f32_16x16x32_bf16 v[120:123], v[68:71], v[196:199], v[120:123]
	v_mfma_f32_16x16x32_bf16 v[108:111], v[28:31], v[210:213], v[108:111]
	v_mfma_f32_16x16x32_bf16 v[104:107], v[68:71], v[210:213], v[104:107]
	v_mfma_f32_16x16x32_bf16 v[92:95], v[28:31], v[218:221], v[92:95]
	v_mfma_f32_16x16x32_bf16 v[88:91], v[68:71], v[218:221], v[88:91]
	s_setprio 0
	s_setprio 1
	v_mfma_f32_16x16x32_bf16 v[132:135], v[144:147], v[184:187], v[132:135]
	v_mfma_f32_16x16x32_bf16 v[128:131], v[176:179], v[184:187], v[128:131]
	v_mfma_f32_16x16x32_bf16 v[116:119], v[144:147], v[192:195], v[116:119]
	v_mfma_f32_16x16x32_bf16 v[112:115], v[176:179], v[192:195], v[112:115]
	v_mfma_f32_16x16x32_bf16 v[100:103], v[144:147], v[206:209], v[100:103]
	v_mfma_f32_16x16x32_bf16 v[96:99], v[176:179], v[206:209], v[96:99]
	v_mfma_f32_16x16x32_bf16 v[84:87], v[144:147], v[214:217], v[84:87]
	v_mfma_f32_16x16x32_bf16 v[80:83], v[176:179], v[214:217], v[80:83]
	v_mfma_f32_16x16x32_bf16 v[132:135], v[148:151], v[188:191], v[132:135]
	v_mfma_f32_16x16x32_bf16 v[128:131], v[180:183], v[188:191], v[128:131]
	v_mfma_f32_16x16x32_bf16 v[116:119], v[148:151], v[196:199], v[116:119]
	v_mfma_f32_16x16x32_bf16 v[112:115], v[180:183], v[196:199], v[112:115]
	v_mfma_f32_16x16x32_bf16 v[100:103], v[148:151], v[210:213], v[100:103]
	v_mfma_f32_16x16x32_bf16 v[96:99], v[180:183], v[210:213], v[96:99]
	v_mfma_f32_16x16x32_bf16 v[84:87], v[148:151], v[218:221], v[84:87]
	v_mfma_f32_16x16x32_bf16 v[80:83], v[180:183], v[218:221], v[80:83]
	s_setprio 0
	s_barrier
; #define PG8_STAGE(bufoff, gbase, voff) do { _Pragma("unroll") for (int _i = 0; _i < 2; ++_i) \
;         __builtin_amdgcn_global_load_lds((const unsigned*)((const char*)(gbase) + (voff)[_i]), (LAS unsigned*)(lds + (bufoff) + ldsw + _i * 8192), 16, 0, 0); } while (0)
; #define PG8_LDA(dst, b, h) do { _Pragma("unroll") for (int m = 0; m < 4; ++m) _Pragma("unroll") for (int k = 0; k < 2; ++k) dst[m][k] = *(const LAS bf16x8*)(lds + PG8_SA(b, h) + aoff + m * 2048 + k * 1024); } while (0)
; #define PG8_LDB(dst, b, h) do { _Pragma("unroll") for (int n = 0; n < 2; ++n) _Pragma("unroll") for (int k = 0; k < 2; ++k) dst[n][k] = *(const LAS bf16x8*)(lds + PG8_SB(b, h) + boff + n * 2048 + k * 1024); } while (0)
; #define PG8_MMA(ai, bj, At, Bt) do { __builtin_amdgcn_s_setprio(1); _Pragma("unroll") for (int m = 0; m < 4; ++m) _Pragma("unroll") for (int n = 0; n < 2; ++n) _Pragma("unroll") for (int k = 0; k < 2; ++k) \
;         acc[ai][bj][m][n] = __builtin_amdgcn_mfma_f32_16x16x32_bf16(Bt[n][k], At[m][k], acc[ai][bj][m][n], 0, 0, 0); __builtin_amdgcn_s_setprio(0); } while (0)
; #define PG8_WAIT_V(n) asm volatile("s_waitcnt vmcnt(" #n ")" ::: "memory")
; #define PG8_WAIT_L(n) asm volatile("s_waitcnt lgkmcnt(" #n ")" ::: "memory")
; #define PG8_BAR __builtin_amdgcn_s_barrier()
; #define PG8_SCHED __builtin_amdgcn_sched_barrier(0)
; template <class Epi, class Sched>
; __device__ __forceinline__ void gemm_phase(LAS unsigned char* lds, const Gemm g, const Sched& S, const Epi& E, int wave_id) {
;     ...
;             PG8_LDB(B0, 0, 0); PG8_LDB(B1, 0, 1); PG8_SCHED; PG8_LDA(At, 0, 0); PG8_STAGE(PG8_SA(1, 1), a1 + hstepA, voffA);
;             PG8_WAIT_V(8); PG8_WAIT_L(0); PG8_BAR; PG8_MMA(0, 0, At, B0); PG8_MMA(0, 1, At, B1); PG8_BAR; PG8_SCHED;
;     ...
;             PG8_LDA(At, 1, 1); PG8_STAGE(PG8_SB(1, 0), b3, voffB); PG8_STAGE(PG8_SB(1, 1), b3 + hstepB, voffB); PG8_STAGE(PG8_SA(1, 0), a3, voffA);
;             PG8_WAIT_V(8); PG8_WAIT_L(0); PG8_BAR; PG8_MMA(1, 0, At, B0); PG8_MMA(1, 1, At, B1); PG8_BAR; PG8_SCHED;
	s_add_i32 s48, s72, s35
	v_lshl_add_u64 v[222:223], v[222:223], 0, s[22:23]
	s_mov_b32 m0, s48
	ds_read_b128 v[184:187], v202 offset:49152
	ds_read_b128 v[188:191], v202 offset:50176
	ds_read_b128 v[192:195], v202 offset:51200
	ds_read_b128 v[196:199], v202 offset:52224
	ds_read_b128 v[206:209], v202 offset:53248
	ds_read_b128 v[210:213], v202 offset:54272
	ds_read_b128 v[214:217], v202 offset:55296
	ds_read_b128 v[218:221], v202 offset:56320
	global_load_lds_dwordx4 v[222:223], off
	s_add_i32 m0, s48, 0x2000
	s_add_u32 s46, s46, 0x40080
	v_lshl_add_u64 v[222:223], v[224:225], 0, s[22:23]
	s_addc_u32 s47, s47, 0
	s_add_i32 s48, s73, s35
	global_load_lds_dwordx4 v[222:223], off
	s_mov_b32 m0, s48
	s_nop 0
	global_load_lds_dwordx4 v154, s[46:47]
	s_add_i32 m0, s48, 0x2000
	s_nop 0
	global_load_lds_dwordx4 v158, s[46:47]
	v_lshl_add_u64 v[222:223], v[226:227], 0, s[22:23]
	s_mov_b32 m0, s55
	s_nop 0
	global_load_lds_dwordx4 v[222:223], off
	v_lshl_add_u64 v[222:223], v[228:229], 0, s[22:23]
	s_mov_b32 m0, s56
	s_nop 0
	global_load_lds_dwordx4 v[222:223], off
	s_waitcnt vmcnt(8)
	s_waitcnt lgkmcnt(0)
	s_barrier
	s_setprio 1
	s_waitcnt lgkmcnt(0)
	v_mfma_f32_16x16x32_bf16 v[76:79], v[24:27], v[184:187], v[76:79]
	v_mfma_f32_16x16x32_bf16 v[60:63], v[24:27], v[192:195], v[60:63]
	v_mfma_f32_16x16x32_bf16 v[44:47], v[24:27], v[206:209], v[44:47]
	v_mfma_f32_16x16x32_bf16 v[8:11], v[24:27], v[214:217], v[8:11]
	v_mfma_f32_16x16x32_bf16 v[76:79], v[28:31], v[188:191], v[76:79]
	v_mfma_f32_16x16x32_bf16 v[72:75], v[64:67], v[184:187], v[72:75]
	v_mfma_f32_16x16x32_bf16 v[60:63], v[28:31], v[196:199], v[60:63]
	v_mfma_f32_16x16x32_bf16 v[56:59], v[64:67], v[192:195], v[56:59]
	v_mfma_f32_16x16x32_bf16 v[44:47], v[28:31], v[210:213], v[44:47]
	v_mfma_f32_16x16x32_bf16 v[40:43], v[64:67], v[206:209], v[40:43]
	v_mfma_f32_16x16x32_bf16 v[28:31], v[28:31], v[218:221], v[8:11]
	v_mfma_f32_16x16x32_bf16 v[8:11], v[64:67], v[214:217], v[12:15]
	v_mfma_f32_16x16x32_bf16 v[72:75], v[68:71], v[188:191], v[72:75]
	v_mfma_f32_16x16x32_bf16 v[56:59], v[68:71], v[196:199], v[56:59]
	v_mfma_f32_16x16x32_bf16 v[40:43], v[68:71], v[210:213], v[40:43]
	v_mfma_f32_16x16x32_bf16 v[24:27], v[68:71], v[218:221], v[8:11]
	s_setprio 0
	s_setprio 1
	v_mfma_f32_16x16x32_bf16 v[8:11], v[144:147], v[184:187], v[16:19]
	v_mfma_f32_16x16x32_bf16 v[68:71], v[148:151], v[188:191], v[8:11]
	v_mfma_f32_16x16x32_bf16 v[8:11], v[176:179], v[184:187], v[20:23]
	v_mfma_f32_16x16x32_bf16 v[64:67], v[180:183], v[188:191], v[8:11]
	v_mfma_f32_16x16x32_bf16 v[8:11], v[144:147], v[192:195], v[52:55]
	v_mfma_f32_16x16x32_bf16 v[52:55], v[148:151], v[196:199], v[8:11]
	v_mfma_f32_16x16x32_bf16 v[8:11], v[176:179], v[192:195], v[48:51]
	v_mfma_f32_16x16x32_bf16 v[48:51], v[180:183], v[196:199], v[8:11]
	v_mfma_f32_16x16x32_bf16 v[8:11], v[144:147], v[206:209], v[36:39]
	v_mfma_f32_16x16x32_bf16 v[36:39], v[148:151], v[210:213], v[8:11]
	v_mfma_f32_16x16x32_bf16 v[8:11], v[176:179], v[206:209], v[32:35]
	v_mfma_f32_16x16x32_bf16 v[4:7], v[144:147], v[214:217], v[4:7]
	v_mfma_f32_16x16x32_bf16 v[0:3], v[176:179], v[214:217], v[0:3]
	v_mfma_f32_16x16x32_bf16 v[32:35], v[180:183], v[210:213], v[8:11]
	v_mfma_f32_16x16x32_bf16 v[4:7], v[148:151], v[218:221], v[4:7]
	v_mfma_f32_16x16x32_bf16 v[0:3], v[180:183], v[218:221], v[0:3]
	s_setprio 0
	s_barrier
	s_add_i32 s67, s67, 2
	s_add_u32 s12, s12, 0x100
	s_addc_u32 s13, s13, 0
	s_add_u32 s65, s65, 0x100
	s_addc_u32 s66, s66, 0
	s_cmp_gt_u32 s67, 13
.LBB0_1382:
	ds_read_b128 v[8:11], v200
	ds_read_b128 v[12:15], v200 offset:1024
	ds_read_b128 v[16:19], v200 offset:2048
	ds_read_b128 v[20:23], v200 offset:3072
	ds_read_b128 v[144:147], v201
	ds_read_b128 v[148:151], v201 offset:1024
	ds_read_b128 v[176:179], v201 offset:2048
	ds_read_b128 v[180:183], v201 offset:3072
	s_add_u32 s46, s12, 0xfffc0080
	s_addc_u32 s47, s13, -1
	s_cmp_eq_u32 s67, 12
	s_cselect_b32 s49, s41, s47
	s_cselect_b32 s48, s50, s46
	s_cselect_b32 s47, s39, s66
	s_cselect_b32 s46, s51, s65
	s_add_i32 m0, s37, 0xc000
	ds_read_b128 v[184:187], v202
	ds_read_b128 v[188:191], v202 offset:1024
	ds_read_b128 v[192:195], v202 offset:2048
	ds_read_b128 v[196:199], v202 offset:3072
	ds_read_b128 v[206:209], v202 offset:4096
	ds_read_b128 v[210:213], v202 offset:5120
	ds_read_b128 v[214:217], v202 offset:6144
	ds_read_b128 v[218:221], v202 offset:7168
	global_load_lds_dwordx4 v168, s[12:13]
	s_add_i32 m0, s37, 0xe000
	s_nop 0
	global_load_lds_dwordx4 v170, s[12:13]
	s_waitcnt vmcnt(8)
	s_waitcnt lgkmcnt(0)
	s_barrier
; #define PG8_STAGE(bufoff, gbase, voff) do { _Pragma("unroll") for (int _i = 0; _i < 2; ++_i) \
;         __builtin_amdgcn_global_load_lds((const unsigned*)((const char*)(gbase) + (voff)[_i]), (LAS unsigned*)(lds + (bufoff) + ldsw + _i * 8192), 16, 0, 0); } while (0)
; #define PG8_LDA(dst, b, h) do { _Pragma("unroll") for (int m = 0; m < 4; ++m) _Pragma("unroll") for (int k = 0; k < 2; ++k) dst[m][k] = *(const LAS bf16x8*)(lds + PG8_SA(b, h) + aoff + m * 2048 + k * 1024); } while (0)
; #define PG8_LDB(dst, b, h) do { _Pragma("unroll") for (int n = 0; n < 2; ++n) _Pragma("unroll") for (int k = 0; k < 2; ++k) dst[n][k] = *(const LAS bf16x8*)(lds + PG8_SB(b, h) + boff + n * 2048 + k * 1024); } while (0)
; #define PG8_MMA(ai, bj, At, Bt) do { __builtin_amdgcn_s_setprio(1); _Pragma("unroll") for (int m = 0; m < 4; ++m) _Pragma("unroll") for (int n = 0; n < 2; ++n) _Pragma("unroll") for (int k = 0; k < 2; ++k) \
;         acc[ai][bj][m][n] = __builtin_amdgcn_mfma_f32_16x16x32_bf16(Bt[n][k], At[m][k], acc[ai][bj][m][n], 0, 0, 0); __builtin_amdgcn_s_setprio(0); } while (0)
; #define PG8_WAIT_V(n) asm volatile("s_waitcnt vmcnt(" #n ")" ::: "memory")
; #define PG8_WAIT_L(n) asm volatile("s_waitcnt lgkmcnt(" #n ")" ::: "memory")
; #define PG8_BAR __builtin_amdgcn_s_barrier()
; #define PG8_SCHED __builtin_amdgcn_sched_barrier(0)
; template <class Epi, class Sched>
; __device__ __forceinline__ void gemm_phase(LAS unsigned char* lds, const Gemm g, const Sched& S, const Epi& E, int wave_id) {
;     ...
;             PG8_LDB(B0, 0, 0); PG8_LDB(B1, 0, 1); PG8_SCHED; PG8_LDA(At, 0, 0); PG8_STAGE(PG8_SA(1, 1), a1 + hstepA, voffA);
;             PG8_WAIT_V(8); PG8_WAIT_L(0); PG8_BAR; PG8_MMA(0, 0, At, B0); PG8_MMA(0, 1, At, B1); PG8_BAR; PG8_SCHED;
;             PG8_LDA(At, 0, 1); PG8_STAGE(PG8_SB(0, 0), b2, voffB); PG8_STAGE(PG8_SB(0, 1), b2 + hstepB, voffB); PG8_STAGE(PG8_SA(0, 0), a2, voffA);
;             PG8_WAIT_V(8); PG8_WAIT_L(0); PG8_BAR; PG8_MMA(1, 0, At, B0); PG8_MMA(1, 1, At, B1); PG8_BAR; PG8_SCHED;
	s_setprio 1
	s_waitcnt lgkmcnt(0)
	v_mfma_f32_16x16x32_bf16 v[140:143], v[8:11], v[184:187], v[140:143]
	v_mfma_f32_16x16x32_bf16 v[136:139], v[16:19], v[184:187], v[136:139]
	v_mfma_f32_16x16x32_bf16 v[124:127], v[8:11], v[192:195], v[124:127]
	v_mfma_f32_16x16x32_bf16 v[120:123], v[16:19], v[192:195], v[120:123]
	v_mfma_f32_16x16x32_bf16 v[108:111], v[8:11], v[206:209], v[108:111]
	v_mfma_f32_16x16x32_bf16 v[104:107], v[16:19], v[206:209], v[104:107]
	v_mfma_f32_16x16x32_bf16 v[92:95], v[8:11], v[214:217], v[92:95]
	v_mfma_f32_16x16x32_bf16 v[88:91], v[16:19], v[214:217], v[88:91]
	v_mfma_f32_16x16x32_bf16 v[140:143], v[12:15], v[188:191], v[140:143]
	v_mfma_f32_16x16x32_bf16 v[136:139], v[20:23], v[188:191], v[136:139]
	v_mfma_f32_16x16x32_bf16 v[124:127], v[12:15], v[196:199], v[124:127]
	v_mfma_f32_16x16x32_bf16 v[120:123], v[20:23], v[196:199], v[120:123]
	v_mfma_f32_16x16x32_bf16 v[108:111], v[12:15], v[210:213], v[108:111]
	v_mfma_f32_16x16x32_bf16 v[104:107], v[20:23], v[210:213], v[104:107]
	v_mfma_f32_16x16x32_bf16 v[92:95], v[12:15], v[218:221], v[92:95]
	v_mfma_f32_16x16x32_bf16 v[88:91], v[20:23], v[218:221], v[88:91]
	s_setprio 0
	s_setprio 1
	v_mfma_f32_16x16x32_bf16 v[132:135], v[144:147], v[184:187], v[132:135]
	v_mfma_f32_16x16x32_bf16 v[128:131], v[176:179], v[184:187], v[128:131]
	v_mfma_f32_16x16x32_bf16 v[116:119], v[144:147], v[192:195], v[116:119]
	v_mfma_f32_16x16x32_bf16 v[112:115], v[176:179], v[192:195], v[112:115]
	v_mfma_f32_16x16x32_bf16 v[100:103], v[144:147], v[206:209], v[100:103]
	v_mfma_f32_16x16x32_bf16 v[96:99], v[176:179], v[206:209], v[96:99]
	v_mfma_f32_16x16x32_bf16 v[84:87], v[144:147], v[214:217], v[84:87]
	v_mfma_f32_16x16x32_bf16 v[80:83], v[176:179], v[214:217], v[80:83]
	v_mfma_f32_16x16x32_bf16 v[132:135], v[148:151], v[188:191], v[132:135]
	v_mfma_f32_16x16x32_bf16 v[128:131], v[180:183], v[188:191], v[128:131]
	v_mfma_f32_16x16x32_bf16 v[116:119], v[148:151], v[196:199], v[116:119]
	v_mfma_f32_16x16x32_bf16 v[112:115], v[180:183], v[196:199], v[112:115]
	v_mfma_f32_16x16x32_bf16 v[100:103], v[148:151], v[210:213], v[100:103]
	v_mfma_f32_16x16x32_bf16 v[96:99], v[180:183], v[210:213], v[96:99]
	v_mfma_f32_16x16x32_bf16 v[84:87], v[148:151], v[218:221], v[84:87]
	v_mfma_f32_16x16x32_bf16 v[80:83], v[180:183], v[218:221], v[80:83]
	s_setprio 0
	s_barrier
	s_add_i32 s72, s61, s35
	v_lshl_add_u64 v[222:223], s[46:47], 0, v[154:155]
	s_mov_b32 m0, s72
	ds_read_b128 v[184:187], v202 offset:16384
	ds_read_b128 v[188:191], v202 offset:17408
	ds_read_b128 v[192:195], v202 offset:18432
	ds_read_b128 v[196:199], v202 offset:19456
	ds_read_b128 v[206:209], v202 offset:20480
	ds_read_b128 v[210:213], v202 offset:21504
	ds_read_b128 v[214:217], v202 offset:22528
	ds_read_b128 v[218:221], v202 offset:23552
	global_load_lds_dwordx4 v[222:223], off
	s_add_i32 m0, s72, 0x2000
	s_add_u32 s72, s46, 0x40000
	v_lshl_add_u64 v[224:225], s[46:47], 0, v[158:159]
	s_addc_u32 s73, s47, 0
	s_add_i32 s74, s62, s35
	global_load_lds_dwordx4 v[224:225], off
	s_mov_b32 m0, s74
	v_lshl_add_u64 v[228:229], s[48:49], 0, v[156:157]
	global_load_lds_dwordx4 v154, s[72:73]
	s_add_i32 m0, s74, 0x2000
	s_nop 0
	global_load_lds_dwordx4 v158, s[72:73]
	v_lshl_add_u64 v[226:227], s[48:49], 0, v[152:153]
	s_mov_b32 m0, s37
	s_nop 0
	global_load_lds_dwordx4 v[226:227], off
	s_mov_b32 m0, s52
	s_nop 0
	global_load_lds_dwordx4 v[228:229], off
	s_waitcnt vmcnt(8)
	s_waitcnt lgkmcnt(0)
	s_barrier
	s_setprio 1
	s_waitcnt lgkmcnt(0)
	v_mfma_f32_16x16x32_bf16 v[76:79], v[8:11], v[184:187], v[76:79]
	v_mfma_f32_16x16x32_bf16 v[72:75], v[16:19], v[184:187], v[72:75]
	v_mfma_f32_16x16x32_bf16 v[60:63], v[8:11], v[192:195], v[60:63]
	v_mfma_f32_16x16x32_bf16 v[56:59], v[16:19], v[192:195], v[56:59]
	v_mfma_f32_16x16x32_bf16 v[44:47], v[8:11], v[206:209], v[44:47]
	v_mfma_f32_16x16x32_bf16 v[40:43], v[16:19], v[206:209], v[40:43]
	v_mfma_f32_16x16x32_bf16 v[8:11], v[8:11], v[214:217], v[28:31]
	v_mfma_f32_16x16x32_bf16 v[76:79], v[12:15], v[188:191], v[76:79]
	v_mfma_f32_16x16x32_bf16 v[72:75], v[20:23], v[188:191], v[72:75]
	v_mfma_f32_16x16x32_bf16 v[60:63], v[12:15], v[196:199], v[60:63]
	v_mfma_f32_16x16x32_bf16 v[56:59], v[20:23], v[196:199], v[56:59]
	v_mfma_f32_16x16x32_bf16 v[44:47], v[12:15], v[210:213], v[44:47]
	v_mfma_f32_16x16x32_bf16 v[40:43], v[20:23], v[210:213], v[40:43]
	v_mfma_f32_16x16x32_bf16 v[8:11], v[12:15], v[218:221], v[8:11]
	v_mfma_f32_16x16x32_bf16 v[12:15], v[16:19], v[214:217], v[24:27]
	v_mfma_f32_16x16x32_bf16 v[12:15], v[20:23], v[218:221], v[12:15]
	s_setprio 0
	s_setprio 1
	v_mfma_f32_16x16x32_bf16 v[24:27], v[144:147], v[192:195], v[52:55]
	v_mfma_f32_16x16x32_bf16 v[52:55], v[148:151], v[196:199], v[24:27]
	v_mfma_f32_16x16x32_bf16 v[24:27], v[176:179], v[192:195], v[48:51]
	v_mfma_f32_16x16x32_bf16 v[48:51], v[180:183], v[196:199], v[24:27]
	v_mfma_f32_16x16x32_bf16 v[24:27], v[144:147], v[206:209], v[36:39]
	v_mfma_f32_16x16x32_bf16 v[36:39], v[148:151], v[210:213], v[24:27]
	v_mfma_f32_16x16x32_bf16 v[24:27], v[176:179], v[206:209], v[32:35]
	v_mfma_f32_16x16x32_bf16 v[4:7], v[144:147], v[214:217], v[4:7]
	v_mfma_f32_16x16x32_bf16 v[0:3], v[176:179], v[214:217], v[0:3]
	v_mfma_f32_16x16x32_bf16 v[16:19], v[144:147], v[184:187], v[68:71]
	v_mfma_f32_16x16x32_bf16 v[20:23], v[176:179], v[184:187], v[64:67]
	v_mfma_f32_16x16x32_bf16 v[32:35], v[180:183], v[210:213], v[24:27]
	v_mfma_f32_16x16x32_bf16 v[4:7], v[148:151], v[218:221], v[4:7]
	v_mfma_f32_16x16x32_bf16 v[0:3], v[180:183], v[218:221], v[0:3]
	v_mfma_f32_16x16x32_bf16 v[16:19], v[148:151], v[188:191], v[16:19]
	v_mfma_f32_16x16x32_bf16 v[20:23], v[180:183], v[188:191], v[20:23]
	s_setprio 0
	s_barrier
; #define PG8_STAGE(bufoff, gbase, voff) do { _Pragma("unroll") for (int _i = 0; _i < 2; ++_i) \
;         __builtin_amdgcn_global_load_lds((const unsigned*)((const char*)(gbase) + (voff)[_i]), (LAS unsigned*)(lds + (bufoff) + ldsw + _i * 8192), 16, 0, 0); } while (0)
; #define PG8_LDA(dst, b, h) do { _Pragma("unroll") for (int m = 0; m < 4; ++m) _Pragma("unroll") for (int k = 0; k < 2; ++k) dst[m][k] = *(const LAS bf16x8*)(lds + PG8_SA(b, h) + aoff + m * 2048 + k * 1024); } while (0)
; #define PG8_LDB(dst, b, h) do { _Pragma("unroll") for (int n = 0; n < 2; ++n) _Pragma("unroll") for (int k = 0; k < 2; ++k) dst[n][k] = *(const LAS bf16x8*)(lds + PG8_SB(b, h) + boff + n * 2048 + k * 1024); } while (0)
; #define PG8_MMA(ai, bj, At, Bt) do { __builtin_amdgcn_s_setprio(1); _Pragma("unroll") for (int m = 0; m < 4; ++m) _Pragma("unroll") for (int n = 0; n < 2; ++n) _Pragma("unroll") for (int k = 0; k < 2; ++k) \
;         acc[ai][bj][m][n] = __builtin_amdgcn_mfma_f32_16x16x32_bf16(Bt[n][k], At[m][k], acc[ai][bj][m][n], 0, 0, 0); __builtin_amdgcn_s_setprio(0); } while (0)
; #define PG8_WAIT_V(n) asm volatile("s_waitcnt vmcnt(" #n ")" ::: "memory")
; #define PG8_WAIT_L(n) asm volatile("s_waitcnt lgkmcnt(" #n ")" ::: "memory")
; #define PG8_BAR __builtin_amdgcn_s_barrier()
; #define PG8_SCHED __builtin_amdgcn_sched_barrier(0)
; template <class Epi, class Sched>
; __device__ __forceinline__ void gemm_phase(LAS unsigned char* lds, const Gemm g, const Sched& S, const Epi& E, int wave_id) {
;     ...
;             PG8_LDB(B0, 1, 0); PG8_LDB(B1, 1, 1); PG8_SCHED; PG8_LDA(At, 1, 0); PG8_STAGE(PG8_SA(0, 1), a2 + hstepA, voffA);
;             PG8_WAIT_V(8); PG8_WAIT_L(0); PG8_BAR; PG8_MMA(0, 0, At, B0); PG8_MMA(0, 1, At, B1); PG8_BAR; PG8_SCHED;
;             PG8_LDA(At, 1, 1); PG8_STAGE(PG8_SB(1, 0), b3, voffB); PG8_STAGE(PG8_SB(1, 1), b3 + hstepB, voffB); PG8_STAGE(PG8_SA(1, 0), a3, voffA);
;             PG8_WAIT_V(8); PG8_WAIT_L(0); PG8_BAR; PG8_MMA(1, 0, At, B0); PG8_MMA(1, 1, At, B1); PG8_BAR; PG8_SCHED;
;         }
;         if (wr == 0) PG8_BAR;
	s_add_i32 s72, 0, 0x18000
	s_add_i32 s73, 0, 0x1c000
	v_add_u32_e32 v68, s72, v165
	v_add_u32_e32 v180, s73, v165
	ds_read_b128 v[24:27], v68
	ds_read_b128 v[28:31], v68 offset:1024
	ds_read_b128 v[64:67], v68 offset:2048
	ds_read_b128 v[68:71], v68 offset:3072
	ds_read_b128 v[144:147], v180
	ds_read_b128 v[148:151], v180 offset:1024
	ds_read_b128 v[176:179], v180 offset:2048
	ds_read_b128 v[180:183], v180 offset:3072
	s_add_u32 s48, s48, 0x40000
	s_addc_u32 s49, s49, 0
	s_mov_b32 m0, s53
	ds_read_b128 v[184:187], v202 offset:32768
	ds_read_b128 v[188:191], v202 offset:33792
	ds_read_b128 v[192:195], v202 offset:34816
	ds_read_b128 v[196:199], v202 offset:35840
	ds_read_b128 v[206:209], v202 offset:36864
	ds_read_b128 v[210:213], v202 offset:37888
	ds_read_b128 v[214:217], v202 offset:38912
	ds_read_b128 v[218:221], v202 offset:39936
	global_load_lds_dwordx4 v152, s[48:49]
	s_mov_b32 m0, s54
	s_nop 0
	global_load_lds_dwordx4 v156, s[48:49]
	s_waitcnt vmcnt(8)
	s_waitcnt lgkmcnt(0)
	s_barrier
	s_setprio 1
	s_waitcnt lgkmcnt(0)
	v_mfma_f32_16x16x32_bf16 v[140:143], v[24:27], v[184:187], v[140:143]
	v_mfma_f32_16x16x32_bf16 v[136:139], v[64:67], v[184:187], v[136:139]
	v_mfma_f32_16x16x32_bf16 v[124:127], v[24:27], v[192:195], v[124:127]
	v_mfma_f32_16x16x32_bf16 v[120:123], v[64:67], v[192:195], v[120:123]
	v_mfma_f32_16x16x32_bf16 v[108:111], v[24:27], v[206:209], v[108:111]
	v_mfma_f32_16x16x32_bf16 v[104:107], v[64:67], v[206:209], v[104:107]
	v_mfma_f32_16x16x32_bf16 v[92:95], v[24:27], v[214:217], v[92:95]
	v_mfma_f32_16x16x32_bf16 v[88:91], v[64:67], v[214:217], v[88:91]
	v_mfma_f32_16x16x32_bf16 v[140:143], v[28:31], v[188:191], v[140:143]
	v_mfma_f32_16x16x32_bf16 v[136:139], v[68:71], v[188:191], v[136:139]
	v_mfma_f32_16x16x32_bf16 v[124:127], v[28:31], v[196:199], v[124:127]
	v_mfma_f32_16x16x32_bf16 v[120:123], v[68:71], v[196:199], v[120:123]
	v_mfma_f32_16x16x32_bf16 v[108:111], v[28:31], v[210:213], v[108:111]
	v_mfma_f32_16x16x32_bf16 v[104:107], v[68:71], v[210:213], v[104:107]
	v_mfma_f32_16x16x32_bf16 v[92:95], v[28:31], v[218:221], v[92:95]
	v_mfma_f32_16x16x32_bf16 v[88:91], v[68:71], v[218:221], v[88:91]
	s_setprio 0
	s_setprio 1
	v_mfma_f32_16x16x32_bf16 v[132:135], v[144:147], v[184:187], v[132:135]
	v_mfma_f32_16x16x32_bf16 v[128:131], v[176:179], v[184:187], v[128:131]
	v_mfma_f32_16x16x32_bf16 v[116:119], v[144:147], v[192:195], v[116:119]
	v_mfma_f32_16x16x32_bf16 v[112:115], v[176:179], v[192:195], v[112:115]
	v_mfma_f32_16x16x32_bf16 v[100:103], v[144:147], v[206:209], v[100:103]
	v_mfma_f32_16x16x32_bf16 v[96:99], v[176:179], v[206:209], v[96:99]
	v_mfma_f32_16x16x32_bf16 v[84:87], v[144:147], v[214:217], v[84:87]
	v_mfma_f32_16x16x32_bf16 v[80:83], v[176:179], v[214:217], v[80:83]
	v_mfma_f32_16x16x32_bf16 v[132:135], v[148:151], v[188:191], v[132:135]
	v_mfma_f32_16x16x32_bf16 v[128:131], v[180:183], v[188:191], v[128:131]
	v_mfma_f32_16x16x32_bf16 v[116:119], v[148:151], v[196:199], v[116:119]
	v_mfma_f32_16x16x32_bf16 v[112:115], v[180:183], v[196:199], v[112:115]
	v_mfma_f32_16x16x32_bf16 v[100:103], v[148:151], v[210:213], v[100:103]
	v_mfma_f32_16x16x32_bf16 v[96:99], v[180:183], v[210:213], v[96:99]
	v_mfma_f32_16x16x32_bf16 v[84:87], v[148:151], v[218:221], v[84:87]
	v_mfma_f32_16x16x32_bf16 v[80:83], v[180:183], v[218:221], v[80:83]
	s_setprio 0
	s_barrier
	s_add_i32 s48, s72, s35
	v_lshl_add_u64 v[222:223], v[222:223], 0, s[22:23]
	s_mov_b32 m0, s48
	ds_read_b128 v[184:187], v202 offset:49152
	ds_read_b128 v[188:191], v202 offset:50176
	ds_read_b128 v[192:195], v202 offset:51200
	ds_read_b128 v[196:199], v202 offset:52224
	ds_read_b128 v[206:209], v202 offset:53248
	ds_read_b128 v[210:213], v202 offset:54272
	ds_read_b128 v[214:217], v202 offset:55296
	ds_read_b128 v[218:221], v202 offset:56320
	global_load_lds_dwordx4 v[222:223], off
	s_add_i32 m0, s48, 0x2000
	s_add_u32 s46, s46, 0x40080
	v_lshl_add_u64 v[222:223], v[224:225], 0, s[22:23]
	s_addc_u32 s47, s47, 0
	s_add_i32 s48, s73, s35
	global_load_lds_dwordx4 v[222:223], off
	s_mov_b32 m0, s48
	s_nop 0
	global_load_lds_dwordx4 v154, s[46:47]
	s_add_i32 m0, s48, 0x2000
	s_nop 0
	global_load_lds_dwordx4 v158, s[46:47]
	v_lshl_add_u64 v[222:223], v[226:227], 0, s[22:23]
	s_mov_b32 m0, s55
	s_nop 0
	global_load_lds_dwordx4 v[222:223], off
	v_lshl_add_u64 v[222:223], v[228:229], 0, s[22:23]
	s_mov_b32 m0, s56
	s_nop 0
	global_load_lds_dwordx4 v[222:223], off
	s_waitcnt vmcnt(8)
	s_waitcnt lgkmcnt(0)
	s_barrier
	s_setprio 1
	s_waitcnt lgkmcnt(0)
	v_mfma_f32_16x16x32_bf16 v[76:79], v[24:27], v[184:187], v[76:79]
	v_mfma_f32_16x16x32_bf16 v[60:63], v[24:27], v[192:195], v[60:63]
	v_mfma_f32_16x16x32_bf16 v[44:47], v[24:27], v[206:209], v[44:47]
	v_mfma_f32_16x16x32_bf16 v[8:11], v[24:27], v[214:217], v[8:11]
	v_mfma_f32_16x16x32_bf16 v[76:79], v[28:31], v[188:191], v[76:79]
	v_mfma_f32_16x16x32_bf16 v[72:75], v[64:67], v[184:187], v[72:75]
	v_mfma_f32_16x16x32_bf16 v[60:63], v[28:31], v[196:199], v[60:63]
	v_mfma_f32_16x16x32_bf16 v[56:59], v[64:67], v[192:195], v[56:59]
	v_mfma_f32_16x16x32_bf16 v[44:47], v[28:31], v[210:213], v[44:47]
	v_mfma_f32_16x16x32_bf16 v[40:43], v[64:67], v[206:209], v[40:43]
	v_mfma_f32_16x16x32_bf16 v[28:31], v[28:31], v[218:221], v[8:11]
	v_mfma_f32_16x16x32_bf16 v[8:11], v[64:67], v[214:217], v[12:15]
	v_mfma_f32_16x16x32_bf16 v[72:75], v[68:71], v[188:191], v[72:75]
	v_mfma_f32_16x16x32_bf16 v[56:59], v[68:71], v[196:199], v[56:59]
	v_mfma_f32_16x16x32_bf16 v[40:43], v[68:71], v[210:213], v[40:43]
	v_mfma_f32_16x16x32_bf16 v[24:27], v[68:71], v[218:221], v[8:11]
	s_setprio 0
	s_setprio 1
	v_mfma_f32_16x16x32_bf16 v[8:11], v[144:147], v[184:187], v[16:19]
	v_mfma_f32_16x16x32_bf16 v[68:71], v[148:151], v[188:191], v[8:11]
	v_mfma_f32_16x16x32_bf16 v[8:11], v[176:179], v[184:187], v[20:23]
	v_mfma_f32_16x16x32_bf16 v[64:67], v[180:183], v[188:191], v[8:11]
	v_mfma_f32_16x16x32_bf16 v[8:11], v[144:147], v[192:195], v[52:55]
	v_mfma_f32_16x16x32_bf16 v[52:55], v[148:151], v[196:199], v[8:11]
	v_mfma_f32_16x16x32_bf16 v[8:11], v[176:179], v[192:195], v[48:51]
	v_mfma_f32_16x16x32_bf16 v[48:51], v[180:183], v[196:199], v[8:11]
	v_mfma_f32_16x16x32_bf16 v[8:11], v[144:147], v[206:209], v[36:39]
	v_mfma_f32_16x16x32_bf16 v[36:39], v[148:151], v[210:213], v[8:11]
	v_mfma_f32_16x16x32_bf16 v[8:11], v[176:179], v[206:209], v[32:35]
	v_mfma_f32_16x16x32_bf16 v[4:7], v[144:147], v[214:217], v[4:7]
	v_mfma_f32_16x16x32_bf16 v[0:3], v[176:179], v[214:217], v[0:3]
	v_mfma_f32_16x16x32_bf16 v[32:35], v[180:183], v[210:213], v[8:11]
	v_mfma_f32_16x16x32_bf16 v[4:7], v[148:151], v[218:221], v[4:7]
	v_mfma_f32_16x16x32_bf16 v[0:3], v[180:183], v[218:221], v[0:3]
	s_setprio 0
	s_barrier
	s_add_i32 s67, s67, 2
	s_add_u32 s12, s12, 0x100
	s_addc_u32 s13, s13, 0
	s_add_u32 s65, s65, 0x100
	s_addc_u32 s66, s66, 0
	s_cmp_gt_u32 s67, 13
	s_cbranch_scc0 .LBB0_1382
	s_and_b64 vcc, exec, s[24:25]
	s_cbranch_vccz .LBB0_1385
	s_barrier
